# write-through (sc1) on bulk 16-byte epilogue/transposes stores so the grid-barrier L2 writeback finds few dirty lines
# baseline (speedup 1.0000x reference)
; #define LDS_WAIT() asm volatile("s_waitcnt lgkmcnt(0)" ::: "memory")
; DI void transpose_item(const float* __restrict__ W, int K, int N, u16* __restrict__ WT, float* scr, int item, int lane, bool perm, bool pair_up = false) {
;   const int nblk = N / 32, kb = item / nblk, nb = item % nblk, k0 = 64 * kb, n0 = 32 * nb;
;   const int ns0 = pair_up ? (((n0 & 255) < 128) ? 128 * (n0 >> 8) + (n0 & 255) : FF + 128 * (n0 >> 8) + (n0 & 255) - 128) : n0;
;   float tv[32];
; #pragma unroll
;   for (int i = 0; i < 32; ++i) { const int kk = 2 * i + (lane >> 5); tv[i] = W[(size_t)(k0 + kk) * N + ns0 + (lane & 31)]; }
; #pragma unroll
;   for (int i = 0; i < 32; ++i) { const int kk = 2 * i + (lane >> 5); scr[kk * 33 + (lane & 31)] = tv[i]; }
;   LDS_WAIT(); asm volatile("" ::: "memory");
; __global__ void __launch_bounds__(512, 2) fwd_megakernel(Params p_unused) {
;     ...
;     for (int it = gw; it < NITEMS; it += NGW) {
;       int r = it;
;       { const int nb = r % 384; transpose_item(p.w_in, DM, NIN, WIN, scr, r, lane, (nb < 32) || (nb >= 160 && nb < 192)); }
.LBB0_14:
	s_mul_hi_i32 s4, s26, 0x2aaaaaab
	s_lshr_b32 s5, s4, 31
	s_ashr_i32 s4, s4, 6
	s_add_i32 s13, s4, s5
	s_mul_i32 s4, s13, 0xfffffe80
	s_add_i32 s14, s26, s4
	s_cmp_lt_i32 s14, 32
	s_cselect_b64 s[4:5], -1, 0
	s_and_b32 s14, s14, 0x7fffffe0
	s_mul_i32 s12, s13, 0xffffd000
	s_cmpk_eq_i32 s14, 0xa0
	s_cselect_b64 s[24:25], -1, 0
	s_add_i32 s12, s0, s12
	s_lshl_b32 s14, s13, 6
	v_or_b32_e32 v26, s14, v6
	s_ashr_i32 s13, s12, 31
	v_lshl_add_u64 v[24:25], s[12:13], 2, v[2:3]
	v_or_b32_e32 v34, 8, v26
	v_or_b32_e32 v39, 12, v26
	v_or_b32_e32 v42, 14, v26
	v_or_b32_e32 v50, 22, v26
	v_or_b32_e32 v52, 24, v26
	v_or_b32_e32 v54, 26, v26
	v_or_b32_e32 v56, 28, v26
	v_or_b32_e32 v58, 30, v26
	v_or_b32_e32 v28, 2, v26
	v_or_b32_e32 v30, 4, v26
	v_or_b32_e32 v32, 6, v26
	v_or_b32_e32 v36, 10, v26
	v_or_b32_e32 v44, 16, v26
	v_or_b32_e32 v46, 18, v26
	v_or_b32_e32 v48, 20, v26
	v_or_b32_e32 v60, 32, v26
	v_or_b32_e32 v62, 34, v26
	v_or_b32_e32 v64, 36, v26
	v_or_b32_e32 v66, 38, v26
	v_or_b32_e32 v68, 40, v26
	v_or_b32_e32 v70, 42, v26
	v_or_b32_e32 v72, 44, v26
	v_or_b32_e32 v74, 46, v26
	v_or_b32_e32 v76, 48, v26
	v_or_b32_e32 v78, 50, v26
	v_or_b32_e32 v80, 52, v26
	v_or_b32_e32 v82, 54, v26
	v_or_b32_e32 v84, 56, v26
	v_or_b32_e32 v86, 58, v26
	v_or_b32_e32 v88, 60, v26
	v_or_b32_e32 v90, 62, v26
	v_mad_i64_i32 v[26:27], s[28:29], v26, s27, v[24:25]
	v_mad_i64_i32 v[34:35], s[28:29], v34, s27, v[24:25]
	v_mad_i64_i32 v[40:41], s[28:29], v39, s27, v[24:25]
	v_mad_i64_i32 v[42:43], s[28:29], v42, s27, v[24:25]
	v_mad_i64_i32 v[50:51], s[28:29], v50, s27, v[24:25]
	v_mad_i64_i32 v[52:53], s[28:29], v52, s27, v[24:25]
	v_mad_i64_i32 v[54:55], s[28:29], v54, s27, v[24:25]
	v_mad_i64_i32 v[56:57], s[28:29], v56, s27, v[24:25]
	v_mad_i64_i32 v[58:59], s[28:29], v58, s27, v[24:25]
	v_mad_i64_i32 v[28:29], s[28:29], v28, s27, v[24:25]
	v_mad_i64_i32 v[30:31], s[28:29], v30, s27, v[24:25]
	v_mad_i64_i32 v[32:33], s[28:29], v32, s27, v[24:25]
	v_mad_i64_i32 v[36:37], s[28:29], v36, s27, v[24:25]
	v_mad_i64_i32 v[44:45], s[28:29], v44, s27, v[24:25]
	v_mad_i64_i32 v[46:47], s[28:29], v46, s27, v[24:25]
	v_mad_i64_i32 v[48:49], s[28:29], v48, s27, v[24:25]
	v_mad_i64_i32 v[60:61], s[28:29], v60, s27, v[24:25]
	v_mad_i64_i32 v[62:63], s[28:29], v62, s27, v[24:25]
	v_mad_i64_i32 v[64:65], s[28:29], v64, s27, v[24:25]
	v_mad_i64_i32 v[66:67], s[28:29], v66, s27, v[24:25]
	v_mad_i64_i32 v[68:69], s[28:29], v68, s27, v[24:25]
	v_mad_i64_i32 v[70:71], s[28:29], v70, s27, v[24:25]
	v_mad_i64_i32 v[72:73], s[28:29], v72, s27, v[24:25]
	v_mad_i64_i32 v[74:75], s[28:29], v74, s27, v[24:25]
	v_mad_i64_i32 v[76:77], s[28:29], v76, s27, v[24:25]
	v_mad_i64_i32 v[78:79], s[28:29], v78, s27, v[24:25]
	v_mad_i64_i32 v[80:81], s[28:29], v80, s27, v[24:25]
	v_mad_i64_i32 v[82:83], s[28:29], v82, s27, v[24:25]
	v_mad_i64_i32 v[84:85], s[28:29], v84, s27, v[24:25]
	v_mad_i64_i32 v[86:87], s[28:29], v86, s27, v[24:25]
	v_mad_i64_i32 v[88:89], s[28:29], v88, s27, v[24:25]
	v_mad_i64_i32 v[24:25], s[28:29], v90, s27, v[24:25]
	global_load_dword v39, v[26:27], off
	global_load_dword v90, v[28:29], off
	global_load_dword v91, v[30:31], off
	global_load_dword v92, v[32:33], off
	global_load_dword v93, v[34:35], off
	global_load_dword v94, v[36:37], off
	global_load_dword v95, v[40:41], off
	global_load_dword v96, v[42:43], off
	global_load_dword v97, v[44:45], off
	global_load_dword v98, v[46:47], off
	global_load_dword v99, v[48:49], off
	global_load_dword v100, v[50:51], off
	global_load_dword v101, v[52:53], off
	global_load_dword v102, v[54:55], off
	global_load_dword v103, v[56:57], off
	global_load_dword v34, v[58:59], off
	global_load_dword v35, v[60:61], off
	global_load_dword v40, v[62:63], off
	global_load_dword v41, v[64:65], off
	global_load_dword v42, v[66:67], off
	global_load_dword v43, v[68:69], off
	global_load_dword v50, v[70:71], off
	global_load_dword v51, v[72:73], off
	global_load_dword v52, v[74:75], off
	global_load_dword v53, v[76:77], off
	global_load_dword v54, v[78:79], off
	global_load_dword v55, v[80:81], off
	global_load_dword v56, v[82:83], off
	global_load_dword v57, v[84:85], off
	global_load_dword v104, v[86:87], off
	global_load_dword v58, v[88:89], off
	global_load_dword v59, v[24:25], off
	s_or_b64 vcc, s[4:5], s[24:25]
	v_cndmask_b32_e32 v25, v8, v10, vcc
	v_add_u32_e32 v24, s12, v8
	s_ashr_i32 s15, s14, 31
	v_lshl_add_u32 v60, v25, 2, v9
	v_ashrrev_i32_e32 v25, 31, v24
	v_cndmask_b32_e32 v29, v11, v12, vcc
	v_add_u32_e32 v28, 8, v24
	v_cndmask_b32_e32 v31, v13, v14, vcc
	v_add_u32_e32 v30, 16, v24
	v_cndmask_b32_e32 v33, v15, v16, vcc
	v_add_u32_e32 v32, 24, v24
	s_waitcnt vmcnt(30)
; DI unsigned cvtpk(float lo, float hi) { f32x2 v = {lo, hi}; bf16x2_t b = __builtin_convertvector(v, bf16x2_t); return __builtin_bit_cast(unsigned, b); }
; #define LDS_WAIT() asm volatile("s_waitcnt lgkmcnt(0)" ::: "memory")
; DI void transpose_item(const float* __restrict__ W, int K, int N, u16* __restrict__ WT, float* scr, int item, int lane, bool perm, bool pair_up = false) {
;     ...
;   for (int i = 0; i < 32; ++i) { const int kk = 2 * i + (lane >> 5); scr[kk * 33 + (lane & 31)] = tv[i]; }
;   LDS_WAIT(); asm volatile("" ::: "memory");
;   const int c = lane & 7;
; #pragma unroll
;   for (int j = 0; j < 4; ++j) { const int n = (lane >> 3) + 8 * j; const float* s = scr + (8 * c) * 33 + (perm ? cperm(n) : n);
;     u32x4v o; o.x = cvtpk(s[0 * 33], s[1 * 33]); o.y = cvtpk(s[2 * 33], s[3 * 33]); o.z = cvtpk(s[4 * 33], s[5 * 33]); o.w = cvtpk(s[6 * 33], s[7 * 33]);
;     *(u32x4v*)(WT + (size_t)(n0 + n) * K + k0 + 8 * c) = o; }
	ds_write2_b32 v7, v39, v90 offset1:66
	s_waitcnt vmcnt(28)
	ds_write2_b32 v7, v91, v92 offset0:132 offset1:198
	s_waitcnt vmcnt(26)
	ds_write2_b32 v17, v93, v94 offset0:8 offset1:74
	s_waitcnt vmcnt(24)
	ds_write2_b32 v17, v95, v96 offset0:140 offset1:206
	s_waitcnt vmcnt(22)
	ds_write2_b32 v18, v97, v98 offset0:16 offset1:82
	s_waitcnt vmcnt(20)
	ds_write2_b32 v18, v99, v100 offset0:148 offset1:214
	s_waitcnt vmcnt(18)
	ds_write2_b32 v19, v101, v102 offset0:24 offset1:90
	s_waitcnt vmcnt(16)
	ds_write2_b32 v19, v103, v34 offset0:156 offset1:222
	s_waitcnt vmcnt(14)
	ds_write2_b32 v20, v35, v40 offset0:32 offset1:98
	s_waitcnt vmcnt(12)
	ds_write2_b32 v20, v41, v42 offset0:164 offset1:230
	s_waitcnt vmcnt(10)
	ds_write2_b32 v21, v43, v50 offset0:40 offset1:106
	s_waitcnt vmcnt(8)
	ds_write2_b32 v21, v51, v52 offset0:172 offset1:238
	s_waitcnt vmcnt(6)
	ds_write2_b32 v22, v53, v54 offset0:48 offset1:114
	s_waitcnt vmcnt(4)
	ds_write2_b32 v22, v55, v56 offset0:180 offset1:246
	s_waitcnt vmcnt(2)
	ds_write2_b32 v23, v57, v104 offset0:56 offset1:122
	s_waitcnt vmcnt(0)
	ds_write2_b32 v23, v58, v59 offset0:188 offset1:254
	v_lshl_add_u64 v[26:27], s[14:15], 1, v[4:5]
	v_lshlrev_b64 v[24:25], 12, v[24:25]
	v_lshl_add_u32 v61, v29, 2, v9
	v_ashrrev_i32_e32 v29, 31, v28
	v_lshl_add_u32 v62, v31, 2, v9
	v_ashrrev_i32_e32 v31, 31, v30
	v_lshl_add_u32 v64, v33, 2, v9
	v_ashrrev_i32_e32 v33, 31, v32
	s_waitcnt lgkmcnt(0)
	v_lshl_add_u64 v[36:37], v[26:27], 0, v[24:25]
	v_lshlrev_b64 v[24:25], 12, v[28:29]
	v_lshlrev_b64 v[28:29], 12, v[30:31]
	v_lshlrev_b64 v[30:31], 12, v[32:33]
	v_lshl_add_u64 v[44:45], v[26:27], 0, v[24:25]
	v_lshl_add_u64 v[46:47], v[26:27], 0, v[28:29]
	v_lshl_add_u64 v[48:49], v[26:27], 0, v[30:31]
	ds_read2_b32 v[24:25], v60 offset1:33
	ds_read2_b32 v[26:27], v60 offset0:66 offset1:99
	ds_read2_b32 v[28:29], v60 offset0:132 offset1:165
	ds_read2_b32 v[30:31], v60 offset0:198 offset1:231
	ds_read2_b32 v[32:33], v61 offset1:33
	ds_read2_b32 v[34:35], v61 offset0:66 offset1:99
	ds_read2_b32 v[40:41], v61 offset0:132 offset1:165
	ds_read2_b32 v[42:43], v61 offset0:198 offset1:231
	ds_read2_b32 v[50:51], v62 offset1:33
	ds_read2_b32 v[52:53], v62 offset0:66 offset1:99
	ds_read2_b32 v[54:55], v62 offset0:132 offset1:165
	ds_read2_b32 v[56:57], v62 offset0:198 offset1:231
	ds_read2_b32 v[58:59], v64 offset1:33
	ds_read2_b32 v[60:61], v64 offset0:66 offset1:99
	ds_read2_b32 v[62:63], v64 offset0:132 offset1:165
	ds_read2_b32 v[64:65], v64 offset0:198 offset1:231
	s_waitcnt lgkmcnt(14)
	v_cvt_pk_bf16_f32 v24, v24, v25
	v_cvt_pk_bf16_f32 v25, v26, v27
	s_waitcnt lgkmcnt(13)
	v_cvt_pk_bf16_f32 v26, v28, v29
	s_waitcnt lgkmcnt(12)
	v_cvt_pk_bf16_f32 v27, v30, v31
	s_waitcnt lgkmcnt(11)
	v_cvt_pk_bf16_f32 v28, v32, v33
	s_waitcnt lgkmcnt(10)
	v_cvt_pk_bf16_f32 v29, v34, v35
	s_waitcnt lgkmcnt(9)
	v_cvt_pk_bf16_f32 v30, v40, v41
	s_waitcnt lgkmcnt(8)
	v_cvt_pk_bf16_f32 v31, v42, v43
	s_waitcnt lgkmcnt(7)
	v_cvt_pk_bf16_f32 v32, v50, v51
	s_waitcnt lgkmcnt(6)
	v_cvt_pk_bf16_f32 v33, v52, v53
	s_waitcnt lgkmcnt(5)
	v_cvt_pk_bf16_f32 v34, v54, v55
	s_waitcnt lgkmcnt(4)
	v_cvt_pk_bf16_f32 v35, v56, v57
	s_waitcnt lgkmcnt(3)
	v_cvt_pk_bf16_f32 v40, v58, v59
	s_waitcnt lgkmcnt(2)
	v_cvt_pk_bf16_f32 v41, v60, v61
	s_waitcnt lgkmcnt(1)
	v_cvt_pk_bf16_f32 v42, v62, v63
	s_waitcnt lgkmcnt(0)
	v_cvt_pk_bf16_f32 v43, v64, v65
	global_store_dwordx4 v[36:37], v[24:27], off sc1
	global_store_dwordx4 v[44:45], v[28:31], off sc1
	global_store_dwordx4 v[46:47], v[32:35], off sc1
	global_store_dwordx4 v[48:49], v[40:43], off sc1
	s_waitcnt lgkmcnt(0)
	s_add_i32 s26, s26, s74
	s_add_i32 s0, s0, s1
	s_cmpk_gt_i32 s26, 0x2fff
	s_cbranch_scc0 .LBB0_14

; DI unsigned cvtpk(float lo, float hi) { f32x2 v = {lo, hi}; bf16x2_t b = __builtin_convertvector(v, bf16x2_t); return __builtin_bit_cast(unsigned, b); }
; DI unsigned cvtpk_h(float lo, float hi) { f32x2 v = {lo, hi}; h16x2_t b = __builtin_convertvector(v, h16x2_t); return __builtin_bit_cast(unsigned, b); }
; DI float sigm(float x) { return __builtin_amdgcn_rcpf(1.f + fexp(-x)); }
; DI float silu_(float x) { return x * sigm(x); }
;     template <int MODE> __device__ __forceinline__ void run(const f32x4 (&acc)[2][2][4][2], u16* dst, int ld, int row0, int col0, int trow0, int wc, int fq, const float* lb) const {
;     ...
;                     if (MODE == 4) {
; #pragma unroll
;                         for (int i = 0; i < 4; ++i) { v0[i] = silu_(v0[i]); v1[i] = silu_(v1[i]); }
;                     }
;                     if (MODE == 5) {
; #pragma unroll
;                         for (int i = 0; i < 4; ++i) { v0[i] = sigm(v0[i]); v1[i] = sigm(v1[i]); }
;                     }
;                     u32x4 w;
;                     if (MODE == 3) { w.x = cvtpk_h(v0[0], v0[1]); w.y = cvtpk_h(v0[2], v0[3]); w.z = cvtpk_h(v1[0], v1[1]); w.w = cvtpk_h(v1[2], v1[3]); }
;                     else { w.x = cvtpk(v0[0], v0[1]); w.y = cvtpk(v0[2], v0[3]); w.z = cvtpk(v1[0], v1[1]); w.w = cvtpk(v1[2], v1[3]); }
;                     *(u32x4*)(rowp + bj * HALF) = w;
;     __device__ __forceinline__ void operator()(const f32x4 (&acc)[2][2][4][2], const Unit& u, int wr, int wc, int fr, int fq) const {
;         const int pm = u.pm, pn = u.pn; const bool ctx = pm >= 64;
;         const int b = ctx ? pm - 64 : (pm >> 3);
;         const int trow0 = (ctx ? 0 : (pm & 7) * 256) + wr * 64 + fr;
;         const int kvrow0 = b * TKV + (ctx ? SEQ : 0) + trow0;
;         const int latrow0 = pm * 256 + wr * 64 + fr;
;         const int seg = pn >> 2, c1 = (pn & 3) * 256 + wc * 32 + 8 * fq;
;         switch (seg) {
.LBB0_180:
	s_cmp_lt_i32 s8, 64
	s_cselect_b64 s[66:67], -1, 0
	s_lshl_b32 s3, s8, 8
	s_sub_i32 s0, s8, 64
	s_lshr_b32 s2, s8, 3
	s_and_b32 s7, s3, 0x700
	s_cmp_gt_i32 s8, 63
	s_cselect_b32 s0, s0, s2
	s_cselect_b32 s55, 0, s7
	s_cselect_b32 s2, 0x800, 0
	s_add_i32 s55, s55, s79
	s_mulk_i32 s0, 0x900
	v_or_b32_e32 v128, s55, v175
	s_add_i32 s0, s0, s2
	s_lshl_b32 s57, s6, 8
	v_add_u32_e32 v166, s0, v128
	s_ashr_i32 s58, s6, 2
	s_and_b32 s0, s57, 0x300
	v_add_u32_e32 v168, s3, v176
	v_or_b32_e32 v187, s0, v178
	s_mov_b64 s[8:9], -1
	s_mov_b64 s[6:7], 0
	s_cmp_lt_i32 s58, 4
	s_mov_b64 s[68:69], 0
	s_cbranch_scc1 .LBB0_195
	s_cmp_gt_i32 s58, 5
	s_cbranch_scc0 .LBB0_186
	s_cmp_gt_i32 s58, 6
	s_cbranch_scc0 .LBB0_187
	s_cmp_eq_u32 s58, 7
	s_mov_b64 s[68:69], -1
	s_cbranch_scc0 .LBB0_185
	v_mul_f32_e32 v132, 0xbfb8aa3b, v124
	v_exp_f32_e32 v132, v132
	v_mul_f32_e32 v133, 0xbfb8aa3b, v120
	v_exp_f32_e32 v133, v133
	v_lshlrev_b32_e32 v152, 1, v187
	v_ashrrev_i32_e32 v169, 31, v168
	v_lshl_add_u64 v[128:129], s[36:37], 0, v[152:153]
	v_lshlrev_b64 v[130:131], 11, v[168:169]
	v_lshl_add_u64 v[134:135], v[128:129], 0, v[130:131]
	v_add_f32_e32 v130, 1.0, v132
	v_mul_f32_e32 v132, 0xbfb8aa3b, v125
	v_add_f32_e32 v131, 1.0, v133
	v_exp_f32_e32 v133, v132
	v_mul_f32_e32 v132, 0xbfb8aa3b, v121
	v_exp_f32_e32 v136, v132
	v_mul_f32_e32 v137, 0xbfb8aa3b, v122
	v_rcp_f32_e32 v132, v131
	v_add_f32_e32 v131, 1.0, v133
	v_add_f32_e32 v133, 1.0, v136
	v_mul_f32_e32 v136, 0xbfb8aa3b, v126
	v_exp_f32_e32 v137, v137
	v_mul_f32_e32 v138, 0xbfb8aa3b, v127
	v_exp_f32_e32 v136, v136
	v_exp_f32_e32 v139, v138
	v_mul_f32_e32 v138, 0xbfb8aa3b, v123
	v_exp_f32_e32 v140, v138
	v_add_f32_e32 v137, 1.0, v137
	v_add_f32_e32 v136, 1.0, v136
	v_rcp_f32_e32 v138, v137
	v_add_f32_e32 v137, 1.0, v139
	v_rcp_f32_e32 v130, v130
	v_rcp_f32_e32 v131, v131
	v_rcp_f32_e32 v136, v136
	v_rcp_f32_e32 v137, v137
	v_add_f32_e32 v139, 1.0, v140
	v_rcp_f32_e32 v133, v133
	v_rcp_f32_e32 v139, v139
	v_pk_mul_f32 v[130:131], v[124:125], v[130:131]
	v_pk_mul_f32 v[136:137], v[126:127], v[136:137]
	v_cvt_pk_bf16_f32 v130, v130, v131
	v_cvt_pk_bf16_f32 v131, v136, v137
	v_mul_f32_e32 v136, 0xbfb8aa3b, v108
	v_pk_mul_f32 v[132:133], v[120:121], v[132:133]
	v_pk_mul_f32 v[138:139], v[122:123], v[138:139]
	v_exp_f32_e32 v136, v136
	v_cvt_pk_bf16_f32 v132, v132, v133
	v_cvt_pk_bf16_f32 v133, v138, v139
	v_mul_f32_e32 v137, 0xbfb8aa3b, v104
	global_store_dwordx4 v[134:135], v[130:133], off sc1
	v_exp_f32_e32 v137, v137
	v_mul_f32_e32 v138, 0xbfb8aa3b, v111
	v_mul_f32_e32 v132, 0xbfb8aa3b, v109
	v_exp_f32_e32 v133, v132
	v_mul_f32_e32 v132, 0xbfb8aa3b, v105
	v_add_f32_e32 v130, 1.0, v136
	v_exp_f32_e32 v136, v132
	v_add_f32_e32 v131, 1.0, v137
	v_mul_f32_e32 v137, 0xbfb8aa3b, v106
	v_rcp_f32_e32 v132, v131
	v_add_f32_e32 v131, 1.0, v133
	v_add_f32_e32 v133, 1.0, v136
	v_mul_f32_e32 v136, 0xbfb8aa3b, v110
	v_exp_f32_e32 v137, v137
	v_exp_f32_e32 v139, v138
	v_mul_f32_e32 v138, 0xbfb8aa3b, v107
	v_exp_f32_e32 v136, v136
	v_exp_f32_e32 v140, v138
	v_add_f32_e32 v137, 1.0, v137
	v_rcp_f32_e32 v138, v137
	v_add_f32_e32 v136, 1.0, v136
	v_add_f32_e32 v137, 1.0, v139
	v_add_f32_e32 v139, 1.0, v140
	v_rcp_f32_e32 v130, v130
	v_rcp_f32_e32 v131, v131
	v_rcp_f32_e32 v133, v133
	v_rcp_f32_e32 v136, v136
	v_rcp_f32_e32 v137, v137
	v_rcp_f32_e32 v139, v139
	v_pk_mul_f32 v[130:131], v[108:109], v[130:131]
	v_pk_mul_f32 v[132:133], v[104:105], v[132:133]
	v_pk_mul_f32 v[136:137], v[110:111], v[136:137]
	v_pk_mul_f32 v[138:139], v[106:107], v[138:139]
	v_cvt_pk_bf16_f32 v130, v130, v131
	v_cvt_pk_bf16_f32 v131, v136, v137
	v_cvt_pk_bf16_f32 v132, v132, v133
	v_cvt_pk_bf16_f32 v133, v138, v139
	global_store_dwordx4 v[134:135], v[130:133], off offset:256 sc1
	v_mul_f32_e32 v137, 0xbfb8aa3b, v114
	v_exp_f32_e32 v137, v137
	v_mul_f32_e32 v132, 0xbfb8aa3b, v116
	v_exp_f32_e32 v132, v132
	v_mul_f32_e32 v133, 0xbfb8aa3b, v112
	v_or_b32_e32 v130, 16, v168
	v_exp_f32_e32 v133, v133
	v_ashrrev_i32_e32 v131, 31, v130
	v_lshlrev_b64 v[130:131], 11, v[130:131]
	v_lshl_add_u64 v[134:135], v[128:129], 0, v[130:131]
	v_add_f32_e32 v130, 1.0, v132
	v_mul_f32_e32 v132, 0xbfb8aa3b, v117
	v_add_f32_e32 v131, 1.0, v133
	v_exp_f32_e32 v133, v132
	v_mul_f32_e32 v132, 0xbfb8aa3b, v113
	v_exp_f32_e32 v136, v132
	v_rcp_f32_e32 v132, v131
	v_add_f32_e32 v131, 1.0, v133
	v_mul_f32_e32 v138, 0xbfb8aa3b, v119
	v_add_f32_e32 v133, 1.0, v136
	v_mul_f32_e32 v136, 0xbfb8aa3b, v118
	v_exp_f32_e32 v136, v136
	v_exp_f32_e32 v139, v138
	v_mul_f32_e32 v138, 0xbfb8aa3b, v115
	v_exp_f32_e32 v140, v138
	v_add_f32_e32 v137, 1.0, v137
	v_add_f32_e32 v136, 1.0, v136
	v_rcp_f32_e32 v138, v137
	v_add_f32_e32 v137, 1.0, v139
	v_rcp_f32_e32 v130, v130
	v_rcp_f32_e32 v131, v131
	v_rcp_f32_e32 v136, v136
	v_rcp_f32_e32 v137, v137
	v_add_f32_e32 v139, 1.0, v140
	v_rcp_f32_e32 v133, v133
	v_rcp_f32_e32 v139, v139
	v_pk_mul_f32 v[130:131], v[116:117], v[130:131]
	v_pk_mul_f32 v[136:137], v[118:119], v[136:137]
	v_cvt_pk_bf16_f32 v130, v130, v131
	v_cvt_pk_bf16_f32 v131, v136, v137
	v_mul_f32_e32 v136, 0xbfb8aa3b, v92
	v_pk_mul_f32 v[132:133], v[112:113], v[132:133]
	v_pk_mul_f32 v[138:139], v[114:115], v[138:139]
	v_exp_f32_e32 v136, v136
	v_cvt_pk_bf16_f32 v132, v132, v133
	v_cvt_pk_bf16_f32 v133, v138, v139
	v_mul_f32_e32 v137, 0xbfb8aa3b, v88
	global_store_dwordx4 v[134:135], v[130:133], off sc1
	v_exp_f32_e32 v137, v137
	v_mul_f32_e32 v138, 0xbfb8aa3b, v95
	v_mul_f32_e32 v132, 0xbfb8aa3b, v93
	v_exp_f32_e32 v133, v132
	v_mul_f32_e32 v132, 0xbfb8aa3b, v89
	v_add_f32_e32 v130, 1.0, v136
	v_exp_f32_e32 v136, v132
	v_add_f32_e32 v131, 1.0, v137
	v_mul_f32_e32 v137, 0xbfb8aa3b, v90
; DI unsigned cvtpk(float lo, float hi) { f32x2 v = {lo, hi}; bf16x2_t b = __builtin_convertvector(v, bf16x2_t); return __builtin_bit_cast(unsigned, b); }
; DI unsigned cvtpk_h(float lo, float hi) { f32x2 v = {lo, hi}; h16x2_t b = __builtin_convertvector(v, h16x2_t); return __builtin_bit_cast(unsigned, b); }
;     template <int MODE> __device__ __forceinline__ void run(const f32x4 (&acc)[2][2][4][2], u16* dst, int ld, int row0, int col0, int trow0, int wc, int fq, const float* lb) const {
;     ...
;             for (int m = 0; m < 4; ++m) {
;                 const int rr = ai * HALF + m * 16;
;                 u16* rowp = dst + (size_t)(row0 + rr) * ld + col0;
;                 f32x4 cs, sn;
;                 if (MODE == 1 || MODE == 2) { const int t = trow0 + rr; const int pos = (wc & 1) ? (t & 63) : (t >> 6);
;                     cs = *(const f32x4*)(rcos + pos * 16 + 4 * fq); sn = *(const f32x4*)(rsin + pos * 16 + 4 * fq); }
; #pragma unroll
;                 for (int bj = 0; bj < 2; ++bj) {
;                     f32x4 v0 = acc[ai][bj][m][0], v1 = acc[ai][bj][m][1];
;                     if (MODE == 1 || MODE == 2) { const f32x4 a = v0 * cs - v1 * sn, b = v1 * cs + v0 * sn; v0 = a; v1 = b;
;                         if (MODE == 2) { v0 = v0 * 0.18033688011112042f; v1 = v1 * 0.18033688011112042f; } }
;                     if (MODE == 3) {
; #pragma unroll
;                         for (int i = 0; i < 4; ++i) { const float l0 = lb0[bj][i], l1 = lb1[bj][i];
;                             v0[i] = __logf(l0 + (1.f - l0) * sigm(v0[i])); v1[i] = __logf(l1 + (1.f - l1) * sigm(v1[i])); }
;                     }
;                     if (MODE == 4) {
; #pragma unroll
;                         for (int i = 0; i < 4; ++i) { v0[i] = silu_(v0[i]); v1[i] = silu_(v1[i]); }
;                     }
;                     if (MODE == 5) {
; #pragma unroll
;                         for (int i = 0; i < 4; ++i) { v0[i] = sigm(v0[i]); v1[i] = sigm(v1[i]); }
;                     }
;                     u32x4 w;
;                     if (MODE == 3) { w.x = cvtpk_h(v0[0], v0[1]); w.y = cvtpk_h(v0[2], v0[3]); w.z = cvtpk_h(v1[0], v1[1]); w.w = cvtpk_h(v1[2], v1[3]); }
;                     else { w.x = cvtpk(v0[0], v0[1]); w.y = cvtpk(v0[2], v0[3]); w.z = cvtpk(v1[0], v1[1]); w.w = cvtpk(v1[2], v1[3]); }
;                     *(u32x4*)(rowp + bj * HALF) = w;
	v_rcp_f32_e32 v132, v131
	v_add_f32_e32 v131, 1.0, v133
	v_add_f32_e32 v133, 1.0, v136
	v_mul_f32_e32 v136, 0xbfb8aa3b, v94
	v_exp_f32_e32 v137, v137
	v_exp_f32_e32 v139, v138
	v_mul_f32_e32 v138, 0xbfb8aa3b, v91
	v_exp_f32_e32 v136, v136
	v_exp_f32_e32 v140, v138
	v_add_f32_e32 v137, 1.0, v137
	v_rcp_f32_e32 v138, v137
	v_add_f32_e32 v136, 1.0, v136
	v_add_f32_e32 v137, 1.0, v139
	v_add_f32_e32 v139, 1.0, v140
	v_rcp_f32_e32 v130, v130
	v_rcp_f32_e32 v131, v131
	v_rcp_f32_e32 v133, v133
	v_rcp_f32_e32 v136, v136
	v_rcp_f32_e32 v137, v137
	v_rcp_f32_e32 v139, v139
	v_pk_mul_f32 v[130:131], v[92:93], v[130:131]
	v_pk_mul_f32 v[132:133], v[88:89], v[132:133]
	v_pk_mul_f32 v[136:137], v[94:95], v[136:137]
	v_pk_mul_f32 v[138:139], v[90:91], v[138:139]
	v_cvt_pk_bf16_f32 v130, v130, v131
	v_cvt_pk_bf16_f32 v131, v136, v137
	v_cvt_pk_bf16_f32 v132, v132, v133
	v_cvt_pk_bf16_f32 v133, v138, v139
	global_store_dwordx4 v[134:135], v[130:133], off offset:256 sc1
	v_mul_f32_e32 v137, 0xbfb8aa3b, v98
	v_exp_f32_e32 v137, v137
	v_mul_f32_e32 v132, 0xbfb8aa3b, v100
	v_exp_f32_e32 v132, v132
	v_mul_f32_e32 v133, 0xbfb8aa3b, v96
	v_or_b32_e32 v130, 32, v168
	v_exp_f32_e32 v133, v133
	v_ashrrev_i32_e32 v131, 31, v130
	v_lshlrev_b64 v[130:131], 11, v[130:131]
	v_lshl_add_u64 v[134:135], v[128:129], 0, v[130:131]
	v_add_f32_e32 v130, 1.0, v132
	v_mul_f32_e32 v132, 0xbfb8aa3b, v101
	v_add_f32_e32 v131, 1.0, v133
	v_exp_f32_e32 v133, v132
	v_mul_f32_e32 v132, 0xbfb8aa3b, v97
	v_exp_f32_e32 v136, v132
	v_rcp_f32_e32 v132, v131
	v_add_f32_e32 v131, 1.0, v133
	v_mul_f32_e32 v138, 0xbfb8aa3b, v103
	v_add_f32_e32 v133, 1.0, v136
	v_mul_f32_e32 v136, 0xbfb8aa3b, v102
	v_exp_f32_e32 v136, v136
	v_exp_f32_e32 v139, v138
	v_mul_f32_e32 v138, 0xbfb8aa3b, v99
	v_exp_f32_e32 v140, v138
	v_add_f32_e32 v137, 1.0, v137
	v_add_f32_e32 v136, 1.0, v136
	v_rcp_f32_e32 v138, v137
	v_add_f32_e32 v137, 1.0, v139
	v_rcp_f32_e32 v130, v130
	v_rcp_f32_e32 v131, v131
	v_rcp_f32_e32 v136, v136
	v_rcp_f32_e32 v137, v137
	v_add_f32_e32 v139, 1.0, v140
	v_rcp_f32_e32 v133, v133
	v_rcp_f32_e32 v139, v139
	v_pk_mul_f32 v[130:131], v[100:101], v[130:131]
	v_pk_mul_f32 v[136:137], v[102:103], v[136:137]
	v_cvt_pk_bf16_f32 v130, v130, v131
	v_cvt_pk_bf16_f32 v131, v136, v137
	v_mul_f32_e32 v136, 0xbfb8aa3b, v76
	v_pk_mul_f32 v[132:133], v[96:97], v[132:133]
	v_pk_mul_f32 v[138:139], v[98:99], v[138:139]
	v_exp_f32_e32 v136, v136
	v_cvt_pk_bf16_f32 v132, v132, v133
	v_cvt_pk_bf16_f32 v133, v138, v139
	v_mul_f32_e32 v137, 0xbfb8aa3b, v72
	global_store_dwordx4 v[134:135], v[130:133], off sc1
	v_exp_f32_e32 v137, v137
	v_mul_f32_e32 v138, 0xbfb8aa3b, v79
	v_mul_f32_e32 v132, 0xbfb8aa3b, v77
	v_exp_f32_e32 v133, v132
	v_mul_f32_e32 v132, 0xbfb8aa3b, v73
	v_add_f32_e32 v130, 1.0, v136
	v_exp_f32_e32 v136, v132
	v_add_f32_e32 v131, 1.0, v137
	v_mul_f32_e32 v137, 0xbfb8aa3b, v74
	v_rcp_f32_e32 v132, v131
	v_add_f32_e32 v131, 1.0, v133
	v_add_f32_e32 v133, 1.0, v136
	v_mul_f32_e32 v136, 0xbfb8aa3b, v78
	v_exp_f32_e32 v137, v137
	v_exp_f32_e32 v139, v138
	v_mul_f32_e32 v138, 0xbfb8aa3b, v75
	v_exp_f32_e32 v136, v136
	v_exp_f32_e32 v140, v138
	v_add_f32_e32 v137, 1.0, v137
	v_rcp_f32_e32 v138, v137
	v_add_f32_e32 v136, 1.0, v136
	v_add_f32_e32 v137, 1.0, v139
	v_add_f32_e32 v139, 1.0, v140
	v_rcp_f32_e32 v130, v130
	v_rcp_f32_e32 v131, v131
	v_rcp_f32_e32 v133, v133
	v_rcp_f32_e32 v136, v136
	v_rcp_f32_e32 v137, v137
	v_rcp_f32_e32 v139, v139
	v_pk_mul_f32 v[130:131], v[76:77], v[130:131]
	v_pk_mul_f32 v[132:133], v[72:73], v[132:133]
	v_pk_mul_f32 v[136:137], v[78:79], v[136:137]
	v_pk_mul_f32 v[138:139], v[74:75], v[138:139]
	v_cvt_pk_bf16_f32 v130, v130, v131
	v_cvt_pk_bf16_f32 v131, v136, v137
	v_cvt_pk_bf16_f32 v132, v132, v133
	v_cvt_pk_bf16_f32 v133, v138, v139
	global_store_dwordx4 v[134:135], v[130:133], off offset:256 sc1
	v_mul_f32_e32 v137, 0xbfb8aa3b, v82
	v_exp_f32_e32 v137, v137
	v_mul_f32_e32 v132, 0xbfb8aa3b, v84
	v_exp_f32_e32 v132, v132
	v_mul_f32_e32 v133, 0xbfb8aa3b, v80
	v_or_b32_e32 v130, 48, v168
	v_exp_f32_e32 v133, v133
	v_ashrrev_i32_e32 v131, 31, v130
	v_lshlrev_b64 v[130:131], 11, v[130:131]
	v_lshl_add_u64 v[134:135], v[128:129], 0, v[130:131]
	v_add_f32_e32 v130, 1.0, v132
	v_mul_f32_e32 v132, 0xbfb8aa3b, v85
	v_add_f32_e32 v131, 1.0, v133
	v_exp_f32_e32 v133, v132
	v_mul_f32_e32 v132, 0xbfb8aa3b, v81
	v_exp_f32_e32 v136, v132
	v_rcp_f32_e32 v132, v131
	v_add_f32_e32 v131, 1.0, v133
	v_mul_f32_e32 v138, 0xbfb8aa3b, v87
	v_add_f32_e32 v133, 1.0, v136
	v_mul_f32_e32 v136, 0xbfb8aa3b, v86
	v_exp_f32_e32 v136, v136
	v_exp_f32_e32 v139, v138
	v_mul_f32_e32 v138, 0xbfb8aa3b, v83
	v_exp_f32_e32 v140, v138
	v_add_f32_e32 v137, 1.0, v137
	v_add_f32_e32 v136, 1.0, v136
	v_rcp_f32_e32 v138, v137
	v_add_f32_e32 v137, 1.0, v139
	v_rcp_f32_e32 v130, v130
	v_rcp_f32_e32 v131, v131
	v_rcp_f32_e32 v136, v136
	v_rcp_f32_e32 v137, v137
	v_add_f32_e32 v139, 1.0, v140
	v_rcp_f32_e32 v133, v133
	v_rcp_f32_e32 v139, v139
	v_pk_mul_f32 v[130:131], v[84:85], v[130:131]
	v_pk_mul_f32 v[136:137], v[86:87], v[136:137]
	v_cvt_pk_bf16_f32 v130, v130, v131
	v_cvt_pk_bf16_f32 v131, v136, v137
	v_mul_f32_e32 v136, 0xbfb8aa3b, v68
	v_pk_mul_f32 v[132:133], v[80:81], v[132:133]
	v_pk_mul_f32 v[138:139], v[82:83], v[138:139]
	v_exp_f32_e32 v136, v136
	v_cvt_pk_bf16_f32 v132, v132, v133
	v_cvt_pk_bf16_f32 v133, v138, v139
	v_mul_f32_e32 v137, 0xbfb8aa3b, v64
	global_store_dwordx4 v[134:135], v[130:133], off sc1
	v_exp_f32_e32 v137, v137
	v_mul_f32_e32 v138, 0xbfb8aa3b, v71
	v_mul_f32_e32 v132, 0xbfb8aa3b, v69
	v_exp_f32_e32 v133, v132
	v_mul_f32_e32 v132, 0xbfb8aa3b, v65
	v_add_f32_e32 v130, 1.0, v136
; DI unsigned cvtpk(float lo, float hi) { f32x2 v = {lo, hi}; bf16x2_t b = __builtin_convertvector(v, bf16x2_t); return __builtin_bit_cast(unsigned, b); }
; DI unsigned cvtpk_h(float lo, float hi) { f32x2 v = {lo, hi}; h16x2_t b = __builtin_convertvector(v, h16x2_t); return __builtin_bit_cast(unsigned, b); }
;     template <int MODE> __device__ __forceinline__ void run(const f32x4 (&acc)[2][2][4][2], u16* dst, int ld, int row0, int col0, int trow0, int wc, int fq, const float* lb) const {
;     ...
;             for (int m = 0; m < 4; ++m) {
;                 const int rr = ai * HALF + m * 16;
;                 u16* rowp = dst + (size_t)(row0 + rr) * ld + col0;
;                 f32x4 cs, sn;
;                 if (MODE == 1 || MODE == 2) { const int t = trow0 + rr; const int pos = (wc & 1) ? (t & 63) : (t >> 6);
;                     cs = *(const f32x4*)(rcos + pos * 16 + 4 * fq); sn = *(const f32x4*)(rsin + pos * 16 + 4 * fq); }
; #pragma unroll
;                 for (int bj = 0; bj < 2; ++bj) {
;                     f32x4 v0 = acc[ai][bj][m][0], v1 = acc[ai][bj][m][1];
;                     if (MODE == 1 || MODE == 2) { const f32x4 a = v0 * cs - v1 * sn, b = v1 * cs + v0 * sn; v0 = a; v1 = b;
;                         if (MODE == 2) { v0 = v0 * 0.18033688011112042f; v1 = v1 * 0.18033688011112042f; } }
;                     if (MODE == 3) {
; #pragma unroll
;                         for (int i = 0; i < 4; ++i) { const float l0 = lb0[bj][i], l1 = lb1[bj][i];
;                             v0[i] = __logf(l0 + (1.f - l0) * sigm(v0[i])); v1[i] = __logf(l1 + (1.f - l1) * sigm(v1[i])); }
;                     }
;                     if (MODE == 4) {
; #pragma unroll
;                         for (int i = 0; i < 4; ++i) { v0[i] = silu_(v0[i]); v1[i] = silu_(v1[i]); }
;                     }
;                     if (MODE == 5) {
; #pragma unroll
;                         for (int i = 0; i < 4; ++i) { v0[i] = sigm(v0[i]); v1[i] = sigm(v1[i]); }
;                     }
;                     u32x4 w;
;                     if (MODE == 3) { w.x = cvtpk_h(v0[0], v0[1]); w.y = cvtpk_h(v0[2], v0[3]); w.z = cvtpk_h(v1[0], v1[1]); w.w = cvtpk_h(v1[2], v1[3]); }
;                     else { w.x = cvtpk(v0[0], v0[1]); w.y = cvtpk(v0[2], v0[3]); w.z = cvtpk(v1[0], v1[1]); w.w = cvtpk(v1[2], v1[3]); }
;                     *(u32x4*)(rowp + bj * HALF) = w;
	v_exp_f32_e32 v136, v132
	v_add_f32_e32 v131, 1.0, v137
	v_mul_f32_e32 v137, 0xbfb8aa3b, v66
	v_rcp_f32_e32 v132, v131
	v_add_f32_e32 v131, 1.0, v133
	v_add_f32_e32 v133, 1.0, v136
	v_mul_f32_e32 v136, 0xbfb8aa3b, v70
	v_exp_f32_e32 v137, v137
	v_exp_f32_e32 v139, v138
	v_mul_f32_e32 v138, 0xbfb8aa3b, v67
	v_exp_f32_e32 v136, v136
	v_exp_f32_e32 v140, v138
	v_add_f32_e32 v137, 1.0, v137
	v_rcp_f32_e32 v138, v137
	v_add_f32_e32 v136, 1.0, v136
	v_add_f32_e32 v137, 1.0, v139
	v_add_f32_e32 v139, 1.0, v140
	v_rcp_f32_e32 v130, v130
	v_rcp_f32_e32 v131, v131
	v_rcp_f32_e32 v133, v133
	v_rcp_f32_e32 v136, v136
	v_rcp_f32_e32 v137, v137
	v_rcp_f32_e32 v139, v139
	v_pk_mul_f32 v[130:131], v[68:69], v[130:131]
	v_pk_mul_f32 v[132:133], v[64:65], v[132:133]
	v_pk_mul_f32 v[136:137], v[70:71], v[136:137]
	v_pk_mul_f32 v[138:139], v[66:67], v[138:139]
	v_cvt_pk_bf16_f32 v130, v130, v131
	v_cvt_pk_bf16_f32 v131, v136, v137
	v_cvt_pk_bf16_f32 v132, v132, v133
	v_cvt_pk_bf16_f32 v133, v138, v139
	global_store_dwordx4 v[134:135], v[130:133], off offset:256 sc1
	v_mul_f32_e32 v137, 0xbfb8aa3b, v58
	v_exp_f32_e32 v137, v137
	v_mul_f32_e32 v132, 0xbfb8aa3b, v60
	v_exp_f32_e32 v132, v132
	v_mul_f32_e32 v133, 0xbfb8aa3b, v56
	v_add_u32_e32 v130, 0x80, v168
	v_exp_f32_e32 v133, v133
	v_ashrrev_i32_e32 v131, 31, v130
	v_lshlrev_b64 v[130:131], 11, v[130:131]
	v_lshl_add_u64 v[134:135], v[128:129], 0, v[130:131]
	v_add_f32_e32 v130, 1.0, v132
	v_mul_f32_e32 v132, 0xbfb8aa3b, v61
	v_add_f32_e32 v131, 1.0, v133
	v_exp_f32_e32 v133, v132
	v_mul_f32_e32 v132, 0xbfb8aa3b, v57
	v_exp_f32_e32 v136, v132
	v_rcp_f32_e32 v132, v131
	v_add_f32_e32 v131, 1.0, v133
	v_mul_f32_e32 v138, 0xbfb8aa3b, v63
	v_add_f32_e32 v133, 1.0, v136
	v_mul_f32_e32 v136, 0xbfb8aa3b, v62
	v_exp_f32_e32 v136, v136
	v_exp_f32_e32 v139, v138
	v_mul_f32_e32 v138, 0xbfb8aa3b, v59
	v_exp_f32_e32 v140, v138
	v_add_f32_e32 v137, 1.0, v137
	v_add_f32_e32 v136, 1.0, v136
	v_rcp_f32_e32 v138, v137
	v_add_f32_e32 v137, 1.0, v139
	v_rcp_f32_e32 v130, v130
	v_rcp_f32_e32 v131, v131
	v_rcp_f32_e32 v136, v136
	v_rcp_f32_e32 v137, v137
	v_add_f32_e32 v139, 1.0, v140
	v_rcp_f32_e32 v133, v133
	v_rcp_f32_e32 v139, v139
	v_pk_mul_f32 v[130:131], v[60:61], v[130:131]
	v_pk_mul_f32 v[136:137], v[62:63], v[136:137]
	v_cvt_pk_bf16_f32 v130, v130, v131
	v_cvt_pk_bf16_f32 v131, v136, v137
	v_mul_f32_e32 v136, 0xbfb8aa3b, v44
	v_pk_mul_f32 v[132:133], v[56:57], v[132:133]
	v_pk_mul_f32 v[138:139], v[58:59], v[138:139]
	v_exp_f32_e32 v136, v136
	v_cvt_pk_bf16_f32 v132, v132, v133
	v_cvt_pk_bf16_f32 v133, v138, v139
	v_mul_f32_e32 v137, 0xbfb8aa3b, v40
	global_store_dwordx4 v[134:135], v[130:133], off sc1
	v_exp_f32_e32 v137, v137
	v_mul_f32_e32 v138, 0xbfb8aa3b, v47
	v_mul_f32_e32 v132, 0xbfb8aa3b, v45
	v_exp_f32_e32 v133, v132
	v_mul_f32_e32 v132, 0xbfb8aa3b, v41
	v_add_f32_e32 v130, 1.0, v136
	v_exp_f32_e32 v136, v132
	v_add_f32_e32 v131, 1.0, v137
	v_mul_f32_e32 v137, 0xbfb8aa3b, v42
	v_rcp_f32_e32 v132, v131
	v_add_f32_e32 v131, 1.0, v133
	v_add_f32_e32 v133, 1.0, v136
	v_mul_f32_e32 v136, 0xbfb8aa3b, v46
	v_exp_f32_e32 v137, v137
	v_exp_f32_e32 v139, v138
	v_mul_f32_e32 v138, 0xbfb8aa3b, v43
	v_exp_f32_e32 v136, v136
	v_exp_f32_e32 v140, v138
	v_add_f32_e32 v137, 1.0, v137
	v_rcp_f32_e32 v138, v137
	v_add_f32_e32 v136, 1.0, v136
	v_add_f32_e32 v137, 1.0, v139
	v_add_f32_e32 v139, 1.0, v140
	v_rcp_f32_e32 v130, v130
	v_rcp_f32_e32 v131, v131
	v_rcp_f32_e32 v133, v133
	v_rcp_f32_e32 v136, v136
	v_rcp_f32_e32 v137, v137
	v_rcp_f32_e32 v139, v139
	v_pk_mul_f32 v[130:131], v[44:45], v[130:131]
	v_pk_mul_f32 v[132:133], v[40:41], v[132:133]
	v_pk_mul_f32 v[136:137], v[46:47], v[136:137]
	v_pk_mul_f32 v[138:139], v[42:43], v[138:139]
	v_cvt_pk_bf16_f32 v130, v130, v131
	v_cvt_pk_bf16_f32 v131, v136, v137
	v_cvt_pk_bf16_f32 v132, v132, v133
	v_cvt_pk_bf16_f32 v133, v138, v139
	global_store_dwordx4 v[134:135], v[130:133], off offset:256 sc1
	v_mul_f32_e32 v137, 0xbfb8aa3b, v50
	v_exp_f32_e32 v137, v137
	v_mul_f32_e32 v132, 0xbfb8aa3b, v52
	v_exp_f32_e32 v132, v132
	v_mul_f32_e32 v133, 0xbfb8aa3b, v48
	v_add_u32_e32 v130, 0x90, v168
	v_exp_f32_e32 v133, v133
	v_ashrrev_i32_e32 v131, 31, v130
	v_lshlrev_b64 v[130:131], 11, v[130:131]
	v_lshl_add_u64 v[134:135], v[128:129], 0, v[130:131]
	v_add_f32_e32 v130, 1.0, v132
	v_mul_f32_e32 v132, 0xbfb8aa3b, v53
	v_add_f32_e32 v131, 1.0, v133
	v_exp_f32_e32 v133, v132
	v_mul_f32_e32 v132, 0xbfb8aa3b, v49
	v_exp_f32_e32 v136, v132
	v_rcp_f32_e32 v132, v131
	v_add_f32_e32 v131, 1.0, v133
	v_mul_f32_e32 v138, 0xbfb8aa3b, v55
	v_add_f32_e32 v133, 1.0, v136
	v_mul_f32_e32 v136, 0xbfb8aa3b, v54
	v_exp_f32_e32 v136, v136
	v_exp_f32_e32 v139, v138
	v_mul_f32_e32 v138, 0xbfb8aa3b, v51
	v_exp_f32_e32 v140, v138
	v_add_f32_e32 v137, 1.0, v137
	v_add_f32_e32 v136, 1.0, v136
	v_rcp_f32_e32 v138, v137
	v_add_f32_e32 v137, 1.0, v139
	v_rcp_f32_e32 v130, v130
	v_rcp_f32_e32 v131, v131
	v_rcp_f32_e32 v136, v136
	v_rcp_f32_e32 v137, v137
	v_add_f32_e32 v139, 1.0, v140
	v_rcp_f32_e32 v133, v133
	v_rcp_f32_e32 v139, v139
	v_pk_mul_f32 v[130:131], v[52:53], v[130:131]
	v_pk_mul_f32 v[136:137], v[54:55], v[136:137]
	v_cvt_pk_bf16_f32 v130, v130, v131
	v_cvt_pk_bf16_f32 v131, v136, v137
	v_mul_f32_e32 v136, 0xbfb8aa3b, v28
	v_pk_mul_f32 v[132:133], v[48:49], v[132:133]
	v_pk_mul_f32 v[138:139], v[50:51], v[138:139]
	v_exp_f32_e32 v136, v136
	v_cvt_pk_bf16_f32 v132, v132, v133
	v_cvt_pk_bf16_f32 v133, v138, v139
	v_mul_f32_e32 v137, 0xbfb8aa3b, v24
	global_store_dwordx4 v[134:135], v[130:133], off sc1
	v_exp_f32_e32 v137, v137
	v_mul_f32_e32 v138, 0xbfb8aa3b, v31
	v_mul_f32_e32 v132, 0xbfb8aa3b, v29
; DI unsigned cvtpk(float lo, float hi) { f32x2 v = {lo, hi}; bf16x2_t b = __builtin_convertvector(v, bf16x2_t); return __builtin_bit_cast(unsigned, b); }
; DI unsigned cvtpk_h(float lo, float hi) { f32x2 v = {lo, hi}; h16x2_t b = __builtin_convertvector(v, h16x2_t); return __builtin_bit_cast(unsigned, b); }
;     template <int MODE> __device__ __forceinline__ void run(const f32x4 (&acc)[2][2][4][2], u16* dst, int ld, int row0, int col0, int trow0, int wc, int fq, const float* lb) const {
;     ...
;             for (int m = 0; m < 4; ++m) {
;                 const int rr = ai * HALF + m * 16;
;                 u16* rowp = dst + (size_t)(row0 + rr) * ld + col0;
;                 f32x4 cs, sn;
;                 if (MODE == 1 || MODE == 2) { const int t = trow0 + rr; const int pos = (wc & 1) ? (t & 63) : (t >> 6);
;                     cs = *(const f32x4*)(rcos + pos * 16 + 4 * fq); sn = *(const f32x4*)(rsin + pos * 16 + 4 * fq); }
; #pragma unroll
;                 for (int bj = 0; bj < 2; ++bj) {
;                     f32x4 v0 = acc[ai][bj][m][0], v1 = acc[ai][bj][m][1];
;                     if (MODE == 1 || MODE == 2) { const f32x4 a = v0 * cs - v1 * sn, b = v1 * cs + v0 * sn; v0 = a; v1 = b;
;                         if (MODE == 2) { v0 = v0 * 0.18033688011112042f; v1 = v1 * 0.18033688011112042f; } }
;                     if (MODE == 3) {
; #pragma unroll
;                         for (int i = 0; i < 4; ++i) { const float l0 = lb0[bj][i], l1 = lb1[bj][i];
;                             v0[i] = __logf(l0 + (1.f - l0) * sigm(v0[i])); v1[i] = __logf(l1 + (1.f - l1) * sigm(v1[i])); }
;                     }
;                     if (MODE == 4) {
; #pragma unroll
;                         for (int i = 0; i < 4; ++i) { v0[i] = silu_(v0[i]); v1[i] = silu_(v1[i]); }
;                     }
;                     if (MODE == 5) {
; #pragma unroll
;                         for (int i = 0; i < 4; ++i) { v0[i] = sigm(v0[i]); v1[i] = sigm(v1[i]); }
;                     }
;                     u32x4 w;
;                     if (MODE == 3) { w.x = cvtpk_h(v0[0], v0[1]); w.y = cvtpk_h(v0[2], v0[3]); w.z = cvtpk_h(v1[0], v1[1]); w.w = cvtpk_h(v1[2], v1[3]); }
;                     else { w.x = cvtpk(v0[0], v0[1]); w.y = cvtpk(v0[2], v0[3]); w.z = cvtpk(v1[0], v1[1]); w.w = cvtpk(v1[2], v1[3]); }
;                     *(u32x4*)(rowp + bj * HALF) = w;
	v_exp_f32_e32 v133, v132
	v_mul_f32_e32 v132, 0xbfb8aa3b, v25
	v_add_f32_e32 v130, 1.0, v136
	v_exp_f32_e32 v136, v132
	v_add_f32_e32 v131, 1.0, v137
	v_mul_f32_e32 v137, 0xbfb8aa3b, v26
	v_rcp_f32_e32 v132, v131
	v_add_f32_e32 v131, 1.0, v133
	v_add_f32_e32 v133, 1.0, v136
	v_mul_f32_e32 v136, 0xbfb8aa3b, v30
	v_exp_f32_e32 v137, v137
	v_exp_f32_e32 v139, v138
	v_mul_f32_e32 v138, 0xbfb8aa3b, v27
	v_exp_f32_e32 v136, v136
	v_exp_f32_e32 v140, v138
	v_add_f32_e32 v137, 1.0, v137
	v_rcp_f32_e32 v138, v137
	v_add_f32_e32 v136, 1.0, v136
	v_add_f32_e32 v137, 1.0, v139
	v_add_f32_e32 v139, 1.0, v140
	v_rcp_f32_e32 v130, v130
	v_rcp_f32_e32 v131, v131
	v_rcp_f32_e32 v133, v133
	v_rcp_f32_e32 v136, v136
	v_rcp_f32_e32 v137, v137
	v_rcp_f32_e32 v139, v139
	v_pk_mul_f32 v[130:131], v[28:29], v[130:131]
	v_pk_mul_f32 v[132:133], v[24:25], v[132:133]
	v_pk_mul_f32 v[136:137], v[30:31], v[136:137]
	v_pk_mul_f32 v[138:139], v[26:27], v[138:139]
	v_cvt_pk_bf16_f32 v130, v130, v131
	v_cvt_pk_bf16_f32 v131, v136, v137
	v_cvt_pk_bf16_f32 v132, v132, v133
	v_cvt_pk_bf16_f32 v133, v138, v139
	global_store_dwordx4 v[134:135], v[130:133], off offset:256 sc1
	v_mul_f32_e32 v137, 0xbfb8aa3b, v34
	v_exp_f32_e32 v137, v137
	v_mul_f32_e32 v132, 0xbfb8aa3b, v36
	v_exp_f32_e32 v132, v132
	v_mul_f32_e32 v133, 0xbfb8aa3b, v32
	v_add_u32_e32 v130, 0xa0, v168
	v_exp_f32_e32 v133, v133
	v_ashrrev_i32_e32 v131, 31, v130
	v_lshlrev_b64 v[130:131], 11, v[130:131]
	v_lshl_add_u64 v[134:135], v[128:129], 0, v[130:131]
	v_add_f32_e32 v130, 1.0, v132
	v_mul_f32_e32 v132, 0xbfb8aa3b, v37
	v_add_f32_e32 v131, 1.0, v133
	v_exp_f32_e32 v133, v132
	v_mul_f32_e32 v132, 0xbfb8aa3b, v33
	v_exp_f32_e32 v136, v132
	v_rcp_f32_e32 v132, v131
	v_add_f32_e32 v131, 1.0, v133
	v_mul_f32_e32 v138, 0xbfb8aa3b, v39
	v_add_f32_e32 v133, 1.0, v136
	v_mul_f32_e32 v136, 0xbfb8aa3b, v38
	v_exp_f32_e32 v136, v136
	v_exp_f32_e32 v139, v138
	v_mul_f32_e32 v138, 0xbfb8aa3b, v35
	v_exp_f32_e32 v140, v138
	v_add_f32_e32 v137, 1.0, v137
	v_add_f32_e32 v136, 1.0, v136
	v_rcp_f32_e32 v138, v137
	v_add_f32_e32 v137, 1.0, v139
	v_rcp_f32_e32 v130, v130
	v_rcp_f32_e32 v131, v131
	v_rcp_f32_e32 v136, v136
	v_rcp_f32_e32 v137, v137
	v_add_f32_e32 v139, 1.0, v140
	v_rcp_f32_e32 v133, v133
	v_rcp_f32_e32 v139, v139
	v_pk_mul_f32 v[130:131], v[36:37], v[130:131]
	v_pk_mul_f32 v[136:137], v[38:39], v[136:137]
	v_cvt_pk_bf16_f32 v130, v130, v131
	v_cvt_pk_bf16_f32 v131, v136, v137
	v_mul_f32_e32 v136, 0xbfb8aa3b, v12
	v_pk_mul_f32 v[132:133], v[32:33], v[132:133]
	v_pk_mul_f32 v[138:139], v[34:35], v[138:139]
	v_exp_f32_e32 v136, v136
	v_cvt_pk_bf16_f32 v132, v132, v133
	v_cvt_pk_bf16_f32 v133, v138, v139
	v_mul_f32_e32 v137, 0xbfb8aa3b, v8
	global_store_dwordx4 v[134:135], v[130:133], off sc1
	v_exp_f32_e32 v137, v137
	v_mul_f32_e32 v138, 0xbfb8aa3b, v15
	v_mul_f32_e32 v132, 0xbfb8aa3b, v13
	v_exp_f32_e32 v133, v132
	v_mul_f32_e32 v132, 0xbfb8aa3b, v9
	v_add_f32_e32 v130, 1.0, v136
	v_exp_f32_e32 v136, v132
	v_add_f32_e32 v131, 1.0, v137
	v_mul_f32_e32 v137, 0xbfb8aa3b, v10
	v_rcp_f32_e32 v132, v131
	v_add_f32_e32 v131, 1.0, v133
	v_add_f32_e32 v133, 1.0, v136
	v_mul_f32_e32 v136, 0xbfb8aa3b, v14
	v_exp_f32_e32 v137, v137
	v_exp_f32_e32 v139, v138
	v_mul_f32_e32 v138, 0xbfb8aa3b, v11
	v_exp_f32_e32 v136, v136
	v_exp_f32_e32 v140, v138
	v_add_f32_e32 v137, 1.0, v137
	v_rcp_f32_e32 v138, v137
	v_add_f32_e32 v136, 1.0, v136
	v_add_f32_e32 v137, 1.0, v139
	v_add_f32_e32 v139, 1.0, v140
	v_rcp_f32_e32 v130, v130
	v_rcp_f32_e32 v131, v131
	v_rcp_f32_e32 v133, v133
	v_rcp_f32_e32 v136, v136
	v_rcp_f32_e32 v137, v137
	v_rcp_f32_e32 v139, v139
	v_pk_mul_f32 v[130:131], v[12:13], v[130:131]
	v_pk_mul_f32 v[132:133], v[8:9], v[132:133]
	v_pk_mul_f32 v[136:137], v[14:15], v[136:137]
	v_pk_mul_f32 v[138:139], v[10:11], v[138:139]
	v_cvt_pk_bf16_f32 v130, v130, v131
	v_cvt_pk_bf16_f32 v131, v136, v137
	v_cvt_pk_bf16_f32 v132, v132, v133
	v_cvt_pk_bf16_f32 v133, v138, v139
	global_store_dwordx4 v[134:135], v[130:133], off offset:256 sc1
	v_mul_f32_e32 v134, 0xbfb8aa3b, v23
	v_exp_f32_e32 v135, v134
	v_add_u32_e32 v130, 0xb0, v168
	v_mul_f32_e32 v132, 0xbfb8aa3b, v20
	v_ashrrev_i32_e32 v131, 31, v130
	v_exp_f32_e32 v132, v132
	v_lshlrev_b64 v[130:131], 11, v[130:131]
	v_mul_f32_e32 v133, 0xbfb8aa3b, v16
	v_lshl_add_u64 v[170:171], v[128:129], 0, v[130:131]
	v_mul_f32_e32 v130, 0xbfb8aa3b, v21
	v_exp_f32_e32 v133, v133
	v_exp_f32_e32 v131, v130
	v_mul_f32_e32 v130, 0xbfb8aa3b, v17
	v_add_f32_e32 v128, 1.0, v132
	v_exp_f32_e32 v132, v130
	v_add_f32_e32 v129, 1.0, v133
	v_mul_f32_e32 v133, 0xbfb8aa3b, v18
	v_rcp_f32_e32 v130, v129
	v_add_f32_e32 v129, 1.0, v131
	v_add_f32_e32 v131, 1.0, v132
	v_mul_f32_e32 v132, 0xbfb8aa3b, v22
	v_exp_f32_e32 v133, v133
	v_exp_f32_e32 v132, v132
	v_mul_f32_e32 v134, 0xbfb8aa3b, v19
	v_exp_f32_e32 v136, v134
	v_add_f32_e32 v133, 1.0, v133
	v_add_f32_e32 v132, 1.0, v132
	v_rcp_f32_e32 v134, v133
	v_add_f32_e32 v133, 1.0, v135
	v_rcp_f32_e32 v128, v128
	v_rcp_f32_e32 v129, v129
	v_rcp_f32_e32 v132, v132
	v_rcp_f32_e32 v133, v133
	v_add_f32_e32 v135, 1.0, v136
	v_rcp_f32_e32 v131, v131
	v_rcp_f32_e32 v135, v135
	v_pk_mul_f32 v[128:129], v[20:21], v[128:129]
	v_pk_mul_f32 v[132:133], v[22:23], v[132:133]
	v_cvt_pk_bf16_f32 v128, v128, v129
	v_cvt_pk_bf16_f32 v129, v132, v133
	v_mul_f32_e32 v132, 0xbfb8aa3b, v4
	v_pk_mul_f32 v[130:131], v[16:17], v[130:131]
	v_pk_mul_f32 v[134:135], v[18:19], v[134:135]
	v_exp_f32_e32 v132, v132
	v_cvt_pk_bf16_f32 v130, v130, v131
	v_cvt_pk_bf16_f32 v131, v134, v135
	v_mul_f32_e32 v133, 0xbfb8aa3b, v0
	global_store_dwordx4 v[170:171], v[128:131], off sc1
	v_exp_f32_e32 v133, v133
	v_mul_f32_e32 v134, 0xbfb8aa3b, v7
	v_mul_f32_e32 v130, 0xbfb8aa3b, v5
	v_exp_f32_e32 v131, v130
	v_mul_f32_e32 v130, 0xbfb8aa3b, v1
	v_add_f32_e32 v128, 1.0, v132
	v_exp_f32_e32 v132, v130
	v_add_f32_e32 v129, 1.0, v133
	v_mul_f32_e32 v133, 0xbfb8aa3b, v2
	v_rcp_f32_e32 v130, v129
	v_add_f32_e32 v129, 1.0, v131
	v_add_f32_e32 v131, 1.0, v132
	v_mul_f32_e32 v132, 0xbfb8aa3b, v6
	v_exp_f32_e32 v133, v133
	v_exp_f32_e32 v135, v134
	v_mul_f32_e32 v134, 0xbfb8aa3b, v3
	v_exp_f32_e32 v132, v132
	v_exp_f32_e32 v136, v134
	v_add_f32_e32 v133, 1.0, v133
	v_rcp_f32_e32 v134, v133
	v_add_f32_e32 v132, 1.0, v132
	v_add_f32_e32 v133, 1.0, v135
	v_add_f32_e32 v135, 1.0, v136
	v_rcp_f32_e32 v128, v128
	v_rcp_f32_e32 v129, v129
	v_rcp_f32_e32 v131, v131
	v_rcp_f32_e32 v132, v132
	v_rcp_f32_e32 v133, v133
	v_rcp_f32_e32 v135, v135
	v_pk_mul_f32 v[128:129], v[4:5], v[128:129]
	v_pk_mul_f32 v[130:131], v[0:1], v[130:131]
	v_pk_mul_f32 v[132:133], v[6:7], v[132:133]
	v_pk_mul_f32 v[134:135], v[2:3], v[134:135]
	v_cvt_pk_bf16_f32 v128, v128, v129
	v_cvt_pk_bf16_f32 v129, v132, v133
	v_cvt_pk_bf16_f32 v130, v130, v131
	v_cvt_pk_bf16_f32 v131, v134, v135
	s_mov_b64 s[68:69], 0

; DI unsigned cvtpk(float lo, float hi) { f32x2 v = {lo, hi}; bf16x2_t b = __builtin_convertvector(v, bf16x2_t); return __builtin_bit_cast(unsigned, b); }
; DI unsigned cvtpk_h(float lo, float hi) { f32x2 v = {lo, hi}; h16x2_t b = __builtin_convertvector(v, h16x2_t); return __builtin_bit_cast(unsigned, b); }
; DI float sigm(float x) { return __builtin_amdgcn_rcpf(1.f + fexp(-x)); }
; DI float silu_(float x) { return x * sigm(x); }
;     template <int MODE> __device__ __forceinline__ void run(const f32x4 (&acc)[2][2][4][2], u16* dst, int ld, int row0, int col0, int trow0, int wc, int fq, const float* lb) const {
;     ...
;                     if (MODE == 4) {
; #pragma unroll
;                         for (int i = 0; i < 4; ++i) { v0[i] = silu_(v0[i]); v1[i] = silu_(v1[i]); }
;                     }
;                     if (MODE == 5) {
; #pragma unroll
;                         for (int i = 0; i < 4; ++i) { v0[i] = sigm(v0[i]); v1[i] = sigm(v1[i]); }
;                     }
;                     u32x4 w;
;                     if (MODE == 3) { w.x = cvtpk_h(v0[0], v0[1]); w.y = cvtpk_h(v0[2], v0[3]); w.z = cvtpk_h(v1[0], v1[1]); w.w = cvtpk_h(v1[2], v1[3]); }
;                     else { w.x = cvtpk(v0[0], v0[1]); w.y = cvtpk(v0[2], v0[3]); w.z = cvtpk(v1[0], v1[1]); w.w = cvtpk(v1[2], v1[3]); }
;                     *(u32x4*)(rowp + bj * HALF) = w;
;     __device__ __forceinline__ void operator()(const f32x4 (&acc)[2][2][4][2], const Unit& u, int wr, int wc, int fr, int fq) const {
;     ...
;         case 6: run<4>(acc, RQ, 1024, latrow0, c1, trow0, wc, fq, nullptr); break;
.LBB0_187:
	s_and_b64 vcc, exec, s[8:9]
	s_cbranch_vccz .LBB0_189
	v_mul_f32_e32 v132, 0xbfb8aa3b, v124
	v_exp_f32_e32 v132, v132
	v_mul_f32_e32 v133, 0xbfb8aa3b, v120
	v_exp_f32_e32 v133, v133
	v_lshlrev_b32_e32 v152, 1, v187
	v_ashrrev_i32_e32 v169, 31, v168
	v_lshl_add_u64 v[128:129], s[30:31], 0, v[152:153]
	v_lshlrev_b64 v[130:131], 11, v[168:169]
	v_lshl_add_u64 v[134:135], v[128:129], 0, v[130:131]
	v_add_f32_e32 v130, 1.0, v132
	v_mul_f32_e32 v132, 0xbfb8aa3b, v125
	v_add_f32_e32 v131, 1.0, v133
	v_exp_f32_e32 v133, v132
	v_mul_f32_e32 v132, 0xbfb8aa3b, v121
	v_exp_f32_e32 v136, v132
	v_mul_f32_e32 v137, 0xbfb8aa3b, v122
	v_rcp_f32_e32 v132, v131
	v_add_f32_e32 v131, 1.0, v133
	v_add_f32_e32 v133, 1.0, v136
	v_mul_f32_e32 v136, 0xbfb8aa3b, v126
	v_exp_f32_e32 v137, v137
	v_mul_f32_e32 v138, 0xbfb8aa3b, v127
	v_exp_f32_e32 v136, v136
	v_exp_f32_e32 v139, v138
	v_mul_f32_e32 v138, 0xbfb8aa3b, v123
	v_exp_f32_e32 v140, v138
	v_add_f32_e32 v137, 1.0, v137
	v_add_f32_e32 v136, 1.0, v136
	v_rcp_f32_e32 v138, v137
	v_add_f32_e32 v137, 1.0, v139
	v_rcp_f32_e32 v130, v130
	v_rcp_f32_e32 v131, v131
	v_rcp_f32_e32 v136, v136
	v_rcp_f32_e32 v137, v137
	v_add_f32_e32 v139, 1.0, v140
	v_rcp_f32_e32 v133, v133
	v_rcp_f32_e32 v139, v139
	v_pk_mul_f32 v[130:131], v[124:125], v[130:131]
	v_pk_mul_f32 v[136:137], v[126:127], v[136:137]
	v_cvt_pk_bf16_f32 v130, v130, v131
	v_cvt_pk_bf16_f32 v131, v136, v137
	v_mul_f32_e32 v136, 0xbfb8aa3b, v108
	v_pk_mul_f32 v[132:133], v[120:121], v[132:133]
	v_pk_mul_f32 v[138:139], v[122:123], v[138:139]
	v_exp_f32_e32 v136, v136
	v_cvt_pk_bf16_f32 v132, v132, v133
	v_cvt_pk_bf16_f32 v133, v138, v139
	v_mul_f32_e32 v137, 0xbfb8aa3b, v104
	global_store_dwordx4 v[134:135], v[130:133], off sc1
	v_exp_f32_e32 v137, v137
	v_mul_f32_e32 v138, 0xbfb8aa3b, v111
	v_mul_f32_e32 v132, 0xbfb8aa3b, v109
	v_exp_f32_e32 v133, v132
	v_mul_f32_e32 v132, 0xbfb8aa3b, v105
	v_add_f32_e32 v130, 1.0, v136
	v_exp_f32_e32 v136, v132
	v_add_f32_e32 v131, 1.0, v137
	v_mul_f32_e32 v137, 0xbfb8aa3b, v106
	v_rcp_f32_e32 v132, v131
	v_add_f32_e32 v131, 1.0, v133
	v_add_f32_e32 v133, 1.0, v136
	v_mul_f32_e32 v136, 0xbfb8aa3b, v110
	v_exp_f32_e32 v137, v137
	v_exp_f32_e32 v139, v138
	v_mul_f32_e32 v138, 0xbfb8aa3b, v107
	v_exp_f32_e32 v136, v136
	v_exp_f32_e32 v140, v138
	v_add_f32_e32 v137, 1.0, v137
	v_rcp_f32_e32 v138, v137
	v_add_f32_e32 v136, 1.0, v136
	v_add_f32_e32 v137, 1.0, v139
	v_add_f32_e32 v139, 1.0, v140
	v_rcp_f32_e32 v130, v130
	v_rcp_f32_e32 v131, v131
	v_rcp_f32_e32 v133, v133
	v_rcp_f32_e32 v136, v136
	v_rcp_f32_e32 v137, v137
	v_rcp_f32_e32 v139, v139
	v_pk_mul_f32 v[130:131], v[108:109], v[130:131]
	v_pk_mul_f32 v[132:133], v[104:105], v[132:133]
	v_pk_mul_f32 v[136:137], v[110:111], v[136:137]
	v_pk_mul_f32 v[138:139], v[106:107], v[138:139]
	v_cvt_pk_bf16_f32 v130, v130, v131
	v_cvt_pk_bf16_f32 v131, v136, v137
	v_cvt_pk_bf16_f32 v132, v132, v133
	v_cvt_pk_bf16_f32 v133, v138, v139
	global_store_dwordx4 v[134:135], v[130:133], off offset:256 sc1
	v_mul_f32_e32 v137, 0xbfb8aa3b, v114
	v_exp_f32_e32 v137, v137
	v_mul_f32_e32 v132, 0xbfb8aa3b, v116
	v_exp_f32_e32 v132, v132
	v_mul_f32_e32 v133, 0xbfb8aa3b, v112
	v_or_b32_e32 v130, 16, v168
	v_exp_f32_e32 v133, v133
	v_ashrrev_i32_e32 v131, 31, v130
	v_lshlrev_b64 v[130:131], 11, v[130:131]
	v_lshl_add_u64 v[134:135], v[128:129], 0, v[130:131]
	v_add_f32_e32 v130, 1.0, v132
	v_mul_f32_e32 v132, 0xbfb8aa3b, v117
	v_add_f32_e32 v131, 1.0, v133
	v_exp_f32_e32 v133, v132
	v_mul_f32_e32 v132, 0xbfb8aa3b, v113
	v_exp_f32_e32 v136, v132
	v_rcp_f32_e32 v132, v131
	v_add_f32_e32 v131, 1.0, v133
	v_mul_f32_e32 v138, 0xbfb8aa3b, v119
	v_add_f32_e32 v133, 1.0, v136
	v_mul_f32_e32 v136, 0xbfb8aa3b, v118
	v_exp_f32_e32 v136, v136
	v_exp_f32_e32 v139, v138
	v_mul_f32_e32 v138, 0xbfb8aa3b, v115
	v_exp_f32_e32 v140, v138
	v_add_f32_e32 v137, 1.0, v137
	v_add_f32_e32 v136, 1.0, v136
	v_rcp_f32_e32 v138, v137
	v_add_f32_e32 v137, 1.0, v139
	v_rcp_f32_e32 v130, v130
	v_rcp_f32_e32 v131, v131
	v_rcp_f32_e32 v136, v136
	v_rcp_f32_e32 v137, v137
	v_add_f32_e32 v139, 1.0, v140
	v_rcp_f32_e32 v133, v133
	v_rcp_f32_e32 v139, v139
	v_pk_mul_f32 v[130:131], v[116:117], v[130:131]
	v_pk_mul_f32 v[136:137], v[118:119], v[136:137]
	v_cvt_pk_bf16_f32 v130, v130, v131
	v_cvt_pk_bf16_f32 v131, v136, v137
	v_mul_f32_e32 v136, 0xbfb8aa3b, v92
	v_pk_mul_f32 v[132:133], v[112:113], v[132:133]
	v_pk_mul_f32 v[138:139], v[114:115], v[138:139]
	v_exp_f32_e32 v136, v136
	v_cvt_pk_bf16_f32 v132, v132, v133
	v_cvt_pk_bf16_f32 v133, v138, v139
	v_mul_f32_e32 v137, 0xbfb8aa3b, v88
	global_store_dwordx4 v[134:135], v[130:133], off sc1
	v_exp_f32_e32 v137, v137
	v_mul_f32_e32 v138, 0xbfb8aa3b, v95
	v_mul_f32_e32 v132, 0xbfb8aa3b, v93
	v_exp_f32_e32 v133, v132
	v_mul_f32_e32 v132, 0xbfb8aa3b, v89
	v_add_f32_e32 v130, 1.0, v136
	v_exp_f32_e32 v136, v132
	v_add_f32_e32 v131, 1.0, v137
	v_mul_f32_e32 v137, 0xbfb8aa3b, v90
	v_rcp_f32_e32 v132, v131
	v_add_f32_e32 v131, 1.0, v133
	v_add_f32_e32 v133, 1.0, v136
	v_mul_f32_e32 v136, 0xbfb8aa3b, v94
	v_exp_f32_e32 v137, v137
	v_exp_f32_e32 v139, v138
	v_mul_f32_e32 v138, 0xbfb8aa3b, v91
	v_exp_f32_e32 v136, v136
	v_exp_f32_e32 v140, v138
	v_add_f32_e32 v137, 1.0, v137
	v_rcp_f32_e32 v138, v137
	v_add_f32_e32 v136, 1.0, v136
	v_add_f32_e32 v137, 1.0, v139
	v_add_f32_e32 v139, 1.0, v140
	v_rcp_f32_e32 v130, v130
	v_rcp_f32_e32 v131, v131
	v_rcp_f32_e32 v133, v133
	v_rcp_f32_e32 v136, v136
	v_rcp_f32_e32 v137, v137
	v_rcp_f32_e32 v139, v139
	v_pk_mul_f32 v[130:131], v[92:93], v[130:131]
	v_pk_mul_f32 v[132:133], v[88:89], v[132:133]
	v_pk_mul_f32 v[136:137], v[94:95], v[136:137]
; DI unsigned cvtpk(float lo, float hi) { f32x2 v = {lo, hi}; bf16x2_t b = __builtin_convertvector(v, bf16x2_t); return __builtin_bit_cast(unsigned, b); }
; DI unsigned cvtpk_h(float lo, float hi) { f32x2 v = {lo, hi}; h16x2_t b = __builtin_convertvector(v, h16x2_t); return __builtin_bit_cast(unsigned, b); }
;     template <int MODE> __device__ __forceinline__ void run(const f32x4 (&acc)[2][2][4][2], u16* dst, int ld, int row0, int col0, int trow0, int wc, int fq, const float* lb) const {
;     ...
;             for (int m = 0; m < 4; ++m) {
;                 const int rr = ai * HALF + m * 16;
;                 u16* rowp = dst + (size_t)(row0 + rr) * ld + col0;
;                 f32x4 cs, sn;
;                 if (MODE == 1 || MODE == 2) { const int t = trow0 + rr; const int pos = (wc & 1) ? (t & 63) : (t >> 6);
;                     cs = *(const f32x4*)(rcos + pos * 16 + 4 * fq); sn = *(const f32x4*)(rsin + pos * 16 + 4 * fq); }
; #pragma unroll
;                 for (int bj = 0; bj < 2; ++bj) {
;                     f32x4 v0 = acc[ai][bj][m][0], v1 = acc[ai][bj][m][1];
;                     if (MODE == 1 || MODE == 2) { const f32x4 a = v0 * cs - v1 * sn, b = v1 * cs + v0 * sn; v0 = a; v1 = b;
;                         if (MODE == 2) { v0 = v0 * 0.18033688011112042f; v1 = v1 * 0.18033688011112042f; } }
;                     if (MODE == 3) {
; #pragma unroll
;                         for (int i = 0; i < 4; ++i) { const float l0 = lb0[bj][i], l1 = lb1[bj][i];
;                             v0[i] = __logf(l0 + (1.f - l0) * sigm(v0[i])); v1[i] = __logf(l1 + (1.f - l1) * sigm(v1[i])); }
;                     }
;                     if (MODE == 4) {
; #pragma unroll
;                         for (int i = 0; i < 4; ++i) { v0[i] = silu_(v0[i]); v1[i] = silu_(v1[i]); }
;                     }
;                     if (MODE == 5) {
; #pragma unroll
;                         for (int i = 0; i < 4; ++i) { v0[i] = sigm(v0[i]); v1[i] = sigm(v1[i]); }
;                     }
;                     u32x4 w;
;                     if (MODE == 3) { w.x = cvtpk_h(v0[0], v0[1]); w.y = cvtpk_h(v0[2], v0[3]); w.z = cvtpk_h(v1[0], v1[1]); w.w = cvtpk_h(v1[2], v1[3]); }
;                     else { w.x = cvtpk(v0[0], v0[1]); w.y = cvtpk(v0[2], v0[3]); w.z = cvtpk(v1[0], v1[1]); w.w = cvtpk(v1[2], v1[3]); }
;                     *(u32x4*)(rowp + bj * HALF) = w;
	v_pk_mul_f32 v[138:139], v[90:91], v[138:139]
	v_cvt_pk_bf16_f32 v130, v130, v131
	v_cvt_pk_bf16_f32 v131, v136, v137
	v_cvt_pk_bf16_f32 v132, v132, v133
	v_cvt_pk_bf16_f32 v133, v138, v139
	global_store_dwordx4 v[134:135], v[130:133], off offset:256 sc1
	v_mul_f32_e32 v137, 0xbfb8aa3b, v98
	v_exp_f32_e32 v137, v137
	v_mul_f32_e32 v132, 0xbfb8aa3b, v100
	v_exp_f32_e32 v132, v132
	v_mul_f32_e32 v133, 0xbfb8aa3b, v96
	v_or_b32_e32 v130, 32, v168
	v_exp_f32_e32 v133, v133
	v_ashrrev_i32_e32 v131, 31, v130
	v_lshlrev_b64 v[130:131], 11, v[130:131]
	v_lshl_add_u64 v[134:135], v[128:129], 0, v[130:131]
	v_add_f32_e32 v130, 1.0, v132
	v_mul_f32_e32 v132, 0xbfb8aa3b, v101
	v_add_f32_e32 v131, 1.0, v133
	v_exp_f32_e32 v133, v132
	v_mul_f32_e32 v132, 0xbfb8aa3b, v97
	v_exp_f32_e32 v136, v132
	v_rcp_f32_e32 v132, v131
	v_add_f32_e32 v131, 1.0, v133
	v_mul_f32_e32 v138, 0xbfb8aa3b, v103
	v_add_f32_e32 v133, 1.0, v136
	v_mul_f32_e32 v136, 0xbfb8aa3b, v102
	v_exp_f32_e32 v136, v136
	v_exp_f32_e32 v139, v138
	v_mul_f32_e32 v138, 0xbfb8aa3b, v99
	v_exp_f32_e32 v140, v138
	v_add_f32_e32 v137, 1.0, v137
	v_add_f32_e32 v136, 1.0, v136
	v_rcp_f32_e32 v138, v137
	v_add_f32_e32 v137, 1.0, v139
	v_rcp_f32_e32 v130, v130
	v_rcp_f32_e32 v131, v131
	v_rcp_f32_e32 v136, v136
	v_rcp_f32_e32 v137, v137
	v_add_f32_e32 v139, 1.0, v140
	v_rcp_f32_e32 v133, v133
	v_rcp_f32_e32 v139, v139
	v_pk_mul_f32 v[130:131], v[100:101], v[130:131]
	v_pk_mul_f32 v[136:137], v[102:103], v[136:137]
	v_cvt_pk_bf16_f32 v130, v130, v131
	v_cvt_pk_bf16_f32 v131, v136, v137
	v_mul_f32_e32 v136, 0xbfb8aa3b, v76
	v_pk_mul_f32 v[132:133], v[96:97], v[132:133]
	v_pk_mul_f32 v[138:139], v[98:99], v[138:139]
	v_exp_f32_e32 v136, v136
	v_cvt_pk_bf16_f32 v132, v132, v133
	v_cvt_pk_bf16_f32 v133, v138, v139
	v_mul_f32_e32 v137, 0xbfb8aa3b, v72
	global_store_dwordx4 v[134:135], v[130:133], off sc1
	v_exp_f32_e32 v137, v137
	v_mul_f32_e32 v138, 0xbfb8aa3b, v79
	v_mul_f32_e32 v132, 0xbfb8aa3b, v77
	v_exp_f32_e32 v133, v132
	v_mul_f32_e32 v132, 0xbfb8aa3b, v73
	v_add_f32_e32 v130, 1.0, v136
	v_exp_f32_e32 v136, v132
	v_add_f32_e32 v131, 1.0, v137
	v_mul_f32_e32 v137, 0xbfb8aa3b, v74
	v_rcp_f32_e32 v132, v131
	v_add_f32_e32 v131, 1.0, v133
	v_add_f32_e32 v133, 1.0, v136
	v_mul_f32_e32 v136, 0xbfb8aa3b, v78
	v_exp_f32_e32 v137, v137
	v_exp_f32_e32 v139, v138
	v_mul_f32_e32 v138, 0xbfb8aa3b, v75
	v_exp_f32_e32 v136, v136
	v_exp_f32_e32 v140, v138
	v_add_f32_e32 v137, 1.0, v137
	v_rcp_f32_e32 v138, v137
	v_add_f32_e32 v136, 1.0, v136
	v_add_f32_e32 v137, 1.0, v139
	v_add_f32_e32 v139, 1.0, v140
	v_rcp_f32_e32 v130, v130
	v_rcp_f32_e32 v131, v131
	v_rcp_f32_e32 v133, v133
	v_rcp_f32_e32 v136, v136
	v_rcp_f32_e32 v137, v137
	v_rcp_f32_e32 v139, v139
	v_pk_mul_f32 v[130:131], v[76:77], v[130:131]
	v_pk_mul_f32 v[132:133], v[72:73], v[132:133]
	v_pk_mul_f32 v[136:137], v[78:79], v[136:137]
	v_pk_mul_f32 v[138:139], v[74:75], v[138:139]
	v_cvt_pk_bf16_f32 v130, v130, v131
	v_cvt_pk_bf16_f32 v131, v136, v137
	v_cvt_pk_bf16_f32 v132, v132, v133
	v_cvt_pk_bf16_f32 v133, v138, v139
	global_store_dwordx4 v[134:135], v[130:133], off offset:256 sc1
	v_mul_f32_e32 v137, 0xbfb8aa3b, v82
	v_exp_f32_e32 v137, v137
	v_mul_f32_e32 v132, 0xbfb8aa3b, v84
	v_exp_f32_e32 v132, v132
	v_mul_f32_e32 v133, 0xbfb8aa3b, v80
	v_or_b32_e32 v130, 48, v168
	v_exp_f32_e32 v133, v133
	v_ashrrev_i32_e32 v131, 31, v130
	v_lshlrev_b64 v[130:131], 11, v[130:131]
	v_lshl_add_u64 v[134:135], v[128:129], 0, v[130:131]
	v_add_f32_e32 v130, 1.0, v132
	v_mul_f32_e32 v132, 0xbfb8aa3b, v85
	v_add_f32_e32 v131, 1.0, v133
	v_exp_f32_e32 v133, v132
	v_mul_f32_e32 v132, 0xbfb8aa3b, v81
	v_exp_f32_e32 v136, v132
	v_rcp_f32_e32 v132, v131
	v_add_f32_e32 v131, 1.0, v133
	v_mul_f32_e32 v138, 0xbfb8aa3b, v87
	v_add_f32_e32 v133, 1.0, v136
	v_mul_f32_e32 v136, 0xbfb8aa3b, v86
	v_exp_f32_e32 v136, v136
	v_exp_f32_e32 v139, v138
	v_mul_f32_e32 v138, 0xbfb8aa3b, v83
	v_exp_f32_e32 v140, v138
	v_add_f32_e32 v137, 1.0, v137
	v_add_f32_e32 v136, 1.0, v136
	v_rcp_f32_e32 v138, v137
	v_add_f32_e32 v137, 1.0, v139
	v_rcp_f32_e32 v130, v130
	v_rcp_f32_e32 v131, v131
	v_rcp_f32_e32 v136, v136
	v_rcp_f32_e32 v137, v137
	v_add_f32_e32 v139, 1.0, v140
	v_rcp_f32_e32 v133, v133
	v_rcp_f32_e32 v139, v139
	v_pk_mul_f32 v[130:131], v[84:85], v[130:131]
	v_pk_mul_f32 v[136:137], v[86:87], v[136:137]
	v_cvt_pk_bf16_f32 v130, v130, v131
	v_cvt_pk_bf16_f32 v131, v136, v137
	v_mul_f32_e32 v136, 0xbfb8aa3b, v68
	v_pk_mul_f32 v[132:133], v[80:81], v[132:133]
	v_pk_mul_f32 v[138:139], v[82:83], v[138:139]
	v_exp_f32_e32 v136, v136
	v_cvt_pk_bf16_f32 v132, v132, v133
	v_cvt_pk_bf16_f32 v133, v138, v139
	v_mul_f32_e32 v137, 0xbfb8aa3b, v64
	global_store_dwordx4 v[134:135], v[130:133], off sc1
	v_exp_f32_e32 v137, v137
	v_mul_f32_e32 v138, 0xbfb8aa3b, v71
	v_mul_f32_e32 v132, 0xbfb8aa3b, v69
	v_exp_f32_e32 v133, v132
	v_mul_f32_e32 v132, 0xbfb8aa3b, v65
	v_add_f32_e32 v130, 1.0, v136
	v_exp_f32_e32 v136, v132
	v_add_f32_e32 v131, 1.0, v137
	v_mul_f32_e32 v137, 0xbfb8aa3b, v66
	v_rcp_f32_e32 v132, v131
	v_add_f32_e32 v131, 1.0, v133
	v_add_f32_e32 v133, 1.0, v136
	v_mul_f32_e32 v136, 0xbfb8aa3b, v70
	v_exp_f32_e32 v137, v137
	v_exp_f32_e32 v139, v138
	v_mul_f32_e32 v138, 0xbfb8aa3b, v67
	v_exp_f32_e32 v136, v136
	v_exp_f32_e32 v140, v138
	v_add_f32_e32 v137, 1.0, v137
	v_rcp_f32_e32 v138, v137
	v_add_f32_e32 v136, 1.0, v136
	v_add_f32_e32 v137, 1.0, v139
	v_add_f32_e32 v139, 1.0, v140
	v_rcp_f32_e32 v130, v130
	v_rcp_f32_e32 v131, v131
	v_rcp_f32_e32 v133, v133
	v_rcp_f32_e32 v136, v136
	v_rcp_f32_e32 v137, v137
	v_rcp_f32_e32 v139, v139
	v_pk_mul_f32 v[130:131], v[68:69], v[130:131]
; DI unsigned cvtpk(float lo, float hi) { f32x2 v = {lo, hi}; bf16x2_t b = __builtin_convertvector(v, bf16x2_t); return __builtin_bit_cast(unsigned, b); }
; DI unsigned cvtpk_h(float lo, float hi) { f32x2 v = {lo, hi}; h16x2_t b = __builtin_convertvector(v, h16x2_t); return __builtin_bit_cast(unsigned, b); }
;     template <int MODE> __device__ __forceinline__ void run(const f32x4 (&acc)[2][2][4][2], u16* dst, int ld, int row0, int col0, int trow0, int wc, int fq, const float* lb) const {
;     ...
;             for (int m = 0; m < 4; ++m) {
;                 const int rr = ai * HALF + m * 16;
;                 u16* rowp = dst + (size_t)(row0 + rr) * ld + col0;
;                 f32x4 cs, sn;
;                 if (MODE == 1 || MODE == 2) { const int t = trow0 + rr; const int pos = (wc & 1) ? (t & 63) : (t >> 6);
;                     cs = *(const f32x4*)(rcos + pos * 16 + 4 * fq); sn = *(const f32x4*)(rsin + pos * 16 + 4 * fq); }
; #pragma unroll
;                 for (int bj = 0; bj < 2; ++bj) {
;                     f32x4 v0 = acc[ai][bj][m][0], v1 = acc[ai][bj][m][1];
;                     if (MODE == 1 || MODE == 2) { const f32x4 a = v0 * cs - v1 * sn, b = v1 * cs + v0 * sn; v0 = a; v1 = b;
;                         if (MODE == 2) { v0 = v0 * 0.18033688011112042f; v1 = v1 * 0.18033688011112042f; } }
;                     if (MODE == 3) {
; #pragma unroll
;                         for (int i = 0; i < 4; ++i) { const float l0 = lb0[bj][i], l1 = lb1[bj][i];
;                             v0[i] = __logf(l0 + (1.f - l0) * sigm(v0[i])); v1[i] = __logf(l1 + (1.f - l1) * sigm(v1[i])); }
;                     }
;                     if (MODE == 4) {
; #pragma unroll
;                         for (int i = 0; i < 4; ++i) { v0[i] = silu_(v0[i]); v1[i] = silu_(v1[i]); }
;                     }
;                     if (MODE == 5) {
; #pragma unroll
;                         for (int i = 0; i < 4; ++i) { v0[i] = sigm(v0[i]); v1[i] = sigm(v1[i]); }
;                     }
;                     u32x4 w;
;                     if (MODE == 3) { w.x = cvtpk_h(v0[0], v0[1]); w.y = cvtpk_h(v0[2], v0[3]); w.z = cvtpk_h(v1[0], v1[1]); w.w = cvtpk_h(v1[2], v1[3]); }
;                     else { w.x = cvtpk(v0[0], v0[1]); w.y = cvtpk(v0[2], v0[3]); w.z = cvtpk(v1[0], v1[1]); w.w = cvtpk(v1[2], v1[3]); }
;                     *(u32x4*)(rowp + bj * HALF) = w;
	v_pk_mul_f32 v[132:133], v[64:65], v[132:133]
	v_pk_mul_f32 v[136:137], v[70:71], v[136:137]
	v_pk_mul_f32 v[138:139], v[66:67], v[138:139]
	v_cvt_pk_bf16_f32 v130, v130, v131
	v_cvt_pk_bf16_f32 v131, v136, v137
	v_cvt_pk_bf16_f32 v132, v132, v133
	v_cvt_pk_bf16_f32 v133, v138, v139
	global_store_dwordx4 v[134:135], v[130:133], off offset:256 sc1
	v_mul_f32_e32 v137, 0xbfb8aa3b, v58
	v_exp_f32_e32 v137, v137
	v_mul_f32_e32 v132, 0xbfb8aa3b, v60
	v_exp_f32_e32 v132, v132
	v_mul_f32_e32 v133, 0xbfb8aa3b, v56
	v_add_u32_e32 v130, 0x80, v168
	v_exp_f32_e32 v133, v133
	v_ashrrev_i32_e32 v131, 31, v130
	v_lshlrev_b64 v[130:131], 11, v[130:131]
	v_lshl_add_u64 v[134:135], v[128:129], 0, v[130:131]
	v_add_f32_e32 v130, 1.0, v132
	v_mul_f32_e32 v132, 0xbfb8aa3b, v61
	v_add_f32_e32 v131, 1.0, v133
	v_exp_f32_e32 v133, v132
	v_mul_f32_e32 v132, 0xbfb8aa3b, v57
	v_exp_f32_e32 v136, v132
	v_rcp_f32_e32 v132, v131
	v_add_f32_e32 v131, 1.0, v133
	v_mul_f32_e32 v138, 0xbfb8aa3b, v63
	v_add_f32_e32 v133, 1.0, v136
	v_mul_f32_e32 v136, 0xbfb8aa3b, v62
	v_exp_f32_e32 v136, v136
	v_exp_f32_e32 v139, v138
	v_mul_f32_e32 v138, 0xbfb8aa3b, v59
	v_exp_f32_e32 v140, v138
	v_add_f32_e32 v137, 1.0, v137
	v_add_f32_e32 v136, 1.0, v136
	v_rcp_f32_e32 v138, v137
	v_add_f32_e32 v137, 1.0, v139
	v_rcp_f32_e32 v130, v130
	v_rcp_f32_e32 v131, v131
	v_rcp_f32_e32 v136, v136
	v_rcp_f32_e32 v137, v137
	v_add_f32_e32 v139, 1.0, v140
	v_rcp_f32_e32 v133, v133
	v_rcp_f32_e32 v139, v139
	v_pk_mul_f32 v[130:131], v[60:61], v[130:131]
	v_pk_mul_f32 v[136:137], v[62:63], v[136:137]
	v_cvt_pk_bf16_f32 v130, v130, v131
	v_cvt_pk_bf16_f32 v131, v136, v137
	v_mul_f32_e32 v136, 0xbfb8aa3b, v44
	v_pk_mul_f32 v[132:133], v[56:57], v[132:133]
	v_pk_mul_f32 v[138:139], v[58:59], v[138:139]
	v_exp_f32_e32 v136, v136
	v_cvt_pk_bf16_f32 v132, v132, v133
	v_cvt_pk_bf16_f32 v133, v138, v139
	v_mul_f32_e32 v137, 0xbfb8aa3b, v40
	global_store_dwordx4 v[134:135], v[130:133], off sc1
	v_exp_f32_e32 v137, v137
	v_mul_f32_e32 v138, 0xbfb8aa3b, v47
	v_mul_f32_e32 v132, 0xbfb8aa3b, v45
	v_exp_f32_e32 v133, v132
	v_mul_f32_e32 v132, 0xbfb8aa3b, v41
	v_add_f32_e32 v130, 1.0, v136
	v_exp_f32_e32 v136, v132
	v_add_f32_e32 v131, 1.0, v137
	v_mul_f32_e32 v137, 0xbfb8aa3b, v42
	v_rcp_f32_e32 v132, v131
	v_add_f32_e32 v131, 1.0, v133
	v_add_f32_e32 v133, 1.0, v136
	v_mul_f32_e32 v136, 0xbfb8aa3b, v46
	v_exp_f32_e32 v137, v137
	v_exp_f32_e32 v139, v138
	v_mul_f32_e32 v138, 0xbfb8aa3b, v43
	v_exp_f32_e32 v136, v136
	v_exp_f32_e32 v140, v138
	v_add_f32_e32 v137, 1.0, v137
	v_rcp_f32_e32 v138, v137
	v_add_f32_e32 v136, 1.0, v136
	v_add_f32_e32 v137, 1.0, v139
	v_add_f32_e32 v139, 1.0, v140
	v_rcp_f32_e32 v130, v130
	v_rcp_f32_e32 v131, v131
	v_rcp_f32_e32 v133, v133
	v_rcp_f32_e32 v136, v136
	v_rcp_f32_e32 v137, v137
	v_rcp_f32_e32 v139, v139
	v_pk_mul_f32 v[130:131], v[44:45], v[130:131]
	v_pk_mul_f32 v[132:133], v[40:41], v[132:133]
	v_pk_mul_f32 v[136:137], v[46:47], v[136:137]
	v_pk_mul_f32 v[138:139], v[42:43], v[138:139]
	v_cvt_pk_bf16_f32 v130, v130, v131
	v_cvt_pk_bf16_f32 v131, v136, v137
	v_cvt_pk_bf16_f32 v132, v132, v133
	v_cvt_pk_bf16_f32 v133, v138, v139
	global_store_dwordx4 v[134:135], v[130:133], off offset:256 sc1
	v_mul_f32_e32 v137, 0xbfb8aa3b, v50
	v_exp_f32_e32 v137, v137
	v_mul_f32_e32 v132, 0xbfb8aa3b, v52
	v_exp_f32_e32 v132, v132
	v_mul_f32_e32 v133, 0xbfb8aa3b, v48
	v_add_u32_e32 v130, 0x90, v168
	v_exp_f32_e32 v133, v133
	v_ashrrev_i32_e32 v131, 31, v130
	v_lshlrev_b64 v[130:131], 11, v[130:131]
	v_lshl_add_u64 v[134:135], v[128:129], 0, v[130:131]
	v_add_f32_e32 v130, 1.0, v132
	v_mul_f32_e32 v132, 0xbfb8aa3b, v53
	v_add_f32_e32 v131, 1.0, v133
	v_exp_f32_e32 v133, v132
	v_mul_f32_e32 v132, 0xbfb8aa3b, v49
	v_exp_f32_e32 v136, v132
	v_rcp_f32_e32 v132, v131
	v_add_f32_e32 v131, 1.0, v133
	v_mul_f32_e32 v138, 0xbfb8aa3b, v55
	v_add_f32_e32 v133, 1.0, v136
	v_mul_f32_e32 v136, 0xbfb8aa3b, v54
	v_exp_f32_e32 v136, v136
	v_exp_f32_e32 v139, v138
	v_mul_f32_e32 v138, 0xbfb8aa3b, v51
	v_exp_f32_e32 v140, v138
	v_add_f32_e32 v137, 1.0, v137
	v_add_f32_e32 v136, 1.0, v136
	v_rcp_f32_e32 v138, v137
	v_add_f32_e32 v137, 1.0, v139
	v_rcp_f32_e32 v130, v130
	v_rcp_f32_e32 v131, v131
	v_rcp_f32_e32 v136, v136
	v_rcp_f32_e32 v137, v137
	v_add_f32_e32 v139, 1.0, v140
	v_rcp_f32_e32 v133, v133
	v_rcp_f32_e32 v139, v139
	v_pk_mul_f32 v[130:131], v[52:53], v[130:131]
	v_pk_mul_f32 v[136:137], v[54:55], v[136:137]
	v_cvt_pk_bf16_f32 v130, v130, v131
	v_cvt_pk_bf16_f32 v131, v136, v137
	v_mul_f32_e32 v136, 0xbfb8aa3b, v28
	v_pk_mul_f32 v[132:133], v[48:49], v[132:133]
	v_pk_mul_f32 v[138:139], v[50:51], v[138:139]
	v_exp_f32_e32 v136, v136
	v_cvt_pk_bf16_f32 v132, v132, v133
	v_cvt_pk_bf16_f32 v133, v138, v139
	v_mul_f32_e32 v137, 0xbfb8aa3b, v24
	global_store_dwordx4 v[134:135], v[130:133], off sc1
	v_exp_f32_e32 v137, v137
	v_mul_f32_e32 v138, 0xbfb8aa3b, v31
	v_mul_f32_e32 v132, 0xbfb8aa3b, v29
	v_exp_f32_e32 v133, v132
	v_mul_f32_e32 v132, 0xbfb8aa3b, v25
	v_add_f32_e32 v130, 1.0, v136
	v_exp_f32_e32 v136, v132
	v_add_f32_e32 v131, 1.0, v137
	v_mul_f32_e32 v137, 0xbfb8aa3b, v26
	v_rcp_f32_e32 v132, v131
	v_add_f32_e32 v131, 1.0, v133
	v_add_f32_e32 v133, 1.0, v136
	v_mul_f32_e32 v136, 0xbfb8aa3b, v30
	v_exp_f32_e32 v137, v137
	v_exp_f32_e32 v139, v138
	v_mul_f32_e32 v138, 0xbfb8aa3b, v27
	v_exp_f32_e32 v136, v136
	v_exp_f32_e32 v140, v138
	v_add_f32_e32 v137, 1.0, v137
	v_rcp_f32_e32 v138, v137
	v_add_f32_e32 v136, 1.0, v136
	v_add_f32_e32 v137, 1.0, v139
	v_add_f32_e32 v139, 1.0, v140
	v_rcp_f32_e32 v130, v130
	v_rcp_f32_e32 v131, v131
	v_rcp_f32_e32 v133, v133
	v_rcp_f32_e32 v136, v136
; DI unsigned cvtpk(float lo, float hi) { f32x2 v = {lo, hi}; bf16x2_t b = __builtin_convertvector(v, bf16x2_t); return __builtin_bit_cast(unsigned, b); }
; DI unsigned cvtpk_h(float lo, float hi) { f32x2 v = {lo, hi}; h16x2_t b = __builtin_convertvector(v, h16x2_t); return __builtin_bit_cast(unsigned, b); }
;     template <int MODE> __device__ __forceinline__ void run(const f32x4 (&acc)[2][2][4][2], u16* dst, int ld, int row0, int col0, int trow0, int wc, int fq, const float* lb) const {
;     ...
;             for (int m = 0; m < 4; ++m) {
;                 const int rr = ai * HALF + m * 16;
;                 u16* rowp = dst + (size_t)(row0 + rr) * ld + col0;
;                 f32x4 cs, sn;
;                 if (MODE == 1 || MODE == 2) { const int t = trow0 + rr; const int pos = (wc & 1) ? (t & 63) : (t >> 6);
;                     cs = *(const f32x4*)(rcos + pos * 16 + 4 * fq); sn = *(const f32x4*)(rsin + pos * 16 + 4 * fq); }
; #pragma unroll
;                 for (int bj = 0; bj < 2; ++bj) {
;                     f32x4 v0 = acc[ai][bj][m][0], v1 = acc[ai][bj][m][1];
;                     if (MODE == 1 || MODE == 2) { const f32x4 a = v0 * cs - v1 * sn, b = v1 * cs + v0 * sn; v0 = a; v1 = b;
;                         if (MODE == 2) { v0 = v0 * 0.18033688011112042f; v1 = v1 * 0.18033688011112042f; } }
;                     if (MODE == 3) {
; #pragma unroll
;                         for (int i = 0; i < 4; ++i) { const float l0 = lb0[bj][i], l1 = lb1[bj][i];
;                             v0[i] = __logf(l0 + (1.f - l0) * sigm(v0[i])); v1[i] = __logf(l1 + (1.f - l1) * sigm(v1[i])); }
;                     }
;                     if (MODE == 4) {
; #pragma unroll
;                         for (int i = 0; i < 4; ++i) { v0[i] = silu_(v0[i]); v1[i] = silu_(v1[i]); }
;                     }
;                     if (MODE == 5) {
; #pragma unroll
;                         for (int i = 0; i < 4; ++i) { v0[i] = sigm(v0[i]); v1[i] = sigm(v1[i]); }
;                     }
;                     u32x4 w;
;                     if (MODE == 3) { w.x = cvtpk_h(v0[0], v0[1]); w.y = cvtpk_h(v0[2], v0[3]); w.z = cvtpk_h(v1[0], v1[1]); w.w = cvtpk_h(v1[2], v1[3]); }
;                     else { w.x = cvtpk(v0[0], v0[1]); w.y = cvtpk(v0[2], v0[3]); w.z = cvtpk(v1[0], v1[1]); w.w = cvtpk(v1[2], v1[3]); }
;                     *(u32x4*)(rowp + bj * HALF) = w;
	v_rcp_f32_e32 v137, v137
	v_rcp_f32_e32 v139, v139
	v_pk_mul_f32 v[130:131], v[28:29], v[130:131]
	v_pk_mul_f32 v[132:133], v[24:25], v[132:133]
	v_pk_mul_f32 v[136:137], v[30:31], v[136:137]
	v_pk_mul_f32 v[138:139], v[26:27], v[138:139]
	v_cvt_pk_bf16_f32 v130, v130, v131
	v_cvt_pk_bf16_f32 v131, v136, v137
	v_cvt_pk_bf16_f32 v132, v132, v133
	v_cvt_pk_bf16_f32 v133, v138, v139
	global_store_dwordx4 v[134:135], v[130:133], off offset:256 sc1
	v_mul_f32_e32 v137, 0xbfb8aa3b, v34
	v_exp_f32_e32 v137, v137
	v_mul_f32_e32 v132, 0xbfb8aa3b, v36
	v_exp_f32_e32 v132, v132
	v_mul_f32_e32 v133, 0xbfb8aa3b, v32
	v_add_u32_e32 v130, 0xa0, v168
	v_exp_f32_e32 v133, v133
	v_ashrrev_i32_e32 v131, 31, v130
	v_lshlrev_b64 v[130:131], 11, v[130:131]
	v_lshl_add_u64 v[134:135], v[128:129], 0, v[130:131]
	v_add_f32_e32 v130, 1.0, v132
	v_mul_f32_e32 v132, 0xbfb8aa3b, v37
	v_add_f32_e32 v131, 1.0, v133
	v_exp_f32_e32 v133, v132
	v_mul_f32_e32 v132, 0xbfb8aa3b, v33
	v_exp_f32_e32 v136, v132
	v_rcp_f32_e32 v132, v131
	v_add_f32_e32 v131, 1.0, v133
	v_mul_f32_e32 v138, 0xbfb8aa3b, v39
	v_add_f32_e32 v133, 1.0, v136
	v_mul_f32_e32 v136, 0xbfb8aa3b, v38
	v_exp_f32_e32 v136, v136
	v_exp_f32_e32 v139, v138
	v_mul_f32_e32 v138, 0xbfb8aa3b, v35
	v_exp_f32_e32 v140, v138
	v_add_f32_e32 v137, 1.0, v137
	v_add_f32_e32 v136, 1.0, v136
	v_rcp_f32_e32 v138, v137
	v_add_f32_e32 v137, 1.0, v139
	v_rcp_f32_e32 v130, v130
	v_rcp_f32_e32 v131, v131
	v_rcp_f32_e32 v136, v136
	v_rcp_f32_e32 v137, v137
	v_add_f32_e32 v139, 1.0, v140
	v_rcp_f32_e32 v133, v133
	v_rcp_f32_e32 v139, v139
	v_pk_mul_f32 v[130:131], v[36:37], v[130:131]
	v_pk_mul_f32 v[136:137], v[38:39], v[136:137]
	v_cvt_pk_bf16_f32 v130, v130, v131
	v_cvt_pk_bf16_f32 v131, v136, v137
	v_mul_f32_e32 v136, 0xbfb8aa3b, v12
	v_pk_mul_f32 v[132:133], v[32:33], v[132:133]
	v_pk_mul_f32 v[138:139], v[34:35], v[138:139]
	v_exp_f32_e32 v136, v136
	v_cvt_pk_bf16_f32 v132, v132, v133
	v_cvt_pk_bf16_f32 v133, v138, v139
	v_mul_f32_e32 v137, 0xbfb8aa3b, v8
	global_store_dwordx4 v[134:135], v[130:133], off sc1
	v_exp_f32_e32 v137, v137
	v_mul_f32_e32 v138, 0xbfb8aa3b, v15
	v_mul_f32_e32 v132, 0xbfb8aa3b, v13
	v_exp_f32_e32 v133, v132
	v_mul_f32_e32 v132, 0xbfb8aa3b, v9
	v_add_f32_e32 v130, 1.0, v136
	v_exp_f32_e32 v136, v132
	v_add_f32_e32 v131, 1.0, v137
	v_mul_f32_e32 v137, 0xbfb8aa3b, v10
	v_rcp_f32_e32 v132, v131
	v_add_f32_e32 v131, 1.0, v133
	v_add_f32_e32 v133, 1.0, v136
	v_mul_f32_e32 v136, 0xbfb8aa3b, v14
	v_exp_f32_e32 v137, v137
	v_exp_f32_e32 v139, v138
	v_mul_f32_e32 v138, 0xbfb8aa3b, v11
	v_exp_f32_e32 v136, v136
	v_exp_f32_e32 v140, v138
	v_add_f32_e32 v137, 1.0, v137
	v_rcp_f32_e32 v138, v137
	v_add_f32_e32 v136, 1.0, v136
	v_add_f32_e32 v137, 1.0, v139
	v_add_f32_e32 v139, 1.0, v140
	v_rcp_f32_e32 v130, v130
	v_rcp_f32_e32 v131, v131
	v_rcp_f32_e32 v133, v133
	v_rcp_f32_e32 v136, v136
	v_rcp_f32_e32 v137, v137
	v_rcp_f32_e32 v139, v139
	v_pk_mul_f32 v[130:131], v[12:13], v[130:131]
	v_pk_mul_f32 v[132:133], v[8:9], v[132:133]
	v_pk_mul_f32 v[136:137], v[14:15], v[136:137]
	v_pk_mul_f32 v[138:139], v[10:11], v[138:139]
	v_cvt_pk_bf16_f32 v130, v130, v131
	v_cvt_pk_bf16_f32 v131, v136, v137
	v_cvt_pk_bf16_f32 v132, v132, v133
	v_cvt_pk_bf16_f32 v133, v138, v139
	global_store_dwordx4 v[134:135], v[130:133], off offset:256 sc1
	v_mul_f32_e32 v134, 0xbfb8aa3b, v23
	v_exp_f32_e32 v135, v134
	v_add_u32_e32 v130, 0xb0, v168
	v_mul_f32_e32 v132, 0xbfb8aa3b, v20
	v_ashrrev_i32_e32 v131, 31, v130
	v_exp_f32_e32 v132, v132
	v_lshlrev_b64 v[130:131], 11, v[130:131]
	v_mul_f32_e32 v133, 0xbfb8aa3b, v16
	v_lshl_add_u64 v[170:171], v[128:129], 0, v[130:131]
	v_mul_f32_e32 v130, 0xbfb8aa3b, v21
	v_exp_f32_e32 v133, v133
	v_exp_f32_e32 v131, v130
	v_mul_f32_e32 v130, 0xbfb8aa3b, v17
	v_add_f32_e32 v128, 1.0, v132
	v_exp_f32_e32 v132, v130
	v_add_f32_e32 v129, 1.0, v133
	v_mul_f32_e32 v133, 0xbfb8aa3b, v18
	v_rcp_f32_e32 v130, v129
	v_add_f32_e32 v129, 1.0, v131
	v_add_f32_e32 v131, 1.0, v132
	v_mul_f32_e32 v132, 0xbfb8aa3b, v22
	v_exp_f32_e32 v133, v133
	v_exp_f32_e32 v132, v132
	v_mul_f32_e32 v134, 0xbfb8aa3b, v19
	v_exp_f32_e32 v136, v134
	v_add_f32_e32 v133, 1.0, v133
	v_add_f32_e32 v132, 1.0, v132
	v_rcp_f32_e32 v134, v133
	v_add_f32_e32 v133, 1.0, v135
	v_rcp_f32_e32 v128, v128
	v_rcp_f32_e32 v129, v129
	v_rcp_f32_e32 v132, v132
	v_rcp_f32_e32 v133, v133
	v_add_f32_e32 v135, 1.0, v136
	v_rcp_f32_e32 v131, v131
	v_rcp_f32_e32 v135, v135
	v_pk_mul_f32 v[128:129], v[20:21], v[128:129]
	v_pk_mul_f32 v[132:133], v[22:23], v[132:133]
	v_cvt_pk_bf16_f32 v128, v128, v129
	v_cvt_pk_bf16_f32 v129, v132, v133
	v_mul_f32_e32 v132, 0xbfb8aa3b, v4
	v_pk_mul_f32 v[130:131], v[16:17], v[130:131]
	v_pk_mul_f32 v[134:135], v[18:19], v[134:135]
	v_exp_f32_e32 v132, v132
	v_cvt_pk_bf16_f32 v130, v130, v131
	v_cvt_pk_bf16_f32 v131, v134, v135
	v_mul_f32_e32 v133, 0xbfb8aa3b, v0
	global_store_dwordx4 v[170:171], v[128:131], off sc1
	v_exp_f32_e32 v133, v133
	v_mul_f32_e32 v134, 0xbfb8aa3b, v7
	v_mul_f32_e32 v130, 0xbfb8aa3b, v5
	v_exp_f32_e32 v131, v130
	v_mul_f32_e32 v130, 0xbfb8aa3b, v1
	v_add_f32_e32 v128, 1.0, v132
	v_exp_f32_e32 v132, v130
	v_add_f32_e32 v129, 1.0, v133
	v_mul_f32_e32 v133, 0xbfb8aa3b, v2
	v_rcp_f32_e32 v130, v129
	v_add_f32_e32 v129, 1.0, v131
	v_add_f32_e32 v131, 1.0, v132
	v_mul_f32_e32 v132, 0xbfb8aa3b, v6
	v_exp_f32_e32 v133, v133
	v_exp_f32_e32 v135, v134
	v_mul_f32_e32 v134, 0xbfb8aa3b, v3
	v_exp_f32_e32 v132, v132
	v_exp_f32_e32 v136, v134
	v_add_f32_e32 v133, 1.0, v133
	v_rcp_f32_e32 v134, v133
	v_add_f32_e32 v132, 1.0, v132
	v_add_f32_e32 v133, 1.0, v135
	v_add_f32_e32 v135, 1.0, v136
	v_rcp_f32_e32 v128, v128
	v_rcp_f32_e32 v129, v129
	v_rcp_f32_e32 v131, v131
	v_rcp_f32_e32 v132, v132
	v_rcp_f32_e32 v133, v133
	v_rcp_f32_e32 v135, v135
	v_pk_mul_f32 v[128:129], v[4:5], v[128:129]
	v_pk_mul_f32 v[130:131], v[0:1], v[130:131]
	v_pk_mul_f32 v[132:133], v[6:7], v[132:133]
	v_pk_mul_f32 v[134:135], v[2:3], v[134:135]
	v_cvt_pk_bf16_f32 v128, v128, v129
	v_cvt_pk_bf16_f32 v129, v132, v133
	v_cvt_pk_bf16_f32 v130, v130, v131
	v_cvt_pk_bf16_f32 v131, v134, v135

; DI unsigned cvtpk(float lo, float hi) { f32x2 v = {lo, hi}; bf16x2_t b = __builtin_convertvector(v, bf16x2_t); return __builtin_bit_cast(unsigned, b); }
; DI unsigned cvtpk_h(float lo, float hi) { f32x2 v = {lo, hi}; h16x2_t b = __builtin_convertvector(v, h16x2_t); return __builtin_bit_cast(unsigned, b); }
; DI float sigm(float x) { return __builtin_amdgcn_rcpf(1.f + fexp(-x)); }
;     template <int MODE> __device__ __forceinline__ void run(const f32x4 (&acc)[2][2][4][2], u16* dst, int ld, int row0, int col0, int trow0, int wc, int fq, const float* lb) const {
;     ...
;                 const int rr = ai * HALF + m * 16;
;                 u16* rowp = dst + (size_t)(row0 + rr) * ld + col0;
;                 f32x4 cs, sn;
;                 if (MODE == 1 || MODE == 2) { const int t = trow0 + rr; const int pos = (wc & 1) ? (t & 63) : (t >> 6);
;                     cs = *(const f32x4*)(rcos + pos * 16 + 4 * fq); sn = *(const f32x4*)(rsin + pos * 16 + 4 * fq); }
; #pragma unroll
;                 for (int bj = 0; bj < 2; ++bj) {
;                     f32x4 v0 = acc[ai][bj][m][0], v1 = acc[ai][bj][m][1];
;                     if (MODE == 1 || MODE == 2) { const f32x4 a = v0 * cs - v1 * sn, b = v1 * cs + v0 * sn; v0 = a; v1 = b;
;                         if (MODE == 2) { v0 = v0 * 0.18033688011112042f; v1 = v1 * 0.18033688011112042f; } }
;                     if (MODE == 3) {
; #pragma unroll
;                         for (int i = 0; i < 4; ++i) { const float l0 = lb0[bj][i], l1 = lb1[bj][i];
;                             v0[i] = __logf(l0 + (1.f - l0) * sigm(v0[i])); v1[i] = __logf(l1 + (1.f - l1) * sigm(v1[i])); }
;                     }
;                     if (MODE == 4) {
; #pragma unroll
;                         for (int i = 0; i < 4; ++i) { v0[i] = silu_(v0[i]); v1[i] = silu_(v1[i]); }
;                     }
;                     if (MODE == 5) {
; #pragma unroll
;                         for (int i = 0; i < 4; ++i) { v0[i] = sigm(v0[i]); v1[i] = sigm(v1[i]); }
;                     }
;                     u32x4 w;
;                     if (MODE == 3) { w.x = cvtpk_h(v0[0], v0[1]); w.y = cvtpk_h(v0[2], v0[3]); w.z = cvtpk_h(v1[0], v1[1]); w.w = cvtpk_h(v1[2], v1[3]); }
;                     else { w.x = cvtpk(v0[0], v0[1]); w.y = cvtpk(v0[2], v0[3]); w.z = cvtpk(v1[0], v1[1]); w.w = cvtpk(v1[2], v1[3]); }
;                     *(u32x4*)(rowp + bj * HALF) = w;
.LBB0_190:
	s_cmp_gt_i32 s58, 4
	s_mov_b64 s[8:9], -1
	s_cbranch_scc0 .LBB0_192
	s_ashr_i32 s0, s55, 6
	v_mov_b32_e32 v167, s0
	v_cndmask_b32_e64 v128, v175, v167, s[4:5]
	v_lshlrev_b32_e32 v128, 4, v128
	v_ashrrev_i32_e32 v129, 31, v128
	v_lshlrev_b64 v[128:129], 2, v[128:129]
	v_lshl_add_u64 v[130:131], v[156:157], 0, v[128:129]
	global_load_dwordx4 v[132:135], v[130:131], off
	v_lshl_add_u64 v[128:129], v[154:155], 0, v[128:129]
	global_load_dwordx4 v[136:139], v[128:129], off
	v_cndmask_b32_e64 v140, v180, v167, s[4:5]
	v_lshlrev_b32_e32 v152, 1, v187
	v_ashrrev_i32_e32 v169, 31, v168
	v_lshlrev_b32_e32 v140, 4, v140
	v_lshl_add_u64 v[130:131], s[34:35], 0, v[152:153]
	v_lshlrev_b64 v[128:129], 11, v[168:169]
	v_ashrrev_i32_e32 v141, 31, v140
	v_lshl_add_u64 v[128:129], v[130:131], 0, v[128:129]
	v_lshlrev_b64 v[140:141], 2, v[140:141]
	v_lshl_add_u64 v[142:143], v[156:157], 0, v[140:141]
	s_add_i32 s0, s55, 0x80
	s_ashr_i32 s0, s0, 6
	s_mov_b64 s[8:9], 0
	s_waitcnt vmcnt(0)
	v_pk_mul_f32 v[170:171], v[122:123], v[134:135]
	v_pk_mul_f32 v[172:173], v[120:121], v[132:133]
	v_pk_mul_f32 v[188:189], v[126:127], v[134:135]
	v_pk_mul_f32 v[190:191], v[124:125], v[132:133]
	v_pk_mul_f32 v[192:193], v[106:107], v[134:135]
	v_pk_mul_f32 v[196:197], v[104:105], v[132:133]
	v_pk_mul_f32 v[134:135], v[110:111], v[134:135]
	v_pk_mul_f32 v[132:133], v[108:109], v[132:133]
	v_pk_fma_f32 v[170:171], v[126:127], v[138:139], v[170:171] neg_lo:[0,0,1] neg_hi:[0,0,1]
	v_pk_fma_f32 v[172:173], v[124:125], v[136:137], v[172:173] neg_lo:[0,0,1] neg_hi:[0,0,1]
	v_pk_fma_f32 v[188:189], v[122:123], v[138:139], v[188:189]
	v_pk_fma_f32 v[190:191], v[120:121], v[136:137], v[190:191]
	v_pk_fma_f32 v[192:193], v[110:111], v[138:139], v[192:193] neg_lo:[0,0,1] neg_hi:[0,0,1]
	v_pk_fma_f32 v[196:197], v[108:109], v[136:137], v[196:197] neg_lo:[0,0,1] neg_hi:[0,0,1]
	v_pk_fma_f32 v[134:135], v[106:107], v[138:139], v[134:135]
	v_pk_fma_f32 v[132:133], v[104:105], v[136:137], v[132:133]
	v_pk_mul_f32 v[136:137], v[170:171], s[18:19] op_sel_hi:[1,0]
	v_pk_mul_f32 v[138:139], v[172:173], s[18:19] op_sel_hi:[1,0]
	v_pk_mul_f32 v[170:171], v[188:189], s[18:19] op_sel_hi:[1,0]
	v_pk_mul_f32 v[172:173], v[190:191], s[18:19] op_sel_hi:[1,0]
	v_pk_mul_f32 v[188:189], v[192:193], s[18:19] op_sel_hi:[1,0]
	v_pk_mul_f32 v[190:191], v[196:197], s[18:19] op_sel_hi:[1,0]
	v_pk_mul_f32 v[192:193], v[134:135], s[18:19] op_sel_hi:[1,0]
	v_pk_mul_f32 v[196:197], v[132:133], s[18:19] op_sel_hi:[1,0]
	v_cvt_pk_bf16_f32 v132, v138, v139
	v_cvt_pk_bf16_f32 v133, v136, v137
	v_cvt_pk_bf16_f32 v134, v172, v173
	v_cvt_pk_bf16_f32 v135, v170, v171
	v_cvt_pk_bf16_f32 v136, v190, v191
	v_cvt_pk_bf16_f32 v137, v188, v189
	v_cvt_pk_bf16_f32 v138, v196, v197
	v_cvt_pk_bf16_f32 v139, v192, v193
	global_store_dwordx4 v[128:129], v[132:135], off sc1
	global_store_dwordx4 v[128:129], v[136:139], off offset:256 sc1
	global_load_dwordx4 v[132:135], v[142:143], off
	s_nop 0
	v_lshl_add_u64 v[136:137], v[154:155], 0, v[140:141]
	global_load_dwordx4 v[136:139], v[136:137], off
	v_or_b32_e32 v140, 16, v168
	v_cndmask_b32_e64 v142, v181, v167, s[4:5]
	v_ashrrev_i32_e32 v141, 31, v140
	v_lshlrev_b32_e32 v142, 4, v142
	v_lshlrev_b64 v[140:141], 11, v[140:141]
	v_ashrrev_i32_e32 v143, 31, v142
	v_lshl_add_u64 v[140:141], v[130:131], 0, v[140:141]
	v_lshlrev_b64 v[142:143], 2, v[142:143]
	v_lshl_add_u64 v[170:171], v[156:157], 0, v[142:143]
	s_waitcnt vmcnt(1)
	v_pk_mul_f32 v[172:173], v[114:115], v[134:135]
	v_pk_mul_f32 v[188:189], v[112:113], v[132:133]
	v_pk_mul_f32 v[190:191], v[118:119], v[134:135]
	v_pk_mul_f32 v[192:193], v[116:117], v[132:133]
	v_pk_mul_f32 v[196:197], v[90:91], v[134:135]
	v_pk_mul_f32 v[198:199], v[88:89], v[132:133]
	v_pk_mul_f32 v[134:135], v[94:95], v[134:135]
	v_pk_mul_f32 v[132:133], v[92:93], v[132:133]
	s_waitcnt vmcnt(0)
	v_pk_fma_f32 v[172:173], v[118:119], v[138:139], v[172:173] neg_lo:[0,0,1] neg_hi:[0,0,1]
	v_pk_fma_f32 v[188:189], v[116:117], v[136:137], v[188:189] neg_lo:[0,0,1] neg_hi:[0,0,1]
	v_pk_fma_f32 v[190:191], v[114:115], v[138:139], v[190:191]
	v_pk_fma_f32 v[192:193], v[112:113], v[136:137], v[192:193]
	v_pk_fma_f32 v[196:197], v[94:95], v[138:139], v[196:197] neg_lo:[0,0,1] neg_hi:[0,0,1]
	v_pk_fma_f32 v[198:199], v[92:93], v[136:137], v[198:199] neg_lo:[0,0,1] neg_hi:[0,0,1]
	v_pk_fma_f32 v[134:135], v[90:91], v[138:139], v[134:135]
	v_pk_fma_f32 v[132:133], v[88:89], v[136:137], v[132:133]
	v_pk_mul_f32 v[136:137], v[172:173], s[18:19] op_sel_hi:[1,0]
	v_pk_mul_f32 v[138:139], v[188:189], s[18:19] op_sel_hi:[1,0]
	v_pk_mul_f32 v[172:173], v[190:191], s[18:19] op_sel_hi:[1,0]
	v_pk_mul_f32 v[188:189], v[192:193], s[18:19] op_sel_hi:[1,0]
	v_pk_mul_f32 v[190:191], v[196:197], s[18:19] op_sel_hi:[1,0]
	v_pk_mul_f32 v[192:193], v[198:199], s[18:19] op_sel_hi:[1,0]
	v_pk_mul_f32 v[196:197], v[134:135], s[18:19] op_sel_hi:[1,0]
	v_pk_mul_f32 v[198:199], v[132:133], s[18:19] op_sel_hi:[1,0]
	v_cvt_pk_bf16_f32 v132, v138, v139
	v_cvt_pk_bf16_f32 v133, v136, v137
	v_cvt_pk_bf16_f32 v134, v188, v189
	v_cvt_pk_bf16_f32 v135, v172, v173
	v_cvt_pk_bf16_f32 v136, v192, v193
	v_cvt_pk_bf16_f32 v137, v190, v191
	v_cvt_pk_bf16_f32 v138, v198, v199
	v_cvt_pk_bf16_f32 v139, v196, v197
	global_store_dwordx4 v[140:141], v[132:135], off sc1
	global_store_dwordx4 v[140:141], v[136:139], off offset:256 sc1
	global_load_dwordx4 v[132:135], v[170:171], off
	v_or_b32_e32 v140, 32, v168
	v_lshl_add_u64 v[136:137], v[154:155], 0, v[142:143]
	global_load_dwordx4 v[136:139], v[136:137], off
	v_cndmask_b32_e64 v142, v182, v167, s[4:5]
	v_ashrrev_i32_e32 v141, 31, v140
	v_lshlrev_b32_e32 v142, 4, v142
	v_lshlrev_b64 v[140:141], 11, v[140:141]
	v_ashrrev_i32_e32 v143, 31, v142
	v_lshl_add_u64 v[140:141], v[130:131], 0, v[140:141]
	v_lshlrev_b64 v[142:143], 2, v[142:143]
	v_lshl_add_u64 v[170:171], v[156:157], 0, v[142:143]
	s_waitcnt vmcnt(1)
; DI unsigned cvtpk(float lo, float hi) { f32x2 v = {lo, hi}; bf16x2_t b = __builtin_convertvector(v, bf16x2_t); return __builtin_bit_cast(unsigned, b); }
; DI unsigned cvtpk_h(float lo, float hi) { f32x2 v = {lo, hi}; h16x2_t b = __builtin_convertvector(v, h16x2_t); return __builtin_bit_cast(unsigned, b); }
; DI float sigm(float x) { return __builtin_amdgcn_rcpf(1.f + fexp(-x)); }
;     template <int MODE> __device__ __forceinline__ void run(const f32x4 (&acc)[2][2][4][2], u16* dst, int ld, int row0, int col0, int trow0, int wc, int fq, const float* lb) const {
;     ...
;                 const int rr = ai * HALF + m * 16;
;                 u16* rowp = dst + (size_t)(row0 + rr) * ld + col0;
;                 f32x4 cs, sn;
;                 if (MODE == 1 || MODE == 2) { const int t = trow0 + rr; const int pos = (wc & 1) ? (t & 63) : (t >> 6);
;                     cs = *(const f32x4*)(rcos + pos * 16 + 4 * fq); sn = *(const f32x4*)(rsin + pos * 16 + 4 * fq); }
; #pragma unroll
;                 for (int bj = 0; bj < 2; ++bj) {
;                     f32x4 v0 = acc[ai][bj][m][0], v1 = acc[ai][bj][m][1];
;                     if (MODE == 1 || MODE == 2) { const f32x4 a = v0 * cs - v1 * sn, b = v1 * cs + v0 * sn; v0 = a; v1 = b;
;                         if (MODE == 2) { v0 = v0 * 0.18033688011112042f; v1 = v1 * 0.18033688011112042f; } }
;                     if (MODE == 3) {
; #pragma unroll
;                         for (int i = 0; i < 4; ++i) { const float l0 = lb0[bj][i], l1 = lb1[bj][i];
;                             v0[i] = __logf(l0 + (1.f - l0) * sigm(v0[i])); v1[i] = __logf(l1 + (1.f - l1) * sigm(v1[i])); }
;                     }
;                     if (MODE == 4) {
; #pragma unroll
;                         for (int i = 0; i < 4; ++i) { v0[i] = silu_(v0[i]); v1[i] = silu_(v1[i]); }
;                     }
;                     if (MODE == 5) {
; #pragma unroll
;                         for (int i = 0; i < 4; ++i) { v0[i] = sigm(v0[i]); v1[i] = sigm(v1[i]); }
;                     }
;                     u32x4 w;
;                     if (MODE == 3) { w.x = cvtpk_h(v0[0], v0[1]); w.y = cvtpk_h(v0[2], v0[3]); w.z = cvtpk_h(v1[0], v1[1]); w.w = cvtpk_h(v1[2], v1[3]); }
;                     else { w.x = cvtpk(v0[0], v0[1]); w.y = cvtpk(v0[2], v0[3]); w.z = cvtpk(v1[0], v1[1]); w.w = cvtpk(v1[2], v1[3]); }
;                     *(u32x4*)(rowp + bj * HALF) = w;
	v_pk_mul_f32 v[172:173], v[98:99], v[134:135]
	v_pk_mul_f32 v[188:189], v[96:97], v[132:133]
	v_pk_mul_f32 v[190:191], v[102:103], v[134:135]
	v_pk_mul_f32 v[192:193], v[100:101], v[132:133]
	v_pk_mul_f32 v[196:197], v[74:75], v[134:135]
	v_pk_mul_f32 v[198:199], v[72:73], v[132:133]
	v_pk_mul_f32 v[134:135], v[78:79], v[134:135]
	v_pk_mul_f32 v[132:133], v[76:77], v[132:133]
	s_waitcnt vmcnt(0)
	v_pk_fma_f32 v[172:173], v[102:103], v[138:139], v[172:173] neg_lo:[0,0,1] neg_hi:[0,0,1]
	v_pk_fma_f32 v[188:189], v[100:101], v[136:137], v[188:189] neg_lo:[0,0,1] neg_hi:[0,0,1]
	v_pk_fma_f32 v[190:191], v[98:99], v[138:139], v[190:191]
	v_pk_fma_f32 v[192:193], v[96:97], v[136:137], v[192:193]
	v_pk_fma_f32 v[196:197], v[78:79], v[138:139], v[196:197] neg_lo:[0,0,1] neg_hi:[0,0,1]
	v_pk_fma_f32 v[198:199], v[76:77], v[136:137], v[198:199] neg_lo:[0,0,1] neg_hi:[0,0,1]
	v_pk_fma_f32 v[134:135], v[74:75], v[138:139], v[134:135]
	v_pk_fma_f32 v[132:133], v[72:73], v[136:137], v[132:133]
	v_pk_mul_f32 v[136:137], v[172:173], s[18:19] op_sel_hi:[1,0]
	v_pk_mul_f32 v[138:139], v[188:189], s[18:19] op_sel_hi:[1,0]
	v_pk_mul_f32 v[172:173], v[190:191], s[18:19] op_sel_hi:[1,0]
	v_pk_mul_f32 v[188:189], v[192:193], s[18:19] op_sel_hi:[1,0]
	v_pk_mul_f32 v[190:191], v[196:197], s[18:19] op_sel_hi:[1,0]
	v_pk_mul_f32 v[192:193], v[198:199], s[18:19] op_sel_hi:[1,0]
	v_pk_mul_f32 v[196:197], v[134:135], s[18:19] op_sel_hi:[1,0]
	v_pk_mul_f32 v[198:199], v[132:133], s[18:19] op_sel_hi:[1,0]
	v_cvt_pk_bf16_f32 v132, v138, v139
	v_cvt_pk_bf16_f32 v133, v136, v137
	v_cvt_pk_bf16_f32 v134, v188, v189
	v_cvt_pk_bf16_f32 v135, v172, v173
	v_cvt_pk_bf16_f32 v136, v192, v193
	v_cvt_pk_bf16_f32 v137, v190, v191
	v_cvt_pk_bf16_f32 v138, v198, v199
	v_cvt_pk_bf16_f32 v139, v196, v197
	global_store_dwordx4 v[140:141], v[132:135], off sc1
	global_store_dwordx4 v[140:141], v[136:139], off offset:256 sc1
	global_load_dwordx4 v[132:135], v[170:171], off
	v_or_b32_e32 v140, 48, v168
	v_lshl_add_u64 v[136:137], v[154:155], 0, v[142:143]
	global_load_dwordx4 v[136:139], v[136:137], off
	v_ashrrev_i32_e32 v141, 31, v140
	v_lshlrev_b64 v[140:141], 11, v[140:141]
	v_mov_b32_e32 v142, s0
	v_lshl_add_u64 v[140:141], v[130:131], 0, v[140:141]
	v_cndmask_b32_e64 v130, v175, v142, s[4:5]
	v_lshlrev_b32_e32 v130, 4, v130
	v_ashrrev_i32_e32 v131, 31, v130
	v_lshlrev_b64 v[142:143], 2, v[130:131]
	v_lshl_add_u64 v[170:171], v[156:157], 0, v[142:143]
	s_add_i32 s0, s55, 0x90
	s_ashr_i32 s0, s0, 6
	s_waitcnt vmcnt(1)
	v_pk_mul_f32 v[130:131], v[82:83], v[134:135]
	v_pk_mul_f32 v[172:173], v[80:81], v[132:133]
	v_pk_mul_f32 v[188:189], v[86:87], v[134:135]
	v_pk_mul_f32 v[190:191], v[84:85], v[132:133]
	v_pk_mul_f32 v[192:193], v[66:67], v[134:135]
	v_pk_mul_f32 v[196:197], v[64:65], v[132:133]
	v_pk_mul_f32 v[134:135], v[70:71], v[134:135]
	v_pk_mul_f32 v[132:133], v[68:69], v[132:133]
	s_waitcnt vmcnt(0)
	v_pk_fma_f32 v[130:131], v[86:87], v[138:139], v[130:131] neg_lo:[0,0,1] neg_hi:[0,0,1]
	v_pk_fma_f32 v[172:173], v[84:85], v[136:137], v[172:173] neg_lo:[0,0,1] neg_hi:[0,0,1]
	v_pk_fma_f32 v[188:189], v[82:83], v[138:139], v[188:189]
	v_pk_fma_f32 v[190:191], v[80:81], v[136:137], v[190:191]
	v_pk_fma_f32 v[192:193], v[70:71], v[138:139], v[192:193] neg_lo:[0,0,1] neg_hi:[0,0,1]
	v_pk_fma_f32 v[196:197], v[68:69], v[136:137], v[196:197] neg_lo:[0,0,1] neg_hi:[0,0,1]
	v_pk_fma_f32 v[134:135], v[66:67], v[138:139], v[134:135]
	v_pk_fma_f32 v[132:133], v[64:65], v[136:137], v[132:133]
	v_pk_mul_f32 v[136:137], v[130:131], s[18:19] op_sel_hi:[1,0]
	v_pk_mul_f32 v[130:131], v[172:173], s[18:19] op_sel_hi:[1,0]
	v_pk_mul_f32 v[138:139], v[188:189], s[18:19] op_sel_hi:[1,0]
	v_pk_mul_f32 v[172:173], v[190:191], s[18:19] op_sel_hi:[1,0]
	v_pk_mul_f32 v[188:189], v[192:193], s[18:19] op_sel_hi:[1,0]
	v_pk_mul_f32 v[190:191], v[196:197], s[18:19] op_sel_hi:[1,0]
	v_pk_mul_f32 v[192:193], v[134:135], s[18:19] op_sel_hi:[1,0]
	v_pk_mul_f32 v[196:197], v[132:133], s[18:19] op_sel_hi:[1,0]
	v_cvt_pk_bf16_f32 v130, v130, v131
	v_cvt_pk_bf16_f32 v131, v136, v137
	v_cvt_pk_bf16_f32 v132, v172, v173
	v_cvt_pk_bf16_f32 v133, v138, v139
	v_cvt_pk_bf16_f32 v134, v190, v191
	v_cvt_pk_bf16_f32 v135, v188, v189
	v_cvt_pk_bf16_f32 v136, v196, v197
	v_cvt_pk_bf16_f32 v137, v192, v193
	global_store_dwordx4 v[140:141], v[130:133], off sc1
	global_store_dwordx4 v[140:141], v[134:137], off offset:256 sc1
	global_load_dwordx4 v[130:133], v[170:171], off
	v_add_co_u32_e32 v140, vcc, s84, v128
	v_lshl_add_u64 v[134:135], v[154:155], 0, v[142:143]
	global_load_dwordx4 v[134:137], v[134:135], off
	v_mov_b32_e32 v142, s0
	v_cndmask_b32_e64 v142, v180, v142, s[4:5]
	v_lshlrev_b32_e32 v142, 4, v142
	v_ashrrev_i32_e32 v143, 31, v142
	v_addc_co_u32_e32 v141, vcc, 0, v129, vcc
	v_lshlrev_b64 v[142:143], 2, v[142:143]
	v_lshl_add_u64 v[138:139], v[128:129], 0, s[46:47]
	v_lshl_add_u64 v[170:171], v[156:157], 0, v[142:143]
	s_add_i32 s0, s55, 0xa0
	s_ashr_i32 s0, s0, 6
	s_waitcnt vmcnt(1)
	v_pk_mul_f32 v[172:173], v[58:59], v[132:133]
	v_pk_mul_f32 v[188:189], v[56:57], v[130:131]
	v_pk_mul_f32 v[190:191], v[62:63], v[132:133]
	v_pk_mul_f32 v[192:193], v[60:61], v[130:131]
	v_pk_mul_f32 v[196:197], v[42:43], v[132:133]
	v_pk_mul_f32 v[198:199], v[40:41], v[130:131]
	v_pk_mul_f32 v[132:133], v[46:47], v[132:133]
	v_pk_mul_f32 v[130:131], v[44:45], v[130:131]
	s_waitcnt vmcnt(0)
; DI unsigned cvtpk(float lo, float hi) { f32x2 v = {lo, hi}; bf16x2_t b = __builtin_convertvector(v, bf16x2_t); return __builtin_bit_cast(unsigned, b); }
; DI unsigned cvtpk_h(float lo, float hi) { f32x2 v = {lo, hi}; h16x2_t b = __builtin_convertvector(v, h16x2_t); return __builtin_bit_cast(unsigned, b); }
; DI float sigm(float x) { return __builtin_amdgcn_rcpf(1.f + fexp(-x)); }
;     template <int MODE> __device__ __forceinline__ void run(const f32x4 (&acc)[2][2][4][2], u16* dst, int ld, int row0, int col0, int trow0, int wc, int fq, const float* lb) const {
;     ...
;                 const int rr = ai * HALF + m * 16;
;                 u16* rowp = dst + (size_t)(row0 + rr) * ld + col0;
;                 f32x4 cs, sn;
;                 if (MODE == 1 || MODE == 2) { const int t = trow0 + rr; const int pos = (wc & 1) ? (t & 63) : (t >> 6);
;                     cs = *(const f32x4*)(rcos + pos * 16 + 4 * fq); sn = *(const f32x4*)(rsin + pos * 16 + 4 * fq); }
; #pragma unroll
;                 for (int bj = 0; bj < 2; ++bj) {
;                     f32x4 v0 = acc[ai][bj][m][0], v1 = acc[ai][bj][m][1];
;                     if (MODE == 1 || MODE == 2) { const f32x4 a = v0 * cs - v1 * sn, b = v1 * cs + v0 * sn; v0 = a; v1 = b;
;                         if (MODE == 2) { v0 = v0 * 0.18033688011112042f; v1 = v1 * 0.18033688011112042f; } }
;                     if (MODE == 3) {
; #pragma unroll
;                         for (int i = 0; i < 4; ++i) { const float l0 = lb0[bj][i], l1 = lb1[bj][i];
;                             v0[i] = __logf(l0 + (1.f - l0) * sigm(v0[i])); v1[i] = __logf(l1 + (1.f - l1) * sigm(v1[i])); }
;                     }
;                     if (MODE == 4) {
; #pragma unroll
;                         for (int i = 0; i < 4; ++i) { v0[i] = silu_(v0[i]); v1[i] = silu_(v1[i]); }
;                     }
;                     if (MODE == 5) {
; #pragma unroll
;                         for (int i = 0; i < 4; ++i) { v0[i] = sigm(v0[i]); v1[i] = sigm(v1[i]); }
;                     }
;                     u32x4 w;
;                     if (MODE == 3) { w.x = cvtpk_h(v0[0], v0[1]); w.y = cvtpk_h(v0[2], v0[3]); w.z = cvtpk_h(v1[0], v1[1]); w.w = cvtpk_h(v1[2], v1[3]); }
;                     else { w.x = cvtpk(v0[0], v0[1]); w.y = cvtpk(v0[2], v0[3]); w.z = cvtpk(v1[0], v1[1]); w.w = cvtpk(v1[2], v1[3]); }
;                     *(u32x4*)(rowp + bj * HALF) = w;
	v_pk_fma_f32 v[172:173], v[62:63], v[136:137], v[172:173] neg_lo:[0,0,1] neg_hi:[0,0,1]
	v_pk_fma_f32 v[188:189], v[60:61], v[134:135], v[188:189] neg_lo:[0,0,1] neg_hi:[0,0,1]
	v_pk_fma_f32 v[190:191], v[58:59], v[136:137], v[190:191]
	v_pk_fma_f32 v[192:193], v[56:57], v[134:135], v[192:193]
	v_pk_fma_f32 v[196:197], v[46:47], v[136:137], v[196:197] neg_lo:[0,0,1] neg_hi:[0,0,1]
	v_pk_fma_f32 v[198:199], v[44:45], v[134:135], v[198:199] neg_lo:[0,0,1] neg_hi:[0,0,1]
	v_pk_fma_f32 v[132:133], v[42:43], v[136:137], v[132:133]
	v_pk_fma_f32 v[130:131], v[40:41], v[134:135], v[130:131]
	v_pk_mul_f32 v[134:135], v[172:173], s[18:19] op_sel_hi:[1,0]
	v_pk_mul_f32 v[136:137], v[188:189], s[18:19] op_sel_hi:[1,0]
	v_pk_mul_f32 v[172:173], v[190:191], s[18:19] op_sel_hi:[1,0]
	v_pk_mul_f32 v[188:189], v[192:193], s[18:19] op_sel_hi:[1,0]
	v_pk_mul_f32 v[190:191], v[196:197], s[18:19] op_sel_hi:[1,0]
	v_pk_mul_f32 v[192:193], v[198:199], s[18:19] op_sel_hi:[1,0]
	v_pk_mul_f32 v[196:197], v[132:133], s[18:19] op_sel_hi:[1,0]
	v_pk_mul_f32 v[198:199], v[130:131], s[18:19] op_sel_hi:[1,0]
	v_cvt_pk_bf16_f32 v130, v136, v137
	v_cvt_pk_bf16_f32 v131, v134, v135
	v_cvt_pk_bf16_f32 v132, v188, v189
	v_cvt_pk_bf16_f32 v133, v172, v173
	v_cvt_pk_bf16_f32 v134, v192, v193
	v_cvt_pk_bf16_f32 v135, v190, v191
	v_cvt_pk_bf16_f32 v136, v198, v199
	v_cvt_pk_bf16_f32 v137, v196, v197
	global_store_dwordx4 v[140:141], v[130:133], off sc1
	global_store_dwordx4 v[138:139], v[134:137], off offset:256 sc1
	global_load_dwordx4 v[130:133], v[170:171], off
	v_add_co_u32_e32 v140, vcc, s85, v128
	v_lshl_add_u64 v[134:135], v[154:155], 0, v[142:143]
	global_load_dwordx4 v[134:137], v[134:135], off
	v_mov_b32_e32 v142, s0
	v_cndmask_b32_e64 v142, v181, v142, s[4:5]
	v_lshlrev_b32_e32 v142, 4, v142
	v_ashrrev_i32_e32 v143, 31, v142
	v_addc_co_u32_e32 v141, vcc, 0, v129, vcc
	v_lshlrev_b64 v[142:143], 2, v[142:143]
	v_lshl_add_u64 v[138:139], v[128:129], 0, s[48:49]
	v_lshl_add_u64 v[170:171], v[156:157], 0, v[142:143]
	s_add_i32 s0, s55, 0xb0
	s_ashr_i32 s0, s0, 6
	s_waitcnt vmcnt(1)
	v_pk_mul_f32 v[172:173], v[50:51], v[132:133]
	v_pk_mul_f32 v[188:189], v[48:49], v[130:131]
	v_pk_mul_f32 v[190:191], v[54:55], v[132:133]
	v_pk_mul_f32 v[192:193], v[52:53], v[130:131]
	v_pk_mul_f32 v[196:197], v[26:27], v[132:133]
	v_pk_mul_f32 v[198:199], v[24:25], v[130:131]
	v_pk_mul_f32 v[132:133], v[30:31], v[132:133]
	v_pk_mul_f32 v[130:131], v[28:29], v[130:131]
	s_waitcnt vmcnt(0)
	v_pk_fma_f32 v[172:173], v[54:55], v[136:137], v[172:173] neg_lo:[0,0,1] neg_hi:[0,0,1]
	v_pk_fma_f32 v[188:189], v[52:53], v[134:135], v[188:189] neg_lo:[0,0,1] neg_hi:[0,0,1]
	v_pk_fma_f32 v[190:191], v[50:51], v[136:137], v[190:191]
	v_pk_fma_f32 v[192:193], v[48:49], v[134:135], v[192:193]
	v_pk_fma_f32 v[196:197], v[30:31], v[136:137], v[196:197] neg_lo:[0,0,1] neg_hi:[0,0,1]
	v_pk_fma_f32 v[198:199], v[28:29], v[134:135], v[198:199] neg_lo:[0,0,1] neg_hi:[0,0,1]
	v_pk_fma_f32 v[132:133], v[26:27], v[136:137], v[132:133]
	v_pk_fma_f32 v[130:131], v[24:25], v[134:135], v[130:131]
	v_pk_mul_f32 v[134:135], v[172:173], s[18:19] op_sel_hi:[1,0]
	v_pk_mul_f32 v[136:137], v[188:189], s[18:19] op_sel_hi:[1,0]
	v_pk_mul_f32 v[172:173], v[190:191], s[18:19] op_sel_hi:[1,0]
	v_pk_mul_f32 v[188:189], v[192:193], s[18:19] op_sel_hi:[1,0]
	v_pk_mul_f32 v[190:191], v[196:197], s[18:19] op_sel_hi:[1,0]
	v_pk_mul_f32 v[192:193], v[198:199], s[18:19] op_sel_hi:[1,0]
	v_pk_mul_f32 v[196:197], v[132:133], s[18:19] op_sel_hi:[1,0]
	v_pk_mul_f32 v[198:199], v[130:131], s[18:19] op_sel_hi:[1,0]
	v_cvt_pk_bf16_f32 v130, v136, v137
	v_cvt_pk_bf16_f32 v131, v134, v135
	v_cvt_pk_bf16_f32 v132, v188, v189
	v_cvt_pk_bf16_f32 v133, v172, v173
	v_cvt_pk_bf16_f32 v134, v192, v193
	v_cvt_pk_bf16_f32 v135, v190, v191
	v_cvt_pk_bf16_f32 v136, v198, v199
	v_cvt_pk_bf16_f32 v137, v196, v197
	global_store_dwordx4 v[140:141], v[130:133], off sc1
	global_store_dwordx4 v[138:139], v[134:137], off offset:256 sc1
	global_load_dwordx4 v[130:133], v[170:171], off
	v_add_co_u32_e32 v140, vcc, s88, v128
	v_lshl_add_u64 v[134:135], v[154:155], 0, v[142:143]
	global_load_dwordx4 v[134:137], v[134:135], off
	v_mov_b32_e32 v142, s0
	v_cndmask_b32_e64 v142, v182, v142, s[4:5]
	v_lshlrev_b32_e32 v142, 4, v142
	v_ashrrev_i32_e32 v143, 31, v142
	v_addc_co_u32_e32 v141, vcc, 0, v129, vcc
	v_lshlrev_b64 v[142:143], 2, v[142:143]
	v_lshl_add_u64 v[138:139], v[128:129], 0, s[50:51]
	v_lshl_add_u64 v[170:171], v[156:157], 0, v[142:143]
	s_waitcnt vmcnt(1)
	v_pk_mul_f32 v[172:173], v[34:35], v[132:133]
	v_pk_mul_f32 v[188:189], v[32:33], v[130:131]
	v_pk_mul_f32 v[190:191], v[38:39], v[132:133]
	v_pk_mul_f32 v[192:193], v[36:37], v[130:131]
	v_pk_mul_f32 v[196:197], v[10:11], v[132:133]
	v_pk_mul_f32 v[198:199], v[8:9], v[130:131]
	v_pk_mul_f32 v[132:133], v[14:15], v[132:133]
	v_pk_mul_f32 v[130:131], v[12:13], v[130:131]
	s_waitcnt vmcnt(0)
; DI unsigned cvtpk(float lo, float hi) { f32x2 v = {lo, hi}; bf16x2_t b = __builtin_convertvector(v, bf16x2_t); return __builtin_bit_cast(unsigned, b); }
; DI unsigned cvtpk_h(float lo, float hi) { f32x2 v = {lo, hi}; h16x2_t b = __builtin_convertvector(v, h16x2_t); return __builtin_bit_cast(unsigned, b); }
; DI float sigm(float x) { return __builtin_amdgcn_rcpf(1.f + fexp(-x)); }
;     template <int MODE> __device__ __forceinline__ void run(const f32x4 (&acc)[2][2][4][2], u16* dst, int ld, int row0, int col0, int trow0, int wc, int fq, const float* lb) const {
;     ...
;                 const int rr = ai * HALF + m * 16;
;                 u16* rowp = dst + (size_t)(row0 + rr) * ld + col0;
;                 f32x4 cs, sn;
;                 if (MODE == 1 || MODE == 2) { const int t = trow0 + rr; const int pos = (wc & 1) ? (t & 63) : (t >> 6);
;                     cs = *(const f32x4*)(rcos + pos * 16 + 4 * fq); sn = *(const f32x4*)(rsin + pos * 16 + 4 * fq); }
; #pragma unroll
;                 for (int bj = 0; bj < 2; ++bj) {
;                     f32x4 v0 = acc[ai][bj][m][0], v1 = acc[ai][bj][m][1];
;                     if (MODE == 1 || MODE == 2) { const f32x4 a = v0 * cs - v1 * sn, b = v1 * cs + v0 * sn; v0 = a; v1 = b;
;                         if (MODE == 2) { v0 = v0 * 0.18033688011112042f; v1 = v1 * 0.18033688011112042f; } }
;                     if (MODE == 3) {
; #pragma unroll
;                         for (int i = 0; i < 4; ++i) { const float l0 = lb0[bj][i], l1 = lb1[bj][i];
;                             v0[i] = __logf(l0 + (1.f - l0) * sigm(v0[i])); v1[i] = __logf(l1 + (1.f - l1) * sigm(v1[i])); }
;                     }
;                     if (MODE == 4) {
; #pragma unroll
;                         for (int i = 0; i < 4; ++i) { v0[i] = silu_(v0[i]); v1[i] = silu_(v1[i]); }
;                     }
;                     if (MODE == 5) {
; #pragma unroll
;                         for (int i = 0; i < 4; ++i) { v0[i] = sigm(v0[i]); v1[i] = sigm(v1[i]); }
;                     }
;                     u32x4 w;
;                     if (MODE == 3) { w.x = cvtpk_h(v0[0], v0[1]); w.y = cvtpk_h(v0[2], v0[3]); w.z = cvtpk_h(v1[0], v1[1]); w.w = cvtpk_h(v1[2], v1[3]); }
;                     else { w.x = cvtpk(v0[0], v0[1]); w.y = cvtpk(v0[2], v0[3]); w.z = cvtpk(v1[0], v1[1]); w.w = cvtpk(v1[2], v1[3]); }
;                     *(u32x4*)(rowp + bj * HALF) = w;
	v_pk_fma_f32 v[172:173], v[38:39], v[136:137], v[172:173] neg_lo:[0,0,1] neg_hi:[0,0,1]
	v_pk_fma_f32 v[188:189], v[36:37], v[134:135], v[188:189] neg_lo:[0,0,1] neg_hi:[0,0,1]
	v_pk_fma_f32 v[190:191], v[34:35], v[136:137], v[190:191]
	v_pk_fma_f32 v[192:193], v[32:33], v[134:135], v[192:193]
	v_pk_fma_f32 v[196:197], v[14:15], v[136:137], v[196:197] neg_lo:[0,0,1] neg_hi:[0,0,1]
	v_pk_fma_f32 v[198:199], v[12:13], v[134:135], v[198:199] neg_lo:[0,0,1] neg_hi:[0,0,1]
	v_pk_fma_f32 v[132:133], v[10:11], v[136:137], v[132:133]
	v_pk_fma_f32 v[130:131], v[8:9], v[134:135], v[130:131]
	v_pk_mul_f32 v[134:135], v[172:173], s[18:19] op_sel_hi:[1,0]
	v_pk_mul_f32 v[136:137], v[188:189], s[18:19] op_sel_hi:[1,0]
	v_pk_mul_f32 v[172:173], v[190:191], s[18:19] op_sel_hi:[1,0]
	v_pk_mul_f32 v[188:189], v[192:193], s[18:19] op_sel_hi:[1,0]
	v_pk_mul_f32 v[190:191], v[196:197], s[18:19] op_sel_hi:[1,0]
	v_pk_mul_f32 v[192:193], v[198:199], s[18:19] op_sel_hi:[1,0]
	v_pk_mul_f32 v[196:197], v[132:133], s[18:19] op_sel_hi:[1,0]
	v_pk_mul_f32 v[198:199], v[130:131], s[18:19] op_sel_hi:[1,0]
	v_cvt_pk_bf16_f32 v130, v136, v137
	v_cvt_pk_bf16_f32 v131, v134, v135
	v_cvt_pk_bf16_f32 v132, v188, v189
	v_cvt_pk_bf16_f32 v133, v172, v173
	v_cvt_pk_bf16_f32 v134, v192, v193
	v_cvt_pk_bf16_f32 v135, v190, v191
	v_cvt_pk_bf16_f32 v136, v198, v199
	v_cvt_pk_bf16_f32 v137, v196, v197
	global_store_dwordx4 v[140:141], v[130:133], off sc1
	global_store_dwordx4 v[138:139], v[134:137], off offset:256 sc1
	global_load_dwordx4 v[130:133], v[170:171], off
	v_add_co_u32_e32 v138, vcc, s89, v128
	v_lshl_add_u64 v[134:135], v[154:155], 0, v[142:143]
	global_load_dwordx4 v[134:137], v[134:135], off
	v_lshl_add_u64 v[170:171], v[128:129], 0, s[52:53]
	v_addc_co_u32_e32 v139, vcc, 0, v129, vcc
	s_waitcnt vmcnt(1)
	v_pk_mul_f32 v[128:129], v[18:19], v[132:133]
	v_pk_mul_f32 v[140:141], v[16:17], v[130:131]
	v_pk_mul_f32 v[142:143], v[22:23], v[132:133]
	v_pk_mul_f32 v[172:173], v[20:21], v[130:131]
	v_pk_mul_f32 v[188:189], v[2:3], v[132:133]
	v_pk_mul_f32 v[190:191], v[0:1], v[130:131]
	v_pk_mul_f32 v[132:133], v[6:7], v[132:133]
	v_pk_mul_f32 v[130:131], v[4:5], v[130:131]
	s_waitcnt vmcnt(0)
	v_pk_fma_f32 v[128:129], v[22:23], v[136:137], v[128:129] neg_lo:[0,0,1] neg_hi:[0,0,1]
	v_pk_fma_f32 v[140:141], v[20:21], v[134:135], v[140:141] neg_lo:[0,0,1] neg_hi:[0,0,1]
	v_pk_fma_f32 v[142:143], v[18:19], v[136:137], v[142:143]
	v_pk_fma_f32 v[172:173], v[16:17], v[134:135], v[172:173]
	v_pk_fma_f32 v[188:189], v[6:7], v[136:137], v[188:189] neg_lo:[0,0,1] neg_hi:[0,0,1]
	v_pk_fma_f32 v[190:191], v[4:5], v[134:135], v[190:191] neg_lo:[0,0,1] neg_hi:[0,0,1]
	v_pk_fma_f32 v[132:133], v[2:3], v[136:137], v[132:133]
	v_pk_fma_f32 v[130:131], v[0:1], v[134:135], v[130:131]
	v_pk_mul_f32 v[128:129], v[128:129], s[18:19] op_sel_hi:[1,0]
	v_pk_mul_f32 v[134:135], v[140:141], s[18:19] op_sel_hi:[1,0]
	v_pk_mul_f32 v[136:137], v[142:143], s[18:19] op_sel_hi:[1,0]
	v_pk_mul_f32 v[140:141], v[172:173], s[18:19] op_sel_hi:[1,0]
	v_pk_mul_f32 v[142:143], v[188:189], s[18:19] op_sel_hi:[1,0]
	v_pk_mul_f32 v[172:173], v[190:191], s[18:19] op_sel_hi:[1,0]
	v_pk_mul_f32 v[188:189], v[132:133], s[18:19] op_sel_hi:[1,0]
	v_pk_mul_f32 v[130:131], v[130:131], s[18:19] op_sel_hi:[1,0]
	v_cvt_pk_bf16_f32 v132, v134, v135
	v_cvt_pk_bf16_f32 v133, v128, v129
	v_cvt_pk_bf16_f32 v134, v140, v141
	v_cvt_pk_bf16_f32 v135, v136, v137
	v_cvt_pk_bf16_f32 v128, v172, v173
	v_cvt_pk_bf16_f32 v129, v142, v143
	v_cvt_pk_bf16_f32 v130, v130, v131
	v_cvt_pk_bf16_f32 v131, v188, v189
	global_store_dwordx4 v[138:139], v[132:135], off sc1
; DI unsigned cvtpk(float lo, float hi) { f32x2 v = {lo, hi}; bf16x2_t b = __builtin_convertvector(v, bf16x2_t); return __builtin_bit_cast(unsigned, b); }
; DI unsigned cvtpk_h(float lo, float hi) { f32x2 v = {lo, hi}; h16x2_t b = __builtin_convertvector(v, h16x2_t); return __builtin_bit_cast(unsigned, b); }
;     template <int MODE> __device__ __forceinline__ void run(const f32x4 (&acc)[2][2][4][2], u16* dst, int ld, int row0, int col0, int trow0, int wc, int fq, const float* lb) const {
;     ...
;                     u32x4 w;
;                     if (MODE == 3) { w.x = cvtpk_h(v0[0], v0[1]); w.y = cvtpk_h(v0[2], v0[3]); w.z = cvtpk_h(v1[0], v1[1]); w.w = cvtpk_h(v1[2], v1[3]); }
;                     else { w.x = cvtpk(v0[0], v0[1]); w.y = cvtpk(v0[2], v0[3]); w.z = cvtpk(v1[0], v1[1]); w.w = cvtpk(v1[2], v1[3]); }
;                     *(u32x4*)(rowp + bj * HALF) = w;
;     __device__ __forceinline__ void operator()(const f32x4 (&acc)[2][2][4][2], const Unit& u, int wr, int wc, int fr, int fq) const {
;     ...
;         case 0: if (ctx) run<0>(acc, AK, 1024, kvrow0, c1, trow0, wc, fq, nullptr); else run<1>(acc, AK, 1024, kvrow0, c1, trow0, wc, fq, nullptr); break;
;         case 1: run<0>(acc, AV, 1024, kvrow0, c1, trow0, wc, fq, nullptr); break;
;         case 2: run<3>(acc, LFF, 1024, kvrow0, c1, trow0, wc, fq, lbf); break;
;         case 3: run<3>(acc, LFB, 1024, kvrow0, c1, trow0, wc, fq, lbb); break;
;         case 4: run<0>(acc, RI, 1024, kvrow0, c1, trow0, wc, fq, nullptr); break;
.LBB0_192:
	s_andn2_b64 vcc, exec, s[8:9]
	s_cbranch_vccnz .LBB0_194
	v_lshlrev_b32_e32 v152, 1, v187
	v_ashrrev_i32_e32 v167, 31, v166
	v_lshl_add_u64 v[132:133], s[28:29], 0, v[152:153]
	v_lshlrev_b64 v[128:129], 11, v[166:167]
	v_lshl_add_u64 v[134:135], v[132:133], 0, v[128:129]
	v_cvt_pk_bf16_f32 v128, v124, v125
	v_cvt_pk_bf16_f32 v129, v126, v127
	v_cvt_pk_bf16_f32 v130, v120, v121
	v_cvt_pk_bf16_f32 v131, v122, v123
	global_store_dwordx4 v[134:135], v[128:131], off sc1
	s_nop 1
	v_cvt_pk_bf16_f32 v128, v108, v109
	v_cvt_pk_bf16_f32 v129, v110, v111
	v_cvt_pk_bf16_f32 v130, v104, v105
	v_cvt_pk_bf16_f32 v131, v106, v107
	global_store_dwordx4 v[134:135], v[128:131], off offset:256 sc1
	s_nop 1
	v_or_b32_e32 v128, 16, v166
	v_ashrrev_i32_e32 v129, 31, v128
	v_lshlrev_b64 v[128:129], 11, v[128:129]
	v_lshl_add_u64 v[134:135], v[132:133], 0, v[128:129]
	v_cvt_pk_bf16_f32 v128, v116, v117
	v_cvt_pk_bf16_f32 v129, v118, v119
	v_cvt_pk_bf16_f32 v130, v112, v113
	v_cvt_pk_bf16_f32 v131, v114, v115
	global_store_dwordx4 v[134:135], v[128:131], off sc1
	s_nop 1
	v_cvt_pk_bf16_f32 v128, v92, v93
	v_cvt_pk_bf16_f32 v129, v94, v95
	v_cvt_pk_bf16_f32 v130, v88, v89
	v_cvt_pk_bf16_f32 v131, v90, v91
	global_store_dwordx4 v[134:135], v[128:131], off offset:256 sc1
	s_nop 1
	v_or_b32_e32 v128, 32, v166
	v_ashrrev_i32_e32 v129, 31, v128
	v_lshlrev_b64 v[128:129], 11, v[128:129]
	v_lshl_add_u64 v[134:135], v[132:133], 0, v[128:129]
	v_cvt_pk_bf16_f32 v128, v100, v101
	v_cvt_pk_bf16_f32 v129, v102, v103
	v_cvt_pk_bf16_f32 v130, v96, v97
	v_cvt_pk_bf16_f32 v131, v98, v99
	global_store_dwordx4 v[134:135], v[128:131], off sc1
	s_nop 1
	v_cvt_pk_bf16_f32 v128, v76, v77
	v_cvt_pk_bf16_f32 v129, v78, v79
	v_cvt_pk_bf16_f32 v130, v72, v73
	v_cvt_pk_bf16_f32 v131, v74, v75
	global_store_dwordx4 v[134:135], v[128:131], off offset:256 sc1
	s_nop 1
	v_or_b32_e32 v128, 48, v166
	v_ashrrev_i32_e32 v129, 31, v128
	v_lshlrev_b64 v[128:129], 11, v[128:129]
	v_lshl_add_u64 v[134:135], v[132:133], 0, v[128:129]
	v_cvt_pk_bf16_f32 v128, v84, v85
	v_cvt_pk_bf16_f32 v129, v86, v87
	v_cvt_pk_bf16_f32 v130, v80, v81
	v_cvt_pk_bf16_f32 v131, v82, v83
	global_store_dwordx4 v[134:135], v[128:131], off sc1
	s_nop 1
	v_cvt_pk_bf16_f32 v128, v68, v69
	v_cvt_pk_bf16_f32 v129, v70, v71
	v_cvt_pk_bf16_f32 v130, v64, v65
	v_cvt_pk_bf16_f32 v131, v66, v67
	global_store_dwordx4 v[134:135], v[128:131], off offset:256 sc1
	s_nop 1
	v_add_u32_e32 v128, 0x80, v166
	v_ashrrev_i32_e32 v129, 31, v128
	v_lshlrev_b64 v[128:129], 11, v[128:129]
	v_lshl_add_u64 v[134:135], v[132:133], 0, v[128:129]
	v_cvt_pk_bf16_f32 v128, v60, v61
	v_cvt_pk_bf16_f32 v129, v62, v63
	v_cvt_pk_bf16_f32 v130, v56, v57
	v_cvt_pk_bf16_f32 v131, v58, v59
	global_store_dwordx4 v[134:135], v[128:131], off sc1
	s_nop 1
	v_cvt_pk_bf16_f32 v128, v44, v45
	v_cvt_pk_bf16_f32 v129, v46, v47
	v_cvt_pk_bf16_f32 v130, v40, v41
	v_cvt_pk_bf16_f32 v131, v42, v43
	global_store_dwordx4 v[134:135], v[128:131], off offset:256 sc1
	s_nop 1
	v_add_u32_e32 v128, 0x90, v166
	v_ashrrev_i32_e32 v129, 31, v128
	v_lshlrev_b64 v[128:129], 11, v[128:129]
	v_lshl_add_u64 v[134:135], v[132:133], 0, v[128:129]
	v_cvt_pk_bf16_f32 v128, v52, v53
	v_cvt_pk_bf16_f32 v129, v54, v55
	v_cvt_pk_bf16_f32 v130, v48, v49
	v_cvt_pk_bf16_f32 v131, v50, v51
	global_store_dwordx4 v[134:135], v[128:131], off sc1
	s_nop 1
	v_cvt_pk_bf16_f32 v128, v28, v29
	v_cvt_pk_bf16_f32 v129, v30, v31
	v_cvt_pk_bf16_f32 v130, v24, v25
	v_cvt_pk_bf16_f32 v131, v26, v27
	global_store_dwordx4 v[134:135], v[128:131], off offset:256 sc1
	s_nop 1
	v_add_u32_e32 v128, 0xa0, v166
	v_ashrrev_i32_e32 v129, 31, v128
	v_lshlrev_b64 v[128:129], 11, v[128:129]
	v_lshl_add_u64 v[134:135], v[132:133], 0, v[128:129]
	v_cvt_pk_bf16_f32 v128, v36, v37
	v_cvt_pk_bf16_f32 v129, v38, v39
	v_cvt_pk_bf16_f32 v130, v32, v33
	v_cvt_pk_bf16_f32 v131, v34, v35
	global_store_dwordx4 v[134:135], v[128:131], off sc1
	s_nop 1
	v_cvt_pk_bf16_f32 v128, v12, v13
	v_cvt_pk_bf16_f32 v129, v14, v15
	v_cvt_pk_bf16_f32 v130, v8, v9
	v_cvt_pk_bf16_f32 v131, v10, v11
	global_store_dwordx4 v[134:135], v[128:131], off offset:256 sc1
	s_nop 1
	v_add_u32_e32 v128, 0xb0, v166
	v_ashrrev_i32_e32 v129, 31, v128
	v_lshlrev_b64 v[128:129], 11, v[128:129]
	v_lshl_add_u64 v[170:171], v[132:133], 0, v[128:129]
	v_cvt_pk_bf16_f32 v128, v20, v21
	v_cvt_pk_bf16_f32 v129, v22, v23
	v_cvt_pk_bf16_f32 v130, v16, v17
	v_cvt_pk_bf16_f32 v131, v18, v19
	global_store_dwordx4 v[170:171], v[128:131], off sc1
	s_nop 1
	v_cvt_pk_bf16_f32 v128, v4, v5
	v_cvt_pk_bf16_f32 v129, v6, v7
	v_cvt_pk_bf16_f32 v130, v0, v1
	v_cvt_pk_bf16_f32 v131, v2, v3

; DI float sigm(float x) { return __builtin_amdgcn_rcpf(1.f + fexp(-x)); }
;     template <int MODE> __device__ __forceinline__ void run(const f32x4 (&acc)[2][2][4][2], u16* dst, int ld, int row0, int col0, int trow0, int wc, int fq, const float* lb) const {
;         f32x4 lb0[2], lb1[2];
;         if (MODE == 3) {
; #pragma unroll
;             for (int bj = 0; bj < 2; ++bj) { lb0[bj] = *(const f32x4*)(lb + col0 + bj * HALF); lb1[bj] = *(const f32x4*)(lb + col0 + bj * HALF + 4); }
;         }
; #pragma unroll
;         for (int ai = 0; ai < 2; ++ai)
; #pragma unroll
;             for (int m = 0; m < 4; ++m) {
;                 const int rr = ai * HALF + m * 16;
;                 u16* rowp = dst + (size_t)(row0 + rr) * ld + col0;
;                 f32x4 cs, sn;
;                 if (MODE == 1 || MODE == 2) { const int t = trow0 + rr; const int pos = (wc & 1) ? (t & 63) : (t >> 6);
;                     cs = *(const f32x4*)(rcos + pos * 16 + 4 * fq); sn = *(const f32x4*)(rsin + pos * 16 + 4 * fq); }
; #pragma unroll
;                 for (int bj = 0; bj < 2; ++bj) {
;                     f32x4 v0 = acc[ai][bj][m][0], v1 = acc[ai][bj][m][1];
;                     if (MODE == 1 || MODE == 2) { const f32x4 a = v0 * cs - v1 * sn, b = v1 * cs + v0 * sn; v0 = a; v1 = b;
;                         if (MODE == 2) { v0 = v0 * 0.18033688011112042f; v1 = v1 * 0.18033688011112042f; } }
;                     if (MODE == 3) {
; #pragma unroll
;                         for (int i = 0; i < 4; ++i) { const float l0 = lb0[bj][i], l1 = lb1[bj][i];
;                             v0[i] = __logf(l0 + (1.f - l0) * sigm(v0[i])); v1[i] = __logf(l1 + (1.f - l1) * sigm(v1[i])); }
;     __device__ __forceinline__ void operator()(const f32x4 (&acc)[2][2][4][2], const Unit& u, int wr, int wc, int fr, int fq) const {
;     ...
;         switch (seg) {
;         case 0: if (ctx) run<0>(acc, AK, 1024, kvrow0, c1, trow0, wc, fq, nullptr); else run<1>(acc, AK, 1024, kvrow0, c1, trow0, wc, fq, nullptr); break;
;         case 1: run<0>(acc, AV, 1024, kvrow0, c1, trow0, wc, fq, nullptr); break;
;         case 2: run<3>(acc, LFF, 1024, kvrow0, c1, trow0, wc, fq, lbf); break;
;         case 3: run<3>(acc, LFB, 1024, kvrow0, c1, trow0, wc, fq, lbb); break;
.LBB0_195:
	s_and_b64 vcc, exec, s[8:9]
	s_cbranch_vccz .LBB0_207
	s_cmp_gt_i32 s58, 1
	s_mov_b64 s[6:7], -1
	s_cbranch_scc0 .LBB0_202
	s_cmp_gt_i32 s58, 2
	v_lshlrev_b32_e32 v169, 2, v187
	s_cbranch_scc0 .LBB0_199
	global_load_dwordx4 v[132:135], v169, s[40:41] offset:512
	global_load_dwordx4 v[140:143], v169, s[40:41]
	global_load_dwordx4 v[136:139], v169, s[40:41] offset:16
	global_load_dwordx4 v[128:131], v169, s[40:41] offset:528
	v_lshlrev_b32_e32 v152, 1, v187
	v_mul_f32_e32 v188, 0xbfb8aa3b, v124
	v_ashrrev_i32_e32 v167, 31, v166
	v_mul_f32_e32 v189, 0xbfb8aa3b, v120
	v_lshl_add_u64 v[170:171], s[26:27], 0, v[152:153]
	v_exp_f32_e32 v152, v188
	v_mul_f32_e32 v190, 0xbfb8aa3b, v125
	v_lshlrev_b64 v[172:173], 11, v[166:167]
	v_exp_f32_e32 v167, v189
	v_mul_f32_e32 v191, 0xbfb8aa3b, v121
	v_exp_f32_e32 v188, v190
	v_exp_f32_e32 v189, v191
	v_mul_f32_e32 v192, 0xbfb8aa3b, v126
	v_add_f32_e32 v152, 1.0, v152
	v_mul_f32_e32 v193, 0xbfb8aa3b, v122
	v_exp_f32_e32 v190, v192
	v_add_f32_e32 v167, 1.0, v167
	v_rcp_f32_e32 v192, v152
	v_exp_f32_e32 v191, v193
	v_add_f32_e32 v188, 1.0, v188
	v_rcp_f32_e32 v193, v167
	v_add_f32_e32 v189, 1.0, v189
	v_rcp_f32_e32 v195, v188
	v_rcp_f32_e32 v189, v189
	v_add_f32_e32 v190, 1.0, v190
	v_rcp_f32_e32 v190, v190
	v_lshl_add_u64 v[172:173], v[170:171], 0, v[172:173]
	s_waitcnt vmcnt(0)
	v_sub_f32_e32 v152, 1.0, v132
	v_sub_f32_e32 v202, 1.0, v140
	v_sub_f32_e32 v201, 1.0, v136
	v_fma_f32 v192, v192, v202, v140
	v_sub_f32_e32 v200, 1.0, v141
	v_fma_f32 v193, v193, v201, v136
	v_cmp_gt_f32_e32 vcc, s90, v192
	v_sub_f32_e32 v188, 1.0, v137
	v_fma_f32 v195, v195, v200, v141
	v_cndmask_b32_e64 v196, 0, 32, vcc
	v_cmp_gt_f32_e64 s[6:7], s90, v193
	v_fma_f32 v189, v189, v188, v137
	v_cmp_gt_f32_e64 s[8:9], s90, v195
	v_cndmask_b32_e64 v197, 0, 32, s[6:7]
	v_ldexp_f32 v192, v192, v196
	v_sub_f32_e32 v167, 1.0, v142
	v_cndmask_b32_e64 v198, 0, 32, s[8:9]
	v_cmp_gt_f32_e64 s[10:11], s90, v189
	v_ldexp_f32 v193, v193, v197
	v_log_f32_e32 v192, v192
	v_fma_f32 v190, v190, v167, v142
	v_cndmask_b32_e64 v199, 0, 32, s[10:11]
	v_ldexp_f32 v195, v195, v198
	v_log_f32_e32 v193, v193
	v_cmp_gt_f32_e64 s[12:13], s90, v190
	v_ldexp_f32 v189, v189, v199
	v_log_f32_e32 v195, v195
	v_cndmask_b32_e64 v203, 0, 32, s[12:13]
	v_log_f32_e32 v189, v189
	v_ldexp_f32 v190, v190, v203
	v_mul_f32_e32 v203, 0x3f317217, v192
	v_mul_f32_e32 v204, 0x3f317217, v193
	v_fma_f32 v203, v192, s91, -v203
	v_mul_f32_e32 v205, 0x3f317217, v195
	v_fma_f32 v204, v193, s91, -v204
	v_fmac_f32_e32 v203, 0x3377d1cf, v192
	v_cndmask_b32_e32 v196, 0, v186, vcc
	v_mul_f32_e32 v206, 0x3f317217, v189
	v_fma_f32 v205, v195, s91, -v205
	v_fmac_f32_e32 v204, 0x3377d1cf, v193
	v_fmac_f32_e32 v203, 0x3f317217, v192
	v_cmp_lt_f32_e64 vcc, |v192|, s92
	v_log_f32_e32 v190, v190
	v_fma_f32 v206, v189, s91, -v206
	v_fmac_f32_e32 v205, 0x3377d1cf, v195
	v_fmac_f32_e32 v204, 0x3f317217, v193
	v_cndmask_b32_e32 v192, v192, v203, vcc
	v_cmp_lt_f32_e64 vcc, |v193|, s92
	v_fmac_f32_e32 v206, 0x3377d1cf, v189
	v_fmac_f32_e32 v205, 0x3f317217, v195
	v_cndmask_b32_e32 v193, v193, v204, vcc
	v_cmp_lt_f32_e64 vcc, |v195|, s92
	v_fmac_f32_e32 v206, 0x3f317217, v189
	v_cndmask_b32_e64 v198, 0, v186, s[8:9]
	v_cndmask_b32_e32 v195, v195, v205, vcc
	v_cmp_lt_f32_e64 vcc, |v189|, s92
	v_cndmask_b32_e64 v199, 0, v186, s[10:11]
	v_sub_f32_e32 v195, v195, v198
	v_cndmask_b32_e32 v189, v189, v206, vcc
	v_sub_f32_e32 v198, v189, v199
	v_mul_f32_e32 v189, 0x3f317217, v190
	v_sub_f32_e32 v192, v192, v196
	v_fma_f32 v196, v190, s91, -v189
	v_add_f32_e32 v189, 1.0, v191
	v_rcp_f32_e32 v191, v189
	v_sub_f32_e32 v189, 1.0, v138
	v_fmac_f32_e32 v196, 0x3377d1cf, v190
	v_cndmask_b32_e64 v197, 0, v186, s[6:7]
	v_fma_f32 v191, v191, v189, v138
	v_fmac_f32_e32 v196, 0x3f317217, v190
	v_cmp_gt_f32_e32 vcc, s90, v191
	v_cmp_lt_f32_e64 s[6:7], |v190|, s92
	v_sub_f32_e32 v193, v193, v197
	v_cndmask_b32_e64 v197, 0, 32, vcc
	v_cndmask_b32_e64 v190, v190, v196, s[6:7]
	v_cndmask_b32_e64 v196, 0, v186, s[12:13]
	v_ldexp_f32 v191, v191, v197
	v_sub_f32_e32 v197, v190, v196
	v_mul_f32_e32 v196, 0xbfb8aa3b, v127
	v_log_f32_e32 v191, v191
	v_exp_f32_e32 v196, v196
	v_cndmask_b32_e32 v199, 0, v186, vcc
	v_cvt_pk_f16_f32 v198, v193, v198
	v_mul_f32_e32 v190, 0x3f317217, v191
	v_add_f32_e32 v196, 1.0, v196
	v_fma_f32 v190, v191, s91, -v190
	v_rcp_f32_e32 v196, v196
	v_fmac_f32_e32 v190, 0x3377d1cf, v191
	v_fmac_f32_e32 v190, 0x3f317217, v191
	v_cmp_lt_f32_e64 s[6:7], |v191|, s92
	s_nop 1
	v_cndmask_b32_e64 v191, v191, v190, s[6:7]
	v_sub_f32_e32 v190, 1.0, v143
	v_fma_f32 v196, v196, v190, v143
	v_cmp_gt_f32_e32 vcc, s90, v196
	v_sub_f32_e32 v199, v191, v199
	s_nop 0
	v_cndmask_b32_e64 v203, 0, 32, vcc
	v_ldexp_f32 v196, v196, v203
	v_log_f32_e32 v196, v196
	v_mul_f32_e32 v203, 0xbfb8aa3b, v123
	v_exp_f32_e32 v203, v203
	v_mul_f32_e32 v191, 0x3f317217, v196
	v_fma_f32 v204, v196, s91, -v191
	v_add_f32_e32 v191, 1.0, v203
	v_rcp_f32_e32 v203, v191
	v_sub_f32_e32 v191, 1.0, v139
	v_fmac_f32_e32 v204, 0x3377d1cf, v196
	v_fmac_f32_e32 v204, 0x3f317217, v196
	v_fma_f32 v203, v203, v191, v139
	v_cmp_gt_f32_e64 s[6:7], s90, v203
	v_cmp_lt_f32_e64 s[8:9], |v196|, s92
	s_nop 0
	v_cndmask_b32_e64 v205, 0, 32, s[6:7]
	v_ldexp_f32 v203, v203, v205
	v_log_f32_e32 v203, v203
	v_cndmask_b32_e64 v196, v196, v204, s[8:9]
	v_cndmask_b32_e32 v204, 0, v186, vcc
	v_sub_f32_e32 v204, v196, v204
	v_mul_f32_e32 v196, 0x3f317217, v203
	v_fma_f32 v196, v203, s91, -v196
	v_fmac_f32_e32 v196, 0x3377d1cf, v203
	v_fmac_f32_e32 v196, 0x3f317217, v203
	v_cmp_lt_f32_e64 vcc, |v203|, s92
	v_cndmask_b32_e64 v205, 0, v186, s[6:7]
; DI unsigned cvtpk(float lo, float hi) { f32x2 v = {lo, hi}; bf16x2_t b = __builtin_convertvector(v, bf16x2_t); return __builtin_bit_cast(unsigned, b); }
; DI unsigned cvtpk_h(float lo, float hi) { f32x2 v = {lo, hi}; h16x2_t b = __builtin_convertvector(v, h16x2_t); return __builtin_bit_cast(unsigned, b); }
; DI float sigm(float x) { return __builtin_amdgcn_rcpf(1.f + fexp(-x)); }
; DI float silu_(float x) { return x * sigm(x); }
;     template <int MODE> __device__ __forceinline__ void run(const f32x4 (&acc)[2][2][4][2], u16* dst, int ld, int row0, int col0, int trow0, int wc, int fq, const float* lb) const {
;     ...
;                         for (int i = 0; i < 4; ++i) { const float l0 = lb0[bj][i], l1 = lb1[bj][i];
;                             v0[i] = __logf(l0 + (1.f - l0) * sigm(v0[i])); v1[i] = __logf(l1 + (1.f - l1) * sigm(v1[i])); }
;                     }
;                     if (MODE == 4) {
; #pragma unroll
;                         for (int i = 0; i < 4; ++i) { v0[i] = silu_(v0[i]); v1[i] = silu_(v1[i]); }
;                     }
;                     if (MODE == 5) {
; #pragma unroll
;                         for (int i = 0; i < 4; ++i) { v0[i] = sigm(v0[i]); v1[i] = sigm(v1[i]); }
;                     }
;                     u32x4 w;
;                     if (MODE == 3) { w.x = cvtpk_h(v0[0], v0[1]); w.y = cvtpk_h(v0[2], v0[3]); w.z = cvtpk_h(v1[0], v1[1]); w.w = cvtpk_h(v1[2], v1[3]); }
;                     else { w.x = cvtpk(v0[0], v0[1]); w.y = cvtpk(v0[2], v0[3]); w.z = cvtpk(v1[0], v1[1]); w.w = cvtpk(v1[2], v1[3]); }
;                     *(u32x4*)(rowp + bj * HALF) = w;
	v_cvt_pk_f16_f32 v197, v197, v204
	v_cndmask_b32_e32 v196, v203, v196, vcc
	v_mul_f32_e32 v203, 0xbfb8aa3b, v108
	v_exp_f32_e32 v203, v203
	v_sub_f32_e32 v205, v196, v205
	v_cvt_pk_f16_f32 v196, v192, v195
	v_cvt_pk_f16_f32 v199, v199, v205
	v_add_f32_e32 v192, 1.0, v203
	v_rcp_f32_e32 v192, v192
	global_store_dwordx4 v[172:173], v[196:199], off sc1
	v_fma_f32 v192, v192, v152, v132
	v_cmp_gt_f32_e32 vcc, s90, v192
	s_nop 1
	v_cndmask_b32_e64 v193, 0, 32, vcc
	v_ldexp_f32 v192, v192, v193
	v_log_f32_e32 v193, v192
	v_mul_f32_e32 v192, 0xbfb8aa3b, v104
	v_exp_f32_e32 v192, v192
	v_mul_f32_e32 v195, 0x3f317217, v193
	v_fma_f32 v195, v193, s91, -v195
	v_add_f32_e32 v192, 1.0, v192
	v_rcp_f32_e32 v196, v192
	v_sub_f32_e32 v192, 1.0, v128
	v_fmac_f32_e32 v195, 0x3377d1cf, v193
	v_fmac_f32_e32 v195, 0x3f317217, v193
	v_fma_f32 v196, v196, v192, v128
	v_cmp_gt_f32_e64 s[6:7], s90, v196
	v_cmp_lt_f32_e64 s[8:9], |v193|, s92
	s_nop 0
	v_cndmask_b32_e64 v197, 0, 32, s[6:7]
	v_cndmask_b32_e64 v193, v193, v195, s[8:9]
	v_cndmask_b32_e32 v195, 0, v186, vcc
	v_ldexp_f32 v196, v196, v197
	v_sub_f32_e32 v203, v193, v195
	v_mul_f32_e32 v195, 0xbfb8aa3b, v109
	v_log_f32_e32 v196, v196
	v_exp_f32_e32 v195, v195
	v_cndmask_b32_e64 v197, 0, v186, s[6:7]
	v_mul_f32_e32 v193, 0x3f317217, v196
	v_add_f32_e32 v195, 1.0, v195
	v_fma_f32 v193, v196, s91, -v193
	v_rcp_f32_e32 v195, v195
	v_fmac_f32_e32 v193, 0x3377d1cf, v196
	v_fmac_f32_e32 v193, 0x3f317217, v196
	v_cmp_lt_f32_e64 vcc, |v196|, s92
	s_nop 1
	v_cndmask_b32_e32 v196, v196, v193, vcc
	v_sub_f32_e32 v193, 1.0, v133
	v_fma_f32 v195, v195, v193, v133
	v_cmp_gt_f32_e32 vcc, s90, v195
	v_sub_f32_e32 v206, v196, v197
	s_nop 0
	v_cndmask_b32_e64 v198, 0, 32, vcc
	v_ldexp_f32 v195, v195, v198
	v_log_f32_e32 v198, v195
	v_mul_f32_e32 v195, 0xbfb8aa3b, v105
	v_exp_f32_e32 v195, v195
	v_mul_f32_e32 v196, 0x3f317217, v198
	v_fma_f32 v196, v198, s91, -v196
	v_add_f32_e32 v195, 1.0, v195
	v_rcp_f32_e32 v197, v195
	v_sub_f32_e32 v195, 1.0, v129
	v_fmac_f32_e32 v196, 0x3377d1cf, v198
	v_fmac_f32_e32 v196, 0x3f317217, v198
	v_fma_f32 v197, v197, v195, v129
	v_cmp_gt_f32_e64 s[6:7], s90, v197
	v_cmp_lt_f32_e64 s[8:9], |v198|, s92
	s_nop 0
	v_cndmask_b32_e64 v199, 0, 32, s[6:7]
	v_cndmask_b32_e64 v196, v198, v196, s[8:9]
	v_cndmask_b32_e32 v198, 0, v186, vcc
	v_ldexp_f32 v197, v197, v199
	v_sub_f32_e32 v204, v196, v198
	v_mul_f32_e32 v198, 0xbfb8aa3b, v110
	v_log_f32_e32 v197, v197
	v_exp_f32_e32 v198, v198
	v_cndmask_b32_e64 v199, 0, v186, s[6:7]
	v_cvt_pk_f16_f32 v204, v203, v204
	v_mul_f32_e32 v196, 0x3f317217, v197
	v_add_f32_e32 v198, 1.0, v198
	v_fma_f32 v196, v197, s91, -v196
	v_rcp_f32_e32 v198, v198
	v_fmac_f32_e32 v196, 0x3377d1cf, v197
	v_fmac_f32_e32 v196, 0x3f317217, v197
	v_cmp_lt_f32_e64 vcc, |v197|, s92
	v_mul_f32_e32 v203, 0xbfb8aa3b, v116
	v_exp_f32_e32 v203, v203
	v_cndmask_b32_e32 v196, v197, v196, vcc
	v_sub_f32_e32 v197, 1.0, v134
	v_fma_f32 v198, v198, v197, v134
	v_cmp_gt_f32_e32 vcc, s90, v198
	v_sub_f32_e32 v207, v196, v199
	v_add_f32_e32 v203, 1.0, v203
	v_cndmask_b32_e64 v205, 0, 32, vcc
	v_ldexp_f32 v198, v198, v205
	v_log_f32_e32 v198, v198
	v_mul_f32_e32 v205, 0xbfb8aa3b, v106
	v_exp_f32_e32 v205, v205
	v_rcp_f32_e32 v203, v203
	v_mul_f32_e32 v196, 0x3f317217, v198
	v_fma_f32 v199, v198, s91, -v196
	v_add_f32_e32 v196, 1.0, v205
	v_rcp_f32_e32 v205, v196
	v_sub_f32_e32 v196, 1.0, v130
	v_fmac_f32_e32 v199, 0x3377d1cf, v198
	v_fmac_f32_e32 v199, 0x3f317217, v198
	v_fma_f32 v205, v205, v196, v130
	v_cmp_gt_f32_e64 s[6:7], s90, v205
	v_cmp_lt_f32_e64 s[8:9], |v198|, s92
	v_fma_f32 v203, v203, v202, v140
	v_cndmask_b32_e64 v208, 0, 32, s[6:7]
	v_cndmask_b32_e64 v198, v198, v199, s[8:9]
	v_cndmask_b32_e32 v199, 0, v186, vcc
	v_ldexp_f32 v205, v205, v208
	v_sub_f32_e32 v208, v198, v199
	v_mul_f32_e32 v199, 0xbfb8aa3b, v111
	v_log_f32_e32 v205, v205
	v_exp_f32_e32 v199, v199
	v_cndmask_b32_e64 v209, 0, v186, s[6:7]
	v_cvt_pk_f16_f32 v206, v206, v207
	v_mul_f32_e32 v198, 0x3f317217, v205
	v_add_f32_e32 v199, 1.0, v199
	v_fma_f32 v198, v205, s91, -v198
	v_rcp_f32_e32 v199, v199
	v_fmac_f32_e32 v198, 0x3377d1cf, v205
	v_fmac_f32_e32 v198, 0x3f317217, v205
	v_cmp_lt_f32_e64 vcc, |v205|, s92
	s_nop 1
	v_cndmask_b32_e32 v205, v205, v198, vcc
	v_sub_f32_e32 v198, 1.0, v135
	v_fma_f32 v199, v199, v198, v135
	v_cmp_gt_f32_e32 vcc, s90, v199
	v_sub_f32_e32 v209, v205, v209
	s_nop 0
	v_cndmask_b32_e64 v210, 0, 32, vcc
	v_ldexp_f32 v199, v199, v210
	v_log_f32_e32 v210, v199
	v_mul_f32_e32 v199, 0xbfb8aa3b, v107
	v_exp_f32_e32 v199, v199
	v_mul_f32_e32 v205, 0x3f317217, v210
	v_fma_f32 v205, v210, s91, -v205
	v_add_f32_e32 v199, 1.0, v199
	v_rcp_f32_e32 v211, v199
	v_sub_f32_e32 v199, 1.0, v131
	v_fmac_f32_e32 v205, 0x3377d1cf, v210
	v_fmac_f32_e32 v205, 0x3f317217, v210
	v_fma_f32 v211, v211, v199, v131
	v_cmp_gt_f32_e64 s[6:7], s90, v211
	v_cmp_lt_f32_e64 s[8:9], |v210|, s92
	s_nop 0
	v_cndmask_b32_e64 v212, 0, 32, s[6:7]
	v_ldexp_f32 v211, v211, v212
	v_log_f32_e32 v211, v211
	v_cndmask_b32_e64 v205, v210, v205, s[8:9]
	v_cndmask_b32_e32 v210, 0, v186, vcc
	v_sub_f32_e32 v205, v205, v210
	v_mul_f32_e32 v210, 0x3f317217, v211
	v_fma_f32 v210, v211, s91, -v210
	v_fmac_f32_e32 v210, 0x3377d1cf, v211
	v_fmac_f32_e32 v210, 0x3f317217, v211
	v_cmp_lt_f32_e64 vcc, |v211|, s92
	v_cvt_pk_f16_f32 v205, v208, v205
	s_nop 0
	v_cndmask_b32_e32 v210, v211, v210, vcc
	v_cndmask_b32_e64 v211, 0, v186, s[6:7]
	v_sub_f32_e32 v210, v210, v211
	v_cvt_pk_f16_f32 v207, v209, v210
	v_cmp_gt_f32_e32 vcc, s90, v203
	global_store_dwordx4 v[172:173], v[204:207], off offset:256 sc1
	v_or_b32_e32 v172, 16, v166
	v_ashrrev_i32_e32 v173, 31, v172
; DI unsigned cvtpk(float lo, float hi) { f32x2 v = {lo, hi}; bf16x2_t b = __builtin_convertvector(v, bf16x2_t); return __builtin_bit_cast(unsigned, b); }
; DI unsigned cvtpk_h(float lo, float hi) { f32x2 v = {lo, hi}; h16x2_t b = __builtin_convertvector(v, h16x2_t); return __builtin_bit_cast(unsigned, b); }
; DI float sigm(float x) { return __builtin_amdgcn_rcpf(1.f + fexp(-x)); }
; DI float silu_(float x) { return x * sigm(x); }
;     template <int MODE> __device__ __forceinline__ void run(const f32x4 (&acc)[2][2][4][2], u16* dst, int ld, int row0, int col0, int trow0, int wc, int fq, const float* lb) const {
;     ...
;                         for (int i = 0; i < 4; ++i) { const float l0 = lb0[bj][i], l1 = lb1[bj][i];
;                             v0[i] = __logf(l0 + (1.f - l0) * sigm(v0[i])); v1[i] = __logf(l1 + (1.f - l1) * sigm(v1[i])); }
;                     }
;                     if (MODE == 4) {
; #pragma unroll
;                         for (int i = 0; i < 4; ++i) { v0[i] = silu_(v0[i]); v1[i] = silu_(v1[i]); }
;                     }
;                     if (MODE == 5) {
; #pragma unroll
;                         for (int i = 0; i < 4; ++i) { v0[i] = sigm(v0[i]); v1[i] = sigm(v1[i]); }
;                     }
;                     u32x4 w;
;                     if (MODE == 3) { w.x = cvtpk_h(v0[0], v0[1]); w.y = cvtpk_h(v0[2], v0[3]); w.z = cvtpk_h(v1[0], v1[1]); w.w = cvtpk_h(v1[2], v1[3]); }
;                     else { w.x = cvtpk(v0[0], v0[1]); w.y = cvtpk(v0[2], v0[3]); w.z = cvtpk(v1[0], v1[1]); w.w = cvtpk(v1[2], v1[3]); }
;                     *(u32x4*)(rowp + bj * HALF) = w;
	v_cndmask_b32_e64 v204, 0, 32, vcc
	v_ldexp_f32 v203, v203, v204
	v_mul_f32_e32 v204, 0xbfb8aa3b, v112
	v_exp_f32_e32 v204, v204
	v_log_f32_e32 v203, v203
	v_lshlrev_b64 v[172:173], 11, v[172:173]
	v_lshl_add_u64 v[172:173], v[170:171], 0, v[172:173]
	v_add_f32_e32 v204, 1.0, v204
	v_rcp_f32_e32 v204, v204
	v_mul_f32_e32 v205, 0x3f317217, v203
	v_fma_f32 v205, v203, s91, -v205
	v_fmac_f32_e32 v205, 0x3377d1cf, v203
	v_fma_f32 v204, v204, v201, v136
	v_cmp_gt_f32_e64 s[6:7], s90, v204
	v_fmac_f32_e32 v205, 0x3f317217, v203
	v_cmp_lt_f32_e64 s[8:9], |v203|, s92
	v_cndmask_b32_e64 v206, 0, 32, s[6:7]
	v_ldexp_f32 v204, v204, v206
	v_mul_f32_e32 v206, 0xbfb8aa3b, v117
	v_exp_f32_e32 v206, v206
	v_log_f32_e32 v204, v204
	v_cndmask_b32_e64 v203, v203, v205, s[8:9]
	v_cndmask_b32_e32 v205, 0, v186, vcc
	v_add_f32_e32 v206, 1.0, v206
	v_rcp_f32_e32 v206, v206
	v_sub_f32_e32 v203, v203, v205
	v_mul_f32_e32 v205, 0x3f317217, v204
	v_fma_f32 v205, v204, s91, -v205
	v_fmac_f32_e32 v205, 0x3377d1cf, v204
	v_fmac_f32_e32 v205, 0x3f317217, v204
	v_cmp_lt_f32_e64 vcc, |v204|, s92
	v_fma_f32 v206, v206, v200, v141
	s_nop 0
	v_cndmask_b32_e32 v204, v204, v205, vcc
	v_cmp_gt_f32_e32 vcc, s90, v206
	v_cndmask_b32_e64 v205, 0, v186, s[6:7]
	s_nop 0
	v_cndmask_b32_e64 v207, 0, 32, vcc
	v_ldexp_f32 v206, v206, v207
	v_sub_f32_e32 v207, v204, v205
	v_mul_f32_e32 v204, 0xbfb8aa3b, v113
	v_exp_f32_e32 v204, v204
	v_log_f32_e32 v206, v206
	v_cndmask_b32_e32 v208, 0, v186, vcc
	v_add_f32_e32 v204, 1.0, v204
	v_rcp_f32_e32 v204, v204
	v_mul_f32_e32 v205, 0x3f317217, v206
	v_fma_f32 v205, v206, s91, -v205
	v_fmac_f32_e32 v205, 0x3377d1cf, v206
	v_fmac_f32_e32 v205, 0x3f317217, v206
	v_cmp_lt_f32_e64 s[6:7], |v206|, s92
	v_fma_f32 v204, v204, v188, v137
	s_nop 0
	v_cndmask_b32_e64 v205, v206, v205, s[6:7]
	v_cmp_gt_f32_e64 s[6:7], s90, v204
	v_sub_f32_e32 v205, v205, v208
	s_nop 0
	v_cndmask_b32_e64 v206, 0, 32, s[6:7]
	v_ldexp_f32 v204, v204, v206
	v_mul_f32_e32 v206, 0xbfb8aa3b, v118
	v_exp_f32_e32 v206, v206
	v_log_f32_e32 v204, v204
	v_add_f32_e32 v206, 1.0, v206
	v_rcp_f32_e32 v206, v206
	v_mul_f32_e32 v208, 0x3f317217, v204
	v_fma_f32 v208, v204, s91, -v208
	v_fmac_f32_e32 v208, 0x3377d1cf, v204
	v_fma_f32 v206, v206, v167, v142
	v_cmp_gt_f32_e32 vcc, s90, v206
	v_fmac_f32_e32 v208, 0x3f317217, v204
	v_cmp_lt_f32_e64 s[8:9], |v204|, s92
	v_cndmask_b32_e64 v209, 0, 32, vcc
	v_ldexp_f32 v206, v206, v209
	v_mul_f32_e32 v209, 0xbfb8aa3b, v114
	v_exp_f32_e32 v209, v209
	v_log_f32_e32 v206, v206
	v_cndmask_b32_e64 v204, v204, v208, s[8:9]
	v_cndmask_b32_e64 v208, 0, v186, s[6:7]
	v_add_f32_e32 v209, 1.0, v209
	v_sub_f32_e32 v208, v204, v208
	v_mul_f32_e32 v204, 0x3f317217, v206
	v_rcp_f32_e32 v209, v209
	v_fma_f32 v204, v206, s91, -v204
	v_fmac_f32_e32 v204, 0x3377d1cf, v206
	v_fmac_f32_e32 v204, 0x3f317217, v206
	v_cmp_lt_f32_e64 s[6:7], |v206|, s92
	v_fma_f32 v209, v209, v189, v138
	s_nop 0
	v_cndmask_b32_e64 v204, v206, v204, s[6:7]
	v_cndmask_b32_e32 v206, 0, v186, vcc
	v_cmp_gt_f32_e32 vcc, s90, v209
	v_sub_f32_e32 v206, v204, v206
	v_mul_f32_e32 v204, 0xbfb8aa3b, v119
	v_cndmask_b32_e64 v210, 0, 32, vcc
	v_exp_f32_e32 v204, v204
	v_ldexp_f32 v209, v209, v210
	v_log_f32_e32 v209, v209
	v_cndmask_b32_e32 v211, 0, v186, vcc
	v_add_f32_e32 v204, 1.0, v204
	v_rcp_f32_e32 v204, v204
	v_mul_f32_e32 v210, 0x3f317217, v209
	v_fma_f32 v210, v209, s91, -v210
	v_fmac_f32_e32 v210, 0x3377d1cf, v209
	v_fmac_f32_e32 v210, 0x3f317217, v209
	v_cmp_lt_f32_e64 s[6:7], |v209|, s92
	v_fma_f32 v204, v204, v190, v143
	s_nop 0
	v_cndmask_b32_e64 v209, v209, v210, s[6:7]
	v_cmp_gt_f32_e64 s[6:7], s90, v204
	v_sub_f32_e32 v209, v209, v211
	s_nop 0
	v_cndmask_b32_e64 v210, 0, 32, s[6:7]
	v_ldexp_f32 v204, v204, v210
	v_mul_f32_e32 v210, 0xbfb8aa3b, v115
	v_exp_f32_e32 v210, v210
	v_log_f32_e32 v204, v204
	v_add_f32_e32 v210, 1.0, v210
	v_rcp_f32_e32 v210, v210
	v_mul_f32_e32 v211, 0x3f317217, v204
	v_fma_f32 v211, v204, s91, -v211
	v_fmac_f32_e32 v211, 0x3377d1cf, v204
	v_fma_f32 v210, v210, v191, v139
	v_cmp_gt_f32_e32 vcc, s90, v210
	v_fmac_f32_e32 v211, 0x3f317217, v204
	v_cmp_lt_f32_e64 s[8:9], |v204|, s92
	v_cndmask_b32_e64 v212, 0, 32, vcc
	v_ldexp_f32 v210, v210, v212
	v_log_f32_e32 v210, v210
	v_cndmask_b32_e64 v204, v204, v211, s[8:9]
	v_cndmask_b32_e64 v211, 0, v186, s[6:7]
	v_sub_f32_e32 v211, v204, v211
	v_mul_f32_e32 v204, 0x3f317217, v210
	v_mul_f32_e32 v212, 0xbfb8aa3b, v92
	v_fma_f32 v204, v210, s91, -v204
	v_exp_f32_e32 v212, v212
	v_fmac_f32_e32 v204, 0x3377d1cf, v210
	v_fmac_f32_e32 v204, 0x3f317217, v210
	v_cmp_lt_f32_e64 s[6:7], |v210|, s92
	s_nop 1
	v_cndmask_b32_e64 v204, v210, v204, s[6:7]
	v_cndmask_b32_e32 v210, 0, v186, vcc
	v_sub_f32_e32 v210, v204, v210
	v_add_f32_e32 v204, 1.0, v212
	v_rcp_f32_e32 v212, v204
	v_cvt_pk_f16_f32 v204, v203, v205
	v_cvt_pk_f16_f32 v205, v206, v211
	v_cvt_pk_f16_f32 v206, v207, v208
	v_fma_f32 v203, v212, v152, v132
	v_cmp_gt_f32_e32 vcc, s90, v203
	s_nop 1
	v_cndmask_b32_e64 v207, 0, 32, vcc
	v_ldexp_f32 v203, v203, v207
	v_mul_f32_e32 v207, 0xbfb8aa3b, v88
	v_exp_f32_e32 v208, v207
	v_cvt_pk_f16_f32 v207, v209, v210
	global_store_dwordx4 v[172:173], v[204:207], off sc1
	v_log_f32_e32 v203, v203
	s_nop 0
	v_add_f32_e32 v205, 1.0, v208
	v_rcp_f32_e32 v205, v205
	v_mul_f32_e32 v204, 0x3f317217, v203
	v_fma_f32 v204, v203, s91, -v204
	v_fmac_f32_e32 v204, 0x3377d1cf, v203
	v_fma_f32 v205, v205, v192, v128
	v_cmp_gt_f32_e64 s[6:7], s90, v205
	v_fmac_f32_e32 v204, 0x3f317217, v203
	v_cmp_lt_f32_e64 s[8:9], |v203|, s92
	v_cndmask_b32_e64 v206, 0, 32, s[6:7]
	v_ldexp_f32 v205, v205, v206
	v_mul_f32_e32 v206, 0xbfb8aa3b, v93
; DI unsigned cvtpk(float lo, float hi) { f32x2 v = {lo, hi}; bf16x2_t b = __builtin_convertvector(v, bf16x2_t); return __builtin_bit_cast(unsigned, b); }
; DI unsigned cvtpk_h(float lo, float hi) { f32x2 v = {lo, hi}; h16x2_t b = __builtin_convertvector(v, h16x2_t); return __builtin_bit_cast(unsigned, b); }
; DI float sigm(float x) { return __builtin_amdgcn_rcpf(1.f + fexp(-x)); }
; DI float silu_(float x) { return x * sigm(x); }
;     template <int MODE> __device__ __forceinline__ void run(const f32x4 (&acc)[2][2][4][2], u16* dst, int ld, int row0, int col0, int trow0, int wc, int fq, const float* lb) const {
;     ...
;                         for (int i = 0; i < 4; ++i) { const float l0 = lb0[bj][i], l1 = lb1[bj][i];
;                             v0[i] = __logf(l0 + (1.f - l0) * sigm(v0[i])); v1[i] = __logf(l1 + (1.f - l1) * sigm(v1[i])); }
;                     }
;                     if (MODE == 4) {
; #pragma unroll
;                         for (int i = 0; i < 4; ++i) { v0[i] = silu_(v0[i]); v1[i] = silu_(v1[i]); }
;                     }
;                     if (MODE == 5) {
; #pragma unroll
;                         for (int i = 0; i < 4; ++i) { v0[i] = sigm(v0[i]); v1[i] = sigm(v1[i]); }
;                     }
;                     u32x4 w;
;                     if (MODE == 3) { w.x = cvtpk_h(v0[0], v0[1]); w.y = cvtpk_h(v0[2], v0[3]); w.z = cvtpk_h(v1[0], v1[1]); w.w = cvtpk_h(v1[2], v1[3]); }
;                     else { w.x = cvtpk(v0[0], v0[1]); w.y = cvtpk(v0[2], v0[3]); w.z = cvtpk(v1[0], v1[1]); w.w = cvtpk(v1[2], v1[3]); }
;                     *(u32x4*)(rowp + bj * HALF) = w;
	v_exp_f32_e32 v206, v206
	v_log_f32_e32 v205, v205
	v_cndmask_b32_e64 v203, v203, v204, s[8:9]
	v_cndmask_b32_e32 v204, 0, v186, vcc
	v_add_f32_e32 v206, 1.0, v206
	v_rcp_f32_e32 v206, v206
	v_sub_f32_e32 v203, v203, v204
	v_mul_f32_e32 v204, 0x3f317217, v205
	v_fma_f32 v204, v205, s91, -v204
	v_fmac_f32_e32 v204, 0x3377d1cf, v205
	v_fmac_f32_e32 v204, 0x3f317217, v205
	v_cmp_lt_f32_e64 vcc, |v205|, s92
	v_fma_f32 v206, v206, v193, v133
	s_nop 0
	v_cndmask_b32_e32 v204, v205, v204, vcc
	v_cmp_gt_f32_e32 vcc, s90, v206
	v_cndmask_b32_e64 v205, 0, v186, s[6:7]
	s_nop 0
	v_cndmask_b32_e64 v207, 0, 32, vcc
	v_ldexp_f32 v206, v206, v207
	v_sub_f32_e32 v207, v204, v205
	v_mul_f32_e32 v204, 0xbfb8aa3b, v89
	v_exp_f32_e32 v204, v204
	v_log_f32_e32 v206, v206
	v_cndmask_b32_e32 v208, 0, v186, vcc
	v_add_f32_e32 v204, 1.0, v204
	v_rcp_f32_e32 v204, v204
	v_mul_f32_e32 v205, 0x3f317217, v206
	v_fma_f32 v205, v206, s91, -v205
	v_fmac_f32_e32 v205, 0x3377d1cf, v206
	v_fmac_f32_e32 v205, 0x3f317217, v206
	v_cmp_lt_f32_e64 s[6:7], |v206|, s92
	v_fma_f32 v204, v204, v195, v129
	s_nop 0
	v_cndmask_b32_e64 v205, v206, v205, s[6:7]
	v_cmp_gt_f32_e64 s[6:7], s90, v204
	v_sub_f32_e32 v205, v205, v208
	s_nop 0
	v_cndmask_b32_e64 v206, 0, 32, s[6:7]
	v_ldexp_f32 v204, v204, v206
	v_mul_f32_e32 v206, 0xbfb8aa3b, v94
	v_exp_f32_e32 v206, v206
	v_log_f32_e32 v204, v204
	v_add_f32_e32 v206, 1.0, v206
	v_rcp_f32_e32 v206, v206
	v_mul_f32_e32 v208, 0x3f317217, v204
	v_fma_f32 v208, v204, s91, -v208
	v_fmac_f32_e32 v208, 0x3377d1cf, v204
	v_fma_f32 v206, v206, v197, v134
	v_cmp_gt_f32_e32 vcc, s90, v206
	v_fmac_f32_e32 v208, 0x3f317217, v204
	v_cmp_lt_f32_e64 s[8:9], |v204|, s92
	v_cndmask_b32_e64 v209, 0, 32, vcc
	v_ldexp_f32 v206, v206, v209
	v_mul_f32_e32 v209, 0xbfb8aa3b, v90
	v_exp_f32_e32 v209, v209
	v_log_f32_e32 v206, v206
	v_cndmask_b32_e64 v204, v204, v208, s[8:9]
	v_cndmask_b32_e64 v208, 0, v186, s[6:7]
	v_add_f32_e32 v209, 1.0, v209
	v_sub_f32_e32 v208, v204, v208
	v_mul_f32_e32 v204, 0x3f317217, v206
	v_rcp_f32_e32 v209, v209
	v_fma_f32 v204, v206, s91, -v204
	v_fmac_f32_e32 v204, 0x3377d1cf, v206
	v_fmac_f32_e32 v204, 0x3f317217, v206
	v_cmp_lt_f32_e64 s[6:7], |v206|, s92
	v_fma_f32 v209, v209, v196, v130
	s_nop 0
	v_cndmask_b32_e64 v204, v206, v204, s[6:7]
	v_cndmask_b32_e32 v206, 0, v186, vcc
	v_cmp_gt_f32_e32 vcc, s90, v209
	v_sub_f32_e32 v206, v204, v206
	v_mul_f32_e32 v204, 0xbfb8aa3b, v95
	v_cndmask_b32_e64 v210, 0, 32, vcc
	v_exp_f32_e32 v204, v204
	v_ldexp_f32 v209, v209, v210
	v_log_f32_e32 v209, v209
	v_cndmask_b32_e32 v211, 0, v186, vcc
	v_add_f32_e32 v204, 1.0, v204
	v_rcp_f32_e32 v204, v204
	v_mul_f32_e32 v210, 0x3f317217, v209
	v_fma_f32 v210, v209, s91, -v210
	v_fmac_f32_e32 v210, 0x3377d1cf, v209
	v_fmac_f32_e32 v210, 0x3f317217, v209
	v_cmp_lt_f32_e64 s[6:7], |v209|, s92
	v_fma_f32 v204, v204, v198, v135
	s_nop 0
	v_cndmask_b32_e64 v209, v209, v210, s[6:7]
	v_cmp_gt_f32_e64 s[6:7], s90, v204
	v_sub_f32_e32 v209, v209, v211
	s_nop 0
	v_cndmask_b32_e64 v210, 0, 32, s[6:7]
	v_ldexp_f32 v204, v204, v210
	v_mul_f32_e32 v210, 0xbfb8aa3b, v91
	v_exp_f32_e32 v210, v210
	v_log_f32_e32 v204, v204
	v_add_f32_e32 v210, 1.0, v210
	v_rcp_f32_e32 v210, v210
	v_mul_f32_e32 v211, 0x3f317217, v204
	v_fma_f32 v211, v204, s91, -v211
	v_fmac_f32_e32 v211, 0x3377d1cf, v204
	v_fma_f32 v210, v210, v199, v131
	v_cmp_gt_f32_e32 vcc, s90, v210
	v_fmac_f32_e32 v211, 0x3f317217, v204
	v_cmp_lt_f32_e64 s[8:9], |v204|, s92
	v_cndmask_b32_e64 v212, 0, 32, vcc
	v_ldexp_f32 v210, v210, v212
	v_log_f32_e32 v210, v210
	v_cndmask_b32_e64 v204, v204, v211, s[8:9]
	v_cndmask_b32_e64 v211, 0, v186, s[6:7]
	v_sub_f32_e32 v211, v204, v211
	v_mul_f32_e32 v204, 0x3f317217, v210
	v_fma_f32 v204, v210, s91, -v204
	v_fmac_f32_e32 v204, 0x3377d1cf, v210
	v_fmac_f32_e32 v204, 0x3f317217, v210
	v_cmp_lt_f32_e64 s[6:7], |v210|, s92
	s_nop 1
	v_cndmask_b32_e64 v204, v210, v204, s[6:7]
	v_cndmask_b32_e32 v210, 0, v186, vcc
	v_sub_f32_e32 v210, v204, v210
	v_cvt_pk_f16_f32 v204, v203, v205
	v_mul_f32_e32 v203, 0xbfb8aa3b, v100
	v_exp_f32_e32 v203, v203
	v_cvt_pk_f16_f32 v205, v206, v211
	v_cvt_pk_f16_f32 v206, v207, v208
	v_cvt_pk_f16_f32 v207, v209, v210
	v_add_f32_e32 v203, 1.0, v203
	v_rcp_f32_e32 v203, v203
	global_store_dwordx4 v[172:173], v[204:207], off offset:256 sc1
	v_or_b32_e32 v172, 32, v166
	v_ashrrev_i32_e32 v173, 31, v172
	v_fma_f32 v203, v203, v202, v140
	v_cmp_gt_f32_e32 vcc, s90, v203
	v_lshlrev_b64 v[172:173], 11, v[172:173]
	v_lshl_add_u64 v[172:173], v[170:171], 0, v[172:173]
	v_cndmask_b32_e64 v204, 0, 32, vcc
	v_ldexp_f32 v203, v203, v204
	v_mul_f32_e32 v204, 0xbfb8aa3b, v96
	v_exp_f32_e32 v204, v204
	v_log_f32_e32 v203, v203
	v_add_f32_e32 v204, 1.0, v204
	v_rcp_f32_e32 v204, v204
	v_mul_f32_e32 v205, 0x3f317217, v203
	v_fma_f32 v205, v203, s91, -v205
	v_fmac_f32_e32 v205, 0x3377d1cf, v203
	v_fma_f32 v204, v204, v201, v136
	v_cmp_gt_f32_e64 s[6:7], s90, v204
	v_fmac_f32_e32 v205, 0x3f317217, v203
	v_cmp_lt_f32_e64 s[8:9], |v203|, s92
	v_cndmask_b32_e64 v206, 0, 32, s[6:7]
	v_ldexp_f32 v204, v204, v206
	v_mul_f32_e32 v206, 0xbfb8aa3b, v101
	v_exp_f32_e32 v206, v206
	v_log_f32_e32 v204, v204
	v_cndmask_b32_e64 v203, v203, v205, s[8:9]
	v_cndmask_b32_e32 v205, 0, v186, vcc
	v_add_f32_e32 v206, 1.0, v206
	v_rcp_f32_e32 v206, v206
	v_sub_f32_e32 v203, v203, v205
	v_mul_f32_e32 v205, 0x3f317217, v204
	v_fma_f32 v205, v204, s91, -v205
	v_fmac_f32_e32 v205, 0x3377d1cf, v204
	v_fmac_f32_e32 v205, 0x3f317217, v204
	v_cmp_lt_f32_e64 vcc, |v204|, s92
	v_fma_f32 v206, v206, v200, v141
	s_nop 0
	v_cndmask_b32_e32 v204, v204, v205, vcc
	v_cmp_gt_f32_e32 vcc, s90, v206
; DI unsigned cvtpk(float lo, float hi) { f32x2 v = {lo, hi}; bf16x2_t b = __builtin_convertvector(v, bf16x2_t); return __builtin_bit_cast(unsigned, b); }
; DI unsigned cvtpk_h(float lo, float hi) { f32x2 v = {lo, hi}; h16x2_t b = __builtin_convertvector(v, h16x2_t); return __builtin_bit_cast(unsigned, b); }
; DI float sigm(float x) { return __builtin_amdgcn_rcpf(1.f + fexp(-x)); }
; DI float silu_(float x) { return x * sigm(x); }
;     template <int MODE> __device__ __forceinline__ void run(const f32x4 (&acc)[2][2][4][2], u16* dst, int ld, int row0, int col0, int trow0, int wc, int fq, const float* lb) const {
;     ...
;                         for (int i = 0; i < 4; ++i) { const float l0 = lb0[bj][i], l1 = lb1[bj][i];
;                             v0[i] = __logf(l0 + (1.f - l0) * sigm(v0[i])); v1[i] = __logf(l1 + (1.f - l1) * sigm(v1[i])); }
;                     }
;                     if (MODE == 4) {
; #pragma unroll
;                         for (int i = 0; i < 4; ++i) { v0[i] = silu_(v0[i]); v1[i] = silu_(v1[i]); }
;                     }
;                     if (MODE == 5) {
; #pragma unroll
;                         for (int i = 0; i < 4; ++i) { v0[i] = sigm(v0[i]); v1[i] = sigm(v1[i]); }
;                     }
;                     u32x4 w;
;                     if (MODE == 3) { w.x = cvtpk_h(v0[0], v0[1]); w.y = cvtpk_h(v0[2], v0[3]); w.z = cvtpk_h(v1[0], v1[1]); w.w = cvtpk_h(v1[2], v1[3]); }
;                     else { w.x = cvtpk(v0[0], v0[1]); w.y = cvtpk(v0[2], v0[3]); w.z = cvtpk(v1[0], v1[1]); w.w = cvtpk(v1[2], v1[3]); }
;                     *(u32x4*)(rowp + bj * HALF) = w;
	v_cndmask_b32_e64 v205, 0, v186, s[6:7]
	s_nop 0
	v_cndmask_b32_e64 v207, 0, 32, vcc
	v_ldexp_f32 v206, v206, v207
	v_sub_f32_e32 v207, v204, v205
	v_mul_f32_e32 v204, 0xbfb8aa3b, v97
	v_exp_f32_e32 v204, v204
	v_log_f32_e32 v206, v206
	v_cndmask_b32_e32 v208, 0, v186, vcc
	v_add_f32_e32 v204, 1.0, v204
	v_rcp_f32_e32 v204, v204
	v_mul_f32_e32 v205, 0x3f317217, v206
	v_fma_f32 v205, v206, s91, -v205
	v_fmac_f32_e32 v205, 0x3377d1cf, v206
	v_fmac_f32_e32 v205, 0x3f317217, v206
	v_cmp_lt_f32_e64 s[6:7], |v206|, s92
	v_fma_f32 v204, v204, v188, v137
	s_nop 0
	v_cndmask_b32_e64 v205, v206, v205, s[6:7]
	v_cmp_gt_f32_e64 s[6:7], s90, v204
	v_sub_f32_e32 v205, v205, v208
	s_nop 0
	v_cndmask_b32_e64 v206, 0, 32, s[6:7]
	v_ldexp_f32 v204, v204, v206
	v_mul_f32_e32 v206, 0xbfb8aa3b, v102
	v_exp_f32_e32 v206, v206
	v_log_f32_e32 v204, v204
	v_add_f32_e32 v206, 1.0, v206
	v_rcp_f32_e32 v206, v206
	v_mul_f32_e32 v208, 0x3f317217, v204
	v_fma_f32 v208, v204, s91, -v208
	v_fmac_f32_e32 v208, 0x3377d1cf, v204
	v_fma_f32 v206, v206, v167, v142
	v_cmp_gt_f32_e32 vcc, s90, v206
	v_fmac_f32_e32 v208, 0x3f317217, v204
	v_cmp_lt_f32_e64 s[8:9], |v204|, s92
	v_cndmask_b32_e64 v209, 0, 32, vcc
	v_ldexp_f32 v206, v206, v209
	v_mul_f32_e32 v209, 0xbfb8aa3b, v98
	v_exp_f32_e32 v209, v209
	v_log_f32_e32 v206, v206
	v_cndmask_b32_e64 v204, v204, v208, s[8:9]
	v_cndmask_b32_e64 v208, 0, v186, s[6:7]
	v_add_f32_e32 v209, 1.0, v209
	v_sub_f32_e32 v208, v204, v208
	v_mul_f32_e32 v204, 0x3f317217, v206
	v_rcp_f32_e32 v209, v209
	v_fma_f32 v204, v206, s91, -v204
	v_fmac_f32_e32 v204, 0x3377d1cf, v206
	v_fmac_f32_e32 v204, 0x3f317217, v206
	v_cmp_lt_f32_e64 s[6:7], |v206|, s92
	v_fma_f32 v209, v209, v189, v138
	s_nop 0
	v_cndmask_b32_e64 v204, v206, v204, s[6:7]
	v_cndmask_b32_e32 v206, 0, v186, vcc
	v_cmp_gt_f32_e32 vcc, s90, v209
	v_sub_f32_e32 v206, v204, v206
	v_mul_f32_e32 v204, 0xbfb8aa3b, v103
	v_cndmask_b32_e64 v210, 0, 32, vcc
	v_exp_f32_e32 v204, v204
	v_ldexp_f32 v209, v209, v210
	v_log_f32_e32 v209, v209
	v_cndmask_b32_e32 v211, 0, v186, vcc
	v_add_f32_e32 v204, 1.0, v204
	v_rcp_f32_e32 v204, v204
	v_mul_f32_e32 v210, 0x3f317217, v209
	v_fma_f32 v210, v209, s91, -v210
	v_fmac_f32_e32 v210, 0x3377d1cf, v209
	v_fmac_f32_e32 v210, 0x3f317217, v209
	v_cmp_lt_f32_e64 s[6:7], |v209|, s92
	v_fma_f32 v204, v204, v190, v143
	s_nop 0
	v_cndmask_b32_e64 v209, v209, v210, s[6:7]
	v_cmp_gt_f32_e64 s[6:7], s90, v204
	v_sub_f32_e32 v209, v209, v211
	s_nop 0
	v_cndmask_b32_e64 v210, 0, 32, s[6:7]
	v_ldexp_f32 v204, v204, v210
	v_mul_f32_e32 v210, 0xbfb8aa3b, v99
	v_exp_f32_e32 v210, v210
	v_log_f32_e32 v204, v204
	v_add_f32_e32 v210, 1.0, v210
	v_rcp_f32_e32 v210, v210
	v_mul_f32_e32 v211, 0x3f317217, v204
	v_fma_f32 v211, v204, s91, -v211
	v_fmac_f32_e32 v211, 0x3377d1cf, v204
	v_fma_f32 v210, v210, v191, v139
	v_cmp_gt_f32_e32 vcc, s90, v210
	v_fmac_f32_e32 v211, 0x3f317217, v204
	v_cmp_lt_f32_e64 s[8:9], |v204|, s92
	v_cndmask_b32_e64 v212, 0, 32, vcc
	v_ldexp_f32 v210, v210, v212
	v_log_f32_e32 v210, v210
	v_cndmask_b32_e64 v204, v204, v211, s[8:9]
	v_cndmask_b32_e64 v211, 0, v186, s[6:7]
	v_sub_f32_e32 v211, v204, v211
	v_mul_f32_e32 v204, 0x3f317217, v210
	v_mul_f32_e32 v212, 0xbfb8aa3b, v76
	v_fma_f32 v204, v210, s91, -v204
	v_exp_f32_e32 v212, v212
	v_fmac_f32_e32 v204, 0x3377d1cf, v210
	v_fmac_f32_e32 v204, 0x3f317217, v210
	v_cmp_lt_f32_e64 s[6:7], |v210|, s92
	s_nop 1
	v_cndmask_b32_e64 v204, v210, v204, s[6:7]
	v_cndmask_b32_e32 v210, 0, v186, vcc
	v_sub_f32_e32 v210, v204, v210
	v_add_f32_e32 v204, 1.0, v212
	v_rcp_f32_e32 v212, v204
	v_cvt_pk_f16_f32 v204, v203, v205
	v_cvt_pk_f16_f32 v205, v206, v211
	v_cvt_pk_f16_f32 v206, v207, v208
	v_fma_f32 v203, v212, v152, v132
	v_cmp_gt_f32_e32 vcc, s90, v203
	s_nop 1
	v_cndmask_b32_e64 v207, 0, 32, vcc
	v_ldexp_f32 v203, v203, v207
	v_mul_f32_e32 v207, 0xbfb8aa3b, v72
	v_exp_f32_e32 v208, v207
	v_cvt_pk_f16_f32 v207, v209, v210
	global_store_dwordx4 v[172:173], v[204:207], off sc1
	v_log_f32_e32 v203, v203
	s_nop 0
	v_add_f32_e32 v205, 1.0, v208
	v_rcp_f32_e32 v205, v205
	v_mul_f32_e32 v204, 0x3f317217, v203
	v_fma_f32 v204, v203, s91, -v204
	v_fmac_f32_e32 v204, 0x3377d1cf, v203
	v_fma_f32 v205, v205, v192, v128
	v_cmp_gt_f32_e64 s[6:7], s90, v205
	v_fmac_f32_e32 v204, 0x3f317217, v203
	v_cmp_lt_f32_e64 s[8:9], |v203|, s92
	v_cndmask_b32_e64 v206, 0, 32, s[6:7]
	v_ldexp_f32 v205, v205, v206
	v_mul_f32_e32 v206, 0xbfb8aa3b, v77
	v_exp_f32_e32 v206, v206
	v_log_f32_e32 v205, v205
	v_cndmask_b32_e64 v203, v203, v204, s[8:9]
	v_cndmask_b32_e32 v204, 0, v186, vcc
	v_add_f32_e32 v206, 1.0, v206
	v_rcp_f32_e32 v206, v206
	v_sub_f32_e32 v203, v203, v204
	v_mul_f32_e32 v204, 0x3f317217, v205
	v_fma_f32 v204, v205, s91, -v204
	v_fmac_f32_e32 v204, 0x3377d1cf, v205
	v_fmac_f32_e32 v204, 0x3f317217, v205
	v_cmp_lt_f32_e64 vcc, |v205|, s92
	v_fma_f32 v206, v206, v193, v133
	s_nop 0
	v_cndmask_b32_e32 v204, v205, v204, vcc
	v_cmp_gt_f32_e32 vcc, s90, v206
	v_cndmask_b32_e64 v205, 0, v186, s[6:7]
	s_nop 0
	v_cndmask_b32_e64 v207, 0, 32, vcc
	v_ldexp_f32 v206, v206, v207
	v_sub_f32_e32 v207, v204, v205
	v_mul_f32_e32 v204, 0xbfb8aa3b, v73
	v_exp_f32_e32 v204, v204
	v_log_f32_e32 v206, v206
	v_cndmask_b32_e32 v208, 0, v186, vcc
	v_add_f32_e32 v204, 1.0, v204
	v_rcp_f32_e32 v204, v204
	v_mul_f32_e32 v205, 0x3f317217, v206
	v_fma_f32 v205, v206, s91, -v205
	v_fmac_f32_e32 v205, 0x3377d1cf, v206
	v_fmac_f32_e32 v205, 0x3f317217, v206
	v_cmp_lt_f32_e64 s[6:7], |v206|, s92
	v_fma_f32 v204, v204, v195, v129
	s_nop 0
	v_cndmask_b32_e64 v205, v206, v205, s[6:7]
	v_cmp_gt_f32_e64 s[6:7], s90, v204
	v_sub_f32_e32 v205, v205, v208
	s_nop 0
; DI unsigned cvtpk(float lo, float hi) { f32x2 v = {lo, hi}; bf16x2_t b = __builtin_convertvector(v, bf16x2_t); return __builtin_bit_cast(unsigned, b); }
; DI unsigned cvtpk_h(float lo, float hi) { f32x2 v = {lo, hi}; h16x2_t b = __builtin_convertvector(v, h16x2_t); return __builtin_bit_cast(unsigned, b); }
; DI float sigm(float x) { return __builtin_amdgcn_rcpf(1.f + fexp(-x)); }
; DI float silu_(float x) { return x * sigm(x); }
;     template <int MODE> __device__ __forceinline__ void run(const f32x4 (&acc)[2][2][4][2], u16* dst, int ld, int row0, int col0, int trow0, int wc, int fq, const float* lb) const {
;     ...
;                         for (int i = 0; i < 4; ++i) { const float l0 = lb0[bj][i], l1 = lb1[bj][i];
;                             v0[i] = __logf(l0 + (1.f - l0) * sigm(v0[i])); v1[i] = __logf(l1 + (1.f - l1) * sigm(v1[i])); }
;                     }
;                     if (MODE == 4) {
; #pragma unroll
;                         for (int i = 0; i < 4; ++i) { v0[i] = silu_(v0[i]); v1[i] = silu_(v1[i]); }
;                     }
;                     if (MODE == 5) {
; #pragma unroll
;                         for (int i = 0; i < 4; ++i) { v0[i] = sigm(v0[i]); v1[i] = sigm(v1[i]); }
;                     }
;                     u32x4 w;
;                     if (MODE == 3) { w.x = cvtpk_h(v0[0], v0[1]); w.y = cvtpk_h(v0[2], v0[3]); w.z = cvtpk_h(v1[0], v1[1]); w.w = cvtpk_h(v1[2], v1[3]); }
;                     else { w.x = cvtpk(v0[0], v0[1]); w.y = cvtpk(v0[2], v0[3]); w.z = cvtpk(v1[0], v1[1]); w.w = cvtpk(v1[2], v1[3]); }
;                     *(u32x4*)(rowp + bj * HALF) = w;
	v_cndmask_b32_e64 v206, 0, 32, s[6:7]
	v_ldexp_f32 v204, v204, v206
	v_mul_f32_e32 v206, 0xbfb8aa3b, v78
	v_exp_f32_e32 v206, v206
	v_log_f32_e32 v204, v204
	v_add_f32_e32 v206, 1.0, v206
	v_rcp_f32_e32 v206, v206
	v_mul_f32_e32 v208, 0x3f317217, v204
	v_fma_f32 v208, v204, s91, -v208
	v_fmac_f32_e32 v208, 0x3377d1cf, v204
	v_fma_f32 v206, v206, v197, v134
	v_cmp_gt_f32_e32 vcc, s90, v206
	v_fmac_f32_e32 v208, 0x3f317217, v204
	v_cmp_lt_f32_e64 s[8:9], |v204|, s92
	v_cndmask_b32_e64 v209, 0, 32, vcc
	v_ldexp_f32 v206, v206, v209
	v_mul_f32_e32 v209, 0xbfb8aa3b, v74
	v_exp_f32_e32 v209, v209
	v_log_f32_e32 v206, v206
	v_cndmask_b32_e64 v204, v204, v208, s[8:9]
	v_cndmask_b32_e64 v208, 0, v186, s[6:7]
	v_add_f32_e32 v209, 1.0, v209
	v_sub_f32_e32 v208, v204, v208
	v_mul_f32_e32 v204, 0x3f317217, v206
	v_rcp_f32_e32 v209, v209
	v_fma_f32 v204, v206, s91, -v204
	v_fmac_f32_e32 v204, 0x3377d1cf, v206
	v_fmac_f32_e32 v204, 0x3f317217, v206
	v_cmp_lt_f32_e64 s[6:7], |v206|, s92
	v_fma_f32 v209, v209, v196, v130
	s_nop 0
	v_cndmask_b32_e64 v204, v206, v204, s[6:7]
	v_cndmask_b32_e32 v206, 0, v186, vcc
	v_cmp_gt_f32_e32 vcc, s90, v209
	v_sub_f32_e32 v206, v204, v206
	v_mul_f32_e32 v204, 0xbfb8aa3b, v79
	v_cndmask_b32_e64 v210, 0, 32, vcc
	v_exp_f32_e32 v204, v204
	v_ldexp_f32 v209, v209, v210
	v_log_f32_e32 v209, v209
	v_cndmask_b32_e32 v211, 0, v186, vcc
	v_add_f32_e32 v204, 1.0, v204
	v_rcp_f32_e32 v204, v204
	v_mul_f32_e32 v210, 0x3f317217, v209
	v_fma_f32 v210, v209, s91, -v210
	v_fmac_f32_e32 v210, 0x3377d1cf, v209
	v_fmac_f32_e32 v210, 0x3f317217, v209
	v_cmp_lt_f32_e64 s[6:7], |v209|, s92
	v_fma_f32 v204, v204, v198, v135
	s_nop 0
	v_cndmask_b32_e64 v209, v209, v210, s[6:7]
	v_cmp_gt_f32_e64 s[6:7], s90, v204
	v_sub_f32_e32 v209, v209, v211
	s_nop 0
	v_cndmask_b32_e64 v210, 0, 32, s[6:7]
	v_ldexp_f32 v204, v204, v210
	v_mul_f32_e32 v210, 0xbfb8aa3b, v75
	v_exp_f32_e32 v210, v210
	v_log_f32_e32 v204, v204
	v_add_f32_e32 v210, 1.0, v210
	v_rcp_f32_e32 v210, v210
	v_mul_f32_e32 v211, 0x3f317217, v204
	v_fma_f32 v211, v204, s91, -v211
	v_fmac_f32_e32 v211, 0x3377d1cf, v204
	v_fma_f32 v210, v210, v199, v131
	v_cmp_gt_f32_e32 vcc, s90, v210
	v_fmac_f32_e32 v211, 0x3f317217, v204
	v_cmp_lt_f32_e64 s[8:9], |v204|, s92
	v_cndmask_b32_e64 v212, 0, 32, vcc
	v_ldexp_f32 v210, v210, v212
	v_log_f32_e32 v210, v210
	v_cndmask_b32_e64 v204, v204, v211, s[8:9]
	v_cndmask_b32_e64 v211, 0, v186, s[6:7]
	v_sub_f32_e32 v211, v204, v211
	v_mul_f32_e32 v204, 0x3f317217, v210
	v_fma_f32 v204, v210, s91, -v204
	v_fmac_f32_e32 v204, 0x3377d1cf, v210
	v_fmac_f32_e32 v204, 0x3f317217, v210
	v_cmp_lt_f32_e64 s[6:7], |v210|, s92
	s_nop 1
	v_cndmask_b32_e64 v204, v210, v204, s[6:7]
	v_cndmask_b32_e32 v210, 0, v186, vcc
	v_sub_f32_e32 v210, v204, v210
	v_cvt_pk_f16_f32 v204, v203, v205
	v_mul_f32_e32 v203, 0xbfb8aa3b, v84
	v_exp_f32_e32 v203, v203
	v_cvt_pk_f16_f32 v205, v206, v211
	v_cvt_pk_f16_f32 v206, v207, v208
	v_cvt_pk_f16_f32 v207, v209, v210
	v_add_f32_e32 v203, 1.0, v203
	v_rcp_f32_e32 v203, v203
	global_store_dwordx4 v[172:173], v[204:207], off offset:256 sc1
	v_or_b32_e32 v172, 48, v166
	v_ashrrev_i32_e32 v173, 31, v172
	v_fma_f32 v203, v203, v202, v140
	v_cmp_gt_f32_e32 vcc, s90, v203
	v_lshlrev_b64 v[172:173], 11, v[172:173]
	v_lshl_add_u64 v[172:173], v[170:171], 0, v[172:173]
	v_cndmask_b32_e64 v204, 0, 32, vcc
	v_ldexp_f32 v203, v203, v204
	v_mul_f32_e32 v204, 0xbfb8aa3b, v80
	v_exp_f32_e32 v204, v204
	v_log_f32_e32 v203, v203
	v_add_f32_e32 v204, 1.0, v204
	v_rcp_f32_e32 v204, v204
	v_mul_f32_e32 v205, 0x3f317217, v203
	v_fma_f32 v205, v203, s91, -v205
	v_fmac_f32_e32 v205, 0x3377d1cf, v203
	v_fma_f32 v204, v204, v201, v136
	v_cmp_gt_f32_e64 s[6:7], s90, v204
	v_fmac_f32_e32 v205, 0x3f317217, v203
	v_cmp_lt_f32_e64 s[8:9], |v203|, s92
	v_cndmask_b32_e64 v206, 0, 32, s[6:7]
	v_ldexp_f32 v204, v204, v206
	v_mul_f32_e32 v206, 0xbfb8aa3b, v85
	v_exp_f32_e32 v206, v206
	v_log_f32_e32 v204, v204
	v_cndmask_b32_e64 v203, v203, v205, s[8:9]
	v_cndmask_b32_e32 v205, 0, v186, vcc
	v_add_f32_e32 v206, 1.0, v206
	v_rcp_f32_e32 v206, v206
	v_sub_f32_e32 v203, v203, v205
	v_mul_f32_e32 v205, 0x3f317217, v204
	v_fma_f32 v205, v204, s91, -v205
	v_fmac_f32_e32 v205, 0x3377d1cf, v204
	v_fmac_f32_e32 v205, 0x3f317217, v204
	v_cmp_lt_f32_e64 vcc, |v204|, s92
	v_fma_f32 v206, v206, v200, v141
	s_nop 0
	v_cndmask_b32_e32 v204, v204, v205, vcc
	v_cmp_gt_f32_e32 vcc, s90, v206
	v_cndmask_b32_e64 v205, 0, v186, s[6:7]
	s_nop 0
	v_cndmask_b32_e64 v207, 0, 32, vcc
	v_ldexp_f32 v206, v206, v207
	v_sub_f32_e32 v207, v204, v205
	v_mul_f32_e32 v204, 0xbfb8aa3b, v81
	v_exp_f32_e32 v204, v204
	v_log_f32_e32 v206, v206
	v_cndmask_b32_e32 v208, 0, v186, vcc
	v_add_f32_e32 v204, 1.0, v204
	v_rcp_f32_e32 v204, v204
	v_mul_f32_e32 v205, 0x3f317217, v206
	v_fma_f32 v205, v206, s91, -v205
	v_fmac_f32_e32 v205, 0x3377d1cf, v206
	v_fmac_f32_e32 v205, 0x3f317217, v206
	v_cmp_lt_f32_e64 s[6:7], |v206|, s92
	v_fma_f32 v204, v204, v188, v137
	s_nop 0
	v_cndmask_b32_e64 v205, v206, v205, s[6:7]
	v_cmp_gt_f32_e64 s[6:7], s90, v204
	v_sub_f32_e32 v205, v205, v208
	s_nop 0
	v_cndmask_b32_e64 v206, 0, 32, s[6:7]
	v_ldexp_f32 v204, v204, v206
	v_mul_f32_e32 v206, 0xbfb8aa3b, v86
	v_exp_f32_e32 v206, v206
	v_log_f32_e32 v204, v204
	v_add_f32_e32 v206, 1.0, v206
	v_rcp_f32_e32 v206, v206
	v_mul_f32_e32 v208, 0x3f317217, v204
	v_fma_f32 v208, v204, s91, -v208
	v_fmac_f32_e32 v208, 0x3377d1cf, v204
	v_fma_f32 v206, v206, v167, v142
	v_cmp_gt_f32_e32 vcc, s90, v206
	v_fmac_f32_e32 v208, 0x3f317217, v204
	v_cmp_lt_f32_e64 s[8:9], |v204|, s92
	v_cndmask_b32_e64 v209, 0, 32, vcc
	v_ldexp_f32 v206, v206, v209
; DI unsigned cvtpk(float lo, float hi) { f32x2 v = {lo, hi}; bf16x2_t b = __builtin_convertvector(v, bf16x2_t); return __builtin_bit_cast(unsigned, b); }
; DI unsigned cvtpk_h(float lo, float hi) { f32x2 v = {lo, hi}; h16x2_t b = __builtin_convertvector(v, h16x2_t); return __builtin_bit_cast(unsigned, b); }
; DI float sigm(float x) { return __builtin_amdgcn_rcpf(1.f + fexp(-x)); }
; DI float silu_(float x) { return x * sigm(x); }
;     template <int MODE> __device__ __forceinline__ void run(const f32x4 (&acc)[2][2][4][2], u16* dst, int ld, int row0, int col0, int trow0, int wc, int fq, const float* lb) const {
;     ...
;                         for (int i = 0; i < 4; ++i) { const float l0 = lb0[bj][i], l1 = lb1[bj][i];
;                             v0[i] = __logf(l0 + (1.f - l0) * sigm(v0[i])); v1[i] = __logf(l1 + (1.f - l1) * sigm(v1[i])); }
;                     }
;                     if (MODE == 4) {
; #pragma unroll
;                         for (int i = 0; i < 4; ++i) { v0[i] = silu_(v0[i]); v1[i] = silu_(v1[i]); }
;                     }
;                     if (MODE == 5) {
; #pragma unroll
;                         for (int i = 0; i < 4; ++i) { v0[i] = sigm(v0[i]); v1[i] = sigm(v1[i]); }
;                     }
;                     u32x4 w;
;                     if (MODE == 3) { w.x = cvtpk_h(v0[0], v0[1]); w.y = cvtpk_h(v0[2], v0[3]); w.z = cvtpk_h(v1[0], v1[1]); w.w = cvtpk_h(v1[2], v1[3]); }
;                     else { w.x = cvtpk(v0[0], v0[1]); w.y = cvtpk(v0[2], v0[3]); w.z = cvtpk(v1[0], v1[1]); w.w = cvtpk(v1[2], v1[3]); }
;                     *(u32x4*)(rowp + bj * HALF) = w;
	v_mul_f32_e32 v209, 0xbfb8aa3b, v82
	v_exp_f32_e32 v209, v209
	v_log_f32_e32 v206, v206
	v_cndmask_b32_e64 v204, v204, v208, s[8:9]
	v_cndmask_b32_e64 v208, 0, v186, s[6:7]
	v_add_f32_e32 v209, 1.0, v209
	v_sub_f32_e32 v208, v204, v208
	v_mul_f32_e32 v204, 0x3f317217, v206
	v_rcp_f32_e32 v209, v209
	v_fma_f32 v204, v206, s91, -v204
	v_fmac_f32_e32 v204, 0x3377d1cf, v206
	v_fmac_f32_e32 v204, 0x3f317217, v206
	v_cmp_lt_f32_e64 s[6:7], |v206|, s92
	v_fma_f32 v209, v209, v189, v138
	s_nop 0
	v_cndmask_b32_e64 v204, v206, v204, s[6:7]
	v_cndmask_b32_e32 v206, 0, v186, vcc
	v_cmp_gt_f32_e32 vcc, s90, v209
	v_sub_f32_e32 v206, v204, v206
	v_mul_f32_e32 v204, 0xbfb8aa3b, v87
	v_cndmask_b32_e64 v210, 0, 32, vcc
	v_exp_f32_e32 v204, v204
	v_ldexp_f32 v209, v209, v210
	v_log_f32_e32 v209, v209
	v_cndmask_b32_e32 v211, 0, v186, vcc
	v_add_f32_e32 v204, 1.0, v204
	v_rcp_f32_e32 v204, v204
	v_mul_f32_e32 v210, 0x3f317217, v209
	v_fma_f32 v210, v209, s91, -v210
	v_fmac_f32_e32 v210, 0x3377d1cf, v209
	v_fmac_f32_e32 v210, 0x3f317217, v209
	v_cmp_lt_f32_e64 s[6:7], |v209|, s92
	v_fma_f32 v204, v204, v190, v143
	s_nop 0
	v_cndmask_b32_e64 v209, v209, v210, s[6:7]
	v_cmp_gt_f32_e64 s[6:7], s90, v204
	v_sub_f32_e32 v209, v209, v211
	s_nop 0
	v_cndmask_b32_e64 v210, 0, 32, s[6:7]
	v_ldexp_f32 v204, v204, v210
	v_mul_f32_e32 v210, 0xbfb8aa3b, v83
	v_exp_f32_e32 v210, v210
	v_log_f32_e32 v204, v204
	v_add_f32_e32 v210, 1.0, v210
	v_rcp_f32_e32 v210, v210
	v_mul_f32_e32 v211, 0x3f317217, v204
	v_fma_f32 v211, v204, s91, -v211
	v_fmac_f32_e32 v211, 0x3377d1cf, v204
	v_fma_f32 v210, v210, v191, v139
	v_cmp_gt_f32_e32 vcc, s90, v210
	v_fmac_f32_e32 v211, 0x3f317217, v204
	v_cmp_lt_f32_e64 s[8:9], |v204|, s92
	v_cndmask_b32_e64 v212, 0, 32, vcc
	v_ldexp_f32 v210, v210, v212
	v_log_f32_e32 v210, v210
	v_cndmask_b32_e64 v204, v204, v211, s[8:9]
	v_cndmask_b32_e64 v211, 0, v186, s[6:7]
	v_sub_f32_e32 v211, v204, v211
	v_mul_f32_e32 v204, 0x3f317217, v210
	v_mul_f32_e32 v212, 0xbfb8aa3b, v68
	v_fma_f32 v204, v210, s91, -v204
	v_exp_f32_e32 v212, v212
	v_fmac_f32_e32 v204, 0x3377d1cf, v210
	v_fmac_f32_e32 v204, 0x3f317217, v210
	v_cmp_lt_f32_e64 s[6:7], |v210|, s92
	s_nop 1
	v_cndmask_b32_e64 v204, v210, v204, s[6:7]
	v_cndmask_b32_e32 v210, 0, v186, vcc
	v_sub_f32_e32 v210, v204, v210
	v_add_f32_e32 v204, 1.0, v212
	v_rcp_f32_e32 v212, v204
	v_cvt_pk_f16_f32 v204, v203, v205
	v_cvt_pk_f16_f32 v205, v206, v211
	v_cvt_pk_f16_f32 v206, v207, v208
	v_fma_f32 v203, v212, v152, v132
	v_cmp_gt_f32_e32 vcc, s90, v203
	s_nop 1
	v_cndmask_b32_e64 v207, 0, 32, vcc
	v_ldexp_f32 v203, v203, v207
	v_mul_f32_e32 v207, 0xbfb8aa3b, v64
	v_exp_f32_e32 v208, v207
	v_cvt_pk_f16_f32 v207, v209, v210
	global_store_dwordx4 v[172:173], v[204:207], off sc1
	v_log_f32_e32 v203, v203
	s_nop 0
	v_add_f32_e32 v205, 1.0, v208
	v_rcp_f32_e32 v205, v205
	v_mul_f32_e32 v204, 0x3f317217, v203
	v_fma_f32 v204, v203, s91, -v204
	v_fmac_f32_e32 v204, 0x3377d1cf, v203
	v_fma_f32 v205, v205, v192, v128
	v_cmp_gt_f32_e64 s[6:7], s90, v205
	v_fmac_f32_e32 v204, 0x3f317217, v203
	v_cmp_lt_f32_e64 s[8:9], |v203|, s92
	v_cndmask_b32_e64 v206, 0, 32, s[6:7]
	v_ldexp_f32 v205, v205, v206
	v_mul_f32_e32 v206, 0xbfb8aa3b, v69
	v_exp_f32_e32 v206, v206
	v_log_f32_e32 v205, v205
	v_cndmask_b32_e64 v203, v203, v204, s[8:9]
	v_cndmask_b32_e32 v204, 0, v186, vcc
	v_add_f32_e32 v206, 1.0, v206
	v_rcp_f32_e32 v206, v206
	v_sub_f32_e32 v203, v203, v204
	v_mul_f32_e32 v204, 0x3f317217, v205
	v_fma_f32 v204, v205, s91, -v204
	v_fmac_f32_e32 v204, 0x3377d1cf, v205
	v_fmac_f32_e32 v204, 0x3f317217, v205
	v_cmp_lt_f32_e64 vcc, |v205|, s92
	v_fma_f32 v206, v206, v193, v133
	s_nop 0
	v_cndmask_b32_e32 v204, v205, v204, vcc
	v_cmp_gt_f32_e32 vcc, s90, v206
	v_cndmask_b32_e64 v205, 0, v186, s[6:7]
	s_nop 0
	v_cndmask_b32_e64 v207, 0, 32, vcc
	v_ldexp_f32 v206, v206, v207
	v_sub_f32_e32 v207, v204, v205
	v_mul_f32_e32 v204, 0xbfb8aa3b, v65
	v_exp_f32_e32 v204, v204
	v_log_f32_e32 v206, v206
	v_cndmask_b32_e32 v208, 0, v186, vcc
	v_add_f32_e32 v204, 1.0, v204
	v_rcp_f32_e32 v204, v204
	v_mul_f32_e32 v205, 0x3f317217, v206
	v_fma_f32 v205, v206, s91, -v205
	v_fmac_f32_e32 v205, 0x3377d1cf, v206
	v_fmac_f32_e32 v205, 0x3f317217, v206
	v_cmp_lt_f32_e64 s[6:7], |v206|, s92
	v_fma_f32 v204, v204, v195, v129
	s_nop 0
	v_cndmask_b32_e64 v205, v206, v205, s[6:7]
	v_cmp_gt_f32_e64 s[6:7], s90, v204
	v_sub_f32_e32 v205, v205, v208
	s_nop 0
	v_cndmask_b32_e64 v206, 0, 32, s[6:7]
	v_ldexp_f32 v204, v204, v206
	v_mul_f32_e32 v206, 0xbfb8aa3b, v70
	v_exp_f32_e32 v206, v206
	v_log_f32_e32 v204, v204
	v_add_f32_e32 v206, 1.0, v206
	v_rcp_f32_e32 v206, v206
	v_mul_f32_e32 v208, 0x3f317217, v204
	v_fma_f32 v208, v204, s91, -v208
	v_fmac_f32_e32 v208, 0x3377d1cf, v204
	v_fma_f32 v206, v206, v197, v134
	v_cmp_gt_f32_e32 vcc, s90, v206
	v_fmac_f32_e32 v208, 0x3f317217, v204
	v_cmp_lt_f32_e64 s[8:9], |v204|, s92
	v_cndmask_b32_e64 v209, 0, 32, vcc
	v_ldexp_f32 v206, v206, v209
	v_mul_f32_e32 v209, 0xbfb8aa3b, v66
	v_exp_f32_e32 v209, v209
	v_log_f32_e32 v206, v206
	v_cndmask_b32_e64 v204, v204, v208, s[8:9]
	v_cndmask_b32_e64 v208, 0, v186, s[6:7]
	v_add_f32_e32 v209, 1.0, v209
	v_sub_f32_e32 v208, v204, v208
	v_mul_f32_e32 v204, 0x3f317217, v206
	v_rcp_f32_e32 v209, v209
	v_fma_f32 v204, v206, s91, -v204
	v_fmac_f32_e32 v204, 0x3377d1cf, v206
	v_fmac_f32_e32 v204, 0x3f317217, v206
	v_cmp_lt_f32_e64 s[6:7], |v206|, s92
	v_fma_f32 v209, v209, v196, v130
	s_nop 0
	v_cndmask_b32_e64 v204, v206, v204, s[6:7]
	v_cndmask_b32_e32 v206, 0, v186, vcc
	v_cmp_gt_f32_e32 vcc, s90, v209
	v_sub_f32_e32 v206, v204, v206
	v_mul_f32_e32 v204, 0xbfb8aa3b, v71
; DI unsigned cvtpk(float lo, float hi) { f32x2 v = {lo, hi}; bf16x2_t b = __builtin_convertvector(v, bf16x2_t); return __builtin_bit_cast(unsigned, b); }
; DI unsigned cvtpk_h(float lo, float hi) { f32x2 v = {lo, hi}; h16x2_t b = __builtin_convertvector(v, h16x2_t); return __builtin_bit_cast(unsigned, b); }
; DI float sigm(float x) { return __builtin_amdgcn_rcpf(1.f + fexp(-x)); }
; DI float silu_(float x) { return x * sigm(x); }
;     template <int MODE> __device__ __forceinline__ void run(const f32x4 (&acc)[2][2][4][2], u16* dst, int ld, int row0, int col0, int trow0, int wc, int fq, const float* lb) const {
;     ...
;                         for (int i = 0; i < 4; ++i) { const float l0 = lb0[bj][i], l1 = lb1[bj][i];
;                             v0[i] = __logf(l0 + (1.f - l0) * sigm(v0[i])); v1[i] = __logf(l1 + (1.f - l1) * sigm(v1[i])); }
;                     }
;                     if (MODE == 4) {
; #pragma unroll
;                         for (int i = 0; i < 4; ++i) { v0[i] = silu_(v0[i]); v1[i] = silu_(v1[i]); }
;                     }
;                     if (MODE == 5) {
; #pragma unroll
;                         for (int i = 0; i < 4; ++i) { v0[i] = sigm(v0[i]); v1[i] = sigm(v1[i]); }
;                     }
;                     u32x4 w;
;                     if (MODE == 3) { w.x = cvtpk_h(v0[0], v0[1]); w.y = cvtpk_h(v0[2], v0[3]); w.z = cvtpk_h(v1[0], v1[1]); w.w = cvtpk_h(v1[2], v1[3]); }
;                     else { w.x = cvtpk(v0[0], v0[1]); w.y = cvtpk(v0[2], v0[3]); w.z = cvtpk(v1[0], v1[1]); w.w = cvtpk(v1[2], v1[3]); }
;                     *(u32x4*)(rowp + bj * HALF) = w;
	v_cndmask_b32_e64 v210, 0, 32, vcc
	v_exp_f32_e32 v204, v204
	v_ldexp_f32 v209, v209, v210
	v_log_f32_e32 v209, v209
	v_cndmask_b32_e32 v211, 0, v186, vcc
	v_add_f32_e32 v204, 1.0, v204
	v_rcp_f32_e32 v204, v204
	v_mul_f32_e32 v210, 0x3f317217, v209
	v_fma_f32 v210, v209, s91, -v210
	v_fmac_f32_e32 v210, 0x3377d1cf, v209
	v_fmac_f32_e32 v210, 0x3f317217, v209
	v_cmp_lt_f32_e64 s[6:7], |v209|, s92
	v_fma_f32 v204, v204, v198, v135
	s_nop 0
	v_cndmask_b32_e64 v209, v209, v210, s[6:7]
	v_cmp_gt_f32_e64 s[6:7], s90, v204
	v_sub_f32_e32 v209, v209, v211
	s_nop 0
	v_cndmask_b32_e64 v210, 0, 32, s[6:7]
	v_ldexp_f32 v204, v204, v210
	v_mul_f32_e32 v210, 0xbfb8aa3b, v67
	v_exp_f32_e32 v210, v210
	v_log_f32_e32 v204, v204
	v_add_f32_e32 v210, 1.0, v210
	v_rcp_f32_e32 v210, v210
	v_mul_f32_e32 v211, 0x3f317217, v204
	v_fma_f32 v211, v204, s91, -v211
	v_fmac_f32_e32 v211, 0x3377d1cf, v204
	v_fma_f32 v210, v210, v199, v131
	v_cmp_gt_f32_e32 vcc, s90, v210
	v_fmac_f32_e32 v211, 0x3f317217, v204
	v_cmp_lt_f32_e64 s[8:9], |v204|, s92
	v_cndmask_b32_e64 v212, 0, 32, vcc
	v_ldexp_f32 v210, v210, v212
	v_log_f32_e32 v210, v210
	v_cndmask_b32_e64 v204, v204, v211, s[8:9]
	v_cndmask_b32_e64 v211, 0, v186, s[6:7]
	v_sub_f32_e32 v211, v204, v211
	v_mul_f32_e32 v204, 0x3f317217, v210
	v_fma_f32 v204, v210, s91, -v204
	v_fmac_f32_e32 v204, 0x3377d1cf, v210
	v_fmac_f32_e32 v204, 0x3f317217, v210
	v_cmp_lt_f32_e64 s[6:7], |v210|, s92
	s_nop 1
	v_cndmask_b32_e64 v204, v210, v204, s[6:7]
	v_cndmask_b32_e32 v210, 0, v186, vcc
	v_sub_f32_e32 v210, v204, v210
	v_cvt_pk_f16_f32 v204, v203, v205
	v_mul_f32_e32 v203, 0xbfb8aa3b, v60
	v_exp_f32_e32 v203, v203
	v_cvt_pk_f16_f32 v205, v206, v211
	v_cvt_pk_f16_f32 v206, v207, v208
	v_cvt_pk_f16_f32 v207, v209, v210
	v_add_f32_e32 v203, 1.0, v203
	v_rcp_f32_e32 v203, v203
	global_store_dwordx4 v[172:173], v[204:207], off offset:256 sc1
	v_add_u32_e32 v172, 0x80, v166
	v_ashrrev_i32_e32 v173, 31, v172
	v_fma_f32 v203, v203, v202, v140
	v_cmp_gt_f32_e32 vcc, s90, v203
	v_lshlrev_b64 v[172:173], 11, v[172:173]
	v_lshl_add_u64 v[172:173], v[170:171], 0, v[172:173]
	v_cndmask_b32_e64 v204, 0, 32, vcc
	v_ldexp_f32 v203, v203, v204
	v_mul_f32_e32 v204, 0xbfb8aa3b, v56
	v_exp_f32_e32 v204, v204
	v_log_f32_e32 v203, v203
	v_add_f32_e32 v204, 1.0, v204
	v_rcp_f32_e32 v204, v204
	v_mul_f32_e32 v205, 0x3f317217, v203
	v_fma_f32 v205, v203, s91, -v205
	v_fmac_f32_e32 v205, 0x3377d1cf, v203
	v_fma_f32 v204, v204, v201, v136
	v_cmp_gt_f32_e64 s[6:7], s90, v204
	v_fmac_f32_e32 v205, 0x3f317217, v203
	v_cmp_lt_f32_e64 s[8:9], |v203|, s92
	v_cndmask_b32_e64 v206, 0, 32, s[6:7]
	v_ldexp_f32 v204, v204, v206
	v_mul_f32_e32 v206, 0xbfb8aa3b, v61
	v_exp_f32_e32 v206, v206
	v_log_f32_e32 v204, v204
	v_cndmask_b32_e64 v203, v203, v205, s[8:9]
	v_cndmask_b32_e32 v205, 0, v186, vcc
	v_add_f32_e32 v206, 1.0, v206
	v_rcp_f32_e32 v206, v206
	v_sub_f32_e32 v203, v203, v205
	v_mul_f32_e32 v205, 0x3f317217, v204
	v_fma_f32 v205, v204, s91, -v205
	v_fmac_f32_e32 v205, 0x3377d1cf, v204
	v_fmac_f32_e32 v205, 0x3f317217, v204
	v_cmp_lt_f32_e64 vcc, |v204|, s92
	v_fma_f32 v206, v206, v200, v141
	s_nop 0
	v_cndmask_b32_e32 v204, v204, v205, vcc
	v_cmp_gt_f32_e32 vcc, s90, v206
	v_cndmask_b32_e64 v205, 0, v186, s[6:7]
	s_nop 0
	v_cndmask_b32_e64 v207, 0, 32, vcc
	v_ldexp_f32 v206, v206, v207
	v_sub_f32_e32 v207, v204, v205
	v_mul_f32_e32 v204, 0xbfb8aa3b, v57
	v_exp_f32_e32 v204, v204
	v_log_f32_e32 v206, v206
	v_cndmask_b32_e32 v208, 0, v186, vcc
	v_add_f32_e32 v204, 1.0, v204
	v_rcp_f32_e32 v204, v204
	v_mul_f32_e32 v205, 0x3f317217, v206
	v_fma_f32 v205, v206, s91, -v205
	v_fmac_f32_e32 v205, 0x3377d1cf, v206
	v_fmac_f32_e32 v205, 0x3f317217, v206
	v_cmp_lt_f32_e64 s[6:7], |v206|, s92
	v_fma_f32 v204, v204, v188, v137
	s_nop 0
	v_cndmask_b32_e64 v205, v206, v205, s[6:7]
	v_cmp_gt_f32_e64 s[6:7], s90, v204
	v_sub_f32_e32 v205, v205, v208
	s_nop 0
	v_cndmask_b32_e64 v206, 0, 32, s[6:7]
	v_ldexp_f32 v204, v204, v206
	v_mul_f32_e32 v206, 0xbfb8aa3b, v62
	v_exp_f32_e32 v206, v206
	v_log_f32_e32 v204, v204
	v_add_f32_e32 v206, 1.0, v206
	v_rcp_f32_e32 v206, v206
	v_mul_f32_e32 v208, 0x3f317217, v204
	v_fma_f32 v208, v204, s91, -v208
	v_fmac_f32_e32 v208, 0x3377d1cf, v204
	v_fma_f32 v206, v206, v167, v142
	v_cmp_gt_f32_e32 vcc, s90, v206
	v_fmac_f32_e32 v208, 0x3f317217, v204
	v_cmp_lt_f32_e64 s[8:9], |v204|, s92
	v_cndmask_b32_e64 v209, 0, 32, vcc
	v_ldexp_f32 v206, v206, v209
	v_mul_f32_e32 v209, 0xbfb8aa3b, v58
	v_exp_f32_e32 v209, v209
	v_log_f32_e32 v206, v206
	v_cndmask_b32_e64 v204, v204, v208, s[8:9]
	v_cndmask_b32_e64 v208, 0, v186, s[6:7]
	v_add_f32_e32 v209, 1.0, v209
	v_sub_f32_e32 v208, v204, v208
	v_mul_f32_e32 v204, 0x3f317217, v206
	v_rcp_f32_e32 v209, v209
	v_fma_f32 v204, v206, s91, -v204
	v_fmac_f32_e32 v204, 0x3377d1cf, v206
	v_fmac_f32_e32 v204, 0x3f317217, v206
	v_cmp_lt_f32_e64 s[6:7], |v206|, s92
	v_fma_f32 v209, v209, v189, v138
	s_nop 0
	v_cndmask_b32_e64 v204, v206, v204, s[6:7]
	v_cndmask_b32_e32 v206, 0, v186, vcc
	v_cmp_gt_f32_e32 vcc, s90, v209
	v_sub_f32_e32 v206, v204, v206
	v_mul_f32_e32 v204, 0xbfb8aa3b, v63
	v_cndmask_b32_e64 v210, 0, 32, vcc
	v_exp_f32_e32 v204, v204
	v_ldexp_f32 v209, v209, v210
	v_log_f32_e32 v209, v209
	v_cndmask_b32_e32 v211, 0, v186, vcc
	v_add_f32_e32 v204, 1.0, v204
	v_rcp_f32_e32 v204, v204
	v_mul_f32_e32 v210, 0x3f317217, v209
	v_fma_f32 v210, v209, s91, -v210
	v_fmac_f32_e32 v210, 0x3377d1cf, v209
	v_fmac_f32_e32 v210, 0x3f317217, v209
	v_cmp_lt_f32_e64 s[6:7], |v209|, s92
	v_fma_f32 v204, v204, v190, v143
	s_nop 0
	v_cndmask_b32_e64 v209, v209, v210, s[6:7]
	v_cmp_gt_f32_e64 s[6:7], s90, v204
; DI unsigned cvtpk(float lo, float hi) { f32x2 v = {lo, hi}; bf16x2_t b = __builtin_convertvector(v, bf16x2_t); return __builtin_bit_cast(unsigned, b); }
; DI unsigned cvtpk_h(float lo, float hi) { f32x2 v = {lo, hi}; h16x2_t b = __builtin_convertvector(v, h16x2_t); return __builtin_bit_cast(unsigned, b); }
; DI float sigm(float x) { return __builtin_amdgcn_rcpf(1.f + fexp(-x)); }
; DI float silu_(float x) { return x * sigm(x); }
;     template <int MODE> __device__ __forceinline__ void run(const f32x4 (&acc)[2][2][4][2], u16* dst, int ld, int row0, int col0, int trow0, int wc, int fq, const float* lb) const {
;     ...
;                         for (int i = 0; i < 4; ++i) { const float l0 = lb0[bj][i], l1 = lb1[bj][i];
;                             v0[i] = __logf(l0 + (1.f - l0) * sigm(v0[i])); v1[i] = __logf(l1 + (1.f - l1) * sigm(v1[i])); }
;                     }
;                     if (MODE == 4) {
; #pragma unroll
;                         for (int i = 0; i < 4; ++i) { v0[i] = silu_(v0[i]); v1[i] = silu_(v1[i]); }
;                     }
;                     if (MODE == 5) {
; #pragma unroll
;                         for (int i = 0; i < 4; ++i) { v0[i] = sigm(v0[i]); v1[i] = sigm(v1[i]); }
;                     }
;                     u32x4 w;
;                     if (MODE == 3) { w.x = cvtpk_h(v0[0], v0[1]); w.y = cvtpk_h(v0[2], v0[3]); w.z = cvtpk_h(v1[0], v1[1]); w.w = cvtpk_h(v1[2], v1[3]); }
;                     else { w.x = cvtpk(v0[0], v0[1]); w.y = cvtpk(v0[2], v0[3]); w.z = cvtpk(v1[0], v1[1]); w.w = cvtpk(v1[2], v1[3]); }
;                     *(u32x4*)(rowp + bj * HALF) = w;
	v_sub_f32_e32 v209, v209, v211
	s_nop 0
	v_cndmask_b32_e64 v210, 0, 32, s[6:7]
	v_ldexp_f32 v204, v204, v210
	v_mul_f32_e32 v210, 0xbfb8aa3b, v59
	v_exp_f32_e32 v210, v210
	v_log_f32_e32 v204, v204
	v_add_f32_e32 v210, 1.0, v210
	v_rcp_f32_e32 v210, v210
	v_mul_f32_e32 v211, 0x3f317217, v204
	v_fma_f32 v211, v204, s91, -v211
	v_fmac_f32_e32 v211, 0x3377d1cf, v204
	v_fma_f32 v210, v210, v191, v139
	v_cmp_gt_f32_e32 vcc, s90, v210
	v_fmac_f32_e32 v211, 0x3f317217, v204
	v_cmp_lt_f32_e64 s[8:9], |v204|, s92
	v_cndmask_b32_e64 v212, 0, 32, vcc
	v_ldexp_f32 v210, v210, v212
	v_log_f32_e32 v210, v210
	v_cndmask_b32_e64 v204, v204, v211, s[8:9]
	v_cndmask_b32_e64 v211, 0, v186, s[6:7]
	v_sub_f32_e32 v211, v204, v211
	v_mul_f32_e32 v204, 0x3f317217, v210
	v_mul_f32_e32 v212, 0xbfb8aa3b, v44
	v_fma_f32 v204, v210, s91, -v204
	v_exp_f32_e32 v212, v212
	v_fmac_f32_e32 v204, 0x3377d1cf, v210
	v_fmac_f32_e32 v204, 0x3f317217, v210
	v_cmp_lt_f32_e64 s[6:7], |v210|, s92
	s_nop 1
	v_cndmask_b32_e64 v204, v210, v204, s[6:7]
	v_cndmask_b32_e32 v210, 0, v186, vcc
	v_sub_f32_e32 v210, v204, v210
	v_add_f32_e32 v204, 1.0, v212
	v_rcp_f32_e32 v212, v204
	v_cvt_pk_f16_f32 v204, v203, v205
	v_cvt_pk_f16_f32 v205, v206, v211
	v_cvt_pk_f16_f32 v206, v207, v208
	v_fma_f32 v203, v212, v152, v132
	v_cmp_gt_f32_e32 vcc, s90, v203
	s_nop 1
	v_cndmask_b32_e64 v207, 0, 32, vcc
	v_ldexp_f32 v203, v203, v207
	v_mul_f32_e32 v207, 0xbfb8aa3b, v40
	v_exp_f32_e32 v208, v207
	v_cvt_pk_f16_f32 v207, v209, v210
	global_store_dwordx4 v[172:173], v[204:207], off sc1
	v_log_f32_e32 v203, v203
	s_nop 0
	v_add_f32_e32 v205, 1.0, v208
	v_rcp_f32_e32 v205, v205
	v_mul_f32_e32 v204, 0x3f317217, v203
	v_fma_f32 v204, v203, s91, -v204
	v_fmac_f32_e32 v204, 0x3377d1cf, v203
	v_fma_f32 v205, v205, v192, v128
	v_cmp_gt_f32_e64 s[6:7], s90, v205
	v_fmac_f32_e32 v204, 0x3f317217, v203
	v_cmp_lt_f32_e64 s[8:9], |v203|, s92
	v_cndmask_b32_e64 v206, 0, 32, s[6:7]
	v_ldexp_f32 v205, v205, v206
	v_mul_f32_e32 v206, 0xbfb8aa3b, v45
	v_exp_f32_e32 v206, v206
	v_log_f32_e32 v205, v205
	v_cndmask_b32_e64 v203, v203, v204, s[8:9]
	v_cndmask_b32_e32 v204, 0, v186, vcc
	v_add_f32_e32 v206, 1.0, v206
	v_rcp_f32_e32 v206, v206
	v_sub_f32_e32 v203, v203, v204
	v_mul_f32_e32 v204, 0x3f317217, v205
	v_fma_f32 v204, v205, s91, -v204
	v_fmac_f32_e32 v204, 0x3377d1cf, v205
	v_fmac_f32_e32 v204, 0x3f317217, v205
	v_cmp_lt_f32_e64 vcc, |v205|, s92
	v_fma_f32 v206, v206, v193, v133
	s_nop 0
	v_cndmask_b32_e32 v204, v205, v204, vcc
	v_cmp_gt_f32_e32 vcc, s90, v206
	v_cndmask_b32_e64 v205, 0, v186, s[6:7]
	s_nop 0
	v_cndmask_b32_e64 v207, 0, 32, vcc
	v_ldexp_f32 v206, v206, v207
	v_sub_f32_e32 v207, v204, v205
	v_mul_f32_e32 v204, 0xbfb8aa3b, v41
	v_exp_f32_e32 v204, v204
	v_log_f32_e32 v206, v206
	v_cndmask_b32_e32 v208, 0, v186, vcc
	v_add_f32_e32 v204, 1.0, v204
	v_rcp_f32_e32 v204, v204
	v_mul_f32_e32 v205, 0x3f317217, v206
	v_fma_f32 v205, v206, s91, -v205
	v_fmac_f32_e32 v205, 0x3377d1cf, v206
	v_fmac_f32_e32 v205, 0x3f317217, v206
	v_cmp_lt_f32_e64 s[6:7], |v206|, s92
	v_fma_f32 v204, v204, v195, v129
	s_nop 0
	v_cndmask_b32_e64 v205, v206, v205, s[6:7]
	v_cmp_gt_f32_e64 s[6:7], s90, v204
	v_sub_f32_e32 v205, v205, v208
	s_nop 0
	v_cndmask_b32_e64 v206, 0, 32, s[6:7]
	v_ldexp_f32 v204, v204, v206
	v_mul_f32_e32 v206, 0xbfb8aa3b, v46
	v_exp_f32_e32 v206, v206
	v_log_f32_e32 v204, v204
	v_add_f32_e32 v206, 1.0, v206
	v_rcp_f32_e32 v206, v206
	v_mul_f32_e32 v208, 0x3f317217, v204
	v_fma_f32 v208, v204, s91, -v208
	v_fmac_f32_e32 v208, 0x3377d1cf, v204
	v_fma_f32 v206, v206, v197, v134
	v_cmp_gt_f32_e32 vcc, s90, v206
	v_fmac_f32_e32 v208, 0x3f317217, v204
	v_cmp_lt_f32_e64 s[8:9], |v204|, s92
	v_cndmask_b32_e64 v209, 0, 32, vcc
	v_ldexp_f32 v206, v206, v209
	v_mul_f32_e32 v209, 0xbfb8aa3b, v42
	v_exp_f32_e32 v209, v209
	v_log_f32_e32 v206, v206
	v_cndmask_b32_e64 v204, v204, v208, s[8:9]
	v_cndmask_b32_e64 v208, 0, v186, s[6:7]
	v_add_f32_e32 v209, 1.0, v209
	v_sub_f32_e32 v208, v204, v208
	v_mul_f32_e32 v204, 0x3f317217, v206
	v_rcp_f32_e32 v209, v209
	v_fma_f32 v204, v206, s91, -v204
	v_fmac_f32_e32 v204, 0x3377d1cf, v206
	v_fmac_f32_e32 v204, 0x3f317217, v206
	v_cmp_lt_f32_e64 s[6:7], |v206|, s92
	v_fma_f32 v209, v209, v196, v130
	s_nop 0
	v_cndmask_b32_e64 v204, v206, v204, s[6:7]
	v_cndmask_b32_e32 v206, 0, v186, vcc
	v_cmp_gt_f32_e32 vcc, s90, v209
	v_sub_f32_e32 v206, v204, v206
	v_mul_f32_e32 v204, 0xbfb8aa3b, v47
	v_cndmask_b32_e64 v210, 0, 32, vcc
	v_exp_f32_e32 v204, v204
	v_ldexp_f32 v209, v209, v210
	v_log_f32_e32 v209, v209
	v_cndmask_b32_e32 v211, 0, v186, vcc
	v_add_f32_e32 v204, 1.0, v204
	v_rcp_f32_e32 v204, v204
	v_mul_f32_e32 v210, 0x3f317217, v209
	v_fma_f32 v210, v209, s91, -v210
	v_fmac_f32_e32 v210, 0x3377d1cf, v209
	v_fmac_f32_e32 v210, 0x3f317217, v209
	v_cmp_lt_f32_e64 s[6:7], |v209|, s92
	v_fma_f32 v204, v204, v198, v135
	s_nop 0
	v_cndmask_b32_e64 v209, v209, v210, s[6:7]
	v_cmp_gt_f32_e64 s[6:7], s90, v204
	v_sub_f32_e32 v209, v209, v211
	s_nop 0
	v_cndmask_b32_e64 v210, 0, 32, s[6:7]
	v_ldexp_f32 v204, v204, v210
	v_mul_f32_e32 v210, 0xbfb8aa3b, v43
	v_exp_f32_e32 v210, v210
	v_log_f32_e32 v204, v204
	v_add_f32_e32 v210, 1.0, v210
	v_rcp_f32_e32 v210, v210
	v_mul_f32_e32 v211, 0x3f317217, v204
	v_fma_f32 v211, v204, s91, -v211
	v_fmac_f32_e32 v211, 0x3377d1cf, v204
	v_fma_f32 v210, v210, v199, v131
	v_cmp_gt_f32_e32 vcc, s90, v210
	v_fmac_f32_e32 v211, 0x3f317217, v204
	v_cmp_lt_f32_e64 s[8:9], |v204|, s92
	v_cndmask_b32_e64 v212, 0, 32, vcc
	v_ldexp_f32 v210, v210, v212
	v_log_f32_e32 v210, v210
	v_cndmask_b32_e64 v204, v204, v211, s[8:9]
	v_cndmask_b32_e64 v211, 0, v186, s[6:7]
; DI unsigned cvtpk(float lo, float hi) { f32x2 v = {lo, hi}; bf16x2_t b = __builtin_convertvector(v, bf16x2_t); return __builtin_bit_cast(unsigned, b); }
; DI unsigned cvtpk_h(float lo, float hi) { f32x2 v = {lo, hi}; h16x2_t b = __builtin_convertvector(v, h16x2_t); return __builtin_bit_cast(unsigned, b); }
; DI float sigm(float x) { return __builtin_amdgcn_rcpf(1.f + fexp(-x)); }
; DI float silu_(float x) { return x * sigm(x); }
;     template <int MODE> __device__ __forceinline__ void run(const f32x4 (&acc)[2][2][4][2], u16* dst, int ld, int row0, int col0, int trow0, int wc, int fq, const float* lb) const {
;     ...
;                         for (int i = 0; i < 4; ++i) { const float l0 = lb0[bj][i], l1 = lb1[bj][i];
;                             v0[i] = __logf(l0 + (1.f - l0) * sigm(v0[i])); v1[i] = __logf(l1 + (1.f - l1) * sigm(v1[i])); }
;                     }
;                     if (MODE == 4) {
; #pragma unroll
;                         for (int i = 0; i < 4; ++i) { v0[i] = silu_(v0[i]); v1[i] = silu_(v1[i]); }
;                     }
;                     if (MODE == 5) {
; #pragma unroll
;                         for (int i = 0; i < 4; ++i) { v0[i] = sigm(v0[i]); v1[i] = sigm(v1[i]); }
;                     }
;                     u32x4 w;
;                     if (MODE == 3) { w.x = cvtpk_h(v0[0], v0[1]); w.y = cvtpk_h(v0[2], v0[3]); w.z = cvtpk_h(v1[0], v1[1]); w.w = cvtpk_h(v1[2], v1[3]); }
;                     else { w.x = cvtpk(v0[0], v0[1]); w.y = cvtpk(v0[2], v0[3]); w.z = cvtpk(v1[0], v1[1]); w.w = cvtpk(v1[2], v1[3]); }
;                     *(u32x4*)(rowp + bj * HALF) = w;
	v_sub_f32_e32 v211, v204, v211
	v_mul_f32_e32 v204, 0x3f317217, v210
	v_fma_f32 v204, v210, s91, -v204
	v_fmac_f32_e32 v204, 0x3377d1cf, v210
	v_fmac_f32_e32 v204, 0x3f317217, v210
	v_cmp_lt_f32_e64 s[6:7], |v210|, s92
	s_nop 1
	v_cndmask_b32_e64 v204, v210, v204, s[6:7]
	v_cndmask_b32_e32 v210, 0, v186, vcc
	v_sub_f32_e32 v210, v204, v210
	v_cvt_pk_f16_f32 v204, v203, v205
	v_mul_f32_e32 v203, 0xbfb8aa3b, v52
	v_exp_f32_e32 v203, v203
	v_cvt_pk_f16_f32 v205, v206, v211
	v_cvt_pk_f16_f32 v206, v207, v208
	v_cvt_pk_f16_f32 v207, v209, v210
	v_add_f32_e32 v203, 1.0, v203
	v_rcp_f32_e32 v203, v203
	global_store_dwordx4 v[172:173], v[204:207], off offset:256 sc1
	v_add_u32_e32 v172, 0x90, v166
	v_ashrrev_i32_e32 v173, 31, v172
	v_fma_f32 v203, v203, v202, v140
	v_cmp_gt_f32_e32 vcc, s90, v203
	v_lshlrev_b64 v[172:173], 11, v[172:173]
	v_lshl_add_u64 v[172:173], v[170:171], 0, v[172:173]
	v_cndmask_b32_e64 v204, 0, 32, vcc
	v_ldexp_f32 v203, v203, v204
	v_mul_f32_e32 v204, 0xbfb8aa3b, v48
	v_exp_f32_e32 v204, v204
	v_log_f32_e32 v203, v203
	v_add_f32_e32 v204, 1.0, v204
	v_rcp_f32_e32 v204, v204
	v_mul_f32_e32 v205, 0x3f317217, v203
	v_fma_f32 v205, v203, s91, -v205
	v_fmac_f32_e32 v205, 0x3377d1cf, v203
	v_fma_f32 v204, v204, v201, v136
	v_cmp_gt_f32_e64 s[6:7], s90, v204
	v_fmac_f32_e32 v205, 0x3f317217, v203
	v_cmp_lt_f32_e64 s[8:9], |v203|, s92
	v_cndmask_b32_e64 v206, 0, 32, s[6:7]
	v_ldexp_f32 v204, v204, v206
	v_mul_f32_e32 v206, 0xbfb8aa3b, v53
	v_exp_f32_e32 v206, v206
	v_log_f32_e32 v204, v204
	v_cndmask_b32_e64 v203, v203, v205, s[8:9]
	v_cndmask_b32_e32 v205, 0, v186, vcc
	v_add_f32_e32 v206, 1.0, v206
	v_rcp_f32_e32 v206, v206
	v_sub_f32_e32 v203, v203, v205
	v_mul_f32_e32 v205, 0x3f317217, v204
	v_fma_f32 v205, v204, s91, -v205
	v_fmac_f32_e32 v205, 0x3377d1cf, v204
	v_fmac_f32_e32 v205, 0x3f317217, v204
	v_cmp_lt_f32_e64 vcc, |v204|, s92
	v_fma_f32 v206, v206, v200, v141
	s_nop 0
	v_cndmask_b32_e32 v204, v204, v205, vcc
	v_cmp_gt_f32_e32 vcc, s90, v206
	v_cndmask_b32_e64 v205, 0, v186, s[6:7]
	s_nop 0
	v_cndmask_b32_e64 v207, 0, 32, vcc
	v_ldexp_f32 v206, v206, v207
	v_sub_f32_e32 v207, v204, v205
	v_mul_f32_e32 v204, 0xbfb8aa3b, v49
	v_exp_f32_e32 v204, v204
	v_log_f32_e32 v206, v206
	v_cndmask_b32_e32 v208, 0, v186, vcc
	v_add_f32_e32 v204, 1.0, v204
	v_rcp_f32_e32 v204, v204
	v_mul_f32_e32 v205, 0x3f317217, v206
	v_fma_f32 v205, v206, s91, -v205
	v_fmac_f32_e32 v205, 0x3377d1cf, v206
	v_fmac_f32_e32 v205, 0x3f317217, v206
	v_cmp_lt_f32_e64 s[6:7], |v206|, s92
	v_fma_f32 v204, v204, v188, v137
	s_nop 0
	v_cndmask_b32_e64 v205, v206, v205, s[6:7]
	v_cmp_gt_f32_e64 s[6:7], s90, v204
	v_sub_f32_e32 v205, v205, v208
	s_nop 0
	v_cndmask_b32_e64 v206, 0, 32, s[6:7]
	v_ldexp_f32 v204, v204, v206
	v_mul_f32_e32 v206, 0xbfb8aa3b, v54
	v_exp_f32_e32 v206, v206
	v_log_f32_e32 v204, v204
	v_add_f32_e32 v206, 1.0, v206
	v_rcp_f32_e32 v206, v206
	v_mul_f32_e32 v208, 0x3f317217, v204
	v_fma_f32 v208, v204, s91, -v208
	v_fmac_f32_e32 v208, 0x3377d1cf, v204
	v_fma_f32 v206, v206, v167, v142
	v_cmp_gt_f32_e32 vcc, s90, v206
	v_fmac_f32_e32 v208, 0x3f317217, v204
	v_cmp_lt_f32_e64 s[8:9], |v204|, s92
	v_cndmask_b32_e64 v209, 0, 32, vcc
	v_ldexp_f32 v206, v206, v209
	v_mul_f32_e32 v209, 0xbfb8aa3b, v50
	v_exp_f32_e32 v209, v209
	v_log_f32_e32 v206, v206
	v_cndmask_b32_e64 v204, v204, v208, s[8:9]
	v_cndmask_b32_e64 v208, 0, v186, s[6:7]
	v_add_f32_e32 v209, 1.0, v209
	v_sub_f32_e32 v208, v204, v208
	v_mul_f32_e32 v204, 0x3f317217, v206
	v_rcp_f32_e32 v209, v209
	v_fma_f32 v204, v206, s91, -v204
	v_fmac_f32_e32 v204, 0x3377d1cf, v206
	v_fmac_f32_e32 v204, 0x3f317217, v206
	v_cmp_lt_f32_e64 s[6:7], |v206|, s92
	v_fma_f32 v209, v209, v189, v138
	s_nop 0
	v_cndmask_b32_e64 v204, v206, v204, s[6:7]
	v_cndmask_b32_e32 v206, 0, v186, vcc
	v_cmp_gt_f32_e32 vcc, s90, v209
	v_sub_f32_e32 v206, v204, v206
	v_mul_f32_e32 v204, 0xbfb8aa3b, v55
	v_cndmask_b32_e64 v210, 0, 32, vcc
	v_exp_f32_e32 v204, v204
	v_ldexp_f32 v209, v209, v210
	v_log_f32_e32 v209, v209
	v_cndmask_b32_e32 v211, 0, v186, vcc
	v_add_f32_e32 v204, 1.0, v204
	v_rcp_f32_e32 v204, v204
	v_mul_f32_e32 v210, 0x3f317217, v209
	v_fma_f32 v210, v209, s91, -v210
	v_fmac_f32_e32 v210, 0x3377d1cf, v209
	v_fmac_f32_e32 v210, 0x3f317217, v209
	v_cmp_lt_f32_e64 s[6:7], |v209|, s92
	v_fma_f32 v204, v204, v190, v143
	s_nop 0
	v_cndmask_b32_e64 v209, v209, v210, s[6:7]
	v_cmp_gt_f32_e64 s[6:7], s90, v204
	v_sub_f32_e32 v209, v209, v211
	s_nop 0
	v_cndmask_b32_e64 v210, 0, 32, s[6:7]
	v_ldexp_f32 v204, v204, v210
	v_mul_f32_e32 v210, 0xbfb8aa3b, v51
	v_exp_f32_e32 v210, v210
	v_log_f32_e32 v204, v204
	v_add_f32_e32 v210, 1.0, v210
	v_rcp_f32_e32 v210, v210
	v_mul_f32_e32 v211, 0x3f317217, v204
	v_fma_f32 v211, v204, s91, -v211
	v_fmac_f32_e32 v211, 0x3377d1cf, v204
	v_fma_f32 v210, v210, v191, v139
	v_cmp_gt_f32_e32 vcc, s90, v210
	v_fmac_f32_e32 v211, 0x3f317217, v204
	v_cmp_lt_f32_e64 s[8:9], |v204|, s92
	v_cndmask_b32_e64 v212, 0, 32, vcc
	v_ldexp_f32 v210, v210, v212
	v_log_f32_e32 v210, v210
	v_cndmask_b32_e64 v204, v204, v211, s[8:9]
	v_cndmask_b32_e64 v211, 0, v186, s[6:7]
	v_sub_f32_e32 v211, v204, v211
	v_mul_f32_e32 v204, 0x3f317217, v210
	v_mul_f32_e32 v212, 0xbfb8aa3b, v28
	v_fma_f32 v204, v210, s91, -v204
	v_exp_f32_e32 v212, v212
	v_fmac_f32_e32 v204, 0x3377d1cf, v210
	v_fmac_f32_e32 v204, 0x3f317217, v210
	v_cmp_lt_f32_e64 s[6:7], |v210|, s92
	s_nop 1
	v_cndmask_b32_e64 v204, v210, v204, s[6:7]
	v_cndmask_b32_e32 v210, 0, v186, vcc
	v_sub_f32_e32 v210, v204, v210
	v_add_f32_e32 v204, 1.0, v212
	v_rcp_f32_e32 v212, v204
	v_cvt_pk_f16_f32 v204, v203, v205
	v_cvt_pk_f16_f32 v205, v206, v211
; DI unsigned cvtpk(float lo, float hi) { f32x2 v = {lo, hi}; bf16x2_t b = __builtin_convertvector(v, bf16x2_t); return __builtin_bit_cast(unsigned, b); }
; DI unsigned cvtpk_h(float lo, float hi) { f32x2 v = {lo, hi}; h16x2_t b = __builtin_convertvector(v, h16x2_t); return __builtin_bit_cast(unsigned, b); }
; DI float sigm(float x) { return __builtin_amdgcn_rcpf(1.f + fexp(-x)); }
; DI float silu_(float x) { return x * sigm(x); }
;     template <int MODE> __device__ __forceinline__ void run(const f32x4 (&acc)[2][2][4][2], u16* dst, int ld, int row0, int col0, int trow0, int wc, int fq, const float* lb) const {
;     ...
;                         for (int i = 0; i < 4; ++i) { const float l0 = lb0[bj][i], l1 = lb1[bj][i];
;                             v0[i] = __logf(l0 + (1.f - l0) * sigm(v0[i])); v1[i] = __logf(l1 + (1.f - l1) * sigm(v1[i])); }
;                     }
;                     if (MODE == 4) {
; #pragma unroll
;                         for (int i = 0; i < 4; ++i) { v0[i] = silu_(v0[i]); v1[i] = silu_(v1[i]); }
;                     }
;                     if (MODE == 5) {
; #pragma unroll
;                         for (int i = 0; i < 4; ++i) { v0[i] = sigm(v0[i]); v1[i] = sigm(v1[i]); }
;                     }
;                     u32x4 w;
;                     if (MODE == 3) { w.x = cvtpk_h(v0[0], v0[1]); w.y = cvtpk_h(v0[2], v0[3]); w.z = cvtpk_h(v1[0], v1[1]); w.w = cvtpk_h(v1[2], v1[3]); }
;                     else { w.x = cvtpk(v0[0], v0[1]); w.y = cvtpk(v0[2], v0[3]); w.z = cvtpk(v1[0], v1[1]); w.w = cvtpk(v1[2], v1[3]); }
;                     *(u32x4*)(rowp + bj * HALF) = w;
	v_cvt_pk_f16_f32 v206, v207, v208
	v_fma_f32 v203, v212, v152, v132
	v_cmp_gt_f32_e32 vcc, s90, v203
	s_nop 1
	v_cndmask_b32_e64 v207, 0, 32, vcc
	v_ldexp_f32 v203, v203, v207
	v_mul_f32_e32 v207, 0xbfb8aa3b, v24
	v_exp_f32_e32 v208, v207
	v_cvt_pk_f16_f32 v207, v209, v210
	global_store_dwordx4 v[172:173], v[204:207], off sc1
	v_log_f32_e32 v203, v203
	s_nop 0
	v_add_f32_e32 v205, 1.0, v208
	v_rcp_f32_e32 v205, v205
	v_mul_f32_e32 v204, 0x3f317217, v203
	v_fma_f32 v204, v203, s91, -v204
	v_fmac_f32_e32 v204, 0x3377d1cf, v203
	v_fma_f32 v205, v205, v192, v128
	v_cmp_gt_f32_e64 s[6:7], s90, v205
	v_fmac_f32_e32 v204, 0x3f317217, v203
	v_cmp_lt_f32_e64 s[8:9], |v203|, s92
	v_cndmask_b32_e64 v206, 0, 32, s[6:7]
	v_ldexp_f32 v205, v205, v206
	v_mul_f32_e32 v206, 0xbfb8aa3b, v29
	v_exp_f32_e32 v206, v206
	v_log_f32_e32 v205, v205
	v_cndmask_b32_e64 v203, v203, v204, s[8:9]
	v_cndmask_b32_e32 v204, 0, v186, vcc
	v_add_f32_e32 v206, 1.0, v206
	v_rcp_f32_e32 v206, v206
	v_sub_f32_e32 v203, v203, v204
	v_mul_f32_e32 v204, 0x3f317217, v205
	v_fma_f32 v204, v205, s91, -v204
	v_fmac_f32_e32 v204, 0x3377d1cf, v205
	v_fmac_f32_e32 v204, 0x3f317217, v205
	v_cmp_lt_f32_e64 vcc, |v205|, s92
	v_fma_f32 v206, v206, v193, v133
	s_nop 0
	v_cndmask_b32_e32 v204, v205, v204, vcc
	v_cmp_gt_f32_e32 vcc, s90, v206
	v_cndmask_b32_e64 v205, 0, v186, s[6:7]
	s_nop 0
	v_cndmask_b32_e64 v207, 0, 32, vcc
	v_ldexp_f32 v206, v206, v207
	v_sub_f32_e32 v207, v204, v205
	v_mul_f32_e32 v204, 0xbfb8aa3b, v25
	v_exp_f32_e32 v204, v204
	v_log_f32_e32 v206, v206
	v_cndmask_b32_e32 v208, 0, v186, vcc
	v_add_f32_e32 v204, 1.0, v204
	v_rcp_f32_e32 v204, v204
	v_mul_f32_e32 v205, 0x3f317217, v206
	v_fma_f32 v205, v206, s91, -v205
	v_fmac_f32_e32 v205, 0x3377d1cf, v206
	v_fmac_f32_e32 v205, 0x3f317217, v206
	v_cmp_lt_f32_e64 s[6:7], |v206|, s92
	v_fma_f32 v204, v204, v195, v129
	s_nop 0
	v_cndmask_b32_e64 v205, v206, v205, s[6:7]
	v_cmp_gt_f32_e64 s[6:7], s90, v204
	v_sub_f32_e32 v205, v205, v208
	s_nop 0
	v_cndmask_b32_e64 v206, 0, 32, s[6:7]
	v_ldexp_f32 v204, v204, v206
	v_mul_f32_e32 v206, 0xbfb8aa3b, v30
	v_exp_f32_e32 v206, v206
	v_log_f32_e32 v204, v204
	v_add_f32_e32 v206, 1.0, v206
	v_rcp_f32_e32 v206, v206
	v_mul_f32_e32 v208, 0x3f317217, v204
	v_fma_f32 v208, v204, s91, -v208
	v_fmac_f32_e32 v208, 0x3377d1cf, v204
	v_fma_f32 v206, v206, v197, v134
	v_cmp_gt_f32_e32 vcc, s90, v206
	v_fmac_f32_e32 v208, 0x3f317217, v204
	v_cmp_lt_f32_e64 s[8:9], |v204|, s92
	v_cndmask_b32_e64 v209, 0, 32, vcc
	v_ldexp_f32 v206, v206, v209
	v_mul_f32_e32 v209, 0xbfb8aa3b, v26
	v_exp_f32_e32 v209, v209
	v_log_f32_e32 v206, v206
	v_cndmask_b32_e64 v204, v204, v208, s[8:9]
	v_cndmask_b32_e64 v208, 0, v186, s[6:7]
	v_add_f32_e32 v209, 1.0, v209
	v_sub_f32_e32 v208, v204, v208
	v_mul_f32_e32 v204, 0x3f317217, v206
	v_rcp_f32_e32 v209, v209
	v_fma_f32 v204, v206, s91, -v204
	v_fmac_f32_e32 v204, 0x3377d1cf, v206
	v_fmac_f32_e32 v204, 0x3f317217, v206
	v_cmp_lt_f32_e64 s[6:7], |v206|, s92
	v_fma_f32 v209, v209, v196, v130
	s_nop 0
	v_cndmask_b32_e64 v204, v206, v204, s[6:7]
	v_cndmask_b32_e32 v206, 0, v186, vcc
	v_cmp_gt_f32_e32 vcc, s90, v209
	v_sub_f32_e32 v206, v204, v206
	v_mul_f32_e32 v204, 0xbfb8aa3b, v31
	v_cndmask_b32_e64 v210, 0, 32, vcc
	v_exp_f32_e32 v204, v204
	v_ldexp_f32 v209, v209, v210
	v_log_f32_e32 v209, v209
	v_cndmask_b32_e32 v211, 0, v186, vcc
	v_add_f32_e32 v204, 1.0, v204
	v_rcp_f32_e32 v204, v204
	v_mul_f32_e32 v210, 0x3f317217, v209
	v_fma_f32 v210, v209, s91, -v210
	v_fmac_f32_e32 v210, 0x3377d1cf, v209
	v_fmac_f32_e32 v210, 0x3f317217, v209
	v_cmp_lt_f32_e64 s[6:7], |v209|, s92
	v_fma_f32 v204, v204, v198, v135
	s_nop 0
	v_cndmask_b32_e64 v209, v209, v210, s[6:7]
	v_cmp_gt_f32_e64 s[6:7], s90, v204
	v_sub_f32_e32 v209, v209, v211
	s_nop 0
	v_cndmask_b32_e64 v210, 0, 32, s[6:7]
	v_ldexp_f32 v204, v204, v210
	v_mul_f32_e32 v210, 0xbfb8aa3b, v27
	v_exp_f32_e32 v210, v210
	v_log_f32_e32 v204, v204
	v_add_f32_e32 v210, 1.0, v210
	v_rcp_f32_e32 v210, v210
	v_mul_f32_e32 v211, 0x3f317217, v204
	v_fma_f32 v211, v204, s91, -v211
	v_fmac_f32_e32 v211, 0x3377d1cf, v204
	v_fma_f32 v210, v210, v199, v131
	v_cmp_gt_f32_e32 vcc, s90, v210
	v_fmac_f32_e32 v211, 0x3f317217, v204
	v_cmp_lt_f32_e64 s[8:9], |v204|, s92
	v_cndmask_b32_e64 v212, 0, 32, vcc
	v_ldexp_f32 v210, v210, v212
	v_log_f32_e32 v210, v210
	v_cndmask_b32_e64 v204, v204, v211, s[8:9]
	v_cndmask_b32_e64 v211, 0, v186, s[6:7]
	v_sub_f32_e32 v211, v204, v211
	v_mul_f32_e32 v204, 0x3f317217, v210
	v_fma_f32 v204, v210, s91, -v204
	v_fmac_f32_e32 v204, 0x3377d1cf, v210
	v_fmac_f32_e32 v204, 0x3f317217, v210
	v_cmp_lt_f32_e64 s[6:7], |v210|, s92
	s_nop 1
	v_cndmask_b32_e64 v204, v210, v204, s[6:7]
	v_cndmask_b32_e32 v210, 0, v186, vcc
	v_sub_f32_e32 v210, v204, v210
	v_cvt_pk_f16_f32 v204, v203, v205
	v_mul_f32_e32 v203, 0xbfb8aa3b, v36
	v_exp_f32_e32 v203, v203
	v_cvt_pk_f16_f32 v205, v206, v211
	v_cvt_pk_f16_f32 v206, v207, v208
	v_cvt_pk_f16_f32 v207, v209, v210
	v_add_f32_e32 v203, 1.0, v203
	v_rcp_f32_e32 v203, v203
	global_store_dwordx4 v[172:173], v[204:207], off offset:256 sc1
	v_add_u32_e32 v172, 0xa0, v166
	v_ashrrev_i32_e32 v173, 31, v172
	v_fma_f32 v203, v203, v202, v140
	v_cmp_gt_f32_e32 vcc, s90, v203
	v_lshlrev_b64 v[172:173], 11, v[172:173]
	v_lshl_add_u64 v[172:173], v[170:171], 0, v[172:173]
	v_cndmask_b32_e64 v204, 0, 32, vcc
	v_ldexp_f32 v203, v203, v204
	v_mul_f32_e32 v204, 0xbfb8aa3b, v32
	v_exp_f32_e32 v204, v204
	v_log_f32_e32 v203, v203
	v_add_f32_e32 v204, 1.0, v204
	v_rcp_f32_e32 v204, v204
	v_mul_f32_e32 v205, 0x3f317217, v203
	v_fma_f32 v205, v203, s91, -v205
	v_fmac_f32_e32 v205, 0x3377d1cf, v203
; DI unsigned cvtpk(float lo, float hi) { f32x2 v = {lo, hi}; bf16x2_t b = __builtin_convertvector(v, bf16x2_t); return __builtin_bit_cast(unsigned, b); }
; DI unsigned cvtpk_h(float lo, float hi) { f32x2 v = {lo, hi}; h16x2_t b = __builtin_convertvector(v, h16x2_t); return __builtin_bit_cast(unsigned, b); }
; DI float sigm(float x) { return __builtin_amdgcn_rcpf(1.f + fexp(-x)); }
; DI float silu_(float x) { return x * sigm(x); }
;     template <int MODE> __device__ __forceinline__ void run(const f32x4 (&acc)[2][2][4][2], u16* dst, int ld, int row0, int col0, int trow0, int wc, int fq, const float* lb) const {
;     ...
;                         for (int i = 0; i < 4; ++i) { const float l0 = lb0[bj][i], l1 = lb1[bj][i];
;                             v0[i] = __logf(l0 + (1.f - l0) * sigm(v0[i])); v1[i] = __logf(l1 + (1.f - l1) * sigm(v1[i])); }
;                     }
;                     if (MODE == 4) {
; #pragma unroll
;                         for (int i = 0; i < 4; ++i) { v0[i] = silu_(v0[i]); v1[i] = silu_(v1[i]); }
;                     }
;                     if (MODE == 5) {
; #pragma unroll
;                         for (int i = 0; i < 4; ++i) { v0[i] = sigm(v0[i]); v1[i] = sigm(v1[i]); }
;                     }
;                     u32x4 w;
;                     if (MODE == 3) { w.x = cvtpk_h(v0[0], v0[1]); w.y = cvtpk_h(v0[2], v0[3]); w.z = cvtpk_h(v1[0], v1[1]); w.w = cvtpk_h(v1[2], v1[3]); }
;                     else { w.x = cvtpk(v0[0], v0[1]); w.y = cvtpk(v0[2], v0[3]); w.z = cvtpk(v1[0], v1[1]); w.w = cvtpk(v1[2], v1[3]); }
;                     *(u32x4*)(rowp + bj * HALF) = w;
	v_fma_f32 v204, v204, v201, v136
	v_cmp_gt_f32_e64 s[6:7], s90, v204
	v_fmac_f32_e32 v205, 0x3f317217, v203
	v_cmp_lt_f32_e64 s[8:9], |v203|, s92
	v_cndmask_b32_e64 v206, 0, 32, s[6:7]
	v_ldexp_f32 v204, v204, v206
	v_mul_f32_e32 v206, 0xbfb8aa3b, v37
	v_exp_f32_e32 v206, v206
	v_log_f32_e32 v204, v204
	v_cndmask_b32_e64 v203, v203, v205, s[8:9]
	v_cndmask_b32_e32 v205, 0, v186, vcc
	v_add_f32_e32 v206, 1.0, v206
	v_rcp_f32_e32 v206, v206
	v_sub_f32_e32 v203, v203, v205
	v_mul_f32_e32 v205, 0x3f317217, v204
	v_fma_f32 v205, v204, s91, -v205
	v_fmac_f32_e32 v205, 0x3377d1cf, v204
	v_fmac_f32_e32 v205, 0x3f317217, v204
	v_cmp_lt_f32_e64 vcc, |v204|, s92
	v_fma_f32 v206, v206, v200, v141
	s_nop 0
	v_cndmask_b32_e32 v204, v204, v205, vcc
	v_cmp_gt_f32_e32 vcc, s90, v206
	v_cndmask_b32_e64 v205, 0, v186, s[6:7]
	s_nop 0
	v_cndmask_b32_e64 v207, 0, 32, vcc
	v_ldexp_f32 v206, v206, v207
	v_sub_f32_e32 v207, v204, v205
	v_mul_f32_e32 v204, 0xbfb8aa3b, v33
	v_exp_f32_e32 v204, v204
	v_log_f32_e32 v206, v206
	v_cndmask_b32_e32 v208, 0, v186, vcc
	v_add_f32_e32 v204, 1.0, v204
	v_rcp_f32_e32 v204, v204
	v_mul_f32_e32 v205, 0x3f317217, v206
	v_fma_f32 v205, v206, s91, -v205
	v_fmac_f32_e32 v205, 0x3377d1cf, v206
	v_fmac_f32_e32 v205, 0x3f317217, v206
	v_cmp_lt_f32_e64 s[6:7], |v206|, s92
	v_fma_f32 v204, v204, v188, v137
	s_nop 0
	v_cndmask_b32_e64 v205, v206, v205, s[6:7]
	v_cmp_gt_f32_e64 s[6:7], s90, v204
	v_sub_f32_e32 v205, v205, v208
	s_nop 0
	v_cndmask_b32_e64 v206, 0, 32, s[6:7]
	v_ldexp_f32 v204, v204, v206
	v_mul_f32_e32 v206, 0xbfb8aa3b, v38
	v_exp_f32_e32 v206, v206
	v_log_f32_e32 v204, v204
	v_add_f32_e32 v206, 1.0, v206
	v_rcp_f32_e32 v206, v206
	v_mul_f32_e32 v208, 0x3f317217, v204
	v_fma_f32 v208, v204, s91, -v208
	v_fmac_f32_e32 v208, 0x3377d1cf, v204
	v_fma_f32 v206, v206, v167, v142
	v_cmp_gt_f32_e32 vcc, s90, v206
	v_fmac_f32_e32 v208, 0x3f317217, v204
	v_cmp_lt_f32_e64 s[8:9], |v204|, s92
	v_cndmask_b32_e64 v209, 0, 32, vcc
	v_ldexp_f32 v206, v206, v209
	v_mul_f32_e32 v209, 0xbfb8aa3b, v34
	v_exp_f32_e32 v209, v209
	v_log_f32_e32 v206, v206
	v_cndmask_b32_e64 v204, v204, v208, s[8:9]
	v_cndmask_b32_e64 v208, 0, v186, s[6:7]
	v_add_f32_e32 v209, 1.0, v209
	v_sub_f32_e32 v208, v204, v208
	v_mul_f32_e32 v204, 0x3f317217, v206
	v_rcp_f32_e32 v209, v209
	v_fma_f32 v204, v206, s91, -v204
	v_fmac_f32_e32 v204, 0x3377d1cf, v206
	v_fmac_f32_e32 v204, 0x3f317217, v206
	v_cmp_lt_f32_e64 s[6:7], |v206|, s92
	v_fma_f32 v209, v209, v189, v138
	s_nop 0
	v_cndmask_b32_e64 v204, v206, v204, s[6:7]
	v_cndmask_b32_e32 v206, 0, v186, vcc
	v_cmp_gt_f32_e32 vcc, s90, v209
	v_sub_f32_e32 v206, v204, v206
	v_mul_f32_e32 v204, 0xbfb8aa3b, v39
	v_cndmask_b32_e64 v210, 0, 32, vcc
	v_exp_f32_e32 v204, v204
	v_ldexp_f32 v209, v209, v210
	v_log_f32_e32 v209, v209
	v_cndmask_b32_e32 v211, 0, v186, vcc
	v_add_f32_e32 v204, 1.0, v204
	v_rcp_f32_e32 v204, v204
	v_mul_f32_e32 v210, 0x3f317217, v209
	v_fma_f32 v210, v209, s91, -v210
	v_fmac_f32_e32 v210, 0x3377d1cf, v209
	v_fmac_f32_e32 v210, 0x3f317217, v209
	v_cmp_lt_f32_e64 s[6:7], |v209|, s92
	v_fma_f32 v204, v204, v190, v143
	s_nop 0
	v_cndmask_b32_e64 v209, v209, v210, s[6:7]
	v_cmp_gt_f32_e64 s[6:7], s90, v204
	v_sub_f32_e32 v209, v209, v211
	s_nop 0
	v_cndmask_b32_e64 v210, 0, 32, s[6:7]
	v_ldexp_f32 v204, v204, v210
	v_mul_f32_e32 v210, 0xbfb8aa3b, v35
	v_exp_f32_e32 v210, v210
	v_log_f32_e32 v204, v204
	v_add_f32_e32 v210, 1.0, v210
	v_rcp_f32_e32 v210, v210
	v_mul_f32_e32 v211, 0x3f317217, v204
	v_fma_f32 v211, v204, s91, -v211
	v_fmac_f32_e32 v211, 0x3377d1cf, v204
	v_fma_f32 v210, v210, v191, v139
	v_cmp_gt_f32_e32 vcc, s90, v210
	v_fmac_f32_e32 v211, 0x3f317217, v204
	v_cmp_lt_f32_e64 s[8:9], |v204|, s92
	v_cndmask_b32_e64 v212, 0, 32, vcc
	v_ldexp_f32 v210, v210, v212
	v_log_f32_e32 v210, v210
	v_cndmask_b32_e64 v204, v204, v211, s[8:9]
	v_cndmask_b32_e64 v211, 0, v186, s[6:7]
	v_sub_f32_e32 v211, v204, v211
	v_mul_f32_e32 v204, 0x3f317217, v210
	v_mul_f32_e32 v212, 0xbfb8aa3b, v12
	v_fma_f32 v204, v210, s91, -v204
	v_exp_f32_e32 v212, v212
	v_fmac_f32_e32 v204, 0x3377d1cf, v210
	v_fmac_f32_e32 v204, 0x3f317217, v210
	v_cmp_lt_f32_e64 s[6:7], |v210|, s92
	s_nop 1
	v_cndmask_b32_e64 v204, v210, v204, s[6:7]
	v_cndmask_b32_e32 v210, 0, v186, vcc
	v_sub_f32_e32 v210, v204, v210
	v_add_f32_e32 v204, 1.0, v212
	v_rcp_f32_e32 v212, v204
	v_cvt_pk_f16_f32 v204, v203, v205
	v_cvt_pk_f16_f32 v205, v206, v211
	v_cvt_pk_f16_f32 v206, v207, v208
	v_fma_f32 v203, v212, v152, v132
	v_cmp_gt_f32_e32 vcc, s90, v203
	s_nop 1
	v_cndmask_b32_e64 v207, 0, 32, vcc
	v_ldexp_f32 v203, v203, v207
	v_mul_f32_e32 v207, 0xbfb8aa3b, v8
	v_exp_f32_e32 v208, v207
	v_cvt_pk_f16_f32 v207, v209, v210
	global_store_dwordx4 v[172:173], v[204:207], off sc1
	v_log_f32_e32 v203, v203
	s_nop 0
	v_add_f32_e32 v205, 1.0, v208
	v_rcp_f32_e32 v205, v205
	v_mul_f32_e32 v204, 0x3f317217, v203
	v_fma_f32 v204, v203, s91, -v204
	v_fmac_f32_e32 v204, 0x3377d1cf, v203
	v_fma_f32 v205, v205, v192, v128
	v_cmp_gt_f32_e64 s[6:7], s90, v205
	v_fmac_f32_e32 v204, 0x3f317217, v203
	v_cmp_lt_f32_e64 s[8:9], |v203|, s92
	v_cndmask_b32_e64 v206, 0, 32, s[6:7]
	v_ldexp_f32 v205, v205, v206
	v_mul_f32_e32 v206, 0xbfb8aa3b, v13
	v_exp_f32_e32 v206, v206
	v_log_f32_e32 v205, v205
	v_cndmask_b32_e64 v203, v203, v204, s[8:9]
	v_cndmask_b32_e32 v204, 0, v186, vcc
	v_add_f32_e32 v206, 1.0, v206
	v_rcp_f32_e32 v206, v206
	v_sub_f32_e32 v203, v203, v204
	v_mul_f32_e32 v204, 0x3f317217, v205
	v_fma_f32 v204, v205, s91, -v204
	v_fmac_f32_e32 v204, 0x3377d1cf, v205
	v_fmac_f32_e32 v204, 0x3f317217, v205
	v_cmp_lt_f32_e64 vcc, |v205|, s92
	v_fma_f32 v206, v206, v193, v133
; DI unsigned cvtpk(float lo, float hi) { f32x2 v = {lo, hi}; bf16x2_t b = __builtin_convertvector(v, bf16x2_t); return __builtin_bit_cast(unsigned, b); }
; DI unsigned cvtpk_h(float lo, float hi) { f32x2 v = {lo, hi}; h16x2_t b = __builtin_convertvector(v, h16x2_t); return __builtin_bit_cast(unsigned, b); }
; DI float sigm(float x) { return __builtin_amdgcn_rcpf(1.f + fexp(-x)); }
; DI float silu_(float x) { return x * sigm(x); }
;     template <int MODE> __device__ __forceinline__ void run(const f32x4 (&acc)[2][2][4][2], u16* dst, int ld, int row0, int col0, int trow0, int wc, int fq, const float* lb) const {
;     ...
;                         for (int i = 0; i < 4; ++i) { const float l0 = lb0[bj][i], l1 = lb1[bj][i];
;                             v0[i] = __logf(l0 + (1.f - l0) * sigm(v0[i])); v1[i] = __logf(l1 + (1.f - l1) * sigm(v1[i])); }
;                     }
;                     if (MODE == 4) {
; #pragma unroll
;                         for (int i = 0; i < 4; ++i) { v0[i] = silu_(v0[i]); v1[i] = silu_(v1[i]); }
;                     }
;                     if (MODE == 5) {
; #pragma unroll
;                         for (int i = 0; i < 4; ++i) { v0[i] = sigm(v0[i]); v1[i] = sigm(v1[i]); }
;                     }
;                     u32x4 w;
;                     if (MODE == 3) { w.x = cvtpk_h(v0[0], v0[1]); w.y = cvtpk_h(v0[2], v0[3]); w.z = cvtpk_h(v1[0], v1[1]); w.w = cvtpk_h(v1[2], v1[3]); }
;                     else { w.x = cvtpk(v0[0], v0[1]); w.y = cvtpk(v0[2], v0[3]); w.z = cvtpk(v1[0], v1[1]); w.w = cvtpk(v1[2], v1[3]); }
;                     *(u32x4*)(rowp + bj * HALF) = w;
	s_nop 0
	v_cndmask_b32_e32 v204, v205, v204, vcc
	v_cmp_gt_f32_e32 vcc, s90, v206
	v_cndmask_b32_e64 v205, 0, v186, s[6:7]
	s_nop 0
	v_cndmask_b32_e64 v207, 0, 32, vcc
	v_ldexp_f32 v206, v206, v207
	v_sub_f32_e32 v207, v204, v205
	v_mul_f32_e32 v204, 0xbfb8aa3b, v9
	v_exp_f32_e32 v204, v204
	v_log_f32_e32 v206, v206
	v_cndmask_b32_e32 v208, 0, v186, vcc
	v_add_f32_e32 v204, 1.0, v204
	v_rcp_f32_e32 v204, v204
	v_mul_f32_e32 v205, 0x3f317217, v206
	v_fma_f32 v205, v206, s91, -v205
	v_fmac_f32_e32 v205, 0x3377d1cf, v206
	v_fmac_f32_e32 v205, 0x3f317217, v206
	v_cmp_lt_f32_e64 s[6:7], |v206|, s92
	v_fma_f32 v204, v204, v195, v129
	s_nop 0
	v_cndmask_b32_e64 v205, v206, v205, s[6:7]
	v_cmp_gt_f32_e64 s[6:7], s90, v204
	v_sub_f32_e32 v205, v205, v208
	s_nop 0
	v_cndmask_b32_e64 v206, 0, 32, s[6:7]
	v_ldexp_f32 v204, v204, v206
	v_mul_f32_e32 v206, 0xbfb8aa3b, v14
	v_exp_f32_e32 v206, v206
	v_log_f32_e32 v204, v204
	v_add_f32_e32 v206, 1.0, v206
	v_rcp_f32_e32 v206, v206
	v_mul_f32_e32 v208, 0x3f317217, v204
	v_fma_f32 v208, v204, s91, -v208
	v_fmac_f32_e32 v208, 0x3377d1cf, v204
	v_fma_f32 v206, v206, v197, v134
	v_cmp_gt_f32_e32 vcc, s90, v206
	v_fmac_f32_e32 v208, 0x3f317217, v204
	v_cmp_lt_f32_e64 s[8:9], |v204|, s92
	v_cndmask_b32_e64 v209, 0, 32, vcc
	v_ldexp_f32 v206, v206, v209
	v_mul_f32_e32 v209, 0xbfb8aa3b, v10
	v_exp_f32_e32 v209, v209
	v_log_f32_e32 v206, v206
	v_cndmask_b32_e64 v204, v204, v208, s[8:9]
	v_cndmask_b32_e64 v208, 0, v186, s[6:7]
	v_add_f32_e32 v209, 1.0, v209
	v_sub_f32_e32 v208, v204, v208
	v_mul_f32_e32 v204, 0x3f317217, v206
	v_rcp_f32_e32 v209, v209
	v_fma_f32 v204, v206, s91, -v204
	v_fmac_f32_e32 v204, 0x3377d1cf, v206
	v_fmac_f32_e32 v204, 0x3f317217, v206
	v_cmp_lt_f32_e64 s[6:7], |v206|, s92
	v_fma_f32 v209, v209, v196, v130
	s_nop 0
	v_cndmask_b32_e64 v204, v206, v204, s[6:7]
	v_cndmask_b32_e32 v206, 0, v186, vcc
	v_cmp_gt_f32_e32 vcc, s90, v209
	v_sub_f32_e32 v206, v204, v206
	v_mul_f32_e32 v204, 0xbfb8aa3b, v15
	v_cndmask_b32_e64 v210, 0, 32, vcc
	v_exp_f32_e32 v204, v204
	v_ldexp_f32 v209, v209, v210
	v_log_f32_e32 v209, v209
	v_cndmask_b32_e32 v211, 0, v186, vcc
	v_add_f32_e32 v204, 1.0, v204
	v_rcp_f32_e32 v204, v204
	v_mul_f32_e32 v210, 0x3f317217, v209
	v_fma_f32 v210, v209, s91, -v210
	v_fmac_f32_e32 v210, 0x3377d1cf, v209
	v_fmac_f32_e32 v210, 0x3f317217, v209
	v_cmp_lt_f32_e64 s[6:7], |v209|, s92
	v_fma_f32 v204, v204, v198, v135
	s_nop 0
	v_cndmask_b32_e64 v209, v209, v210, s[6:7]
	v_cmp_gt_f32_e64 s[6:7], s90, v204
	v_sub_f32_e32 v209, v209, v211
	s_nop 0
	v_cndmask_b32_e64 v210, 0, 32, s[6:7]
	v_ldexp_f32 v204, v204, v210
	v_mul_f32_e32 v210, 0xbfb8aa3b, v11
	v_exp_f32_e32 v210, v210
	v_log_f32_e32 v204, v204
	v_add_f32_e32 v210, 1.0, v210
	v_rcp_f32_e32 v210, v210
	v_mul_f32_e32 v211, 0x3f317217, v204
	v_fma_f32 v211, v204, s91, -v211
	v_fmac_f32_e32 v211, 0x3377d1cf, v204
	v_fma_f32 v210, v210, v199, v131
	v_cmp_gt_f32_e32 vcc, s90, v210
	v_fmac_f32_e32 v211, 0x3f317217, v204
	v_cmp_lt_f32_e64 s[8:9], |v204|, s92
	v_cndmask_b32_e64 v212, 0, 32, vcc
	v_ldexp_f32 v210, v210, v212
	v_log_f32_e32 v210, v210
	v_cndmask_b32_e64 v204, v204, v211, s[8:9]
	v_cndmask_b32_e64 v211, 0, v186, s[6:7]
	v_sub_f32_e32 v211, v204, v211
	v_mul_f32_e32 v204, 0x3f317217, v210
	v_fma_f32 v204, v210, s91, -v204
	v_fmac_f32_e32 v204, 0x3377d1cf, v210
	v_fmac_f32_e32 v204, 0x3f317217, v210
	v_cmp_lt_f32_e64 s[6:7], |v210|, s92
	s_nop 1
	v_cndmask_b32_e64 v204, v210, v204, s[6:7]
	v_cndmask_b32_e32 v210, 0, v186, vcc
	v_sub_f32_e32 v210, v204, v210
	v_cvt_pk_f16_f32 v204, v203, v205
	v_mul_f32_e32 v203, 0xbfb8aa3b, v20
	v_exp_f32_e32 v203, v203
	v_cvt_pk_f16_f32 v205, v206, v211
	v_cvt_pk_f16_f32 v206, v207, v208
	v_cvt_pk_f16_f32 v207, v209, v210
	v_add_f32_e32 v203, 1.0, v203
	v_rcp_f32_e32 v203, v203
	global_store_dwordx4 v[172:173], v[204:207], off offset:256 sc1
	v_add_u32_e32 v172, 0xb0, v166
	v_ashrrev_i32_e32 v173, 31, v172
	v_fma_f32 v140, v203, v202, v140
	v_cmp_gt_f32_e32 vcc, s90, v140
	v_lshlrev_b64 v[172:173], 11, v[172:173]
	v_lshl_add_u64 v[170:171], v[170:171], 0, v[172:173]
	v_cndmask_b32_e64 v202, 0, 32, vcc
	v_ldexp_f32 v140, v140, v202
	v_mul_f32_e32 v202, 0xbfb8aa3b, v16
	v_exp_f32_e32 v202, v202
	v_log_f32_e32 v140, v140
	v_add_f32_e32 v173, 1.0, v202
	v_rcp_f32_e32 v173, v173
	v_mul_f32_e32 v172, 0x3f317217, v140
	v_fma_f32 v172, v140, s91, -v172
	v_fmac_f32_e32 v172, 0x3377d1cf, v140
	v_fma_f32 v136, v173, v201, v136
	v_cmp_gt_f32_e64 s[6:7], s90, v136
	v_fmac_f32_e32 v172, 0x3f317217, v140
	v_cmp_lt_f32_e64 s[8:9], |v140|, s92
	v_cndmask_b32_e64 v173, 0, 32, s[6:7]
	v_ldexp_f32 v136, v136, v173
	v_mul_f32_e32 v173, 0xbfb8aa3b, v21
	v_exp_f32_e32 v173, v173
	v_log_f32_e32 v136, v136
	v_cndmask_b32_e64 v140, v140, v172, s[8:9]
	v_cndmask_b32_e32 v172, 0, v186, vcc
	v_add_f32_e32 v173, 1.0, v173
	v_sub_f32_e32 v140, v140, v172
	v_mul_f32_e32 v172, 0x3f317217, v136
	v_rcp_f32_e32 v173, v173
	v_fma_f32 v172, v136, s91, -v172
	v_fmac_f32_e32 v172, 0x3377d1cf, v136
	v_fmac_f32_e32 v172, 0x3f317217, v136
	v_cmp_lt_f32_e64 vcc, |v136|, s92
	v_fma_f32 v141, v173, v200, v141
	s_nop 0
	v_cndmask_b32_e32 v136, v136, v172, vcc
	v_cndmask_b32_e64 v172, 0, v186, s[6:7]
	v_cmp_gt_f32_e32 vcc, s90, v141
	v_sub_f32_e32 v172, v136, v172
	v_mul_f32_e32 v136, 0xbfb8aa3b, v17
	v_cndmask_b32_e64 v173, 0, 32, vcc
	v_exp_f32_e32 v136, v136
	v_ldexp_f32 v141, v141, v173
	v_log_f32_e32 v141, v141
	v_add_f32_e32 v136, 1.0, v136
	v_rcp_f32_e32 v136, v136
	v_mul_f32_e32 v173, 0x3f317217, v141
	v_fma_f32 v173, v141, s91, -v173
	v_fmac_f32_e32 v173, 0x3377d1cf, v141
	v_fmac_f32_e32 v173, 0x3f317217, v141
; DI unsigned cvtpk(float lo, float hi) { f32x2 v = {lo, hi}; bf16x2_t b = __builtin_convertvector(v, bf16x2_t); return __builtin_bit_cast(unsigned, b); }
; DI unsigned cvtpk_h(float lo, float hi) { f32x2 v = {lo, hi}; h16x2_t b = __builtin_convertvector(v, h16x2_t); return __builtin_bit_cast(unsigned, b); }
; DI float sigm(float x) { return __builtin_amdgcn_rcpf(1.f + fexp(-x)); }
; DI float silu_(float x) { return x * sigm(x); }
;     template <int MODE> __device__ __forceinline__ void run(const f32x4 (&acc)[2][2][4][2], u16* dst, int ld, int row0, int col0, int trow0, int wc, int fq, const float* lb) const {
;     ...
;                         for (int i = 0; i < 4; ++i) { const float l0 = lb0[bj][i], l1 = lb1[bj][i];
;                             v0[i] = __logf(l0 + (1.f - l0) * sigm(v0[i])); v1[i] = __logf(l1 + (1.f - l1) * sigm(v1[i])); }
;                     }
;                     if (MODE == 4) {
; #pragma unroll
;                         for (int i = 0; i < 4; ++i) { v0[i] = silu_(v0[i]); v1[i] = silu_(v1[i]); }
;                     }
;                     if (MODE == 5) {
; #pragma unroll
;                         for (int i = 0; i < 4; ++i) { v0[i] = sigm(v0[i]); v1[i] = sigm(v1[i]); }
;                     }
;                     u32x4 w;
;                     if (MODE == 3) { w.x = cvtpk_h(v0[0], v0[1]); w.y = cvtpk_h(v0[2], v0[3]); w.z = cvtpk_h(v1[0], v1[1]); w.w = cvtpk_h(v1[2], v1[3]); }
;                     else { w.x = cvtpk(v0[0], v0[1]); w.y = cvtpk(v0[2], v0[3]); w.z = cvtpk(v1[0], v1[1]); w.w = cvtpk(v1[2], v1[3]); }
;                     *(u32x4*)(rowp + bj * HALF) = w;
	v_cmp_lt_f32_e64 s[6:7], |v141|, s92
	v_fma_f32 v136, v136, v188, v137
	s_nop 0
	v_cndmask_b32_e64 v141, v141, v173, s[6:7]
	v_cmp_gt_f32_e64 s[6:7], s90, v136
	v_cndmask_b32_e32 v173, 0, v186, vcc
	v_sub_f32_e32 v141, v141, v173
	v_cndmask_b32_e64 v137, 0, 32, s[6:7]
	v_ldexp_f32 v136, v136, v137
	v_mul_f32_e32 v137, 0xbfb8aa3b, v22
	v_exp_f32_e32 v137, v137
	v_log_f32_e32 v136, v136
	v_add_f32_e32 v137, 1.0, v137
	v_rcp_f32_e32 v137, v137
	v_mul_f32_e32 v173, 0x3f317217, v136
	v_fma_f32 v173, v136, s91, -v173
	v_fmac_f32_e32 v173, 0x3377d1cf, v136
	v_fma_f32 v137, v137, v167, v142
	v_cmp_gt_f32_e32 vcc, s90, v137
	v_mul_f32_e32 v167, 0xbfb8aa3b, v18
	v_exp_f32_e32 v167, v167
	v_cndmask_b32_e64 v142, 0, 32, vcc
	v_ldexp_f32 v137, v137, v142
	v_log_f32_e32 v137, v137
	v_fmac_f32_e32 v173, 0x3f317217, v136
	v_cmp_lt_f32_e64 s[8:9], |v136|, s92
	v_cndmask_b32_e64 v142, 0, v186, s[6:7]
	v_add_f32_e32 v167, 1.0, v167
	v_cndmask_b32_e64 v136, v136, v173, s[8:9]
	v_sub_f32_e32 v142, v136, v142
	v_mul_f32_e32 v136, 0x3f317217, v137
	v_rcp_f32_e32 v167, v167
	v_fma_f32 v136, v137, s91, -v136
	v_fmac_f32_e32 v136, 0x3377d1cf, v137
	v_fmac_f32_e32 v136, 0x3f317217, v137
	v_cmp_lt_f32_e64 s[6:7], |v137|, s92
	v_fma_f32 v138, v167, v189, v138
	s_nop 0
	v_cndmask_b32_e64 v136, v137, v136, s[6:7]
	v_cndmask_b32_e32 v137, 0, v186, vcc
	v_cmp_gt_f32_e32 vcc, s90, v138
	v_sub_f32_e32 v137, v136, v137
	v_mul_f32_e32 v136, 0xbfb8aa3b, v23
	v_cndmask_b32_e64 v167, 0, 32, vcc
	v_exp_f32_e32 v136, v136
	v_ldexp_f32 v138, v138, v167
	v_log_f32_e32 v138, v138
	v_add_f32_e32 v136, 1.0, v136
	v_rcp_f32_e32 v136, v136
	v_mul_f32_e32 v167, 0x3f317217, v138
	v_fma_f32 v167, v138, s91, -v167
	v_fmac_f32_e32 v167, 0x3377d1cf, v138
	v_fmac_f32_e32 v167, 0x3f317217, v138
	v_cmp_lt_f32_e64 s[6:7], |v138|, s92
	v_fmac_f32_e32 v143, v136, v190
	s_nop 0
	v_cndmask_b32_e64 v138, v138, v167, s[6:7]
	v_cmp_gt_f32_e64 s[6:7], s90, v143
	v_cndmask_b32_e32 v167, 0, v186, vcc
	v_sub_f32_e32 v167, v138, v167
	v_cndmask_b32_e64 v136, 0, 32, s[6:7]
	v_ldexp_f32 v136, v143, v136
	v_mul_f32_e32 v143, 0xbfb8aa3b, v19
	v_exp_f32_e32 v143, v143
	v_log_f32_e32 v136, v136
	v_add_f32_e32 v143, 1.0, v143
	v_rcp_f32_e32 v143, v143
	v_mul_f32_e32 v138, 0x3f317217, v136
	v_fma_f32 v138, v136, s91, -v138
	v_fmac_f32_e32 v138, 0x3377d1cf, v136
	v_fmac_f32_e32 v139, v143, v191
	v_cmp_gt_f32_e32 vcc, s90, v139
	v_fmac_f32_e32 v138, 0x3f317217, v136
	v_cmp_lt_f32_e64 s[8:9], |v136|, s92
	v_cndmask_b32_e64 v143, 0, 32, vcc
	v_ldexp_f32 v139, v139, v143
	v_log_f32_e32 v139, v139
	v_cndmask_b32_e64 v136, v136, v138, s[8:9]
	v_cndmask_b32_e64 v138, 0, v186, s[6:7]
	v_sub_f32_e32 v138, v136, v138
	v_mul_f32_e32 v136, 0x3f317217, v139
	v_mul_f32_e32 v143, 0xbfb8aa3b, v4
	v_fma_f32 v136, v139, s91, -v136
	v_exp_f32_e32 v143, v143
	v_fmac_f32_e32 v136, 0x3377d1cf, v139
	v_fmac_f32_e32 v136, 0x3f317217, v139
	v_cmp_lt_f32_e64 s[6:7], |v139|, s92
	v_cvt_pk_f16_f32 v137, v137, v138
	v_cvt_pk_f16_f32 v138, v172, v142
	v_cndmask_b32_e64 v136, v139, v136, s[6:7]
	v_cndmask_b32_e32 v139, 0, v186, vcc
	v_sub_f32_e32 v139, v136, v139
	v_add_f32_e32 v136, 1.0, v143
	v_rcp_f32_e32 v143, v136
	v_cvt_pk_f16_f32 v136, v140, v141
	v_cvt_pk_f16_f32 v139, v167, v139
	global_store_dwordx4 v[170:171], v[136:139], off sc1
	v_fma_f32 v132, v143, v152, v132
	v_cmp_gt_f32_e32 vcc, s90, v132
	s_nop 1
	v_cndmask_b32_e64 v140, 0, 32, vcc
	v_ldexp_f32 v132, v132, v140
	v_mul_f32_e32 v140, 0xbfb8aa3b, v0
	v_exp_f32_e32 v140, v140
	v_log_f32_e32 v132, v132
	v_add_f32_e32 v137, 1.0, v140
	v_rcp_f32_e32 v137, v137
	v_mul_f32_e32 v136, 0x3f317217, v132
	v_fma_f32 v136, v132, s91, -v136
	v_fmac_f32_e32 v136, 0x3377d1cf, v132
	v_fma_f32 v128, v137, v192, v128
	v_cmp_gt_f32_e64 s[6:7], s90, v128
	v_fmac_f32_e32 v136, 0x3f317217, v132
	v_cmp_lt_f32_e64 s[8:9], |v132|, s92
	v_cndmask_b32_e64 v137, 0, 32, s[6:7]
	v_ldexp_f32 v128, v128, v137
	v_mul_f32_e32 v137, 0xbfb8aa3b, v5
	v_exp_f32_e32 v137, v137
	v_log_f32_e32 v128, v128
	v_cndmask_b32_e64 v132, v132, v136, s[8:9]
	v_cndmask_b32_e32 v136, 0, v186, vcc
	v_add_f32_e32 v137, 1.0, v137
	v_sub_f32_e32 v132, v132, v136
	v_mul_f32_e32 v136, 0x3f317217, v128
	v_rcp_f32_e32 v137, v137
	v_fma_f32 v136, v128, s91, -v136
	v_fmac_f32_e32 v136, 0x3377d1cf, v128
	v_fmac_f32_e32 v136, 0x3f317217, v128
	v_cmp_lt_f32_e64 vcc, |v128|, s92
	v_fma_f32 v133, v137, v193, v133
	s_nop 0
	v_cndmask_b32_e32 v128, v128, v136, vcc
	v_cndmask_b32_e64 v136, 0, v186, s[6:7]
	v_cmp_gt_f32_e32 vcc, s90, v133
	v_sub_f32_e32 v136, v128, v136
	v_mul_f32_e32 v128, 0xbfb8aa3b, v1
	v_cndmask_b32_e64 v137, 0, 32, vcc
	v_exp_f32_e32 v128, v128
	v_ldexp_f32 v133, v133, v137
	v_log_f32_e32 v133, v133
	v_add_f32_e32 v128, 1.0, v128
	v_rcp_f32_e32 v128, v128
	v_mul_f32_e32 v137, 0x3f317217, v133
	v_fma_f32 v137, v133, s91, -v137
	v_fmac_f32_e32 v137, 0x3377d1cf, v133
	v_fmac_f32_e32 v137, 0x3f317217, v133
	v_cmp_lt_f32_e64 s[6:7], |v133|, s92
	v_fma_f32 v128, v128, v195, v129
	s_nop 0
	v_cndmask_b32_e64 v133, v133, v137, s[6:7]
	v_cmp_gt_f32_e64 s[6:7], s90, v128
	v_cndmask_b32_e32 v137, 0, v186, vcc
	v_sub_f32_e32 v133, v133, v137
	v_cndmask_b32_e64 v129, 0, 32, s[6:7]
	v_ldexp_f32 v128, v128, v129
	v_mul_f32_e32 v129, 0xbfb8aa3b, v6
	v_exp_f32_e32 v129, v129
	v_log_f32_e32 v128, v128
	v_add_f32_e32 v129, 1.0, v129
	v_rcp_f32_e32 v129, v129
	v_mul_f32_e32 v137, 0x3f317217, v128
	v_fma_f32 v137, v128, s91, -v137
	v_fmac_f32_e32 v137, 0x3377d1cf, v128
	v_fma_f32 v129, v129, v197, v134
	v_fmac_f32_e32 v137, 0x3f317217, v128
	v_cmp_gt_f32_e32 vcc, s90, v129
	v_cmp_lt_f32_e64 s[8:9], |v128|, s92
	s_nop 0
	v_cndmask_b32_e64 v134, 0, 32, vcc
;     template <int MODE> __device__ __forceinline__ void run(const f32x4 (&acc)[2][2][4][2], u16* dst, int ld, int row0, int col0, int trow0, int wc, int fq, const float* lb) const {
;         f32x4 lb0[2], lb1[2];
;         if (MODE == 3) {
; #pragma unroll
;             for (int bj = 0; bj < 2; ++bj) { lb0[bj] = *(const f32x4*)(lb + col0 + bj * HALF); lb1[bj] = *(const f32x4*)(lb + col0 + bj * HALF + 4); }
;         }
; #pragma unroll
;         for (int ai = 0; ai < 2; ++ai)
; #pragma unroll
;             for (int m = 0; m < 4; ++m) {
;                 const int rr = ai * HALF + m * 16;
;                 u16* rowp = dst + (size_t)(row0 + rr) * ld + col0;
;                 f32x4 cs, sn;
;                 if (MODE == 1 || MODE == 2) { const int t = trow0 + rr; const int pos = (wc & 1) ? (t & 63) : (t >> 6);
;                     cs = *(const f32x4*)(rcos + pos * 16 + 4 * fq); sn = *(const f32x4*)(rsin + pos * 16 + 4 * fq); }
; #pragma unroll
;                 for (int bj = 0; bj < 2; ++bj) {
;                     f32x4 v0 = acc[ai][bj][m][0], v1 = acc[ai][bj][m][1];
;                     if (MODE == 1 || MODE == 2) { const f32x4 a = v0 * cs - v1 * sn, b = v1 * cs + v0 * sn; v0 = a; v1 = b;
;                         if (MODE == 2) { v0 = v0 * 0.18033688011112042f; v1 = v1 * 0.18033688011112042f; } }
;                     if (MODE == 3) {
; #pragma unroll
;                         for (int i = 0; i < 4; ++i) { const float l0 = lb0[bj][i], l1 = lb1[bj][i];
;                             v0[i] = __logf(l0 + (1.f - l0) * sigm(v0[i])); v1[i] = __logf(l1 + (1.f - l1) * sigm(v1[i])); }
;                     }
;                     if (MODE == 4) {
; #pragma unroll
;                         for (int i = 0; i < 4; ++i) { v0[i] = silu_(v0[i]); v1[i] = silu_(v1[i]); }
;                     }
;                     if (MODE == 5) {
; #pragma unroll
;                         for (int i = 0; i < 4; ++i) { v0[i] = sigm(v0[i]); v1[i] = sigm(v1[i]); }
;                     }
;                     u32x4 w;
;                     if (MODE == 3) { w.x = cvtpk_h(v0[0], v0[1]); w.y = cvtpk_h(v0[2], v0[3]); w.z = cvtpk_h(v1[0], v1[1]); w.w = cvtpk_h(v1[2], v1[3]); }
;                     else { w.x = cvtpk(v0[0], v0[1]); w.y = cvtpk(v0[2], v0[3]); w.z = cvtpk(v1[0], v1[1]); w.w = cvtpk(v1[2], v1[3]); }
;                     *(u32x4*)(rowp + bj * HALF) = w;
	v_cndmask_b32_e64 v128, v128, v137, s[8:9]
	v_mul_f32_e32 v137, 0xbfb8aa3b, v2
	v_ldexp_f32 v129, v129, v134
	v_exp_f32_e32 v137, v137
	v_log_f32_e32 v129, v129
	v_cndmask_b32_e64 v134, 0, v186, s[6:7]
	v_sub_f32_e32 v134, v128, v134
	v_add_f32_e32 v137, 1.0, v137
	v_mul_f32_e32 v128, 0x3f317217, v129
	v_rcp_f32_e32 v137, v137
	v_fma_f32 v128, v129, s91, -v128
	v_fmac_f32_e32 v128, 0x3377d1cf, v129
	v_fmac_f32_e32 v128, 0x3f317217, v129
	v_cmp_lt_f32_e64 s[6:7], |v129|, s92
	v_fma_f32 v130, v137, v196, v130
	s_nop 0
	v_cndmask_b32_e64 v128, v129, v128, s[6:7]
	v_cndmask_b32_e32 v129, 0, v186, vcc
	v_cmp_gt_f32_e32 vcc, s90, v130
	v_sub_f32_e32 v129, v128, v129
	v_mul_f32_e32 v128, 0xbfb8aa3b, v7
	v_cndmask_b32_e64 v137, 0, 32, vcc
	v_exp_f32_e32 v128, v128
	v_ldexp_f32 v130, v130, v137
	v_log_f32_e32 v130, v130
	v_add_f32_e32 v128, 1.0, v128
	v_rcp_f32_e32 v128, v128
	v_mul_f32_e32 v137, 0x3f317217, v130
	v_fma_f32 v137, v130, s91, -v137
	v_fmac_f32_e32 v137, 0x3377d1cf, v130
	v_fmac_f32_e32 v137, 0x3f317217, v130
	v_cmp_lt_f32_e64 s[6:7], |v130|, s92
	v_fmac_f32_e32 v135, v128, v198
	s_nop 0
	v_cndmask_b32_e64 v130, v130, v137, s[6:7]
	v_cmp_gt_f32_e64 s[6:7], s90, v135
	v_cndmask_b32_e32 v137, 0, v186, vcc
	v_sub_f32_e32 v137, v130, v137
	v_cndmask_b32_e64 v128, 0, 32, s[6:7]
	v_ldexp_f32 v128, v135, v128
	v_mul_f32_e32 v135, 0xbfb8aa3b, v3
	v_exp_f32_e32 v135, v135
	v_log_f32_e32 v128, v128
	v_add_f32_e32 v135, 1.0, v135
	v_rcp_f32_e32 v135, v135
	v_mul_f32_e32 v130, 0x3f317217, v128
	v_fma_f32 v130, v128, s91, -v130
	v_fmac_f32_e32 v130, 0x3377d1cf, v128
	v_fmac_f32_e32 v131, v135, v199
	v_cmp_gt_f32_e32 vcc, s90, v131
	v_fmac_f32_e32 v130, 0x3f317217, v128
	v_cmp_lt_f32_e64 s[8:9], |v128|, s92
	v_cndmask_b32_e64 v135, 0, 32, vcc
	v_ldexp_f32 v131, v131, v135
	v_log_f32_e32 v131, v131
	v_cndmask_b32_e64 v128, v128, v130, s[8:9]
	v_cndmask_b32_e64 v130, 0, v186, s[6:7]
	v_sub_f32_e32 v130, v128, v130
	v_mul_f32_e32 v128, 0x3f317217, v131
	v_fma_f32 v128, v131, s91, -v128
	v_fmac_f32_e32 v128, 0x3377d1cf, v131
	v_fmac_f32_e32 v128, 0x3f317217, v131
	v_cmp_lt_f32_e64 s[6:7], |v131|, s92
	v_cvt_pk_f16_f32 v129, v129, v130
	v_cvt_pk_f16_f32 v130, v136, v134
	v_cndmask_b32_e64 v128, v131, v128, s[6:7]
	v_cndmask_b32_e32 v131, 0, v186, vcc
	v_sub_f32_e32 v131, v128, v131
	v_cvt_pk_f16_f32 v128, v132, v133
	v_cvt_pk_f16_f32 v131, v137, v131
	s_mov_b64 s[6:7], 0
.LBB0_199:
	s_andn2_b64 vcc, exec, s[6:7]
	s_cbranch_vccnz .LBB0_201
	global_load_dwordx4 v[132:135], v169, s[38:39] offset:512
	global_load_dwordx4 v[140:143], v169, s[38:39]
	global_load_dwordx4 v[136:139], v169, s[38:39] offset:16
	global_load_dwordx4 v[128:131], v169, s[38:39] offset:528
	v_lshlrev_b32_e32 v152, 1, v187
	v_mul_f32_e32 v169, 0xbfb8aa3b, v124
	v_ashrrev_i32_e32 v167, 31, v166
	v_mul_f32_e32 v188, 0xbfb8aa3b, v120
	v_lshl_add_u64 v[170:171], s[24:25], 0, v[152:153]
	v_exp_f32_e32 v152, v169
	v_mul_f32_e32 v189, 0xbfb8aa3b, v125
	v_lshlrev_b64 v[172:173], 11, v[166:167]
	v_exp_f32_e32 v167, v188
	v_mul_f32_e32 v190, 0xbfb8aa3b, v121
	v_exp_f32_e32 v169, v189
	v_exp_f32_e32 v188, v190
	v_mul_f32_e32 v191, 0xbfb8aa3b, v126
	v_add_f32_e32 v152, 1.0, v152
	v_mul_f32_e32 v192, 0xbfb8aa3b, v122
	v_exp_f32_e32 v189, v191
	v_add_f32_e32 v167, 1.0, v167
	v_rcp_f32_e32 v191, v152
	v_exp_f32_e32 v190, v192
	v_add_f32_e32 v169, 1.0, v169
	v_rcp_f32_e32 v192, v167
	v_add_f32_e32 v188, 1.0, v188
	v_rcp_f32_e32 v193, v169
	v_rcp_f32_e32 v188, v188
	v_add_f32_e32 v189, 1.0, v189
	v_rcp_f32_e32 v189, v189
	v_lshl_add_u64 v[172:173], v[170:171], 0, v[172:173]
	s_waitcnt vmcnt(0)
	v_sub_f32_e32 v152, 1.0, v132
	v_sub_f32_e32 v201, 1.0, v140
	v_sub_f32_e32 v200, 1.0, v136
	v_fma_f32 v191, v191, v201, v140
	v_sub_f32_e32 v199, 1.0, v141
	v_fma_f32 v192, v192, v200, v136
	v_cmp_gt_f32_e32 vcc, s90, v191
	v_sub_f32_e32 v169, 1.0, v137
	v_fma_f32 v193, v193, v199, v141
	v_cndmask_b32_e64 v195, 0, 32, vcc
	v_cmp_gt_f32_e64 s[6:7], s90, v192
	v_fma_f32 v188, v188, v169, v137
	v_cmp_gt_f32_e64 s[8:9], s90, v193
	v_cndmask_b32_e64 v196, 0, 32, s[6:7]
	v_ldexp_f32 v191, v191, v195
	v_sub_f32_e32 v167, 1.0, v142
	v_cndmask_b32_e64 v197, 0, 32, s[8:9]
	v_cmp_gt_f32_e64 s[10:11], s90, v188
	v_ldexp_f32 v192, v192, v196
	v_log_f32_e32 v191, v191
	v_fma_f32 v189, v189, v167, v142
	v_cndmask_b32_e64 v198, 0, 32, s[10:11]
	v_ldexp_f32 v193, v193, v197
	v_log_f32_e32 v192, v192
	v_cmp_gt_f32_e64 s[12:13], s90, v189
	v_ldexp_f32 v188, v188, v198
	v_log_f32_e32 v193, v193
	v_cndmask_b32_e64 v202, 0, 32, s[12:13]
	v_log_f32_e32 v188, v188
	v_ldexp_f32 v189, v189, v202
	v_mul_f32_e32 v202, 0x3f317217, v191
	v_mul_f32_e32 v203, 0x3f317217, v192
	v_fma_f32 v202, v191, s91, -v202
	v_mul_f32_e32 v204, 0x3f317217, v193
	v_fma_f32 v203, v192, s91, -v203
	v_fmac_f32_e32 v202, 0x3377d1cf, v191
	v_cndmask_b32_e32 v195, 0, v186, vcc
	v_mul_f32_e32 v205, 0x3f317217, v188
	v_fma_f32 v204, v193, s91, -v204
	v_fmac_f32_e32 v203, 0x3377d1cf, v192
	v_fmac_f32_e32 v202, 0x3f317217, v191
	v_cmp_lt_f32_e64 vcc, |v191|, s92
	v_log_f32_e32 v189, v189
	v_fma_f32 v205, v188, s91, -v205
	v_fmac_f32_e32 v204, 0x3377d1cf, v193
	v_fmac_f32_e32 v203, 0x3f317217, v192
	v_cndmask_b32_e32 v191, v191, v202, vcc
	v_cmp_lt_f32_e64 vcc, |v192|, s92
	v_fmac_f32_e32 v205, 0x3377d1cf, v188
	v_fmac_f32_e32 v204, 0x3f317217, v193
	v_cndmask_b32_e32 v192, v192, v203, vcc
	v_cmp_lt_f32_e64 vcc, |v193|, s92
	v_fmac_f32_e32 v205, 0x3f317217, v188
	v_cndmask_b32_e64 v198, 0, v186, s[10:11]
	v_cndmask_b32_e32 v193, v193, v204, vcc
	v_cmp_lt_f32_e64 vcc, |v188|, s92
	v_cndmask_b32_e64 v196, 0, v186, s[6:7]
	v_sub_f32_e32 v191, v191, v195
; DI unsigned cvtpk(float lo, float hi) { f32x2 v = {lo, hi}; bf16x2_t b = __builtin_convertvector(v, bf16x2_t); return __builtin_bit_cast(unsigned, b); }
; DI unsigned cvtpk_h(float lo, float hi) { f32x2 v = {lo, hi}; h16x2_t b = __builtin_convertvector(v, h16x2_t); return __builtin_bit_cast(unsigned, b); }
; DI float sigm(float x) { return __builtin_amdgcn_rcpf(1.f + fexp(-x)); }
; DI float silu_(float x) { return x * sigm(x); }
;     template <int MODE> __device__ __forceinline__ void run(const f32x4 (&acc)[2][2][4][2], u16* dst, int ld, int row0, int col0, int trow0, int wc, int fq, const float* lb) const {
;     ...
;                         for (int i = 0; i < 4; ++i) { const float l0 = lb0[bj][i], l1 = lb1[bj][i];
;                             v0[i] = __logf(l0 + (1.f - l0) * sigm(v0[i])); v1[i] = __logf(l1 + (1.f - l1) * sigm(v1[i])); }
;                     }
;                     if (MODE == 4) {
; #pragma unroll
;                         for (int i = 0; i < 4; ++i) { v0[i] = silu_(v0[i]); v1[i] = silu_(v1[i]); }
;                     }
;                     if (MODE == 5) {
; #pragma unroll
;                         for (int i = 0; i < 4; ++i) { v0[i] = sigm(v0[i]); v1[i] = sigm(v1[i]); }
;                     }
;                     u32x4 w;
;                     if (MODE == 3) { w.x = cvtpk_h(v0[0], v0[1]); w.y = cvtpk_h(v0[2], v0[3]); w.z = cvtpk_h(v1[0], v1[1]); w.w = cvtpk_h(v1[2], v1[3]); }
;                     else { w.x = cvtpk(v0[0], v0[1]); w.y = cvtpk(v0[2], v0[3]); w.z = cvtpk(v1[0], v1[1]); w.w = cvtpk(v1[2], v1[3]); }
;                     *(u32x4*)(rowp + bj * HALF) = w;
	v_cndmask_b32_e32 v188, v188, v205, vcc
	v_sub_f32_e32 v195, v188, v198
	v_mul_f32_e32 v188, 0x3f317217, v189
	v_sub_f32_e32 v192, v192, v196
	v_fma_f32 v196, v189, s91, -v188
	v_add_f32_e32 v188, 1.0, v190
	v_rcp_f32_e32 v190, v188
	v_sub_f32_e32 v188, 1.0, v138
	v_cndmask_b32_e64 v197, 0, v186, s[8:9]
	v_sub_f32_e32 v193, v193, v197
	v_fma_f32 v190, v190, v188, v138
	v_cmp_gt_f32_e32 vcc, s90, v190
	v_fmac_f32_e32 v196, 0x3377d1cf, v189
	v_fmac_f32_e32 v196, 0x3f317217, v189
	v_cndmask_b32_e64 v197, 0, 32, vcc
	v_ldexp_f32 v190, v190, v197
	v_mul_f32_e32 v197, 0xbfb8aa3b, v127
	v_log_f32_e32 v190, v190
	v_exp_f32_e32 v197, v197
	v_cmp_lt_f32_e64 s[6:7], |v189|, s92
	v_cndmask_b32_e32 v198, 0, v186, vcc
	v_add_f32_e32 v197, 1.0, v197
	v_cndmask_b32_e64 v189, v189, v196, s[6:7]
	v_cndmask_b32_e64 v196, 0, v186, s[12:13]
	v_sub_f32_e32 v196, v189, v196
	v_mul_f32_e32 v189, 0x3f317217, v190
	v_fma_f32 v189, v190, s91, -v189
	v_rcp_f32_e32 v197, v197
	v_fmac_f32_e32 v189, 0x3377d1cf, v190
	v_fmac_f32_e32 v189, 0x3f317217, v190
	v_cmp_lt_f32_e64 s[6:7], |v190|, s92
	s_nop 1
	v_cndmask_b32_e64 v190, v190, v189, s[6:7]
	v_sub_f32_e32 v189, 1.0, v143
	v_fma_f32 v197, v197, v189, v143
	v_cmp_gt_f32_e32 vcc, s90, v197
	v_sub_f32_e32 v198, v190, v198
	s_nop 0
	v_cndmask_b32_e64 v202, 0, 32, vcc
	v_ldexp_f32 v197, v197, v202
	v_log_f32_e32 v197, v197
	v_mul_f32_e32 v202, 0xbfb8aa3b, v123
	v_exp_f32_e32 v202, v202
	v_mul_f32_e32 v190, 0x3f317217, v197
	v_fma_f32 v203, v197, s91, -v190
	v_add_f32_e32 v190, 1.0, v202
	v_rcp_f32_e32 v202, v190
	v_sub_f32_e32 v190, 1.0, v139
	v_fmac_f32_e32 v203, 0x3377d1cf, v197
	v_fmac_f32_e32 v203, 0x3f317217, v197
	v_fma_f32 v202, v202, v190, v139
	v_cmp_gt_f32_e64 s[6:7], s90, v202
	v_cmp_lt_f32_e64 s[8:9], |v197|, s92
	s_nop 0
	v_cndmask_b32_e64 v204, 0, 32, s[6:7]
	v_ldexp_f32 v202, v202, v204
	v_log_f32_e32 v202, v202
	v_cndmask_b32_e64 v197, v197, v203, s[8:9]
	v_cndmask_b32_e32 v203, 0, v186, vcc
	v_sub_f32_e32 v197, v197, v203
	v_mul_f32_e32 v203, 0x3f317217, v202
	v_fma_f32 v203, v202, s91, -v203
	v_fmac_f32_e32 v203, 0x3377d1cf, v202
	v_fmac_f32_e32 v203, 0x3f317217, v202
	v_cmp_lt_f32_e64 vcc, |v202|, s92
	v_cndmask_b32_e64 v204, 0, v186, s[6:7]
	s_nop 0
	v_cndmask_b32_e32 v202, v202, v203, vcc
	v_mul_f32_e32 v203, 0xbfb8aa3b, v108
	v_exp_f32_e32 v203, v203
	v_sub_f32_e32 v205, v202, v204
	v_cvt_pk_f16_f32 v202, v191, v193
	v_cvt_pk_f16_f32 v204, v192, v195
	v_add_f32_e32 v191, 1.0, v203
	v_rcp_f32_e32 v191, v191
	v_cvt_pk_f16_f32 v203, v196, v197
	v_cvt_pk_f16_f32 v205, v198, v205
	global_store_dwordx4 v[172:173], v[202:205], off sc1
	v_fma_f32 v191, v191, v152, v132
	v_cmp_gt_f32_e32 vcc, s90, v191
	s_nop 1
	v_cndmask_b32_e64 v192, 0, 32, vcc
	v_ldexp_f32 v191, v191, v192
	v_log_f32_e32 v192, v191
	v_mul_f32_e32 v191, 0xbfb8aa3b, v104
	v_exp_f32_e32 v191, v191
	v_mul_f32_e32 v193, 0x3f317217, v192
	v_fma_f32 v193, v192, s91, -v193
	v_add_f32_e32 v191, 1.0, v191
	v_rcp_f32_e32 v195, v191
	v_sub_f32_e32 v191, 1.0, v128
	v_fmac_f32_e32 v193, 0x3377d1cf, v192
	v_fmac_f32_e32 v193, 0x3f317217, v192
	v_fma_f32 v195, v195, v191, v128
	v_cmp_gt_f32_e64 s[6:7], s90, v195
	v_cmp_lt_f32_e64 s[8:9], |v192|, s92
	s_nop 0
	v_cndmask_b32_e64 v196, 0, 32, s[6:7]
	v_cndmask_b32_e64 v192, v192, v193, s[8:9]
	v_cndmask_b32_e32 v193, 0, v186, vcc
	v_ldexp_f32 v195, v195, v196
	v_sub_f32_e32 v202, v192, v193
	v_mul_f32_e32 v193, 0xbfb8aa3b, v109
	v_log_f32_e32 v195, v195
	v_exp_f32_e32 v193, v193
	v_cndmask_b32_e64 v196, 0, v186, s[6:7]
	v_mul_f32_e32 v192, 0x3f317217, v195
	v_add_f32_e32 v193, 1.0, v193
	v_fma_f32 v192, v195, s91, -v192
	v_rcp_f32_e32 v193, v193
	v_fmac_f32_e32 v192, 0x3377d1cf, v195
	v_fmac_f32_e32 v192, 0x3f317217, v195
	v_cmp_lt_f32_e64 vcc, |v195|, s92
	s_nop 1
	v_cndmask_b32_e32 v195, v195, v192, vcc
	v_sub_f32_e32 v192, 1.0, v133
	v_fma_f32 v193, v193, v192, v133
	v_cmp_gt_f32_e32 vcc, s90, v193
	v_sub_f32_e32 v204, v195, v196
	s_nop 0
	v_cndmask_b32_e64 v197, 0, 32, vcc
	v_ldexp_f32 v193, v193, v197
	v_log_f32_e32 v197, v193
	v_mul_f32_e32 v193, 0xbfb8aa3b, v105
	v_exp_f32_e32 v193, v193
	v_mul_f32_e32 v195, 0x3f317217, v197
	v_fma_f32 v195, v197, s91, -v195
	v_add_f32_e32 v193, 1.0, v193
	v_rcp_f32_e32 v196, v193
	v_sub_f32_e32 v193, 1.0, v129
	v_fmac_f32_e32 v195, 0x3377d1cf, v197
	v_fmac_f32_e32 v195, 0x3f317217, v197
	v_fma_f32 v196, v196, v193, v129
	v_cmp_gt_f32_e64 s[6:7], s90, v196
	v_cmp_lt_f32_e64 s[8:9], |v197|, s92
	s_nop 0
	v_cndmask_b32_e64 v198, 0, 32, s[6:7]
	v_cndmask_b32_e64 v195, v197, v195, s[8:9]
	v_cndmask_b32_e32 v197, 0, v186, vcc
	v_ldexp_f32 v196, v196, v198
	v_sub_f32_e32 v203, v195, v197
	v_mul_f32_e32 v197, 0xbfb8aa3b, v110
	v_log_f32_e32 v196, v196
	v_exp_f32_e32 v197, v197
	v_cndmask_b32_e64 v198, 0, v186, s[6:7]
	v_cvt_pk_f16_f32 v202, v202, v203
	v_mul_f32_e32 v195, 0x3f317217, v196
	v_add_f32_e32 v197, 1.0, v197
	v_fma_f32 v195, v196, s91, -v195
	v_rcp_f32_e32 v197, v197
	v_fmac_f32_e32 v195, 0x3377d1cf, v196
	v_fmac_f32_e32 v195, 0x3f317217, v196
	v_cmp_lt_f32_e64 vcc, |v196|, s92
	v_mul_f32_e32 v203, 0xbfb8aa3b, v116
	s_nop 0
	v_cndmask_b32_e32 v195, v196, v195, vcc
	v_sub_f32_e32 v196, 1.0, v134
	v_fma_f32 v197, v197, v196, v134
	v_cmp_gt_f32_e32 vcc, s90, v197
	v_sub_f32_e32 v206, v195, v198
	v_cvt_pk_f16_f32 v204, v204, v206
	v_cndmask_b32_e64 v205, 0, 32, vcc
	v_ldexp_f32 v197, v197, v205
	v_log_f32_e32 v197, v197
	v_mul_f32_e32 v205, 0xbfb8aa3b, v106
	v_exp_f32_e32 v205, v205
	v_mul_f32_e32 v195, 0x3f317217, v197
	v_fma_f32 v198, v197, s91, -v195
	v_add_f32_e32 v195, 1.0, v205
	v_rcp_f32_e32 v205, v195
	v_sub_f32_e32 v195, 1.0, v130
	v_fmac_f32_e32 v198, 0x3377d1cf, v197
; DI unsigned cvtpk(float lo, float hi) { f32x2 v = {lo, hi}; bf16x2_t b = __builtin_convertvector(v, bf16x2_t); return __builtin_bit_cast(unsigned, b); }
; DI unsigned cvtpk_h(float lo, float hi) { f32x2 v = {lo, hi}; h16x2_t b = __builtin_convertvector(v, h16x2_t); return __builtin_bit_cast(unsigned, b); }
; DI float sigm(float x) { return __builtin_amdgcn_rcpf(1.f + fexp(-x)); }
; DI float silu_(float x) { return x * sigm(x); }
;     template <int MODE> __device__ __forceinline__ void run(const f32x4 (&acc)[2][2][4][2], u16* dst, int ld, int row0, int col0, int trow0, int wc, int fq, const float* lb) const {
;     ...
;                         for (int i = 0; i < 4; ++i) { const float l0 = lb0[bj][i], l1 = lb1[bj][i];
;                             v0[i] = __logf(l0 + (1.f - l0) * sigm(v0[i])); v1[i] = __logf(l1 + (1.f - l1) * sigm(v1[i])); }
;                     }
;                     if (MODE == 4) {
; #pragma unroll
;                         for (int i = 0; i < 4; ++i) { v0[i] = silu_(v0[i]); v1[i] = silu_(v1[i]); }
;                     }
;                     if (MODE == 5) {
; #pragma unroll
;                         for (int i = 0; i < 4; ++i) { v0[i] = sigm(v0[i]); v1[i] = sigm(v1[i]); }
;                     }
;                     u32x4 w;
;                     if (MODE == 3) { w.x = cvtpk_h(v0[0], v0[1]); w.y = cvtpk_h(v0[2], v0[3]); w.z = cvtpk_h(v1[0], v1[1]); w.w = cvtpk_h(v1[2], v1[3]); }
;                     else { w.x = cvtpk(v0[0], v0[1]); w.y = cvtpk(v0[2], v0[3]); w.z = cvtpk(v1[0], v1[1]); w.w = cvtpk(v1[2], v1[3]); }
;                     *(u32x4*)(rowp + bj * HALF) = w;
	v_fmac_f32_e32 v198, 0x3f317217, v197
	v_fma_f32 v205, v205, v195, v130
	v_cmp_gt_f32_e64 s[6:7], s90, v205
	v_cmp_lt_f32_e64 s[8:9], |v197|, s92
	s_nop 0
	v_cndmask_b32_e64 v207, 0, 32, s[6:7]
	v_cndmask_b32_e64 v197, v197, v198, s[8:9]
	v_cndmask_b32_e32 v198, 0, v186, vcc
	v_ldexp_f32 v205, v205, v207
	v_sub_f32_e32 v207, v197, v198
	v_mul_f32_e32 v198, 0xbfb8aa3b, v111
	v_log_f32_e32 v205, v205
	v_exp_f32_e32 v198, v198
	v_cndmask_b32_e64 v208, 0, v186, s[6:7]
	v_mul_f32_e32 v197, 0x3f317217, v205
	v_add_f32_e32 v198, 1.0, v198
	v_fma_f32 v197, v205, s91, -v197
	v_rcp_f32_e32 v198, v198
	v_fmac_f32_e32 v197, 0x3377d1cf, v205
	v_fmac_f32_e32 v197, 0x3f317217, v205
	v_cmp_lt_f32_e64 vcc, |v205|, s92
	s_nop 1
	v_cndmask_b32_e32 v205, v205, v197, vcc
	v_sub_f32_e32 v197, 1.0, v135
	v_fma_f32 v198, v198, v197, v135
	v_cmp_gt_f32_e32 vcc, s90, v198
	v_sub_f32_e32 v205, v205, v208
	s_nop 0
	v_cndmask_b32_e64 v209, 0, 32, vcc
	v_ldexp_f32 v198, v198, v209
	v_log_f32_e32 v209, v198
	v_mul_f32_e32 v198, 0xbfb8aa3b, v107
	v_exp_f32_e32 v198, v198
	v_mul_f32_e32 v208, 0x3f317217, v209
	v_fma_f32 v208, v209, s91, -v208
	v_add_f32_e32 v198, 1.0, v198
	v_rcp_f32_e32 v210, v198
	v_sub_f32_e32 v198, 1.0, v131
	v_fmac_f32_e32 v208, 0x3377d1cf, v209
	v_fmac_f32_e32 v208, 0x3f317217, v209
	v_fma_f32 v210, v210, v198, v131
	v_cmp_gt_f32_e64 s[6:7], s90, v210
	v_cmp_lt_f32_e64 s[8:9], |v209|, s92
	s_nop 0
	v_cndmask_b32_e64 v211, 0, 32, s[6:7]
	v_ldexp_f32 v210, v210, v211
	v_log_f32_e32 v210, v210
	v_cndmask_b32_e64 v208, v209, v208, s[8:9]
	v_cndmask_b32_e32 v209, 0, v186, vcc
	v_sub_f32_e32 v208, v208, v209
	v_mul_f32_e32 v209, 0x3f317217, v210
	v_fma_f32 v209, v210, s91, -v209
	v_fmac_f32_e32 v209, 0x3377d1cf, v210
	v_fmac_f32_e32 v209, 0x3f317217, v210
	v_cmp_lt_f32_e64 vcc, |v210|, s92
	s_nop 1
	v_cndmask_b32_e32 v209, v210, v209, vcc
	v_cndmask_b32_e64 v210, 0, v186, s[6:7]
	v_sub_f32_e32 v209, v209, v210
	v_exp_f32_e32 v210, v203
	v_cvt_pk_f16_f32 v203, v207, v208
	v_cvt_pk_f16_f32 v205, v205, v209
	global_store_dwordx4 v[172:173], v[202:205], off offset:256 sc1
	v_add_f32_e32 v206, 1.0, v210
	v_rcp_f32_e32 v206, v206
	v_or_b32_e32 v172, 16, v166
	v_ashrrev_i32_e32 v173, 31, v172
	v_lshlrev_b64 v[172:173], 11, v[172:173]
	v_fma_f32 v202, v206, v201, v140
	v_cmp_gt_f32_e32 vcc, s90, v202
	v_lshl_add_u64 v[172:173], v[170:171], 0, v[172:173]
	s_nop 0
	v_cndmask_b32_e64 v203, 0, 32, vcc
	v_ldexp_f32 v202, v202, v203
	v_mul_f32_e32 v203, 0xbfb8aa3b, v112
	v_exp_f32_e32 v203, v203
	v_log_f32_e32 v202, v202
	v_add_f32_e32 v203, 1.0, v203
	v_rcp_f32_e32 v203, v203
	v_mul_f32_e32 v204, 0x3f317217, v202
	v_fma_f32 v204, v202, s91, -v204
	v_fmac_f32_e32 v204, 0x3377d1cf, v202
	v_fma_f32 v203, v203, v200, v136
	v_cmp_gt_f32_e64 s[6:7], s90, v203
	v_fmac_f32_e32 v204, 0x3f317217, v202
	v_cmp_lt_f32_e64 s[8:9], |v202|, s92
	v_cndmask_b32_e64 v205, 0, 32, s[6:7]
	v_ldexp_f32 v203, v203, v205
	v_mul_f32_e32 v205, 0xbfb8aa3b, v117
	v_exp_f32_e32 v205, v205
	v_log_f32_e32 v203, v203
	v_cndmask_b32_e64 v202, v202, v204, s[8:9]
	v_cndmask_b32_e32 v204, 0, v186, vcc
	v_add_f32_e32 v205, 1.0, v205
	v_sub_f32_e32 v202, v202, v204
	v_mul_f32_e32 v204, 0x3f317217, v203
	v_rcp_f32_e32 v205, v205
	v_fma_f32 v204, v203, s91, -v204
	v_fmac_f32_e32 v204, 0x3377d1cf, v203
	v_fmac_f32_e32 v204, 0x3f317217, v203
	v_cmp_lt_f32_e64 vcc, |v203|, s92
	v_fma_f32 v205, v205, v199, v141
	s_nop 0
	v_cndmask_b32_e32 v203, v203, v204, vcc
	v_cndmask_b32_e64 v204, 0, v186, s[6:7]
	v_cmp_gt_f32_e32 vcc, s90, v205
	v_sub_f32_e32 v204, v203, v204
	v_mul_f32_e32 v203, 0xbfb8aa3b, v113
	v_cndmask_b32_e64 v206, 0, 32, vcc
	v_exp_f32_e32 v203, v203
	v_ldexp_f32 v205, v205, v206
	v_log_f32_e32 v205, v205
	v_cndmask_b32_e32 v207, 0, v186, vcc
	v_add_f32_e32 v203, 1.0, v203
	v_rcp_f32_e32 v203, v203
	v_mul_f32_e32 v206, 0x3f317217, v205
	v_fma_f32 v206, v205, s91, -v206
	v_fmac_f32_e32 v206, 0x3377d1cf, v205
	v_fmac_f32_e32 v206, 0x3f317217, v205
	v_cmp_lt_f32_e64 s[6:7], |v205|, s92
	v_fma_f32 v203, v203, v169, v137
	s_nop 0
	v_cndmask_b32_e64 v205, v205, v206, s[6:7]
	v_cmp_gt_f32_e64 s[6:7], s90, v203
	v_sub_f32_e32 v205, v205, v207
	v_cvt_pk_f16_f32 v202, v202, v205
	v_cndmask_b32_e64 v206, 0, 32, s[6:7]
	v_ldexp_f32 v203, v203, v206
	v_mul_f32_e32 v206, 0xbfb8aa3b, v118
	v_exp_f32_e32 v206, v206
	v_log_f32_e32 v203, v203
	v_add_f32_e32 v206, 1.0, v206
	v_rcp_f32_e32 v206, v206
	v_mul_f32_e32 v207, 0x3f317217, v203
	v_fma_f32 v207, v203, s91, -v207
	v_fmac_f32_e32 v207, 0x3377d1cf, v203
	v_fma_f32 v206, v206, v167, v142
	v_cmp_gt_f32_e32 vcc, s90, v206
	v_fmac_f32_e32 v207, 0x3f317217, v203
	v_cmp_lt_f32_e64 s[8:9], |v203|, s92
	v_cndmask_b32_e64 v208, 0, 32, vcc
	v_ldexp_f32 v206, v206, v208
	v_mul_f32_e32 v208, 0xbfb8aa3b, v114
	v_exp_f32_e32 v208, v208
	v_log_f32_e32 v206, v206
	v_cndmask_b32_e64 v203, v203, v207, s[8:9]
	v_cndmask_b32_e64 v207, 0, v186, s[6:7]
	v_add_f32_e32 v208, 1.0, v208
	v_sub_f32_e32 v207, v203, v207
	v_mul_f32_e32 v203, 0x3f317217, v206
	v_rcp_f32_e32 v208, v208
	v_fma_f32 v203, v206, s91, -v203
	v_fmac_f32_e32 v203, 0x3377d1cf, v206
	v_fmac_f32_e32 v203, 0x3f317217, v206
	v_cmp_lt_f32_e64 s[6:7], |v206|, s92
	v_fma_f32 v208, v208, v188, v138
	v_cvt_pk_f16_f32 v204, v204, v207
	v_cndmask_b32_e64 v203, v206, v203, s[6:7]
	v_cndmask_b32_e32 v206, 0, v186, vcc
	v_cmp_gt_f32_e32 vcc, s90, v208
	v_sub_f32_e32 v203, v203, v206
	v_mul_f32_e32 v206, 0xbfb8aa3b, v119
	v_cndmask_b32_e64 v209, 0, 32, vcc
	v_exp_f32_e32 v206, v206
	v_ldexp_f32 v208, v208, v209
	v_log_f32_e32 v208, v208
	v_cndmask_b32_e32 v210, 0, v186, vcc
	v_add_f32_e32 v206, 1.0, v206
	v_rcp_f32_e32 v206, v206
; DI unsigned cvtpk(float lo, float hi) { f32x2 v = {lo, hi}; bf16x2_t b = __builtin_convertvector(v, bf16x2_t); return __builtin_bit_cast(unsigned, b); }
; DI unsigned cvtpk_h(float lo, float hi) { f32x2 v = {lo, hi}; h16x2_t b = __builtin_convertvector(v, h16x2_t); return __builtin_bit_cast(unsigned, b); }
; DI float sigm(float x) { return __builtin_amdgcn_rcpf(1.f + fexp(-x)); }
; DI float silu_(float x) { return x * sigm(x); }
;     template <int MODE> __device__ __forceinline__ void run(const f32x4 (&acc)[2][2][4][2], u16* dst, int ld, int row0, int col0, int trow0, int wc, int fq, const float* lb) const {
;     ...
;                         for (int i = 0; i < 4; ++i) { const float l0 = lb0[bj][i], l1 = lb1[bj][i];
;                             v0[i] = __logf(l0 + (1.f - l0) * sigm(v0[i])); v1[i] = __logf(l1 + (1.f - l1) * sigm(v1[i])); }
;                     }
;                     if (MODE == 4) {
; #pragma unroll
;                         for (int i = 0; i < 4; ++i) { v0[i] = silu_(v0[i]); v1[i] = silu_(v1[i]); }
;                     }
;                     if (MODE == 5) {
; #pragma unroll
;                         for (int i = 0; i < 4; ++i) { v0[i] = sigm(v0[i]); v1[i] = sigm(v1[i]); }
;                     }
;                     u32x4 w;
;                     if (MODE == 3) { w.x = cvtpk_h(v0[0], v0[1]); w.y = cvtpk_h(v0[2], v0[3]); w.z = cvtpk_h(v1[0], v1[1]); w.w = cvtpk_h(v1[2], v1[3]); }
;                     else { w.x = cvtpk(v0[0], v0[1]); w.y = cvtpk(v0[2], v0[3]); w.z = cvtpk(v1[0], v1[1]); w.w = cvtpk(v1[2], v1[3]); }
;                     *(u32x4*)(rowp + bj * HALF) = w;
	v_mul_f32_e32 v209, 0x3f317217, v208
	v_fma_f32 v209, v208, s91, -v209
	v_fmac_f32_e32 v209, 0x3377d1cf, v208
	v_fmac_f32_e32 v209, 0x3f317217, v208
	v_cmp_lt_f32_e64 s[6:7], |v208|, s92
	v_fma_f32 v206, v206, v189, v143
	s_nop 0
	v_cndmask_b32_e64 v208, v208, v209, s[6:7]
	v_cmp_gt_f32_e64 s[6:7], s90, v206
	v_sub_f32_e32 v208, v208, v210
	s_nop 0
	v_cndmask_b32_e64 v209, 0, 32, s[6:7]
	v_ldexp_f32 v206, v206, v209
	v_mul_f32_e32 v209, 0xbfb8aa3b, v115
	v_exp_f32_e32 v209, v209
	v_log_f32_e32 v206, v206
	v_add_f32_e32 v209, 1.0, v209
	v_rcp_f32_e32 v209, v209
	v_mul_f32_e32 v210, 0x3f317217, v206
	v_fma_f32 v210, v206, s91, -v210
	v_fmac_f32_e32 v210, 0x3377d1cf, v206
	v_fma_f32 v209, v209, v190, v139
	v_cmp_gt_f32_e32 vcc, s90, v209
	v_fmac_f32_e32 v210, 0x3f317217, v206
	v_cmp_lt_f32_e64 s[8:9], |v206|, s92
	v_cndmask_b32_e64 v211, 0, 32, vcc
	v_ldexp_f32 v209, v209, v211
	v_log_f32_e32 v209, v209
	v_cndmask_b32_e64 v206, v206, v210, s[8:9]
	v_cndmask_b32_e64 v210, 0, v186, s[6:7]
	v_sub_f32_e32 v206, v206, v210
	v_mul_f32_e32 v210, 0x3f317217, v209
	v_mul_f32_e32 v211, 0xbfb8aa3b, v92
	v_fma_f32 v210, v209, s91, -v210
	v_exp_f32_e32 v211, v211
	v_fmac_f32_e32 v210, 0x3377d1cf, v209
	v_fmac_f32_e32 v210, 0x3f317217, v209
	v_cmp_lt_f32_e64 s[6:7], |v209|, s92
	v_cvt_pk_f16_f32 v203, v203, v206
	s_nop 0
	v_cndmask_b32_e64 v209, v209, v210, s[6:7]
	v_cndmask_b32_e32 v210, 0, v186, vcc
	v_sub_f32_e32 v209, v209, v210
	v_add_f32_e32 v210, 1.0, v211
	v_rcp_f32_e32 v210, v210
	s_nop 0
	v_fma_f32 v205, v210, v152, v132
	v_cmp_gt_f32_e32 vcc, s90, v205
	s_nop 1
	v_cndmask_b32_e64 v206, 0, 32, vcc
	v_ldexp_f32 v205, v205, v206
	v_log_f32_e32 v206, v205
	v_mul_f32_e32 v205, 0xbfb8aa3b, v88
	v_exp_f32_e32 v207, v205
	v_cvt_pk_f16_f32 v205, v208, v209
	global_store_dwordx4 v[172:173], v[202:205], off sc1
	v_cmp_lt_f32_e64 s[8:9], |v206|, s92
	s_nop 0
	v_add_f32_e32 v203, 1.0, v207
	v_rcp_f32_e32 v203, v203
	v_mul_f32_e32 v205, 0xbfb8aa3b, v93
	v_mul_f32_e32 v202, 0x3f317217, v206
	v_exp_f32_e32 v205, v205
	v_fma_f32 v203, v203, v191, v128
	v_cmp_gt_f32_e64 s[6:7], s90, v203
	v_fma_f32 v202, v206, s91, -v202
	v_fmac_f32_e32 v202, 0x3377d1cf, v206
	v_cndmask_b32_e64 v204, 0, 32, s[6:7]
	v_ldexp_f32 v203, v203, v204
	v_log_f32_e32 v203, v203
	v_fmac_f32_e32 v202, 0x3f317217, v206
	v_cndmask_b32_e64 v202, v206, v202, s[8:9]
	v_cndmask_b32_e32 v204, 0, v186, vcc
	v_add_f32_e32 v205, 1.0, v205
	v_sub_f32_e32 v202, v202, v204
	v_mul_f32_e32 v204, 0x3f317217, v203
	v_rcp_f32_e32 v205, v205
	v_fma_f32 v204, v203, s91, -v204
	v_fmac_f32_e32 v204, 0x3377d1cf, v203
	v_fmac_f32_e32 v204, 0x3f317217, v203
	v_cmp_lt_f32_e64 vcc, |v203|, s92
	v_fma_f32 v205, v205, v192, v133
	s_nop 0
	v_cndmask_b32_e32 v203, v203, v204, vcc
	v_cndmask_b32_e64 v204, 0, v186, s[6:7]
	v_cmp_gt_f32_e32 vcc, s90, v205
	v_sub_f32_e32 v204, v203, v204
	v_mul_f32_e32 v203, 0xbfb8aa3b, v89
	v_cndmask_b32_e64 v206, 0, 32, vcc
	v_exp_f32_e32 v203, v203
	v_ldexp_f32 v205, v205, v206
	v_log_f32_e32 v205, v205
	v_cndmask_b32_e32 v207, 0, v186, vcc
	v_add_f32_e32 v203, 1.0, v203
	v_rcp_f32_e32 v203, v203
	v_mul_f32_e32 v206, 0x3f317217, v205
	v_fma_f32 v206, v205, s91, -v206
	v_fmac_f32_e32 v206, 0x3377d1cf, v205
	v_fmac_f32_e32 v206, 0x3f317217, v205
	v_cmp_lt_f32_e64 s[6:7], |v205|, s92
	v_fma_f32 v203, v203, v193, v129
	s_nop 0
	v_cndmask_b32_e64 v205, v205, v206, s[6:7]
	v_cmp_gt_f32_e64 s[6:7], s90, v203
	v_sub_f32_e32 v205, v205, v207
	v_cvt_pk_f16_f32 v202, v202, v205
	v_cndmask_b32_e64 v206, 0, 32, s[6:7]
	v_ldexp_f32 v203, v203, v206
	v_mul_f32_e32 v206, 0xbfb8aa3b, v94
	v_exp_f32_e32 v206, v206
	v_log_f32_e32 v203, v203
	v_mul_f32_e32 v205, 0xbfb8aa3b, v100
	v_add_f32_e32 v206, 1.0, v206
	v_rcp_f32_e32 v206, v206
	v_mul_f32_e32 v207, 0x3f317217, v203
	v_fma_f32 v207, v203, s91, -v207
	v_fmac_f32_e32 v207, 0x3377d1cf, v203
	v_fma_f32 v206, v206, v196, v134
	v_cmp_gt_f32_e32 vcc, s90, v206
	v_fmac_f32_e32 v207, 0x3f317217, v203
	v_cmp_lt_f32_e64 s[8:9], |v203|, s92
	v_cndmask_b32_e64 v208, 0, 32, vcc
	v_ldexp_f32 v206, v206, v208
	v_mul_f32_e32 v208, 0xbfb8aa3b, v90
	v_exp_f32_e32 v208, v208
	v_log_f32_e32 v206, v206
	v_cndmask_b32_e64 v203, v203, v207, s[8:9]
	v_cndmask_b32_e64 v207, 0, v186, s[6:7]
	v_add_f32_e32 v208, 1.0, v208
	v_sub_f32_e32 v207, v203, v207
	v_mul_f32_e32 v203, 0x3f317217, v206
	v_rcp_f32_e32 v208, v208
	v_fma_f32 v203, v206, s91, -v203
	v_fmac_f32_e32 v203, 0x3377d1cf, v206
	v_fmac_f32_e32 v203, 0x3f317217, v206
	v_cmp_lt_f32_e64 s[6:7], |v206|, s92
	v_fma_f32 v208, v208, v195, v130
	v_cvt_pk_f16_f32 v204, v204, v207
	v_cndmask_b32_e64 v203, v206, v203, s[6:7]
	v_cndmask_b32_e32 v206, 0, v186, vcc
	v_cmp_gt_f32_e32 vcc, s90, v208
	v_sub_f32_e32 v203, v203, v206
	v_mul_f32_e32 v206, 0xbfb8aa3b, v95
	v_cndmask_b32_e64 v209, 0, 32, vcc
	v_exp_f32_e32 v206, v206
	v_ldexp_f32 v208, v208, v209
	v_log_f32_e32 v208, v208
	v_cndmask_b32_e32 v210, 0, v186, vcc
	v_add_f32_e32 v206, 1.0, v206
	v_rcp_f32_e32 v206, v206
	v_mul_f32_e32 v209, 0x3f317217, v208
	v_fma_f32 v209, v208, s91, -v209
	v_fmac_f32_e32 v209, 0x3377d1cf, v208
	v_fmac_f32_e32 v209, 0x3f317217, v208
	v_cmp_lt_f32_e64 s[6:7], |v208|, s92
	v_fma_f32 v206, v206, v197, v135
	s_nop 0
	v_cndmask_b32_e64 v208, v208, v209, s[6:7]
	v_cmp_gt_f32_e64 s[6:7], s90, v206
	v_sub_f32_e32 v208, v208, v210
	s_nop 0
	v_cndmask_b32_e64 v209, 0, 32, s[6:7]
	v_ldexp_f32 v206, v206, v209
	v_mul_f32_e32 v209, 0xbfb8aa3b, v91
	v_exp_f32_e32 v209, v209
	v_log_f32_e32 v206, v206
	v_add_f32_e32 v209, 1.0, v209
	v_rcp_f32_e32 v209, v209
	v_mul_f32_e32 v210, 0x3f317217, v206
	v_fma_f32 v210, v206, s91, -v210
	v_fmac_f32_e32 v210, 0x3377d1cf, v206
; DI unsigned cvtpk(float lo, float hi) { f32x2 v = {lo, hi}; bf16x2_t b = __builtin_convertvector(v, bf16x2_t); return __builtin_bit_cast(unsigned, b); }
; DI unsigned cvtpk_h(float lo, float hi) { f32x2 v = {lo, hi}; h16x2_t b = __builtin_convertvector(v, h16x2_t); return __builtin_bit_cast(unsigned, b); }
; DI float sigm(float x) { return __builtin_amdgcn_rcpf(1.f + fexp(-x)); }
; DI float silu_(float x) { return x * sigm(x); }
;     template <int MODE> __device__ __forceinline__ void run(const f32x4 (&acc)[2][2][4][2], u16* dst, int ld, int row0, int col0, int trow0, int wc, int fq, const float* lb) const {
;     ...
;                         for (int i = 0; i < 4; ++i) { const float l0 = lb0[bj][i], l1 = lb1[bj][i];
;                             v0[i] = __logf(l0 + (1.f - l0) * sigm(v0[i])); v1[i] = __logf(l1 + (1.f - l1) * sigm(v1[i])); }
;                     }
;                     if (MODE == 4) {
; #pragma unroll
;                         for (int i = 0; i < 4; ++i) { v0[i] = silu_(v0[i]); v1[i] = silu_(v1[i]); }
;                     }
;                     if (MODE == 5) {
; #pragma unroll
;                         for (int i = 0; i < 4; ++i) { v0[i] = sigm(v0[i]); v1[i] = sigm(v1[i]); }
;                     }
;                     u32x4 w;
;                     if (MODE == 3) { w.x = cvtpk_h(v0[0], v0[1]); w.y = cvtpk_h(v0[2], v0[3]); w.z = cvtpk_h(v1[0], v1[1]); w.w = cvtpk_h(v1[2], v1[3]); }
;                     else { w.x = cvtpk(v0[0], v0[1]); w.y = cvtpk(v0[2], v0[3]); w.z = cvtpk(v1[0], v1[1]); w.w = cvtpk(v1[2], v1[3]); }
;                     *(u32x4*)(rowp + bj * HALF) = w;
	v_fma_f32 v209, v209, v198, v131
	v_cmp_gt_f32_e32 vcc, s90, v209
	v_fmac_f32_e32 v210, 0x3f317217, v206
	v_cmp_lt_f32_e64 s[8:9], |v206|, s92
	v_cndmask_b32_e64 v211, 0, 32, vcc
	v_ldexp_f32 v209, v209, v211
	v_log_f32_e32 v209, v209
	v_cndmask_b32_e64 v206, v206, v210, s[8:9]
	v_cndmask_b32_e64 v210, 0, v186, s[6:7]
	v_sub_f32_e32 v206, v206, v210
	v_mul_f32_e32 v210, 0x3f317217, v209
	v_fma_f32 v210, v209, s91, -v210
	v_fmac_f32_e32 v210, 0x3377d1cf, v209
	v_fmac_f32_e32 v210, 0x3f317217, v209
	v_cmp_lt_f32_e64 s[6:7], |v209|, s92
	v_cvt_pk_f16_f32 v203, v203, v206
	s_nop 0
	v_cndmask_b32_e64 v209, v209, v210, s[6:7]
	v_cndmask_b32_e32 v210, 0, v186, vcc
	v_sub_f32_e32 v209, v209, v210
	v_exp_f32_e32 v210, v205
	v_cvt_pk_f16_f32 v205, v208, v209
	global_store_dwordx4 v[172:173], v[202:205], off offset:256 sc1
	v_or_b32_e32 v172, 32, v166
	v_add_f32_e32 v206, 1.0, v210
	v_rcp_f32_e32 v206, v206
	v_ashrrev_i32_e32 v173, 31, v172
	v_lshlrev_b64 v[172:173], 11, v[172:173]
	v_lshl_add_u64 v[172:173], v[170:171], 0, v[172:173]
	v_fma_f32 v202, v206, v201, v140
	v_cmp_gt_f32_e32 vcc, s90, v202
	s_nop 1
	v_cndmask_b32_e64 v203, 0, 32, vcc
	v_ldexp_f32 v202, v202, v203
	v_mul_f32_e32 v203, 0xbfb8aa3b, v96
	v_exp_f32_e32 v203, v203
	v_log_f32_e32 v202, v202
	v_add_f32_e32 v203, 1.0, v203
	v_rcp_f32_e32 v203, v203
	v_mul_f32_e32 v204, 0x3f317217, v202
	v_fma_f32 v204, v202, s91, -v204
	v_fmac_f32_e32 v204, 0x3377d1cf, v202
	v_fma_f32 v203, v203, v200, v136
	v_cmp_gt_f32_e64 s[6:7], s90, v203
	v_fmac_f32_e32 v204, 0x3f317217, v202
	v_cmp_lt_f32_e64 s[8:9], |v202|, s92
	v_cndmask_b32_e64 v205, 0, 32, s[6:7]
	v_ldexp_f32 v203, v203, v205
	v_mul_f32_e32 v205, 0xbfb8aa3b, v101
	v_exp_f32_e32 v205, v205
	v_log_f32_e32 v203, v203
	v_cndmask_b32_e64 v202, v202, v204, s[8:9]
	v_cndmask_b32_e32 v204, 0, v186, vcc
	v_add_f32_e32 v205, 1.0, v205
	v_sub_f32_e32 v202, v202, v204
	v_mul_f32_e32 v204, 0x3f317217, v203
	v_rcp_f32_e32 v205, v205
	v_fma_f32 v204, v203, s91, -v204
	v_fmac_f32_e32 v204, 0x3377d1cf, v203
	v_fmac_f32_e32 v204, 0x3f317217, v203
	v_cmp_lt_f32_e64 vcc, |v203|, s92
	v_fma_f32 v205, v205, v199, v141
	s_nop 0
	v_cndmask_b32_e32 v203, v203, v204, vcc
	v_cndmask_b32_e64 v204, 0, v186, s[6:7]
	v_cmp_gt_f32_e32 vcc, s90, v205
	v_sub_f32_e32 v204, v203, v204
	v_mul_f32_e32 v203, 0xbfb8aa3b, v97
	v_cndmask_b32_e64 v206, 0, 32, vcc
	v_exp_f32_e32 v203, v203
	v_ldexp_f32 v205, v205, v206
	v_log_f32_e32 v205, v205
	v_cndmask_b32_e32 v207, 0, v186, vcc
	v_add_f32_e32 v203, 1.0, v203
	v_rcp_f32_e32 v203, v203
	v_mul_f32_e32 v206, 0x3f317217, v205
	v_fma_f32 v206, v205, s91, -v206
	v_fmac_f32_e32 v206, 0x3377d1cf, v205
	v_fmac_f32_e32 v206, 0x3f317217, v205
	v_cmp_lt_f32_e64 s[6:7], |v205|, s92
	v_fma_f32 v203, v203, v169, v137
	s_nop 0
	v_cndmask_b32_e64 v205, v205, v206, s[6:7]
	v_cmp_gt_f32_e64 s[6:7], s90, v203
	v_sub_f32_e32 v205, v205, v207
	v_cvt_pk_f16_f32 v202, v202, v205
	v_cndmask_b32_e64 v206, 0, 32, s[6:7]
	v_ldexp_f32 v203, v203, v206
	v_mul_f32_e32 v206, 0xbfb8aa3b, v102
	v_exp_f32_e32 v206, v206
	v_log_f32_e32 v203, v203
	v_add_f32_e32 v206, 1.0, v206
	v_rcp_f32_e32 v206, v206
	v_mul_f32_e32 v207, 0x3f317217, v203
	v_fma_f32 v207, v203, s91, -v207
	v_fmac_f32_e32 v207, 0x3377d1cf, v203
	v_fma_f32 v206, v206, v167, v142
	v_cmp_gt_f32_e32 vcc, s90, v206
	v_fmac_f32_e32 v207, 0x3f317217, v203
	v_cmp_lt_f32_e64 s[8:9], |v203|, s92
	v_cndmask_b32_e64 v208, 0, 32, vcc
	v_ldexp_f32 v206, v206, v208
	v_mul_f32_e32 v208, 0xbfb8aa3b, v98
	v_exp_f32_e32 v208, v208
	v_log_f32_e32 v206, v206
	v_cndmask_b32_e64 v203, v203, v207, s[8:9]
	v_cndmask_b32_e64 v207, 0, v186, s[6:7]
	v_add_f32_e32 v208, 1.0, v208
	v_sub_f32_e32 v207, v203, v207
	v_mul_f32_e32 v203, 0x3f317217, v206
	v_rcp_f32_e32 v208, v208
	v_fma_f32 v203, v206, s91, -v203
	v_fmac_f32_e32 v203, 0x3377d1cf, v206
	v_fmac_f32_e32 v203, 0x3f317217, v206
	v_cmp_lt_f32_e64 s[6:7], |v206|, s92
	v_fma_f32 v208, v208, v188, v138
	v_cvt_pk_f16_f32 v204, v204, v207
	v_cndmask_b32_e64 v203, v206, v203, s[6:7]
	v_cndmask_b32_e32 v206, 0, v186, vcc
	v_cmp_gt_f32_e32 vcc, s90, v208
	v_sub_f32_e32 v203, v203, v206
	v_mul_f32_e32 v206, 0xbfb8aa3b, v103
	v_cndmask_b32_e64 v209, 0, 32, vcc
	v_exp_f32_e32 v206, v206
	v_ldexp_f32 v208, v208, v209
	v_log_f32_e32 v208, v208
	v_cndmask_b32_e32 v210, 0, v186, vcc
	v_add_f32_e32 v206, 1.0, v206
	v_rcp_f32_e32 v206, v206
	v_mul_f32_e32 v209, 0x3f317217, v208
	v_fma_f32 v209, v208, s91, -v209
	v_fmac_f32_e32 v209, 0x3377d1cf, v208
	v_fmac_f32_e32 v209, 0x3f317217, v208
	v_cmp_lt_f32_e64 s[6:7], |v208|, s92
	v_fma_f32 v206, v206, v189, v143
	s_nop 0
	v_cndmask_b32_e64 v208, v208, v209, s[6:7]
	v_cmp_gt_f32_e64 s[6:7], s90, v206
	v_sub_f32_e32 v208, v208, v210
	s_nop 0
	v_cndmask_b32_e64 v209, 0, 32, s[6:7]
	v_ldexp_f32 v206, v206, v209
	v_mul_f32_e32 v209, 0xbfb8aa3b, v99
	v_exp_f32_e32 v209, v209
	v_log_f32_e32 v206, v206
	v_add_f32_e32 v209, 1.0, v209
	v_rcp_f32_e32 v209, v209
	v_mul_f32_e32 v210, 0x3f317217, v206
	v_fma_f32 v210, v206, s91, -v210
	v_fmac_f32_e32 v210, 0x3377d1cf, v206
	v_fma_f32 v209, v209, v190, v139
	v_cmp_gt_f32_e32 vcc, s90, v209
	v_fmac_f32_e32 v210, 0x3f317217, v206
	v_cmp_lt_f32_e64 s[8:9], |v206|, s92
	v_cndmask_b32_e64 v211, 0, 32, vcc
	v_ldexp_f32 v209, v209, v211
	v_log_f32_e32 v209, v209
	v_cndmask_b32_e64 v206, v206, v210, s[8:9]
	v_cndmask_b32_e64 v210, 0, v186, s[6:7]
	v_sub_f32_e32 v206, v206, v210
	v_mul_f32_e32 v210, 0x3f317217, v209
	v_mul_f32_e32 v211, 0xbfb8aa3b, v76
	v_fma_f32 v210, v209, s91, -v210
	v_exp_f32_e32 v211, v211
	v_fmac_f32_e32 v210, 0x3377d1cf, v209
	v_fmac_f32_e32 v210, 0x3f317217, v209
	v_cmp_lt_f32_e64 s[6:7], |v209|, s92
; DI unsigned cvtpk(float lo, float hi) { f32x2 v = {lo, hi}; bf16x2_t b = __builtin_convertvector(v, bf16x2_t); return __builtin_bit_cast(unsigned, b); }
; DI unsigned cvtpk_h(float lo, float hi) { f32x2 v = {lo, hi}; h16x2_t b = __builtin_convertvector(v, h16x2_t); return __builtin_bit_cast(unsigned, b); }
; DI float sigm(float x) { return __builtin_amdgcn_rcpf(1.f + fexp(-x)); }
; DI float silu_(float x) { return x * sigm(x); }
;     template <int MODE> __device__ __forceinline__ void run(const f32x4 (&acc)[2][2][4][2], u16* dst, int ld, int row0, int col0, int trow0, int wc, int fq, const float* lb) const {
;     ...
;                         for (int i = 0; i < 4; ++i) { const float l0 = lb0[bj][i], l1 = lb1[bj][i];
;                             v0[i] = __logf(l0 + (1.f - l0) * sigm(v0[i])); v1[i] = __logf(l1 + (1.f - l1) * sigm(v1[i])); }
;                     }
;                     if (MODE == 4) {
; #pragma unroll
;                         for (int i = 0; i < 4; ++i) { v0[i] = silu_(v0[i]); v1[i] = silu_(v1[i]); }
;                     }
;                     if (MODE == 5) {
; #pragma unroll
;                         for (int i = 0; i < 4; ++i) { v0[i] = sigm(v0[i]); v1[i] = sigm(v1[i]); }
;                     }
;                     u32x4 w;
;                     if (MODE == 3) { w.x = cvtpk_h(v0[0], v0[1]); w.y = cvtpk_h(v0[2], v0[3]); w.z = cvtpk_h(v1[0], v1[1]); w.w = cvtpk_h(v1[2], v1[3]); }
;                     else { w.x = cvtpk(v0[0], v0[1]); w.y = cvtpk(v0[2], v0[3]); w.z = cvtpk(v1[0], v1[1]); w.w = cvtpk(v1[2], v1[3]); }
;                     *(u32x4*)(rowp + bj * HALF) = w;
	v_cvt_pk_f16_f32 v203, v203, v206
	s_nop 0
	v_cndmask_b32_e64 v209, v209, v210, s[6:7]
	v_cndmask_b32_e32 v210, 0, v186, vcc
	v_sub_f32_e32 v209, v209, v210
	v_add_f32_e32 v210, 1.0, v211
	v_rcp_f32_e32 v210, v210
	s_nop 0
	v_fma_f32 v205, v210, v152, v132
	v_cmp_gt_f32_e32 vcc, s90, v205
	s_nop 1
	v_cndmask_b32_e64 v206, 0, 32, vcc
	v_ldexp_f32 v205, v205, v206
	v_log_f32_e32 v206, v205
	v_mul_f32_e32 v205, 0xbfb8aa3b, v72
	v_exp_f32_e32 v207, v205
	v_cvt_pk_f16_f32 v205, v208, v209
	global_store_dwordx4 v[172:173], v[202:205], off sc1
	v_cmp_lt_f32_e64 s[8:9], |v206|, s92
	s_nop 0
	v_add_f32_e32 v203, 1.0, v207
	v_rcp_f32_e32 v203, v203
	v_mul_f32_e32 v205, 0xbfb8aa3b, v77
	v_mul_f32_e32 v202, 0x3f317217, v206
	v_exp_f32_e32 v205, v205
	v_fma_f32 v203, v203, v191, v128
	v_cmp_gt_f32_e64 s[6:7], s90, v203
	v_fma_f32 v202, v206, s91, -v202
	v_fmac_f32_e32 v202, 0x3377d1cf, v206
	v_cndmask_b32_e64 v204, 0, 32, s[6:7]
	v_ldexp_f32 v203, v203, v204
	v_log_f32_e32 v203, v203
	v_fmac_f32_e32 v202, 0x3f317217, v206
	v_cndmask_b32_e64 v202, v206, v202, s[8:9]
	v_cndmask_b32_e32 v204, 0, v186, vcc
	v_add_f32_e32 v205, 1.0, v205
	v_sub_f32_e32 v202, v202, v204
	v_mul_f32_e32 v204, 0x3f317217, v203
	v_rcp_f32_e32 v205, v205
	v_fma_f32 v204, v203, s91, -v204
	v_fmac_f32_e32 v204, 0x3377d1cf, v203
	v_fmac_f32_e32 v204, 0x3f317217, v203
	v_cmp_lt_f32_e64 vcc, |v203|, s92
	v_fma_f32 v205, v205, v192, v133
	s_nop 0
	v_cndmask_b32_e32 v203, v203, v204, vcc
	v_cndmask_b32_e64 v204, 0, v186, s[6:7]
	v_cmp_gt_f32_e32 vcc, s90, v205
	v_sub_f32_e32 v204, v203, v204
	v_mul_f32_e32 v203, 0xbfb8aa3b, v73
	v_cndmask_b32_e64 v206, 0, 32, vcc
	v_exp_f32_e32 v203, v203
	v_ldexp_f32 v205, v205, v206
	v_log_f32_e32 v205, v205
	v_cndmask_b32_e32 v207, 0, v186, vcc
	v_add_f32_e32 v203, 1.0, v203
	v_rcp_f32_e32 v203, v203
	v_mul_f32_e32 v206, 0x3f317217, v205
	v_fma_f32 v206, v205, s91, -v206
	v_fmac_f32_e32 v206, 0x3377d1cf, v205
	v_fmac_f32_e32 v206, 0x3f317217, v205
	v_cmp_lt_f32_e64 s[6:7], |v205|, s92
	v_fma_f32 v203, v203, v193, v129
	s_nop 0
	v_cndmask_b32_e64 v205, v205, v206, s[6:7]
	v_cmp_gt_f32_e64 s[6:7], s90, v203
	v_sub_f32_e32 v205, v205, v207
	v_cvt_pk_f16_f32 v202, v202, v205
	v_cndmask_b32_e64 v206, 0, 32, s[6:7]
	v_ldexp_f32 v203, v203, v206
	v_mul_f32_e32 v206, 0xbfb8aa3b, v78
	v_exp_f32_e32 v206, v206
	v_log_f32_e32 v203, v203
	v_mul_f32_e32 v205, 0xbfb8aa3b, v84
	v_add_f32_e32 v206, 1.0, v206
	v_rcp_f32_e32 v206, v206
	v_mul_f32_e32 v207, 0x3f317217, v203
	v_fma_f32 v207, v203, s91, -v207
	v_fmac_f32_e32 v207, 0x3377d1cf, v203
	v_fma_f32 v206, v206, v196, v134
	v_cmp_gt_f32_e32 vcc, s90, v206
	v_fmac_f32_e32 v207, 0x3f317217, v203
	v_cmp_lt_f32_e64 s[8:9], |v203|, s92
	v_cndmask_b32_e64 v208, 0, 32, vcc
	v_ldexp_f32 v206, v206, v208
	v_mul_f32_e32 v208, 0xbfb8aa3b, v74
	v_exp_f32_e32 v208, v208
	v_log_f32_e32 v206, v206
	v_cndmask_b32_e64 v203, v203, v207, s[8:9]
	v_cndmask_b32_e64 v207, 0, v186, s[6:7]
	v_add_f32_e32 v208, 1.0, v208
	v_sub_f32_e32 v207, v203, v207
	v_mul_f32_e32 v203, 0x3f317217, v206
	v_rcp_f32_e32 v208, v208
	v_fma_f32 v203, v206, s91, -v203
	v_fmac_f32_e32 v203, 0x3377d1cf, v206
	v_fmac_f32_e32 v203, 0x3f317217, v206
	v_cmp_lt_f32_e64 s[6:7], |v206|, s92
	v_fma_f32 v208, v208, v195, v130
	v_cvt_pk_f16_f32 v204, v204, v207
	v_cndmask_b32_e64 v203, v206, v203, s[6:7]
	v_cndmask_b32_e32 v206, 0, v186, vcc
	v_cmp_gt_f32_e32 vcc, s90, v208
	v_sub_f32_e32 v203, v203, v206
	v_mul_f32_e32 v206, 0xbfb8aa3b, v79
	v_cndmask_b32_e64 v209, 0, 32, vcc
	v_exp_f32_e32 v206, v206
	v_ldexp_f32 v208, v208, v209
	v_log_f32_e32 v208, v208
	v_cndmask_b32_e32 v210, 0, v186, vcc
	v_add_f32_e32 v206, 1.0, v206
	v_rcp_f32_e32 v206, v206
	v_mul_f32_e32 v209, 0x3f317217, v208
	v_fma_f32 v209, v208, s91, -v209
	v_fmac_f32_e32 v209, 0x3377d1cf, v208
	v_fmac_f32_e32 v209, 0x3f317217, v208
	v_cmp_lt_f32_e64 s[6:7], |v208|, s92
	v_fma_f32 v206, v206, v197, v135
	s_nop 0
	v_cndmask_b32_e64 v208, v208, v209, s[6:7]
	v_cmp_gt_f32_e64 s[6:7], s90, v206
	v_sub_f32_e32 v208, v208, v210
	s_nop 0
	v_cndmask_b32_e64 v209, 0, 32, s[6:7]
	v_ldexp_f32 v206, v206, v209
	v_mul_f32_e32 v209, 0xbfb8aa3b, v75
	v_exp_f32_e32 v209, v209
	v_log_f32_e32 v206, v206
	v_add_f32_e32 v209, 1.0, v209
	v_rcp_f32_e32 v209, v209
	v_mul_f32_e32 v210, 0x3f317217, v206
	v_fma_f32 v210, v206, s91, -v210
	v_fmac_f32_e32 v210, 0x3377d1cf, v206
	v_fma_f32 v209, v209, v198, v131
	v_cmp_gt_f32_e32 vcc, s90, v209
	v_fmac_f32_e32 v210, 0x3f317217, v206
	v_cmp_lt_f32_e64 s[8:9], |v206|, s92
	v_cndmask_b32_e64 v211, 0, 32, vcc
	v_ldexp_f32 v209, v209, v211
	v_log_f32_e32 v209, v209
	v_cndmask_b32_e64 v206, v206, v210, s[8:9]
	v_cndmask_b32_e64 v210, 0, v186, s[6:7]
	v_sub_f32_e32 v206, v206, v210
	v_mul_f32_e32 v210, 0x3f317217, v209
	v_fma_f32 v210, v209, s91, -v210
	v_fmac_f32_e32 v210, 0x3377d1cf, v209
	v_fmac_f32_e32 v210, 0x3f317217, v209
	v_cmp_lt_f32_e64 s[6:7], |v209|, s92
	v_cvt_pk_f16_f32 v203, v203, v206
	s_nop 0
	v_cndmask_b32_e64 v209, v209, v210, s[6:7]
	v_cndmask_b32_e32 v210, 0, v186, vcc
	v_sub_f32_e32 v209, v209, v210
	v_exp_f32_e32 v210, v205
	v_cvt_pk_f16_f32 v205, v208, v209
	global_store_dwordx4 v[172:173], v[202:205], off offset:256 sc1
	v_or_b32_e32 v172, 48, v166
	v_add_f32_e32 v206, 1.0, v210
	v_rcp_f32_e32 v206, v206
	v_ashrrev_i32_e32 v173, 31, v172
	v_lshlrev_b64 v[172:173], 11, v[172:173]
	v_lshl_add_u64 v[172:173], v[170:171], 0, v[172:173]
	v_fma_f32 v202, v206, v201, v140
	v_cmp_gt_f32_e32 vcc, s90, v202
	s_nop 1
	v_cndmask_b32_e64 v203, 0, 32, vcc
	v_ldexp_f32 v202, v202, v203
	v_mul_f32_e32 v203, 0xbfb8aa3b, v80
	v_exp_f32_e32 v203, v203
	v_log_f32_e32 v202, v202
; DI unsigned cvtpk(float lo, float hi) { f32x2 v = {lo, hi}; bf16x2_t b = __builtin_convertvector(v, bf16x2_t); return __builtin_bit_cast(unsigned, b); }
; DI unsigned cvtpk_h(float lo, float hi) { f32x2 v = {lo, hi}; h16x2_t b = __builtin_convertvector(v, h16x2_t); return __builtin_bit_cast(unsigned, b); }
; DI float sigm(float x) { return __builtin_amdgcn_rcpf(1.f + fexp(-x)); }
; DI float silu_(float x) { return x * sigm(x); }
;     template <int MODE> __device__ __forceinline__ void run(const f32x4 (&acc)[2][2][4][2], u16* dst, int ld, int row0, int col0, int trow0, int wc, int fq, const float* lb) const {
;     ...
;                         for (int i = 0; i < 4; ++i) { const float l0 = lb0[bj][i], l1 = lb1[bj][i];
;                             v0[i] = __logf(l0 + (1.f - l0) * sigm(v0[i])); v1[i] = __logf(l1 + (1.f - l1) * sigm(v1[i])); }
;                     }
;                     if (MODE == 4) {
; #pragma unroll
;                         for (int i = 0; i < 4; ++i) { v0[i] = silu_(v0[i]); v1[i] = silu_(v1[i]); }
;                     }
;                     if (MODE == 5) {
; #pragma unroll
;                         for (int i = 0; i < 4; ++i) { v0[i] = sigm(v0[i]); v1[i] = sigm(v1[i]); }
;                     }
;                     u32x4 w;
;                     if (MODE == 3) { w.x = cvtpk_h(v0[0], v0[1]); w.y = cvtpk_h(v0[2], v0[3]); w.z = cvtpk_h(v1[0], v1[1]); w.w = cvtpk_h(v1[2], v1[3]); }
;                     else { w.x = cvtpk(v0[0], v0[1]); w.y = cvtpk(v0[2], v0[3]); w.z = cvtpk(v1[0], v1[1]); w.w = cvtpk(v1[2], v1[3]); }
;                     *(u32x4*)(rowp + bj * HALF) = w;
	v_add_f32_e32 v203, 1.0, v203
	v_rcp_f32_e32 v203, v203
	v_mul_f32_e32 v204, 0x3f317217, v202
	v_fma_f32 v204, v202, s91, -v204
	v_fmac_f32_e32 v204, 0x3377d1cf, v202
	v_fma_f32 v203, v203, v200, v136
	v_cmp_gt_f32_e64 s[6:7], s90, v203
	v_fmac_f32_e32 v204, 0x3f317217, v202
	v_cmp_lt_f32_e64 s[8:9], |v202|, s92
	v_cndmask_b32_e64 v205, 0, 32, s[6:7]
	v_ldexp_f32 v203, v203, v205
	v_mul_f32_e32 v205, 0xbfb8aa3b, v85
	v_exp_f32_e32 v205, v205
	v_log_f32_e32 v203, v203
	v_cndmask_b32_e64 v202, v202, v204, s[8:9]
	v_cndmask_b32_e32 v204, 0, v186, vcc
	v_add_f32_e32 v205, 1.0, v205
	v_sub_f32_e32 v202, v202, v204
	v_mul_f32_e32 v204, 0x3f317217, v203
	v_rcp_f32_e32 v205, v205
	v_fma_f32 v204, v203, s91, -v204
	v_fmac_f32_e32 v204, 0x3377d1cf, v203
	v_fmac_f32_e32 v204, 0x3f317217, v203
	v_cmp_lt_f32_e64 vcc, |v203|, s92
	v_fma_f32 v205, v205, v199, v141
	s_nop 0
	v_cndmask_b32_e32 v203, v203, v204, vcc
	v_cndmask_b32_e64 v204, 0, v186, s[6:7]
	v_cmp_gt_f32_e32 vcc, s90, v205
	v_sub_f32_e32 v204, v203, v204
	v_mul_f32_e32 v203, 0xbfb8aa3b, v81
	v_cndmask_b32_e64 v206, 0, 32, vcc
	v_exp_f32_e32 v203, v203
	v_ldexp_f32 v205, v205, v206
	v_log_f32_e32 v205, v205
	v_cndmask_b32_e32 v207, 0, v186, vcc
	v_add_f32_e32 v203, 1.0, v203
	v_rcp_f32_e32 v203, v203
	v_mul_f32_e32 v206, 0x3f317217, v205
	v_fma_f32 v206, v205, s91, -v206
	v_fmac_f32_e32 v206, 0x3377d1cf, v205
	v_fmac_f32_e32 v206, 0x3f317217, v205
	v_cmp_lt_f32_e64 s[6:7], |v205|, s92
	v_fma_f32 v203, v203, v169, v137
	s_nop 0
	v_cndmask_b32_e64 v205, v205, v206, s[6:7]
	v_cmp_gt_f32_e64 s[6:7], s90, v203
	v_sub_f32_e32 v205, v205, v207
	v_cvt_pk_f16_f32 v202, v202, v205
	v_cndmask_b32_e64 v206, 0, 32, s[6:7]
	v_ldexp_f32 v203, v203, v206
	v_mul_f32_e32 v206, 0xbfb8aa3b, v86
	v_exp_f32_e32 v206, v206
	v_log_f32_e32 v203, v203
	v_add_f32_e32 v206, 1.0, v206
	v_rcp_f32_e32 v206, v206
	v_mul_f32_e32 v207, 0x3f317217, v203
	v_fma_f32 v207, v203, s91, -v207
	v_fmac_f32_e32 v207, 0x3377d1cf, v203
	v_fma_f32 v206, v206, v167, v142
	v_cmp_gt_f32_e32 vcc, s90, v206
	v_fmac_f32_e32 v207, 0x3f317217, v203
	v_cmp_lt_f32_e64 s[8:9], |v203|, s92
	v_cndmask_b32_e64 v208, 0, 32, vcc
	v_ldexp_f32 v206, v206, v208
	v_mul_f32_e32 v208, 0xbfb8aa3b, v82
	v_exp_f32_e32 v208, v208
	v_log_f32_e32 v206, v206
	v_cndmask_b32_e64 v203, v203, v207, s[8:9]
	v_cndmask_b32_e64 v207, 0, v186, s[6:7]
	v_add_f32_e32 v208, 1.0, v208
	v_sub_f32_e32 v207, v203, v207
	v_mul_f32_e32 v203, 0x3f317217, v206
	v_rcp_f32_e32 v208, v208
	v_fma_f32 v203, v206, s91, -v203
	v_fmac_f32_e32 v203, 0x3377d1cf, v206
	v_fmac_f32_e32 v203, 0x3f317217, v206
	v_cmp_lt_f32_e64 s[6:7], |v206|, s92
	v_fma_f32 v208, v208, v188, v138
	v_cvt_pk_f16_f32 v204, v204, v207
	v_cndmask_b32_e64 v203, v206, v203, s[6:7]
	v_cndmask_b32_e32 v206, 0, v186, vcc
	v_cmp_gt_f32_e32 vcc, s90, v208
	v_sub_f32_e32 v203, v203, v206
	v_mul_f32_e32 v206, 0xbfb8aa3b, v87
	v_cndmask_b32_e64 v209, 0, 32, vcc
	v_exp_f32_e32 v206, v206
	v_ldexp_f32 v208, v208, v209
	v_log_f32_e32 v208, v208
	v_cndmask_b32_e32 v210, 0, v186, vcc
	v_add_f32_e32 v206, 1.0, v206
	v_rcp_f32_e32 v206, v206
	v_mul_f32_e32 v209, 0x3f317217, v208
	v_fma_f32 v209, v208, s91, -v209
	v_fmac_f32_e32 v209, 0x3377d1cf, v208
	v_fmac_f32_e32 v209, 0x3f317217, v208
	v_cmp_lt_f32_e64 s[6:7], |v208|, s92
	v_fma_f32 v206, v206, v189, v143
	s_nop 0
	v_cndmask_b32_e64 v208, v208, v209, s[6:7]
	v_cmp_gt_f32_e64 s[6:7], s90, v206
	v_sub_f32_e32 v208, v208, v210
	s_nop 0
	v_cndmask_b32_e64 v209, 0, 32, s[6:7]
	v_ldexp_f32 v206, v206, v209
	v_mul_f32_e32 v209, 0xbfb8aa3b, v83
	v_exp_f32_e32 v209, v209
	v_log_f32_e32 v206, v206
	v_add_f32_e32 v209, 1.0, v209
	v_rcp_f32_e32 v209, v209
	v_mul_f32_e32 v210, 0x3f317217, v206
	v_fma_f32 v210, v206, s91, -v210
	v_fmac_f32_e32 v210, 0x3377d1cf, v206
	v_fma_f32 v209, v209, v190, v139
	v_cmp_gt_f32_e32 vcc, s90, v209
	v_fmac_f32_e32 v210, 0x3f317217, v206
	v_cmp_lt_f32_e64 s[8:9], |v206|, s92
	v_cndmask_b32_e64 v211, 0, 32, vcc
	v_ldexp_f32 v209, v209, v211
	v_log_f32_e32 v209, v209
	v_cndmask_b32_e64 v206, v206, v210, s[8:9]
	v_cndmask_b32_e64 v210, 0, v186, s[6:7]
	v_sub_f32_e32 v206, v206, v210
	v_mul_f32_e32 v210, 0x3f317217, v209
	v_mul_f32_e32 v211, 0xbfb8aa3b, v68
	v_fma_f32 v210, v209, s91, -v210
	v_exp_f32_e32 v211, v211
	v_fmac_f32_e32 v210, 0x3377d1cf, v209
	v_fmac_f32_e32 v210, 0x3f317217, v209
	v_cmp_lt_f32_e64 s[6:7], |v209|, s92
	v_cvt_pk_f16_f32 v203, v203, v206
	s_nop 0
	v_cndmask_b32_e64 v209, v209, v210, s[6:7]
	v_cndmask_b32_e32 v210, 0, v186, vcc
	v_sub_f32_e32 v209, v209, v210
	v_add_f32_e32 v210, 1.0, v211
	v_rcp_f32_e32 v210, v210
	s_nop 0
	v_fma_f32 v205, v210, v152, v132
	v_cmp_gt_f32_e32 vcc, s90, v205
	s_nop 1
	v_cndmask_b32_e64 v206, 0, 32, vcc
	v_ldexp_f32 v205, v205, v206
	v_log_f32_e32 v206, v205
	v_mul_f32_e32 v205, 0xbfb8aa3b, v64
	v_exp_f32_e32 v207, v205
	v_cvt_pk_f16_f32 v205, v208, v209
	global_store_dwordx4 v[172:173], v[202:205], off sc1
	v_cmp_lt_f32_e64 s[8:9], |v206|, s92
	s_nop 0
	v_add_f32_e32 v203, 1.0, v207
	v_rcp_f32_e32 v203, v203
	v_mul_f32_e32 v205, 0xbfb8aa3b, v69
	v_mul_f32_e32 v202, 0x3f317217, v206
	v_exp_f32_e32 v205, v205
	v_fma_f32 v203, v203, v191, v128
	v_cmp_gt_f32_e64 s[6:7], s90, v203
	v_fma_f32 v202, v206, s91, -v202
	v_fmac_f32_e32 v202, 0x3377d1cf, v206
	v_cndmask_b32_e64 v204, 0, 32, s[6:7]
	v_ldexp_f32 v203, v203, v204
	v_log_f32_e32 v203, v203
	v_fmac_f32_e32 v202, 0x3f317217, v206
	v_cndmask_b32_e64 v202, v206, v202, s[8:9]
	v_cndmask_b32_e32 v204, 0, v186, vcc
	v_add_f32_e32 v205, 1.0, v205
	v_sub_f32_e32 v202, v202, v204
	v_mul_f32_e32 v204, 0x3f317217, v203
	v_rcp_f32_e32 v205, v205
	v_fma_f32 v204, v203, s91, -v204
; DI unsigned cvtpk(float lo, float hi) { f32x2 v = {lo, hi}; bf16x2_t b = __builtin_convertvector(v, bf16x2_t); return __builtin_bit_cast(unsigned, b); }
; DI unsigned cvtpk_h(float lo, float hi) { f32x2 v = {lo, hi}; h16x2_t b = __builtin_convertvector(v, h16x2_t); return __builtin_bit_cast(unsigned, b); }
; DI float sigm(float x) { return __builtin_amdgcn_rcpf(1.f + fexp(-x)); }
; DI float silu_(float x) { return x * sigm(x); }
;     template <int MODE> __device__ __forceinline__ void run(const f32x4 (&acc)[2][2][4][2], u16* dst, int ld, int row0, int col0, int trow0, int wc, int fq, const float* lb) const {
;     ...
;                     if (MODE == 3) {
; #pragma unroll
;                         for (int i = 0; i < 4; ++i) { const float l0 = lb0[bj][i], l1 = lb1[bj][i];
;                             v0[i] = __logf(l0 + (1.f - l0) * sigm(v0[i])); v1[i] = __logf(l1 + (1.f - l1) * sigm(v1[i])); }
;                     }
;                     if (MODE == 4) {
; #pragma unroll
;                         for (int i = 0; i < 4; ++i) { v0[i] = silu_(v0[i]); v1[i] = silu_(v1[i]); }
;                     }
;                     if (MODE == 5) {
; #pragma unroll
;                         for (int i = 0; i < 4; ++i) { v0[i] = sigm(v0[i]); v1[i] = sigm(v1[i]); }
;                     }
;                     u32x4 w;
;                     if (MODE == 3) { w.x = cvtpk_h(v0[0], v0[1]); w.y = cvtpk_h(v0[2], v0[3]); w.z = cvtpk_h(v1[0], v1[1]); w.w = cvtpk_h(v1[2], v1[3]); }
;                     else { w.x = cvtpk(v0[0], v0[1]); w.y = cvtpk(v0[2], v0[3]); w.z = cvtpk(v1[0], v1[1]); w.w = cvtpk(v1[2], v1[3]); }
;                     *(u32x4*)(rowp + bj * HALF) = w;
	v_fmac_f32_e32 v204, 0x3377d1cf, v203
	v_fmac_f32_e32 v204, 0x3f317217, v203
	v_cmp_lt_f32_e64 vcc, |v203|, s92
	v_fma_f32 v205, v205, v192, v133
	s_nop 0
	v_cndmask_b32_e32 v203, v203, v204, vcc
	v_cndmask_b32_e64 v204, 0, v186, s[6:7]
	v_cmp_gt_f32_e32 vcc, s90, v205
	v_sub_f32_e32 v204, v203, v204
	v_mul_f32_e32 v203, 0xbfb8aa3b, v65
	v_cndmask_b32_e64 v206, 0, 32, vcc
	v_exp_f32_e32 v203, v203
	v_ldexp_f32 v205, v205, v206
	v_log_f32_e32 v205, v205
	v_cndmask_b32_e32 v207, 0, v186, vcc
	v_add_f32_e32 v203, 1.0, v203
	v_rcp_f32_e32 v203, v203
	v_mul_f32_e32 v206, 0x3f317217, v205
	v_fma_f32 v206, v205, s91, -v206
	v_fmac_f32_e32 v206, 0x3377d1cf, v205
	v_fmac_f32_e32 v206, 0x3f317217, v205
	v_cmp_lt_f32_e64 s[6:7], |v205|, s92
	v_fma_f32 v203, v203, v193, v129
	s_nop 0
	v_cndmask_b32_e64 v205, v205, v206, s[6:7]
	v_cmp_gt_f32_e64 s[6:7], s90, v203
	v_sub_f32_e32 v205, v205, v207
	v_cvt_pk_f16_f32 v202, v202, v205
	v_cndmask_b32_e64 v206, 0, 32, s[6:7]
	v_ldexp_f32 v203, v203, v206
	v_mul_f32_e32 v206, 0xbfb8aa3b, v70
	v_exp_f32_e32 v206, v206
	v_log_f32_e32 v203, v203
	v_mul_f32_e32 v205, 0xbfb8aa3b, v60
	v_add_f32_e32 v206, 1.0, v206
	v_rcp_f32_e32 v206, v206
	v_mul_f32_e32 v207, 0x3f317217, v203
	v_fma_f32 v207, v203, s91, -v207
	v_fmac_f32_e32 v207, 0x3377d1cf, v203
	v_fma_f32 v206, v206, v196, v134
	v_cmp_gt_f32_e32 vcc, s90, v206
	v_fmac_f32_e32 v207, 0x3f317217, v203
	v_cmp_lt_f32_e64 s[8:9], |v203|, s92
	v_cndmask_b32_e64 v208, 0, 32, vcc
	v_ldexp_f32 v206, v206, v208
	v_mul_f32_e32 v208, 0xbfb8aa3b, v66
	v_exp_f32_e32 v208, v208
	v_log_f32_e32 v206, v206
	v_cndmask_b32_e64 v203, v203, v207, s[8:9]
	v_cndmask_b32_e64 v207, 0, v186, s[6:7]
	v_add_f32_e32 v208, 1.0, v208
	v_sub_f32_e32 v207, v203, v207
	v_mul_f32_e32 v203, 0x3f317217, v206
	v_rcp_f32_e32 v208, v208
	v_fma_f32 v203, v206, s91, -v203
	v_fmac_f32_e32 v203, 0x3377d1cf, v206
	v_fmac_f32_e32 v203, 0x3f317217, v206
	v_cmp_lt_f32_e64 s[6:7], |v206|, s92
	v_fma_f32 v208, v208, v195, v130
	v_cvt_pk_f16_f32 v204, v204, v207
	v_cndmask_b32_e64 v203, v206, v203, s[6:7]
	v_cndmask_b32_e32 v206, 0, v186, vcc
	v_cmp_gt_f32_e32 vcc, s90, v208
	v_sub_f32_e32 v203, v203, v206
	v_mul_f32_e32 v206, 0xbfb8aa3b, v71
	v_cndmask_b32_e64 v209, 0, 32, vcc
	v_exp_f32_e32 v206, v206
	v_ldexp_f32 v208, v208, v209
	v_log_f32_e32 v208, v208
	v_cndmask_b32_e32 v210, 0, v186, vcc
	v_add_f32_e32 v206, 1.0, v206
	v_rcp_f32_e32 v206, v206
	v_mul_f32_e32 v209, 0x3f317217, v208
	v_fma_f32 v209, v208, s91, -v209
	v_fmac_f32_e32 v209, 0x3377d1cf, v208
	v_fmac_f32_e32 v209, 0x3f317217, v208
	v_cmp_lt_f32_e64 s[6:7], |v208|, s92
	v_fma_f32 v206, v206, v197, v135
	s_nop 0
	v_cndmask_b32_e64 v208, v208, v209, s[6:7]
	v_cmp_gt_f32_e64 s[6:7], s90, v206
	v_sub_f32_e32 v208, v208, v210
	s_nop 0
	v_cndmask_b32_e64 v209, 0, 32, s[6:7]
	v_ldexp_f32 v206, v206, v209
	v_mul_f32_e32 v209, 0xbfb8aa3b, v67
	v_exp_f32_e32 v209, v209
	v_log_f32_e32 v206, v206
	v_add_f32_e32 v209, 1.0, v209
	v_rcp_f32_e32 v209, v209
	v_mul_f32_e32 v210, 0x3f317217, v206
	v_fma_f32 v210, v206, s91, -v210
	v_fmac_f32_e32 v210, 0x3377d1cf, v206
	v_fma_f32 v209, v209, v198, v131
	v_cmp_gt_f32_e32 vcc, s90, v209
	v_fmac_f32_e32 v210, 0x3f317217, v206
	v_cmp_lt_f32_e64 s[8:9], |v206|, s92
	v_cndmask_b32_e64 v211, 0, 32, vcc
	v_ldexp_f32 v209, v209, v211
	v_log_f32_e32 v209, v209
	v_cndmask_b32_e64 v206, v206, v210, s[8:9]
	v_cndmask_b32_e64 v210, 0, v186, s[6:7]
	v_sub_f32_e32 v206, v206, v210
	v_mul_f32_e32 v210, 0x3f317217, v209
	v_fma_f32 v210, v209, s91, -v210
	v_fmac_f32_e32 v210, 0x3377d1cf, v209
	v_fmac_f32_e32 v210, 0x3f317217, v209
	v_cmp_lt_f32_e64 s[6:7], |v209|, s92
	v_cvt_pk_f16_f32 v203, v203, v206
	s_nop 0
	v_cndmask_b32_e64 v209, v209, v210, s[6:7]
	v_cndmask_b32_e32 v210, 0, v186, vcc
	v_sub_f32_e32 v209, v209, v210
	v_exp_f32_e32 v210, v205
	v_cvt_pk_f16_f32 v205, v208, v209
	global_store_dwordx4 v[172:173], v[202:205], off offset:256 sc1
	v_add_u32_e32 v172, 0x80, v166
	v_add_f32_e32 v206, 1.0, v210
	v_rcp_f32_e32 v206, v206
	v_ashrrev_i32_e32 v173, 31, v172
	v_lshlrev_b64 v[172:173], 11, v[172:173]
	v_lshl_add_u64 v[172:173], v[170:171], 0, v[172:173]
	v_fma_f32 v202, v206, v201, v140
	v_cmp_gt_f32_e32 vcc, s90, v202
	s_nop 1
	v_cndmask_b32_e64 v203, 0, 32, vcc
	v_ldexp_f32 v202, v202, v203
	v_mul_f32_e32 v203, 0xbfb8aa3b, v56
	v_exp_f32_e32 v203, v203
	v_log_f32_e32 v202, v202
	v_add_f32_e32 v203, 1.0, v203
	v_rcp_f32_e32 v203, v203
	v_mul_f32_e32 v204, 0x3f317217, v202
	v_fma_f32 v204, v202, s91, -v204
	v_fmac_f32_e32 v204, 0x3377d1cf, v202
	v_fma_f32 v203, v203, v200, v136
	v_cmp_gt_f32_e64 s[6:7], s90, v203
	v_fmac_f32_e32 v204, 0x3f317217, v202
	v_cmp_lt_f32_e64 s[8:9], |v202|, s92
	v_cndmask_b32_e64 v205, 0, 32, s[6:7]
	v_ldexp_f32 v203, v203, v205
	v_mul_f32_e32 v205, 0xbfb8aa3b, v61
	v_exp_f32_e32 v205, v205
	v_log_f32_e32 v203, v203
	v_cndmask_b32_e64 v202, v202, v204, s[8:9]
	v_cndmask_b32_e32 v204, 0, v186, vcc
	v_add_f32_e32 v205, 1.0, v205
	v_sub_f32_e32 v202, v202, v204
	v_mul_f32_e32 v204, 0x3f317217, v203
	v_rcp_f32_e32 v205, v205
	v_fma_f32 v204, v203, s91, -v204
	v_fmac_f32_e32 v204, 0x3377d1cf, v203
	v_fmac_f32_e32 v204, 0x3f317217, v203
	v_cmp_lt_f32_e64 vcc, |v203|, s92
	v_fma_f32 v205, v205, v199, v141
	s_nop 0
	v_cndmask_b32_e32 v203, v203, v204, vcc
	v_cndmask_b32_e64 v204, 0, v186, s[6:7]
	v_cmp_gt_f32_e32 vcc, s90, v205
	v_sub_f32_e32 v204, v203, v204
	v_mul_f32_e32 v203, 0xbfb8aa3b, v57
	v_cndmask_b32_e64 v206, 0, 32, vcc
	v_exp_f32_e32 v203, v203
	v_ldexp_f32 v205, v205, v206
	v_log_f32_e32 v205, v205
	v_cndmask_b32_e32 v207, 0, v186, vcc
	v_add_f32_e32 v203, 1.0, v203
	v_rcp_f32_e32 v203, v203
; DI unsigned cvtpk(float lo, float hi) { f32x2 v = {lo, hi}; bf16x2_t b = __builtin_convertvector(v, bf16x2_t); return __builtin_bit_cast(unsigned, b); }
; DI unsigned cvtpk_h(float lo, float hi) { f32x2 v = {lo, hi}; h16x2_t b = __builtin_convertvector(v, h16x2_t); return __builtin_bit_cast(unsigned, b); }
; DI float sigm(float x) { return __builtin_amdgcn_rcpf(1.f + fexp(-x)); }
; DI float silu_(float x) { return x * sigm(x); }
;     template <int MODE> __device__ __forceinline__ void run(const f32x4 (&acc)[2][2][4][2], u16* dst, int ld, int row0, int col0, int trow0, int wc, int fq, const float* lb) const {
;     ...
;                     if (MODE == 3) {
; #pragma unroll
;                         for (int i = 0; i < 4; ++i) { const float l0 = lb0[bj][i], l1 = lb1[bj][i];
;                             v0[i] = __logf(l0 + (1.f - l0) * sigm(v0[i])); v1[i] = __logf(l1 + (1.f - l1) * sigm(v1[i])); }
;                     }
;                     if (MODE == 4) {
; #pragma unroll
;                         for (int i = 0; i < 4; ++i) { v0[i] = silu_(v0[i]); v1[i] = silu_(v1[i]); }
;                     }
;                     if (MODE == 5) {
; #pragma unroll
;                         for (int i = 0; i < 4; ++i) { v0[i] = sigm(v0[i]); v1[i] = sigm(v1[i]); }
;                     }
;                     u32x4 w;
;                     if (MODE == 3) { w.x = cvtpk_h(v0[0], v0[1]); w.y = cvtpk_h(v0[2], v0[3]); w.z = cvtpk_h(v1[0], v1[1]); w.w = cvtpk_h(v1[2], v1[3]); }
;                     else { w.x = cvtpk(v0[0], v0[1]); w.y = cvtpk(v0[2], v0[3]); w.z = cvtpk(v1[0], v1[1]); w.w = cvtpk(v1[2], v1[3]); }
;                     *(u32x4*)(rowp + bj * HALF) = w;
	v_mul_f32_e32 v206, 0x3f317217, v205
	v_fma_f32 v206, v205, s91, -v206
	v_fmac_f32_e32 v206, 0x3377d1cf, v205
	v_fmac_f32_e32 v206, 0x3f317217, v205
	v_cmp_lt_f32_e64 s[6:7], |v205|, s92
	v_fma_f32 v203, v203, v169, v137
	s_nop 0
	v_cndmask_b32_e64 v205, v205, v206, s[6:7]
	v_cmp_gt_f32_e64 s[6:7], s90, v203
	v_sub_f32_e32 v205, v205, v207
	v_cvt_pk_f16_f32 v202, v202, v205
	v_cndmask_b32_e64 v206, 0, 32, s[6:7]
	v_ldexp_f32 v203, v203, v206
	v_mul_f32_e32 v206, 0xbfb8aa3b, v62
	v_exp_f32_e32 v206, v206
	v_log_f32_e32 v203, v203
	v_add_f32_e32 v206, 1.0, v206
	v_rcp_f32_e32 v206, v206
	v_mul_f32_e32 v207, 0x3f317217, v203
	v_fma_f32 v207, v203, s91, -v207
	v_fmac_f32_e32 v207, 0x3377d1cf, v203
	v_fma_f32 v206, v206, v167, v142
	v_cmp_gt_f32_e32 vcc, s90, v206
	v_fmac_f32_e32 v207, 0x3f317217, v203
	v_cmp_lt_f32_e64 s[8:9], |v203|, s92
	v_cndmask_b32_e64 v208, 0, 32, vcc
	v_ldexp_f32 v206, v206, v208
	v_mul_f32_e32 v208, 0xbfb8aa3b, v58
	v_exp_f32_e32 v208, v208
	v_log_f32_e32 v206, v206
	v_cndmask_b32_e64 v203, v203, v207, s[8:9]
	v_cndmask_b32_e64 v207, 0, v186, s[6:7]
	v_add_f32_e32 v208, 1.0, v208
	v_sub_f32_e32 v207, v203, v207
	v_mul_f32_e32 v203, 0x3f317217, v206
	v_rcp_f32_e32 v208, v208
	v_fma_f32 v203, v206, s91, -v203
	v_fmac_f32_e32 v203, 0x3377d1cf, v206
	v_fmac_f32_e32 v203, 0x3f317217, v206
	v_cmp_lt_f32_e64 s[6:7], |v206|, s92
	v_fma_f32 v208, v208, v188, v138
	v_cvt_pk_f16_f32 v204, v204, v207
	v_cndmask_b32_e64 v203, v206, v203, s[6:7]
	v_cndmask_b32_e32 v206, 0, v186, vcc
	v_cmp_gt_f32_e32 vcc, s90, v208
	v_sub_f32_e32 v203, v203, v206
	v_mul_f32_e32 v206, 0xbfb8aa3b, v63
	v_cndmask_b32_e64 v209, 0, 32, vcc
	v_exp_f32_e32 v206, v206
	v_ldexp_f32 v208, v208, v209
	v_log_f32_e32 v208, v208
	v_cndmask_b32_e32 v210, 0, v186, vcc
	v_add_f32_e32 v206, 1.0, v206
	v_rcp_f32_e32 v206, v206
	v_mul_f32_e32 v209, 0x3f317217, v208
	v_fma_f32 v209, v208, s91, -v209
	v_fmac_f32_e32 v209, 0x3377d1cf, v208
	v_fmac_f32_e32 v209, 0x3f317217, v208
	v_cmp_lt_f32_e64 s[6:7], |v208|, s92
	v_fma_f32 v206, v206, v189, v143
	s_nop 0
	v_cndmask_b32_e64 v208, v208, v209, s[6:7]
	v_cmp_gt_f32_e64 s[6:7], s90, v206
	v_sub_f32_e32 v208, v208, v210
	s_nop 0
	v_cndmask_b32_e64 v209, 0, 32, s[6:7]
	v_ldexp_f32 v206, v206, v209
	v_mul_f32_e32 v209, 0xbfb8aa3b, v59
	v_exp_f32_e32 v209, v209
	v_log_f32_e32 v206, v206
	v_add_f32_e32 v209, 1.0, v209
	v_rcp_f32_e32 v209, v209
	v_mul_f32_e32 v210, 0x3f317217, v206
	v_fma_f32 v210, v206, s91, -v210
	v_fmac_f32_e32 v210, 0x3377d1cf, v206
	v_fma_f32 v209, v209, v190, v139
	v_cmp_gt_f32_e32 vcc, s90, v209
	v_fmac_f32_e32 v210, 0x3f317217, v206
	v_cmp_lt_f32_e64 s[8:9], |v206|, s92
	v_cndmask_b32_e64 v211, 0, 32, vcc
	v_ldexp_f32 v209, v209, v211
	v_log_f32_e32 v209, v209
	v_cndmask_b32_e64 v206, v206, v210, s[8:9]
	v_cndmask_b32_e64 v210, 0, v186, s[6:7]
	v_sub_f32_e32 v206, v206, v210
	v_mul_f32_e32 v210, 0x3f317217, v209
	v_mul_f32_e32 v211, 0xbfb8aa3b, v44
	v_fma_f32 v210, v209, s91, -v210
	v_exp_f32_e32 v211, v211
	v_fmac_f32_e32 v210, 0x3377d1cf, v209
	v_fmac_f32_e32 v210, 0x3f317217, v209
	v_cmp_lt_f32_e64 s[6:7], |v209|, s92
	v_cvt_pk_f16_f32 v203, v203, v206
	s_nop 0
	v_cndmask_b32_e64 v209, v209, v210, s[6:7]
	v_cndmask_b32_e32 v210, 0, v186, vcc
	v_sub_f32_e32 v209, v209, v210
	v_add_f32_e32 v210, 1.0, v211
	v_rcp_f32_e32 v210, v210
	s_nop 0
	v_fma_f32 v205, v210, v152, v132
	v_cmp_gt_f32_e32 vcc, s90, v205
	s_nop 1
	v_cndmask_b32_e64 v206, 0, 32, vcc
	v_ldexp_f32 v205, v205, v206
	v_log_f32_e32 v206, v205
	v_mul_f32_e32 v205, 0xbfb8aa3b, v40
	v_exp_f32_e32 v207, v205
	v_cvt_pk_f16_f32 v205, v208, v209
	global_store_dwordx4 v[172:173], v[202:205], off sc1
	v_cmp_lt_f32_e64 s[8:9], |v206|, s92
	s_nop 0
	v_add_f32_e32 v203, 1.0, v207
	v_rcp_f32_e32 v203, v203
	v_mul_f32_e32 v205, 0xbfb8aa3b, v45
	v_mul_f32_e32 v202, 0x3f317217, v206
	v_exp_f32_e32 v205, v205
	v_fma_f32 v203, v203, v191, v128
	v_cmp_gt_f32_e64 s[6:7], s90, v203
	v_fma_f32 v202, v206, s91, -v202
	v_fmac_f32_e32 v202, 0x3377d1cf, v206
	v_cndmask_b32_e64 v204, 0, 32, s[6:7]
	v_ldexp_f32 v203, v203, v204
	v_log_f32_e32 v203, v203
	v_fmac_f32_e32 v202, 0x3f317217, v206
	v_cndmask_b32_e64 v202, v206, v202, s[8:9]
	v_cndmask_b32_e32 v204, 0, v186, vcc
	v_add_f32_e32 v205, 1.0, v205
	v_sub_f32_e32 v202, v202, v204
	v_mul_f32_e32 v204, 0x3f317217, v203
	v_rcp_f32_e32 v205, v205
	v_fma_f32 v204, v203, s91, -v204
	v_fmac_f32_e32 v204, 0x3377d1cf, v203
	v_fmac_f32_e32 v204, 0x3f317217, v203
	v_cmp_lt_f32_e64 vcc, |v203|, s92
	v_fma_f32 v205, v205, v192, v133
	s_nop 0
	v_cndmask_b32_e32 v203, v203, v204, vcc
	v_cndmask_b32_e64 v204, 0, v186, s[6:7]
	v_cmp_gt_f32_e32 vcc, s90, v205
	v_sub_f32_e32 v204, v203, v204
	v_mul_f32_e32 v203, 0xbfb8aa3b, v41
	v_cndmask_b32_e64 v206, 0, 32, vcc
	v_exp_f32_e32 v203, v203
	v_ldexp_f32 v205, v205, v206
	v_log_f32_e32 v205, v205
	v_cndmask_b32_e32 v207, 0, v186, vcc
	v_add_f32_e32 v203, 1.0, v203
	v_rcp_f32_e32 v203, v203
	v_mul_f32_e32 v206, 0x3f317217, v205
	v_fma_f32 v206, v205, s91, -v206
	v_fmac_f32_e32 v206, 0x3377d1cf, v205
	v_fmac_f32_e32 v206, 0x3f317217, v205
	v_cmp_lt_f32_e64 s[6:7], |v205|, s92
	v_fma_f32 v203, v203, v193, v129
	s_nop 0
	v_cndmask_b32_e64 v205, v205, v206, s[6:7]
	v_cmp_gt_f32_e64 s[6:7], s90, v203
	v_sub_f32_e32 v205, v205, v207
	v_cvt_pk_f16_f32 v202, v202, v205
	v_cndmask_b32_e64 v206, 0, 32, s[6:7]
	v_ldexp_f32 v203, v203, v206
	v_mul_f32_e32 v206, 0xbfb8aa3b, v46
	v_exp_f32_e32 v206, v206
	v_log_f32_e32 v203, v203
	v_mul_f32_e32 v205, 0xbfb8aa3b, v52
	v_add_f32_e32 v206, 1.0, v206
	v_rcp_f32_e32 v206, v206
	v_mul_f32_e32 v207, 0x3f317217, v203
	v_fma_f32 v207, v203, s91, -v207
; DI unsigned cvtpk(float lo, float hi) { f32x2 v = {lo, hi}; bf16x2_t b = __builtin_convertvector(v, bf16x2_t); return __builtin_bit_cast(unsigned, b); }
; DI unsigned cvtpk_h(float lo, float hi) { f32x2 v = {lo, hi}; h16x2_t b = __builtin_convertvector(v, h16x2_t); return __builtin_bit_cast(unsigned, b); }
; DI float sigm(float x) { return __builtin_amdgcn_rcpf(1.f + fexp(-x)); }
; DI float silu_(float x) { return x * sigm(x); }
;     template <int MODE> __device__ __forceinline__ void run(const f32x4 (&acc)[2][2][4][2], u16* dst, int ld, int row0, int col0, int trow0, int wc, int fq, const float* lb) const {
;     ...
;                     if (MODE == 3) {
; #pragma unroll
;                         for (int i = 0; i < 4; ++i) { const float l0 = lb0[bj][i], l1 = lb1[bj][i];
;                             v0[i] = __logf(l0 + (1.f - l0) * sigm(v0[i])); v1[i] = __logf(l1 + (1.f - l1) * sigm(v1[i])); }
;                     }
;                     if (MODE == 4) {
; #pragma unroll
;                         for (int i = 0; i < 4; ++i) { v0[i] = silu_(v0[i]); v1[i] = silu_(v1[i]); }
;                     }
;                     if (MODE == 5) {
; #pragma unroll
;                         for (int i = 0; i < 4; ++i) { v0[i] = sigm(v0[i]); v1[i] = sigm(v1[i]); }
;                     }
;                     u32x4 w;
;                     if (MODE == 3) { w.x = cvtpk_h(v0[0], v0[1]); w.y = cvtpk_h(v0[2], v0[3]); w.z = cvtpk_h(v1[0], v1[1]); w.w = cvtpk_h(v1[2], v1[3]); }
;                     else { w.x = cvtpk(v0[0], v0[1]); w.y = cvtpk(v0[2], v0[3]); w.z = cvtpk(v1[0], v1[1]); w.w = cvtpk(v1[2], v1[3]); }
;                     *(u32x4*)(rowp + bj * HALF) = w;
	v_fmac_f32_e32 v207, 0x3377d1cf, v203
	v_fma_f32 v206, v206, v196, v134
	v_cmp_gt_f32_e32 vcc, s90, v206
	v_fmac_f32_e32 v207, 0x3f317217, v203
	v_cmp_lt_f32_e64 s[8:9], |v203|, s92
	v_cndmask_b32_e64 v208, 0, 32, vcc
	v_ldexp_f32 v206, v206, v208
	v_mul_f32_e32 v208, 0xbfb8aa3b, v42
	v_exp_f32_e32 v208, v208
	v_log_f32_e32 v206, v206
	v_cndmask_b32_e64 v203, v203, v207, s[8:9]
	v_cndmask_b32_e64 v207, 0, v186, s[6:7]
	v_add_f32_e32 v208, 1.0, v208
	v_sub_f32_e32 v207, v203, v207
	v_mul_f32_e32 v203, 0x3f317217, v206
	v_rcp_f32_e32 v208, v208
	v_fma_f32 v203, v206, s91, -v203
	v_fmac_f32_e32 v203, 0x3377d1cf, v206
	v_fmac_f32_e32 v203, 0x3f317217, v206
	v_cmp_lt_f32_e64 s[6:7], |v206|, s92
	v_fma_f32 v208, v208, v195, v130
	v_cvt_pk_f16_f32 v204, v204, v207
	v_cndmask_b32_e64 v203, v206, v203, s[6:7]
	v_cndmask_b32_e32 v206, 0, v186, vcc
	v_cmp_gt_f32_e32 vcc, s90, v208
	v_sub_f32_e32 v203, v203, v206
	v_mul_f32_e32 v206, 0xbfb8aa3b, v47
	v_cndmask_b32_e64 v209, 0, 32, vcc
	v_exp_f32_e32 v206, v206
	v_ldexp_f32 v208, v208, v209
	v_log_f32_e32 v208, v208
	v_cndmask_b32_e32 v210, 0, v186, vcc
	v_add_f32_e32 v206, 1.0, v206
	v_rcp_f32_e32 v206, v206
	v_mul_f32_e32 v209, 0x3f317217, v208
	v_fma_f32 v209, v208, s91, -v209
	v_fmac_f32_e32 v209, 0x3377d1cf, v208
	v_fmac_f32_e32 v209, 0x3f317217, v208
	v_cmp_lt_f32_e64 s[6:7], |v208|, s92
	v_fma_f32 v206, v206, v197, v135
	s_nop 0
	v_cndmask_b32_e64 v208, v208, v209, s[6:7]
	v_cmp_gt_f32_e64 s[6:7], s90, v206
	v_sub_f32_e32 v208, v208, v210
	s_nop 0
	v_cndmask_b32_e64 v209, 0, 32, s[6:7]
	v_ldexp_f32 v206, v206, v209
	v_mul_f32_e32 v209, 0xbfb8aa3b, v43
	v_exp_f32_e32 v209, v209
	v_log_f32_e32 v206, v206
	v_add_f32_e32 v209, 1.0, v209
	v_rcp_f32_e32 v209, v209
	v_mul_f32_e32 v210, 0x3f317217, v206
	v_fma_f32 v210, v206, s91, -v210
	v_fmac_f32_e32 v210, 0x3377d1cf, v206
	v_fma_f32 v209, v209, v198, v131
	v_cmp_gt_f32_e32 vcc, s90, v209
	v_fmac_f32_e32 v210, 0x3f317217, v206
	v_cmp_lt_f32_e64 s[8:9], |v206|, s92
	v_cndmask_b32_e64 v211, 0, 32, vcc
	v_ldexp_f32 v209, v209, v211
	v_log_f32_e32 v209, v209
	v_cndmask_b32_e64 v206, v206, v210, s[8:9]
	v_cndmask_b32_e64 v210, 0, v186, s[6:7]
	v_sub_f32_e32 v206, v206, v210
	v_mul_f32_e32 v210, 0x3f317217, v209
	v_fma_f32 v210, v209, s91, -v210
	v_fmac_f32_e32 v210, 0x3377d1cf, v209
	v_fmac_f32_e32 v210, 0x3f317217, v209
	v_cmp_lt_f32_e64 s[6:7], |v209|, s92
	v_cvt_pk_f16_f32 v203, v203, v206
	s_nop 0
	v_cndmask_b32_e64 v209, v209, v210, s[6:7]
	v_cndmask_b32_e32 v210, 0, v186, vcc
	v_sub_f32_e32 v209, v209, v210
	v_exp_f32_e32 v210, v205
	v_cvt_pk_f16_f32 v205, v208, v209
	global_store_dwordx4 v[172:173], v[202:205], off offset:256 sc1
	v_add_u32_e32 v172, 0x90, v166
	v_add_f32_e32 v206, 1.0, v210
	v_rcp_f32_e32 v206, v206
	v_ashrrev_i32_e32 v173, 31, v172
	v_lshlrev_b64 v[172:173], 11, v[172:173]
	v_lshl_add_u64 v[172:173], v[170:171], 0, v[172:173]
	v_fma_f32 v202, v206, v201, v140
	v_cmp_gt_f32_e32 vcc, s90, v202
	s_nop 1
	v_cndmask_b32_e64 v203, 0, 32, vcc
	v_ldexp_f32 v202, v202, v203
	v_mul_f32_e32 v203, 0xbfb8aa3b, v48
	v_exp_f32_e32 v203, v203
	v_log_f32_e32 v202, v202
	v_add_f32_e32 v203, 1.0, v203
	v_rcp_f32_e32 v203, v203
	v_mul_f32_e32 v204, 0x3f317217, v202
	v_fma_f32 v204, v202, s91, -v204
	v_fmac_f32_e32 v204, 0x3377d1cf, v202
	v_fma_f32 v203, v203, v200, v136
	v_cmp_gt_f32_e64 s[6:7], s90, v203
	v_fmac_f32_e32 v204, 0x3f317217, v202
	v_cmp_lt_f32_e64 s[8:9], |v202|, s92
	v_cndmask_b32_e64 v205, 0, 32, s[6:7]
	v_ldexp_f32 v203, v203, v205
	v_mul_f32_e32 v205, 0xbfb8aa3b, v53
	v_exp_f32_e32 v205, v205
	v_log_f32_e32 v203, v203
	v_cndmask_b32_e64 v202, v202, v204, s[8:9]
	v_cndmask_b32_e32 v204, 0, v186, vcc
	v_add_f32_e32 v205, 1.0, v205
	v_sub_f32_e32 v202, v202, v204
	v_mul_f32_e32 v204, 0x3f317217, v203
	v_rcp_f32_e32 v205, v205
	v_fma_f32 v204, v203, s91, -v204
	v_fmac_f32_e32 v204, 0x3377d1cf, v203
	v_fmac_f32_e32 v204, 0x3f317217, v203
	v_cmp_lt_f32_e64 vcc, |v203|, s92
	v_fma_f32 v205, v205, v199, v141
	s_nop 0
	v_cndmask_b32_e32 v203, v203, v204, vcc
	v_cndmask_b32_e64 v204, 0, v186, s[6:7]
	v_cmp_gt_f32_e32 vcc, s90, v205
	v_sub_f32_e32 v204, v203, v204
	v_mul_f32_e32 v203, 0xbfb8aa3b, v49
	v_cndmask_b32_e64 v206, 0, 32, vcc
	v_exp_f32_e32 v203, v203
	v_ldexp_f32 v205, v205, v206
	v_log_f32_e32 v205, v205
	v_cndmask_b32_e32 v207, 0, v186, vcc
	v_add_f32_e32 v203, 1.0, v203
	v_rcp_f32_e32 v203, v203
	v_mul_f32_e32 v206, 0x3f317217, v205
	v_fma_f32 v206, v205, s91, -v206
	v_fmac_f32_e32 v206, 0x3377d1cf, v205
	v_fmac_f32_e32 v206, 0x3f317217, v205
	v_cmp_lt_f32_e64 s[6:7], |v205|, s92
	v_fma_f32 v203, v203, v169, v137
	s_nop 0
	v_cndmask_b32_e64 v205, v205, v206, s[6:7]
	v_cmp_gt_f32_e64 s[6:7], s90, v203
	v_sub_f32_e32 v205, v205, v207
	v_cvt_pk_f16_f32 v202, v202, v205
	v_cndmask_b32_e64 v206, 0, 32, s[6:7]
	v_ldexp_f32 v203, v203, v206
	v_mul_f32_e32 v206, 0xbfb8aa3b, v54
	v_exp_f32_e32 v206, v206
	v_log_f32_e32 v203, v203
	v_add_f32_e32 v206, 1.0, v206
	v_rcp_f32_e32 v206, v206
	v_mul_f32_e32 v207, 0x3f317217, v203
	v_fma_f32 v207, v203, s91, -v207
	v_fmac_f32_e32 v207, 0x3377d1cf, v203
	v_fma_f32 v206, v206, v167, v142
	v_cmp_gt_f32_e32 vcc, s90, v206
	v_fmac_f32_e32 v207, 0x3f317217, v203
	v_cmp_lt_f32_e64 s[8:9], |v203|, s92
	v_cndmask_b32_e64 v208, 0, 32, vcc
	v_ldexp_f32 v206, v206, v208
	v_mul_f32_e32 v208, 0xbfb8aa3b, v50
	v_exp_f32_e32 v208, v208
	v_log_f32_e32 v206, v206
	v_cndmask_b32_e64 v203, v203, v207, s[8:9]
	v_cndmask_b32_e64 v207, 0, v186, s[6:7]
	v_add_f32_e32 v208, 1.0, v208
	v_sub_f32_e32 v207, v203, v207
	v_mul_f32_e32 v203, 0x3f317217, v206
	v_rcp_f32_e32 v208, v208
	v_fma_f32 v203, v206, s91, -v203
; DI unsigned cvtpk(float lo, float hi) { f32x2 v = {lo, hi}; bf16x2_t b = __builtin_convertvector(v, bf16x2_t); return __builtin_bit_cast(unsigned, b); }
; DI unsigned cvtpk_h(float lo, float hi) { f32x2 v = {lo, hi}; h16x2_t b = __builtin_convertvector(v, h16x2_t); return __builtin_bit_cast(unsigned, b); }
; DI float sigm(float x) { return __builtin_amdgcn_rcpf(1.f + fexp(-x)); }
; DI float silu_(float x) { return x * sigm(x); }
;     template <int MODE> __device__ __forceinline__ void run(const f32x4 (&acc)[2][2][4][2], u16* dst, int ld, int row0, int col0, int trow0, int wc, int fq, const float* lb) const {
;     ...
;                     if (MODE == 3) {
; #pragma unroll
;                         for (int i = 0; i < 4; ++i) { const float l0 = lb0[bj][i], l1 = lb1[bj][i];
;                             v0[i] = __logf(l0 + (1.f - l0) * sigm(v0[i])); v1[i] = __logf(l1 + (1.f - l1) * sigm(v1[i])); }
;                     }
;                     if (MODE == 4) {
; #pragma unroll
;                         for (int i = 0; i < 4; ++i) { v0[i] = silu_(v0[i]); v1[i] = silu_(v1[i]); }
;                     }
;                     if (MODE == 5) {
; #pragma unroll
;                         for (int i = 0; i < 4; ++i) { v0[i] = sigm(v0[i]); v1[i] = sigm(v1[i]); }
;                     }
;                     u32x4 w;
;                     if (MODE == 3) { w.x = cvtpk_h(v0[0], v0[1]); w.y = cvtpk_h(v0[2], v0[3]); w.z = cvtpk_h(v1[0], v1[1]); w.w = cvtpk_h(v1[2], v1[3]); }
;                     else { w.x = cvtpk(v0[0], v0[1]); w.y = cvtpk(v0[2], v0[3]); w.z = cvtpk(v1[0], v1[1]); w.w = cvtpk(v1[2], v1[3]); }
;                     *(u32x4*)(rowp + bj * HALF) = w;
	v_fmac_f32_e32 v203, 0x3377d1cf, v206
	v_fmac_f32_e32 v203, 0x3f317217, v206
	v_cmp_lt_f32_e64 s[6:7], |v206|, s92
	v_fma_f32 v208, v208, v188, v138
	v_cvt_pk_f16_f32 v204, v204, v207
	v_cndmask_b32_e64 v203, v206, v203, s[6:7]
	v_cndmask_b32_e32 v206, 0, v186, vcc
	v_cmp_gt_f32_e32 vcc, s90, v208
	v_sub_f32_e32 v203, v203, v206
	v_mul_f32_e32 v206, 0xbfb8aa3b, v55
	v_cndmask_b32_e64 v209, 0, 32, vcc
	v_exp_f32_e32 v206, v206
	v_ldexp_f32 v208, v208, v209
	v_log_f32_e32 v208, v208
	v_cndmask_b32_e32 v210, 0, v186, vcc
	v_add_f32_e32 v206, 1.0, v206
	v_rcp_f32_e32 v206, v206
	v_mul_f32_e32 v209, 0x3f317217, v208
	v_fma_f32 v209, v208, s91, -v209
	v_fmac_f32_e32 v209, 0x3377d1cf, v208
	v_fmac_f32_e32 v209, 0x3f317217, v208
	v_cmp_lt_f32_e64 s[6:7], |v208|, s92
	v_fma_f32 v206, v206, v189, v143
	s_nop 0
	v_cndmask_b32_e64 v208, v208, v209, s[6:7]
	v_cmp_gt_f32_e64 s[6:7], s90, v206
	v_sub_f32_e32 v208, v208, v210
	s_nop 0
	v_cndmask_b32_e64 v209, 0, 32, s[6:7]
	v_ldexp_f32 v206, v206, v209
	v_mul_f32_e32 v209, 0xbfb8aa3b, v51
	v_exp_f32_e32 v209, v209
	v_log_f32_e32 v206, v206
	v_add_f32_e32 v209, 1.0, v209
	v_rcp_f32_e32 v209, v209
	v_mul_f32_e32 v210, 0x3f317217, v206
	v_fma_f32 v210, v206, s91, -v210
	v_fmac_f32_e32 v210, 0x3377d1cf, v206
	v_fma_f32 v209, v209, v190, v139
	v_cmp_gt_f32_e32 vcc, s90, v209
	v_fmac_f32_e32 v210, 0x3f317217, v206
	v_cmp_lt_f32_e64 s[8:9], |v206|, s92
	v_cndmask_b32_e64 v211, 0, 32, vcc
	v_ldexp_f32 v209, v209, v211
	v_log_f32_e32 v209, v209
	v_cndmask_b32_e64 v206, v206, v210, s[8:9]
	v_cndmask_b32_e64 v210, 0, v186, s[6:7]
	v_sub_f32_e32 v206, v206, v210
	v_mul_f32_e32 v210, 0x3f317217, v209
	v_mul_f32_e32 v211, 0xbfb8aa3b, v28
	v_fma_f32 v210, v209, s91, -v210
	v_exp_f32_e32 v211, v211
	v_fmac_f32_e32 v210, 0x3377d1cf, v209
	v_fmac_f32_e32 v210, 0x3f317217, v209
	v_cmp_lt_f32_e64 s[6:7], |v209|, s92
	v_cvt_pk_f16_f32 v203, v203, v206
	s_nop 0
	v_cndmask_b32_e64 v209, v209, v210, s[6:7]
	v_cndmask_b32_e32 v210, 0, v186, vcc
	v_sub_f32_e32 v209, v209, v210
	v_add_f32_e32 v210, 1.0, v211
	v_rcp_f32_e32 v210, v210
	s_nop 0
	v_fma_f32 v205, v210, v152, v132
	v_cmp_gt_f32_e32 vcc, s90, v205
	s_nop 1
	v_cndmask_b32_e64 v206, 0, 32, vcc
	v_ldexp_f32 v205, v205, v206
	v_log_f32_e32 v206, v205
	v_mul_f32_e32 v205, 0xbfb8aa3b, v24
	v_exp_f32_e32 v207, v205
	v_cvt_pk_f16_f32 v205, v208, v209
	global_store_dwordx4 v[172:173], v[202:205], off sc1
	v_cmp_lt_f32_e64 s[8:9], |v206|, s92
	s_nop 0
	v_add_f32_e32 v203, 1.0, v207
	v_rcp_f32_e32 v203, v203
	v_mul_f32_e32 v205, 0xbfb8aa3b, v29
	v_mul_f32_e32 v202, 0x3f317217, v206
	v_exp_f32_e32 v205, v205
	v_fma_f32 v203, v203, v191, v128
	v_cmp_gt_f32_e64 s[6:7], s90, v203
	v_fma_f32 v202, v206, s91, -v202
	v_fmac_f32_e32 v202, 0x3377d1cf, v206
	v_cndmask_b32_e64 v204, 0, 32, s[6:7]
	v_ldexp_f32 v203, v203, v204
	v_log_f32_e32 v203, v203
	v_fmac_f32_e32 v202, 0x3f317217, v206
	v_cndmask_b32_e64 v202, v206, v202, s[8:9]
	v_cndmask_b32_e32 v204, 0, v186, vcc
	v_add_f32_e32 v205, 1.0, v205
	v_sub_f32_e32 v202, v202, v204
	v_mul_f32_e32 v204, 0x3f317217, v203
	v_rcp_f32_e32 v205, v205
	v_fma_f32 v204, v203, s91, -v204
	v_fmac_f32_e32 v204, 0x3377d1cf, v203
	v_fmac_f32_e32 v204, 0x3f317217, v203
	v_cmp_lt_f32_e64 vcc, |v203|, s92
	v_fma_f32 v205, v205, v192, v133
	s_nop 0
	v_cndmask_b32_e32 v203, v203, v204, vcc
	v_cndmask_b32_e64 v204, 0, v186, s[6:7]
	v_cmp_gt_f32_e32 vcc, s90, v205
	v_sub_f32_e32 v204, v203, v204
	v_mul_f32_e32 v203, 0xbfb8aa3b, v25
	v_cndmask_b32_e64 v206, 0, 32, vcc
	v_exp_f32_e32 v203, v203
	v_ldexp_f32 v205, v205, v206
	v_log_f32_e32 v205, v205
	v_cndmask_b32_e32 v207, 0, v186, vcc
	v_add_f32_e32 v203, 1.0, v203
	v_rcp_f32_e32 v203, v203
	v_mul_f32_e32 v206, 0x3f317217, v205
	v_fma_f32 v206, v205, s91, -v206
	v_fmac_f32_e32 v206, 0x3377d1cf, v205
	v_fmac_f32_e32 v206, 0x3f317217, v205
	v_cmp_lt_f32_e64 s[6:7], |v205|, s92
	v_fma_f32 v203, v203, v193, v129
	s_nop 0
	v_cndmask_b32_e64 v205, v205, v206, s[6:7]
	v_cmp_gt_f32_e64 s[6:7], s90, v203
	v_sub_f32_e32 v205, v205, v207
	v_cvt_pk_f16_f32 v202, v202, v205
	v_cndmask_b32_e64 v206, 0, 32, s[6:7]
	v_ldexp_f32 v203, v203, v206
	v_mul_f32_e32 v206, 0xbfb8aa3b, v30
	v_exp_f32_e32 v206, v206
	v_log_f32_e32 v203, v203
	v_mul_f32_e32 v205, 0xbfb8aa3b, v36
	v_add_f32_e32 v206, 1.0, v206
	v_rcp_f32_e32 v206, v206
	v_mul_f32_e32 v207, 0x3f317217, v203
	v_fma_f32 v207, v203, s91, -v207
	v_fmac_f32_e32 v207, 0x3377d1cf, v203
	v_fma_f32 v206, v206, v196, v134
	v_cmp_gt_f32_e32 vcc, s90, v206
	v_fmac_f32_e32 v207, 0x3f317217, v203
	v_cmp_lt_f32_e64 s[8:9], |v203|, s92
	v_cndmask_b32_e64 v208, 0, 32, vcc
	v_ldexp_f32 v206, v206, v208
	v_mul_f32_e32 v208, 0xbfb8aa3b, v26
	v_exp_f32_e32 v208, v208
	v_log_f32_e32 v206, v206
	v_cndmask_b32_e64 v203, v203, v207, s[8:9]
	v_cndmask_b32_e64 v207, 0, v186, s[6:7]
	v_add_f32_e32 v208, 1.0, v208
	v_sub_f32_e32 v207, v203, v207
	v_mul_f32_e32 v203, 0x3f317217, v206
	v_rcp_f32_e32 v208, v208
	v_fma_f32 v203, v206, s91, -v203
	v_fmac_f32_e32 v203, 0x3377d1cf, v206
	v_fmac_f32_e32 v203, 0x3f317217, v206
	v_cmp_lt_f32_e64 s[6:7], |v206|, s92
	v_fma_f32 v208, v208, v195, v130
	v_cvt_pk_f16_f32 v204, v204, v207
	v_cndmask_b32_e64 v203, v206, v203, s[6:7]
	v_cndmask_b32_e32 v206, 0, v186, vcc
	v_cmp_gt_f32_e32 vcc, s90, v208
	v_sub_f32_e32 v203, v203, v206
	v_mul_f32_e32 v206, 0xbfb8aa3b, v31
	v_cndmask_b32_e64 v209, 0, 32, vcc
	v_exp_f32_e32 v206, v206
	v_ldexp_f32 v208, v208, v209
	v_log_f32_e32 v208, v208
	v_cndmask_b32_e32 v210, 0, v186, vcc
	v_add_f32_e32 v206, 1.0, v206
	v_rcp_f32_e32 v206, v206
	v_mul_f32_e32 v209, 0x3f317217, v208
	v_fma_f32 v209, v208, s91, -v209
; DI unsigned cvtpk(float lo, float hi) { f32x2 v = {lo, hi}; bf16x2_t b = __builtin_convertvector(v, bf16x2_t); return __builtin_bit_cast(unsigned, b); }
; DI unsigned cvtpk_h(float lo, float hi) { f32x2 v = {lo, hi}; h16x2_t b = __builtin_convertvector(v, h16x2_t); return __builtin_bit_cast(unsigned, b); }
; DI float sigm(float x) { return __builtin_amdgcn_rcpf(1.f + fexp(-x)); }
; DI float silu_(float x) { return x * sigm(x); }
;     template <int MODE> __device__ __forceinline__ void run(const f32x4 (&acc)[2][2][4][2], u16* dst, int ld, int row0, int col0, int trow0, int wc, int fq, const float* lb) const {
;     ...
;                     if (MODE == 3) {
; #pragma unroll
;                         for (int i = 0; i < 4; ++i) { const float l0 = lb0[bj][i], l1 = lb1[bj][i];
;                             v0[i] = __logf(l0 + (1.f - l0) * sigm(v0[i])); v1[i] = __logf(l1 + (1.f - l1) * sigm(v1[i])); }
;                     }
;                     if (MODE == 4) {
; #pragma unroll
;                         for (int i = 0; i < 4; ++i) { v0[i] = silu_(v0[i]); v1[i] = silu_(v1[i]); }
;                     }
;                     if (MODE == 5) {
; #pragma unroll
;                         for (int i = 0; i < 4; ++i) { v0[i] = sigm(v0[i]); v1[i] = sigm(v1[i]); }
;                     }
;                     u32x4 w;
;                     if (MODE == 3) { w.x = cvtpk_h(v0[0], v0[1]); w.y = cvtpk_h(v0[2], v0[3]); w.z = cvtpk_h(v1[0], v1[1]); w.w = cvtpk_h(v1[2], v1[3]); }
;                     else { w.x = cvtpk(v0[0], v0[1]); w.y = cvtpk(v0[2], v0[3]); w.z = cvtpk(v1[0], v1[1]); w.w = cvtpk(v1[2], v1[3]); }
;                     *(u32x4*)(rowp + bj * HALF) = w;
	v_fmac_f32_e32 v209, 0x3377d1cf, v208
	v_fmac_f32_e32 v209, 0x3f317217, v208
	v_cmp_lt_f32_e64 s[6:7], |v208|, s92
	v_fma_f32 v206, v206, v197, v135
	s_nop 0
	v_cndmask_b32_e64 v208, v208, v209, s[6:7]
	v_cmp_gt_f32_e64 s[6:7], s90, v206
	v_sub_f32_e32 v208, v208, v210
	s_nop 0
	v_cndmask_b32_e64 v209, 0, 32, s[6:7]
	v_ldexp_f32 v206, v206, v209
	v_mul_f32_e32 v209, 0xbfb8aa3b, v27
	v_exp_f32_e32 v209, v209
	v_log_f32_e32 v206, v206
	v_add_f32_e32 v209, 1.0, v209
	v_rcp_f32_e32 v209, v209
	v_mul_f32_e32 v210, 0x3f317217, v206
	v_fma_f32 v210, v206, s91, -v210
	v_fmac_f32_e32 v210, 0x3377d1cf, v206
	v_fma_f32 v209, v209, v198, v131
	v_cmp_gt_f32_e32 vcc, s90, v209
	v_fmac_f32_e32 v210, 0x3f317217, v206
	v_cmp_lt_f32_e64 s[8:9], |v206|, s92
	v_cndmask_b32_e64 v211, 0, 32, vcc
	v_ldexp_f32 v209, v209, v211
	v_log_f32_e32 v209, v209
	v_cndmask_b32_e64 v206, v206, v210, s[8:9]
	v_cndmask_b32_e64 v210, 0, v186, s[6:7]
	v_sub_f32_e32 v206, v206, v210
	v_mul_f32_e32 v210, 0x3f317217, v209
	v_fma_f32 v210, v209, s91, -v210
	v_fmac_f32_e32 v210, 0x3377d1cf, v209
	v_fmac_f32_e32 v210, 0x3f317217, v209
	v_cmp_lt_f32_e64 s[6:7], |v209|, s92
	v_cvt_pk_f16_f32 v203, v203, v206
	s_nop 0
	v_cndmask_b32_e64 v209, v209, v210, s[6:7]
	v_cndmask_b32_e32 v210, 0, v186, vcc
	v_sub_f32_e32 v209, v209, v210
	v_exp_f32_e32 v210, v205
	v_cvt_pk_f16_f32 v205, v208, v209
	global_store_dwordx4 v[172:173], v[202:205], off offset:256 sc1
	v_add_u32_e32 v172, 0xa0, v166
	v_add_f32_e32 v206, 1.0, v210
	v_rcp_f32_e32 v206, v206
	v_ashrrev_i32_e32 v173, 31, v172
	v_lshlrev_b64 v[172:173], 11, v[172:173]
	v_lshl_add_u64 v[172:173], v[170:171], 0, v[172:173]
	v_fma_f32 v202, v206, v201, v140
	v_cmp_gt_f32_e32 vcc, s90, v202
	s_nop 1
	v_cndmask_b32_e64 v203, 0, 32, vcc
	v_ldexp_f32 v202, v202, v203
	v_mul_f32_e32 v203, 0xbfb8aa3b, v32
	v_exp_f32_e32 v203, v203
	v_log_f32_e32 v202, v202
	v_add_f32_e32 v203, 1.0, v203
	v_rcp_f32_e32 v203, v203
	v_mul_f32_e32 v204, 0x3f317217, v202
	v_fma_f32 v204, v202, s91, -v204
	v_fmac_f32_e32 v204, 0x3377d1cf, v202
	v_fma_f32 v203, v203, v200, v136
	v_cmp_gt_f32_e64 s[6:7], s90, v203
	v_fmac_f32_e32 v204, 0x3f317217, v202
	v_cmp_lt_f32_e64 s[8:9], |v202|, s92
	v_cndmask_b32_e64 v205, 0, 32, s[6:7]
	v_ldexp_f32 v203, v203, v205
	v_mul_f32_e32 v205, 0xbfb8aa3b, v37
	v_exp_f32_e32 v205, v205
	v_log_f32_e32 v203, v203
	v_cndmask_b32_e64 v202, v202, v204, s[8:9]
	v_cndmask_b32_e32 v204, 0, v186, vcc
	v_add_f32_e32 v205, 1.0, v205
	v_sub_f32_e32 v202, v202, v204
	v_mul_f32_e32 v204, 0x3f317217, v203
	v_rcp_f32_e32 v205, v205
	v_fma_f32 v204, v203, s91, -v204
	v_fmac_f32_e32 v204, 0x3377d1cf, v203
	v_fmac_f32_e32 v204, 0x3f317217, v203
	v_cmp_lt_f32_e64 vcc, |v203|, s92
	v_fma_f32 v205, v205, v199, v141
	s_nop 0
	v_cndmask_b32_e32 v203, v203, v204, vcc
	v_cndmask_b32_e64 v204, 0, v186, s[6:7]
	v_cmp_gt_f32_e32 vcc, s90, v205
	v_sub_f32_e32 v204, v203, v204
	v_mul_f32_e32 v203, 0xbfb8aa3b, v33
	v_cndmask_b32_e64 v206, 0, 32, vcc
	v_exp_f32_e32 v203, v203
	v_ldexp_f32 v205, v205, v206
	v_log_f32_e32 v205, v205
	v_cndmask_b32_e32 v207, 0, v186, vcc
	v_add_f32_e32 v203, 1.0, v203
	v_rcp_f32_e32 v203, v203
	v_mul_f32_e32 v206, 0x3f317217, v205
	v_fma_f32 v206, v205, s91, -v206
	v_fmac_f32_e32 v206, 0x3377d1cf, v205
	v_fmac_f32_e32 v206, 0x3f317217, v205
	v_cmp_lt_f32_e64 s[6:7], |v205|, s92
	v_fma_f32 v203, v203, v169, v137
	s_nop 0
	v_cndmask_b32_e64 v205, v205, v206, s[6:7]
	v_cmp_gt_f32_e64 s[6:7], s90, v203
	v_sub_f32_e32 v205, v205, v207
	v_cvt_pk_f16_f32 v202, v202, v205
	v_cndmask_b32_e64 v206, 0, 32, s[6:7]
	v_ldexp_f32 v203, v203, v206
	v_mul_f32_e32 v206, 0xbfb8aa3b, v38
	v_exp_f32_e32 v206, v206
	v_log_f32_e32 v203, v203
	v_add_f32_e32 v206, 1.0, v206
	v_rcp_f32_e32 v206, v206
	v_mul_f32_e32 v207, 0x3f317217, v203
	v_fma_f32 v207, v203, s91, -v207
	v_fmac_f32_e32 v207, 0x3377d1cf, v203
	v_fma_f32 v206, v206, v167, v142
	v_cmp_gt_f32_e32 vcc, s90, v206
	v_fmac_f32_e32 v207, 0x3f317217, v203
	v_cmp_lt_f32_e64 s[8:9], |v203|, s92
	v_cndmask_b32_e64 v208, 0, 32, vcc
	v_ldexp_f32 v206, v206, v208
	v_mul_f32_e32 v208, 0xbfb8aa3b, v34
	v_exp_f32_e32 v208, v208
	v_log_f32_e32 v206, v206
	v_cndmask_b32_e64 v203, v203, v207, s[8:9]
	v_cndmask_b32_e64 v207, 0, v186, s[6:7]
	v_add_f32_e32 v208, 1.0, v208
	v_sub_f32_e32 v207, v203, v207
	v_mul_f32_e32 v203, 0x3f317217, v206
	v_rcp_f32_e32 v208, v208
	v_fma_f32 v203, v206, s91, -v203
	v_fmac_f32_e32 v203, 0x3377d1cf, v206
	v_fmac_f32_e32 v203, 0x3f317217, v206
	v_cmp_lt_f32_e64 s[6:7], |v206|, s92
	v_fma_f32 v208, v208, v188, v138
	v_cvt_pk_f16_f32 v204, v204, v207
	v_cndmask_b32_e64 v203, v206, v203, s[6:7]
	v_cndmask_b32_e32 v206, 0, v186, vcc
	v_cmp_gt_f32_e32 vcc, s90, v208
	v_sub_f32_e32 v203, v203, v206
	v_mul_f32_e32 v206, 0xbfb8aa3b, v39
	v_cndmask_b32_e64 v209, 0, 32, vcc
	v_exp_f32_e32 v206, v206
	v_ldexp_f32 v208, v208, v209
	v_log_f32_e32 v208, v208
	v_cndmask_b32_e32 v210, 0, v186, vcc
	v_add_f32_e32 v206, 1.0, v206
	v_rcp_f32_e32 v206, v206
	v_mul_f32_e32 v209, 0x3f317217, v208
	v_fma_f32 v209, v208, s91, -v209
	v_fmac_f32_e32 v209, 0x3377d1cf, v208
	v_fmac_f32_e32 v209, 0x3f317217, v208
	v_cmp_lt_f32_e64 s[6:7], |v208|, s92
	v_fma_f32 v206, v206, v189, v143
	s_nop 0
	v_cndmask_b32_e64 v208, v208, v209, s[6:7]
	v_cmp_gt_f32_e64 s[6:7], s90, v206
	v_sub_f32_e32 v208, v208, v210
	s_nop 0
	v_cndmask_b32_e64 v209, 0, 32, s[6:7]
	v_ldexp_f32 v206, v206, v209
	v_mul_f32_e32 v209, 0xbfb8aa3b, v35
	v_exp_f32_e32 v209, v209
	v_log_f32_e32 v206, v206
	v_add_f32_e32 v209, 1.0, v209
	v_rcp_f32_e32 v209, v209
	v_mul_f32_e32 v210, 0x3f317217, v206
	v_fma_f32 v210, v206, s91, -v210
	v_fmac_f32_e32 v210, 0x3377d1cf, v206
; DI unsigned cvtpk(float lo, float hi) { f32x2 v = {lo, hi}; bf16x2_t b = __builtin_convertvector(v, bf16x2_t); return __builtin_bit_cast(unsigned, b); }
; DI unsigned cvtpk_h(float lo, float hi) { f32x2 v = {lo, hi}; h16x2_t b = __builtin_convertvector(v, h16x2_t); return __builtin_bit_cast(unsigned, b); }
; DI float sigm(float x) { return __builtin_amdgcn_rcpf(1.f + fexp(-x)); }
; DI float silu_(float x) { return x * sigm(x); }
;     template <int MODE> __device__ __forceinline__ void run(const f32x4 (&acc)[2][2][4][2], u16* dst, int ld, int row0, int col0, int trow0, int wc, int fq, const float* lb) const {
;     ...
;                     if (MODE == 3) {
; #pragma unroll
;                         for (int i = 0; i < 4; ++i) { const float l0 = lb0[bj][i], l1 = lb1[bj][i];
;                             v0[i] = __logf(l0 + (1.f - l0) * sigm(v0[i])); v1[i] = __logf(l1 + (1.f - l1) * sigm(v1[i])); }
;                     }
;                     if (MODE == 4) {
; #pragma unroll
;                         for (int i = 0; i < 4; ++i) { v0[i] = silu_(v0[i]); v1[i] = silu_(v1[i]); }
;                     }
;                     if (MODE == 5) {
; #pragma unroll
;                         for (int i = 0; i < 4; ++i) { v0[i] = sigm(v0[i]); v1[i] = sigm(v1[i]); }
;                     }
;                     u32x4 w;
;                     if (MODE == 3) { w.x = cvtpk_h(v0[0], v0[1]); w.y = cvtpk_h(v0[2], v0[3]); w.z = cvtpk_h(v1[0], v1[1]); w.w = cvtpk_h(v1[2], v1[3]); }
;                     else { w.x = cvtpk(v0[0], v0[1]); w.y = cvtpk(v0[2], v0[3]); w.z = cvtpk(v1[0], v1[1]); w.w = cvtpk(v1[2], v1[3]); }
;                     *(u32x4*)(rowp + bj * HALF) = w;
	v_fma_f32 v209, v209, v190, v139
	v_cmp_gt_f32_e32 vcc, s90, v209
	v_fmac_f32_e32 v210, 0x3f317217, v206
	v_cmp_lt_f32_e64 s[8:9], |v206|, s92
	v_cndmask_b32_e64 v211, 0, 32, vcc
	v_ldexp_f32 v209, v209, v211
	v_log_f32_e32 v209, v209
	v_cndmask_b32_e64 v206, v206, v210, s[8:9]
	v_cndmask_b32_e64 v210, 0, v186, s[6:7]
	v_sub_f32_e32 v206, v206, v210
	v_mul_f32_e32 v210, 0x3f317217, v209
	v_mul_f32_e32 v211, 0xbfb8aa3b, v12
	v_fma_f32 v210, v209, s91, -v210
	v_exp_f32_e32 v211, v211
	v_fmac_f32_e32 v210, 0x3377d1cf, v209
	v_fmac_f32_e32 v210, 0x3f317217, v209
	v_cmp_lt_f32_e64 s[6:7], |v209|, s92
	v_cvt_pk_f16_f32 v203, v203, v206
	s_nop 0
	v_cndmask_b32_e64 v209, v209, v210, s[6:7]
	v_cndmask_b32_e32 v210, 0, v186, vcc
	v_sub_f32_e32 v209, v209, v210
	v_add_f32_e32 v210, 1.0, v211
	v_rcp_f32_e32 v210, v210
	s_nop 0
	v_fma_f32 v205, v210, v152, v132
	v_cmp_gt_f32_e32 vcc, s90, v205
	s_nop 1
	v_cndmask_b32_e64 v206, 0, 32, vcc
	v_ldexp_f32 v205, v205, v206
	v_log_f32_e32 v206, v205
	v_mul_f32_e32 v205, 0xbfb8aa3b, v8
	v_exp_f32_e32 v207, v205
	v_cvt_pk_f16_f32 v205, v208, v209
	global_store_dwordx4 v[172:173], v[202:205], off sc1
	v_cmp_lt_f32_e64 s[8:9], |v206|, s92
	s_nop 0
	v_add_f32_e32 v203, 1.0, v207
	v_rcp_f32_e32 v203, v203
	v_mul_f32_e32 v205, 0xbfb8aa3b, v13
	v_mul_f32_e32 v202, 0x3f317217, v206
	v_exp_f32_e32 v205, v205
	v_fma_f32 v203, v203, v191, v128
	v_cmp_gt_f32_e64 s[6:7], s90, v203
	v_fma_f32 v202, v206, s91, -v202
	v_fmac_f32_e32 v202, 0x3377d1cf, v206
	v_cndmask_b32_e64 v204, 0, 32, s[6:7]
	v_ldexp_f32 v203, v203, v204
	v_log_f32_e32 v203, v203
	v_fmac_f32_e32 v202, 0x3f317217, v206
	v_cndmask_b32_e64 v202, v206, v202, s[8:9]
	v_cndmask_b32_e32 v204, 0, v186, vcc
	v_add_f32_e32 v205, 1.0, v205
	v_sub_f32_e32 v202, v202, v204
	v_mul_f32_e32 v204, 0x3f317217, v203
	v_rcp_f32_e32 v205, v205
	v_fma_f32 v204, v203, s91, -v204
	v_fmac_f32_e32 v204, 0x3377d1cf, v203
	v_fmac_f32_e32 v204, 0x3f317217, v203
	v_cmp_lt_f32_e64 vcc, |v203|, s92
	v_fma_f32 v205, v205, v192, v133
	s_nop 0
	v_cndmask_b32_e32 v203, v203, v204, vcc
	v_cndmask_b32_e64 v204, 0, v186, s[6:7]
	v_cmp_gt_f32_e32 vcc, s90, v205
	v_sub_f32_e32 v204, v203, v204
	v_mul_f32_e32 v203, 0xbfb8aa3b, v9
	v_cndmask_b32_e64 v206, 0, 32, vcc
	v_exp_f32_e32 v203, v203
	v_ldexp_f32 v205, v205, v206
	v_log_f32_e32 v205, v205
	v_cndmask_b32_e32 v207, 0, v186, vcc
	v_add_f32_e32 v203, 1.0, v203
	v_rcp_f32_e32 v203, v203
	v_mul_f32_e32 v206, 0x3f317217, v205
	v_fma_f32 v206, v205, s91, -v206
	v_fmac_f32_e32 v206, 0x3377d1cf, v205
	v_fmac_f32_e32 v206, 0x3f317217, v205
	v_cmp_lt_f32_e64 s[6:7], |v205|, s92
	v_fma_f32 v203, v203, v193, v129
	s_nop 0
	v_cndmask_b32_e64 v205, v205, v206, s[6:7]
	v_cmp_gt_f32_e64 s[6:7], s90, v203
	v_sub_f32_e32 v205, v205, v207
	v_cvt_pk_f16_f32 v202, v202, v205
	v_cndmask_b32_e64 v206, 0, 32, s[6:7]
	v_ldexp_f32 v203, v203, v206
	v_mul_f32_e32 v206, 0xbfb8aa3b, v14
	v_exp_f32_e32 v206, v206
	v_log_f32_e32 v203, v203
	v_mul_f32_e32 v205, 0xbfb8aa3b, v20
	v_add_f32_e32 v206, 1.0, v206
	v_rcp_f32_e32 v206, v206
	v_mul_f32_e32 v207, 0x3f317217, v203
	v_fma_f32 v207, v203, s91, -v207
	v_fmac_f32_e32 v207, 0x3377d1cf, v203
	v_fma_f32 v206, v206, v196, v134
	v_cmp_gt_f32_e32 vcc, s90, v206
	v_fmac_f32_e32 v207, 0x3f317217, v203
	v_cmp_lt_f32_e64 s[8:9], |v203|, s92
	v_cndmask_b32_e64 v208, 0, 32, vcc
	v_ldexp_f32 v206, v206, v208
	v_mul_f32_e32 v208, 0xbfb8aa3b, v10
	v_exp_f32_e32 v208, v208
	v_log_f32_e32 v206, v206
	v_cndmask_b32_e64 v203, v203, v207, s[8:9]
	v_cndmask_b32_e64 v207, 0, v186, s[6:7]
	v_add_f32_e32 v208, 1.0, v208
	v_sub_f32_e32 v207, v203, v207
	v_mul_f32_e32 v203, 0x3f317217, v206
	v_rcp_f32_e32 v208, v208
	v_fma_f32 v203, v206, s91, -v203
	v_fmac_f32_e32 v203, 0x3377d1cf, v206
	v_fmac_f32_e32 v203, 0x3f317217, v206
	v_cmp_lt_f32_e64 s[6:7], |v206|, s92
	v_fma_f32 v208, v208, v195, v130
	v_cvt_pk_f16_f32 v204, v204, v207
	v_cndmask_b32_e64 v203, v206, v203, s[6:7]
	v_cndmask_b32_e32 v206, 0, v186, vcc
	v_cmp_gt_f32_e32 vcc, s90, v208
	v_sub_f32_e32 v203, v203, v206
	v_mul_f32_e32 v206, 0xbfb8aa3b, v15
	v_cndmask_b32_e64 v209, 0, 32, vcc
	v_exp_f32_e32 v206, v206
	v_ldexp_f32 v208, v208, v209
	v_log_f32_e32 v208, v208
	v_cndmask_b32_e32 v210, 0, v186, vcc
	v_add_f32_e32 v206, 1.0, v206
	v_rcp_f32_e32 v206, v206
	v_mul_f32_e32 v209, 0x3f317217, v208
	v_fma_f32 v209, v208, s91, -v209
	v_fmac_f32_e32 v209, 0x3377d1cf, v208
	v_fmac_f32_e32 v209, 0x3f317217, v208
	v_cmp_lt_f32_e64 s[6:7], |v208|, s92
	v_fma_f32 v206, v206, v197, v135
	s_nop 0
	v_cndmask_b32_e64 v208, v208, v209, s[6:7]
	v_cmp_gt_f32_e64 s[6:7], s90, v206
	v_sub_f32_e32 v208, v208, v210
	s_nop 0
	v_cndmask_b32_e64 v209, 0, 32, s[6:7]
	v_ldexp_f32 v206, v206, v209
	v_mul_f32_e32 v209, 0xbfb8aa3b, v11
	v_exp_f32_e32 v209, v209
	v_log_f32_e32 v206, v206
	v_add_f32_e32 v209, 1.0, v209
	v_rcp_f32_e32 v209, v209
	v_mul_f32_e32 v210, 0x3f317217, v206
	v_fma_f32 v210, v206, s91, -v210
	v_fmac_f32_e32 v210, 0x3377d1cf, v206
	v_fma_f32 v209, v209, v198, v131
	v_cmp_gt_f32_e32 vcc, s90, v209
	v_fmac_f32_e32 v210, 0x3f317217, v206
	v_cmp_lt_f32_e64 s[8:9], |v206|, s92
	v_cndmask_b32_e64 v211, 0, 32, vcc
	v_ldexp_f32 v209, v209, v211
	v_log_f32_e32 v209, v209
	v_cndmask_b32_e64 v206, v206, v210, s[8:9]
	v_cndmask_b32_e64 v210, 0, v186, s[6:7]
	v_sub_f32_e32 v206, v206, v210
	v_mul_f32_e32 v210, 0x3f317217, v209
	v_fma_f32 v210, v209, s91, -v210
	v_fmac_f32_e32 v210, 0x3377d1cf, v209
	v_fmac_f32_e32 v210, 0x3f317217, v209
	v_cmp_lt_f32_e64 s[6:7], |v209|, s92
	v_cvt_pk_f16_f32 v203, v203, v206
	s_nop 0
	v_cndmask_b32_e64 v209, v209, v210, s[6:7]
	v_cndmask_b32_e32 v210, 0, v186, vcc
; DI unsigned cvtpk(float lo, float hi) { f32x2 v = {lo, hi}; bf16x2_t b = __builtin_convertvector(v, bf16x2_t); return __builtin_bit_cast(unsigned, b); }
; DI unsigned cvtpk_h(float lo, float hi) { f32x2 v = {lo, hi}; h16x2_t b = __builtin_convertvector(v, h16x2_t); return __builtin_bit_cast(unsigned, b); }
; DI float sigm(float x) { return __builtin_amdgcn_rcpf(1.f + fexp(-x)); }
; DI float silu_(float x) { return x * sigm(x); }
;     template <int MODE> __device__ __forceinline__ void run(const f32x4 (&acc)[2][2][4][2], u16* dst, int ld, int row0, int col0, int trow0, int wc, int fq, const float* lb) const {
;     ...
;                     if (MODE == 3) {
; #pragma unroll
;                         for (int i = 0; i < 4; ++i) { const float l0 = lb0[bj][i], l1 = lb1[bj][i];
;                             v0[i] = __logf(l0 + (1.f - l0) * sigm(v0[i])); v1[i] = __logf(l1 + (1.f - l1) * sigm(v1[i])); }
;                     }
;                     if (MODE == 4) {
; #pragma unroll
;                         for (int i = 0; i < 4; ++i) { v0[i] = silu_(v0[i]); v1[i] = silu_(v1[i]); }
;                     }
;                     if (MODE == 5) {
; #pragma unroll
;                         for (int i = 0; i < 4; ++i) { v0[i] = sigm(v0[i]); v1[i] = sigm(v1[i]); }
;                     }
;                     u32x4 w;
;                     if (MODE == 3) { w.x = cvtpk_h(v0[0], v0[1]); w.y = cvtpk_h(v0[2], v0[3]); w.z = cvtpk_h(v1[0], v1[1]); w.w = cvtpk_h(v1[2], v1[3]); }
;                     else { w.x = cvtpk(v0[0], v0[1]); w.y = cvtpk(v0[2], v0[3]); w.z = cvtpk(v1[0], v1[1]); w.w = cvtpk(v1[2], v1[3]); }
;                     *(u32x4*)(rowp + bj * HALF) = w;
	v_sub_f32_e32 v209, v209, v210
	v_exp_f32_e32 v210, v205
	v_cvt_pk_f16_f32 v205, v208, v209
	global_store_dwordx4 v[172:173], v[202:205], off offset:256 sc1
	v_add_u32_e32 v172, 0xb0, v166
	v_add_f32_e32 v206, 1.0, v210
	v_rcp_f32_e32 v206, v206
	v_ashrrev_i32_e32 v173, 31, v172
	v_lshlrev_b64 v[172:173], 11, v[172:173]
	v_lshl_add_u64 v[170:171], v[170:171], 0, v[172:173]
	v_fma_f32 v140, v206, v201, v140
	v_cmp_gt_f32_e32 vcc, s90, v140
	s_nop 1
	v_cndmask_b32_e64 v201, 0, 32, vcc
	v_ldexp_f32 v140, v140, v201
	v_mul_f32_e32 v201, 0xbfb8aa3b, v16
	v_exp_f32_e32 v201, v201
	v_log_f32_e32 v140, v140
	v_add_f32_e32 v173, 1.0, v201
	v_rcp_f32_e32 v173, v173
	v_mul_f32_e32 v172, 0x3f317217, v140
	v_fma_f32 v172, v140, s91, -v172
	v_fmac_f32_e32 v172, 0x3377d1cf, v140
	v_fma_f32 v136, v173, v200, v136
	v_cmp_gt_f32_e64 s[6:7], s90, v136
	v_fmac_f32_e32 v172, 0x3f317217, v140
	v_cmp_lt_f32_e64 s[8:9], |v140|, s92
	v_cndmask_b32_e64 v173, 0, 32, s[6:7]
	v_ldexp_f32 v136, v136, v173
	v_mul_f32_e32 v173, 0xbfb8aa3b, v21
	v_exp_f32_e32 v173, v173
	v_log_f32_e32 v136, v136
	v_cndmask_b32_e64 v140, v140, v172, s[8:9]
	v_cndmask_b32_e32 v172, 0, v186, vcc
	v_add_f32_e32 v173, 1.0, v173
	v_sub_f32_e32 v140, v140, v172
	v_mul_f32_e32 v172, 0x3f317217, v136
	v_rcp_f32_e32 v173, v173
	v_fma_f32 v172, v136, s91, -v172
	v_fmac_f32_e32 v172, 0x3377d1cf, v136
	v_fmac_f32_e32 v172, 0x3f317217, v136
	v_cmp_lt_f32_e64 vcc, |v136|, s92
	v_fma_f32 v141, v173, v199, v141
	s_nop 0
	v_cndmask_b32_e32 v136, v136, v172, vcc
	v_cndmask_b32_e64 v172, 0, v186, s[6:7]
	v_cmp_gt_f32_e32 vcc, s90, v141
	v_sub_f32_e32 v172, v136, v172
	v_mul_f32_e32 v136, 0xbfb8aa3b, v17
	v_cndmask_b32_e64 v173, 0, 32, vcc
	v_exp_f32_e32 v136, v136
	v_ldexp_f32 v141, v141, v173
	v_log_f32_e32 v141, v141
	v_add_f32_e32 v136, 1.0, v136
	v_rcp_f32_e32 v136, v136
	v_mul_f32_e32 v173, 0x3f317217, v141
	v_fma_f32 v173, v141, s91, -v173
	v_fmac_f32_e32 v173, 0x3377d1cf, v141
	v_fmac_f32_e32 v173, 0x3f317217, v141
	v_cmp_lt_f32_e64 s[6:7], |v141|, s92
	v_fma_f32 v136, v136, v169, v137
	v_cndmask_b32_e32 v169, 0, v186, vcc
	v_cndmask_b32_e64 v141, v141, v173, s[6:7]
	v_cmp_gt_f32_e64 s[6:7], s90, v136
	v_sub_f32_e32 v141, v141, v169
	s_nop 0
	v_cndmask_b32_e64 v137, 0, 32, s[6:7]
	v_ldexp_f32 v136, v136, v137
	v_mul_f32_e32 v137, 0xbfb8aa3b, v22
	v_exp_f32_e32 v137, v137
	v_log_f32_e32 v136, v136
	v_add_f32_e32 v137, 1.0, v137
	v_rcp_f32_e32 v137, v137
	v_mul_f32_e32 v169, 0x3f317217, v136
	v_fma_f32 v169, v136, s91, -v169
	v_fmac_f32_e32 v169, 0x3377d1cf, v136
	v_fma_f32 v137, v137, v167, v142
	v_cmp_gt_f32_e32 vcc, s90, v137
	v_mul_f32_e32 v167, 0xbfb8aa3b, v18
	v_exp_f32_e32 v167, v167
	v_cndmask_b32_e64 v142, 0, 32, vcc
	v_ldexp_f32 v137, v137, v142
	v_log_f32_e32 v137, v137
	v_fmac_f32_e32 v169, 0x3f317217, v136
	v_cmp_lt_f32_e64 s[8:9], |v136|, s92
	v_cndmask_b32_e64 v142, 0, v186, s[6:7]
	v_add_f32_e32 v167, 1.0, v167
	v_cndmask_b32_e64 v136, v136, v169, s[8:9]
	v_sub_f32_e32 v142, v136, v142
	v_mul_f32_e32 v136, 0x3f317217, v137
	v_rcp_f32_e32 v167, v167
	v_fma_f32 v136, v137, s91, -v136
	v_fmac_f32_e32 v136, 0x3377d1cf, v137
	v_fmac_f32_e32 v136, 0x3f317217, v137
	v_cmp_lt_f32_e64 s[6:7], |v137|, s92
	v_fma_f32 v138, v167, v188, v138
	s_nop 0
	v_cndmask_b32_e64 v136, v137, v136, s[6:7]
	v_cndmask_b32_e32 v137, 0, v186, vcc
	v_cmp_gt_f32_e32 vcc, s90, v138
	v_sub_f32_e32 v137, v136, v137
	v_mul_f32_e32 v136, 0xbfb8aa3b, v23
	v_cndmask_b32_e64 v167, 0, 32, vcc
	v_exp_f32_e32 v136, v136
	v_ldexp_f32 v138, v138, v167
	v_log_f32_e32 v138, v138
	v_add_f32_e32 v136, 1.0, v136
	v_rcp_f32_e32 v136, v136
	v_mul_f32_e32 v167, 0x3f317217, v138
	v_fma_f32 v167, v138, s91, -v167
	v_fmac_f32_e32 v167, 0x3377d1cf, v138
	v_fmac_f32_e32 v167, 0x3f317217, v138
	v_cmp_lt_f32_e64 s[6:7], |v138|, s92
	v_fmac_f32_e32 v143, v136, v189
	s_nop 0
	v_cndmask_b32_e64 v138, v138, v167, s[6:7]
	v_cmp_gt_f32_e64 s[6:7], s90, v143
	v_cndmask_b32_e32 v167, 0, v186, vcc
	v_sub_f32_e32 v167, v138, v167
	v_cndmask_b32_e64 v136, 0, 32, s[6:7]
	v_ldexp_f32 v136, v143, v136
	v_mul_f32_e32 v143, 0xbfb8aa3b, v19
	v_exp_f32_e32 v143, v143
	v_log_f32_e32 v136, v136
	v_add_f32_e32 v143, 1.0, v143
	v_rcp_f32_e32 v143, v143
	v_mul_f32_e32 v138, 0x3f317217, v136
	v_fma_f32 v138, v136, s91, -v138
	v_fmac_f32_e32 v138, 0x3377d1cf, v136
	v_fmac_f32_e32 v139, v143, v190
	v_cmp_gt_f32_e32 vcc, s90, v139
	v_fmac_f32_e32 v138, 0x3f317217, v136
	v_cmp_lt_f32_e64 s[8:9], |v136|, s92
	v_cndmask_b32_e64 v143, 0, 32, vcc
	v_ldexp_f32 v139, v139, v143
	v_log_f32_e32 v139, v139
	v_cndmask_b32_e64 v136, v136, v138, s[8:9]
	v_cndmask_b32_e64 v138, 0, v186, s[6:7]
	v_sub_f32_e32 v138, v136, v138
	v_mul_f32_e32 v136, 0x3f317217, v139
	v_mul_f32_e32 v143, 0xbfb8aa3b, v4
	v_fma_f32 v136, v139, s91, -v136
	v_exp_f32_e32 v143, v143
	v_fmac_f32_e32 v136, 0x3377d1cf, v139
	v_fmac_f32_e32 v136, 0x3f317217, v139
	v_cmp_lt_f32_e64 s[6:7], |v139|, s92
	v_cvt_pk_f16_f32 v137, v137, v138
	v_cvt_pk_f16_f32 v138, v172, v142
; DI unsigned cvtpk(float lo, float hi) { f32x2 v = {lo, hi}; bf16x2_t b = __builtin_convertvector(v, bf16x2_t); return __builtin_bit_cast(unsigned, b); }
; DI unsigned cvtpk_h(float lo, float hi) { f32x2 v = {lo, hi}; h16x2_t b = __builtin_convertvector(v, h16x2_t); return __builtin_bit_cast(unsigned, b); }
; DI float sigm(float x) { return __builtin_amdgcn_rcpf(1.f + fexp(-x)); }
; DI float silu_(float x) { return x * sigm(x); }
;     template <int MODE> __device__ __forceinline__ void run(const f32x4 (&acc)[2][2][4][2], u16* dst, int ld, int row0, int col0, int trow0, int wc, int fq, const float* lb) const {
;     ...
;                     if (MODE == 3) {
; #pragma unroll
;                         for (int i = 0; i < 4; ++i) { const float l0 = lb0[bj][i], l1 = lb1[bj][i];
;                             v0[i] = __logf(l0 + (1.f - l0) * sigm(v0[i])); v1[i] = __logf(l1 + (1.f - l1) * sigm(v1[i])); }
;                     }
;                     if (MODE == 4) {
; #pragma unroll
;                         for (int i = 0; i < 4; ++i) { v0[i] = silu_(v0[i]); v1[i] = silu_(v1[i]); }
;                     }
;                     if (MODE == 5) {
; #pragma unroll
;                         for (int i = 0; i < 4; ++i) { v0[i] = sigm(v0[i]); v1[i] = sigm(v1[i]); }
;                     }
;                     u32x4 w;
;                     if (MODE == 3) { w.x = cvtpk_h(v0[0], v0[1]); w.y = cvtpk_h(v0[2], v0[3]); w.z = cvtpk_h(v1[0], v1[1]); w.w = cvtpk_h(v1[2], v1[3]); }
;                     else { w.x = cvtpk(v0[0], v0[1]); w.y = cvtpk(v0[2], v0[3]); w.z = cvtpk(v1[0], v1[1]); w.w = cvtpk(v1[2], v1[3]); }
;                     *(u32x4*)(rowp + bj * HALF) = w;
	v_cndmask_b32_e64 v136, v139, v136, s[6:7]
	v_cndmask_b32_e32 v139, 0, v186, vcc
	v_sub_f32_e32 v139, v136, v139
	v_add_f32_e32 v136, 1.0, v143
	v_rcp_f32_e32 v143, v136
	v_cvt_pk_f16_f32 v136, v140, v141
	v_cvt_pk_f16_f32 v139, v167, v139
	global_store_dwordx4 v[170:171], v[136:139], off sc1
	v_fma_f32 v132, v143, v152, v132
	v_cmp_gt_f32_e32 vcc, s90, v132
	s_nop 1
	v_cndmask_b32_e64 v140, 0, 32, vcc
	v_ldexp_f32 v132, v132, v140
	v_mul_f32_e32 v140, 0xbfb8aa3b, v0
	v_exp_f32_e32 v140, v140
	v_log_f32_e32 v132, v132
	v_add_f32_e32 v137, 1.0, v140
	v_rcp_f32_e32 v137, v137
	v_mul_f32_e32 v136, 0x3f317217, v132
	v_fma_f32 v136, v132, s91, -v136
	v_fmac_f32_e32 v136, 0x3377d1cf, v132
	v_fma_f32 v128, v137, v191, v128
	v_cmp_gt_f32_e64 s[6:7], s90, v128
	v_fmac_f32_e32 v136, 0x3f317217, v132
	v_cmp_lt_f32_e64 s[8:9], |v132|, s92
	v_cndmask_b32_e64 v137, 0, 32, s[6:7]
	v_ldexp_f32 v128, v128, v137
	v_mul_f32_e32 v137, 0xbfb8aa3b, v5
	v_exp_f32_e32 v137, v137
	v_log_f32_e32 v128, v128
	v_cndmask_b32_e64 v132, v132, v136, s[8:9]
	v_cndmask_b32_e32 v136, 0, v186, vcc
	v_add_f32_e32 v137, 1.0, v137
	v_sub_f32_e32 v132, v132, v136
	v_mul_f32_e32 v136, 0x3f317217, v128
	v_rcp_f32_e32 v137, v137
	v_fma_f32 v136, v128, s91, -v136
	v_fmac_f32_e32 v136, 0x3377d1cf, v128
	v_fmac_f32_e32 v136, 0x3f317217, v128
	v_cmp_lt_f32_e64 vcc, |v128|, s92
	v_fma_f32 v133, v137, v192, v133
	s_nop 0
	v_cndmask_b32_e32 v128, v128, v136, vcc
	v_cndmask_b32_e64 v136, 0, v186, s[6:7]
	v_cmp_gt_f32_e32 vcc, s90, v133
	v_sub_f32_e32 v136, v128, v136
	v_mul_f32_e32 v128, 0xbfb8aa3b, v1
	v_cndmask_b32_e64 v137, 0, 32, vcc
	v_exp_f32_e32 v128, v128
	v_ldexp_f32 v133, v133, v137
	v_log_f32_e32 v133, v133
	v_add_f32_e32 v128, 1.0, v128
	v_rcp_f32_e32 v128, v128
	v_mul_f32_e32 v137, 0x3f317217, v133
	v_fma_f32 v137, v133, s91, -v137
	v_fmac_f32_e32 v137, 0x3377d1cf, v133
	v_fmac_f32_e32 v137, 0x3f317217, v133
	v_cmp_lt_f32_e64 s[6:7], |v133|, s92
	v_fma_f32 v128, v128, v193, v129
	s_nop 0
	v_cndmask_b32_e64 v133, v133, v137, s[6:7]
	v_cmp_gt_f32_e64 s[6:7], s90, v128
	v_cndmask_b32_e32 v137, 0, v186, vcc
	v_sub_f32_e32 v133, v133, v137
	v_cndmask_b32_e64 v129, 0, 32, s[6:7]
	v_ldexp_f32 v128, v128, v129
	v_mul_f32_e32 v129, 0xbfb8aa3b, v6
	v_exp_f32_e32 v129, v129
	v_log_f32_e32 v128, v128
	v_add_f32_e32 v129, 1.0, v129
	v_rcp_f32_e32 v129, v129
	v_mul_f32_e32 v137, 0x3f317217, v128
	v_fma_f32 v137, v128, s91, -v137
	v_fmac_f32_e32 v137, 0x3377d1cf, v128
	v_fma_f32 v129, v129, v196, v134
	v_fmac_f32_e32 v137, 0x3f317217, v128
	v_cmp_gt_f32_e32 vcc, s90, v129
	v_cmp_lt_f32_e64 s[8:9], |v128|, s92
	s_nop 0
	v_cndmask_b32_e64 v134, 0, 32, vcc
	v_cndmask_b32_e64 v128, v128, v137, s[8:9]
	v_mul_f32_e32 v137, 0xbfb8aa3b, v2
	v_ldexp_f32 v129, v129, v134
	v_exp_f32_e32 v137, v137
	v_log_f32_e32 v129, v129
	v_cndmask_b32_e64 v134, 0, v186, s[6:7]
	v_sub_f32_e32 v134, v128, v134
	v_add_f32_e32 v137, 1.0, v137
	v_mul_f32_e32 v128, 0x3f317217, v129
	v_rcp_f32_e32 v137, v137
	v_fma_f32 v128, v129, s91, -v128
	v_fmac_f32_e32 v128, 0x3377d1cf, v129
	v_fmac_f32_e32 v128, 0x3f317217, v129
	v_cmp_lt_f32_e64 s[6:7], |v129|, s92
	v_fma_f32 v130, v137, v195, v130
	s_nop 0
	v_cndmask_b32_e64 v128, v129, v128, s[6:7]
	v_cndmask_b32_e32 v129, 0, v186, vcc
	v_cmp_gt_f32_e32 vcc, s90, v130
	v_sub_f32_e32 v129, v128, v129
	v_mul_f32_e32 v128, 0xbfb8aa3b, v7
	v_cndmask_b32_e64 v137, 0, 32, vcc
	v_exp_f32_e32 v128, v128
	v_ldexp_f32 v130, v130, v137
	v_log_f32_e32 v130, v130
	v_add_f32_e32 v128, 1.0, v128
	v_rcp_f32_e32 v128, v128
	v_mul_f32_e32 v137, 0x3f317217, v130
	v_fma_f32 v137, v130, s91, -v137
	v_fmac_f32_e32 v137, 0x3377d1cf, v130
	v_fmac_f32_e32 v137, 0x3f317217, v130
	v_cmp_lt_f32_e64 s[6:7], |v130|, s92
	v_fmac_f32_e32 v135, v128, v197
	s_nop 0
	v_cndmask_b32_e64 v130, v130, v137, s[6:7]
	v_cmp_gt_f32_e64 s[6:7], s90, v135
	v_cndmask_b32_e32 v137, 0, v186, vcc
	v_sub_f32_e32 v137, v130, v137
	v_cndmask_b32_e64 v128, 0, 32, s[6:7]
	v_ldexp_f32 v128, v135, v128
	v_mul_f32_e32 v135, 0xbfb8aa3b, v3
	v_exp_f32_e32 v135, v135
	v_log_f32_e32 v128, v128
	v_add_f32_e32 v135, 1.0, v135
	v_rcp_f32_e32 v135, v135
	v_mul_f32_e32 v130, 0x3f317217, v128
	v_fma_f32 v130, v128, s91, -v130
	v_fmac_f32_e32 v130, 0x3377d1cf, v128
	v_fmac_f32_e32 v131, v135, v198
	v_cmp_gt_f32_e32 vcc, s90, v131
	v_fmac_f32_e32 v130, 0x3f317217, v128
	v_cmp_lt_f32_e64 s[8:9], |v128|, s92
	v_cndmask_b32_e64 v135, 0, 32, vcc
	v_ldexp_f32 v131, v131, v135
	v_log_f32_e32 v131, v131
	v_cndmask_b32_e64 v128, v128, v130, s[8:9]
	v_cndmask_b32_e64 v130, 0, v186, s[6:7]
	v_sub_f32_e32 v130, v128, v130
	v_mul_f32_e32 v128, 0x3f317217, v131
	v_fma_f32 v128, v131, s91, -v128
	v_fmac_f32_e32 v128, 0x3377d1cf, v131
	v_fmac_f32_e32 v128, 0x3f317217, v131
	v_cmp_lt_f32_e64 s[6:7], |v131|, s92
	v_cvt_pk_f16_f32 v129, v129, v130
	v_cvt_pk_f16_f32 v130, v136, v134
	v_cndmask_b32_e64 v128, v131, v128, s[6:7]
	v_cndmask_b32_e32 v131, 0, v186, vcc
	v_sub_f32_e32 v131, v128, v131
	v_cvt_pk_f16_f32 v128, v132, v133
	v_cvt_pk_f16_f32 v131, v137, v131

; DI unsigned cvtpk(float lo, float hi) { f32x2 v = {lo, hi}; bf16x2_t b = __builtin_convertvector(v, bf16x2_t); return __builtin_bit_cast(unsigned, b); }
; DI unsigned cvtpk_h(float lo, float hi) { f32x2 v = {lo, hi}; h16x2_t b = __builtin_convertvector(v, h16x2_t); return __builtin_bit_cast(unsigned, b); }
; DI float sigm(float x) { return __builtin_amdgcn_rcpf(1.f + fexp(-x)); }
;     template <int MODE> __device__ __forceinline__ void run(const f32x4 (&acc)[2][2][4][2], u16* dst, int ld, int row0, int col0, int trow0, int wc, int fq, const float* lb) const {
;     ...
;                 const int rr = ai * HALF + m * 16;
;                 u16* rowp = dst + (size_t)(row0 + rr) * ld + col0;
;                 f32x4 cs, sn;
;                 if (MODE == 1 || MODE == 2) { const int t = trow0 + rr; const int pos = (wc & 1) ? (t & 63) : (t >> 6);
;                     cs = *(const f32x4*)(rcos + pos * 16 + 4 * fq); sn = *(const f32x4*)(rsin + pos * 16 + 4 * fq); }
; #pragma unroll
;                 for (int bj = 0; bj < 2; ++bj) {
;                     f32x4 v0 = acc[ai][bj][m][0], v1 = acc[ai][bj][m][1];
;                     if (MODE == 1 || MODE == 2) { const f32x4 a = v0 * cs - v1 * sn, b = v1 * cs + v0 * sn; v0 = a; v1 = b;
;                         if (MODE == 2) { v0 = v0 * 0.18033688011112042f; v1 = v1 * 0.18033688011112042f; } }
;                     if (MODE == 3) {
; #pragma unroll
;                         for (int i = 0; i < 4; ++i) { const float l0 = lb0[bj][i], l1 = lb1[bj][i];
;                             v0[i] = __logf(l0 + (1.f - l0) * sigm(v0[i])); v1[i] = __logf(l1 + (1.f - l1) * sigm(v1[i])); }
;                     }
;                     if (MODE == 4) {
; #pragma unroll
;                         for (int i = 0; i < 4; ++i) { v0[i] = silu_(v0[i]); v1[i] = silu_(v1[i]); }
;                     }
;                     if (MODE == 5) {
; #pragma unroll
;                         for (int i = 0; i < 4; ++i) { v0[i] = sigm(v0[i]); v1[i] = sigm(v1[i]); }
;                     }
;                     u32x4 w;
;                     if (MODE == 3) { w.x = cvtpk_h(v0[0], v0[1]); w.y = cvtpk_h(v0[2], v0[3]); w.z = cvtpk_h(v1[0], v1[1]); w.w = cvtpk_h(v1[2], v1[3]); }
;                     else { w.x = cvtpk(v0[0], v0[1]); w.y = cvtpk(v0[2], v0[3]); w.z = cvtpk(v1[0], v1[1]); w.w = cvtpk(v1[2], v1[3]); }
;                     *(u32x4*)(rowp + bj * HALF) = w;
.LBB0_202:
	s_andn2_b64 vcc, exec, s[6:7]
	s_mov_b64 s[6:7], 0
	s_cbranch_vccnz .LBB0_207
	s_cmp_gt_i32 s58, 0
	s_mov_b64 s[6:7], -1
	s_cbranch_scc0 .LBB0_205
	v_lshlrev_b32_e32 v152, 1, v187
	v_ashrrev_i32_e32 v167, 31, v166
	v_lshl_add_u64 v[132:133], s[22:23], 0, v[152:153]
	v_lshlrev_b64 v[128:129], 11, v[166:167]
	v_lshl_add_u64 v[134:135], v[132:133], 0, v[128:129]
	v_cvt_pk_bf16_f32 v128, v124, v125
	v_cvt_pk_bf16_f32 v129, v126, v127
	v_cvt_pk_bf16_f32 v130, v120, v121
	v_cvt_pk_bf16_f32 v131, v122, v123
	global_store_dwordx4 v[134:135], v[128:131], off sc1
	s_mov_b64 s[6:7], 0
	s_nop 0
	v_cvt_pk_bf16_f32 v128, v108, v109
	v_cvt_pk_bf16_f32 v129, v110, v111
	v_cvt_pk_bf16_f32 v130, v104, v105
	v_cvt_pk_bf16_f32 v131, v106, v107
	global_store_dwordx4 v[134:135], v[128:131], off offset:256 sc1
	s_nop 1
	v_or_b32_e32 v128, 16, v166
	v_ashrrev_i32_e32 v129, 31, v128
	v_lshlrev_b64 v[128:129], 11, v[128:129]
	v_lshl_add_u64 v[134:135], v[132:133], 0, v[128:129]
	v_cvt_pk_bf16_f32 v128, v116, v117
	v_cvt_pk_bf16_f32 v129, v118, v119
	v_cvt_pk_bf16_f32 v130, v112, v113
	v_cvt_pk_bf16_f32 v131, v114, v115
	global_store_dwordx4 v[134:135], v[128:131], off sc1
	s_nop 1
	v_cvt_pk_bf16_f32 v128, v92, v93
	v_cvt_pk_bf16_f32 v129, v94, v95
	v_cvt_pk_bf16_f32 v130, v88, v89
	v_cvt_pk_bf16_f32 v131, v90, v91
	global_store_dwordx4 v[134:135], v[128:131], off offset:256 sc1
	s_nop 1
	v_or_b32_e32 v128, 32, v166
	v_ashrrev_i32_e32 v129, 31, v128
	v_lshlrev_b64 v[128:129], 11, v[128:129]
	v_lshl_add_u64 v[134:135], v[132:133], 0, v[128:129]
	v_cvt_pk_bf16_f32 v128, v100, v101
	v_cvt_pk_bf16_f32 v129, v102, v103
	v_cvt_pk_bf16_f32 v130, v96, v97
	v_cvt_pk_bf16_f32 v131, v98, v99
	global_store_dwordx4 v[134:135], v[128:131], off sc1
	s_nop 1
	v_cvt_pk_bf16_f32 v128, v76, v77
	v_cvt_pk_bf16_f32 v129, v78, v79
	v_cvt_pk_bf16_f32 v130, v72, v73
	v_cvt_pk_bf16_f32 v131, v74, v75
	global_store_dwordx4 v[134:135], v[128:131], off offset:256 sc1
	s_nop 1
	v_or_b32_e32 v128, 48, v166
	v_ashrrev_i32_e32 v129, 31, v128
	v_lshlrev_b64 v[128:129], 11, v[128:129]
	v_lshl_add_u64 v[134:135], v[132:133], 0, v[128:129]
	v_cvt_pk_bf16_f32 v128, v84, v85
	v_cvt_pk_bf16_f32 v129, v86, v87
	v_cvt_pk_bf16_f32 v130, v80, v81
	v_cvt_pk_bf16_f32 v131, v82, v83
	global_store_dwordx4 v[134:135], v[128:131], off sc1
	s_nop 1
	v_cvt_pk_bf16_f32 v128, v68, v69
	v_cvt_pk_bf16_f32 v129, v70, v71
	v_cvt_pk_bf16_f32 v130, v64, v65
	v_cvt_pk_bf16_f32 v131, v66, v67
	global_store_dwordx4 v[134:135], v[128:131], off offset:256 sc1
	s_nop 1
	v_add_u32_e32 v128, 0x80, v166
	v_ashrrev_i32_e32 v129, 31, v128
	v_lshlrev_b64 v[128:129], 11, v[128:129]
	v_lshl_add_u64 v[134:135], v[132:133], 0, v[128:129]
	v_cvt_pk_bf16_f32 v128, v60, v61
	v_cvt_pk_bf16_f32 v129, v62, v63
	v_cvt_pk_bf16_f32 v130, v56, v57
	v_cvt_pk_bf16_f32 v131, v58, v59
	global_store_dwordx4 v[134:135], v[128:131], off sc1
	s_nop 1
	v_cvt_pk_bf16_f32 v128, v44, v45
	v_cvt_pk_bf16_f32 v129, v46, v47
	v_cvt_pk_bf16_f32 v130, v40, v41
	v_cvt_pk_bf16_f32 v131, v42, v43
	global_store_dwordx4 v[134:135], v[128:131], off offset:256 sc1
	s_nop 1
	v_add_u32_e32 v128, 0x90, v166
	v_ashrrev_i32_e32 v129, 31, v128
	v_lshlrev_b64 v[128:129], 11, v[128:129]
	v_lshl_add_u64 v[134:135], v[132:133], 0, v[128:129]
	v_cvt_pk_bf16_f32 v128, v52, v53
	v_cvt_pk_bf16_f32 v129, v54, v55
	v_cvt_pk_bf16_f32 v130, v48, v49
	v_cvt_pk_bf16_f32 v131, v50, v51
	global_store_dwordx4 v[134:135], v[128:131], off sc1
	s_nop 1
	v_cvt_pk_bf16_f32 v128, v28, v29
	v_cvt_pk_bf16_f32 v129, v30, v31
	v_cvt_pk_bf16_f32 v130, v24, v25
	v_cvt_pk_bf16_f32 v131, v26, v27
	global_store_dwordx4 v[134:135], v[128:131], off offset:256 sc1
	s_nop 1
	v_add_u32_e32 v128, 0xa0, v166
	v_ashrrev_i32_e32 v129, 31, v128
	v_lshlrev_b64 v[128:129], 11, v[128:129]
	v_lshl_add_u64 v[134:135], v[132:133], 0, v[128:129]
	v_cvt_pk_bf16_f32 v128, v36, v37
	v_cvt_pk_bf16_f32 v129, v38, v39
	v_cvt_pk_bf16_f32 v130, v32, v33
	v_cvt_pk_bf16_f32 v131, v34, v35
	global_store_dwordx4 v[134:135], v[128:131], off sc1
	s_nop 1
	v_cvt_pk_bf16_f32 v128, v12, v13
	v_cvt_pk_bf16_f32 v129, v14, v15
	v_cvt_pk_bf16_f32 v130, v8, v9
	v_cvt_pk_bf16_f32 v131, v10, v11
	global_store_dwordx4 v[134:135], v[128:131], off offset:256 sc1
	s_nop 1
	v_add_u32_e32 v128, 0xb0, v166
	v_ashrrev_i32_e32 v129, 31, v128
	v_lshlrev_b64 v[128:129], 11, v[128:129]
	v_lshl_add_u64 v[170:171], v[132:133], 0, v[128:129]
	v_cvt_pk_bf16_f32 v128, v20, v21
	v_cvt_pk_bf16_f32 v129, v22, v23
	v_cvt_pk_bf16_f32 v130, v16, v17
	v_cvt_pk_bf16_f32 v131, v18, v19
	global_store_dwordx4 v[170:171], v[128:131], off sc1
	s_nop 1
	v_cvt_pk_bf16_f32 v128, v4, v5
	v_cvt_pk_bf16_f32 v129, v6, v7
	v_cvt_pk_bf16_f32 v130, v0, v1
	v_cvt_pk_bf16_f32 v131, v2, v3

; DI unsigned cvtpk(float lo, float hi) { f32x2 v = {lo, hi}; bf16x2_t b = __builtin_convertvector(v, bf16x2_t); return __builtin_bit_cast(unsigned, b); }
; DI unsigned cvtpk_h(float lo, float hi) { f32x2 v = {lo, hi}; h16x2_t b = __builtin_convertvector(v, h16x2_t); return __builtin_bit_cast(unsigned, b); }
; DI float sigm(float x) { return __builtin_amdgcn_rcpf(1.f + fexp(-x)); }
;     template <int MODE> __device__ __forceinline__ void run(const f32x4 (&acc)[2][2][4][2], u16* dst, int ld, int row0, int col0, int trow0, int wc, int fq, const float* lb) const {
;     ...
;                     if (MODE == 5) {
; #pragma unroll
;                         for (int i = 0; i < 4; ++i) { v0[i] = sigm(v0[i]); v1[i] = sigm(v1[i]); }
;                     }
;                     u32x4 w;
;                     if (MODE == 3) { w.x = cvtpk_h(v0[0], v0[1]); w.y = cvtpk_h(v0[2], v0[3]); w.z = cvtpk_h(v1[0], v1[1]); w.w = cvtpk_h(v1[2], v1[3]); }
;                     else { w.x = cvtpk(v0[0], v0[1]); w.y = cvtpk(v0[2], v0[3]); w.z = cvtpk(v1[0], v1[1]); w.w = cvtpk(v1[2], v1[3]); }
;                     *(u32x4*)(rowp + bj * HALF) = w;
;     __device__ __forceinline__ void operator()(const f32x4 (&acc)[2][2][4][2], const Unit& u, int wr, int wc, int fr, int fq) const {
;     ...
;         default: run<5>(acc, GATES, 4096, latrow0, (pn - 32) * 256 + wc * 32 + 8 * fq, trow0, wc, fq, nullptr); break;
.LBB0_207:
	s_and_b64 vcc, exec, s[68:69]
	s_cbranch_vccz .LBB0_209
	v_mul_f32_e32 v132, 0xbfb8aa3b, v124
	v_mul_f32_e32 v133, 0xbfb8aa3b, v120
	v_exp_f32_e32 v132, v132
	v_exp_f32_e32 v133, v133
	v_add_u32_e32 v128, s57, v179
	v_ashrrev_i32_e32 v129, 31, v128
	v_ashrrev_i32_e32 v169, 31, v168
	v_lshl_add_u64 v[128:129], v[128:129], 1, s[16:17]
	v_lshlrev_b64 v[130:131], 13, v[168:169]
	v_lshl_add_u64 v[134:135], v[128:129], 0, v[130:131]
	v_add_f32_e32 v130, 1.0, v132
	v_add_f32_e32 v131, 1.0, v133
	v_mul_f32_e32 v132, 0xbfb8aa3b, v125
	v_mul_f32_e32 v133, 0xbfb8aa3b, v121
	v_exp_f32_e32 v132, v132
	v_exp_f32_e32 v133, v133
	v_rcp_f32_e32 v136, v131
	v_mul_f32_e32 v137, 0xbfb8aa3b, v122
	v_add_f32_e32 v131, 1.0, v132
	v_add_f32_e32 v132, 1.0, v133
	v_mul_f32_e32 v133, 0xbfb8aa3b, v126
	v_mul_f32_e32 v138, 0xbfb8aa3b, v127
	v_mul_f32_e32 v139, 0xbfb8aa3b, v123
	v_exp_f32_e32 v133, v133
	v_exp_f32_e32 v137, v137
	v_exp_f32_e32 v138, v138
	v_exp_f32_e32 v139, v139
	v_add_f32_e32 v133, 1.0, v133
	v_add_f32_e32 v137, 1.0, v137
	v_add_f32_e32 v138, 1.0, v138
	v_add_f32_e32 v139, 1.0, v139
	v_rcp_f32_e32 v130, v130
	v_rcp_f32_e32 v131, v131
	v_rcp_f32_e32 v132, v132
	v_rcp_f32_e32 v133, v133
	v_rcp_f32_e32 v137, v137
	v_rcp_f32_e32 v138, v138
	v_rcp_f32_e32 v139, v139
	v_cvt_pk_bf16_f32 v130, v130, v131
	v_cvt_pk_bf16_f32 v132, v136, v132
	v_cvt_pk_bf16_f32 v131, v133, v138
	v_cvt_pk_bf16_f32 v133, v137, v139
	v_mul_f32_e32 v137, 0xbfb8aa3b, v104
	v_mul_f32_e32 v136, 0xbfb8aa3b, v108
	v_exp_f32_e32 v137, v137
	global_store_dwordx4 v[134:135], v[130:133], off sc1
	v_exp_f32_e32 v136, v136
	v_mul_f32_e32 v138, 0xbfb8aa3b, v111
	v_mul_f32_e32 v132, 0xbfb8aa3b, v109
	v_mul_f32_e32 v133, 0xbfb8aa3b, v105
	v_exp_f32_e32 v132, v132
	v_exp_f32_e32 v133, v133
	v_add_f32_e32 v131, 1.0, v137
	v_add_f32_e32 v130, 1.0, v136
	v_rcp_f32_e32 v136, v131
	v_add_f32_e32 v131, 1.0, v132
	v_add_f32_e32 v132, 1.0, v133
	v_mul_f32_e32 v133, 0xbfb8aa3b, v110
	v_mul_f32_e32 v137, 0xbfb8aa3b, v106
	v_mul_f32_e32 v139, 0xbfb8aa3b, v107
	v_exp_f32_e32 v133, v133
	v_exp_f32_e32 v137, v137
	v_exp_f32_e32 v138, v138
	v_exp_f32_e32 v139, v139
	v_add_f32_e32 v133, 1.0, v133
	v_add_f32_e32 v137, 1.0, v137
	v_add_f32_e32 v138, 1.0, v138
	v_add_f32_e32 v139, 1.0, v139
	v_rcp_f32_e32 v130, v130
	v_rcp_f32_e32 v131, v131
	v_rcp_f32_e32 v132, v132
	v_rcp_f32_e32 v133, v133
	v_rcp_f32_e32 v137, v137
	v_rcp_f32_e32 v138, v138
	v_rcp_f32_e32 v139, v139
	v_cvt_pk_bf16_f32 v130, v130, v131
	v_cvt_pk_bf16_f32 v132, v136, v132
	v_cvt_pk_bf16_f32 v131, v133, v138
	v_cvt_pk_bf16_f32 v133, v137, v139
	global_store_dwordx4 v[134:135], v[130:133], off offset:256 sc1
	v_mul_f32_e32 v137, 0xbfb8aa3b, v114
	v_mul_f32_e32 v138, 0xbfb8aa3b, v119
	v_mul_f32_e32 v132, 0xbfb8aa3b, v116
	v_mul_f32_e32 v133, 0xbfb8aa3b, v112
	v_exp_f32_e32 v132, v132
	v_exp_f32_e32 v133, v133
	v_or_b32_e32 v130, 16, v168
	v_ashrrev_i32_e32 v131, 31, v130
	v_lshlrev_b64 v[130:131], 13, v[130:131]
	v_lshl_add_u64 v[134:135], v[128:129], 0, v[130:131]
	v_add_f32_e32 v130, 1.0, v132
	v_add_f32_e32 v131, 1.0, v133
	v_mul_f32_e32 v132, 0xbfb8aa3b, v117
	v_mul_f32_e32 v133, 0xbfb8aa3b, v113
	v_exp_f32_e32 v132, v132
	v_exp_f32_e32 v133, v133
	v_rcp_f32_e32 v136, v131
	v_mul_f32_e32 v139, 0xbfb8aa3b, v115
	v_add_f32_e32 v131, 1.0, v132
	v_add_f32_e32 v132, 1.0, v133
	v_mul_f32_e32 v133, 0xbfb8aa3b, v118
	v_exp_f32_e32 v133, v133
	v_exp_f32_e32 v137, v137
	v_exp_f32_e32 v138, v138
	v_exp_f32_e32 v139, v139
	v_add_f32_e32 v133, 1.0, v133
	v_add_f32_e32 v137, 1.0, v137
	v_add_f32_e32 v138, 1.0, v138
	v_add_f32_e32 v139, 1.0, v139
	v_rcp_f32_e32 v130, v130
	v_rcp_f32_e32 v131, v131
	v_rcp_f32_e32 v132, v132
	v_rcp_f32_e32 v133, v133
	v_rcp_f32_e32 v137, v137
	v_rcp_f32_e32 v138, v138
	v_rcp_f32_e32 v139, v139
	v_cvt_pk_bf16_f32 v130, v130, v131
	v_cvt_pk_bf16_f32 v132, v136, v132
	v_cvt_pk_bf16_f32 v131, v133, v138
	v_cvt_pk_bf16_f32 v133, v137, v139
	v_mul_f32_e32 v137, 0xbfb8aa3b, v88
	v_mul_f32_e32 v136, 0xbfb8aa3b, v92
	v_exp_f32_e32 v137, v137
	global_store_dwordx4 v[134:135], v[130:133], off sc1
	v_exp_f32_e32 v136, v136
	v_mul_f32_e32 v138, 0xbfb8aa3b, v95
	v_mul_f32_e32 v132, 0xbfb8aa3b, v93
	v_mul_f32_e32 v133, 0xbfb8aa3b, v89
	v_exp_f32_e32 v132, v132
	v_exp_f32_e32 v133, v133
	v_add_f32_e32 v131, 1.0, v137
	v_add_f32_e32 v130, 1.0, v136
	v_rcp_f32_e32 v136, v131
	v_add_f32_e32 v131, 1.0, v132
	v_add_f32_e32 v132, 1.0, v133
	v_mul_f32_e32 v133, 0xbfb8aa3b, v94
	v_mul_f32_e32 v137, 0xbfb8aa3b, v90
	v_mul_f32_e32 v139, 0xbfb8aa3b, v91
	v_exp_f32_e32 v133, v133
	v_exp_f32_e32 v137, v137
	v_exp_f32_e32 v138, v138
	v_exp_f32_e32 v139, v139
	v_add_f32_e32 v133, 1.0, v133
	v_add_f32_e32 v137, 1.0, v137
	v_add_f32_e32 v138, 1.0, v138
	v_add_f32_e32 v139, 1.0, v139
	v_rcp_f32_e32 v130, v130
	v_rcp_f32_e32 v131, v131
	v_rcp_f32_e32 v132, v132
	v_rcp_f32_e32 v133, v133
	v_rcp_f32_e32 v137, v137
	v_rcp_f32_e32 v138, v138
	v_rcp_f32_e32 v139, v139
	v_cvt_pk_bf16_f32 v130, v130, v131
	v_cvt_pk_bf16_f32 v132, v136, v132
	v_cvt_pk_bf16_f32 v131, v133, v138
	v_cvt_pk_bf16_f32 v133, v137, v139
	global_store_dwordx4 v[134:135], v[130:133], off offset:256 sc1
	v_mul_f32_e32 v137, 0xbfb8aa3b, v98
	v_mul_f32_e32 v138, 0xbfb8aa3b, v103
	v_mul_f32_e32 v132, 0xbfb8aa3b, v100
	v_mul_f32_e32 v133, 0xbfb8aa3b, v96
	v_exp_f32_e32 v132, v132
	v_exp_f32_e32 v133, v133
	v_or_b32_e32 v130, 32, v168
	v_ashrrev_i32_e32 v131, 31, v130
	v_lshlrev_b64 v[130:131], 13, v[130:131]
	v_lshl_add_u64 v[134:135], v[128:129], 0, v[130:131]
	v_add_f32_e32 v130, 1.0, v132
	v_add_f32_e32 v131, 1.0, v133
	v_mul_f32_e32 v132, 0xbfb8aa3b, v101
	v_mul_f32_e32 v133, 0xbfb8aa3b, v97
; DI unsigned cvtpk(float lo, float hi) { f32x2 v = {lo, hi}; bf16x2_t b = __builtin_convertvector(v, bf16x2_t); return __builtin_bit_cast(unsigned, b); }
; DI unsigned cvtpk_h(float lo, float hi) { f32x2 v = {lo, hi}; h16x2_t b = __builtin_convertvector(v, h16x2_t); return __builtin_bit_cast(unsigned, b); }
; DI float sigm(float x) { return __builtin_amdgcn_rcpf(1.f + fexp(-x)); }
;     template <int MODE> __device__ __forceinline__ void run(const f32x4 (&acc)[2][2][4][2], u16* dst, int ld, int row0, int col0, int trow0, int wc, int fq, const float* lb) const {
;     ...
;                     if (MODE == 5) {
; #pragma unroll
;                         for (int i = 0; i < 4; ++i) { v0[i] = sigm(v0[i]); v1[i] = sigm(v1[i]); }
;                     }
;                     u32x4 w;
;                     if (MODE == 3) { w.x = cvtpk_h(v0[0], v0[1]); w.y = cvtpk_h(v0[2], v0[3]); w.z = cvtpk_h(v1[0], v1[1]); w.w = cvtpk_h(v1[2], v1[3]); }
;                     else { w.x = cvtpk(v0[0], v0[1]); w.y = cvtpk(v0[2], v0[3]); w.z = cvtpk(v1[0], v1[1]); w.w = cvtpk(v1[2], v1[3]); }
;                     *(u32x4*)(rowp + bj * HALF) = w;
	v_exp_f32_e32 v132, v132
	v_exp_f32_e32 v133, v133
	v_rcp_f32_e32 v136, v131
	v_mul_f32_e32 v139, 0xbfb8aa3b, v99
	v_add_f32_e32 v131, 1.0, v132
	v_add_f32_e32 v132, 1.0, v133
	v_mul_f32_e32 v133, 0xbfb8aa3b, v102
	v_exp_f32_e32 v133, v133
	v_exp_f32_e32 v137, v137
	v_exp_f32_e32 v138, v138
	v_exp_f32_e32 v139, v139
	v_add_f32_e32 v133, 1.0, v133
	v_add_f32_e32 v137, 1.0, v137
	v_add_f32_e32 v138, 1.0, v138
	v_add_f32_e32 v139, 1.0, v139
	v_rcp_f32_e32 v130, v130
	v_rcp_f32_e32 v131, v131
	v_rcp_f32_e32 v132, v132
	v_rcp_f32_e32 v133, v133
	v_rcp_f32_e32 v137, v137
	v_rcp_f32_e32 v138, v138
	v_rcp_f32_e32 v139, v139
	v_cvt_pk_bf16_f32 v130, v130, v131
	v_cvt_pk_bf16_f32 v132, v136, v132
	v_cvt_pk_bf16_f32 v131, v133, v138
	v_cvt_pk_bf16_f32 v133, v137, v139
	v_mul_f32_e32 v137, 0xbfb8aa3b, v72
	v_mul_f32_e32 v136, 0xbfb8aa3b, v76
	v_exp_f32_e32 v137, v137
	global_store_dwordx4 v[134:135], v[130:133], off sc1
	v_exp_f32_e32 v136, v136
	v_mul_f32_e32 v138, 0xbfb8aa3b, v79
	v_mul_f32_e32 v132, 0xbfb8aa3b, v77
	v_mul_f32_e32 v133, 0xbfb8aa3b, v73
	v_exp_f32_e32 v132, v132
	v_exp_f32_e32 v133, v133
	v_add_f32_e32 v131, 1.0, v137
	v_add_f32_e32 v130, 1.0, v136
	v_rcp_f32_e32 v136, v131
	v_add_f32_e32 v131, 1.0, v132
	v_add_f32_e32 v132, 1.0, v133
	v_mul_f32_e32 v133, 0xbfb8aa3b, v78
	v_mul_f32_e32 v137, 0xbfb8aa3b, v74
	v_mul_f32_e32 v139, 0xbfb8aa3b, v75
	v_exp_f32_e32 v133, v133
	v_exp_f32_e32 v137, v137
	v_exp_f32_e32 v138, v138
	v_exp_f32_e32 v139, v139
	v_add_f32_e32 v133, 1.0, v133
	v_add_f32_e32 v137, 1.0, v137
	v_add_f32_e32 v138, 1.0, v138
	v_add_f32_e32 v139, 1.0, v139
	v_rcp_f32_e32 v130, v130
	v_rcp_f32_e32 v131, v131
	v_rcp_f32_e32 v132, v132
	v_rcp_f32_e32 v133, v133
	v_rcp_f32_e32 v137, v137
	v_rcp_f32_e32 v138, v138
	v_rcp_f32_e32 v139, v139
	v_cvt_pk_bf16_f32 v130, v130, v131
	v_cvt_pk_bf16_f32 v132, v136, v132
	v_cvt_pk_bf16_f32 v131, v133, v138
	v_cvt_pk_bf16_f32 v133, v137, v139
	global_store_dwordx4 v[134:135], v[130:133], off offset:256 sc1
	v_mul_f32_e32 v137, 0xbfb8aa3b, v82
	v_mul_f32_e32 v138, 0xbfb8aa3b, v87
	v_mul_f32_e32 v132, 0xbfb8aa3b, v84
	v_mul_f32_e32 v133, 0xbfb8aa3b, v80
	v_exp_f32_e32 v132, v132
	v_exp_f32_e32 v133, v133
	v_or_b32_e32 v130, 48, v168
	v_ashrrev_i32_e32 v131, 31, v130
	v_lshlrev_b64 v[130:131], 13, v[130:131]
	v_lshl_add_u64 v[134:135], v[128:129], 0, v[130:131]
	v_add_f32_e32 v130, 1.0, v132
	v_add_f32_e32 v131, 1.0, v133
	v_mul_f32_e32 v132, 0xbfb8aa3b, v85
	v_mul_f32_e32 v133, 0xbfb8aa3b, v81
	v_exp_f32_e32 v132, v132
	v_exp_f32_e32 v133, v133
	v_rcp_f32_e32 v136, v131
	v_mul_f32_e32 v139, 0xbfb8aa3b, v83
	v_add_f32_e32 v131, 1.0, v132
	v_add_f32_e32 v132, 1.0, v133
	v_mul_f32_e32 v133, 0xbfb8aa3b, v86
	v_exp_f32_e32 v133, v133
	v_exp_f32_e32 v137, v137
	v_exp_f32_e32 v138, v138
	v_exp_f32_e32 v139, v139
	v_add_f32_e32 v133, 1.0, v133
	v_add_f32_e32 v137, 1.0, v137
	v_add_f32_e32 v138, 1.0, v138
	v_add_f32_e32 v139, 1.0, v139
	v_rcp_f32_e32 v130, v130
	v_rcp_f32_e32 v131, v131
	v_rcp_f32_e32 v132, v132
	v_rcp_f32_e32 v133, v133
	v_rcp_f32_e32 v137, v137
	v_rcp_f32_e32 v138, v138
	v_rcp_f32_e32 v139, v139
	v_cvt_pk_bf16_f32 v130, v130, v131
	v_cvt_pk_bf16_f32 v132, v136, v132
	v_cvt_pk_bf16_f32 v131, v133, v138
	v_cvt_pk_bf16_f32 v133, v137, v139
	v_mul_f32_e32 v137, 0xbfb8aa3b, v64
	v_mul_f32_e32 v136, 0xbfb8aa3b, v68
	v_exp_f32_e32 v137, v137
	global_store_dwordx4 v[134:135], v[130:133], off sc1
	v_exp_f32_e32 v136, v136
	v_mul_f32_e32 v138, 0xbfb8aa3b, v71
	v_mul_f32_e32 v132, 0xbfb8aa3b, v69
	v_mul_f32_e32 v133, 0xbfb8aa3b, v65
	v_exp_f32_e32 v132, v132
	v_exp_f32_e32 v133, v133
	v_add_f32_e32 v131, 1.0, v137
	v_add_f32_e32 v130, 1.0, v136
	v_rcp_f32_e32 v136, v131
	v_add_f32_e32 v131, 1.0, v132
	v_add_f32_e32 v132, 1.0, v133
	v_mul_f32_e32 v133, 0xbfb8aa3b, v70
	v_mul_f32_e32 v137, 0xbfb8aa3b, v66
	v_mul_f32_e32 v139, 0xbfb8aa3b, v67
	v_exp_f32_e32 v133, v133
	v_exp_f32_e32 v137, v137
	v_exp_f32_e32 v138, v138
	v_exp_f32_e32 v139, v139
	v_add_f32_e32 v133, 1.0, v133
	v_add_f32_e32 v137, 1.0, v137
	v_add_f32_e32 v138, 1.0, v138
	v_add_f32_e32 v139, 1.0, v139
	v_rcp_f32_e32 v130, v130
	v_rcp_f32_e32 v131, v131
	v_rcp_f32_e32 v132, v132
	v_rcp_f32_e32 v133, v133
	v_rcp_f32_e32 v137, v137
	v_rcp_f32_e32 v138, v138
	v_rcp_f32_e32 v139, v139
	v_cvt_pk_bf16_f32 v130, v130, v131
	v_cvt_pk_bf16_f32 v132, v136, v132
	v_cvt_pk_bf16_f32 v131, v133, v138
	v_cvt_pk_bf16_f32 v133, v137, v139
	global_store_dwordx4 v[134:135], v[130:133], off offset:256 sc1
	v_mul_f32_e32 v137, 0xbfb8aa3b, v58
	v_mul_f32_e32 v138, 0xbfb8aa3b, v63
	v_mul_f32_e32 v132, 0xbfb8aa3b, v60
	v_mul_f32_e32 v133, 0xbfb8aa3b, v56
	v_exp_f32_e32 v132, v132
	v_exp_f32_e32 v133, v133
	v_add_u32_e32 v130, 0x80, v168
	v_ashrrev_i32_e32 v131, 31, v130
	v_lshlrev_b64 v[130:131], 13, v[130:131]
	v_lshl_add_u64 v[134:135], v[128:129], 0, v[130:131]
	v_add_f32_e32 v130, 1.0, v132
	v_add_f32_e32 v131, 1.0, v133
	v_mul_f32_e32 v132, 0xbfb8aa3b, v61
	v_mul_f32_e32 v133, 0xbfb8aa3b, v57
	v_exp_f32_e32 v132, v132
	v_exp_f32_e32 v133, v133
	v_rcp_f32_e32 v136, v131
	v_mul_f32_e32 v139, 0xbfb8aa3b, v59
	v_add_f32_e32 v131, 1.0, v132
	v_add_f32_e32 v132, 1.0, v133
	v_mul_f32_e32 v133, 0xbfb8aa3b, v62
	v_exp_f32_e32 v133, v133
	v_exp_f32_e32 v137, v137
	v_exp_f32_e32 v138, v138
	v_exp_f32_e32 v139, v139
	v_add_f32_e32 v133, 1.0, v133
	v_add_f32_e32 v137, 1.0, v137
	v_add_f32_e32 v138, 1.0, v138
	v_add_f32_e32 v139, 1.0, v139
	v_rcp_f32_e32 v130, v130
	v_rcp_f32_e32 v131, v131
	v_rcp_f32_e32 v132, v132
	v_rcp_f32_e32 v133, v133
	v_rcp_f32_e32 v137, v137
	v_rcp_f32_e32 v138, v138
	v_rcp_f32_e32 v139, v139
	v_cvt_pk_bf16_f32 v130, v130, v131
; DI unsigned cvtpk(float lo, float hi) { f32x2 v = {lo, hi}; bf16x2_t b = __builtin_convertvector(v, bf16x2_t); return __builtin_bit_cast(unsigned, b); }
; DI unsigned cvtpk_h(float lo, float hi) { f32x2 v = {lo, hi}; h16x2_t b = __builtin_convertvector(v, h16x2_t); return __builtin_bit_cast(unsigned, b); }
; DI float sigm(float x) { return __builtin_amdgcn_rcpf(1.f + fexp(-x)); }
;     template <int MODE> __device__ __forceinline__ void run(const f32x4 (&acc)[2][2][4][2], u16* dst, int ld, int row0, int col0, int trow0, int wc, int fq, const float* lb) const {
;     ...
;                     if (MODE == 5) {
; #pragma unroll
;                         for (int i = 0; i < 4; ++i) { v0[i] = sigm(v0[i]); v1[i] = sigm(v1[i]); }
;                     }
;                     u32x4 w;
;                     if (MODE == 3) { w.x = cvtpk_h(v0[0], v0[1]); w.y = cvtpk_h(v0[2], v0[3]); w.z = cvtpk_h(v1[0], v1[1]); w.w = cvtpk_h(v1[2], v1[3]); }
;                     else { w.x = cvtpk(v0[0], v0[1]); w.y = cvtpk(v0[2], v0[3]); w.z = cvtpk(v1[0], v1[1]); w.w = cvtpk(v1[2], v1[3]); }
;                     *(u32x4*)(rowp + bj * HALF) = w;
	v_cvt_pk_bf16_f32 v132, v136, v132
	v_cvt_pk_bf16_f32 v131, v133, v138
	v_cvt_pk_bf16_f32 v133, v137, v139
	v_mul_f32_e32 v137, 0xbfb8aa3b, v40
	v_mul_f32_e32 v136, 0xbfb8aa3b, v44
	v_exp_f32_e32 v137, v137
	global_store_dwordx4 v[134:135], v[130:133], off sc1
	v_exp_f32_e32 v136, v136
	v_mul_f32_e32 v138, 0xbfb8aa3b, v47
	v_mul_f32_e32 v132, 0xbfb8aa3b, v45
	v_mul_f32_e32 v133, 0xbfb8aa3b, v41
	v_exp_f32_e32 v132, v132
	v_exp_f32_e32 v133, v133
	v_add_f32_e32 v131, 1.0, v137
	v_add_f32_e32 v130, 1.0, v136
	v_rcp_f32_e32 v136, v131
	v_add_f32_e32 v131, 1.0, v132
	v_add_f32_e32 v132, 1.0, v133
	v_mul_f32_e32 v133, 0xbfb8aa3b, v46
	v_mul_f32_e32 v137, 0xbfb8aa3b, v42
	v_mul_f32_e32 v139, 0xbfb8aa3b, v43
	v_exp_f32_e32 v133, v133
	v_exp_f32_e32 v137, v137
	v_exp_f32_e32 v138, v138
	v_exp_f32_e32 v139, v139
	v_add_f32_e32 v133, 1.0, v133
	v_add_f32_e32 v137, 1.0, v137
	v_add_f32_e32 v138, 1.0, v138
	v_add_f32_e32 v139, 1.0, v139
	v_rcp_f32_e32 v130, v130
	v_rcp_f32_e32 v131, v131
	v_rcp_f32_e32 v132, v132
	v_rcp_f32_e32 v133, v133
	v_rcp_f32_e32 v137, v137
	v_rcp_f32_e32 v138, v138
	v_rcp_f32_e32 v139, v139
	v_cvt_pk_bf16_f32 v130, v130, v131
	v_cvt_pk_bf16_f32 v132, v136, v132
	v_cvt_pk_bf16_f32 v131, v133, v138
	v_cvt_pk_bf16_f32 v133, v137, v139
	global_store_dwordx4 v[134:135], v[130:133], off offset:256 sc1
	v_mul_f32_e32 v137, 0xbfb8aa3b, v50
	v_mul_f32_e32 v138, 0xbfb8aa3b, v55
	v_mul_f32_e32 v132, 0xbfb8aa3b, v52
	v_mul_f32_e32 v133, 0xbfb8aa3b, v48
	v_exp_f32_e32 v132, v132
	v_exp_f32_e32 v133, v133
	v_add_u32_e32 v130, 0x90, v168
	v_ashrrev_i32_e32 v131, 31, v130
	v_lshlrev_b64 v[130:131], 13, v[130:131]
	v_lshl_add_u64 v[134:135], v[128:129], 0, v[130:131]
	v_add_f32_e32 v130, 1.0, v132
	v_add_f32_e32 v131, 1.0, v133
	v_mul_f32_e32 v132, 0xbfb8aa3b, v53
	v_mul_f32_e32 v133, 0xbfb8aa3b, v49
	v_exp_f32_e32 v132, v132
	v_exp_f32_e32 v133, v133
	v_rcp_f32_e32 v136, v131
	v_mul_f32_e32 v139, 0xbfb8aa3b, v51
	v_add_f32_e32 v131, 1.0, v132
	v_add_f32_e32 v132, 1.0, v133
	v_mul_f32_e32 v133, 0xbfb8aa3b, v54
	v_exp_f32_e32 v133, v133
	v_exp_f32_e32 v137, v137
	v_exp_f32_e32 v138, v138
	v_exp_f32_e32 v139, v139
	v_add_f32_e32 v133, 1.0, v133
	v_add_f32_e32 v137, 1.0, v137
	v_add_f32_e32 v138, 1.0, v138
	v_add_f32_e32 v139, 1.0, v139
	v_rcp_f32_e32 v130, v130
	v_rcp_f32_e32 v131, v131
	v_rcp_f32_e32 v132, v132
	v_rcp_f32_e32 v133, v133
	v_rcp_f32_e32 v137, v137
	v_rcp_f32_e32 v138, v138
	v_rcp_f32_e32 v139, v139
	v_cvt_pk_bf16_f32 v130, v130, v131
	v_cvt_pk_bf16_f32 v132, v136, v132
	v_cvt_pk_bf16_f32 v131, v133, v138
	v_cvt_pk_bf16_f32 v133, v137, v139
	v_mul_f32_e32 v137, 0xbfb8aa3b, v24
	v_mul_f32_e32 v136, 0xbfb8aa3b, v28
	v_exp_f32_e32 v137, v137
	global_store_dwordx4 v[134:135], v[130:133], off sc1
	v_exp_f32_e32 v136, v136
	v_mul_f32_e32 v138, 0xbfb8aa3b, v31
	v_mul_f32_e32 v132, 0xbfb8aa3b, v29
	v_mul_f32_e32 v133, 0xbfb8aa3b, v25
	v_exp_f32_e32 v132, v132
	v_exp_f32_e32 v133, v133
	v_add_f32_e32 v131, 1.0, v137
	v_add_f32_e32 v130, 1.0, v136
	v_rcp_f32_e32 v136, v131
	v_add_f32_e32 v131, 1.0, v132
	v_add_f32_e32 v132, 1.0, v133
	v_mul_f32_e32 v133, 0xbfb8aa3b, v30
	v_mul_f32_e32 v137, 0xbfb8aa3b, v26
	v_mul_f32_e32 v139, 0xbfb8aa3b, v27
	v_exp_f32_e32 v133, v133
	v_exp_f32_e32 v137, v137
	v_exp_f32_e32 v138, v138
	v_exp_f32_e32 v139, v139
	v_add_f32_e32 v133, 1.0, v133
	v_add_f32_e32 v137, 1.0, v137
	v_add_f32_e32 v138, 1.0, v138
	v_add_f32_e32 v139, 1.0, v139
	v_rcp_f32_e32 v130, v130
	v_rcp_f32_e32 v131, v131
	v_rcp_f32_e32 v132, v132
	v_rcp_f32_e32 v133, v133
	v_rcp_f32_e32 v137, v137
	v_rcp_f32_e32 v138, v138
	v_rcp_f32_e32 v139, v139
	v_cvt_pk_bf16_f32 v130, v130, v131
	v_cvt_pk_bf16_f32 v132, v136, v132
	v_cvt_pk_bf16_f32 v131, v133, v138
	v_cvt_pk_bf16_f32 v133, v137, v139
	global_store_dwordx4 v[134:135], v[130:133], off offset:256 sc1
	v_mul_f32_e32 v137, 0xbfb8aa3b, v34
	v_mul_f32_e32 v138, 0xbfb8aa3b, v39
	v_mul_f32_e32 v132, 0xbfb8aa3b, v36
	v_mul_f32_e32 v133, 0xbfb8aa3b, v32
	v_exp_f32_e32 v132, v132
	v_exp_f32_e32 v133, v133
	v_add_u32_e32 v130, 0xa0, v168
	v_ashrrev_i32_e32 v131, 31, v130
	v_lshlrev_b64 v[130:131], 13, v[130:131]
	v_lshl_add_u64 v[134:135], v[128:129], 0, v[130:131]
	v_add_f32_e32 v130, 1.0, v132
	v_add_f32_e32 v131, 1.0, v133
	v_mul_f32_e32 v132, 0xbfb8aa3b, v37
	v_mul_f32_e32 v133, 0xbfb8aa3b, v33
	v_exp_f32_e32 v132, v132
	v_exp_f32_e32 v133, v133
	v_rcp_f32_e32 v136, v131
	v_mul_f32_e32 v139, 0xbfb8aa3b, v35
	v_add_f32_e32 v131, 1.0, v132
	v_add_f32_e32 v132, 1.0, v133
	v_mul_f32_e32 v133, 0xbfb8aa3b, v38
	v_exp_f32_e32 v133, v133
	v_exp_f32_e32 v137, v137
	v_exp_f32_e32 v138, v138
	v_exp_f32_e32 v139, v139
	v_add_f32_e32 v133, 1.0, v133
	v_add_f32_e32 v137, 1.0, v137
	v_add_f32_e32 v138, 1.0, v138
	v_add_f32_e32 v139, 1.0, v139
	v_rcp_f32_e32 v130, v130
	v_rcp_f32_e32 v131, v131
	v_rcp_f32_e32 v132, v132
	v_rcp_f32_e32 v133, v133
	v_rcp_f32_e32 v137, v137
	v_rcp_f32_e32 v138, v138
	v_rcp_f32_e32 v139, v139
	v_cvt_pk_bf16_f32 v130, v130, v131
	v_cvt_pk_bf16_f32 v132, v136, v132
	v_cvt_pk_bf16_f32 v131, v133, v138
	v_cvt_pk_bf16_f32 v133, v137, v139
	v_mul_f32_e32 v137, 0xbfb8aa3b, v8
	v_mul_f32_e32 v136, 0xbfb8aa3b, v12
	v_exp_f32_e32 v137, v137
	global_store_dwordx4 v[134:135], v[130:133], off sc1
	v_exp_f32_e32 v136, v136
	v_mul_f32_e32 v138, 0xbfb8aa3b, v15
	v_mul_f32_e32 v132, 0xbfb8aa3b, v13
	v_mul_f32_e32 v133, 0xbfb8aa3b, v9
	v_exp_f32_e32 v132, v132
	v_exp_f32_e32 v133, v133
	v_add_f32_e32 v131, 1.0, v137
	v_add_f32_e32 v130, 1.0, v136
	v_rcp_f32_e32 v136, v131
	v_add_f32_e32 v131, 1.0, v132
	v_add_f32_e32 v132, 1.0, v133
	v_mul_f32_e32 v133, 0xbfb8aa3b, v14
	v_mul_f32_e32 v137, 0xbfb8aa3b, v10
; DI unsigned cvtpk(float lo, float hi) { f32x2 v = {lo, hi}; bf16x2_t b = __builtin_convertvector(v, bf16x2_t); return __builtin_bit_cast(unsigned, b); }
; DI unsigned cvtpk_h(float lo, float hi) { f32x2 v = {lo, hi}; h16x2_t b = __builtin_convertvector(v, h16x2_t); return __builtin_bit_cast(unsigned, b); }
; DI float sigm(float x) { return __builtin_amdgcn_rcpf(1.f + fexp(-x)); }
;     template <int MODE> __device__ __forceinline__ void run(const f32x4 (&acc)[2][2][4][2], u16* dst, int ld, int row0, int col0, int trow0, int wc, int fq, const float* lb) const {
;     ...
;                 f32x4 cs, sn;
;                 if (MODE == 1 || MODE == 2) { const int t = trow0 + rr; const int pos = (wc & 1) ? (t & 63) : (t >> 6);
;                     cs = *(const f32x4*)(rcos + pos * 16 + 4 * fq); sn = *(const f32x4*)(rsin + pos * 16 + 4 * fq); }
; #pragma unroll
;                 for (int bj = 0; bj < 2; ++bj) {
;                     f32x4 v0 = acc[ai][bj][m][0], v1 = acc[ai][bj][m][1];
;                     if (MODE == 1 || MODE == 2) { const f32x4 a = v0 * cs - v1 * sn, b = v1 * cs + v0 * sn; v0 = a; v1 = b;
;     ...
;                     if (MODE == 5) {
; #pragma unroll
;                         for (int i = 0; i < 4; ++i) { v0[i] = sigm(v0[i]); v1[i] = sigm(v1[i]); }
;                     }
;                     u32x4 w;
;                     if (MODE == 3) { w.x = cvtpk_h(v0[0], v0[1]); w.y = cvtpk_h(v0[2], v0[3]); w.z = cvtpk_h(v1[0], v1[1]); w.w = cvtpk_h(v1[2], v1[3]); }
;                     else { w.x = cvtpk(v0[0], v0[1]); w.y = cvtpk(v0[2], v0[3]); w.z = cvtpk(v1[0], v1[1]); w.w = cvtpk(v1[2], v1[3]); }
;                     *(u32x4*)(rowp + bj * HALF) = w;
	v_mul_f32_e32 v139, 0xbfb8aa3b, v11
	v_exp_f32_e32 v133, v133
	v_exp_f32_e32 v137, v137
	v_exp_f32_e32 v138, v138
	v_exp_f32_e32 v139, v139
	v_add_f32_e32 v133, 1.0, v133
	v_add_f32_e32 v137, 1.0, v137
	v_add_f32_e32 v138, 1.0, v138
	v_add_f32_e32 v139, 1.0, v139
	v_rcp_f32_e32 v130, v130
	v_rcp_f32_e32 v131, v131
	v_rcp_f32_e32 v132, v132
	v_rcp_f32_e32 v133, v133
	v_rcp_f32_e32 v137, v137
	v_rcp_f32_e32 v138, v138
	v_rcp_f32_e32 v139, v139
	v_cvt_pk_bf16_f32 v130, v130, v131
	v_cvt_pk_bf16_f32 v132, v136, v132
	v_cvt_pk_bf16_f32 v131, v133, v138
	v_cvt_pk_bf16_f32 v133, v137, v139
	global_store_dwordx4 v[134:135], v[130:133], off offset:256 sc1
	v_mul_f32_e32 v134, 0xbfb8aa3b, v23
	v_mul_f32_e32 v135, 0xbfb8aa3b, v19
	v_add_u32_e32 v130, 0xb0, v168
	v_ashrrev_i32_e32 v131, 31, v130
	v_lshlrev_b64 v[130:131], 13, v[130:131]
	v_mul_f32_e32 v133, 0xbfb8aa3b, v16
	v_mul_f32_e32 v132, 0xbfb8aa3b, v20
	v_exp_f32_e32 v133, v133
	v_lshl_add_u64 v[170:171], v[128:129], 0, v[130:131]
	v_mul_f32_e32 v130, 0xbfb8aa3b, v21
	v_mul_f32_e32 v131, 0xbfb8aa3b, v17
	v_exp_f32_e32 v132, v132
	v_exp_f32_e32 v130, v130
	v_exp_f32_e32 v131, v131
	v_add_f32_e32 v129, 1.0, v133
	v_add_f32_e32 v128, 1.0, v132
	v_rcp_f32_e32 v132, v129
	v_add_f32_e32 v129, 1.0, v130
	v_add_f32_e32 v130, 1.0, v131
	v_mul_f32_e32 v131, 0xbfb8aa3b, v22
	v_mul_f32_e32 v133, 0xbfb8aa3b, v18
	v_exp_f32_e32 v131, v131
	v_exp_f32_e32 v133, v133
	v_exp_f32_e32 v134, v134
	v_exp_f32_e32 v135, v135
	v_add_f32_e32 v131, 1.0, v131
	v_add_f32_e32 v133, 1.0, v133
	v_add_f32_e32 v134, 1.0, v134
	v_add_f32_e32 v135, 1.0, v135
	v_rcp_f32_e32 v128, v128
	v_rcp_f32_e32 v129, v129
	v_rcp_f32_e32 v130, v130
	v_rcp_f32_e32 v131, v131
	v_rcp_f32_e32 v133, v133
	v_rcp_f32_e32 v134, v134
	v_rcp_f32_e32 v135, v135
	v_cvt_pk_bf16_f32 v128, v128, v129
	v_cvt_pk_bf16_f32 v130, v132, v130
	v_cvt_pk_bf16_f32 v129, v131, v134
	v_cvt_pk_bf16_f32 v131, v133, v135
	v_mul_f32_e32 v133, 0xbfb8aa3b, v0
	v_mul_f32_e32 v132, 0xbfb8aa3b, v4
	v_exp_f32_e32 v133, v133
	global_store_dwordx4 v[170:171], v[128:131], off sc1
	v_exp_f32_e32 v132, v132
	v_mul_f32_e32 v134, 0xbfb8aa3b, v7
	v_mul_f32_e32 v130, 0xbfb8aa3b, v5
	v_mul_f32_e32 v131, 0xbfb8aa3b, v1
	v_exp_f32_e32 v130, v130
	v_exp_f32_e32 v131, v131
	v_add_f32_e32 v129, 1.0, v133
	v_add_f32_e32 v128, 1.0, v132
	v_rcp_f32_e32 v132, v129
	v_add_f32_e32 v129, 1.0, v130
	v_add_f32_e32 v130, 1.0, v131
	v_mul_f32_e32 v131, 0xbfb8aa3b, v6
	v_mul_f32_e32 v133, 0xbfb8aa3b, v2
	v_mul_f32_e32 v135, 0xbfb8aa3b, v3
	v_exp_f32_e32 v131, v131
	v_exp_f32_e32 v133, v133
	v_exp_f32_e32 v134, v134
	v_exp_f32_e32 v135, v135
	v_add_f32_e32 v131, 1.0, v131
	v_add_f32_e32 v133, 1.0, v133
	v_add_f32_e32 v134, 1.0, v134
	v_add_f32_e32 v135, 1.0, v135
	v_rcp_f32_e32 v128, v128
	v_rcp_f32_e32 v129, v129
	v_rcp_f32_e32 v130, v130
	v_rcp_f32_e32 v131, v131
	v_rcp_f32_e32 v133, v133
	v_rcp_f32_e32 v134, v134
	v_rcp_f32_e32 v135, v135
	v_cvt_pk_bf16_f32 v128, v128, v129
	v_cvt_pk_bf16_f32 v130, v132, v130
	v_cvt_pk_bf16_f32 v129, v131, v134
	v_cvt_pk_bf16_f32 v131, v133, v135
	s_mov_b64 s[6:7], 0
.LBB0_209:
	s_andn2_b64 vcc, exec, s[6:7]
	s_cbranch_vccnz .LBB0_214
	v_lshlrev_b32_e32 v152, 1, v187
	v_ashrrev_i32_e32 v167, 31, v166
	v_lshl_add_u64 v[132:133], s[20:21], 0, v[152:153]
	v_lshlrev_b64 v[128:129], 11, v[166:167]
	v_or_b32_e32 v140, 16, v166
	v_or_b32_e32 v136, 32, v166
	v_or_b32_e32 v134, 48, v166
	v_lshl_add_u64 v[138:139], v[132:133], 0, v[128:129]
	s_mov_b64 s[6:7], -1
	s_and_b64 vcc, exec, s[66:67]
	v_ashrrev_i32_e32 v141, 31, v140
	v_ashrrev_i32_e32 v137, 31, v136
	v_ashrrev_i32_e32 v135, 31, v134
	s_cbranch_vccz .LBB0_212
	s_ashr_i32 s0, s55, 6
	v_mov_b32_e32 v152, s0
	v_cndmask_b32_e64 v128, v175, v152, s[4:5]
	v_lshlrev_b32_e32 v128, 4, v128
	v_ashrrev_i32_e32 v129, 31, v128
	v_lshlrev_b64 v[142:143], 2, v[128:129]
	v_lshl_add_u64 v[128:129], v[156:157], 0, v[142:143]
	global_load_dwordx4 v[128:131], v[128:129], off
	v_lshl_add_u64 v[142:143], v[154:155], 0, v[142:143]
	global_load_dwordx4 v[168:171], v[142:143], off
	v_cndmask_b32_e64 v142, v180, v152, s[4:5]
	v_lshlrev_b32_e32 v142, 4, v142
	v_ashrrev_i32_e32 v143, 31, v142
	v_lshlrev_b64 v[142:143], 2, v[142:143]
	v_lshl_add_u64 v[172:173], v[156:157], 0, v[142:143]
	v_lshl_add_u64 v[142:143], v[154:155], 0, v[142:143]
	v_cndmask_b32_e64 v167, v181, v152, s[4:5]
	v_cndmask_b32_e64 v152, v182, v152, s[4:5]
	s_add_i32 s0, s55, 0x80
	s_ashr_i32 s0, s0, 6
	s_mov_b64 s[6:7], 0
	s_waitcnt vmcnt(0)
	v_pk_mul_f32 v[188:189], v[122:123], v[130:131]
	v_pk_mul_f32 v[190:191], v[120:121], v[128:129]
	v_pk_mul_f32 v[192:193], v[126:127], v[130:131]
	v_pk_mul_f32 v[196:197], v[124:125], v[128:129]
	v_pk_mul_f32 v[198:199], v[106:107], v[130:131]
	v_pk_mul_f32 v[200:201], v[104:105], v[128:129]
	v_pk_mul_f32 v[130:131], v[110:111], v[130:131]
	v_pk_mul_f32 v[128:129], v[108:109], v[128:129]
	v_pk_fma_f32 v[188:189], v[126:127], v[170:171], v[188:189] neg_lo:[0,0,1] neg_hi:[0,0,1]
	v_pk_fma_f32 v[190:191], v[124:125], v[168:169], v[190:191] neg_lo:[0,0,1] neg_hi:[0,0,1]
	v_pk_fma_f32 v[192:193], v[122:123], v[170:171], v[192:193]
	v_pk_fma_f32 v[196:197], v[120:121], v[168:169], v[196:197]
	v_pk_fma_f32 v[198:199], v[110:111], v[170:171], v[198:199] neg_lo:[0,0,1] neg_hi:[0,0,1]
	v_pk_fma_f32 v[200:201], v[108:109], v[168:169], v[200:201] neg_lo:[0,0,1] neg_hi:[0,0,1]
	v_pk_fma_f32 v[202:203], v[106:107], v[170:171], v[130:131]
	v_pk_fma_f32 v[170:171], v[104:105], v[168:169], v[128:129]
	v_cvt_pk_bf16_f32 v128, v190, v191
	v_cvt_pk_bf16_f32 v129, v188, v189
	v_cvt_pk_bf16_f32 v130, v196, v197
	v_cvt_pk_bf16_f32 v131, v192, v193
	v_cvt_pk_bf16_f32 v168, v200, v201
	v_cvt_pk_bf16_f32 v169, v198, v199
	v_cvt_pk_bf16_f32 v170, v170, v171
	v_cvt_pk_bf16_f32 v171, v202, v203
	global_store_dwordx4 v[138:139], v[128:131], off sc1
	global_store_dwordx4 v[138:139], v[168:171], off offset:256 sc1
	global_load_dwordx4 v[128:131], v[172:173], off
	s_nop 0
	global_load_dwordx4 v[168:171], v[142:143], off
	v_lshlrev_b32_e32 v172, 4, v167
	v_lshlrev_b64 v[142:143], 11, v[140:141]
	v_ashrrev_i32_e32 v173, 31, v172
	v_lshl_add_u64 v[142:143], v[132:133], 0, v[142:143]
	v_lshlrev_b64 v[172:173], 2, v[172:173]
	v_lshl_add_u64 v[188:189], v[156:157], 0, v[172:173]
	s_waitcnt vmcnt(1)
; DI unsigned cvtpk(float lo, float hi) { f32x2 v = {lo, hi}; bf16x2_t b = __builtin_convertvector(v, bf16x2_t); return __builtin_bit_cast(unsigned, b); }
; DI unsigned cvtpk_h(float lo, float hi) { f32x2 v = {lo, hi}; h16x2_t b = __builtin_convertvector(v, h16x2_t); return __builtin_bit_cast(unsigned, b); }
; DI float sigm(float x) { return __builtin_amdgcn_rcpf(1.f + fexp(-x)); }
; DI float silu_(float x) { return x * sigm(x); }
;     template <int MODE> __device__ __forceinline__ void run(const f32x4 (&acc)[2][2][4][2], u16* dst, int ld, int row0, int col0, int trow0, int wc, int fq, const float* lb) const {
;     ...
;                 f32x4 cs, sn;
;                 if (MODE == 1 || MODE == 2) { const int t = trow0 + rr; const int pos = (wc & 1) ? (t & 63) : (t >> 6);
;                     cs = *(const f32x4*)(rcos + pos * 16 + 4 * fq); sn = *(const f32x4*)(rsin + pos * 16 + 4 * fq); }
; #pragma unroll
;                 for (int bj = 0; bj < 2; ++bj) {
;                     f32x4 v0 = acc[ai][bj][m][0], v1 = acc[ai][bj][m][1];
;                     if (MODE == 1 || MODE == 2) { const f32x4 a = v0 * cs - v1 * sn, b = v1 * cs + v0 * sn; v0 = a; v1 = b;
;                         if (MODE == 2) { v0 = v0 * 0.18033688011112042f; v1 = v1 * 0.18033688011112042f; } }
;                     if (MODE == 3) {
; #pragma unroll
;                         for (int i = 0; i < 4; ++i) { const float l0 = lb0[bj][i], l1 = lb1[bj][i];
;                             v0[i] = __logf(l0 + (1.f - l0) * sigm(v0[i])); v1[i] = __logf(l1 + (1.f - l1) * sigm(v1[i])); }
;                     }
;                     if (MODE == 4) {
; #pragma unroll
;                         for (int i = 0; i < 4; ++i) { v0[i] = silu_(v0[i]); v1[i] = silu_(v1[i]); }
;                     }
;                     if (MODE == 5) {
; #pragma unroll
;                         for (int i = 0; i < 4; ++i) { v0[i] = sigm(v0[i]); v1[i] = sigm(v1[i]); }
;                     }
;                     u32x4 w;
;                     if (MODE == 3) { w.x = cvtpk_h(v0[0], v0[1]); w.y = cvtpk_h(v0[2], v0[3]); w.z = cvtpk_h(v1[0], v1[1]); w.w = cvtpk_h(v1[2], v1[3]); }
;                     else { w.x = cvtpk(v0[0], v0[1]); w.y = cvtpk(v0[2], v0[3]); w.z = cvtpk(v1[0], v1[1]); w.w = cvtpk(v1[2], v1[3]); }
;                     *(u32x4*)(rowp + bj * HALF) = w;
	v_pk_mul_f32 v[190:191], v[114:115], v[130:131]
	v_pk_mul_f32 v[192:193], v[112:113], v[128:129]
	v_pk_mul_f32 v[196:197], v[118:119], v[130:131]
	v_pk_mul_f32 v[198:199], v[116:117], v[128:129]
	v_pk_mul_f32 v[200:201], v[90:91], v[130:131]
	v_pk_mul_f32 v[202:203], v[88:89], v[128:129]
	v_pk_mul_f32 v[130:131], v[94:95], v[130:131]
	v_pk_mul_f32 v[128:129], v[92:93], v[128:129]
	s_waitcnt vmcnt(0)
	v_pk_fma_f32 v[190:191], v[118:119], v[170:171], v[190:191] neg_lo:[0,0,1] neg_hi:[0,0,1]
	v_pk_fma_f32 v[192:193], v[116:117], v[168:169], v[192:193] neg_lo:[0,0,1] neg_hi:[0,0,1]
	v_pk_fma_f32 v[196:197], v[114:115], v[170:171], v[196:197]
	v_pk_fma_f32 v[198:199], v[112:113], v[168:169], v[198:199]
	v_pk_fma_f32 v[200:201], v[94:95], v[170:171], v[200:201] neg_lo:[0,0,1] neg_hi:[0,0,1]
	v_pk_fma_f32 v[202:203], v[92:93], v[168:169], v[202:203] neg_lo:[0,0,1] neg_hi:[0,0,1]
	v_pk_fma_f32 v[204:205], v[90:91], v[170:171], v[130:131]
	v_pk_fma_f32 v[170:171], v[88:89], v[168:169], v[128:129]
	v_cvt_pk_bf16_f32 v128, v192, v193
	v_cvt_pk_bf16_f32 v129, v190, v191
	v_cvt_pk_bf16_f32 v130, v198, v199
	v_cvt_pk_bf16_f32 v131, v196, v197
	v_cvt_pk_bf16_f32 v168, v202, v203
	v_cvt_pk_bf16_f32 v169, v200, v201
	v_cvt_pk_bf16_f32 v170, v170, v171
	v_cvt_pk_bf16_f32 v171, v204, v205
	global_store_dwordx4 v[142:143], v[128:131], off sc1
	global_store_dwordx4 v[142:143], v[168:171], off offset:256 sc1
	global_load_dwordx4 v[128:131], v[188:189], off
	v_lshl_add_u64 v[142:143], v[154:155], 0, v[172:173]
	global_load_dwordx4 v[168:171], v[142:143], off
	v_lshlrev_b32_e32 v172, 4, v152
	v_lshlrev_b64 v[142:143], 11, v[136:137]
	v_ashrrev_i32_e32 v173, 31, v172
	v_lshl_add_u64 v[142:143], v[132:133], 0, v[142:143]
	v_lshlrev_b64 v[172:173], 2, v[172:173]
	v_lshl_add_u64 v[188:189], v[156:157], 0, v[172:173]
	v_mov_b32_e32 v152, s0
	v_cndmask_b32_e64 v152, v175, v152, s[4:5]
	s_add_i32 s0, s55, 0x90
	s_ashr_i32 s0, s0, 6
	s_waitcnt vmcnt(1)
	v_pk_mul_f32 v[190:191], v[98:99], v[130:131]
	v_pk_mul_f32 v[192:193], v[96:97], v[128:129]
	v_pk_mul_f32 v[196:197], v[102:103], v[130:131]
	v_pk_mul_f32 v[198:199], v[100:101], v[128:129]
	v_pk_mul_f32 v[200:201], v[74:75], v[130:131]
	v_pk_mul_f32 v[202:203], v[72:73], v[128:129]
	v_pk_mul_f32 v[130:131], v[78:79], v[130:131]
	v_pk_mul_f32 v[128:129], v[76:77], v[128:129]
	s_waitcnt vmcnt(0)
	v_pk_fma_f32 v[190:191], v[102:103], v[170:171], v[190:191] neg_lo:[0,0,1] neg_hi:[0,0,1]
	v_pk_fma_f32 v[192:193], v[100:101], v[168:169], v[192:193] neg_lo:[0,0,1] neg_hi:[0,0,1]
	v_pk_fma_f32 v[196:197], v[98:99], v[170:171], v[196:197]
	v_pk_fma_f32 v[198:199], v[96:97], v[168:169], v[198:199]
	v_pk_fma_f32 v[200:201], v[78:79], v[170:171], v[200:201] neg_lo:[0,0,1] neg_hi:[0,0,1]
	v_pk_fma_f32 v[202:203], v[76:77], v[168:169], v[202:203] neg_lo:[0,0,1] neg_hi:[0,0,1]
	v_pk_fma_f32 v[204:205], v[74:75], v[170:171], v[130:131]
	v_pk_fma_f32 v[170:171], v[72:73], v[168:169], v[128:129]
	v_cvt_pk_bf16_f32 v128, v192, v193
	v_cvt_pk_bf16_f32 v129, v190, v191
	v_cvt_pk_bf16_f32 v130, v198, v199
	v_cvt_pk_bf16_f32 v131, v196, v197
	v_cvt_pk_bf16_f32 v168, v202, v203
	v_cvt_pk_bf16_f32 v169, v200, v201
	v_cvt_pk_bf16_f32 v170, v170, v171
	v_cvt_pk_bf16_f32 v171, v204, v205
	global_store_dwordx4 v[142:143], v[128:131], off sc1
	global_store_dwordx4 v[142:143], v[168:171], off offset:256 sc1
	global_load_dwordx4 v[128:131], v[188:189], off
	v_lshl_add_u64 v[142:143], v[154:155], 0, v[172:173]
	global_load_dwordx4 v[168:171], v[142:143], off
	v_lshlrev_b32_e32 v172, 4, v152
	v_lshlrev_b64 v[142:143], 11, v[134:135]
	v_ashrrev_i32_e32 v173, 31, v172
	v_lshl_add_u64 v[142:143], v[132:133], 0, v[142:143]
	v_lshlrev_b64 v[172:173], 2, v[172:173]
	v_lshl_add_u64 v[188:189], v[156:157], 0, v[172:173]
	v_mov_b32_e32 v152, s0
	v_cndmask_b32_e64 v152, v180, v152, s[4:5]
	s_add_i32 s0, s55, 0xa0
	s_ashr_i32 s0, s0, 6
	s_addk_i32 s55, 0xb0
	s_waitcnt vmcnt(1)
	v_pk_mul_f32 v[190:191], v[82:83], v[130:131]
	v_pk_mul_f32 v[192:193], v[80:81], v[128:129]
	v_pk_mul_f32 v[196:197], v[86:87], v[130:131]
	v_pk_mul_f32 v[198:199], v[84:85], v[128:129]
	v_pk_mul_f32 v[200:201], v[66:67], v[130:131]
	v_pk_mul_f32 v[202:203], v[64:65], v[128:129]
	v_pk_mul_f32 v[130:131], v[70:71], v[130:131]
	v_pk_mul_f32 v[128:129], v[68:69], v[128:129]
	s_waitcnt vmcnt(0)
	v_pk_fma_f32 v[190:191], v[86:87], v[170:171], v[190:191] neg_lo:[0,0,1] neg_hi:[0,0,1]
	v_pk_fma_f32 v[192:193], v[84:85], v[168:169], v[192:193] neg_lo:[0,0,1] neg_hi:[0,0,1]
	v_pk_fma_f32 v[196:197], v[82:83], v[170:171], v[196:197]
	v_pk_fma_f32 v[198:199], v[80:81], v[168:169], v[198:199]
	v_pk_fma_f32 v[200:201], v[70:71], v[170:171], v[200:201] neg_lo:[0,0,1] neg_hi:[0,0,1]
	v_pk_fma_f32 v[202:203], v[68:69], v[168:169], v[202:203] neg_lo:[0,0,1] neg_hi:[0,0,1]
	v_pk_fma_f32 v[204:205], v[66:67], v[170:171], v[130:131]
	v_pk_fma_f32 v[170:171], v[64:65], v[168:169], v[128:129]
	v_cvt_pk_bf16_f32 v128, v192, v193
	v_cvt_pk_bf16_f32 v129, v190, v191
	v_cvt_pk_bf16_f32 v130, v198, v199
	v_cvt_pk_bf16_f32 v131, v196, v197
	v_cvt_pk_bf16_f32 v168, v202, v203
	v_cvt_pk_bf16_f32 v169, v200, v201
	v_cvt_pk_bf16_f32 v170, v170, v171
	v_cvt_pk_bf16_f32 v171, v204, v205
	global_store_dwordx4 v[142:143], v[128:131], off sc1
	global_store_dwordx4 v[142:143], v[168:171], off offset:256 sc1
	global_load_dwordx4 v[128:131], v[188:189], off
	v_lshl_add_u64 v[142:143], v[154:155], 0, v[172:173]
	global_load_dwordx4 v[168:171], v[142:143], off
	v_lshlrev_b32_e32 v188, 4, v152
	v_add_co_u32_e32 v172, vcc, s84, v138
	v_ashrrev_i32_e32 v189, 31, v188
	s_nop 0
	v_addc_co_u32_e32 v173, vcc, 0, v139, vcc
	v_lshlrev_b64 v[188:189], 2, v[188:189]
	v_lshl_add_u64 v[142:143], v[138:139], 0, s[46:47]
	v_lshl_add_u64 v[190:191], v[156:157], 0, v[188:189]
	v_mov_b32_e32 v152, s0
	v_cndmask_b32_e64 v152, v181, v152, s[4:5]
	s_ashr_i32 s0, s55, 6
	s_waitcnt vmcnt(1)
; DI unsigned cvtpk(float lo, float hi) { f32x2 v = {lo, hi}; bf16x2_t b = __builtin_convertvector(v, bf16x2_t); return __builtin_bit_cast(unsigned, b); }
; DI unsigned cvtpk_h(float lo, float hi) { f32x2 v = {lo, hi}; h16x2_t b = __builtin_convertvector(v, h16x2_t); return __builtin_bit_cast(unsigned, b); }
; DI float sigm(float x) { return __builtin_amdgcn_rcpf(1.f + fexp(-x)); }
; DI float silu_(float x) { return x * sigm(x); }
;     template <int MODE> __device__ __forceinline__ void run(const f32x4 (&acc)[2][2][4][2], u16* dst, int ld, int row0, int col0, int trow0, int wc, int fq, const float* lb) const {
;     ...
;                 f32x4 cs, sn;
;                 if (MODE == 1 || MODE == 2) { const int t = trow0 + rr; const int pos = (wc & 1) ? (t & 63) : (t >> 6);
;                     cs = *(const f32x4*)(rcos + pos * 16 + 4 * fq); sn = *(const f32x4*)(rsin + pos * 16 + 4 * fq); }
; #pragma unroll
;                 for (int bj = 0; bj < 2; ++bj) {
;                     f32x4 v0 = acc[ai][bj][m][0], v1 = acc[ai][bj][m][1];
;                     if (MODE == 1 || MODE == 2) { const f32x4 a = v0 * cs - v1 * sn, b = v1 * cs + v0 * sn; v0 = a; v1 = b;
;                         if (MODE == 2) { v0 = v0 * 0.18033688011112042f; v1 = v1 * 0.18033688011112042f; } }
;                     if (MODE == 3) {
; #pragma unroll
;                         for (int i = 0; i < 4; ++i) { const float l0 = lb0[bj][i], l1 = lb1[bj][i];
;                             v0[i] = __logf(l0 + (1.f - l0) * sigm(v0[i])); v1[i] = __logf(l1 + (1.f - l1) * sigm(v1[i])); }
;                     }
;                     if (MODE == 4) {
; #pragma unroll
;                         for (int i = 0; i < 4; ++i) { v0[i] = silu_(v0[i]); v1[i] = silu_(v1[i]); }
;                     }
;                     if (MODE == 5) {
; #pragma unroll
;                         for (int i = 0; i < 4; ++i) { v0[i] = sigm(v0[i]); v1[i] = sigm(v1[i]); }
;                     }
;                     u32x4 w;
;                     if (MODE == 3) { w.x = cvtpk_h(v0[0], v0[1]); w.y = cvtpk_h(v0[2], v0[3]); w.z = cvtpk_h(v1[0], v1[1]); w.w = cvtpk_h(v1[2], v1[3]); }
;                     else { w.x = cvtpk(v0[0], v0[1]); w.y = cvtpk(v0[2], v0[3]); w.z = cvtpk(v1[0], v1[1]); w.w = cvtpk(v1[2], v1[3]); }
;                     *(u32x4*)(rowp + bj * HALF) = w;
	v_pk_mul_f32 v[192:193], v[58:59], v[130:131]
	v_pk_mul_f32 v[196:197], v[56:57], v[128:129]
	v_pk_mul_f32 v[198:199], v[62:63], v[130:131]
	v_pk_mul_f32 v[200:201], v[60:61], v[128:129]
	v_pk_mul_f32 v[202:203], v[42:43], v[130:131]
	v_pk_mul_f32 v[204:205], v[40:41], v[128:129]
	v_pk_mul_f32 v[130:131], v[46:47], v[130:131]
	v_pk_mul_f32 v[128:129], v[44:45], v[128:129]
	s_waitcnt vmcnt(0)
	v_pk_fma_f32 v[192:193], v[62:63], v[170:171], v[192:193] neg_lo:[0,0,1] neg_hi:[0,0,1]
	v_pk_fma_f32 v[196:197], v[60:61], v[168:169], v[196:197] neg_lo:[0,0,1] neg_hi:[0,0,1]
	v_pk_fma_f32 v[198:199], v[58:59], v[170:171], v[198:199]
	v_pk_fma_f32 v[200:201], v[56:57], v[168:169], v[200:201]
	v_pk_fma_f32 v[202:203], v[46:47], v[170:171], v[202:203] neg_lo:[0,0,1] neg_hi:[0,0,1]
	v_pk_fma_f32 v[204:205], v[44:45], v[168:169], v[204:205] neg_lo:[0,0,1] neg_hi:[0,0,1]
	v_pk_fma_f32 v[206:207], v[42:43], v[170:171], v[130:131]
	v_pk_fma_f32 v[170:171], v[40:41], v[168:169], v[128:129]
	v_cvt_pk_bf16_f32 v128, v196, v197
	v_cvt_pk_bf16_f32 v129, v192, v193
	v_cvt_pk_bf16_f32 v130, v200, v201
	v_cvt_pk_bf16_f32 v131, v198, v199
	v_cvt_pk_bf16_f32 v168, v204, v205
	v_cvt_pk_bf16_f32 v169, v202, v203
	v_cvt_pk_bf16_f32 v170, v170, v171
	v_cvt_pk_bf16_f32 v171, v206, v207
	global_store_dwordx4 v[172:173], v[128:131], off sc1
	global_store_dwordx4 v[142:143], v[168:171], off offset:256 sc1
	global_load_dwordx4 v[128:131], v[190:191], off
	v_lshl_add_u64 v[142:143], v[154:155], 0, v[188:189]
	global_load_dwordx4 v[168:171], v[142:143], off
	v_lshlrev_b32_e32 v188, 4, v152
	v_add_co_u32_e32 v172, vcc, s85, v138
	v_ashrrev_i32_e32 v189, 31, v188
	s_nop 0
	v_addc_co_u32_e32 v173, vcc, 0, v139, vcc
	v_lshlrev_b64 v[188:189], 2, v[188:189]
	v_lshl_add_u64 v[142:143], v[138:139], 0, s[48:49]
	v_lshl_add_u64 v[190:191], v[156:157], 0, v[188:189]
	v_mov_b32_e32 v152, s0
	v_cndmask_b32_e64 v152, v182, v152, s[4:5]
	s_waitcnt vmcnt(1)
	v_pk_mul_f32 v[192:193], v[50:51], v[130:131]
	v_pk_mul_f32 v[196:197], v[48:49], v[128:129]
	v_pk_mul_f32 v[198:199], v[54:55], v[130:131]
	v_pk_mul_f32 v[200:201], v[52:53], v[128:129]
	v_pk_mul_f32 v[202:203], v[26:27], v[130:131]
	v_pk_mul_f32 v[204:205], v[24:25], v[128:129]
	v_pk_mul_f32 v[130:131], v[30:31], v[130:131]
	v_pk_mul_f32 v[128:129], v[28:29], v[128:129]
	s_waitcnt vmcnt(0)
	v_pk_fma_f32 v[192:193], v[54:55], v[170:171], v[192:193] neg_lo:[0,0,1] neg_hi:[0,0,1]
	v_pk_fma_f32 v[196:197], v[52:53], v[168:169], v[196:197] neg_lo:[0,0,1] neg_hi:[0,0,1]
	v_pk_fma_f32 v[198:199], v[50:51], v[170:171], v[198:199]
	v_pk_fma_f32 v[200:201], v[48:49], v[168:169], v[200:201]
	v_pk_fma_f32 v[202:203], v[30:31], v[170:171], v[202:203] neg_lo:[0,0,1] neg_hi:[0,0,1]
	v_pk_fma_f32 v[204:205], v[28:29], v[168:169], v[204:205] neg_lo:[0,0,1] neg_hi:[0,0,1]
	v_pk_fma_f32 v[206:207], v[26:27], v[170:171], v[130:131]
	v_pk_fma_f32 v[170:171], v[24:25], v[168:169], v[128:129]
	v_cvt_pk_bf16_f32 v128, v196, v197
	v_cvt_pk_bf16_f32 v129, v192, v193
	v_cvt_pk_bf16_f32 v130, v200, v201
	v_cvt_pk_bf16_f32 v131, v198, v199
	v_cvt_pk_bf16_f32 v168, v204, v205
	v_cvt_pk_bf16_f32 v169, v202, v203
	v_cvt_pk_bf16_f32 v170, v170, v171
	v_cvt_pk_bf16_f32 v171, v206, v207
	global_store_dwordx4 v[172:173], v[128:131], off sc1
	global_store_dwordx4 v[142:143], v[168:171], off offset:256 sc1
	global_load_dwordx4 v[128:131], v[190:191], off
	v_lshl_add_u64 v[142:143], v[154:155], 0, v[188:189]
	global_load_dwordx4 v[168:171], v[142:143], off
	v_lshlrev_b32_e32 v188, 4, v152
	v_add_co_u32_e32 v172, vcc, s88, v138
	v_ashrrev_i32_e32 v189, 31, v188
	s_nop 0
	v_addc_co_u32_e32 v173, vcc, 0, v139, vcc
	v_lshlrev_b64 v[188:189], 2, v[188:189]
	v_lshl_add_u64 v[142:143], v[138:139], 0, s[50:51]
	v_lshl_add_u64 v[190:191], v[156:157], 0, v[188:189]
	s_waitcnt vmcnt(1)
	v_pk_mul_f32 v[192:193], v[34:35], v[130:131]
	v_pk_mul_f32 v[196:197], v[32:33], v[128:129]
	v_pk_mul_f32 v[198:199], v[38:39], v[130:131]
	v_pk_mul_f32 v[200:201], v[36:37], v[128:129]
	v_pk_mul_f32 v[202:203], v[10:11], v[130:131]
	v_pk_mul_f32 v[204:205], v[8:9], v[128:129]
	v_pk_mul_f32 v[130:131], v[14:15], v[130:131]
	v_pk_mul_f32 v[128:129], v[12:13], v[128:129]
	s_waitcnt vmcnt(0)
	v_pk_fma_f32 v[192:193], v[38:39], v[170:171], v[192:193] neg_lo:[0,0,1] neg_hi:[0,0,1]
	v_pk_fma_f32 v[196:197], v[36:37], v[168:169], v[196:197] neg_lo:[0,0,1] neg_hi:[0,0,1]
	v_pk_fma_f32 v[198:199], v[34:35], v[170:171], v[198:199]
	v_pk_fma_f32 v[200:201], v[32:33], v[168:169], v[200:201]
	v_pk_fma_f32 v[202:203], v[14:15], v[170:171], v[202:203] neg_lo:[0,0,1] neg_hi:[0,0,1]
	v_pk_fma_f32 v[204:205], v[12:13], v[168:169], v[204:205] neg_lo:[0,0,1] neg_hi:[0,0,1]
	v_pk_fma_f32 v[206:207], v[10:11], v[170:171], v[130:131]
	v_pk_fma_f32 v[170:171], v[8:9], v[168:169], v[128:129]
	v_cvt_pk_bf16_f32 v128, v196, v197
	v_cvt_pk_bf16_f32 v129, v192, v193
	v_cvt_pk_bf16_f32 v130, v200, v201
	v_cvt_pk_bf16_f32 v131, v198, v199
	v_cvt_pk_bf16_f32 v168, v204, v205
	v_cvt_pk_bf16_f32 v169, v202, v203
	v_cvt_pk_bf16_f32 v170, v170, v171
	v_cvt_pk_bf16_f32 v171, v206, v207
	global_store_dwordx4 v[172:173], v[128:131], off sc1
	global_store_dwordx4 v[142:143], v[168:171], off offset:256 sc1
	global_load_dwordx4 v[128:131], v[190:191], off
	v_lshl_add_u64 v[142:143], v[154:155], 0, v[188:189]
	global_load_dwordx4 v[188:191], v[142:143], off
	v_add_co_u32_e32 v142, vcc, s89, v138
	v_lshl_add_u64 v[170:171], v[138:139], 0, s[52:53]
	s_nop 0
	v_addc_co_u32_e32 v143, vcc, 0, v139, vcc
	s_waitcnt vmcnt(1)
	v_pk_mul_f32 v[168:169], v[18:19], v[130:131]
	v_pk_mul_f32 v[172:173], v[16:17], v[128:129]
	v_pk_mul_f32 v[192:193], v[22:23], v[130:131]
	v_pk_mul_f32 v[196:197], v[20:21], v[128:129]
	v_pk_mul_f32 v[198:199], v[2:3], v[130:131]
	v_pk_mul_f32 v[200:201], v[0:1], v[128:129]
	v_pk_mul_f32 v[130:131], v[6:7], v[130:131]
	v_pk_mul_f32 v[128:129], v[4:5], v[128:129]
	s_waitcnt vmcnt(0)
	v_pk_fma_f32 v[168:169], v[22:23], v[190:191], v[168:169] neg_lo:[0,0,1] neg_hi:[0,0,1]
	v_pk_fma_f32 v[172:173], v[20:21], v[188:189], v[172:173] neg_lo:[0,0,1] neg_hi:[0,0,1]
	v_pk_fma_f32 v[192:193], v[18:19], v[190:191], v[192:193]
	v_pk_fma_f32 v[196:197], v[16:17], v[188:189], v[196:197]
	v_pk_fma_f32 v[198:199], v[6:7], v[190:191], v[198:199] neg_lo:[0,0,1] neg_hi:[0,0,1]
	v_pk_fma_f32 v[200:201], v[4:5], v[188:189], v[200:201] neg_lo:[0,0,1] neg_hi:[0,0,1]
	v_pk_fma_f32 v[202:203], v[2:3], v[190:191], v[130:131]
	v_pk_fma_f32 v[130:131], v[0:1], v[188:189], v[128:129]
	v_cvt_pk_bf16_f32 v188, v172, v173
	v_cvt_pk_bf16_f32 v189, v168, v169
	v_cvt_pk_bf16_f32 v190, v196, v197
	v_cvt_pk_bf16_f32 v191, v192, v193
	v_cvt_pk_bf16_f32 v128, v200, v201
	v_cvt_pk_bf16_f32 v129, v198, v199
	v_cvt_pk_bf16_f32 v130, v130, v131
	v_cvt_pk_bf16_f32 v131, v202, v203
	global_store_dwordx4 v[142:143], v[188:191], off sc1
; DI unsigned cvtpk(float lo, float hi) { f32x2 v = {lo, hi}; bf16x2_t b = __builtin_convertvector(v, bf16x2_t); return __builtin_bit_cast(unsigned, b); }
; DI unsigned cvtpk_h(float lo, float hi) { f32x2 v = {lo, hi}; h16x2_t b = __builtin_convertvector(v, h16x2_t); return __builtin_bit_cast(unsigned, b); }
;     template <int MODE> __device__ __forceinline__ void run(const f32x4 (&acc)[2][2][4][2], u16* dst, int ld, int row0, int col0, int trow0, int wc, int fq, const float* lb) const {
;     ...
;                     u32x4 w;
;                     if (MODE == 3) { w.x = cvtpk_h(v0[0], v0[1]); w.y = cvtpk_h(v0[2], v0[3]); w.z = cvtpk_h(v1[0], v1[1]); w.w = cvtpk_h(v1[2], v1[3]); }
;                     else { w.x = cvtpk(v0[0], v0[1]); w.y = cvtpk(v0[2], v0[3]); w.z = cvtpk(v1[0], v1[1]); w.w = cvtpk(v1[2], v1[3]); }
;                     *(u32x4*)(rowp + bj * HALF) = w;
.LBB0_212:
	s_andn2_b64 vcc, exec, s[6:7]
	s_cbranch_vccnz .LBB0_214
	v_cvt_pk_bf16_f32 v68, v68, v69
	v_cvt_pk_bf16_f32 v69, v70, v71
	v_cvt_pk_bf16_f32 v70, v64, v65
	v_add_u32_e32 v64, 0x80, v166
	v_ashrrev_i32_e32 v65, 31, v64
	v_cvt_pk_bf16_f32 v44, v44, v45
	v_cvt_pk_bf16_f32 v45, v46, v47
	v_cvt_pk_bf16_f32 v46, v40, v41
	v_add_u32_e32 v40, 0x90, v166
	v_cvt_pk_bf16_f32 v108, v108, v109
	v_cvt_pk_bf16_f32 v109, v110, v111
	v_cvt_pk_bf16_f32 v110, v104, v105
	v_cvt_pk_bf16_f32 v111, v106, v107
	v_lshlrev_b64 v[104:105], 11, v[140:141]
	v_lshlrev_b64 v[64:65], 11, v[64:65]
	v_ashrrev_i32_e32 v41, 31, v40
	v_cvt_pk_bf16_f32 v28, v28, v29
	v_cvt_pk_bf16_f32 v29, v30, v31
	v_cvt_pk_bf16_f32 v30, v24, v25
	v_add_u32_e32 v24, 0xa0, v166
	v_cvt_pk_bf16_f32 v12, v12, v13
	v_cvt_pk_bf16_f32 v13, v14, v15
	v_cvt_pk_bf16_f32 v14, v8, v9
	v_add_u32_e32 v8, 0xb0, v166
	global_store_dwordx4 v[138:139], v[108:111], off offset:256 sc1
	v_cvt_pk_bf16_f32 v92, v92, v93
	v_cvt_pk_bf16_f32 v93, v94, v95
	v_lshl_add_u64 v[108:109], v[132:133], 0, v[104:105]
	v_cvt_pk_bf16_f32 v94, v88, v89
	v_cvt_pk_bf16_f32 v95, v90, v91
	v_lshlrev_b64 v[88:89], 11, v[136:137]
	v_lshl_add_u64 v[64:65], v[132:133], 0, v[64:65]
	v_cvt_pk_bf16_f32 v47, v42, v43
	v_lshlrev_b64 v[40:41], 11, v[40:41]
	v_ashrrev_i32_e32 v25, 31, v24
	v_ashrrev_i32_e32 v9, 31, v8
	global_store_dwordx4 v[108:109], v[92:95], off offset:256 sc1
	v_cvt_pk_bf16_f32 v76, v76, v77
	v_cvt_pk_bf16_f32 v77, v78, v79
	v_lshl_add_u64 v[92:93], v[132:133], 0, v[88:89]
	v_cvt_pk_bf16_f32 v78, v72, v73
	v_cvt_pk_bf16_f32 v79, v74, v75
	v_lshlrev_b64 v[72:73], 11, v[134:135]
	global_store_dwordx4 v[64:65], v[44:47], off offset:256 sc1
	v_cvt_pk_bf16_f32 v31, v26, v27
	v_lshlrev_b64 v[24:25], 11, v[24:25]
	v_lshl_add_u64 v[44:45], v[132:133], 0, v[40:41]
	v_lshlrev_b64 v[8:9], 11, v[8:9]
	v_cvt_pk_bf16_f32 v124, v124, v125
	v_cvt_pk_bf16_f32 v125, v126, v127
	v_cvt_pk_bf16_f32 v126, v120, v121
	v_cvt_pk_bf16_f32 v127, v122, v123
	v_cvt_pk_bf16_f32 v104, v116, v117
	v_cvt_pk_bf16_f32 v105, v118, v119
	v_cvt_pk_bf16_f32 v106, v112, v113
	v_cvt_pk_bf16_f32 v107, v114, v115
	v_cvt_pk_bf16_f32 v88, v100, v101
	v_cvt_pk_bf16_f32 v89, v102, v103
	v_cvt_pk_bf16_f32 v90, v96, v97
	v_cvt_pk_bf16_f32 v91, v98, v99
	global_store_dwordx4 v[92:93], v[76:79], off offset:256 sc1
	v_cvt_pk_bf16_f32 v74, v80, v81
	v_cvt_pk_bf16_f32 v75, v82, v83
	v_lshl_add_u64 v[76:77], v[132:133], 0, v[72:73]
	v_cvt_pk_bf16_f32 v72, v84, v85
	v_cvt_pk_bf16_f32 v73, v86, v87
	v_cvt_pk_bf16_f32 v71, v66, v67
	v_cvt_pk_bf16_f32 v60, v60, v61
	v_cvt_pk_bf16_f32 v61, v62, v63
	v_cvt_pk_bf16_f32 v62, v56, v57
	v_cvt_pk_bf16_f32 v63, v58, v59
	v_cvt_pk_bf16_f32 v40, v52, v53
	v_cvt_pk_bf16_f32 v41, v54, v55
	v_cvt_pk_bf16_f32 v42, v48, v49
	v_cvt_pk_bf16_f32 v43, v50, v51
	global_store_dwordx4 v[44:45], v[28:31], off offset:256 sc1
	v_cvt_pk_bf16_f32 v26, v32, v33
	v_cvt_pk_bf16_f32 v27, v34, v35
	v_lshl_add_u64 v[28:29], v[132:133], 0, v[24:25]
	v_cvt_pk_bf16_f32 v24, v36, v37
	v_cvt_pk_bf16_f32 v25, v38, v39
	v_cvt_pk_bf16_f32 v15, v10, v11
	v_lshl_add_u64 v[170:171], v[132:133], 0, v[8:9]
	v_cvt_pk_bf16_f32 v8, v20, v21
	v_cvt_pk_bf16_f32 v9, v22, v23
	v_cvt_pk_bf16_f32 v10, v16, v17
	v_cvt_pk_bf16_f32 v11, v18, v19
	v_cvt_pk_bf16_f32 v128, v4, v5
	v_cvt_pk_bf16_f32 v129, v6, v7
	v_cvt_pk_bf16_f32 v130, v0, v1
	v_cvt_pk_bf16_f32 v131, v2, v3
	global_store_dwordx4 v[138:139], v[124:127], off sc1
	global_store_dwordx4 v[108:109], v[104:107], off sc1
	global_store_dwordx4 v[92:93], v[88:91], off sc1
	global_store_dwordx4 v[76:77], v[72:75], off sc1
	global_store_dwordx4 v[76:77], v[68:71], off offset:256 sc1
	global_store_dwordx4 v[64:65], v[60:63], off sc1
	global_store_dwordx4 v[44:45], v[40:43], off sc1
	global_store_dwordx4 v[28:29], v[24:27], off sc1
	global_store_dwordx4 v[28:29], v[12:15], off offset:256 sc1
	global_store_dwordx4 v[170:171], v[8:11], off sc1
.LBB0_214:
	s_andn2_b64 vcc, exec, s[60:61]
	s_mov_b64 s[6:7], -1
	global_store_dwordx4 v[170:171], v[128:131], off offset:256 sc1
	s_cbranch_vccnz .LBB0_170
	s_andn2_b64 vcc, exec, s[14:15]
	s_cbranch_vccnz .LBB0_169
	s_barrier
	s_branch .LBB0_169

; DI unsigned cvtpk(float lo, float hi) { f32x2 v = {lo, hi}; bf16x2_t b = __builtin_convertvector(v, bf16x2_t); return __builtin_bit_cast(unsigned, b); }
; DI float bflo(unsigned w) { return __uint_as_float(w << 16); }
; DI float bfhi(unsigned w) { return __uint_as_float(w & 0xffff0000u); }
; DI void rec_readout_row(const u16* __restrict__ OF, const u16* __restrict__ OB, u16* RG, const float* __restrict__ gnw, int m, int lane) {
;     const size_t off = (size_t)m * 1024 + lane * 16;
;     const u32x4v a0 = *(const u32x4v*)(OF + off), a1 = *(const u32x4v*)(OF + off + 8), b0 = *(const u32x4v*)(OB + off), b1 = *(const u32x4v*)(OB + off + 8);
;     const u32x4v g0 = *(const u32x4v*)(RG + off), g1 = *(const u32x4v*)(RG + off + 8);
;     float v[16]; float s = 0.f;
; #pragma unroll
;     for (int i = 0; i < 4; ++i) { v[2 * i] = bflo(a0[i]) + bflo(b0[i]); v[2 * i + 1] = bfhi(a0[i]) + bfhi(b0[i]); v[8 + 2 * i] = bflo(a1[i]) + bflo(b1[i]); v[8 + 2 * i + 1] = bfhi(a1[i]) + bfhi(b1[i]); }
; #pragma unroll
;     for (int i = 0; i < 16; ++i) s += v[i] * v[i];
;     const float rstd = rsqrtf(wave_sum(s) * (1.f / 1024.f) + EPS);
;     const float* gw_ = gnw + lane * 16;
;     u32x4v o0, o1;
; #pragma unroll
;     for (int i = 0; i < 4; ++i) {
;       o0[i] = cvtpk(v[2 * i] * rstd * gw_[2 * i] * bflo(g0[i]), v[2 * i + 1] * rstd * gw_[2 * i + 1] * bfhi(g0[i]));
;       o1[i] = cvtpk(v[8 + 2 * i] * rstd * gw_[8 + 2 * i] * bflo(g1[i]), v[8 + 2 * i + 1] * rstd * gw_[8 + 2 * i + 1] * bfhi(g1[i])); }
;     *(u32x4v*)(RG + off) = o0; *(u32x4v*)(RG + off + 8) = o1;
; }
; __global__ void __launch_bounds__(512, 2) fwd_megakernel(Params p_unused) {
;     ...
;         for (int i = 0; i < 8; ++i) rec_readout_row(OF, OB, RG, p.rec_gnorm_w, (int)it * 64 + wave * 8 + i, lane);
.LBB0_430:
	v_lshl_add_u64 v[48:49], v[22:23], 0, s[20:21]
	v_add_co_u32_e32 v42, vcc, 0x8400000, v48
	v_lshl_add_u64 v[40:41], v[48:49], 0, s[12:13]
	s_nop 0
	v_addc_co_u32_e32 v43, vcc, 0, v49, vcc
	v_add_co_u32_e32 v46, vcc, s3, v48
	v_lshl_add_u64 v[44:45], v[48:49], 0, s[14:15]
	s_nop 0
	v_addc_co_u32_e32 v47, vcc, 0, v49, vcc
	global_load_dwordx4 v[32:35], v[40:41], off offset:16
	global_load_dwordx4 v[36:39], v[42:43], off
	s_nop 0
	global_load_dwordx4 v[40:43], v[44:45], off offset:16
	s_nop 0
	global_load_dwordx4 v[44:47], v[46:47], off
	v_add_co_u32_e32 v56, vcc, s6, v48
	v_lshl_add_u64 v[52:53], v[48:49], 0, s[16:17]
	s_nop 0
	v_addc_co_u32_e32 v57, vcc, 0, v49, vcc
	global_load_dwordx4 v[48:51], v[56:57], off
	s_nop 0
	global_load_dwordx4 v[52:55], v[52:53], off offset:16
	s_add_u32 s20, s20, 0x800
	s_addc_u32 s21, s21, 0
	s_cmpk_eq_i32 s20, 0x4000
	s_waitcnt vmcnt(5)
	v_lshlrev_b32_e32 v58, 16, v35
	v_and_b32_e32 v59, 0xffff0000, v35
	s_waitcnt vmcnt(4)
	v_lshlrev_b32_e32 v60, 16, v39
	v_and_b32_e32 v61, 0xffff0000, v39
	v_lshlrev_b32_e32 v62, 16, v34
	v_and_b32_e32 v63, 0xffff0000, v34
	v_lshlrev_b32_e32 v34, 16, v38
	v_and_b32_e32 v35, 0xffff0000, v38
	v_lshlrev_b32_e32 v38, 16, v33
	v_and_b32_e32 v39, 0xffff0000, v33
	v_lshlrev_b32_e32 v64, 16, v37
	v_and_b32_e32 v65, 0xffff0000, v37
	v_lshlrev_b32_e32 v66, 16, v32
	v_and_b32_e32 v67, 0xffff0000, v32
	v_lshlrev_b32_e32 v32, 16, v36
	v_and_b32_e32 v33, 0xffff0000, v36
	s_waitcnt vmcnt(3)
	v_lshlrev_b32_e32 v36, 16, v43
	v_and_b32_e32 v37, 0xffff0000, v43
	s_waitcnt vmcnt(2)
	v_lshlrev_b32_e32 v68, 16, v47
	v_and_b32_e32 v69, 0xffff0000, v47
	v_lshlrev_b32_e32 v70, 16, v42
	v_and_b32_e32 v71, 0xffff0000, v42
	v_lshlrev_b32_e32 v42, 16, v46
	v_and_b32_e32 v43, 0xffff0000, v46
	v_lshlrev_b32_e32 v46, 16, v41
	v_and_b32_e32 v47, 0xffff0000, v41
	v_lshlrev_b32_e32 v74, 16, v40
	v_and_b32_e32 v75, 0xffff0000, v40
	v_lshlrev_b32_e32 v40, 16, v44
	v_and_b32_e32 v41, 0xffff0000, v44
	v_lshlrev_b32_e32 v72, 16, v45
	v_and_b32_e32 v73, 0xffff0000, v45
	v_pk_add_f32 v[32:33], v[32:33], v[40:41]
	v_pk_add_f32 v[36:37], v[58:59], v[36:37]
	s_waitcnt vmcnt(1)
	v_lshlrev_b32_e32 v58, 16, v51
	v_and_b32_e32 v59, 0xffff0000, v51
	v_pk_add_f32 v[34:35], v[34:35], v[42:43]
	v_lshlrev_b32_e32 v42, 16, v50
	v_and_b32_e32 v43, 0xffff0000, v50
	v_pk_add_f32 v[50:51], v[64:65], v[72:73]
	v_pk_mul_f32 v[80:81], v[32:33], v[32:33]
	v_pk_mul_f32 v[76:77], v[50:51], v[50:51]
	v_add_f32_e32 v31, v80, v81
	v_add_f32_e32 v31, v76, v31
	v_pk_mul_f32 v[72:73], v[34:35], v[34:35]
	v_add_f32_e32 v31, v77, v31
	v_pk_add_f32 v[44:45], v[60:61], v[68:69]
	v_add_f32_e32 v31, v72, v31
	v_pk_add_f32 v[60:61], v[62:63], v[70:71]
	s_waitcnt vmcnt(0)
	v_lshlrev_b32_e32 v62, 16, v54
	v_and_b32_e32 v63, 0xffff0000, v54
	v_lshlrev_b32_e32 v64, 16, v49
	v_and_b32_e32 v65, 0xffff0000, v49
	v_lshlrev_b32_e32 v40, 16, v48
	v_and_b32_e32 v41, 0xffff0000, v48
	v_lshlrev_b32_e32 v48, 16, v55
	v_and_b32_e32 v49, 0xffff0000, v55
	v_pk_mul_f32 v[54:55], v[44:45], v[44:45]
	v_add_f32_e32 v31, v73, v31
	v_pk_add_f32 v[66:67], v[66:67], v[74:75]
	v_add_f32_e32 v31, v54, v31
	v_pk_mul_f32 v[78:79], v[66:67], v[66:67]
	v_add_f32_e32 v31, v55, v31
	v_pk_add_f32 v[38:39], v[38:39], v[46:47]
	v_add_f32_e32 v31, v78, v31
	v_pk_mul_f32 v[74:75], v[38:39], v[38:39]
	v_add_f32_e32 v31, v79, v31
	v_add_f32_e32 v31, v74, v31
	v_pk_mul_f32 v[70:71], v[60:61], v[60:61]
	v_add_f32_e32 v31, v75, v31
	v_add_f32_e32 v31, v70, v31
	v_lshlrev_b32_e32 v46, 16, v53
	v_and_b32_e32 v47, 0xffff0000, v53
	v_lshlrev_b32_e32 v68, 16, v52
	v_and_b32_e32 v69, 0xffff0000, v52
	v_pk_mul_f32 v[52:53], v[36:37], v[36:37]
	v_add_f32_e32 v31, v71, v31
	v_add_f32_e32 v31, v52, v31
	v_add_f32_e32 v31, v53, v31
	ds_bpermute_b32 v52, v25, v31
	s_waitcnt lgkmcnt(0)
	v_add_f32_e32 v31, v31, v52
	ds_bpermute_b32 v52, v26, v31
	s_waitcnt lgkmcnt(0)
	v_add_f32_e32 v31, v31, v52
	ds_bpermute_b32 v52, v27, v31
	s_waitcnt lgkmcnt(0)
	v_add_f32_e32 v31, v31, v52
	ds_bpermute_b32 v52, v28, v31
	s_waitcnt lgkmcnt(0)
	v_add_f32_e32 v31, v31, v52
	ds_bpermute_b32 v52, v29, v31
	s_waitcnt lgkmcnt(0)
	v_add_f32_e32 v31, v31, v52
	ds_bpermute_b32 v52, v30, v31
	s_waitcnt lgkmcnt(0)
	v_add_f32_e32 v31, v31, v52
	v_fmamk_f32 v31, v31, 0x3a800000, v16
	v_mul_f32_e32 v52, 0x4b800000, v31
	v_cmp_gt_f32_e32 vcc, s24, v31
	s_nop 1
	v_cndmask_b32_e32 v31, v31, v52, vcc
	v_rsq_f32_e32 v31, v31
	s_nop 0
	v_mul_f32_e32 v52, 0x45800000, v31
	v_cndmask_b32_e32 v52, v31, v52, vcc
	v_pk_mul_f32 v[32:33], v[32:33], v[52:53] op_sel_hi:[1,0]
	v_pk_mul_f32 v[50:51], v[50:51], v[52:53] op_sel_hi:[1,0]
	v_pk_mul_f32 v[34:35], v[34:35], v[52:53] op_sel_hi:[1,0]
	v_pk_mul_f32 v[44:45], v[44:45], v[52:53] op_sel_hi:[1,0]
	v_pk_mul_f32 v[54:55], v[66:67], v[52:53] op_sel_hi:[1,0]
	v_pk_mul_f32 v[38:39], v[38:39], v[52:53] op_sel_hi:[1,0]
	v_pk_mul_f32 v[60:61], v[60:61], v[52:53] op_sel_hi:[1,0]
	v_pk_mul_f32 v[36:37], v[36:37], v[52:53] op_sel_hi:[1,0]
	v_pk_mul_f32 v[32:33], v[12:13], v[32:33]
	v_pk_mul_f32 v[50:51], v[14:15], v[50:51]
	v_pk_mul_f32 v[34:35], v[8:9], v[34:35]
	v_pk_mul_f32 v[44:45], v[10:11], v[44:45]
	v_pk_mul_f32 v[52:53], v[4:5], v[54:55]
	v_pk_mul_f32 v[38:39], v[6:7], v[38:39]
	v_pk_mul_f32 v[54:55], v[0:1], v[60:61]
	v_pk_mul_f32 v[36:37], v[2:3], v[36:37]
	v_pk_mul_f32 v[32:33], v[32:33], v[40:41]
	v_pk_mul_f32 v[50:51], v[50:51], v[64:65]
	v_pk_mul_f32 v[34:35], v[34:35], v[42:43]
	v_pk_mul_f32 v[44:45], v[44:45], v[58:59]
	v_pk_mul_f32 v[40:41], v[52:53], v[68:69]
	v_pk_mul_f32 v[38:39], v[38:39], v[46:47]
	v_pk_mul_f32 v[42:43], v[54:55], v[62:63]
	v_pk_mul_f32 v[46:47], v[36:37], v[48:49]
	v_cvt_pk_bf16_f32 v32, v32, v33
	v_cvt_pk_bf16_f32 v33, v50, v51
	v_cvt_pk_bf16_f32 v34, v34, v35
	v_cvt_pk_bf16_f32 v35, v44, v45
	v_cvt_pk_bf16_f32 v36, v40, v41
	v_cvt_pk_bf16_f32 v37, v38, v39
	v_cvt_pk_bf16_f32 v38, v42, v43
	v_cvt_pk_bf16_f32 v39, v46, v47
	global_store_dwordx4 v[56:57], v[32:35], off sc1
	global_store_dwordx4 v[56:57], v[36:39], off offset:16 sc1
	s_cbranch_scc0 .LBB0_430
	s_xor_b64 s[20:21], exec, -1
	s_branch .LBB0_423

; DI void transpose_item(const float* __restrict__ W, int K, int N, u16* __restrict__ WT, float* scr, int item, int lane, bool perm, bool pair_up = false) {
;   const int nblk = N / 32, kb = item / nblk, nb = item % nblk, k0 = 64 * kb, n0 = 32 * nb;
;   const int ns0 = pair_up ? (((n0 & 255) < 128) ? 128 * (n0 >> 8) + (n0 & 255) : FF + 128 * (n0 >> 8) + (n0 & 255) - 128) : n0;
;   float tv[32];
; #pragma unroll
;   for (int i = 0; i < 32; ++i) { const int kk = 2 * i + (lane >> 5); tv[i] = W[(size_t)(k0 + kk) * N + ns0 + (lane & 31)]; }
; __global__ void __launch_bounds__(512, 2) fwd_megakernel(Params p_unused) {
;     ...
;       for (;;) {
;         if (tid == 0) *(volatile unsigned*)(lds + ATT_CTR) = atomicAdd(tq, 1u);
;         __syncthreads();
;         const unsigned it = *(volatile unsigned*)(lds + ATT_CTR);
;         __syncthreads();
;         if (it >= 1408u + 1216u) break;
;         if (it < 1408u) { transpose_item(p.w_up, DM, FF2, WUP, scr, (int)it * 8 + wave, lane, false, true); continue; }
;         { constexpr int I_BA = 16 * 64, I_OUT = 32 * 64;
;           WSP(WBA, WS_WBA); WSP(WBR, WS_WBR); WSP(WOUT, WS_WOUT); WSP(WDN, WS_WDN);
;           int r = ((int)it - 1408) * 8 + wave;
;           if (r < I_BA) { transpose_item(p.w_branch_attn, 1024, DM, WBA, scr, r, lane, false); continue; } r -= I_BA;
;           if (r < I_BA) { transpose_item(p.w_branch_rec, 1024, DM, WBR, scr, r, lane, false); continue; } r -= I_BA;
;           if (r < I_OUT) { transpose_item(p.w_out, DM, DM, WOUT, scr, r, lane, false); continue; } r -= I_OUT;
;           transpose_item(p.w_down, FF, DM, WDN, scr, r, lane, false); }
.LBB0_439:
	s_or_b64 exec, exec, s[12:13]
	s_cmp_lg_u32 s29, -1
	s_cselect_b32 s12, s29, 0
	s_cselect_b32 s13, s7, 0
	v_mov_b32_e32 v22, s12
	v_mov_b32_e32 v23, s13
	s_waitcnt lgkmcnt(0)
	s_barrier
	flat_load_dword v0, v[22:23] sc0 sc1
	s_waitcnt vmcnt(0)
	s_mov_b64 s[14:15], -1
	s_waitcnt lgkmcnt(0)
	s_barrier
	v_cmp_gt_u32_e32 vcc, s2, v0
	s_and_saveexec_b64 s[12:13], vcc
	s_cbranch_execz .LBB0_434
	v_cmp_lt_u32_e32 vcc, s3, v0
	v_lshlrev_b32_e32 v0, 3, v0
	s_and_saveexec_b64 s[14:15], vcc
	s_xor_b64 s[14:15], exec, s[14:15]
	s_cbranch_execz .LBB0_454
	v_add_u32_e32 v23, s1, v0
	v_cmp_lt_i32_e32 vcc, s6, v23
	s_and_saveexec_b64 s[16:17], vcc
	s_xor_b64 s[16:17], exec, s[16:17]
	s_cbranch_execz .LBB0_451
	v_lshlrev_b32_e32 v0, 5, v23
	v_cmp_lt_u32_e32 vcc, s22, v23
	v_and_b32_e32 v22, 0x7e0, v0
	s_and_saveexec_b64 s[18:19], vcc
	s_xor_b64 s[18:19], exec, s[18:19]
	s_cbranch_execz .LBB0_448
	v_cmp_lt_u32_e32 vcc, s23, v23
	v_lshlrev_b32_e32 v0, 2, v22
	v_or_b32_e32 v27, v22, v32
	v_or_b32_e32 v26, v22, v34
	v_or_b32_e32 v25, v22, v35
	v_or_b32_e32 v24, v22, v36
	s_and_saveexec_b64 s[20:21], vcc
	s_xor_b64 s[20:21], exec, s[20:21]
	s_cbranch_execz .LBB0_445
	v_and_b32_e32 v22, 0x7fffffc0, v23
	v_add_u32_e32 v22, 0xfffff000, v22
	v_or_b32_e32 v28, v22, v30
	v_lshl_add_u64 v[44:45], v[2:3], 0, v[0:1]
	v_or_b32_e32 v0, 2, v28
	v_lshlrev_b64 v[48:49], 13, v[0:1]
	v_or_b32_e32 v0, 4, v28
	v_lshlrev_b64 v[50:51], 13, v[0:1]
	v_or_b32_e32 v0, 6, v28
	v_lshlrev_b64 v[52:53], 13, v[0:1]
	v_or_b32_e32 v0, 8, v28
	v_lshlrev_b64 v[54:55], 13, v[0:1]
	v_or_b32_e32 v0, 10, v28
	v_mov_b32_e32 v29, v1
	v_lshlrev_b64 v[56:57], 13, v[0:1]
	v_or_b32_e32 v0, 12, v28
	v_lshlrev_b64 v[46:47], 13, v[28:29]
	v_lshlrev_b64 v[58:59], 13, v[0:1]
	v_or_b32_e32 v0, 14, v28
	v_lshl_add_u64 v[46:47], v[44:45], 0, v[46:47]
	v_lshlrev_b64 v[60:61], 13, v[0:1]
	v_or_b32_e32 v0, 16, v28
	v_lshl_add_u64 v[48:49], v[44:45], 0, v[48:49]
	v_lshl_add_u64 v[50:51], v[44:45], 0, v[50:51]
	v_lshl_add_u64 v[52:53], v[44:45], 0, v[52:53]
	v_lshl_add_u64 v[54:55], v[44:45], 0, v[54:55]
	v_lshl_add_u64 v[56:57], v[44:45], 0, v[56:57]
	v_lshl_add_u64 v[58:59], v[44:45], 0, v[58:59]
	v_lshl_add_u64 v[60:61], v[44:45], 0, v[60:61]
	global_load_dword v23, v[46:47], off
	global_load_dword v62, v[48:49], off
	global_load_dword v63, v[50:51], off
	global_load_dword v64, v[52:53], off
	global_load_dword v65, v[54:55], off
	global_load_dword v66, v[56:57], off
	global_load_dword v67, v[58:59], off
	global_load_dword v68, v[60:61], off
	v_lshlrev_b64 v[46:47], 13, v[0:1]
	v_or_b32_e32 v0, 18, v28
	v_lshlrev_b64 v[48:49], 13, v[0:1]
	v_or_b32_e32 v0, 20, v28
	v_lshlrev_b64 v[50:51], 13, v[0:1]
	v_or_b32_e32 v0, 22, v28
	v_lshlrev_b64 v[52:53], 13, v[0:1]
	v_or_b32_e32 v0, 24, v28
	v_lshlrev_b64 v[54:55], 13, v[0:1]
	v_or_b32_e32 v0, 26, v28
	v_lshlrev_b64 v[56:57], 13, v[0:1]
	v_or_b32_e32 v0, 28, v28
	v_lshlrev_b64 v[58:59], 13, v[0:1]
	v_or_b32_e32 v0, 30, v28
	v_lshl_add_u64 v[46:47], v[44:45], 0, v[46:47]
	v_lshlrev_b64 v[60:61], 13, v[0:1]
	v_or_b32_e32 v0, 32, v28
	v_lshl_add_u64 v[48:49], v[44:45], 0, v[48:49]
	v_lshl_add_u64 v[50:51], v[44:45], 0, v[50:51]
	v_lshl_add_u64 v[52:53], v[44:45], 0, v[52:53]
	v_lshl_add_u64 v[54:55], v[44:45], 0, v[54:55]
	v_lshl_add_u64 v[56:57], v[44:45], 0, v[56:57]
	v_lshl_add_u64 v[58:59], v[44:45], 0, v[58:59]
	v_lshl_add_u64 v[60:61], v[44:45], 0, v[60:61]
	global_load_dword v69, v[46:47], off
	global_load_dword v70, v[48:49], off
	global_load_dword v71, v[50:51], off
	global_load_dword v72, v[52:53], off
	global_load_dword v73, v[54:55], off
	global_load_dword v74, v[56:57], off
	global_load_dword v75, v[58:59], off
	global_load_dword v76, v[60:61], off
	v_lshlrev_b64 v[46:47], 13, v[0:1]
	v_or_b32_e32 v0, 34, v28
	v_lshlrev_b64 v[48:49], 13, v[0:1]
	v_or_b32_e32 v0, 36, v28
	v_lshlrev_b64 v[50:51], 13, v[0:1]
	v_or_b32_e32 v0, 38, v28
	v_lshlrev_b64 v[52:53], 13, v[0:1]
	v_or_b32_e32 v0, 40, v28
	v_lshlrev_b64 v[54:55], 13, v[0:1]
	v_or_b32_e32 v0, 42, v28
	v_lshlrev_b64 v[56:57], 13, v[0:1]
	v_or_b32_e32 v0, 44, v28
	v_lshlrev_b64 v[58:59], 13, v[0:1]
	v_or_b32_e32 v0, 46, v28
	v_lshl_add_u64 v[46:47], v[44:45], 0, v[46:47]
	v_lshlrev_b64 v[60:61], 13, v[0:1]
	v_or_b32_e32 v0, 48, v28
	v_lshl_add_u64 v[48:49], v[44:45], 0, v[48:49]
	v_lshl_add_u64 v[50:51], v[44:45], 0, v[50:51]
	v_lshl_add_u64 v[52:53], v[44:45], 0, v[52:53]
	v_lshl_add_u64 v[54:55], v[44:45], 0, v[54:55]
	v_lshl_add_u64 v[56:57], v[44:45], 0, v[56:57]
	v_lshl_add_u64 v[58:59], v[44:45], 0, v[58:59]
	v_lshl_add_u64 v[60:61], v[44:45], 0, v[60:61]
	global_load_dword v77, v[46:47], off
	global_load_dword v78, v[48:49], off
	global_load_dword v79, v[50:51], off
	global_load_dword v80, v[52:53], off
	global_load_dword v81, v[54:55], off
	global_load_dword v82, v[56:57], off
	global_load_dword v83, v[58:59], off
	global_load_dword v84, v[60:61], off
	v_lshlrev_b64 v[46:47], 13, v[0:1]
	v_or_b32_e32 v0, 50, v28
	v_lshlrev_b64 v[48:49], 13, v[0:1]
	v_or_b32_e32 v0, 52, v28
	v_lshlrev_b64 v[50:51], 13, v[0:1]
	v_or_b32_e32 v0, 54, v28
	v_lshlrev_b64 v[52:53], 13, v[0:1]
	v_or_b32_e32 v0, 56, v28
	v_lshlrev_b64 v[54:55], 13, v[0:1]
	v_or_b32_e32 v0, 58, v28
	v_lshlrev_b64 v[56:57], 13, v[0:1]
	v_or_b32_e32 v0, 60, v28
	v_lshlrev_b64 v[58:59], 13, v[0:1]
	v_or_b32_e32 v0, 62, v28
	v_lshl_add_u64 v[46:47], v[44:45], 0, v[46:47]
	v_lshlrev_b64 v[28:29], 13, v[0:1]
	v_lshl_add_u64 v[48:49], v[44:45], 0, v[48:49]
	v_lshl_add_u64 v[50:51], v[44:45], 0, v[50:51]
	v_lshl_add_u64 v[52:53], v[44:45], 0, v[52:53]
	v_lshl_add_u64 v[54:55], v[44:45], 0, v[54:55]
	v_lshl_add_u64 v[56:57], v[44:45], 0, v[56:57]
	v_lshl_add_u64 v[58:59], v[44:45], 0, v[58:59]
	v_lshl_add_u64 v[28:29], v[44:45], 0, v[28:29]
	global_load_dword v0, v[46:47], off
	global_load_dword v44, v[48:49], off
	global_load_dword v45, v[50:51], off
	global_load_dword v60, v[52:53], off
	global_load_dword v61, v[54:55], off
	global_load_dword v85, v[56:57], off
	global_load_dword v86, v[58:59], off
	global_load_dword v87, v[28:29], off
	s_waitcnt vmcnt(30)
; DI unsigned cvtpk(float lo, float hi) { f32x2 v = {lo, hi}; bf16x2_t b = __builtin_convertvector(v, bf16x2_t); return __builtin_bit_cast(unsigned, b); }
; #define LDS_WAIT() asm volatile("s_waitcnt lgkmcnt(0)" ::: "memory")
; DI void transpose_item(const float* __restrict__ W, int K, int N, u16* __restrict__ WT, float* scr, int item, int lane, bool perm, bool pair_up = false) {
;     ...
;   for (int i = 0; i < 32; ++i) { const int kk = 2 * i + (lane >> 5); tv[i] = W[(size_t)(k0 + kk) * N + ns0 + (lane & 31)]; }
; #pragma unroll
;   for (int i = 0; i < 32; ++i) { const int kk = 2 * i + (lane >> 5); scr[kk * 33 + (lane & 31)] = tv[i]; }
;   LDS_WAIT(); asm volatile("" ::: "memory");
;   const int c = lane & 7;
; #pragma unroll
;   for (int j = 0; j < 4; ++j) { const int n = (lane >> 3) + 8 * j; const float* s = scr + (8 * c) * 33 + (perm ? cperm(n) : n);
;     u32x4v o; o.x = cvtpk(s[0 * 33], s[1 * 33]); o.y = cvtpk(s[2 * 33], s[3 * 33]); o.z = cvtpk(s[4 * 33], s[5 * 33]); o.w = cvtpk(s[6 * 33], s[7 * 33]);
;     *(u32x4v*)(WT + (size_t)(n0 + n) * K + k0 + 8 * c) = o; }
;   LDS_WAIT(); asm volatile("" ::: "memory");
	ds_write2_b32 v31, v23, v62 offset1:66
	s_waitcnt vmcnt(28)
	ds_write2_b32 v31, v63, v64 offset0:132 offset1:198
	s_waitcnt vmcnt(26)
	ds_write2_b32 v37, v65, v66 offset0:8 offset1:74
	s_waitcnt vmcnt(24)
	ds_write2_b32 v37, v67, v68 offset0:140 offset1:206
	s_waitcnt vmcnt(22)
	ds_write2_b32 v38, v69, v70 offset0:16 offset1:82
	s_waitcnt vmcnt(20)
	ds_write2_b32 v38, v71, v72 offset0:148 offset1:214
	s_waitcnt vmcnt(18)
	ds_write2_b32 v39, v73, v74 offset0:24 offset1:90
	s_waitcnt vmcnt(16)
	ds_write2_b32 v39, v75, v76 offset0:156 offset1:222
	s_waitcnt vmcnt(14)
	ds_write2_b32 v40, v77, v78 offset0:32 offset1:98
	s_waitcnt vmcnt(12)
	ds_write2_b32 v40, v79, v80 offset0:164 offset1:230
	s_waitcnt vmcnt(10)
	ds_write2_b32 v41, v81, v82 offset0:40 offset1:106
	s_waitcnt vmcnt(8)
	ds_write2_b32 v41, v83, v84 offset0:172 offset1:238
	s_waitcnt vmcnt(6)
	ds_write2_b32 v42, v0, v44 offset0:48 offset1:114
	s_waitcnt vmcnt(4)
	ds_write2_b32 v42, v45, v60 offset0:180 offset1:246
	s_waitcnt vmcnt(2)
	ds_write2_b32 v43, v61, v85 offset0:56 offset1:122
	s_waitcnt vmcnt(0)
	ds_write2_b32 v43, v86, v87 offset0:188 offset1:254
	s_waitcnt lgkmcnt(0)
	ds_read2_b32 v[28:29], v33 offset0:33 offset1:41
	ds_read2_b32 v[48:49], v33 offset1:8
	ds_read2_b32 v[50:51], v33 offset0:66 offset1:74
	ds_read2_b32 v[52:53], v33 offset0:99 offset1:107
	ds_read2_b32 v[54:55], v33 offset0:132 offset1:140
	ds_read2_b32 v[56:57], v33 offset0:165 offset1:173
	ds_read2_b32 v[58:59], v33 offset0:198 offset1:206
	ds_read2_b32 v[60:61], v33 offset0:231 offset1:239
	v_mov_b32_e32 v23, v1
	v_mul_u32_u24_e32 v0, 0x1600, v27
	v_lshl_add_u64 v[22:23], v[22:23], 1, v[4:5]
	v_lshlrev_b32_e32 v0, 1, v0
	s_waitcnt lgkmcnt(6)
	v_cvt_pk_bf16_f32 v44, v48, v28
	s_waitcnt lgkmcnt(4)
	v_cvt_pk_bf16_f32 v45, v50, v52
	s_waitcnt lgkmcnt(2)
	v_cvt_pk_bf16_f32 v46, v54, v56
	s_waitcnt lgkmcnt(0)
	v_cvt_pk_bf16_f32 v47, v58, v60
	v_lshl_add_u64 v[62:63], v[22:23], 0, v[0:1]
	global_store_dwordx4 v[62:63], v[44:47], off sc1
	v_mul_u32_u24_e32 v0, 0x1600, v26
	v_lshlrev_b32_e32 v0, 1, v0
	v_cvt_pk_bf16_f32 v44, v49, v29
	v_cvt_pk_bf16_f32 v45, v51, v53
	v_cvt_pk_bf16_f32 v46, v55, v57
	v_cvt_pk_bf16_f32 v47, v59, v61
	ds_read2_b32 v[48:49], v33 offset0:16 offset1:24
	ds_read2_b32 v[50:51], v33 offset0:49 offset1:57
	ds_read2_b32 v[52:53], v33 offset0:82 offset1:90
	ds_read2_b32 v[54:55], v33 offset0:115 offset1:123
	ds_read2_b32 v[56:57], v33 offset0:148 offset1:156
	ds_read2_b32 v[58:59], v33 offset0:181 offset1:189
	ds_read2_b32 v[60:61], v33 offset0:214 offset1:222
	ds_read2_b32 v[62:63], v33 offset0:247 offset1:255
	v_lshl_add_u64 v[26:27], v[22:23], 0, v[0:1]
	v_mul_u32_u24_e32 v0, 0x1600, v25
	v_lshlrev_b32_e32 v0, 1, v0
	global_store_dwordx4 v[26:27], v[44:47], off sc1
	s_waitcnt lgkmcnt(6)
	v_cvt_pk_bf16_f32 v26, v48, v50
	s_waitcnt lgkmcnt(4)
	v_cvt_pk_bf16_f32 v27, v52, v54
	v_lshl_add_u64 v[44:45], v[22:23], 0, v[0:1]
	v_mul_u32_u24_e32 v0, 0x1600, v24
	s_waitcnt lgkmcnt(2)
	v_cvt_pk_bf16_f32 v28, v56, v58
	s_waitcnt lgkmcnt(0)
	v_cvt_pk_bf16_f32 v29, v60, v62
	v_lshlrev_b32_e32 v0, 1, v0
	global_store_dwordx4 v[44:45], v[26:29], off sc1
	v_lshl_add_u64 v[22:23], v[22:23], 0, v[0:1]
	s_nop 0
	v_cvt_pk_bf16_f32 v26, v49, v51
	v_cvt_pk_bf16_f32 v27, v53, v55
	v_cvt_pk_bf16_f32 v28, v57, v59
	v_cvt_pk_bf16_f32 v29, v61, v63
	global_store_dwordx4 v[22:23], v[26:29], off sc1
	s_waitcnt lgkmcnt(0)
.LBB0_445:
	s_andn2_saveexec_b64 s[20:21], s[20:21]
	s_cbranch_execz .LBB0_447
	v_add_u32_e32 v22, 0xf800, v23
	v_and_b32_e32 v58, 0xffc0, v22
	v_or_b32_e32 v28, v58, v30
	v_lshl_add_u64 v[22:23], v[6:7], 0, v[0:1]
	v_lshlrev_b32_e32 v0, 13, v28
	v_lshl_add_u64 v[22:23], v[22:23], 0, v[0:1]
	v_add_co_u32_e32 v28, vcc, 0x4000, v22
	s_nop 1
	v_addc_co_u32_e32 v29, vcc, 0, v23, vcc
	v_add_co_u32_e32 v44, vcc, 0x8000, v22
	s_nop 1
	v_addc_co_u32_e32 v45, vcc, 0, v23, vcc
	v_add_co_u32_e32 v46, vcc, 0xc000, v22
	s_nop 1
	v_addc_co_u32_e32 v47, vcc, 0, v23, vcc
	v_add_co_u32_e32 v48, vcc, 0x10000, v22
	s_nop 1
	v_addc_co_u32_e32 v49, vcc, 0, v23, vcc
	v_add_co_u32_e32 v50, vcc, 0x14000, v22
	s_nop 1
	v_addc_co_u32_e32 v51, vcc, 0, v23, vcc
	v_add_co_u32_e32 v52, vcc, 0x18000, v22
	s_nop 1
	v_addc_co_u32_e32 v53, vcc, 0, v23, vcc
	v_add_co_u32_e32 v54, vcc, 0x1c000, v22
	s_nop 1
	v_addc_co_u32_e32 v55, vcc, 0, v23, vcc
	global_load_dword v0, v[22:23], off
	global_load_dword v59, v[28:29], off
	global_load_dword v60, v[44:45], off
	global_load_dword v61, v[46:47], off
	global_load_dword v62, v[48:49], off
	global_load_dword v63, v[50:51], off
	global_load_dword v64, v[52:53], off
	global_load_dword v65, v[54:55], off
	v_add_co_u32_e32 v28, vcc, 0x20000, v22
	s_nop 1
	v_addc_co_u32_e32 v29, vcc, 0, v23, vcc
	v_add_co_u32_e32 v44, vcc, 0x24000, v22
	s_nop 1
	v_addc_co_u32_e32 v45, vcc, 0, v23, vcc
	v_add_co_u32_e32 v46, vcc, 0x28000, v22
	s_nop 1
	v_addc_co_u32_e32 v47, vcc, 0, v23, vcc
	v_add_co_u32_e32 v48, vcc, 0x2c000, v22
	s_nop 1
	v_addc_co_u32_e32 v49, vcc, 0, v23, vcc
	v_add_co_u32_e32 v50, vcc, 0x30000, v22
	s_nop 1
	v_addc_co_u32_e32 v51, vcc, 0, v23, vcc
	v_add_co_u32_e32 v52, vcc, 0x34000, v22
	s_nop 1
	v_addc_co_u32_e32 v53, vcc, 0, v23, vcc
	v_add_co_u32_e32 v54, vcc, 0x38000, v22
	s_nop 1
	v_addc_co_u32_e32 v55, vcc, 0, v23, vcc
	v_add_co_u32_e32 v56, vcc, 0x3c000, v22
	s_nop 1
	v_addc_co_u32_e32 v57, vcc, 0, v23, vcc
	global_load_dword v66, v[28:29], off
	global_load_dword v67, v[44:45], off
	global_load_dword v68, v[46:47], off
	global_load_dword v69, v[48:49], off
; DI unsigned cvtpk(float lo, float hi) { f32x2 v = {lo, hi}; bf16x2_t b = __builtin_convertvector(v, bf16x2_t); return __builtin_bit_cast(unsigned, b); }
; #define LDS_WAIT() asm volatile("s_waitcnt lgkmcnt(0)" ::: "memory")
; DI void transpose_item(const float* __restrict__ W, int K, int N, u16* __restrict__ WT, float* scr, int item, int lane, bool perm, bool pair_up = false) {
;     ...
;   for (int i = 0; i < 32; ++i) { const int kk = 2 * i + (lane >> 5); tv[i] = W[(size_t)(k0 + kk) * N + ns0 + (lane & 31)]; }
; #pragma unroll
;   for (int i = 0; i < 32; ++i) { const int kk = 2 * i + (lane >> 5); scr[kk * 33 + (lane & 31)] = tv[i]; }
;   LDS_WAIT(); asm volatile("" ::: "memory");
;   const int c = lane & 7;
; #pragma unroll
;   for (int j = 0; j < 4; ++j) { const int n = (lane >> 3) + 8 * j; const float* s = scr + (8 * c) * 33 + (perm ? cperm(n) : n);
;     u32x4v o; o.x = cvtpk(s[0 * 33], s[1 * 33]); o.y = cvtpk(s[2 * 33], s[3 * 33]); o.z = cvtpk(s[4 * 33], s[5 * 33]); o.w = cvtpk(s[6 * 33], s[7 * 33]);
;     *(u32x4v*)(WT + (size_t)(n0 + n) * K + k0 + 8 * c) = o; }
;   LDS_WAIT(); asm volatile("" ::: "memory");
	global_load_dword v70, v[50:51], off
	global_load_dword v71, v[52:53], off
	global_load_dword v72, v[54:55], off
	global_load_dword v73, v[56:57], off
	v_add_co_u32_e32 v28, vcc, 0x40000, v22
	s_nop 1
	v_addc_co_u32_e32 v29, vcc, 0, v23, vcc
	v_add_co_u32_e32 v44, vcc, 0x44000, v22
	s_nop 1
	v_addc_co_u32_e32 v45, vcc, 0, v23, vcc
	v_add_co_u32_e32 v46, vcc, 0x48000, v22
	s_nop 1
	v_addc_co_u32_e32 v47, vcc, 0, v23, vcc
	v_add_co_u32_e32 v48, vcc, 0x4c000, v22
	s_nop 1
	v_addc_co_u32_e32 v49, vcc, 0, v23, vcc
	v_add_co_u32_e32 v50, vcc, 0x50000, v22
	s_nop 1
	v_addc_co_u32_e32 v51, vcc, 0, v23, vcc
	v_add_co_u32_e32 v52, vcc, 0x54000, v22
	s_nop 1
	v_addc_co_u32_e32 v53, vcc, 0, v23, vcc
	v_add_co_u32_e32 v54, vcc, 0x58000, v22
	s_nop 1
	v_addc_co_u32_e32 v55, vcc, 0, v23, vcc
	v_add_co_u32_e32 v56, vcc, 0x5c000, v22
	s_nop 1
	v_addc_co_u32_e32 v57, vcc, 0, v23, vcc
	global_load_dword v74, v[28:29], off
	global_load_dword v75, v[44:45], off
	global_load_dword v76, v[46:47], off
	global_load_dword v77, v[48:49], off
	global_load_dword v78, v[50:51], off
	global_load_dword v79, v[52:53], off
	global_load_dword v80, v[54:55], off
	global_load_dword v81, v[56:57], off
	v_add_co_u32_e32 v28, vcc, 0x60000, v22
	s_nop 1
	v_addc_co_u32_e32 v29, vcc, 0, v23, vcc
	v_add_co_u32_e32 v44, vcc, 0x64000, v22
	s_nop 1
	v_addc_co_u32_e32 v45, vcc, 0, v23, vcc
	v_add_co_u32_e32 v46, vcc, 0x68000, v22
	s_nop 1
	v_addc_co_u32_e32 v47, vcc, 0, v23, vcc
	v_add_co_u32_e32 v48, vcc, 0x6c000, v22
	s_nop 1
	v_addc_co_u32_e32 v49, vcc, 0, v23, vcc
	v_add_co_u32_e32 v50, vcc, 0x70000, v22
	s_nop 1
	v_addc_co_u32_e32 v51, vcc, 0, v23, vcc
	v_add_co_u32_e32 v52, vcc, 0x74000, v22
	s_nop 1
	v_addc_co_u32_e32 v53, vcc, 0, v23, vcc
	v_add_co_u32_e32 v54, vcc, 0x78000, v22
	s_nop 1
	v_addc_co_u32_e32 v55, vcc, 0, v23, vcc
	v_add_co_u32_e32 v22, vcc, 0x7c000, v22
	s_nop 1
	v_addc_co_u32_e32 v23, vcc, 0, v23, vcc
	global_load_dword v56, v[28:29], off
	global_load_dword v57, v[44:45], off
	global_load_dword v82, v[46:47], off
	global_load_dword v83, v[48:49], off
	global_load_dword v84, v[50:51], off
	global_load_dword v85, v[52:53], off
	global_load_dword v86, v[54:55], off
	global_load_dword v87, v[22:23], off
	s_waitcnt vmcnt(30)
	ds_write2_b32 v31, v0, v59 offset1:66
	s_waitcnt vmcnt(28)
	ds_write2_b32 v31, v60, v61 offset0:132 offset1:198
	s_waitcnt vmcnt(26)
	ds_write2_b32 v37, v62, v63 offset0:8 offset1:74
	s_waitcnt vmcnt(24)
	ds_write2_b32 v37, v64, v65 offset0:140 offset1:206
	s_waitcnt vmcnt(22)
	ds_write2_b32 v38, v66, v67 offset0:16 offset1:82
	s_waitcnt vmcnt(20)
	ds_write2_b32 v38, v68, v69 offset0:148 offset1:214
	s_waitcnt vmcnt(18)
	ds_write2_b32 v39, v70, v71 offset0:24 offset1:90
	s_waitcnt vmcnt(16)
	ds_write2_b32 v39, v72, v73 offset0:156 offset1:222
	s_waitcnt vmcnt(14)
	ds_write2_b32 v40, v74, v75 offset0:32 offset1:98
	s_waitcnt vmcnt(12)
	ds_write2_b32 v40, v76, v77 offset0:164 offset1:230
	s_waitcnt vmcnt(10)
	ds_write2_b32 v41, v78, v79 offset0:40 offset1:106
	s_waitcnt vmcnt(8)
	ds_write2_b32 v41, v80, v81 offset0:172 offset1:238
	s_waitcnt vmcnt(6)
	ds_write2_b32 v42, v56, v57 offset0:48 offset1:114
	s_waitcnt vmcnt(4)
	ds_write2_b32 v42, v82, v83 offset0:180 offset1:246
	s_waitcnt vmcnt(2)
	ds_write2_b32 v43, v84, v85 offset0:56 offset1:122
	s_waitcnt vmcnt(0)
	ds_write2_b32 v43, v86, v87 offset0:188 offset1:254
	s_waitcnt lgkmcnt(0)
	v_lshlrev_b32_e32 v0, 1, v58
	ds_read2_b32 v[22:23], v33 offset0:33 offset1:41
	ds_read2_b32 v[28:29], v33 offset1:8
	ds_read2_b32 v[48:49], v33 offset0:66 offset1:74
	ds_read2_b32 v[50:51], v33 offset0:99 offset1:107
	ds_read2_b32 v[52:53], v33 offset0:132 offset1:140
	ds_read2_b32 v[54:55], v33 offset0:165 offset1:173
	ds_read2_b32 v[56:57], v33 offset0:198 offset1:206
	ds_read2_b32 v[58:59], v33 offset0:231 offset1:239
	v_lshl_add_u64 v[60:61], v[8:9], 0, v[0:1]
	v_lshlrev_b32_e32 v0, 12, v27
	s_waitcnt lgkmcnt(6)
	v_cvt_pk_bf16_f32 v44, v28, v22
	s_waitcnt lgkmcnt(4)
	v_cvt_pk_bf16_f32 v45, v48, v50
	s_waitcnt lgkmcnt(2)
	v_cvt_pk_bf16_f32 v46, v52, v54
	s_waitcnt lgkmcnt(0)
	v_cvt_pk_bf16_f32 v47, v56, v58
	v_lshl_add_u64 v[62:63], v[60:61], 0, v[0:1]
	global_store_dwordx4 v[62:63], v[44:47], off sc1
	v_lshlrev_b32_e32 v0, 12, v26
	s_nop 0
	v_cvt_pk_bf16_f32 v45, v49, v51
	v_cvt_pk_bf16_f32 v46, v53, v55
	v_cvt_pk_bf16_f32 v47, v57, v59
	ds_read2_b32 v[48:49], v33 offset0:49 offset1:57
	ds_read2_b32 v[50:51], v33 offset0:16 offset1:24
	ds_read2_b32 v[52:53], v33 offset0:82 offset1:90
	ds_read2_b32 v[54:55], v33 offset0:115 offset1:123
	ds_read2_b32 v[56:57], v33 offset0:148 offset1:156
	ds_read2_b32 v[58:59], v33 offset0:181 offset1:189
	ds_read2_b32 v[62:63], v33 offset0:214 offset1:222
	ds_read2_b32 v[64:65], v33 offset0:247 offset1:255
	v_cvt_pk_bf16_f32 v44, v29, v23
	v_lshl_add_u64 v[22:23], v[60:61], 0, v[0:1]
	v_lshlrev_b32_e32 v0, 12, v25
	global_store_dwordx4 v[22:23], v[44:47], off sc1
	s_waitcnt lgkmcnt(6)
	v_cvt_pk_bf16_f32 v26, v50, v48
	s_waitcnt lgkmcnt(4)
	v_cvt_pk_bf16_f32 v27, v52, v54
	s_waitcnt lgkmcnt(2)
	v_cvt_pk_bf16_f32 v28, v56, v58
	s_waitcnt lgkmcnt(0)
	v_cvt_pk_bf16_f32 v29, v62, v64
	v_lshl_add_u64 v[22:23], v[60:61], 0, v[0:1]
	v_lshlrev_b32_e32 v0, 12, v24
	global_store_dwordx4 v[22:23], v[26:29], off sc1
	v_lshl_add_u64 v[22:23], v[60:61], 0, v[0:1]
	s_nop 0
	v_cvt_pk_bf16_f32 v26, v51, v49
	v_cvt_pk_bf16_f32 v27, v53, v55
	v_cvt_pk_bf16_f32 v28, v57, v59
	v_cvt_pk_bf16_f32 v29, v63, v65
	global_store_dwordx4 v[22:23], v[26:29], off sc1
	s_waitcnt lgkmcnt(0)

; DI void transpose_item(const float* __restrict__ W, int K, int N, u16* __restrict__ WT, float* scr, int item, int lane, bool perm, bool pair_up = false) {
;   const int nblk = N / 32, kb = item / nblk, nb = item % nblk, k0 = 64 * kb, n0 = 32 * nb;
;   const int ns0 = pair_up ? (((n0 & 255) < 128) ? 128 * (n0 >> 8) + (n0 & 255) : FF + 128 * (n0 >> 8) + (n0 & 255) - 128) : n0;
;   float tv[32];
; #pragma unroll
;   for (int i = 0; i < 32; ++i) { const int kk = 2 * i + (lane >> 5); tv[i] = W[(size_t)(k0 + kk) * N + ns0 + (lane & 31)]; }
.LBB0_448:
	s_andn2_saveexec_b64 s[18:19], s[18:19]
	s_cbranch_execz .LBB0_450
	v_add_u32_e32 v0, 0xfc00, v23
	v_and_b32_e32 v23, 0xffc0, v0
	v_or_b32_e32 v26, v23, v30
	v_lshlrev_b32_e32 v0, 2, v22
	v_lshl_add_u64 v[24:25], v[10:11], 0, v[0:1]
	v_lshlrev_b32_e32 v0, 13, v26
	v_lshl_add_u64 v[24:25], v[24:25], 0, v[0:1]
	v_add_co_u32_e32 v26, vcc, 0x4000, v24
	s_nop 1
	v_addc_co_u32_e32 v27, vcc, 0, v25, vcc
	v_add_co_u32_e32 v28, vcc, 0x8000, v24
	s_nop 1
	v_addc_co_u32_e32 v29, vcc, 0, v25, vcc
	v_add_co_u32_e32 v44, vcc, 0xc000, v24
	s_nop 1
	v_addc_co_u32_e32 v45, vcc, 0, v25, vcc
	v_add_co_u32_e32 v46, vcc, 0x10000, v24
	s_nop 1
	v_addc_co_u32_e32 v47, vcc, 0, v25, vcc
	v_add_co_u32_e32 v48, vcc, 0x14000, v24
	s_nop 1
	v_addc_co_u32_e32 v49, vcc, 0, v25, vcc
	v_add_co_u32_e32 v50, vcc, 0x18000, v24
	s_nop 1
	v_addc_co_u32_e32 v51, vcc, 0, v25, vcc
	v_add_co_u32_e32 v52, vcc, 0x1c000, v24
	s_nop 1
	v_addc_co_u32_e32 v53, vcc, 0, v25, vcc
	global_load_dword v0, v[24:25], off
	global_load_dword v56, v[26:27], off
	global_load_dword v57, v[28:29], off
	global_load_dword v58, v[44:45], off
	global_load_dword v59, v[46:47], off
	global_load_dword v60, v[48:49], off
	global_load_dword v61, v[50:51], off
	global_load_dword v62, v[52:53], off
	v_add_co_u32_e32 v26, vcc, 0x20000, v24
	s_nop 1
	v_addc_co_u32_e32 v27, vcc, 0, v25, vcc
	v_add_co_u32_e32 v28, vcc, 0x24000, v24
	s_nop 1
	v_addc_co_u32_e32 v29, vcc, 0, v25, vcc
	v_add_co_u32_e32 v44, vcc, 0x28000, v24
	s_nop 1
	v_addc_co_u32_e32 v45, vcc, 0, v25, vcc
	v_add_co_u32_e32 v46, vcc, 0x2c000, v24
	s_nop 1
	v_addc_co_u32_e32 v47, vcc, 0, v25, vcc
	v_add_co_u32_e32 v48, vcc, 0x30000, v24
	s_nop 1
	v_addc_co_u32_e32 v49, vcc, 0, v25, vcc
	v_add_co_u32_e32 v50, vcc, 0x34000, v24
	s_nop 1
	v_addc_co_u32_e32 v51, vcc, 0, v25, vcc
	v_add_co_u32_e32 v52, vcc, 0x38000, v24
	s_nop 1
	v_addc_co_u32_e32 v53, vcc, 0, v25, vcc
	v_add_co_u32_e32 v54, vcc, 0x3c000, v24
	s_nop 1
	v_addc_co_u32_e32 v55, vcc, 0, v25, vcc
	global_load_dword v63, v[26:27], off
	global_load_dword v64, v[28:29], off
	global_load_dword v65, v[44:45], off
	global_load_dword v66, v[46:47], off
	global_load_dword v67, v[48:49], off
	global_load_dword v68, v[50:51], off
	global_load_dword v69, v[52:53], off
	global_load_dword v70, v[54:55], off
	v_add_co_u32_e32 v26, vcc, 0x40000, v24
	s_nop 1
	v_addc_co_u32_e32 v27, vcc, 0, v25, vcc
	v_add_co_u32_e32 v28, vcc, 0x44000, v24
	s_nop 1
	v_addc_co_u32_e32 v29, vcc, 0, v25, vcc
	v_add_co_u32_e32 v44, vcc, 0x48000, v24
	s_nop 1
	v_addc_co_u32_e32 v45, vcc, 0, v25, vcc
	v_add_co_u32_e32 v46, vcc, 0x4c000, v24
	s_nop 1
	v_addc_co_u32_e32 v47, vcc, 0, v25, vcc
	v_add_co_u32_e32 v48, vcc, 0x50000, v24
	s_nop 1
	v_addc_co_u32_e32 v49, vcc, 0, v25, vcc
	v_add_co_u32_e32 v50, vcc, 0x54000, v24
	s_nop 1
	v_addc_co_u32_e32 v51, vcc, 0, v25, vcc
	v_add_co_u32_e32 v52, vcc, 0x58000, v24
	s_nop 1
	v_addc_co_u32_e32 v53, vcc, 0, v25, vcc
	v_add_co_u32_e32 v54, vcc, 0x5c000, v24
	s_nop 1
	v_addc_co_u32_e32 v55, vcc, 0, v25, vcc
	global_load_dword v71, v[26:27], off
	global_load_dword v72, v[28:29], off
	global_load_dword v73, v[44:45], off
	global_load_dword v74, v[46:47], off
	global_load_dword v75, v[48:49], off
	global_load_dword v76, v[50:51], off
	global_load_dword v77, v[52:53], off
	global_load_dword v78, v[54:55], off
	v_add_co_u32_e32 v26, vcc, 0x60000, v24
	s_nop 1
	v_addc_co_u32_e32 v27, vcc, 0, v25, vcc
	v_add_co_u32_e32 v28, vcc, 0x64000, v24
	s_nop 1
	v_addc_co_u32_e32 v29, vcc, 0, v25, vcc
	v_add_co_u32_e32 v44, vcc, 0x68000, v24
	s_nop 1
	v_addc_co_u32_e32 v45, vcc, 0, v25, vcc
	v_add_co_u32_e32 v46, vcc, 0x6c000, v24
	s_nop 1
	v_addc_co_u32_e32 v47, vcc, 0, v25, vcc
	v_add_co_u32_e32 v48, vcc, 0x70000, v24
	s_nop 1
	v_addc_co_u32_e32 v49, vcc, 0, v25, vcc
	v_add_co_u32_e32 v50, vcc, 0x74000, v24
	s_nop 1
	v_addc_co_u32_e32 v51, vcc, 0, v25, vcc
	v_add_co_u32_e32 v52, vcc, 0x78000, v24
	s_nop 1
	v_addc_co_u32_e32 v53, vcc, 0, v25, vcc
	v_add_co_u32_e32 v24, vcc, 0x7c000, v24
	s_nop 1
	v_addc_co_u32_e32 v25, vcc, 0, v25, vcc
	global_load_dword v54, v[26:27], off
	global_load_dword v55, v[28:29], off
	global_load_dword v79, v[44:45], off
	global_load_dword v80, v[46:47], off
	global_load_dword v81, v[48:49], off
	global_load_dword v82, v[50:51], off
	global_load_dword v83, v[52:53], off
	global_load_dword v84, v[24:25], off
	s_waitcnt vmcnt(30)
; DI unsigned cvtpk(float lo, float hi) { f32x2 v = {lo, hi}; bf16x2_t b = __builtin_convertvector(v, bf16x2_t); return __builtin_bit_cast(unsigned, b); }
; #define LDS_WAIT() asm volatile("s_waitcnt lgkmcnt(0)" ::: "memory")
; DI void transpose_item(const float* __restrict__ W, int K, int N, u16* __restrict__ WT, float* scr, int item, int lane, bool perm, bool pair_up = false) {
;   const int nblk = N / 32, kb = item / nblk, nb = item % nblk, k0 = 64 * kb, n0 = 32 * nb;
;   const int ns0 = pair_up ? (((n0 & 255) < 128) ? 128 * (n0 >> 8) + (n0 & 255) : FF + 128 * (n0 >> 8) + (n0 & 255) - 128) : n0;
;   float tv[32];
; #pragma unroll
;   for (int i = 0; i < 32; ++i) { const int kk = 2 * i + (lane >> 5); tv[i] = W[(size_t)(k0 + kk) * N + ns0 + (lane & 31)]; }
; #pragma unroll
;   for (int i = 0; i < 32; ++i) { const int kk = 2 * i + (lane >> 5); scr[kk * 33 + (lane & 31)] = tv[i]; }
;   LDS_WAIT(); asm volatile("" ::: "memory");
;   const int c = lane & 7;
; #pragma unroll
;   for (int j = 0; j < 4; ++j) { const int n = (lane >> 3) + 8 * j; const float* s = scr + (8 * c) * 33 + (perm ? cperm(n) : n);
;     u32x4v o; o.x = cvtpk(s[0 * 33], s[1 * 33]); o.y = cvtpk(s[2 * 33], s[3 * 33]); o.z = cvtpk(s[4 * 33], s[5 * 33]); o.w = cvtpk(s[6 * 33], s[7 * 33]);
;     *(u32x4v*)(WT + (size_t)(n0 + n) * K + k0 + 8 * c) = o; }
;   LDS_WAIT(); asm volatile("" ::: "memory");
; }
	ds_write2_b32 v31, v0, v56 offset1:66
	s_waitcnt vmcnt(28)
	ds_write2_b32 v31, v57, v58 offset0:132 offset1:198
	s_waitcnt vmcnt(26)
	ds_write2_b32 v37, v59, v60 offset0:8 offset1:74
	s_waitcnt vmcnt(24)
	ds_write2_b32 v37, v61, v62 offset0:140 offset1:206
	s_waitcnt vmcnt(22)
	ds_write2_b32 v38, v63, v64 offset0:16 offset1:82
	s_waitcnt vmcnt(20)
	ds_write2_b32 v38, v65, v66 offset0:148 offset1:214
	s_waitcnt vmcnt(18)
	ds_write2_b32 v39, v67, v68 offset0:24 offset1:90
	s_waitcnt vmcnt(16)
	ds_write2_b32 v39, v69, v70 offset0:156 offset1:222
	s_waitcnt vmcnt(14)
	ds_write2_b32 v40, v71, v72 offset0:32 offset1:98
	s_waitcnt vmcnt(12)
	ds_write2_b32 v40, v73, v74 offset0:164 offset1:230
	s_waitcnt vmcnt(10)
	ds_write2_b32 v41, v75, v76 offset0:40 offset1:106
	s_waitcnt vmcnt(8)
	ds_write2_b32 v41, v77, v78 offset0:172 offset1:238
	s_waitcnt vmcnt(6)
	ds_write2_b32 v42, v54, v55 offset0:48 offset1:114
	s_waitcnt vmcnt(4)
	ds_write2_b32 v42, v79, v80 offset0:180 offset1:246
	s_waitcnt vmcnt(2)
	ds_write2_b32 v43, v81, v82 offset0:56 offset1:122
	s_waitcnt vmcnt(0)
	ds_write2_b32 v43, v83, v84 offset0:188 offset1:254
	s_waitcnt lgkmcnt(0)
	ds_read2_b32 v[28:29], v33 offset0:33 offset1:41
	ds_read2_b32 v[44:45], v33 offset1:8
	ds_read2_b32 v[46:47], v33 offset0:66 offset1:74
	ds_read2_b32 v[48:49], v33 offset0:99 offset1:107
	ds_read2_b32 v[50:51], v33 offset0:132 offset1:140
	ds_read2_b32 v[52:53], v33 offset0:165 offset1:173
	ds_read2_b32 v[54:55], v33 offset0:198 offset1:206
	ds_read2_b32 v[56:57], v33 offset0:231 offset1:239
	v_lshlrev_b32_e32 v0, 1, v23
	v_lshl_add_u64 v[58:59], v[12:13], 0, v[0:1]
	v_or_b32_e32 v0, v22, v32
	v_lshlrev_b32_e32 v0, 11, v0
	s_waitcnt lgkmcnt(6)
	v_cvt_pk_bf16_f32 v24, v44, v28
	s_waitcnt lgkmcnt(4)
	v_cvt_pk_bf16_f32 v25, v46, v48
	s_waitcnt lgkmcnt(2)
	v_cvt_pk_bf16_f32 v26, v50, v52
	s_waitcnt lgkmcnt(0)
	v_cvt_pk_bf16_f32 v27, v54, v56
	v_lshl_add_u64 v[60:61], v[58:59], 0, v[0:1]
	global_store_dwordx4 v[60:61], v[24:27], off sc1
	v_or_b32_e32 v0, v22, v34
	v_lshlrev_b32_e32 v0, 11, v0
	v_cvt_pk_bf16_f32 v24, v45, v29
	v_cvt_pk_bf16_f32 v25, v47, v49
	v_cvt_pk_bf16_f32 v26, v51, v53
	v_cvt_pk_bf16_f32 v27, v55, v57
	ds_read2_b32 v[44:45], v33 offset0:49 offset1:57
	ds_read2_b32 v[46:47], v33 offset0:16 offset1:24
	ds_read2_b32 v[48:49], v33 offset0:82 offset1:90
	ds_read2_b32 v[50:51], v33 offset0:115 offset1:123
	ds_read2_b32 v[52:53], v33 offset0:148 offset1:156
	ds_read2_b32 v[54:55], v33 offset0:181 offset1:189
	ds_read2_b32 v[56:57], v33 offset0:214 offset1:222
	ds_read2_b32 v[60:61], v33 offset0:247 offset1:255
	v_lshl_add_u64 v[28:29], v[58:59], 0, v[0:1]
	v_or_b32_e32 v0, v22, v35
	v_lshlrev_b32_e32 v0, 11, v0
	global_store_dwordx4 v[28:29], v[24:27], off sc1
	v_lshl_add_u64 v[28:29], v[58:59], 0, v[0:1]
	v_or_b32_e32 v0, v22, v36
	s_waitcnt lgkmcnt(6)
	v_cvt_pk_bf16_f32 v24, v46, v44
	s_waitcnt lgkmcnt(4)
	v_cvt_pk_bf16_f32 v25, v48, v50
	s_waitcnt lgkmcnt(2)
	v_cvt_pk_bf16_f32 v26, v52, v54
	s_waitcnt lgkmcnt(0)
	v_cvt_pk_bf16_f32 v27, v56, v60
	v_lshlrev_b32_e32 v0, 11, v0
	global_store_dwordx4 v[28:29], v[24:27], off sc1
	v_lshl_add_u64 v[22:23], v[58:59], 0, v[0:1]
	s_nop 0
	v_cvt_pk_bf16_f32 v24, v47, v45
	v_cvt_pk_bf16_f32 v25, v49, v51
	v_cvt_pk_bf16_f32 v26, v53, v55
	v_cvt_pk_bf16_f32 v27, v57, v61
	global_store_dwordx4 v[22:23], v[24:27], off sc1
	s_waitcnt lgkmcnt(0)

; DI void transpose_item(const float* __restrict__ W, int K, int N, u16* __restrict__ WT, float* scr, int item, int lane, bool perm, bool pair_up = false) {
;   const int nblk = N / 32, kb = item / nblk, nb = item % nblk, k0 = 64 * kb, n0 = 32 * nb;
;   const int ns0 = pair_up ? (((n0 & 255) < 128) ? 128 * (n0 >> 8) + (n0 & 255) : FF + 128 * (n0 >> 8) + (n0 & 255) - 128) : n0;
;   float tv[32];
; #pragma unroll
;   for (int i = 0; i < 32; ++i) { const int kk = 2 * i + (lane >> 5); tv[i] = W[(size_t)(k0 + kk) * N + ns0 + (lane & 31)]; }
.LBB0_451:
	s_andn2_saveexec_b64 s[16:17], s[16:17]
	s_cbranch_execz .LBB0_453
	v_ashrrev_i32_e32 v0, 31, v23
	v_lshrrev_b32_e32 v0, 26, v0
	v_add_u32_e32 v0, v23, v0
	v_and_b32_e32 v24, 0xffffffc0, v0
	v_sub_u32_e32 v0, v23, v24
	v_lshlrev_b32_e32 v22, 5, v0
	v_or_b32_e32 v28, v24, v30
	v_ashrrev_i32_e32 v23, 31, v22
	v_ashrrev_i32_e32 v29, 31, v28
	v_or_b32_e32 v46, 2, v28
	v_or_b32_e32 v48, 4, v28
	v_or_b32_e32 v50, 6, v28
	v_or_b32_e32 v52, 8, v28
	v_or_b32_e32 v54, 10, v28
	v_or_b32_e32 v56, 12, v28
	v_or_b32_e32 v58, 14, v28
	v_lshl_add_u64 v[26:27], v[22:23], 2, v[14:15]
	v_lshlrev_b64 v[44:45], 13, v[28:29]
	v_ashrrev_i32_e32 v47, 31, v46
	v_ashrrev_i32_e32 v49, 31, v48
	v_ashrrev_i32_e32 v51, 31, v50
	v_ashrrev_i32_e32 v53, 31, v52
	v_ashrrev_i32_e32 v55, 31, v54
	v_ashrrev_i32_e32 v57, 31, v56
	v_ashrrev_i32_e32 v59, 31, v58
	v_lshl_add_u64 v[44:45], v[26:27], 0, v[44:45]
	v_lshlrev_b64 v[46:47], 13, v[46:47]
	v_lshlrev_b64 v[48:49], 13, v[48:49]
	v_lshlrev_b64 v[50:51], 13, v[50:51]
	v_lshlrev_b64 v[52:53], 13, v[52:53]
	v_lshlrev_b64 v[54:55], 13, v[54:55]
	v_lshlrev_b64 v[56:57], 13, v[56:57]
	v_lshlrev_b64 v[58:59], 13, v[58:59]
	v_lshl_add_u64 v[46:47], v[26:27], 0, v[46:47]
	v_lshl_add_u64 v[48:49], v[26:27], 0, v[48:49]
	v_lshl_add_u64 v[50:51], v[26:27], 0, v[50:51]
	v_lshl_add_u64 v[52:53], v[26:27], 0, v[52:53]
	v_lshl_add_u64 v[54:55], v[26:27], 0, v[54:55]
	v_lshl_add_u64 v[56:57], v[26:27], 0, v[56:57]
	v_lshl_add_u64 v[58:59], v[26:27], 0, v[58:59]
	global_load_dword v0, v[44:45], off
	global_load_dword v23, v[46:47], off
	global_load_dword v25, v[48:49], off
	global_load_dword v60, v[50:51], off
	global_load_dword v61, v[52:53], off
	global_load_dword v62, v[54:55], off
	global_load_dword v63, v[56:57], off
	global_load_dword v64, v[58:59], off
	v_or_b32_e32 v44, 16, v28
	v_ashrrev_i32_e32 v45, 31, v44
	v_or_b32_e32 v46, 18, v28
	v_or_b32_e32 v48, 20, v28
	v_or_b32_e32 v50, 22, v28
	v_or_b32_e32 v52, 24, v28
	v_or_b32_e32 v54, 26, v28
	v_or_b32_e32 v56, 28, v28
	v_or_b32_e32 v58, 30, v28
	v_lshlrev_b64 v[44:45], 13, v[44:45]
	v_ashrrev_i32_e32 v47, 31, v46
	v_ashrrev_i32_e32 v49, 31, v48
	v_ashrrev_i32_e32 v51, 31, v50
	v_ashrrev_i32_e32 v53, 31, v52
	v_ashrrev_i32_e32 v55, 31, v54
	v_ashrrev_i32_e32 v57, 31, v56
	v_ashrrev_i32_e32 v59, 31, v58
	v_lshl_add_u64 v[44:45], v[26:27], 0, v[44:45]
	v_lshlrev_b64 v[46:47], 13, v[46:47]
	v_lshlrev_b64 v[48:49], 13, v[48:49]
	v_lshlrev_b64 v[50:51], 13, v[50:51]
	v_lshlrev_b64 v[52:53], 13, v[52:53]
	v_lshlrev_b64 v[54:55], 13, v[54:55]
	v_lshlrev_b64 v[56:57], 13, v[56:57]
	v_lshlrev_b64 v[58:59], 13, v[58:59]
	v_lshl_add_u64 v[46:47], v[26:27], 0, v[46:47]
	v_lshl_add_u64 v[48:49], v[26:27], 0, v[48:49]
	v_lshl_add_u64 v[50:51], v[26:27], 0, v[50:51]
	v_lshl_add_u64 v[52:53], v[26:27], 0, v[52:53]
	v_lshl_add_u64 v[54:55], v[26:27], 0, v[54:55]
	v_lshl_add_u64 v[56:57], v[26:27], 0, v[56:57]
	v_lshl_add_u64 v[58:59], v[26:27], 0, v[58:59]
	global_load_dword v65, v[44:45], off
	global_load_dword v66, v[46:47], off
	global_load_dword v67, v[48:49], off
	global_load_dword v68, v[50:51], off
	global_load_dword v69, v[52:53], off
	global_load_dword v70, v[54:55], off
	global_load_dword v71, v[56:57], off
	global_load_dword v72, v[58:59], off
	v_or_b32_e32 v44, 32, v28
	v_ashrrev_i32_e32 v45, 31, v44
	v_or_b32_e32 v46, 34, v28
	v_or_b32_e32 v48, 36, v28
	v_or_b32_e32 v50, 38, v28
	v_or_b32_e32 v52, 40, v28
	v_or_b32_e32 v54, 42, v28
	v_or_b32_e32 v56, 44, v28
	v_or_b32_e32 v58, 46, v28
	v_lshlrev_b64 v[44:45], 13, v[44:45]
	v_ashrrev_i32_e32 v47, 31, v46
	v_ashrrev_i32_e32 v49, 31, v48
	v_ashrrev_i32_e32 v51, 31, v50
	v_ashrrev_i32_e32 v53, 31, v52
	v_ashrrev_i32_e32 v55, 31, v54
	v_ashrrev_i32_e32 v57, 31, v56
	v_ashrrev_i32_e32 v59, 31, v58
	v_lshl_add_u64 v[44:45], v[26:27], 0, v[44:45]
	v_lshlrev_b64 v[46:47], 13, v[46:47]
	v_lshlrev_b64 v[48:49], 13, v[48:49]
	v_lshlrev_b64 v[50:51], 13, v[50:51]
	v_lshlrev_b64 v[52:53], 13, v[52:53]
	v_lshlrev_b64 v[54:55], 13, v[54:55]
	v_lshlrev_b64 v[56:57], 13, v[56:57]
	v_lshlrev_b64 v[58:59], 13, v[58:59]
	v_lshl_add_u64 v[46:47], v[26:27], 0, v[46:47]
	v_lshl_add_u64 v[48:49], v[26:27], 0, v[48:49]
	v_lshl_add_u64 v[50:51], v[26:27], 0, v[50:51]
	v_lshl_add_u64 v[52:53], v[26:27], 0, v[52:53]
	v_lshl_add_u64 v[54:55], v[26:27], 0, v[54:55]
	v_lshl_add_u64 v[56:57], v[26:27], 0, v[56:57]
	v_lshl_add_u64 v[58:59], v[26:27], 0, v[58:59]
	global_load_dword v73, v[44:45], off
	global_load_dword v74, v[46:47], off
	global_load_dword v75, v[48:49], off
	global_load_dword v76, v[50:51], off
	global_load_dword v77, v[52:53], off
	global_load_dword v78, v[54:55], off
	global_load_dword v79, v[56:57], off
	global_load_dword v80, v[58:59], off
	v_or_b32_e32 v44, 48, v28
	v_ashrrev_i32_e32 v45, 31, v44
	v_or_b32_e32 v46, 50, v28
	v_or_b32_e32 v48, 52, v28
	v_or_b32_e32 v50, 54, v28
	v_or_b32_e32 v52, 56, v28
	v_or_b32_e32 v54, 58, v28
	v_or_b32_e32 v56, 60, v28
	v_or_b32_e32 v28, 62, v28
	v_lshlrev_b64 v[44:45], 13, v[44:45]
	v_ashrrev_i32_e32 v47, 31, v46
	v_ashrrev_i32_e32 v49, 31, v48
	v_ashrrev_i32_e32 v51, 31, v50
	v_ashrrev_i32_e32 v53, 31, v52
	v_ashrrev_i32_e32 v55, 31, v54
	v_ashrrev_i32_e32 v57, 31, v56
	v_ashrrev_i32_e32 v29, 31, v28
	v_lshl_add_u64 v[44:45], v[26:27], 0, v[44:45]
	v_lshlrev_b64 v[46:47], 13, v[46:47]
	v_lshlrev_b64 v[48:49], 13, v[48:49]
	v_lshlrev_b64 v[50:51], 13, v[50:51]
	v_lshlrev_b64 v[52:53], 13, v[52:53]
	v_lshlrev_b64 v[54:55], 13, v[54:55]
	v_lshlrev_b64 v[56:57], 13, v[56:57]
	v_lshlrev_b64 v[28:29], 13, v[28:29]
	v_lshl_add_u64 v[46:47], v[26:27], 0, v[46:47]
	v_lshl_add_u64 v[48:49], v[26:27], 0, v[48:49]
	v_lshl_add_u64 v[50:51], v[26:27], 0, v[50:51]
	v_lshl_add_u64 v[52:53], v[26:27], 0, v[52:53]
	v_lshl_add_u64 v[54:55], v[26:27], 0, v[54:55]
	v_lshl_add_u64 v[56:57], v[26:27], 0, v[56:57]
	v_lshl_add_u64 v[26:27], v[26:27], 0, v[28:29]
	global_load_dword v28, v[44:45], off
	global_load_dword v29, v[46:47], off
	global_load_dword v58, v[48:49], off
	global_load_dword v59, v[50:51], off
	global_load_dword v81, v[52:53], off
	global_load_dword v82, v[54:55], off
	global_load_dword v83, v[56:57], off
	global_load_dword v84, v[26:27], off
	s_waitcnt vmcnt(30)
; DI unsigned cvtpk(float lo, float hi) { f32x2 v = {lo, hi}; bf16x2_t b = __builtin_convertvector(v, bf16x2_t); return __builtin_bit_cast(unsigned, b); }
; #define LDS_WAIT() asm volatile("s_waitcnt lgkmcnt(0)" ::: "memory")
; DI void transpose_item(const float* __restrict__ W, int K, int N, u16* __restrict__ WT, float* scr, int item, int lane, bool perm, bool pair_up = false) {
;     ...
;   for (int i = 0; i < 32; ++i) { const int kk = 2 * i + (lane >> 5); scr[kk * 33 + (lane & 31)] = tv[i]; }
;   LDS_WAIT(); asm volatile("" ::: "memory");
;   const int c = lane & 7;
; #pragma unroll
;   for (int j = 0; j < 4; ++j) { const int n = (lane >> 3) + 8 * j; const float* s = scr + (8 * c) * 33 + (perm ? cperm(n) : n);
;     u32x4v o; o.x = cvtpk(s[0 * 33], s[1 * 33]); o.y = cvtpk(s[2 * 33], s[3 * 33]); o.z = cvtpk(s[4 * 33], s[5 * 33]); o.w = cvtpk(s[6 * 33], s[7 * 33]);
;     *(u32x4v*)(WT + (size_t)(n0 + n) * K + k0 + 8 * c) = o; }
;   LDS_WAIT(); asm volatile("" ::: "memory");
; }
	ds_write2_b32 v31, v0, v23 offset1:66
	s_waitcnt vmcnt(28)
	ds_write2_b32 v31, v25, v60 offset0:132 offset1:198
	s_waitcnt vmcnt(26)
	ds_write2_b32 v37, v61, v62 offset0:8 offset1:74
	s_waitcnt vmcnt(24)
	ds_write2_b32 v37, v63, v64 offset0:140 offset1:206
	s_waitcnt vmcnt(22)
	ds_write2_b32 v38, v65, v66 offset0:16 offset1:82
	s_waitcnt vmcnt(20)
	ds_write2_b32 v38, v67, v68 offset0:148 offset1:214
	s_waitcnt vmcnt(18)
	ds_write2_b32 v39, v69, v70 offset0:24 offset1:90
	s_waitcnt vmcnt(16)
	ds_write2_b32 v39, v71, v72 offset0:156 offset1:222
	s_waitcnt vmcnt(14)
	ds_write2_b32 v40, v73, v74 offset0:32 offset1:98
	s_waitcnt vmcnt(12)
	ds_write2_b32 v40, v75, v76 offset0:164 offset1:230
	s_waitcnt vmcnt(10)
	ds_write2_b32 v41, v77, v78 offset0:40 offset1:106
	s_waitcnt vmcnt(8)
	ds_write2_b32 v41, v79, v80 offset0:172 offset1:238
	s_waitcnt vmcnt(6)
	ds_write2_b32 v42, v28, v29 offset0:48 offset1:114
	s_waitcnt vmcnt(4)
	ds_write2_b32 v42, v58, v59 offset0:180 offset1:246
	s_waitcnt vmcnt(2)
	ds_write2_b32 v43, v81, v82 offset0:56 offset1:122
	s_waitcnt vmcnt(0)
	ds_write2_b32 v43, v83, v84 offset0:188 offset1:254
	s_waitcnt lgkmcnt(0)
	ds_read2_b32 v[28:29], v33 offset0:33 offset1:41
	ds_read2_b32 v[44:45], v33 offset1:8
	ds_read2_b32 v[46:47], v33 offset0:66 offset1:74
	ds_read2_b32 v[48:49], v33 offset0:99 offset1:107
	ds_read2_b32 v[50:51], v33 offset0:132 offset1:140
	ds_read2_b32 v[52:53], v33 offset0:165 offset1:173
	ds_read2_b32 v[54:55], v33 offset0:198 offset1:206
	ds_read2_b32 v[56:57], v33 offset0:231 offset1:239
	v_or_b32_e32 v60, v22, v32
	v_ashrrev_i32_e32 v25, 31, v24
	v_ashrrev_i32_e32 v61, 31, v60
	v_lshl_add_u64 v[58:59], v[24:25], 1, v[16:17]
	v_lshlrev_b64 v[60:61], 11, v[60:61]
	s_waitcnt lgkmcnt(6)
	v_cvt_pk_bf16_f32 v24, v44, v28
	s_waitcnt lgkmcnt(4)
	v_cvt_pk_bf16_f32 v25, v46, v48
	s_waitcnt lgkmcnt(2)
	v_cvt_pk_bf16_f32 v26, v50, v52
	s_waitcnt lgkmcnt(0)
	v_cvt_pk_bf16_f32 v27, v54, v56
	v_lshl_add_u64 v[60:61], v[58:59], 0, v[60:61]
	v_or_b32_e32 v28, v22, v34
	global_store_dwordx4 v[60:61], v[24:27], off sc1
	s_nop 1
	v_cvt_pk_bf16_f32 v24, v45, v29
	v_ashrrev_i32_e32 v29, 31, v28
	v_cvt_pk_bf16_f32 v25, v47, v49
	v_cvt_pk_bf16_f32 v26, v51, v53
	v_cvt_pk_bf16_f32 v27, v55, v57
	v_lshlrev_b64 v[28:29], 11, v[28:29]
	ds_read2_b32 v[44:45], v33 offset0:49 offset1:57
	ds_read2_b32 v[46:47], v33 offset0:16 offset1:24
	ds_read2_b32 v[48:49], v33 offset0:82 offset1:90
	ds_read2_b32 v[50:51], v33 offset0:115 offset1:123
	ds_read2_b32 v[52:53], v33 offset0:148 offset1:156
	ds_read2_b32 v[54:55], v33 offset0:181 offset1:189
	ds_read2_b32 v[56:57], v33 offset0:214 offset1:222
	ds_read2_b32 v[60:61], v33 offset0:247 offset1:255
	v_lshl_add_u64 v[28:29], v[58:59], 0, v[28:29]
	global_store_dwordx4 v[28:29], v[24:27], off sc1
	v_or_b32_e32 v28, v22, v35
	v_ashrrev_i32_e32 v29, 31, v28
	v_or_b32_e32 v22, v22, v36
	v_lshlrev_b64 v[28:29], 11, v[28:29]
	v_ashrrev_i32_e32 v23, 31, v22
	s_waitcnt lgkmcnt(6)
	v_cvt_pk_bf16_f32 v24, v46, v44
	s_waitcnt lgkmcnt(4)
	v_cvt_pk_bf16_f32 v25, v48, v50
	s_waitcnt lgkmcnt(2)
	v_cvt_pk_bf16_f32 v26, v52, v54
	s_waitcnt lgkmcnt(0)
	v_cvt_pk_bf16_f32 v27, v56, v60
	v_lshl_add_u64 v[28:29], v[58:59], 0, v[28:29]
	v_lshlrev_b64 v[22:23], 11, v[22:23]
	global_store_dwordx4 v[28:29], v[24:27], off sc1
	v_lshl_add_u64 v[22:23], v[58:59], 0, v[22:23]
	s_nop 0
	v_cvt_pk_bf16_f32 v24, v47, v45
	v_cvt_pk_bf16_f32 v25, v49, v51
	v_cvt_pk_bf16_f32 v26, v53, v55
	v_cvt_pk_bf16_f32 v27, v57, v61
	global_store_dwordx4 v[22:23], v[24:27], off sc1
	s_waitcnt lgkmcnt(0)

; DI void transpose_item(const float* __restrict__ W, int K, int N, u16* __restrict__ WT, float* scr, int item, int lane, bool perm, bool pair_up = false) {
;   const int nblk = N / 32, kb = item / nblk, nb = item % nblk, k0 = 64 * kb, n0 = 32 * nb;
;   const int ns0 = pair_up ? (((n0 & 255) < 128) ? 128 * (n0 >> 8) + (n0 & 255) : FF + 128 * (n0 >> 8) + (n0 & 255) - 128) : n0;
;   float tv[32];
; #pragma unroll
;   for (int i = 0; i < 32; ++i) { const int kk = 2 * i + (lane >> 5); tv[i] = W[(size_t)(k0 + kk) * N + ns0 + (lane & 31)]; }
.LBB0_454:
	s_andn2_saveexec_b64 s[14:15], s[14:15]
	s_cbranch_execz .LBB0_433
	v_add_u32_e32 v0, s0, v0
	v_mul_hi_i32 v22, v0, s24
	v_lshrrev_b32_e32 v23, 31, v22
	v_ashrrev_i32_e32 v22, 6, v22
	v_add_u32_e32 v23, v22, v23
	v_mul_i32_i24_e32 v22, 0x160, v23
	v_sub_u32_e32 v0, v0, v22
	v_lshlrev_b32_e32 v60, 5, v0
	v_lshlrev_b32_e32 v0, 4, v0
	v_and_b32_e32 v22, 0xe0, v60
	v_and_b32_e32 v0, 0xffffff80, v0
	v_or_b32_e32 v24, v0, v22
	v_add3_u32 v0, v0, v22, s26
	v_cmp_gt_u32_e32 vcc, s25, v22
	s_nop 1
	v_cndmask_b32_e32 v22, v0, v24, vcc
	v_lshlrev_b32_e32 v24, 6, v23
	v_or_b32_e32 v0, v24, v30
	v_ashrrev_i32_e32 v23, 31, v22
	v_lshl_add_u64 v[22:23], v[22:23], 2, v[18:19]
	v_or_b32_e32 v25, 2, v0
	v_mad_i64_i32 v[28:29], s[16:17], v25, s27, v[22:23]
	v_or_b32_e32 v25, 4, v0
	v_mad_i64_i32 v[44:45], s[16:17], v25, s27, v[22:23]
	v_or_b32_e32 v25, 6, v0
	v_mad_i64_i32 v[46:47], s[16:17], v25, s27, v[22:23]
	v_or_b32_e32 v25, 8, v0
	v_mad_i64_i32 v[48:49], s[16:17], v25, s27, v[22:23]
	v_or_b32_e32 v25, 10, v0
	v_mad_i64_i32 v[50:51], s[16:17], v25, s27, v[22:23]
	v_or_b32_e32 v25, 12, v0
	v_mad_i64_i32 v[26:27], s[16:17], v0, s27, v[22:23]
	v_mad_i64_i32 v[52:53], s[16:17], v25, s27, v[22:23]
	v_or_b32_e32 v25, 14, v0
	v_mad_i64_i32 v[54:55], s[16:17], v25, s27, v[22:23]
	global_load_dword v25, v[26:27], off
	global_load_dword v56, v[28:29], off
	global_load_dword v57, v[44:45], off
	global_load_dword v58, v[46:47], off
	global_load_dword v59, v[48:49], off
	global_load_dword v61, v[50:51], off
	global_load_dword v62, v[52:53], off
	global_load_dword v63, v[54:55], off
	v_or_b32_e32 v26, 16, v0
	v_mad_i64_i32 v[26:27], s[16:17], v26, s27, v[22:23]
	v_or_b32_e32 v28, 18, v0
	v_or_b32_e32 v44, 20, v0
	v_or_b32_e32 v46, 22, v0
	v_or_b32_e32 v48, 24, v0
	v_or_b32_e32 v50, 26, v0
	v_or_b32_e32 v52, 28, v0
	v_or_b32_e32 v54, 30, v0
	v_mad_i64_i32 v[28:29], s[16:17], v28, s27, v[22:23]
	v_mad_i64_i32 v[44:45], s[16:17], v44, s27, v[22:23]
	v_mad_i64_i32 v[46:47], s[16:17], v46, s27, v[22:23]
	v_mad_i64_i32 v[48:49], s[16:17], v48, s27, v[22:23]
	v_mad_i64_i32 v[50:51], s[16:17], v50, s27, v[22:23]
	v_mad_i64_i32 v[52:53], s[16:17], v52, s27, v[22:23]
	v_mad_i64_i32 v[54:55], s[16:17], v54, s27, v[22:23]
	global_load_dword v64, v[26:27], off
	global_load_dword v65, v[28:29], off
	global_load_dword v66, v[44:45], off
	global_load_dword v67, v[46:47], off
	global_load_dword v68, v[48:49], off
	global_load_dword v69, v[50:51], off
	global_load_dword v70, v[52:53], off
	global_load_dword v71, v[54:55], off
	v_or_b32_e32 v26, 32, v0
	v_mad_i64_i32 v[26:27], s[16:17], v26, s27, v[22:23]
	v_or_b32_e32 v28, 34, v0
	v_or_b32_e32 v44, 36, v0
	v_or_b32_e32 v46, 38, v0
	v_or_b32_e32 v48, 40, v0
	v_or_b32_e32 v50, 42, v0
	v_or_b32_e32 v52, 44, v0
	v_or_b32_e32 v54, 46, v0
	v_mad_i64_i32 v[28:29], s[16:17], v28, s27, v[22:23]
	v_mad_i64_i32 v[44:45], s[16:17], v44, s27, v[22:23]
	v_mad_i64_i32 v[46:47], s[16:17], v46, s27, v[22:23]
	v_mad_i64_i32 v[48:49], s[16:17], v48, s27, v[22:23]
	v_mad_i64_i32 v[50:51], s[16:17], v50, s27, v[22:23]
	v_mad_i64_i32 v[52:53], s[16:17], v52, s27, v[22:23]
	v_mad_i64_i32 v[54:55], s[16:17], v54, s27, v[22:23]
	global_load_dword v72, v[26:27], off
	global_load_dword v73, v[28:29], off
	global_load_dword v74, v[44:45], off
	global_load_dword v75, v[46:47], off
	global_load_dword v76, v[48:49], off
	global_load_dword v77, v[50:51], off
	global_load_dword v78, v[52:53], off
	global_load_dword v79, v[54:55], off
	v_or_b32_e32 v26, 48, v0
	v_mad_i64_i32 v[26:27], s[16:17], v26, s27, v[22:23]
	v_or_b32_e32 v28, 50, v0
	v_or_b32_e32 v44, 52, v0
	v_or_b32_e32 v46, 54, v0
	v_or_b32_e32 v48, 56, v0
	v_or_b32_e32 v50, 58, v0
	v_or_b32_e32 v52, 60, v0
	v_or_b32_e32 v0, 62, v0
	v_mad_i64_i32 v[28:29], s[16:17], v28, s27, v[22:23]
	v_mad_i64_i32 v[44:45], s[16:17], v44, s27, v[22:23]
	v_mad_i64_i32 v[46:47], s[16:17], v46, s27, v[22:23]
	v_mad_i64_i32 v[48:49], s[16:17], v48, s27, v[22:23]
	v_mad_i64_i32 v[50:51], s[16:17], v50, s27, v[22:23]
	v_mad_i64_i32 v[52:53], s[16:17], v52, s27, v[22:23]
	v_mad_i64_i32 v[22:23], s[16:17], v0, s27, v[22:23]
	global_load_dword v0, v[26:27], off
	global_load_dword v54, v[28:29], off
	global_load_dword v55, v[44:45], off
	global_load_dword v80, v[46:47], off
	global_load_dword v81, v[48:49], off
	global_load_dword v82, v[50:51], off
	global_load_dword v83, v[52:53], off
	global_load_dword v84, v[22:23], off
	s_waitcnt vmcnt(30)
; DI unsigned cvtpk(float lo, float hi) { f32x2 v = {lo, hi}; bf16x2_t b = __builtin_convertvector(v, bf16x2_t); return __builtin_bit_cast(unsigned, b); }
; #define LDS_WAIT() asm volatile("s_waitcnt lgkmcnt(0)" ::: "memory")
; DI void transpose_item(const float* __restrict__ W, int K, int N, u16* __restrict__ WT, float* scr, int item, int lane, bool perm, bool pair_up = false) {
;     ...
;   for (int i = 0; i < 32; ++i) { const int kk = 2 * i + (lane >> 5); scr[kk * 33 + (lane & 31)] = tv[i]; }
;   LDS_WAIT(); asm volatile("" ::: "memory");
;   const int c = lane & 7;
; #pragma unroll
;   for (int j = 0; j < 4; ++j) { const int n = (lane >> 3) + 8 * j; const float* s = scr + (8 * c) * 33 + (perm ? cperm(n) : n);
;     u32x4v o; o.x = cvtpk(s[0 * 33], s[1 * 33]); o.y = cvtpk(s[2 * 33], s[3 * 33]); o.z = cvtpk(s[4 * 33], s[5 * 33]); o.w = cvtpk(s[6 * 33], s[7 * 33]);
;     *(u32x4v*)(WT + (size_t)(n0 + n) * K + k0 + 8 * c) = o; }
;   LDS_WAIT(); asm volatile("" ::: "memory");
; }
	ds_write2_b32 v31, v25, v56 offset1:66
	s_waitcnt vmcnt(28)
	ds_write2_b32 v31, v57, v58 offset0:132 offset1:198
	s_waitcnt vmcnt(26)
	ds_write2_b32 v37, v59, v61 offset0:8 offset1:74
	s_waitcnt vmcnt(24)
	ds_write2_b32 v37, v62, v63 offset0:140 offset1:206
	s_waitcnt vmcnt(22)
	ds_write2_b32 v38, v64, v65 offset0:16 offset1:82
	s_waitcnt vmcnt(20)
	ds_write2_b32 v38, v66, v67 offset0:148 offset1:214
	s_waitcnt vmcnt(18)
	ds_write2_b32 v39, v68, v69 offset0:24 offset1:90
	s_waitcnt vmcnt(16)
	ds_write2_b32 v39, v70, v71 offset0:156 offset1:222
	s_waitcnt vmcnt(14)
	ds_write2_b32 v40, v72, v73 offset0:32 offset1:98
	s_waitcnt vmcnt(12)
	ds_write2_b32 v40, v74, v75 offset0:164 offset1:230
	s_waitcnt vmcnt(10)
	ds_write2_b32 v41, v76, v77 offset0:40 offset1:106
	s_waitcnt vmcnt(8)
	ds_write2_b32 v41, v78, v79 offset0:172 offset1:238
	s_waitcnt vmcnt(6)
	ds_write2_b32 v42, v0, v54 offset0:48 offset1:114
	s_waitcnt vmcnt(4)
	ds_write2_b32 v42, v55, v80 offset0:180 offset1:246
	s_waitcnt vmcnt(2)
	ds_write2_b32 v43, v81, v82 offset0:56 offset1:122
	s_waitcnt vmcnt(0)
	ds_write2_b32 v43, v83, v84 offset0:188 offset1:254
	s_waitcnt lgkmcnt(0)
	ds_read2_b32 v[26:27], v33 offset0:33 offset1:41
	ds_read2_b32 v[28:29], v33 offset1:8
	ds_read2_b32 v[44:45], v33 offset0:66 offset1:74
	ds_read2_b32 v[46:47], v33 offset0:99 offset1:107
	ds_read2_b32 v[48:49], v33 offset0:132 offset1:140
	ds_read2_b32 v[50:51], v33 offset0:165 offset1:173
	ds_read2_b32 v[52:53], v33 offset0:198 offset1:206
	ds_read2_b32 v[54:55], v33 offset0:231 offset1:239
	v_or_b32_e32 v58, v60, v32
	v_ashrrev_i32_e32 v25, 31, v24
	v_ashrrev_i32_e32 v59, 31, v58
	v_lshl_add_u64 v[56:57], v[24:25], 1, v[20:21]
	v_lshlrev_b64 v[58:59], 12, v[58:59]
	s_waitcnt lgkmcnt(6)
	v_cvt_pk_bf16_f32 v22, v28, v26
	s_waitcnt lgkmcnt(4)
	v_cvt_pk_bf16_f32 v23, v44, v46
	s_waitcnt lgkmcnt(2)
	v_cvt_pk_bf16_f32 v24, v48, v50
	s_waitcnt lgkmcnt(0)
	v_cvt_pk_bf16_f32 v25, v52, v54
	v_lshl_add_u64 v[58:59], v[56:57], 0, v[58:59]
	v_or_b32_e32 v26, v60, v34
	global_store_dwordx4 v[58:59], v[22:25], off sc1
	s_nop 1
	v_cvt_pk_bf16_f32 v22, v29, v27
	v_ashrrev_i32_e32 v27, 31, v26
	v_cvt_pk_bf16_f32 v23, v45, v47
	v_cvt_pk_bf16_f32 v24, v49, v51
	v_cvt_pk_bf16_f32 v25, v53, v55
	v_lshlrev_b64 v[26:27], 12, v[26:27]
	ds_read2_b32 v[28:29], v33 offset0:49 offset1:57
	ds_read2_b32 v[44:45], v33 offset0:16 offset1:24
	ds_read2_b32 v[46:47], v33 offset0:82 offset1:90
	ds_read2_b32 v[48:49], v33 offset0:115 offset1:123
	ds_read2_b32 v[50:51], v33 offset0:148 offset1:156
	ds_read2_b32 v[52:53], v33 offset0:181 offset1:189
	ds_read2_b32 v[54:55], v33 offset0:214 offset1:222
	ds_read2_b32 v[58:59], v33 offset0:247 offset1:255
	v_lshl_add_u64 v[26:27], v[56:57], 0, v[26:27]
	global_store_dwordx4 v[26:27], v[22:25], off sc1
	v_or_b32_e32 v26, v60, v35
	v_ashrrev_i32_e32 v27, 31, v26
	v_lshlrev_b64 v[26:27], 12, v[26:27]
	s_waitcnt lgkmcnt(6)
	v_cvt_pk_bf16_f32 v22, v44, v28
	s_waitcnt lgkmcnt(4)
	v_cvt_pk_bf16_f32 v23, v46, v48
	s_waitcnt lgkmcnt(2)
	v_cvt_pk_bf16_f32 v24, v50, v52
	s_waitcnt lgkmcnt(0)
	v_cvt_pk_bf16_f32 v25, v54, v58
	v_lshl_add_u64 v[26:27], v[56:57], 0, v[26:27]
	global_store_dwordx4 v[26:27], v[22:25], off sc1
	v_or_b32_e32 v26, v60, v36
	v_ashrrev_i32_e32 v27, 31, v26
	v_lshlrev_b64 v[26:27], 12, v[26:27]
	v_cvt_pk_bf16_f32 v22, v45, v29
	v_cvt_pk_bf16_f32 v23, v47, v49
	v_cvt_pk_bf16_f32 v24, v51, v53
	v_cvt_pk_bf16_f32 v25, v55, v59
	v_lshl_add_u64 v[26:27], v[56:57], 0, v[26:27]
	global_store_dwordx4 v[26:27], v[22:25], off sc1
	s_waitcnt lgkmcnt(0)
	s_branch .LBB0_433

; DI unsigned cvtpk(float lo, float hi) { f32x2 v = {lo, hi}; bf16x2_t b = __builtin_convertvector(v, bf16x2_t); return __builtin_bit_cast(unsigned, b); }
; DI float bflo(unsigned w) { return __uint_as_float(w << 16); }
; DI float bfhi(unsigned w) { return __uint_as_float(w & 0xffff0000u); }
;     __device__ __forceinline__ void operator()(const f32x4 (&acc)[2][2][4][2], const Unit& u, int wr, int wc, int fr, int fq) const {
;         const int row0 = u.pm * BM + wr * 64 + fr, col0 = u.pn * BM + wc * 32 + 8 * fq;
; #pragma unroll
;         for (int ai = 0; ai < 2; ++ai)
; #pragma unroll
;             for (int m = 0; m < 4; ++m) { const size_t r = (size_t)(row0 + ai * HALF + m * 16);
; #pragma unroll
;                 for (int bj = 0; bj < 2; ++bj) { const int c = col0 + bj * HALF;
;                     const u32x4 g = *(const u32x4*)(GATES + r * 4096 + 2048 + c);
;                     const u32x4 t = *(const u32x4*)(T + r * 2048 + c);
;                     const f32x4 v0 = acc[ai][bj][m][0], v1 = acc[ai][bj][m][1];
;                     u32x4 w; w.x = cvtpk(bflo(t.x) + v0[0] * bflo(g.x), bfhi(t.x) + v0[1] * bfhi(g.x)); w.y = cvtpk(bflo(t.y) + v0[2] * bflo(g.y), bfhi(t.y) + v0[3] * bfhi(g.y));
;                     w.z = cvtpk(bflo(t.z) + v1[0] * bflo(g.z), bfhi(t.z) + v1[1] * bfhi(g.z)); w.w = cvtpk(bflo(t.w) + v1[2] * bflo(g.w), bfhi(t.w) + v1[3] * bfhi(g.w));
;                     *(u32x4*)(Y + r * 2048 + c) = w; } }
;     }
.LBB0_544:
	v_lshl_add_u32 v148, s36, 8, v150
	v_ashrrev_i32_e32 v149, 31, v148
	v_lshl_or_b32 v146, s51, 8, v152
	v_lshlrev_b64 v[170:171], 13, v[148:149]
	v_ashrrev_i32_e32 v147, 31, v146
	v_lshlrev_b64 v[160:161], 12, v[148:149]
	v_lshl_add_u64 v[170:171], s[8:9], 0, v[170:171]
	v_lshlrev_b64 v[144:145], 1, v[146:147]
	v_lshl_add_u64 v[156:157], s[16:17], 0, v[160:161]
	v_lshl_add_u64 v[176:177], v[170:171], 0, s[24:25]
	v_lshl_add_u64 v[174:175], v[156:157], 0, v[144:145]
	v_lshl_add_u64 v[170:171], v[176:177], 0, v[144:145]
	global_load_dwordx4 v[156:159], v[174:175], off
	v_or_b32_e32 v146, 0x80, v146
	global_load_dwordx4 v[170:173], v[170:171], off
	v_ashrrev_i32_e32 v147, 31, v146
	v_lshl_add_u64 v[160:161], s[10:11], 0, v[160:161]
	v_lshlrev_b64 v[146:147], 1, v[146:147]
	v_lshl_add_u64 v[160:161], v[160:161], 0, v[144:145]
	v_lshl_add_u64 v[178:179], v[176:177], 0, v[146:147]
	global_load_dwordx4 v[174:177], v[174:175], off offset:256
	s_andn2_b64 vcc, exec, s[6:7]
	s_mov_b64 s[6:7], -1
	s_waitcnt vmcnt(0)
	v_lshlrev_b32_e32 v180, 16, v156
	v_and_b32_e32 v181, 0xffff0000, v156
	v_lshlrev_b32_e32 v156, 16, v157
	v_and_b32_e32 v157, 0xffff0000, v157
	v_lshlrev_b32_e32 v182, 16, v158
	v_and_b32_e32 v183, 0xffff0000, v158
	v_lshlrev_b32_e32 v158, 16, v159
	v_and_b32_e32 v159, 0xffff0000, v159
	v_lshlrev_b32_e32 v184, 16, v170
	v_and_b32_e32 v185, 0xffff0000, v170
	v_lshlrev_b32_e32 v170, 16, v171
	v_and_b32_e32 v171, 0xffff0000, v171
	v_lshlrev_b32_e32 v186, 16, v172
	v_and_b32_e32 v187, 0xffff0000, v172
	v_lshlrev_b32_e32 v172, 16, v173
	v_and_b32_e32 v173, 0xffff0000, v173
	v_pk_fma_f32 v[124:125], v[124:125], v[184:185], v[180:181]
	v_pk_fma_f32 v[126:127], v[126:127], v[170:171], v[156:157]
	v_pk_fma_f32 v[156:157], v[120:121], v[186:187], v[182:183]
	v_pk_fma_f32 v[158:159], v[122:123], v[172:173], v[158:159]
	v_cvt_pk_bf16_f32 v120, v124, v125
	v_cvt_pk_bf16_f32 v121, v126, v127
	v_cvt_pk_bf16_f32 v122, v156, v157
	v_cvt_pk_bf16_f32 v123, v158, v159
	global_store_dwordx4 v[160:161], v[120:123], off sc1
	global_load_dwordx4 v[120:123], v[178:179], off
	v_or_b32_e32 v124, 16, v148
	v_ashrrev_i32_e32 v125, 31, v124
	v_lshlrev_b64 v[126:127], 13, v[124:125]
	v_lshlrev_b32_e32 v178, 16, v174
	v_and_b32_e32 v179, 0xffff0000, v174
	v_lshlrev_b32_e32 v174, 16, v175
	v_and_b32_e32 v175, 0xffff0000, v175
	v_lshlrev_b32_e32 v180, 16, v176
	v_and_b32_e32 v181, 0xffff0000, v176
	v_lshlrev_b32_e32 v176, 16, v177
	v_and_b32_e32 v177, 0xffff0000, v177
	v_lshlrev_b64 v[156:157], 12, v[124:125]
	v_lshl_add_u64 v[124:125], s[8:9], 0, v[126:127]
	v_lshl_add_u64 v[126:127], s[16:17], 0, v[156:157]
	v_lshl_add_u64 v[158:159], v[124:125], 0, s[24:25]
	v_lshl_add_u64 v[170:171], v[126:127], 0, v[144:145]
	v_lshl_add_u64 v[172:173], v[158:159], 0, v[144:145]
	global_load_dwordx4 v[124:127], v[170:171], off
	s_waitcnt vmcnt(1)
	v_lshlrev_b32_e32 v182, 16, v120
	v_and_b32_e32 v183, 0xffff0000, v120
	v_lshlrev_b32_e32 v120, 16, v121
	v_and_b32_e32 v121, 0xffff0000, v121
	v_lshlrev_b32_e32 v184, 16, v122
	v_and_b32_e32 v185, 0xffff0000, v122
	v_lshlrev_b32_e32 v122, 16, v123
	v_and_b32_e32 v123, 0xffff0000, v123
	v_pk_fma_f32 v[116:117], v[116:117], v[182:183], v[178:179]
	v_pk_fma_f32 v[118:119], v[118:119], v[120:121], v[174:175]
	v_pk_fma_f32 v[120:121], v[112:113], v[184:185], v[180:181]
	v_pk_fma_f32 v[122:123], v[114:115], v[122:123], v[176:177]
	v_cvt_pk_bf16_f32 v112, v116, v117
	v_cvt_pk_bf16_f32 v113, v118, v119
	v_cvt_pk_bf16_f32 v114, v120, v121
	v_cvt_pk_bf16_f32 v115, v122, v123
	global_store_dwordx4 v[160:161], v[112:115], off offset:256 sc1
	global_load_dwordx4 v[112:115], v[172:173], off
	v_lshl_add_u64 v[116:117], s[10:11], 0, v[156:157]
	v_lshl_add_u64 v[120:121], v[116:117], 0, v[144:145]
	v_lshl_add_u64 v[122:123], v[158:159], 0, v[146:147]
	global_load_dwordx4 v[116:119], v[170:171], off offset:256
	s_waitcnt vmcnt(3)
	v_lshlrev_b32_e32 v156, 16, v124
	v_and_b32_e32 v157, 0xffff0000, v124
	v_lshlrev_b32_e32 v124, 16, v125
	v_and_b32_e32 v125, 0xffff0000, v125
	v_lshlrev_b32_e32 v158, 16, v126
	v_and_b32_e32 v159, 0xffff0000, v126
	v_lshlrev_b32_e32 v126, 16, v127
	v_and_b32_e32 v127, 0xffff0000, v127
	s_waitcnt vmcnt(1)
	v_lshlrev_b32_e32 v160, 16, v112
	v_and_b32_e32 v161, 0xffff0000, v112
	v_lshlrev_b32_e32 v112, 16, v113
	v_and_b32_e32 v113, 0xffff0000, v113
	v_lshlrev_b32_e32 v170, 16, v114
	v_and_b32_e32 v171, 0xffff0000, v114
	v_lshlrev_b32_e32 v114, 16, v115
	v_and_b32_e32 v115, 0xffff0000, v115
	v_pk_fma_f32 v[108:109], v[108:109], v[160:161], v[156:157]
	v_pk_fma_f32 v[110:111], v[110:111], v[112:113], v[124:125]
	v_pk_fma_f32 v[112:113], v[104:105], v[170:171], v[158:159]
	v_pk_fma_f32 v[114:115], v[106:107], v[114:115], v[126:127]
	v_cvt_pk_bf16_f32 v104, v108, v109
	v_cvt_pk_bf16_f32 v105, v110, v111
	v_cvt_pk_bf16_f32 v106, v112, v113
	v_cvt_pk_bf16_f32 v107, v114, v115
	global_store_dwordx4 v[120:121], v[104:107], off sc1
	global_load_dwordx4 v[104:107], v[122:123], off
	v_or_b32_e32 v108, 32, v148
	v_ashrrev_i32_e32 v109, 31, v108
	v_lshlrev_b64 v[110:111], 13, v[108:109]
	s_waitcnt vmcnt(2)
	v_lshlrev_b32_e32 v126, 16, v116
	v_and_b32_e32 v127, 0xffff0000, v116
	v_lshlrev_b32_e32 v116, 16, v117
	v_and_b32_e32 v117, 0xffff0000, v117
	v_lshlrev_b32_e32 v156, 16, v118
	v_and_b32_e32 v157, 0xffff0000, v118
	v_lshlrev_b32_e32 v118, 16, v119
	v_and_b32_e32 v119, 0xffff0000, v119
	v_lshlrev_b64 v[112:113], 12, v[108:109]
	v_lshl_add_u64 v[108:109], s[8:9], 0, v[110:111]
	v_lshl_add_u64 v[110:111], s[16:17], 0, v[112:113]
	v_lshl_add_u64 v[114:115], v[108:109], 0, s[24:25]
	v_lshl_add_u64 v[122:123], v[110:111], 0, v[144:145]
	v_lshl_add_u64 v[124:125], v[114:115], 0, v[144:145]
	global_load_dwordx4 v[108:111], v[122:123], off
	s_waitcnt vmcnt(1)
; DI unsigned cvtpk(float lo, float hi) { f32x2 v = {lo, hi}; bf16x2_t b = __builtin_convertvector(v, bf16x2_t); return __builtin_bit_cast(unsigned, b); }
; DI float bflo(unsigned w) { return __uint_as_float(w << 16); }
; DI float bfhi(unsigned w) { return __uint_as_float(w & 0xffff0000u); }
;     __device__ __forceinline__ void operator()(const f32x4 (&acc)[2][2][4][2], const Unit& u, int wr, int wc, int fr, int fq) const {
;     ...
;             for (int m = 0; m < 4; ++m) { const size_t r = (size_t)(row0 + ai * HALF + m * 16);
; #pragma unroll
;                 for (int bj = 0; bj < 2; ++bj) { const int c = col0 + bj * HALF;
;                     const u32x4 g = *(const u32x4*)(GATES + r * 4096 + 2048 + c);
;                     const u32x4 t = *(const u32x4*)(T + r * 2048 + c);
;                     const f32x4 v0 = acc[ai][bj][m][0], v1 = acc[ai][bj][m][1];
;                     u32x4 w; w.x = cvtpk(bflo(t.x) + v0[0] * bflo(g.x), bfhi(t.x) + v0[1] * bfhi(g.x)); w.y = cvtpk(bflo(t.y) + v0[2] * bflo(g.y), bfhi(t.y) + v0[3] * bfhi(g.y));
;                     w.z = cvtpk(bflo(t.z) + v1[0] * bflo(g.z), bfhi(t.z) + v1[1] * bfhi(g.z)); w.w = cvtpk(bflo(t.w) + v1[2] * bflo(g.w), bfhi(t.w) + v1[3] * bfhi(g.w));
;                     *(u32x4*)(Y + r * 2048 + c) = w; } }
	v_lshlrev_b32_e32 v158, 16, v104
	v_and_b32_e32 v159, 0xffff0000, v104
	v_lshlrev_b32_e32 v104, 16, v105
	v_and_b32_e32 v105, 0xffff0000, v105
	v_lshlrev_b32_e32 v160, 16, v106
	v_and_b32_e32 v161, 0xffff0000, v106
	v_lshlrev_b32_e32 v106, 16, v107
	v_and_b32_e32 v107, 0xffff0000, v107
	v_pk_fma_f32 v[100:101], v[100:101], v[158:159], v[126:127]
	v_pk_fma_f32 v[102:103], v[102:103], v[104:105], v[116:117]
	v_pk_fma_f32 v[104:105], v[96:97], v[160:161], v[156:157]
	v_pk_fma_f32 v[106:107], v[98:99], v[106:107], v[118:119]
	v_cvt_pk_bf16_f32 v96, v100, v101
	v_cvt_pk_bf16_f32 v97, v102, v103
	v_cvt_pk_bf16_f32 v98, v104, v105
	v_cvt_pk_bf16_f32 v99, v106, v107
	global_store_dwordx4 v[120:121], v[96:99], off offset:256 sc1
	global_load_dwordx4 v[96:99], v[124:125], off
	v_lshl_add_u64 v[100:101], s[10:11], 0, v[112:113]
	v_lshl_add_u64 v[104:105], v[100:101], 0, v[144:145]
	v_lshl_add_u64 v[106:107], v[114:115], 0, v[146:147]
	global_load_dwordx4 v[100:103], v[122:123], off offset:256
	s_waitcnt vmcnt(3)
	v_lshlrev_b32_e32 v112, 16, v108
	v_and_b32_e32 v113, 0xffff0000, v108
	v_lshlrev_b32_e32 v108, 16, v109
	v_and_b32_e32 v109, 0xffff0000, v109
	v_lshlrev_b32_e32 v114, 16, v110
	v_and_b32_e32 v115, 0xffff0000, v110
	v_lshlrev_b32_e32 v110, 16, v111
	v_and_b32_e32 v111, 0xffff0000, v111
	s_waitcnt vmcnt(1)
	v_lshlrev_b32_e32 v116, 16, v96
	v_and_b32_e32 v117, 0xffff0000, v96
	v_lshlrev_b32_e32 v96, 16, v97
	v_and_b32_e32 v97, 0xffff0000, v97
	v_lshlrev_b32_e32 v118, 16, v98
	v_and_b32_e32 v119, 0xffff0000, v98
	v_lshlrev_b32_e32 v98, 16, v99
	v_and_b32_e32 v99, 0xffff0000, v99
	v_pk_fma_f32 v[92:93], v[92:93], v[116:117], v[112:113]
	v_pk_fma_f32 v[94:95], v[94:95], v[96:97], v[108:109]
	v_pk_fma_f32 v[96:97], v[88:89], v[118:119], v[114:115]
	v_pk_fma_f32 v[98:99], v[90:91], v[98:99], v[110:111]
	v_cvt_pk_bf16_f32 v88, v92, v93
	v_cvt_pk_bf16_f32 v89, v94, v95
	v_cvt_pk_bf16_f32 v90, v96, v97
	v_cvt_pk_bf16_f32 v91, v98, v99
	global_store_dwordx4 v[104:105], v[88:91], off sc1
	global_load_dwordx4 v[88:91], v[106:107], off
	v_or_b32_e32 v92, 48, v148
	v_ashrrev_i32_e32 v93, 31, v92
	v_lshlrev_b64 v[94:95], 13, v[92:93]
	s_waitcnt vmcnt(2)
	v_lshlrev_b32_e32 v110, 16, v100
	v_and_b32_e32 v111, 0xffff0000, v100
	v_lshlrev_b32_e32 v100, 16, v101
	v_and_b32_e32 v101, 0xffff0000, v101
	v_lshlrev_b32_e32 v112, 16, v102
	v_and_b32_e32 v113, 0xffff0000, v102
	v_lshlrev_b32_e32 v102, 16, v103
	v_and_b32_e32 v103, 0xffff0000, v103
	v_lshlrev_b64 v[96:97], 12, v[92:93]
	v_lshl_add_u64 v[92:93], s[8:9], 0, v[94:95]
	v_lshl_add_u64 v[94:95], s[16:17], 0, v[96:97]
	v_lshl_add_u64 v[98:99], v[92:93], 0, s[24:25]
	v_lshl_add_u64 v[106:107], v[94:95], 0, v[144:145]
	v_lshl_add_u64 v[108:109], v[98:99], 0, v[144:145]
	global_load_dwordx4 v[92:95], v[106:107], off
	s_waitcnt vmcnt(1)
	v_lshlrev_b32_e32 v114, 16, v88
	v_and_b32_e32 v115, 0xffff0000, v88
	v_lshlrev_b32_e32 v88, 16, v89
	v_and_b32_e32 v89, 0xffff0000, v89
	v_lshlrev_b32_e32 v116, 16, v90
	v_and_b32_e32 v117, 0xffff0000, v90
	v_lshlrev_b32_e32 v90, 16, v91
	v_and_b32_e32 v91, 0xffff0000, v91
	v_pk_fma_f32 v[84:85], v[84:85], v[114:115], v[110:111]
	v_pk_fma_f32 v[86:87], v[86:87], v[88:89], v[100:101]
	v_pk_fma_f32 v[88:89], v[80:81], v[116:117], v[112:113]
	v_pk_fma_f32 v[90:91], v[82:83], v[90:91], v[102:103]
	v_cvt_pk_bf16_f32 v80, v84, v85
	v_cvt_pk_bf16_f32 v81, v86, v87
	v_cvt_pk_bf16_f32 v82, v88, v89
	v_cvt_pk_bf16_f32 v83, v90, v91
	global_store_dwordx4 v[104:105], v[80:83], off offset:256 sc1
	global_load_dwordx4 v[80:83], v[108:109], off
	v_lshl_add_u64 v[84:85], s[10:11], 0, v[96:97]
	v_lshl_add_u64 v[88:89], v[84:85], 0, v[144:145]
	v_lshl_add_u64 v[90:91], v[98:99], 0, v[146:147]
	global_load_dwordx4 v[84:87], v[106:107], off offset:256
	s_waitcnt vmcnt(3)
	v_lshlrev_b32_e32 v96, 16, v92
	v_and_b32_e32 v97, 0xffff0000, v92
	v_lshlrev_b32_e32 v92, 16, v93
	v_and_b32_e32 v93, 0xffff0000, v93
	v_lshlrev_b32_e32 v98, 16, v94
	v_and_b32_e32 v99, 0xffff0000, v94
	v_lshlrev_b32_e32 v94, 16, v95
	v_and_b32_e32 v95, 0xffff0000, v95
	s_waitcnt vmcnt(1)
	v_lshlrev_b32_e32 v100, 16, v80
	v_and_b32_e32 v101, 0xffff0000, v80
	v_lshlrev_b32_e32 v80, 16, v81
	v_and_b32_e32 v81, 0xffff0000, v81
	v_lshlrev_b32_e32 v102, 16, v82
	v_and_b32_e32 v103, 0xffff0000, v82
	v_lshlrev_b32_e32 v82, 16, v83
	v_and_b32_e32 v83, 0xffff0000, v83
	v_pk_fma_f32 v[76:77], v[76:77], v[100:101], v[96:97]
	v_pk_fma_f32 v[78:79], v[78:79], v[80:81], v[92:93]
	v_pk_fma_f32 v[80:81], v[72:73], v[102:103], v[98:99]
	v_pk_fma_f32 v[82:83], v[74:75], v[82:83], v[94:95]
	v_cvt_pk_bf16_f32 v72, v76, v77
	v_cvt_pk_bf16_f32 v73, v78, v79
	v_cvt_pk_bf16_f32 v74, v80, v81
	v_cvt_pk_bf16_f32 v75, v82, v83
	global_store_dwordx4 v[88:89], v[72:75], off sc1
	global_load_dwordx4 v[72:75], v[90:91], off
	v_add_u32_e32 v76, 0x80, v148
	v_ashrrev_i32_e32 v77, 31, v76
	v_lshlrev_b64 v[78:79], 13, v[76:77]
	s_waitcnt vmcnt(2)
	v_lshlrev_b32_e32 v94, 16, v84
	v_and_b32_e32 v95, 0xffff0000, v84
	v_lshlrev_b32_e32 v84, 16, v85
	v_and_b32_e32 v85, 0xffff0000, v85
	v_lshlrev_b32_e32 v96, 16, v86
	v_and_b32_e32 v97, 0xffff0000, v86
	v_lshlrev_b32_e32 v86, 16, v87
	v_and_b32_e32 v87, 0xffff0000, v87
	v_lshlrev_b64 v[80:81], 12, v[76:77]
	v_lshl_add_u64 v[76:77], s[8:9], 0, v[78:79]
	v_lshl_add_u64 v[78:79], s[16:17], 0, v[80:81]
	v_lshl_add_u64 v[82:83], v[76:77], 0, s[24:25]
	v_lshl_add_u64 v[90:91], v[78:79], 0, v[144:145]
	v_lshl_add_u64 v[92:93], v[82:83], 0, v[144:145]
	global_load_dwordx4 v[76:79], v[90:91], off
	s_waitcnt vmcnt(1)
; DI unsigned cvtpk(float lo, float hi) { f32x2 v = {lo, hi}; bf16x2_t b = __builtin_convertvector(v, bf16x2_t); return __builtin_bit_cast(unsigned, b); }
; DI float bflo(unsigned w) { return __uint_as_float(w << 16); }
; DI float bfhi(unsigned w) { return __uint_as_float(w & 0xffff0000u); }
;     __device__ __forceinline__ void operator()(const f32x4 (&acc)[2][2][4][2], const Unit& u, int wr, int wc, int fr, int fq) const {
;     ...
;             for (int m = 0; m < 4; ++m) { const size_t r = (size_t)(row0 + ai * HALF + m * 16);
; #pragma unroll
;                 for (int bj = 0; bj < 2; ++bj) { const int c = col0 + bj * HALF;
;                     const u32x4 g = *(const u32x4*)(GATES + r * 4096 + 2048 + c);
;                     const u32x4 t = *(const u32x4*)(T + r * 2048 + c);
;                     const f32x4 v0 = acc[ai][bj][m][0], v1 = acc[ai][bj][m][1];
;                     u32x4 w; w.x = cvtpk(bflo(t.x) + v0[0] * bflo(g.x), bfhi(t.x) + v0[1] * bfhi(g.x)); w.y = cvtpk(bflo(t.y) + v0[2] * bflo(g.y), bfhi(t.y) + v0[3] * bfhi(g.y));
;                     w.z = cvtpk(bflo(t.z) + v1[0] * bflo(g.z), bfhi(t.z) + v1[1] * bfhi(g.z)); w.w = cvtpk(bflo(t.w) + v1[2] * bflo(g.w), bfhi(t.w) + v1[3] * bfhi(g.w));
;                     *(u32x4*)(Y + r * 2048 + c) = w; } }
	v_lshlrev_b32_e32 v98, 16, v72
	v_and_b32_e32 v99, 0xffff0000, v72
	v_lshlrev_b32_e32 v72, 16, v73
	v_and_b32_e32 v73, 0xffff0000, v73
	v_lshlrev_b32_e32 v100, 16, v74
	v_and_b32_e32 v101, 0xffff0000, v74
	v_lshlrev_b32_e32 v74, 16, v75
	v_and_b32_e32 v75, 0xffff0000, v75
	v_pk_fma_f32 v[68:69], v[68:69], v[98:99], v[94:95]
	v_pk_fma_f32 v[70:71], v[70:71], v[72:73], v[84:85]
	v_pk_fma_f32 v[72:73], v[64:65], v[100:101], v[96:97]
	v_pk_fma_f32 v[74:75], v[66:67], v[74:75], v[86:87]
	v_cvt_pk_bf16_f32 v64, v68, v69
	v_cvt_pk_bf16_f32 v65, v70, v71
	v_cvt_pk_bf16_f32 v66, v72, v73
	v_cvt_pk_bf16_f32 v67, v74, v75
	global_store_dwordx4 v[88:89], v[64:67], off offset:256 sc1
	global_load_dwordx4 v[64:67], v[92:93], off
	v_lshl_add_u64 v[68:69], s[10:11], 0, v[80:81]
	v_lshl_add_u64 v[72:73], v[68:69], 0, v[144:145]
	v_lshl_add_u64 v[74:75], v[82:83], 0, v[146:147]
	global_load_dwordx4 v[68:71], v[90:91], off offset:256
	s_waitcnt vmcnt(3)
	v_lshlrev_b32_e32 v80, 16, v76
	v_and_b32_e32 v81, 0xffff0000, v76
	v_lshlrev_b32_e32 v76, 16, v77
	v_and_b32_e32 v77, 0xffff0000, v77
	v_lshlrev_b32_e32 v82, 16, v78
	v_and_b32_e32 v83, 0xffff0000, v78
	v_lshlrev_b32_e32 v78, 16, v79
	v_and_b32_e32 v79, 0xffff0000, v79
	s_waitcnt vmcnt(1)
	v_lshlrev_b32_e32 v84, 16, v64
	v_and_b32_e32 v85, 0xffff0000, v64
	v_lshlrev_b32_e32 v64, 16, v65
	v_and_b32_e32 v65, 0xffff0000, v65
	v_lshlrev_b32_e32 v86, 16, v66
	v_and_b32_e32 v87, 0xffff0000, v66
	v_lshlrev_b32_e32 v66, 16, v67
	v_and_b32_e32 v67, 0xffff0000, v67
	v_pk_fma_f32 v[60:61], v[60:61], v[84:85], v[80:81]
	v_pk_fma_f32 v[62:63], v[62:63], v[64:65], v[76:77]
	v_pk_fma_f32 v[64:65], v[56:57], v[86:87], v[82:83]
	v_pk_fma_f32 v[66:67], v[58:59], v[66:67], v[78:79]
	v_cvt_pk_bf16_f32 v56, v60, v61
	v_cvt_pk_bf16_f32 v57, v62, v63
	v_cvt_pk_bf16_f32 v58, v64, v65
	v_cvt_pk_bf16_f32 v59, v66, v67
	global_store_dwordx4 v[72:73], v[56:59], off sc1
	global_load_dwordx4 v[56:59], v[74:75], off
	v_add_u32_e32 v60, 0x90, v148
	v_ashrrev_i32_e32 v61, 31, v60
	v_lshlrev_b64 v[62:63], 13, v[60:61]
	s_waitcnt vmcnt(2)
	v_lshlrev_b32_e32 v78, 16, v68
	v_and_b32_e32 v79, 0xffff0000, v68
	v_lshlrev_b32_e32 v68, 16, v69
	v_and_b32_e32 v69, 0xffff0000, v69
	v_lshlrev_b32_e32 v80, 16, v70
	v_and_b32_e32 v81, 0xffff0000, v70
	v_lshlrev_b32_e32 v70, 16, v71
	v_and_b32_e32 v71, 0xffff0000, v71
	v_lshlrev_b64 v[64:65], 12, v[60:61]
	v_lshl_add_u64 v[60:61], s[8:9], 0, v[62:63]
	v_lshl_add_u64 v[62:63], s[16:17], 0, v[64:65]
	v_lshl_add_u64 v[66:67], v[60:61], 0, s[24:25]
	v_lshl_add_u64 v[74:75], v[62:63], 0, v[144:145]
	v_lshl_add_u64 v[76:77], v[66:67], 0, v[144:145]
	global_load_dwordx4 v[60:63], v[74:75], off
	s_waitcnt vmcnt(1)
	v_lshlrev_b32_e32 v82, 16, v56
	v_and_b32_e32 v83, 0xffff0000, v56
	v_lshlrev_b32_e32 v56, 16, v57
	v_and_b32_e32 v57, 0xffff0000, v57
	v_lshlrev_b32_e32 v84, 16, v58
	v_and_b32_e32 v85, 0xffff0000, v58
	v_lshlrev_b32_e32 v58, 16, v59
	v_and_b32_e32 v59, 0xffff0000, v59
	v_pk_fma_f32 v[52:53], v[52:53], v[82:83], v[78:79]
	v_pk_fma_f32 v[54:55], v[54:55], v[56:57], v[68:69]
	v_pk_fma_f32 v[56:57], v[48:49], v[84:85], v[80:81]
	v_pk_fma_f32 v[58:59], v[50:51], v[58:59], v[70:71]
	v_cvt_pk_bf16_f32 v48, v52, v53
	v_cvt_pk_bf16_f32 v49, v54, v55
	v_cvt_pk_bf16_f32 v50, v56, v57
	v_cvt_pk_bf16_f32 v51, v58, v59
	global_store_dwordx4 v[72:73], v[48:51], off offset:256 sc1
	global_load_dwordx4 v[48:51], v[76:77], off
	v_lshl_add_u64 v[52:53], s[10:11], 0, v[64:65]
	v_lshl_add_u64 v[56:57], v[52:53], 0, v[144:145]
	v_lshl_add_u64 v[58:59], v[66:67], 0, v[146:147]
	global_load_dwordx4 v[52:55], v[74:75], off offset:256
	s_waitcnt vmcnt(3)
	v_lshlrev_b32_e32 v64, 16, v60
	v_and_b32_e32 v65, 0xffff0000, v60
	v_lshlrev_b32_e32 v60, 16, v61
	v_and_b32_e32 v61, 0xffff0000, v61
	v_lshlrev_b32_e32 v66, 16, v62
	v_and_b32_e32 v67, 0xffff0000, v62
	v_lshlrev_b32_e32 v62, 16, v63
	v_and_b32_e32 v63, 0xffff0000, v63
	s_waitcnt vmcnt(1)
	v_lshlrev_b32_e32 v68, 16, v48
	v_and_b32_e32 v69, 0xffff0000, v48
	v_lshlrev_b32_e32 v48, 16, v49
	v_and_b32_e32 v49, 0xffff0000, v49
	v_lshlrev_b32_e32 v70, 16, v50
	v_and_b32_e32 v71, 0xffff0000, v50
	v_lshlrev_b32_e32 v50, 16, v51
	v_and_b32_e32 v51, 0xffff0000, v51
	v_pk_fma_f32 v[44:45], v[44:45], v[68:69], v[64:65]
	v_pk_fma_f32 v[46:47], v[46:47], v[48:49], v[60:61]
	v_pk_fma_f32 v[48:49], v[40:41], v[70:71], v[66:67]
	v_pk_fma_f32 v[50:51], v[42:43], v[50:51], v[62:63]
	v_cvt_pk_bf16_f32 v40, v44, v45
	v_cvt_pk_bf16_f32 v41, v46, v47
	v_cvt_pk_bf16_f32 v42, v48, v49
	v_cvt_pk_bf16_f32 v43, v50, v51
	global_store_dwordx4 v[56:57], v[40:43], off sc1
	global_load_dwordx4 v[40:43], v[58:59], off
	v_add_u32_e32 v44, 0xa0, v148
	v_ashrrev_i32_e32 v45, 31, v44
	v_lshlrev_b64 v[46:47], 13, v[44:45]
	s_waitcnt vmcnt(2)
	v_lshlrev_b32_e32 v62, 16, v52
	v_and_b32_e32 v63, 0xffff0000, v52
	v_lshlrev_b32_e32 v52, 16, v53
	v_and_b32_e32 v53, 0xffff0000, v53
	v_lshlrev_b32_e32 v64, 16, v54
	v_and_b32_e32 v65, 0xffff0000, v54
	v_lshlrev_b32_e32 v54, 16, v55
	v_and_b32_e32 v55, 0xffff0000, v55
	v_lshlrev_b64 v[48:49], 12, v[44:45]
	v_lshl_add_u64 v[44:45], s[8:9], 0, v[46:47]
	v_lshl_add_u64 v[46:47], s[16:17], 0, v[48:49]
	v_lshl_add_u64 v[50:51], v[44:45], 0, s[24:25]
	v_lshl_add_u64 v[58:59], v[46:47], 0, v[144:145]
	v_lshl_add_u64 v[60:61], v[50:51], 0, v[144:145]
	global_load_dwordx4 v[44:47], v[58:59], off
	s_waitcnt vmcnt(1)
; template <class Epi, class Sched, bool ALIGN_EPI = false, bool SP2 = false>
; __device__ __forceinline__ void gemm_phase(PG8_LAS unsigned char* lds, const Gemm g, const Sched& S, const Epi& E) {
;     ...
;         for (int t = 0; t < nt; t += 2) {
;             const bool last = (t == nt - 2);
;             const char* a1 = cA + (size_t)(t + 1) * kstep;
;             const char* a2 = last ? nA : cA + (size_t)(t + 2) * kstep; const char* b2 = last ? nB : cB + (size_t)(t + 2) * kstep;
;             const char* a3 = a2 + kstep; const char* b3 = b2 + kstep;
;             if (last && has_next) S.a_ready(nxt);
;             if constexpr (SP2) {
;             PG8_LDB(B0, 0, 0); PG8_LDB(B1, 0, 1); PG8_SCHED; PG8_LDA(At, 0, 0); PG8_STAGE(PG8_SA(1, 1), a1 + hstepA, voffA);
;             PG8_WAIT_V(8); PG8_WAIT_L(0); PG8_BAR; PG8_MMA(0, 0, At, B0); PG8_MMA(0, 1, At, B1); PG8_BAR; PG8_SCHED;
;             PG8_LDA(At, 0, 1); PG8_STAGE(PG8_SB(0, 0), b2, voffB); PG8_STAGE(PG8_SB(0, 1), b2 + hstepB, voffB); PG8_STAGE(PG8_SA(0, 0), a2, voffA);
;             PG8_WAIT_V(8); PG8_WAIT_L(0); PG8_BAR; PG8_MMA(1, 0, At, B0); PG8_MMA(1, 1, At, B1); PG8_BAR; PG8_SCHED;
;             PG8_LDB(B0, 1, 0); PG8_LDB(B1, 1, 1); PG8_SCHED; PG8_LDA(At, 1, 0); PG8_STAGE(PG8_SA(0, 1), a2 + hstepA, voffA);
;             PG8_WAIT_V(8); PG8_WAIT_L(0); PG8_BAR; PG8_MMA(0, 0, At, B0); PG8_MMA(0, 1, At, B1); PG8_BAR; PG8_SCHED;
;     __device__ __forceinline__ void operator()(const f32x4 (&acc)[2][2][4][2], const Unit& u, int wr, int wc, int fr, int fq) const {
;     ...
;             for (int m = 0; m < 4; ++m) { const size_t r = (size_t)(row0 + ai * HALF + m * 16);
; #pragma unroll
;                 for (int bj = 0; bj < 2; ++bj) { const int c = col0 + bj * HALF;
;                     const u32x4 g = *(const u32x4*)(GATES + r * 4096 + 2048 + c);
;                     const u32x4 t = *(const u32x4*)(T + r * 2048 + c);
;                     const f32x4 v0 = acc[ai][bj][m][0], v1 = acc[ai][bj][m][1];
;                     u32x4 w; w.x = cvtpk(bflo(t.x) + v0[0] * bflo(g.x), bfhi(t.x) + v0[1] * bfhi(g.x)); w.y = cvtpk(bflo(t.y) + v0[2] * bflo(g.y), bfhi(t.y) + v0[3] * bfhi(g.y));
;                     w.z = cvtpk(bflo(t.z) + v1[0] * bflo(g.z), bfhi(t.z) + v1[1] * bfhi(g.z)); w.w = cvtpk(bflo(t.w) + v1[2] * bflo(g.w), bfhi(t.w) + v1[3] * bfhi(g.w));
;                     *(u32x4*)(Y + r * 2048 + c) = w; } }
	v_lshlrev_b32_e32 v66, 16, v40
	v_and_b32_e32 v67, 0xffff0000, v40
	v_lshlrev_b32_e32 v40, 16, v41
	v_and_b32_e32 v41, 0xffff0000, v41
	v_lshlrev_b32_e32 v68, 16, v42
	v_and_b32_e32 v69, 0xffff0000, v42
	v_lshlrev_b32_e32 v42, 16, v43
	v_and_b32_e32 v43, 0xffff0000, v43
	v_pk_fma_f32 v[36:37], v[36:37], v[66:67], v[62:63]
	v_pk_fma_f32 v[38:39], v[38:39], v[40:41], v[52:53]
	v_pk_fma_f32 v[40:41], v[32:33], v[68:69], v[64:65]
	v_pk_fma_f32 v[42:43], v[34:35], v[42:43], v[54:55]
	v_cvt_pk_bf16_f32 v32, v36, v37
	v_cvt_pk_bf16_f32 v33, v38, v39
	v_cvt_pk_bf16_f32 v34, v40, v41
	v_cvt_pk_bf16_f32 v35, v42, v43
	global_store_dwordx4 v[56:57], v[32:35], off offset:256 sc1
	global_load_dwordx4 v[32:35], v[60:61], off
	v_lshl_add_u64 v[36:37], s[10:11], 0, v[48:49]
	v_lshl_add_u64 v[40:41], v[36:37], 0, v[144:145]
	v_lshl_add_u64 v[42:43], v[50:51], 0, v[146:147]
	global_load_dwordx4 v[36:39], v[58:59], off offset:256
	s_waitcnt vmcnt(3)
	v_lshlrev_b32_e32 v48, 16, v44
	v_and_b32_e32 v49, 0xffff0000, v44
	v_lshlrev_b32_e32 v44, 16, v45
	v_and_b32_e32 v45, 0xffff0000, v45
	v_lshlrev_b32_e32 v50, 16, v46
	v_and_b32_e32 v51, 0xffff0000, v46
	v_lshlrev_b32_e32 v46, 16, v47
	v_and_b32_e32 v47, 0xffff0000, v47
	s_waitcnt vmcnt(1)
	v_lshlrev_b32_e32 v52, 16, v32
	v_and_b32_e32 v53, 0xffff0000, v32
	v_lshlrev_b32_e32 v32, 16, v33
	v_and_b32_e32 v33, 0xffff0000, v33
	v_lshlrev_b32_e32 v54, 16, v34
	v_and_b32_e32 v55, 0xffff0000, v34
	v_lshlrev_b32_e32 v34, 16, v35
	v_and_b32_e32 v35, 0xffff0000, v35
	v_pk_fma_f32 v[28:29], v[28:29], v[52:53], v[48:49]
	v_pk_fma_f32 v[30:31], v[30:31], v[32:33], v[44:45]
	v_pk_fma_f32 v[32:33], v[24:25], v[54:55], v[50:51]
	v_pk_fma_f32 v[34:35], v[26:27], v[34:35], v[46:47]
	v_cvt_pk_bf16_f32 v24, v28, v29
	v_cvt_pk_bf16_f32 v25, v30, v31
	v_cvt_pk_bf16_f32 v26, v32, v33
	v_cvt_pk_bf16_f32 v27, v34, v35
	global_store_dwordx4 v[40:41], v[24:27], off sc1
	global_load_dwordx4 v[24:27], v[42:43], off
	v_add_u32_e32 v28, 0xb0, v148
	v_ashrrev_i32_e32 v29, 31, v28
	v_lshlrev_b64 v[30:31], 13, v[28:29]
	s_waitcnt vmcnt(2)
	v_lshlrev_b32_e32 v46, 16, v36
	v_and_b32_e32 v47, 0xffff0000, v36
	v_lshlrev_b32_e32 v36, 16, v37
	v_and_b32_e32 v37, 0xffff0000, v37
	v_lshlrev_b32_e32 v48, 16, v38
	v_and_b32_e32 v49, 0xffff0000, v38
	v_lshlrev_b32_e32 v38, 16, v39
	v_and_b32_e32 v39, 0xffff0000, v39
	v_lshlrev_b64 v[32:33], 12, v[28:29]
	v_lshl_add_u64 v[28:29], s[8:9], 0, v[30:31]
	v_lshl_add_u64 v[30:31], s[16:17], 0, v[32:33]
	v_lshl_add_u64 v[34:35], v[28:29], 0, s[24:25]
	v_lshl_add_u64 v[42:43], v[30:31], 0, v[144:145]
	v_lshl_add_u64 v[44:45], v[34:35], 0, v[144:145]
	global_load_dwordx4 v[28:31], v[42:43], off
	s_waitcnt vmcnt(1)
	v_lshlrev_b32_e32 v50, 16, v24
	v_and_b32_e32 v51, 0xffff0000, v24
	v_lshlrev_b32_e32 v24, 16, v25
	v_and_b32_e32 v25, 0xffff0000, v25
	v_lshlrev_b32_e32 v52, 16, v26
	v_and_b32_e32 v53, 0xffff0000, v26
	v_lshlrev_b32_e32 v26, 16, v27
	v_and_b32_e32 v27, 0xffff0000, v27
	v_pk_fma_f32 v[20:21], v[20:21], v[50:51], v[46:47]
	v_pk_fma_f32 v[22:23], v[22:23], v[24:25], v[36:37]
	v_pk_fma_f32 v[24:25], v[16:17], v[52:53], v[48:49]
	v_pk_fma_f32 v[26:27], v[18:19], v[26:27], v[38:39]
	v_cvt_pk_bf16_f32 v16, v20, v21
	v_cvt_pk_bf16_f32 v17, v22, v23
	v_cvt_pk_bf16_f32 v18, v24, v25
	v_cvt_pk_bf16_f32 v19, v26, v27
	global_store_dwordx4 v[40:41], v[16:19], off offset:256 sc1
	global_load_dwordx4 v[16:19], v[44:45], off
	v_lshl_add_u64 v[20:21], s[10:11], 0, v[32:33]
	v_lshl_add_u64 v[24:25], v[20:21], 0, v[144:145]
	v_lshl_add_u64 v[26:27], v[34:35], 0, v[146:147]
	global_load_dwordx4 v[20:23], v[42:43], off offset:256
	s_waitcnt vmcnt(3)
	v_lshlrev_b32_e32 v32, 16, v28
	v_and_b32_e32 v33, 0xffff0000, v28
	v_lshlrev_b32_e32 v28, 16, v29
	v_and_b32_e32 v29, 0xffff0000, v29
	v_lshlrev_b32_e32 v34, 16, v30
	v_and_b32_e32 v35, 0xffff0000, v30
	v_lshlrev_b32_e32 v30, 16, v31
	v_and_b32_e32 v31, 0xffff0000, v31
	s_waitcnt vmcnt(1)
	v_lshlrev_b32_e32 v36, 16, v16
	v_and_b32_e32 v37, 0xffff0000, v16
	v_lshlrev_b32_e32 v16, 16, v17
	v_and_b32_e32 v17, 0xffff0000, v17
	v_lshlrev_b32_e32 v38, 16, v18
	v_and_b32_e32 v39, 0xffff0000, v18
	v_lshlrev_b32_e32 v18, 16, v19
	v_and_b32_e32 v19, 0xffff0000, v19
	v_pk_fma_f32 v[12:13], v[12:13], v[36:37], v[32:33]
	v_pk_fma_f32 v[14:15], v[14:15], v[16:17], v[28:29]
	v_pk_fma_f32 v[16:17], v[8:9], v[38:39], v[34:35]
	v_pk_fma_f32 v[18:19], v[10:11], v[18:19], v[30:31]
	v_cvt_pk_bf16_f32 v8, v12, v13
	v_cvt_pk_bf16_f32 v9, v14, v15
	v_cvt_pk_bf16_f32 v10, v16, v17
	v_cvt_pk_bf16_f32 v11, v18, v19
	global_store_dwordx4 v[24:25], v[8:11], off sc1
	global_load_dwordx4 v[8:11], v[26:27], off
	s_waitcnt vmcnt(2)
	v_lshlrev_b32_e32 v12, 16, v20
	v_and_b32_e32 v13, 0xffff0000, v20
	v_lshlrev_b32_e32 v14, 16, v21
	v_and_b32_e32 v15, 0xffff0000, v21
	v_lshlrev_b32_e32 v16, 16, v22
	v_and_b32_e32 v17, 0xffff0000, v22
	v_lshlrev_b32_e32 v18, 16, v23
	v_and_b32_e32 v19, 0xffff0000, v23
	s_waitcnt vmcnt(0)
	v_lshlrev_b32_e32 v20, 16, v8
	v_and_b32_e32 v21, 0xffff0000, v8
	v_lshlrev_b32_e32 v8, 16, v9
	v_and_b32_e32 v9, 0xffff0000, v9
	v_lshlrev_b32_e32 v22, 16, v10
	v_and_b32_e32 v23, 0xffff0000, v10
	v_lshlrev_b32_e32 v10, 16, v11
	v_and_b32_e32 v11, 0xffff0000, v11
	v_pk_fma_f32 v[4:5], v[4:5], v[20:21], v[12:13]
	v_pk_fma_f32 v[6:7], v[6:7], v[8:9], v[14:15]
	v_pk_fma_f32 v[8:9], v[0:1], v[22:23], v[16:17]
	v_pk_fma_f32 v[10:11], v[2:3], v[10:11], v[18:19]
	v_cvt_pk_bf16_f32 v0, v4, v5
	v_cvt_pk_bf16_f32 v1, v6, v7
	v_cvt_pk_bf16_f32 v2, v8, v9
	v_cvt_pk_bf16_f32 v3, v10, v11
	global_store_dwordx4 v[24:25], v[0:3], off offset:256 sc1
	s_cbranch_vccnz .LBB0_533
	s_andn2_b64 vcc, exec, s[18:19]
	s_cbranch_vccnz .LBB0_532
	s_barrier
	s_branch .LBB0_532

;     __device__ __forceinline__ void operator()(const f32x4 (&acc)[2][2][4][2], const Unit& u, int wr, int wc, int fr, int fq) const {
;         const int row0 = u.pm * BM + wr * 64 + fr, col0 = u.pn * BM + wc * 32 + 4 * fq;
;         const float* gb = gate + (size_t)(u.pm >> 3) * NIN;
;         f32x4 gv[2][2];
; #pragma unroll
;         for (int bj = 0; bj < 2; ++bj)
; #pragma unroll
;             for (int n = 0; n < 2; ++n) gv[bj][n] = *(const f32x4*)(gb + col0 + bj * HALF + n * 16);
; #pragma unroll
;         for (int ai = 0; ai < 2; ++ai)
; #pragma unroll
;             for (int m = 0; m < 4; ++m) { const size_t off = (size_t)(row0 + ai * HALF + m * 16) * 2048 + col0;
; #pragma unroll
;                 for (int bj = 0; bj < 2; ++bj)
; #pragma unroll
;                     for (int n = 0; n < 2; ++n) { const f32x4 bs = *(const f32x4*)(base + off + bj * HALF + n * 16);
;                         *(f32x4*)(out + off + bj * HALF + n * 16) = bs + gv[bj][n] * acc[ai][bj][m][n]; } }
;     }
.LBB0_616:
	v_lshl_add_u32 v178, s38, 8, v158
	v_lshl_or_b32 v176, s55, 8, v160
	s_ashr_i32 s29, s38, 3
	v_ashrrev_i32_e32 v179, 31, v178
	s_mul_hi_i32 s31, s29, 0xc000
	s_mul_i32 s29, s29, 0xc000
	v_ashrrev_i32_e32 v177, 31, v176
	v_lshlrev_b64 v[130:131], 11, v[178:179]
	s_add_u32 s40, s50, s29
	v_lshl_add_u64 v[130:131], v[130:131], 0, v[176:177]
	s_addc_u32 s41, s51, s31
	v_lshlrev_b64 v[156:157], 2, v[130:131]
	v_lshl_add_u64 v[128:129], v[176:177], 2, s[40:41]
	global_load_dwordx4 v[140:143], v[128:129], off
	global_load_dwordx4 v[136:139], v[128:129], off offset:64
	global_load_dwordx4 v[132:135], v[128:129], off offset:512
	s_nop 0
	global_load_dwordx4 v[128:131], v[128:129], off offset:576
	v_add_u32_e32 v192, 0x20000, v156
	v_add_u32_e32 v193, 0x40000, v156
	v_add_u32_e32 v224, 0x60000, v156
	v_add_u32_e32 v225, 0x100000, v156
	v_add_u32_e32 v226, 0x120000, v156
	v_add_u32_e32 v227, 0x140000, v156
	v_add_u32_e32 v228, 0x160000, v156
	s_andn2_b64 vcc, exec, s[4:5]
	s_mov_b64 s[4:5], -1
	global_load_dwordx4 v[172:175], v156, s[6:7]
	global_load_dwordx4 v[176:179], v156, s[6:7] offset:64
	global_load_dwordx4 v[180:183], v156, s[6:7] offset:512
	global_load_dwordx4 v[184:187], v156, s[6:7] offset:576
	global_load_dwordx4 v[188:191], v192, s[6:7]
	global_load_dwordx4 v[196:199], v192, s[6:7] offset:64
	global_load_dwordx4 v[200:203], v192, s[6:7] offset:512
	global_load_dwordx4 v[204:207], v192, s[6:7] offset:576
	global_load_dwordx4 v[208:211], v193, s[6:7]
	global_load_dwordx4 v[212:215], v193, s[6:7] offset:64
	global_load_dwordx4 v[216:219], v193, s[6:7] offset:512
	global_load_dwordx4 v[220:223], v193, s[6:7] offset:576
	s_waitcnt vmcnt(11)
	v_pk_fma_f32 v[126:127], v[126:127], v[142:143], v[174:175]
	v_pk_fma_f32 v[124:125], v[124:125], v[140:141], v[172:173]
	global_store_dwordx4 v156, v[124:127], s[8:9] sc1
	s_waitcnt vmcnt(11)
	v_pk_fma_f32 v[122:123], v[122:123], v[138:139], v[178:179]
	v_pk_fma_f32 v[120:121], v[120:121], v[136:137], v[176:177]
	global_store_dwordx4 v156, v[120:123], s[8:9] offset:64 sc1
	s_waitcnt vmcnt(11)
	v_pk_fma_f32 v[118:119], v[118:119], v[134:135], v[182:183]
	v_pk_fma_f32 v[116:117], v[116:117], v[132:133], v[180:181]
	global_store_dwordx4 v156, v[116:119], s[8:9] offset:512 sc1
	s_waitcnt vmcnt(11)
	v_pk_fma_f32 v[106:107], v[106:107], v[130:131], v[186:187]
	v_pk_fma_f32 v[104:105], v[104:105], v[128:129], v[184:185]
	global_store_dwordx4 v156, v[104:107], s[8:9] offset:576 sc1
	global_load_dwordx4 v[172:175], v224, s[6:7]
	global_load_dwordx4 v[176:179], v224, s[6:7] offset:64
	global_load_dwordx4 v[180:183], v224, s[6:7] offset:512
	global_load_dwordx4 v[184:187], v224, s[6:7] offset:576
	global_load_dwordx4 v[124:127], v225, s[6:7]
	global_load_dwordx4 v[120:123], v225, s[6:7] offset:64
	global_load_dwordx4 v[116:119], v225, s[6:7] offset:512
	global_load_dwordx4 v[104:107], v225, s[6:7] offset:576
	s_waitcnt vmcnt(19)
	v_pk_fma_f32 v[114:115], v[114:115], v[142:143], v[190:191]
	v_pk_fma_f32 v[112:113], v[112:113], v[140:141], v[188:189]
	global_store_dwordx4 v192, v[112:115], s[8:9] sc1
	s_waitcnt vmcnt(19)
	v_pk_fma_f32 v[110:111], v[110:111], v[138:139], v[198:199]
	v_pk_fma_f32 v[108:109], v[108:109], v[136:137], v[196:197]
	global_store_dwordx4 v192, v[108:111], s[8:9] offset:64 sc1
	s_waitcnt vmcnt(19)
	v_pk_fma_f32 v[102:103], v[102:103], v[134:135], v[202:203]
	v_pk_fma_f32 v[100:101], v[100:101], v[132:133], v[200:201]
	global_store_dwordx4 v192, v[100:103], s[8:9] offset:512 sc1
	s_waitcnt vmcnt(19)
	v_pk_fma_f32 v[90:91], v[90:91], v[130:131], v[206:207]
	v_pk_fma_f32 v[88:89], v[88:89], v[128:129], v[204:205]
	global_store_dwordx4 v192, v[88:91], s[8:9] offset:576 sc1
	global_load_dwordx4 v[188:191], v226, s[6:7]
	global_load_dwordx4 v[196:199], v226, s[6:7] offset:64
	global_load_dwordx4 v[200:203], v226, s[6:7] offset:512
	global_load_dwordx4 v[204:207], v226, s[6:7] offset:576
	global_load_dwordx4 v[112:115], v227, s[6:7]
	global_load_dwordx4 v[108:111], v227, s[6:7] offset:64
	global_load_dwordx4 v[100:103], v227, s[6:7] offset:512
	global_load_dwordx4 v[88:91], v227, s[6:7] offset:576
	s_waitcnt vmcnt(27)
	v_pk_fma_f32 v[98:99], v[98:99], v[142:143], v[210:211]
	v_pk_fma_f32 v[96:97], v[96:97], v[140:141], v[208:209]
	global_store_dwordx4 v193, v[96:99], s[8:9] sc1
	s_waitcnt vmcnt(27)
	v_pk_fma_f32 v[94:95], v[94:95], v[138:139], v[214:215]
	v_pk_fma_f32 v[92:93], v[92:93], v[136:137], v[212:213]
	global_store_dwordx4 v193, v[92:95], s[8:9] offset:64 sc1
	s_waitcnt vmcnt(27)
; #define PG8_BAR __builtin_amdgcn_s_barrier()
; template <class Epi, class Sched, bool ALIGN_EPI = false, bool SP2 = false>
; __device__ __forceinline__ void gemm_phase(PG8_LAS unsigned char* lds, const Gemm g, const Sched& S, const Epi& E) {
;     ...
;         if constexpr (ALIGN_EPI) { if (wr == 0) PG8_BAR; }
;         if constexpr (!Epi::AFTER_DRAIN) { E(acc, cur, wr, wc, fr, fq); S.done(cur); }
;         if (!has_next) break;
; #pragma unroll
;         for (int a = 0; a < 2; ++a)
; #pragma unroll
;             for (int b = 0; b < 2; ++b)
; #pragma unroll
;                 for (int m = 0; m < 4; ++m)
; #pragma unroll
;                     for (int n = 0; n < 2; ++n) acc[a][b][m][n] = (f32x4){0.f, 0.f, 0.f, 0.f};
;         cur = nxt; cA = nA; cB = nB; ++ui;
;         if constexpr (ALIGN_EPI) { if (wr == 1) PG8_BAR; }
;     }
;     __device__ __forceinline__ void operator()(const f32x4 (&acc)[2][2][4][2], const Unit& u, int wr, int wc, int fr, int fq) const {
;     ...
;             for (int m = 0; m < 4; ++m) { const size_t off = (size_t)(row0 + ai * HALF + m * 16) * 2048 + col0;
; #pragma unroll
;                 for (int bj = 0; bj < 2; ++bj)
; #pragma unroll
;                     for (int n = 0; n < 2; ++n) { const f32x4 bs = *(const f32x4*)(base + off + bj * HALF + n * 16);
;                         *(f32x4*)(out + off + bj * HALF + n * 16) = bs + gv[bj][n] * acc[ai][bj][m][n]; } }
	v_pk_fma_f32 v[86:87], v[86:87], v[134:135], v[218:219]
	v_pk_fma_f32 v[84:85], v[84:85], v[132:133], v[216:217]
	global_store_dwordx4 v193, v[84:87], s[8:9] offset:512 sc1
	s_waitcnt vmcnt(27)
	v_pk_fma_f32 v[74:75], v[74:75], v[130:131], v[222:223]
	v_pk_fma_f32 v[72:73], v[72:73], v[128:129], v[220:221]
	global_store_dwordx4 v193, v[72:75], s[8:9] offset:576 sc1
	global_load_dwordx4 v[208:211], v228, s[6:7]
	global_load_dwordx4 v[212:215], v228, s[6:7] offset:64
	global_load_dwordx4 v[216:219], v228, s[6:7] offset:512
	global_load_dwordx4 v[220:223], v228, s[6:7] offset:576
	s_waitcnt vmcnt(27)
	v_pk_fma_f32 v[82:83], v[82:83], v[142:143], v[174:175]
	v_pk_fma_f32 v[80:81], v[80:81], v[140:141], v[172:173]
	global_store_dwordx4 v224, v[80:83], s[8:9] sc1
	s_waitcnt vmcnt(27)
	v_pk_fma_f32 v[78:79], v[78:79], v[138:139], v[178:179]
	v_pk_fma_f32 v[76:77], v[76:77], v[136:137], v[176:177]
	global_store_dwordx4 v224, v[76:79], s[8:9] offset:64 sc1
	s_waitcnt vmcnt(27)
	v_pk_fma_f32 v[70:71], v[70:71], v[134:135], v[182:183]
	v_pk_fma_f32 v[68:69], v[68:69], v[132:133], v[180:181]
	global_store_dwordx4 v224, v[68:71], s[8:9] offset:512 sc1
	s_waitcnt vmcnt(27)
	v_pk_fma_f32 v[66:67], v[66:67], v[130:131], v[186:187]
	v_pk_fma_f32 v[64:65], v[64:65], v[128:129], v[184:185]
	global_store_dwordx4 v224, v[64:67], s[8:9] offset:576 sc1
	s_waitcnt vmcnt(27)
	v_pk_fma_f32 v[62:63], v[62:63], v[142:143], v[126:127]
	v_pk_fma_f32 v[60:61], v[60:61], v[140:141], v[124:125]
	global_store_dwordx4 v225, v[60:63], s[8:9] sc1
	s_waitcnt vmcnt(27)
	v_pk_fma_f32 v[58:59], v[58:59], v[138:139], v[122:123]
	v_pk_fma_f32 v[56:57], v[56:57], v[136:137], v[120:121]
	global_store_dwordx4 v225, v[56:59], s[8:9] offset:64 sc1
	s_waitcnt vmcnt(27)
	v_pk_fma_f32 v[54:55], v[54:55], v[134:135], v[118:119]
	v_pk_fma_f32 v[52:53], v[52:53], v[132:133], v[116:117]
	global_store_dwordx4 v225, v[52:55], s[8:9] offset:512 sc1
	s_waitcnt vmcnt(27)
	v_pk_fma_f32 v[42:43], v[42:43], v[130:131], v[106:107]
	v_pk_fma_f32 v[40:41], v[40:41], v[128:129], v[104:105]
	global_store_dwordx4 v225, v[40:43], s[8:9] offset:576 sc1
	s_waitcnt vmcnt(23)
	v_pk_fma_f32 v[50:51], v[50:51], v[142:143], v[190:191]
	v_pk_fma_f32 v[48:49], v[48:49], v[140:141], v[188:189]
	global_store_dwordx4 v226, v[48:51], s[8:9] sc1
	s_waitcnt vmcnt(23)
	v_pk_fma_f32 v[46:47], v[46:47], v[138:139], v[198:199]
	v_pk_fma_f32 v[44:45], v[44:45], v[136:137], v[196:197]
	global_store_dwordx4 v226, v[44:47], s[8:9] offset:64 sc1
	s_waitcnt vmcnt(23)
	v_pk_fma_f32 v[38:39], v[38:39], v[134:135], v[202:203]
	v_pk_fma_f32 v[36:37], v[36:37], v[132:133], v[200:201]
	global_store_dwordx4 v226, v[36:39], s[8:9] offset:512 sc1
	s_waitcnt vmcnt(23)
	v_pk_fma_f32 v[26:27], v[26:27], v[130:131], v[206:207]
	v_pk_fma_f32 v[24:25], v[24:25], v[128:129], v[204:205]
	global_store_dwordx4 v226, v[24:27], s[8:9] offset:576 sc1
	s_waitcnt vmcnt(23)
	v_pk_fma_f32 v[34:35], v[34:35], v[142:143], v[114:115]
	v_pk_fma_f32 v[32:33], v[32:33], v[140:141], v[112:113]
	global_store_dwordx4 v227, v[32:35], s[8:9] sc1
	s_waitcnt vmcnt(23)
	v_pk_fma_f32 v[30:31], v[30:31], v[138:139], v[110:111]
	v_pk_fma_f32 v[28:29], v[28:29], v[136:137], v[108:109]
	global_store_dwordx4 v227, v[28:31], s[8:9] offset:64 sc1
	s_waitcnt vmcnt(23)
	v_pk_fma_f32 v[22:23], v[22:23], v[134:135], v[102:103]
	v_pk_fma_f32 v[20:21], v[20:21], v[132:133], v[100:101]
	global_store_dwordx4 v227, v[20:23], s[8:9] offset:512 sc1
	s_waitcnt vmcnt(23)
	v_pk_fma_f32 v[10:11], v[10:11], v[130:131], v[90:91]
	v_pk_fma_f32 v[8:9], v[8:9], v[128:129], v[88:89]
	global_store_dwordx4 v227, v[8:11], s[8:9] offset:576 sc1
	s_waitcnt vmcnt(19)
	v_pk_fma_f32 v[18:19], v[18:19], v[142:143], v[210:211]
	v_pk_fma_f32 v[16:17], v[16:17], v[140:141], v[208:209]
	global_store_dwordx4 v228, v[16:19], s[8:9] sc1
	s_waitcnt vmcnt(19)
	v_pk_fma_f32 v[14:15], v[14:15], v[138:139], v[214:215]
	v_pk_fma_f32 v[12:13], v[12:13], v[136:137], v[212:213]
	global_store_dwordx4 v228, v[12:15], s[8:9] offset:64 sc1
	s_waitcnt vmcnt(19)
	v_pk_fma_f32 v[6:7], v[6:7], v[134:135], v[218:219]
	v_pk_fma_f32 v[4:5], v[4:5], v[132:133], v[216:217]
	global_store_dwordx4 v228, v[4:7], s[8:9] offset:512 sc1
	s_waitcnt vmcnt(19)
	v_pk_fma_f32 v[2:3], v[2:3], v[130:131], v[222:223]
	v_pk_fma_f32 v[0:1], v[0:1], v[128:129], v[220:221]
	global_store_dwordx4 v228, v[0:3], s[8:9] offset:576 sc1
	s_cbranch_vccnz .LBB0_605
	s_andn2_b64 vcc, exec, s[16:17]
	s_cbranch_vccnz .LBB0_604
	s_barrier
	s_branch .LBB0_604

; DI unsigned cvtpk(float lo, float hi) { f32x2 v = {lo, hi}; bf16x2_t b = __builtin_convertvector(v, bf16x2_t); return __builtin_bit_cast(unsigned, b); }
; DI float silu_(float x) { return x * sigm(x); }
;     __device__ __forceinline__ void fused(f32x4 (&acc)[2][2][4][2], const Unit& u, int wr, int wc, int fr, int fq, PG8_LAS unsigned char* lds, int wid, int lane) const {
;     ...
;         for (int i8 = 0; i8 < 8; ++i8) { const int r = rg * 8 + i8;
;             CONV_LD(na, nb, r + 1);
;             u32x4 o;
; #pragma unroll
;             for (int i = 0; i < 4; ++i) {
;                 const float a0 = ba[2 * i] + wa[0][2 * i] * pa[2 * i] + wa[1][2 * i] * ca[2 * i] + wa[2][2 * i] * na[2 * i];
;                 const float a1 = ba[2 * i + 1] + wa[0][2 * i + 1] * pa[2 * i + 1] + wa[1][2 * i + 1] * ca[2 * i + 1] + wa[2][2 * i + 1] * na[2 * i + 1];
;                 const float b0 = bb[2 * i] + wb[0][2 * i] * pb[2 * i] + wb[1][2 * i] * cb[2 * i] + wb[2][2 * i] * nb[2 * i];
;                 const float b1 = bb[2 * i + 1] + wb[0][2 * i + 1] * pb[2 * i + 1] + wb[1][2 * i + 1] * cb[2 * i + 1] + wb[2][2 * i + 1] * nb[2 * i + 1];
;                 o[i] = cvtpk(silu_(a0) * b0, silu_(a1) * b1); }
;             *(u32x4*)(Gt + (size_t)(u.pm * BM + r) * FF + f) = o;
; #pragma unroll
;             for (int i = 0; i < 8; ++i) { pa[i] = ca[i]; pb[i] = cb[i]; ca[i] = na[i]; cb[i] = nb[i]; } }
.LBB0_745:
	s_or_b64 exec, exec, s[4:5]
	s_waitcnt vmcnt(2)
	v_pk_fma_f32 v[114:115], v[44:45], v[114:115], v[60:61]
	s_waitcnt vmcnt(0)
	v_pk_fma_f32 v[112:113], v[32:33], v[112:113], v[48:49]
	v_pk_fma_f32 v[114:115], v[56:57], v[108:109], v[114:115]
	v_pk_fma_f32 v[112:113], v[36:37], v[68:69], v[112:113]
	v_pk_fma_f32 v[114:115], v[52:53], v[84:85], v[114:115]
	v_pk_fma_f32 v[110:111], v[46:47], v[110:111], v[62:63]
	v_mul_f32_e32 v67, 0xbfb8aa3b, v114
	v_mul_f32_e32 v117, 0xbfb8aa3b, v115
	v_exp_f32_e32 v67, v67
	v_exp_f32_e32 v117, v117
	v_pk_fma_f32 v[112:113], v[40:41], v[80:81], v[112:113]
	v_pk_fma_f32 v[110:111], v[58:59], v[106:107], v[110:111]
	v_add_f32_e32 v67, 1.0, v67
	v_add_f32_e32 v117, 1.0, v117
	v_rcp_f32_e32 v118, v67
	v_rcp_f32_e32 v119, v117
	v_pk_fma_f32 v[100:101], v[12:13], v[100:101], v[28:29]
	v_pk_fma_f32 v[102:103], v[34:35], v[102:103], v[50:51]
	v_pk_fma_f32 v[100:101], v[20:21], v[104:105], v[100:101]
	v_pk_mul_f32 v[114:115], v[114:115], v[118:119]
	v_pk_fma_f32 v[100:101], v[24:25], v[78:79], v[100:101]
	v_pk_mul_f32 v[112:113], v[112:113], v[114:115]
	v_pk_fma_f32 v[114:115], v[54:55], v[82:83], v[110:111]
	v_pk_fma_f32 v[102:103], v[38:39], v[98:99], v[102:103]
	v_mul_f32_e32 v67, 0xbfb8aa3b, v114
	v_exp_f32_e32 v67, v67
	v_mul_f32_e32 v110, 0xbfb8aa3b, v115
	v_exp_f32_e32 v111, v110
	v_cvt_pk_bf16_f32 v110, v112, v113
	v_add_f32_e32 v67, 1.0, v67
	v_rcp_f32_e32 v112, v67
	v_add_f32_e32 v67, 1.0, v111
	v_rcp_f32_e32 v113, v67
	v_mul_f32_e32 v67, 0xbfb8aa3b, v100
	v_pk_fma_f32 v[102:103], v[42:43], v[76:77], v[102:103]
	v_exp_f32_e32 v67, v67
	v_pk_mul_f32 v[112:113], v[114:115], v[112:113]
	v_mul_f32_e32 v111, 0xbfb8aa3b, v101
	v_pk_mul_f32 v[102:103], v[102:103], v[112:113]
	v_exp_f32_e32 v112, v111
	v_add_f32_e32 v67, 1.0, v67
	v_cvt_pk_bf16_f32 v111, v102, v103
	v_rcp_f32_e32 v102, v67
	v_add_f32_e32 v67, 1.0, v112
	v_rcp_f32_e32 v103, v67
	v_pk_fma_f32 v[90:91], v[14:15], v[90:91], v[30:31]
	v_pk_fma_f32 v[92:93], v[0:1], v[92:93], v[16:17]
	v_pk_fma_f32 v[90:91], v[22:23], v[96:97], v[90:91]
	v_pk_fma_f32 v[92:93], v[4:5], v[94:95], v[92:93]
	v_pk_fma_f32 v[90:91], v[26:27], v[74:75], v[90:91]
	v_pk_fma_f32 v[92:93], v[8:9], v[72:73], v[92:93]
	v_pk_mul_f32 v[100:101], v[100:101], v[102:103]
	v_mul_f32_e32 v67, 0xbfb8aa3b, v90
	v_pk_mul_f32 v[92:93], v[92:93], v[100:101]
	v_exp_f32_e32 v67, v67
	v_mul_f32_e32 v100, 0xbfb8aa3b, v91
	v_exp_f32_e32 v100, v100
	v_cvt_pk_bf16_f32 v112, v92, v93
	v_add_f32_e32 v67, 1.0, v67
	v_rcp_f32_e32 v92, v67
	v_add_f32_e32 v67, 1.0, v100
	v_rcp_f32_e32 v93, v67
	v_pk_fma_f32 v[86:87], v[2:3], v[86:87], v[18:19]
	s_lshl_b32 s0, s27, 8
	v_pk_fma_f32 v[86:87], v[6:7], v[88:89], v[86:87]
	v_pk_mul_f32 v[90:91], v[90:91], v[92:93]
	v_pk_fma_f32 v[86:87], v[10:11], v[70:71], v[86:87]
	v_add_u32_e32 v67, s0, v134
	v_pk_mul_f32 v[86:87], v[86:87], v[90:91]
	v_or_b32_e32 v117, 2, v134
	v_cvt_pk_bf16_f32 v113, v86, v87
	v_mov_b64_e32 v[86:87], s[16:17]
	v_mad_i64_i32 v[86:87], s[2:3], v67, s54, v[86:87]
	v_lshl_add_u64 v[86:87], v[64:65], 1, v[86:87]
	global_store_dwordx4 v[86:87], v[110:113], off sc1
	v_mov_b32_e32 v67, 0
	v_mov_b32_e32 v100, 0
	v_mov_b32_e32 v101, 0
	v_mov_b32_e32 v90, 0
	v_mov_b32_e32 v91, 0
	v_mov_b32_e32 v86, 0
	v_mov_b32_e32 v87, 0
	v_mov_b32_e32 v120, 0
	v_mov_b32_e32 v121, 0
	v_mov_b32_e32 v112, 0
	v_mov_b32_e32 v113, 0
	v_mov_b32_e32 v102, 0
	v_mov_b32_e32 v103, 0
	v_mov_b32_e32 v92, 0
	v_mov_b32_e32 v93, 0
	s_and_saveexec_b64 s[4:5], vcc
	s_cbranch_execz .LBB0_747
	v_lshl_add_u32 v66, v117, 9, 0
	v_bitop3_b32 v67, v117, v146, 26 bitop3:0x6c
	v_lshl_add_u32 v67, v67, 4, v66
	ds_read_b128 v[90:93], v67
	v_bitop3_b32 v67, v117, v132, 26 bitop3:0x6c
	v_lshl_add_u32 v66, v67, 4, v66
	ds_read_b128 v[122:125], v66
	s_waitcnt lgkmcnt(1)
	v_lshlrev_b32_e32 v120, 16, v90
	v_and_b32_e32 v121, 0xffff0000, v90
	v_lshlrev_b32_e32 v112, 16, v91
	s_waitcnt lgkmcnt(0)
	v_lshlrev_b32_e32 v66, 16, v122
	v_and_b32_e32 v67, 0xffff0000, v122
	v_and_b32_e32 v113, 0xffff0000, v91
	v_lshlrev_b32_e32 v100, 16, v123
	v_and_b32_e32 v101, 0xffff0000, v123
	v_lshlrev_b32_e32 v102, 16, v92
	v_and_b32_e32 v103, 0xffff0000, v92
	v_lshlrev_b32_e32 v90, 16, v124
	v_and_b32_e32 v91, 0xffff0000, v124
	v_lshlrev_b32_e32 v92, 16, v93
	v_and_b32_e32 v93, 0xffff0000, v93
	v_lshlrev_b32_e32 v86, 16, v125
	v_and_b32_e32 v87, 0xffff0000, v125
; DI unsigned cvtpk(float lo, float hi) { f32x2 v = {lo, hi}; bf16x2_t b = __builtin_convertvector(v, bf16x2_t); return __builtin_bit_cast(unsigned, b); }
; DI float silu_(float x) { return x * sigm(x); }
;     __device__ __forceinline__ void fused(f32x4 (&acc)[2][2][4][2], const Unit& u, int wr, int wc, int fr, int fq, PG8_LAS unsigned char* lds, int wid, int lane) const {
;     ...
;         for (int i8 = 0; i8 < 8; ++i8) { const int r = rg * 8 + i8;
;             CONV_LD(na, nb, r + 1);
;             u32x4 o;
; #pragma unroll
;             for (int i = 0; i < 4; ++i) {
;                 const float a0 = ba[2 * i] + wa[0][2 * i] * pa[2 * i] + wa[1][2 * i] * ca[2 * i] + wa[2][2 * i] * na[2 * i];
;                 const float a1 = ba[2 * i + 1] + wa[0][2 * i + 1] * pa[2 * i + 1] + wa[1][2 * i + 1] * ca[2 * i + 1] + wa[2][2 * i + 1] * na[2 * i + 1];
;                 const float b0 = bb[2 * i] + wb[0][2 * i] * pb[2 * i] + wb[1][2 * i] * cb[2 * i] + wb[2][2 * i] * nb[2 * i];
;                 const float b1 = bb[2 * i + 1] + wb[0][2 * i + 1] * pb[2 * i + 1] + wb[1][2 * i + 1] * cb[2 * i + 1] + wb[2][2 * i + 1] * nb[2 * i + 1];
;                 o[i] = cvtpk(silu_(a0) * b0, silu_(a1) * b1); }
;             *(u32x4*)(Gt + (size_t)(u.pm * BM + r) * FF + f) = o;
; #pragma unroll
;             for (int i = 0; i < 8; ++i) { pa[i] = ca[i]; pb[i] = cb[i]; ca[i] = na[i]; cb[i] = nb[i]; } }
.LBB0_747:
	s_or_b64 exec, exec, s[4:5]
	v_pk_fma_f32 v[108:109], v[44:45], v[108:109], v[60:61]
	v_pk_fma_f32 v[68:69], v[32:33], v[68:69], v[48:49]
	v_pk_fma_f32 v[108:109], v[56:57], v[84:85], v[108:109]
	v_pk_fma_f32 v[68:69], v[36:37], v[80:81], v[68:69]
	v_pk_fma_f32 v[108:109], v[52:53], v[120:121], v[108:109]
	v_pk_fma_f32 v[106:107], v[46:47], v[106:107], v[62:63]
	v_mul_f32_e32 v110, 0xbfb8aa3b, v108
	v_mul_f32_e32 v111, 0xbfb8aa3b, v109
	v_exp_f32_e32 v110, v110
	v_exp_f32_e32 v111, v111
	v_pk_fma_f32 v[68:69], v[40:41], v[66:67], v[68:69]
	v_pk_fma_f32 v[106:107], v[58:59], v[82:83], v[106:107]
	v_add_f32_e32 v110, 1.0, v110
	v_add_f32_e32 v111, 1.0, v111
	v_rcp_f32_e32 v110, v110
	v_rcp_f32_e32 v111, v111
	v_pk_fma_f32 v[98:99], v[34:35], v[98:99], v[50:51]
	v_pk_fma_f32 v[94:95], v[0:1], v[94:95], v[16:17]
	v_pk_fma_f32 v[98:99], v[38:39], v[76:77], v[98:99]
	v_pk_mul_f32 v[108:109], v[108:109], v[110:111]
	v_pk_fma_f32 v[98:99], v[42:43], v[100:101], v[98:99]
	v_pk_mul_f32 v[68:69], v[68:69], v[108:109]
	v_pk_fma_f32 v[108:109], v[54:55], v[112:113], v[106:107]
	v_pk_fma_f32 v[94:95], v[4:5], v[72:73], v[94:95]
	v_mul_f32_e32 v106, 0xbfb8aa3b, v108
	v_exp_f32_e32 v107, v106
	v_mul_f32_e32 v106, 0xbfb8aa3b, v109
	v_exp_f32_e32 v110, v106
	v_cvt_pk_bf16_f32 v106, v68, v69
	v_add_f32_e32 v68, 1.0, v107
	v_rcp_f32_e32 v68, v68
	v_add_f32_e32 v69, 1.0, v110
	v_rcp_f32_e32 v69, v69
	v_pk_fma_f32 v[94:95], v[8:9], v[90:91], v[94:95]
	v_pk_fma_f32 v[88:89], v[2:3], v[88:89], v[18:19]
	v_or_b32_e32 v135, 3, v134
	v_pk_mul_f32 v[68:69], v[108:109], v[68:69]
	v_pk_fma_f32 v[88:89], v[6:7], v[70:71], v[88:89]
	v_pk_mul_f32 v[68:69], v[98:99], v[68:69]
	v_pk_fma_f32 v[98:99], v[12:13], v[104:105], v[28:29]
	v_cvt_pk_bf16_f32 v107, v68, v69
	v_pk_fma_f32 v[98:99], v[20:21], v[78:79], v[98:99]
	v_pk_fma_f32 v[88:89], v[10:11], v[86:87], v[88:89]
	v_pk_fma_f32 v[98:99], v[24:25], v[102:103], v[98:99]
	v_mov_b32_e32 v114, 0
	v_mul_f32_e32 v104, 0xbfb8aa3b, v98
	v_mul_f32_e32 v105, 0xbfb8aa3b, v99
	v_exp_f32_e32 v104, v104
	v_exp_f32_e32 v105, v105
	v_mov_b32_e32 v115, 0
	v_mov_b32_e32 v124, 0
	v_add_f32_e32 v68, 1.0, v104
	v_add_f32_e32 v69, 1.0, v105
	v_rcp_f32_e32 v68, v68
	v_rcp_f32_e32 v69, v69
	v_mov_b32_e32 v125, 0
	v_mov_b32_e32 v118, 0
	v_mov_b32_e32 v119, 0
	v_pk_mul_f32 v[68:69], v[98:99], v[68:69]
	v_mov_b32_e32 v110, 0
	v_pk_mul_f32 v[68:69], v[94:95], v[68:69]
	v_pk_fma_f32 v[94:95], v[14:15], v[96:97], v[30:31]
	v_cvt_pk_bf16_f32 v108, v68, v69
	v_pk_fma_f32 v[94:95], v[22:23], v[74:75], v[94:95]
	v_mov_b32_e32 v111, 0
	v_pk_fma_f32 v[94:95], v[26:27], v[92:93], v[94:95]
	v_mov_b32_e32 v98, 0
	v_mul_f32_e32 v96, 0xbfb8aa3b, v94
	v_mul_f32_e32 v97, 0xbfb8aa3b, v95
	v_exp_f32_e32 v96, v96
	v_exp_f32_e32 v97, v97
	v_mov_b32_e32 v99, 0
	v_add_f32_e32 v68, 1.0, v96
	v_add_f32_e32 v69, 1.0, v97
	v_rcp_f32_e32 v68, v68
	v_rcp_f32_e32 v69, v69
	s_nop 0
	v_pk_mul_f32 v[68:69], v[94:95], v[68:69]
	s_nop 0
	v_pk_mul_f32 v[68:69], v[88:89], v[68:69]
	v_add_u32_e32 v88, s0, v116
	v_cvt_pk_bf16_f32 v109, v68, v69
	v_mov_b64_e32 v[68:69], s[16:17]
	v_mad_i64_i32 v[68:69], s[2:3], v88, s54, v[68:69]
	v_lshl_add_u64 v[68:69], v[64:65], 1, v[68:69]
	global_store_dwordx4 v[68:69], v[106:109], off sc1
	v_mov_b32_e32 v68, 0
	v_mov_b32_e32 v94, 0
	v_mov_b32_e32 v106, 0
	v_mov_b32_e32 v107, 0
	v_mov_b32_e32 v95, 0
	v_mov_b32_e32 v88, 0
	v_mov_b32_e32 v89, 0
	s_and_saveexec_b64 s[4:5], vcc
	s_cbranch_execz .LBB0_749
	v_lshl_add_u32 v69, v135, 9, 0
	v_bitop3_b32 v88, v135, v146, 27 bitop3:0x6c
	v_lshl_add_u32 v88, v88, 4, v69
	ds_read_b128 v[94:97], v88
	v_bitop3_b32 v88, v135, v132, 27 bitop3:0x6c
	v_lshl_add_u32 v69, v88, 4, v69
	ds_read_b128 v[106:109], v69
	s_waitcnt lgkmcnt(1)
	v_lshlrev_b32_e32 v124, 16, v94
	v_and_b32_e32 v125, 0xffff0000, v94
	v_lshlrev_b32_e32 v118, 16, v95
	s_waitcnt lgkmcnt(0)
	v_lshlrev_b32_e32 v114, 16, v106
	v_and_b32_e32 v115, 0xffff0000, v106
	v_and_b32_e32 v119, 0xffff0000, v95
	v_lshlrev_b32_e32 v106, 16, v107
	v_and_b32_e32 v107, 0xffff0000, v107
	v_lshlrev_b32_e32 v110, 16, v96
	v_and_b32_e32 v111, 0xffff0000, v96
	v_lshlrev_b32_e32 v94, 16, v108
	v_and_b32_e32 v95, 0xffff0000, v108
	v_lshlrev_b32_e32 v98, 16, v97
	v_and_b32_e32 v99, 0xffff0000, v97
	v_lshlrev_b32_e32 v88, 16, v109
	v_and_b32_e32 v89, 0xffff0000, v109
; DI unsigned cvtpk(float lo, float hi) { f32x2 v = {lo, hi}; bf16x2_t b = __builtin_convertvector(v, bf16x2_t); return __builtin_bit_cast(unsigned, b); }
; DI float silu_(float x) { return x * sigm(x); }
;     __device__ __forceinline__ void fused(f32x4 (&acc)[2][2][4][2], const Unit& u, int wr, int wc, int fr, int fq, PG8_LAS unsigned char* lds, int wid, int lane) const {
;     ...
;         for (int i8 = 0; i8 < 8; ++i8) { const int r = rg * 8 + i8;
;             CONV_LD(na, nb, r + 1);
;             u32x4 o;
; #pragma unroll
;             for (int i = 0; i < 4; ++i) {
;                 const float a0 = ba[2 * i] + wa[0][2 * i] * pa[2 * i] + wa[1][2 * i] * ca[2 * i] + wa[2][2 * i] * na[2 * i];
;                 const float a1 = ba[2 * i + 1] + wa[0][2 * i + 1] * pa[2 * i + 1] + wa[1][2 * i + 1] * ca[2 * i + 1] + wa[2][2 * i + 1] * na[2 * i + 1];
;                 const float b0 = bb[2 * i] + wb[0][2 * i] * pb[2 * i] + wb[1][2 * i] * cb[2 * i] + wb[2][2 * i] * nb[2 * i];
;                 const float b1 = bb[2 * i + 1] + wb[0][2 * i + 1] * pb[2 * i + 1] + wb[1][2 * i + 1] * cb[2 * i + 1] + wb[2][2 * i + 1] * nb[2 * i + 1];
;                 o[i] = cvtpk(silu_(a0) * b0, silu_(a1) * b1); }
;             *(u32x4*)(Gt + (size_t)(u.pm * BM + r) * FF + f) = o;
; #pragma unroll
;             for (int i = 0; i < 8; ++i) { pa[i] = ca[i]; pb[i] = cb[i]; ca[i] = na[i]; cb[i] = nb[i]; } }
.LBB0_749:
	s_or_b64 exec, exec, s[4:5]
	v_pk_fma_f32 v[84:85], v[44:45], v[84:85], v[60:61]
	v_pk_fma_f32 v[82:83], v[46:47], v[82:83], v[62:63]
	v_pk_fma_f32 v[84:85], v[56:57], v[120:121], v[84:85]
	v_pk_fma_f32 v[80:81], v[32:33], v[80:81], v[48:49]
	v_pk_fma_f32 v[84:85], v[52:53], v[124:125], v[84:85]
	v_pk_fma_f32 v[82:83], v[58:59], v[112:113], v[82:83]
	v_mul_f32_e32 v69, 0xbfb8aa3b, v84
	v_mul_f32_e32 v96, 0xbfb8aa3b, v85
	v_exp_f32_e32 v69, v69
	v_exp_f32_e32 v96, v96
	v_pk_fma_f32 v[80:81], v[36:37], v[66:67], v[80:81]
	v_pk_fma_f32 v[82:83], v[54:55], v[118:119], v[82:83]
	v_add_f32_e32 v69, 1.0, v69
	v_add_f32_e32 v97, 1.0, v96
	v_rcp_f32_e32 v96, v69
	v_rcp_f32_e32 v97, v97
	v_pk_fma_f32 v[80:81], v[40:41], v[114:115], v[80:81]
	v_mul_f32_e32 v69, 0xbfb8aa3b, v82
	v_exp_f32_e32 v69, v69
	v_pk_mul_f32 v[84:85], v[84:85], v[96:97]
	v_pk_fma_f32 v[78:79], v[12:13], v[78:79], v[28:29]
	v_pk_mul_f32 v[80:81], v[80:81], v[84:85]
	v_mul_f32_e32 v84, 0xbfb8aa3b, v83
	v_exp_f32_e32 v85, v84
	v_add_f32_e32 v69, 1.0, v69
	v_rcp_f32_e32 v84, v69
	v_pk_fma_f32 v[78:79], v[20:21], v[102:103], v[78:79]
	v_add_f32_e32 v69, 1.0, v85
	v_rcp_f32_e32 v85, v69
	v_pk_fma_f32 v[76:77], v[34:35], v[76:77], v[50:51]
	v_pk_fma_f32 v[78:79], v[24:25], v[110:111], v[78:79]
	v_pk_fma_f32 v[76:77], v[38:39], v[100:101], v[76:77]
	v_mul_f32_e32 v69, 0xbfb8aa3b, v78
	v_cvt_pk_bf16_f32 v80, v80, v81
	v_pk_fma_f32 v[76:77], v[42:43], v[106:107], v[76:77]
	v_pk_mul_f32 v[82:83], v[82:83], v[84:85]
	v_exp_f32_e32 v69, v69
	v_mul_f32_e32 v81, 0xbfb8aa3b, v79
	v_pk_mul_f32 v[76:77], v[76:77], v[82:83]
	v_exp_f32_e32 v82, v81
	v_add_f32_e32 v69, 1.0, v69
	v_cvt_pk_bf16_f32 v81, v76, v77
	v_rcp_f32_e32 v76, v69
	v_add_f32_e32 v69, 1.0, v82
	v_rcp_f32_e32 v77, v69
	v_pk_fma_f32 v[74:75], v[14:15], v[74:75], v[30:31]
	v_pk_fma_f32 v[72:73], v[0:1], v[72:73], v[16:17]
	v_pk_fma_f32 v[74:75], v[22:23], v[92:93], v[74:75]
	v_pk_fma_f32 v[72:73], v[4:5], v[90:91], v[72:73]
	v_pk_fma_f32 v[74:75], v[26:27], v[98:99], v[74:75]
	v_pk_fma_f32 v[72:73], v[8:9], v[94:95], v[72:73]
	v_pk_mul_f32 v[76:77], v[78:79], v[76:77]
	v_mul_f32_e32 v69, 0xbfb8aa3b, v74
	v_pk_mul_f32 v[72:73], v[72:73], v[76:77]
	v_exp_f32_e32 v69, v69
	v_mul_f32_e32 v76, 0xbfb8aa3b, v75
	v_exp_f32_e32 v76, v76
	v_cvt_pk_bf16_f32 v82, v72, v73
	v_add_f32_e32 v69, 1.0, v69
	v_rcp_f32_e32 v72, v69
	v_add_f32_e32 v69, 1.0, v76
	v_rcp_f32_e32 v73, v69
	v_pk_fma_f32 v[70:71], v[2:3], v[70:71], v[18:19]
	v_add_u32_e32 v69, s0, v117
	v_pk_fma_f32 v[70:71], v[6:7], v[86:87], v[70:71]
	v_pk_mul_f32 v[72:73], v[74:75], v[72:73]
	v_pk_fma_f32 v[70:71], v[10:11], v[88:89], v[70:71]
	v_mov_b32_e32 v104, 0
	v_pk_mul_f32 v[70:71], v[70:71], v[72:73]
	v_mov_b32_e32 v105, 0
	v_cvt_pk_bf16_f32 v83, v70, v71
	v_mov_b64_e32 v[70:71], s[16:17]
	v_mad_i64_i32 v[70:71], s[2:3], v69, s54, v[70:71]
	v_lshl_add_u64 v[70:71], v[64:65], 1, v[70:71]
	global_store_dwordx4 v[70:71], v[80:83], off sc1
	v_or_b32_e32 v70, 4, v134
	v_mov_b32_e32 v69, 0
	v_mov_b32_e32 v80, 0
	v_mov_b32_e32 v81, 0
	v_mov_b32_e32 v74, 0
	v_mov_b32_e32 v75, 0
	v_mov_b32_e32 v122, 0
	v_mov_b32_e32 v123, 0
	v_mov_b32_e32 v116, 0
	v_mov_b32_e32 v117, 0
	v_mov_b32_e32 v108, 0
	v_mov_b32_e32 v109, 0
	v_mov_b32_e32 v96, 0
	v_mov_b32_e32 v97, 0
	s_and_saveexec_b64 s[4:5], vcc
	s_cbranch_execz .LBB0_751
	v_lshl_add_u32 v68, v70, 9, 0
	v_bitop3_b32 v69, v70, v146, 28 bitop3:0x6c
	v_lshl_add_u32 v69, v69, 4, v68
	ds_read_b128 v[72:75], v69
	v_bitop3_b32 v69, v70, v132, 28 bitop3:0x6c
	v_lshl_add_u32 v68, v69, 4, v68
	ds_read_b128 v[76:79], v68
	s_waitcnt lgkmcnt(1)
	v_lshlrev_b32_e32 v122, 16, v72
	v_and_b32_e32 v123, 0xffff0000, v72
	v_lshlrev_b32_e32 v116, 16, v73
	s_waitcnt lgkmcnt(0)
	v_lshlrev_b32_e32 v68, 16, v76
	v_and_b32_e32 v69, 0xffff0000, v76
	v_and_b32_e32 v117, 0xffff0000, v73
	v_lshlrev_b32_e32 v104, 16, v77
	v_and_b32_e32 v105, 0xffff0000, v77
	v_lshlrev_b32_e32 v108, 16, v74
	v_and_b32_e32 v109, 0xffff0000, v74
	v_lshlrev_b32_e32 v80, 16, v78
	v_and_b32_e32 v81, 0xffff0000, v78
	v_lshlrev_b32_e32 v96, 16, v75
	v_and_b32_e32 v97, 0xffff0000, v75
	v_lshlrev_b32_e32 v74, 16, v79
	v_and_b32_e32 v75, 0xffff0000, v79
.LBB0_751:
	s_or_b64 exec, exec, s[4:5]
	v_pk_fma_f32 v[72:73], v[44:45], v[120:121], v[60:61]
	v_pk_fma_f32 v[66:67], v[32:33], v[66:67], v[48:49]
	v_pk_fma_f32 v[72:73], v[56:57], v[124:125], v[72:73]
	v_pk_fma_f32 v[66:67], v[36:37], v[114:115], v[66:67]
	v_pk_fma_f32 v[72:73], v[52:53], v[122:123], v[72:73]
	v_pk_fma_f32 v[66:67], v[40:41], v[68:69], v[66:67]
	v_mul_f32_e32 v71, 0xbfb8aa3b, v72
	v_mul_f32_e32 v76, 0xbfb8aa3b, v73
	v_exp_f32_e32 v71, v71
	v_exp_f32_e32 v76, v76
	v_pk_fma_f32 v[78:79], v[34:35], v[100:101], v[50:51]
	v_pk_fma_f32 v[82:83], v[2:3], v[86:87], v[18:19]
	v_add_f32_e32 v71, 1.0, v71
	v_add_f32_e32 v77, 1.0, v76
	v_rcp_f32_e32 v76, v71
	v_rcp_f32_e32 v77, v77
	v_pk_fma_f32 v[78:79], v[38:39], v[106:107], v[78:79]
	v_pk_fma_f32 v[82:83], v[6:7], v[88:89], v[82:83]
	v_pk_fma_f32 v[78:79], v[42:43], v[104:105], v[78:79]
	v_pk_mul_f32 v[72:73], v[72:73], v[76:77]
	v_pk_fma_f32 v[82:83], v[10:11], v[74:75], v[82:83]
	v_pk_mul_f32 v[66:67], v[66:67], v[72:73]
	v_pk_fma_f32 v[72:73], v[46:47], v[112:113], v[62:63]
	v_or_b32_e32 v120, 5, v134
	v_pk_fma_f32 v[72:73], v[58:59], v[118:119], v[72:73]
	v_mov_b32_e32 v100, 0
	v_pk_fma_f32 v[72:73], v[54:55], v[116:117], v[72:73]
	v_mov_b32_e32 v101, 0
	v_mul_f32_e32 v71, 0xbfb8aa3b, v72
	v_mul_f32_e32 v76, 0xbfb8aa3b, v73
	v_exp_f32_e32 v71, v71
	v_exp_f32_e32 v77, v76
	v_cvt_pk_bf16_f32 v76, v66, v67
	v_mov_b32_e32 v112, 0
	v_add_f32_e32 v66, 1.0, v71
	v_add_f32_e32 v67, 1.0, v77
; DI unsigned cvtpk(float lo, float hi) { f32x2 v = {lo, hi}; bf16x2_t b = __builtin_convertvector(v, bf16x2_t); return __builtin_bit_cast(unsigned, b); }
; DI float silu_(float x) { return x * sigm(x); }
;     __device__ __forceinline__ void fused(f32x4 (&acc)[2][2][4][2], const Unit& u, int wr, int wc, int fr, int fq, PG8_LAS unsigned char* lds, int wid, int lane) const {
;     ...
;         for (int i8 = 0; i8 < 8; ++i8) { const int r = rg * 8 + i8;
;             CONV_LD(na, nb, r + 1);
;             u32x4 o;
; #pragma unroll
;             for (int i = 0; i < 4; ++i) {
;                 const float a0 = ba[2 * i] + wa[0][2 * i] * pa[2 * i] + wa[1][2 * i] * ca[2 * i] + wa[2][2 * i] * na[2 * i];
;                 const float a1 = ba[2 * i + 1] + wa[0][2 * i + 1] * pa[2 * i + 1] + wa[1][2 * i + 1] * ca[2 * i + 1] + wa[2][2 * i + 1] * na[2 * i + 1];
;                 const float b0 = bb[2 * i] + wb[0][2 * i] * pb[2 * i] + wb[1][2 * i] * cb[2 * i] + wb[2][2 * i] * nb[2 * i];
;                 const float b1 = bb[2 * i + 1] + wb[0][2 * i + 1] * pb[2 * i + 1] + wb[1][2 * i + 1] * cb[2 * i + 1] + wb[2][2 * i + 1] * nb[2 * i + 1];
;                 o[i] = cvtpk(silu_(a0) * b0, silu_(a1) * b1); }
;             *(u32x4*)(Gt + (size_t)(u.pm * BM + r) * FF + f) = o;
; #pragma unroll
;             for (int i = 0; i < 8; ++i) { pa[i] = ca[i]; pb[i] = cb[i]; ca[i] = na[i]; cb[i] = nb[i]; } }
	v_rcp_f32_e32 v66, v66
	v_rcp_f32_e32 v67, v67
	v_mov_b32_e32 v113, 0
	v_mov_b32_e32 v84, 0
	v_mov_b32_e32 v85, 0
	v_pk_mul_f32 v[66:67], v[72:73], v[66:67]
	v_pk_fma_f32 v[72:73], v[12:13], v[102:103], v[28:29]
	v_pk_mul_f32 v[66:67], v[78:79], v[66:67]
	v_pk_fma_f32 v[72:73], v[20:21], v[110:111], v[72:73]
	v_mov_b32_e32 v102, 0
	v_pk_fma_f32 v[72:73], v[24:25], v[108:109], v[72:73]
	v_mov_b32_e32 v103, 0
	v_mul_f32_e32 v71, 0xbfb8aa3b, v72
	v_mul_f32_e32 v77, 0xbfb8aa3b, v73
	v_exp_f32_e32 v71, v71
	v_exp_f32_e32 v78, v77
	v_cvt_pk_bf16_f32 v77, v66, v67
	v_add_f32_e32 v66, 1.0, v71
	v_add_f32_e32 v67, 1.0, v78
	v_rcp_f32_e32 v66, v66
	v_rcp_f32_e32 v67, v67
	v_pk_fma_f32 v[78:79], v[0:1], v[90:91], v[16:17]
	v_mov_b32_e32 v90, 0
	v_pk_fma_f32 v[78:79], v[4:5], v[94:95], v[78:79]
	v_pk_mul_f32 v[66:67], v[72:73], v[66:67]
	v_pk_fma_f32 v[72:73], v[14:15], v[92:93], v[30:31]
	v_pk_fma_f32 v[78:79], v[8:9], v[80:81], v[78:79]
	v_pk_fma_f32 v[72:73], v[22:23], v[98:99], v[72:73]
	v_pk_mul_f32 v[66:67], v[78:79], v[66:67]
	v_pk_fma_f32 v[72:73], v[26:27], v[96:97], v[72:73]
	v_mov_b32_e32 v91, 0
	v_mul_f32_e32 v71, 0xbfb8aa3b, v72
	v_mul_f32_e32 v78, 0xbfb8aa3b, v73
	v_exp_f32_e32 v71, v71
	v_exp_f32_e32 v79, v78
	v_cvt_pk_bf16_f32 v78, v66, v67
	v_mov_b32_e32 v92, 0
	v_add_f32_e32 v66, 1.0, v71
	v_add_f32_e32 v67, 1.0, v79
	v_rcp_f32_e32 v66, v66
	v_rcp_f32_e32 v67, v67
	v_add_u32_e32 v71, s0, v135
	v_mov_b32_e32 v93, 0
	v_pk_mul_f32 v[66:67], v[72:73], v[66:67]
	s_nop 0
	v_pk_mul_f32 v[66:67], v[82:83], v[66:67]
	v_mov_b32_e32 v72, 0
	v_cvt_pk_bf16_f32 v79, v66, v67
	v_mov_b64_e32 v[66:67], s[16:17]
	v_mad_i64_i32 v[66:67], s[2:3], v71, s54, v[66:67]
	v_lshl_add_u64 v[66:67], v[64:65], 1, v[66:67]
	global_store_dwordx4 v[66:67], v[76:79], off sc1
	v_mov_b32_e32 v66, 0
	v_mov_b32_e32 v73, 0
	v_mov_b32_e32 v78, 0
	v_mov_b32_e32 v79, 0
	s_and_saveexec_b64 s[4:5], vcc
	s_cbranch_execz .LBB0_753
	v_lshl_add_u32 v67, v120, 9, 0
	v_bitop3_b32 v71, v120, v146, 29 bitop3:0x6c
	v_lshl_add_u32 v71, v71, 4, v67
	ds_read_b128 v[82:85], v71
	v_bitop3_b32 v71, v120, v132, 29 bitop3:0x6c
	v_lshl_add_u32 v67, v71, 4, v67
	ds_read_b128 v[136:139], v67
	s_waitcnt lgkmcnt(1)
	v_lshlrev_b32_e32 v112, 16, v82
	v_and_b32_e32 v113, 0xffff0000, v82
	v_lshlrev_b32_e32 v102, 16, v83
	s_waitcnt lgkmcnt(0)
	v_lshlrev_b32_e32 v100, 16, v136
	v_and_b32_e32 v101, 0xffff0000, v136
	v_and_b32_e32 v103, 0xffff0000, v83
	v_lshlrev_b32_e32 v90, 16, v137
	v_and_b32_e32 v91, 0xffff0000, v137
	v_lshlrev_b32_e32 v92, 16, v84
	v_and_b32_e32 v93, 0xffff0000, v84
	v_lshlrev_b32_e32 v78, 16, v138
	v_and_b32_e32 v79, 0xffff0000, v138
	v_lshlrev_b32_e32 v84, 16, v85
	v_and_b32_e32 v85, 0xffff0000, v85
	v_lshlrev_b32_e32 v72, 16, v139
	v_and_b32_e32 v73, 0xffff0000, v139
.LBB0_753:
	s_or_b64 exec, exec, s[4:5]
	v_pk_fma_f32 v[76:77], v[44:45], v[124:125], v[60:61]
	v_pk_fma_f32 v[86:87], v[32:33], v[114:115], v[48:49]
	v_pk_fma_f32 v[76:77], v[56:57], v[122:123], v[76:77]
	v_pk_fma_f32 v[86:87], v[36:37], v[68:69], v[86:87]
	v_pk_fma_f32 v[76:77], v[52:53], v[112:113], v[76:77]
	v_pk_fma_f32 v[86:87], v[40:41], v[100:101], v[86:87]
	v_mul_f32_e32 v67, 0xbfb8aa3b, v76
	v_mul_f32_e32 v71, 0xbfb8aa3b, v77
	v_exp_f32_e32 v67, v67
	v_exp_f32_e32 v71, v71
	v_add_f32_e32 v67, 1.0, v67
	v_add_f32_e32 v71, 1.0, v71
	v_rcp_f32_e32 v82, v67
	v_rcp_f32_e32 v83, v71
	s_nop 0
	v_pk_mul_f32 v[76:77], v[76:77], v[82:83]
	v_pk_fma_f32 v[82:83], v[46:47], v[118:119], v[62:63]
	v_pk_mul_f32 v[76:77], v[86:87], v[76:77]
	v_pk_fma_f32 v[82:83], v[58:59], v[116:117], v[82:83]
	v_cvt_pk_bf16_f32 v136, v76, v77
	v_pk_fma_f32 v[82:83], v[54:55], v[102:103], v[82:83]
	v_pk_fma_f32 v[86:87], v[34:35], v[106:107], v[50:51]
	v_mul_f32_e32 v67, 0xbfb8aa3b, v82
	v_exp_f32_e32 v67, v67
	v_mul_f32_e32 v71, 0xbfb8aa3b, v83
	v_exp_f32_e32 v71, v71
	v_pk_fma_f32 v[86:87], v[38:39], v[104:105], v[86:87]
	v_add_f32_e32 v67, 1.0, v67
	v_rcp_f32_e32 v76, v67
	v_add_f32_e32 v67, 1.0, v71
	v_rcp_f32_e32 v77, v67
	v_pk_fma_f32 v[86:87], v[42:43], v[90:91], v[86:87]
	v_or_b32_e32 v107, 6, v134
	v_pk_mul_f32 v[76:77], v[82:83], v[76:77]
	v_pk_fma_f32 v[82:83], v[12:13], v[110:111], v[28:29]
	v_pk_mul_f32 v[76:77], v[86:87], v[76:77]
	v_pk_fma_f32 v[82:83], v[20:21], v[108:109], v[82:83]
	v_cvt_pk_bf16_f32 v137, v76, v77
	v_pk_fma_f32 v[82:83], v[24:25], v[92:93], v[82:83]
	v_pk_fma_f32 v[86:87], v[0:1], v[94:95], v[16:17]
	v_mul_f32_e32 v67, 0xbfb8aa3b, v82
	v_exp_f32_e32 v67, v67
	v_mul_f32_e32 v71, 0xbfb8aa3b, v83
	v_exp_f32_e32 v71, v71
	v_pk_fma_f32 v[86:87], v[4:5], v[80:81], v[86:87]
	v_add_f32_e32 v67, 1.0, v67
	v_rcp_f32_e32 v76, v67
	v_add_f32_e32 v67, 1.0, v71
	v_rcp_f32_e32 v77, v67
	v_pk_fma_f32 v[86:87], v[8:9], v[78:79], v[86:87]
	v_mov_b32_e32 v94, 0
	v_mov_b32_e32 v95, 0
	v_pk_mul_f32 v[76:77], v[82:83], v[76:77]
	v_pk_fma_f32 v[82:83], v[14:15], v[98:99], v[30:31]
	v_pk_mul_f32 v[76:77], v[86:87], v[76:77]
	v_pk_fma_f32 v[82:83], v[22:23], v[96:97], v[82:83]
	v_cvt_pk_bf16_f32 v138, v76, v77
	v_pk_fma_f32 v[82:83], v[26:27], v[84:85], v[82:83]
	v_pk_fma_f32 v[86:87], v[2:3], v[88:89], v[18:19]
	v_mul_f32_e32 v67, 0xbfb8aa3b, v82
	v_exp_f32_e32 v67, v67
	v_mul_f32_e32 v71, 0xbfb8aa3b, v83
	v_exp_f32_e32 v71, v71
	v_pk_fma_f32 v[86:87], v[6:7], v[74:75], v[86:87]
	v_add_f32_e32 v67, 1.0, v67
	v_rcp_f32_e32 v76, v67
	v_add_f32_e32 v67, 1.0, v71
	v_rcp_f32_e32 v77, v67
	v_pk_fma_f32 v[86:87], v[10:11], v[72:73], v[86:87]
	v_add_u32_e32 v67, s0, v70
	v_mov_b64_e32 v[70:71], s[16:17]
	v_pk_mul_f32 v[76:77], v[82:83], v[76:77]
	v_mad_i64_i32 v[70:71], s[2:3], v67, s54, v[70:71]
	v_pk_mul_f32 v[76:77], v[86:87], v[76:77]
	v_lshl_add_u64 v[70:71], v[64:65], 1, v[70:71]
	v_cvt_pk_bf16_f32 v139, v76, v77
	global_store_dwordx4 v[70:71], v[136:139], off sc1
	v_mov_b32_e32 v67, 0
	v_mov_b32_e32 v86, 0
	v_mov_b32_e32 v87, 0
	v_mov_b32_e32 v76, 0
	v_mov_b32_e32 v77, 0
	v_mov_b32_e32 v70, 0
	v_mov_b32_e32 v71, 0
	v_mov_b32_e32 v98, 0
	v_mov_b32_e32 v99, 0
	v_mov_b32_e32 v88, 0
	v_mov_b32_e32 v89, 0
	v_mov_b32_e32 v82, 0
	v_mov_b32_e32 v83, 0
	s_and_saveexec_b64 s[4:5], vcc
	s_cbranch_execz .LBB0_755
	v_lshl_add_u32 v66, v107, 9, 0
	v_bitop3_b32 v67, v107, v146, 30 bitop3:0x6c
	v_lshl_add_u32 v67, v67, 4, v66
	ds_read_b128 v[134:137], v67
	v_bitop3_b32 v67, v107, v132, 30 bitop3:0x6c
	v_lshl_add_u32 v66, v67, 4, v66
	ds_read_b128 v[138:141], v66
	s_waitcnt lgkmcnt(1)
	v_lshlrev_b32_e32 v98, 16, v134
	v_and_b32_e32 v99, 0xffff0000, v134
	v_lshlrev_b32_e32 v94, 16, v135
	s_waitcnt lgkmcnt(0)
	v_lshlrev_b32_e32 v66, 16, v138
	v_and_b32_e32 v67, 0xffff0000, v138
	v_and_b32_e32 v95, 0xffff0000, v135
	v_lshlrev_b32_e32 v86, 16, v139
	v_and_b32_e32 v87, 0xffff0000, v139
	v_lshlrev_b32_e32 v88, 16, v136
	v_and_b32_e32 v89, 0xffff0000, v136
	v_lshlrev_b32_e32 v76, 16, v140
	v_and_b32_e32 v77, 0xffff0000, v140
	v_lshlrev_b32_e32 v82, 16, v137
	v_and_b32_e32 v83, 0xffff0000, v137
	v_lshlrev_b32_e32 v70, 16, v141
	v_and_b32_e32 v71, 0xffff0000, v141
; DI unsigned cvtpk(float lo, float hi) { f32x2 v = {lo, hi}; bf16x2_t b = __builtin_convertvector(v, bf16x2_t); return __builtin_bit_cast(unsigned, b); }
; DI float silu_(float x) { return x * sigm(x); }
;     __device__ __forceinline__ void fused(f32x4 (&acc)[2][2][4][2], const Unit& u, int wr, int wc, int fr, int fq, PG8_LAS unsigned char* lds, int wid, int lane) const {
;     ...
;         for (int i8 = 0; i8 < 8; ++i8) { const int r = rg * 8 + i8;
;             CONV_LD(na, nb, r + 1);
;             u32x4 o;
; #pragma unroll
;             for (int i = 0; i < 4; ++i) {
;                 const float a0 = ba[2 * i] + wa[0][2 * i] * pa[2 * i] + wa[1][2 * i] * ca[2 * i] + wa[2][2 * i] * na[2 * i];
;                 const float a1 = ba[2 * i + 1] + wa[0][2 * i + 1] * pa[2 * i + 1] + wa[1][2 * i + 1] * ca[2 * i + 1] + wa[2][2 * i + 1] * na[2 * i + 1];
;                 const float b0 = bb[2 * i] + wb[0][2 * i] * pb[2 * i] + wb[1][2 * i] * cb[2 * i] + wb[2][2 * i] * nb[2 * i];
;                 const float b1 = bb[2 * i + 1] + wb[0][2 * i + 1] * pb[2 * i + 1] + wb[1][2 * i + 1] * cb[2 * i + 1] + wb[2][2 * i + 1] * nb[2 * i + 1];
;                 o[i] = cvtpk(silu_(a0) * b0, silu_(a1) * b1); }
;             *(u32x4*)(Gt + (size_t)(u.pm * BM + r) * FF + f) = o;
; #pragma unroll
;             for (int i = 0; i < 8; ++i) { pa[i] = ca[i]; pb[i] = cb[i]; ca[i] = na[i]; cb[i] = nb[i]; } }
.LBB0_755:
	s_or_b64 exec, exec, s[4:5]
	v_pk_fma_f32 v[110:111], v[44:45], v[122:123], v[60:61]
	v_pk_fma_f32 v[68:69], v[32:33], v[68:69], v[48:49]
	v_pk_fma_f32 v[110:111], v[56:57], v[112:113], v[110:111]
	v_pk_fma_f32 v[68:69], v[36:37], v[100:101], v[68:69]
	v_pk_fma_f32 v[110:111], v[52:53], v[98:99], v[110:111]
	v_pk_fma_f32 v[68:69], v[40:41], v[66:67], v[68:69]
	v_mul_f32_e32 v106, 0xbfb8aa3b, v110
	v_mul_f32_e32 v114, 0xbfb8aa3b, v111
	v_exp_f32_e32 v106, v106
	v_exp_f32_e32 v114, v114
	v_pk_fma_f32 v[104:105], v[34:35], v[104:105], v[50:51]
	v_pk_fma_f32 v[80:81], v[0:1], v[80:81], v[16:17]
	v_add_f32_e32 v106, 1.0, v106
	v_add_f32_e32 v115, 1.0, v114
	v_rcp_f32_e32 v114, v106
	v_rcp_f32_e32 v115, v115
	v_pk_fma_f32 v[104:105], v[38:39], v[90:91], v[104:105]
	v_pk_fma_f32 v[80:81], v[4:5], v[78:79], v[80:81]
	v_pk_fma_f32 v[104:105], v[42:43], v[86:87], v[104:105]
	v_pk_mul_f32 v[110:111], v[110:111], v[114:115]
	v_pk_fma_f32 v[80:81], v[8:9], v[76:77], v[80:81]
	v_pk_mul_f32 v[68:69], v[68:69], v[110:111]
	v_pk_fma_f32 v[110:111], v[46:47], v[116:117], v[62:63]
	v_pk_fma_f32 v[74:75], v[2:3], v[74:75], v[18:19]
	v_pk_fma_f32 v[110:111], v[58:59], v[102:103], v[110:111]
	v_pk_fma_f32 v[74:75], v[6:7], v[72:73], v[74:75]
	v_pk_fma_f32 v[110:111], v[54:55], v[94:95], v[110:111]
	v_pk_fma_f32 v[74:75], v[10:11], v[70:71], v[74:75]
	v_mul_f32_e32 v106, 0xbfb8aa3b, v110
	v_mul_f32_e32 v114, 0xbfb8aa3b, v111
	v_exp_f32_e32 v106, v106
	v_exp_f32_e32 v115, v114
	v_cvt_pk_bf16_f32 v114, v68, v69
	v_add_f32_e32 v68, 1.0, v106
	v_add_f32_e32 v69, 1.0, v115
	v_rcp_f32_e32 v68, v68
	v_rcp_f32_e32 v69, v69
	s_nop 0
	v_pk_mul_f32 v[68:69], v[110:111], v[68:69]
	s_nop 0
	v_pk_mul_f32 v[68:69], v[104:105], v[68:69]
	v_pk_fma_f32 v[104:105], v[12:13], v[108:109], v[28:29]
	v_cvt_pk_bf16_f32 v115, v68, v69
	v_pk_fma_f32 v[104:105], v[20:21], v[92:93], v[104:105]
	v_mov_b32_e32 v109, 0
	v_pk_fma_f32 v[104:105], v[24:25], v[88:89], v[104:105]
	v_mov_b32_e32 v110, 0
	v_mul_f32_e32 v106, 0xbfb8aa3b, v104
	v_mul_f32_e32 v108, 0xbfb8aa3b, v105
	v_exp_f32_e32 v106, v106
	v_exp_f32_e32 v108, v108
	v_mov_b32_e32 v111, 0
	v_add_f32_e32 v68, 1.0, v106
	v_add_f32_e32 v69, 1.0, v108
	v_rcp_f32_e32 v68, v68
	v_rcp_f32_e32 v69, v69
	v_mov_b32_e32 v106, 0
	v_mov_b32_e32 v108, 0
	v_pk_mul_f32 v[68:69], v[104:105], v[68:69]
	s_nop 0
	v_pk_mul_f32 v[68:69], v[80:81], v[68:69]
	v_pk_fma_f32 v[80:81], v[14:15], v[96:97], v[30:31]
	v_cvt_pk_bf16_f32 v116, v68, v69
	v_pk_fma_f32 v[80:81], v[22:23], v[84:85], v[80:81]
	v_mov_b32_e32 v104, 0
	v_pk_fma_f32 v[80:81], v[26:27], v[82:83], v[80:81]
	v_mov_b32_e32 v105, 0
	v_mul_f32_e32 v96, 0xbfb8aa3b, v80
	v_mul_f32_e32 v97, 0xbfb8aa3b, v81
	v_exp_f32_e32 v96, v96
	v_exp_f32_e32 v97, v97
	v_add_f32_e32 v68, 1.0, v96
	v_add_f32_e32 v69, 1.0, v97
	v_rcp_f32_e32 v68, v68
	v_rcp_f32_e32 v69, v69
	v_mov_b32_e32 v96, 0
	v_mov_b32_e32 v97, 0
	v_pk_mul_f32 v[68:69], v[80:81], v[68:69]
	s_nop 0
	v_pk_mul_f32 v[68:69], v[74:75], v[68:69]
	v_add_u32_e32 v74, s0, v120
	v_cvt_pk_bf16_f32 v117, v68, v69
	v_mov_b64_e32 v[68:69], s[16:17]
	v_mad_i64_i32 v[68:69], s[2:3], v74, s54, v[68:69]
	v_lshl_add_u64 v[68:69], v[64:65], 1, v[68:69]
	global_store_dwordx4 v[68:69], v[114:117], off sc1
	v_mov_b32_e32 v74, 0
	v_mov_b32_e32 v75, 0
	v_or_b32_e32 v116, 7, v127
	v_mov_b32_e32 v68, 0
	v_mov_b32_e32 v69, 0
	v_mov_b32_e32 v114, 0
	v_mov_b32_e32 v115, 0
	v_mov_b32_e32 v80, 0
	v_mov_b32_e32 v81, 0
	s_and_saveexec_b64 s[4:5], vcc
	s_cbranch_execz .LBB0_757
	v_lshl_add_u32 v68, v116, 9, 0
	v_bitop3_b32 v69, v116, v146, 31 bitop3:0x6c
	v_lshl_add_u32 v69, v69, 4, v68
	ds_read_b128 v[118:121], v69
	v_bitop3_b32 v69, v116, v132, 31 bitop3:0x6c
	v_lshl_add_u32 v68, v69, 4, v68
	ds_read_b128 v[122:125], v68
	s_waitcnt lgkmcnt(1)
	v_lshlrev_b32_e32 v114, 16, v118
	v_and_b32_e32 v115, 0xffff0000, v118
	v_lshlrev_b32_e32 v110, 16, v119
	s_waitcnt lgkmcnt(0)
	v_lshlrev_b32_e32 v108, 16, v122
	v_and_b32_e32 v109, 0xffff0000, v122
	v_and_b32_e32 v111, 0xffff0000, v119
	v_lshlrev_b32_e32 v96, 16, v123
	v_and_b32_e32 v97, 0xffff0000, v123
	v_lshlrev_b32_e32 v104, 16, v120
	v_and_b32_e32 v105, 0xffff0000, v120
	v_lshlrev_b32_e32 v74, 16, v124
	v_and_b32_e32 v75, 0xffff0000, v124
	v_lshlrev_b32_e32 v80, 16, v121
	v_and_b32_e32 v81, 0xffff0000, v121
	v_lshlrev_b32_e32 v68, 16, v125
	v_and_b32_e32 v69, 0xffff0000, v125
; DI unsigned cvtpk(float lo, float hi) { f32x2 v = {lo, hi}; bf16x2_t b = __builtin_convertvector(v, bf16x2_t); return __builtin_bit_cast(unsigned, b); }
; DI float silu_(float x) { return x * sigm(x); }
;     __device__ __forceinline__ void fused(f32x4 (&acc)[2][2][4][2], const Unit& u, int wr, int wc, int fr, int fq, PG8_LAS unsigned char* lds, int wid, int lane) const {
;     ...
;         for (int i8 = 0; i8 < 8; ++i8) { const int r = rg * 8 + i8;
;             CONV_LD(na, nb, r + 1);
;             u32x4 o;
; #pragma unroll
;             for (int i = 0; i < 4; ++i) {
;                 const float a0 = ba[2 * i] + wa[0][2 * i] * pa[2 * i] + wa[1][2 * i] * ca[2 * i] + wa[2][2 * i] * na[2 * i];
;                 const float a1 = ba[2 * i + 1] + wa[0][2 * i + 1] * pa[2 * i + 1] + wa[1][2 * i + 1] * ca[2 * i + 1] + wa[2][2 * i + 1] * na[2 * i + 1];
;                 const float b0 = bb[2 * i] + wb[0][2 * i] * pb[2 * i] + wb[1][2 * i] * cb[2 * i] + wb[2][2 * i] * nb[2 * i];
;                 const float b1 = bb[2 * i + 1] + wb[0][2 * i + 1] * pb[2 * i + 1] + wb[1][2 * i + 1] * cb[2 * i + 1] + wb[2][2 * i + 1] * nb[2 * i + 1];
;                 o[i] = cvtpk(silu_(a0) * b0, silu_(a1) * b1); }
;             *(u32x4*)(Gt + (size_t)(u.pm * BM + r) * FF + f) = o;
; #pragma unroll
;             for (int i = 0; i < 8; ++i) { pa[i] = ca[i]; pb[i] = cb[i]; ca[i] = na[i]; cb[i] = nb[i]; } }
.LBB0_757:
	s_or_b64 exec, exec, s[4:5]
	v_pk_fma_f32 v[112:113], v[44:45], v[112:113], v[60:61]
	v_pk_fma_f32 v[100:101], v[32:33], v[100:101], v[48:49]
	v_pk_fma_f32 v[112:113], v[56:57], v[98:99], v[112:113]
	v_pk_fma_f32 v[102:103], v[46:47], v[102:103], v[62:63]
	v_pk_fma_f32 v[112:113], v[52:53], v[114:115], v[112:113]
	v_pk_fma_f32 v[100:101], v[36:37], v[66:67], v[100:101]
	v_mul_f32_e32 v117, 0xbfb8aa3b, v112
	v_mul_f32_e32 v118, 0xbfb8aa3b, v113
	v_exp_f32_e32 v117, v117
	v_exp_f32_e32 v118, v118
	v_pk_fma_f32 v[102:103], v[58:59], v[94:95], v[102:103]
	v_pk_fma_f32 v[100:101], v[40:41], v[108:109], v[100:101]
	v_add_f32_e32 v117, 1.0, v117
	v_add_f32_e32 v119, 1.0, v118
	v_rcp_f32_e32 v118, v117
	v_rcp_f32_e32 v119, v119
	v_pk_fma_f32 v[102:103], v[54:55], v[110:111], v[102:103]
	v_pk_fma_f32 v[92:93], v[12:13], v[92:93], v[28:29]
	v_pk_fma_f32 v[90:91], v[34:35], v[90:91], v[50:51]
	v_pk_mul_f32 v[112:113], v[112:113], v[118:119]
	v_pk_fma_f32 v[92:93], v[20:21], v[88:89], v[92:93]
	v_pk_mul_f32 v[100:101], v[100:101], v[112:113]
	v_mul_f32_e32 v112, 0xbfb8aa3b, v102
	v_exp_f32_e32 v112, v112
	v_mul_f32_e32 v113, 0xbfb8aa3b, v103
	v_exp_f32_e32 v113, v113
	v_cvt_pk_bf16_f32 v100, v100, v101
	v_add_f32_e32 v101, 1.0, v112
	v_rcp_f32_e32 v112, v101
	v_add_f32_e32 v101, 1.0, v113
	v_rcp_f32_e32 v113, v101
	v_pk_fma_f32 v[90:91], v[38:39], v[86:87], v[90:91]
	v_pk_fma_f32 v[92:93], v[24:25], v[104:105], v[92:93]
	v_pk_fma_f32 v[90:91], v[42:43], v[96:97], v[90:91]
	v_pk_mul_f32 v[102:103], v[102:103], v[112:113]
	v_mul_f32_e32 v101, 0xbfb8aa3b, v92
	v_pk_mul_f32 v[90:91], v[90:91], v[102:103]
	v_exp_f32_e32 v102, v101
	v_mul_f32_e32 v101, 0xbfb8aa3b, v93
	v_exp_f32_e32 v103, v101
	v_cvt_pk_bf16_f32 v101, v90, v91
	v_add_f32_e32 v90, 1.0, v102
	v_rcp_f32_e32 v90, v90
	v_add_f32_e32 v91, 1.0, v103
	v_rcp_f32_e32 v91, v91
	v_pk_fma_f32 v[78:79], v[0:1], v[78:79], v[16:17]
	v_pk_fma_f32 v[84:85], v[14:15], v[84:85], v[30:31]
	v_pk_fma_f32 v[78:79], v[4:5], v[76:77], v[78:79]
	v_pk_fma_f32 v[84:85], v[22:23], v[82:83], v[84:85]
	v_pk_fma_f32 v[78:79], v[8:9], v[74:75], v[78:79]
	v_pk_mul_f32 v[90:91], v[92:93], v[90:91]
	v_pk_fma_f32 v[84:85], v[26:27], v[80:81], v[84:85]
	v_pk_mul_f32 v[78:79], v[78:79], v[90:91]
	v_mul_f32_e32 v90, 0xbfb8aa3b, v84
	v_mul_f32_e32 v91, 0xbfb8aa3b, v85
	v_exp_f32_e32 v90, v90
	v_exp_f32_e32 v91, v91
	v_cvt_pk_bf16_f32 v102, v78, v79
	v_pk_fma_f32 v[72:73], v[2:3], v[72:73], v[18:19]
	v_add_f32_e32 v78, 1.0, v90
	v_add_f32_e32 v79, 1.0, v91
	v_rcp_f32_e32 v78, v78
	v_rcp_f32_e32 v79, v79
	v_pk_fma_f32 v[72:73], v[6:7], v[70:71], v[72:73]
	v_add_u32_e32 v112, 1, v116
	v_pk_fma_f32 v[72:73], v[10:11], v[68:69], v[72:73]
	v_pk_mul_f32 v[78:79], v[84:85], v[78:79]
	v_cmp_gt_u32_e32 vcc, s53, v112
	v_pk_mul_f32 v[72:73], v[72:73], v[78:79]
	v_add_u32_e32 v78, s0, v107
	v_cvt_pk_bf16_f32 v103, v72, v73
	v_mov_b64_e32 v[72:73], s[16:17]
	v_mad_i64_i32 v[72:73], s[2:3], v78, s54, v[72:73]
	v_lshl_add_u64 v[72:73], v[64:65], 1, v[72:73]
	global_store_dwordx4 v[72:73], v[100:103], off sc1
	v_mov_b32_e32 v107, 0
	v_mov_b32_e32 v90, 0
	v_mov_b32_e32 v91, 0
	v_mov_b32_e32 v78, 0
	v_mov_b32_e32 v79, 0
	v_mov_b32_e32 v72, 0
	v_mov_b32_e32 v73, 0
	v_mov_b32_e32 v102, 0
	v_mov_b32_e32 v103, 0
	v_mov_b32_e32 v100, 0
	v_mov_b32_e32 v101, 0
	v_mov_b32_e32 v92, 0
	v_mov_b32_e32 v93, 0
	v_mov_b32_e32 v84, 0
	v_mov_b32_e32 v85, 0
	s_and_saveexec_b64 s[4:5], vcc
	s_cbranch_execz .LBB0_759
	v_lshl_add_u32 v72, v112, 9, 0
	v_bitop3_b32 v73, v112, v146, 24 bitop3:0x6c
	v_lshl_add_u32 v73, v73, 4, v72
	ds_read_b128 v[118:121], v73
	v_bitop3_b32 v73, v112, v132, 24 bitop3:0x6c
	v_lshl_add_u32 v72, v73, 4, v72
	ds_read_b128 v[122:125], v72
	s_waitcnt lgkmcnt(1)
	v_lshlrev_b32_e32 v102, 16, v118
	v_and_b32_e32 v103, 0xffff0000, v118
	v_lshlrev_b32_e32 v100, 16, v119
	s_waitcnt lgkmcnt(0)
	v_lshlrev_b32_e32 v106, 16, v122
	v_and_b32_e32 v107, 0xffff0000, v122
	v_and_b32_e32 v101, 0xffff0000, v119
	v_lshlrev_b32_e32 v90, 16, v123
	v_and_b32_e32 v91, 0xffff0000, v123
	v_lshlrev_b32_e32 v92, 16, v120
	v_and_b32_e32 v93, 0xffff0000, v120
	v_lshlrev_b32_e32 v78, 16, v124
	v_and_b32_e32 v79, 0xffff0000, v124
	v_lshlrev_b32_e32 v84, 16, v121
	v_and_b32_e32 v85, 0xffff0000, v121
	v_lshlrev_b32_e32 v72, 16, v125
	v_and_b32_e32 v73, 0xffff0000, v125
; DI unsigned cvtpk(float lo, float hi) { f32x2 v = {lo, hi}; bf16x2_t b = __builtin_convertvector(v, bf16x2_t); return __builtin_bit_cast(unsigned, b); }
; DI float silu_(float x) { return x * sigm(x); }
; #define PG8_LAS __attribute__((address_space(3)))
;     __device__ __forceinline__ void fused(f32x4 (&acc)[2][2][4][2], const Unit& u, int wr, int wc, int fr, int fq, PG8_LAS unsigned char* lds, int wid, int lane) const {
;     ...
;                 const float a0 = ba[2 * i] + wa[0][2 * i] * pa[2 * i] + wa[1][2 * i] * ca[2 * i] + wa[2][2 * i] * na[2 * i];
;                 const float a1 = ba[2 * i + 1] + wa[0][2 * i + 1] * pa[2 * i + 1] + wa[1][2 * i + 1] * ca[2 * i + 1] + wa[2][2 * i + 1] * na[2 * i + 1];
;                 const float b0 = bb[2 * i] + wb[0][2 * i] * pb[2 * i] + wb[1][2 * i] * cb[2 * i] + wb[2][2 * i] * nb[2 * i];
;                 const float b1 = bb[2 * i + 1] + wb[0][2 * i + 1] * pb[2 * i + 1] + wb[1][2 * i + 1] * cb[2 * i + 1] + wb[2][2 * i + 1] * nb[2 * i + 1];
;                 o[i] = cvtpk(silu_(a0) * b0, silu_(a1) * b1); }
;             *(u32x4*)(Gt + (size_t)(u.pm * BM + r) * FF + f) = o;
; #pragma unroll
;             for (int i = 0; i < 8; ++i) { pa[i] = ca[i]; pb[i] = cb[i]; ca[i] = na[i]; cb[i] = nb[i]; } }
;     ...
;         if (t < 128) { const int rr = t >> 5, ch = t & 31, row = (rr < 2) ? rr : 252 + rr;
;             const u32x4 v = *(const PG8_LAS u32x4*)(lds + row * 512 + ((ch ^ (row & 31)) << 4));
;             *(u32x4*)(SIDE2 + ((size_t)(u.pm * 44 + u.pn) * 4 + rr) * 256 + ch * 8) = v; }
.LBB0_759:
	s_or_b64 exec, exec, s[4:5]
	v_pk_fma_f32 v[44:45], v[44:45], v[98:99], v[60:61]
	v_pk_fma_f32 v[12:13], v[12:13], v[88:89], v[28:29]
	v_pk_fma_f32 v[44:45], v[56:57], v[114:115], v[44:45]
	v_pk_fma_f32 v[12:13], v[20:21], v[104:105], v[12:13]
	v_pk_fma_f32 v[44:45], v[52:53], v[102:103], v[44:45]
	v_pk_fma_f32 v[12:13], v[24:25], v[92:93], v[12:13]
	v_mul_f32_e32 v52, 0xbfb8aa3b, v44
	v_mul_f32_e32 v53, 0xbfb8aa3b, v45
	v_exp_f32_e32 v52, v52
	v_exp_f32_e32 v53, v53
	v_pk_fma_f32 v[32:33], v[32:33], v[66:67], v[48:49]
	v_mul_f32_e32 v20, 0xbfb8aa3b, v12
	v_add_f32_e32 v52, 1.0, v52
	v_add_f32_e32 v53, 1.0, v53
	v_rcp_f32_e32 v52, v52
	v_rcp_f32_e32 v53, v53
	v_mul_f32_e32 v21, 0xbfb8aa3b, v13
	v_pk_fma_f32 v[32:33], v[36:37], v[108:109], v[32:33]
	v_exp_f32_e32 v20, v20
	v_exp_f32_e32 v21, v21
	v_pk_fma_f32 v[32:33], v[40:41], v[106:107], v[32:33]
	v_pk_mul_f32 v[36:37], v[44:45], v[52:53]
	v_add_f32_e32 v20, 1.0, v20
	v_pk_mul_f32 v[32:33], v[32:33], v[36:37]
	v_pk_fma_f32 v[36:37], v[46:47], v[94:95], v[62:63]
	v_add_f32_e32 v21, 1.0, v21
	v_pk_fma_f32 v[36:37], v[58:59], v[110:111], v[36:37]
	v_rcp_f32_e32 v20, v20
	v_pk_fma_f32 v[36:37], v[54:55], v[100:101], v[36:37]
	v_rcp_f32_e32 v21, v21
	v_mul_f32_e32 v40, 0xbfb8aa3b, v36
	v_exp_f32_e32 v40, v40
	v_mul_f32_e32 v41, 0xbfb8aa3b, v37
	v_exp_f32_e32 v41, v41
	v_pk_fma_f32 v[0:1], v[0:1], v[76:77], v[16:17]
	v_cvt_pk_bf16_f32 v32, v32, v33
	v_pk_fma_f32 v[0:1], v[4:5], v[74:75], v[0:1]
	v_pk_mul_f32 v[4:5], v[12:13], v[20:21]
	v_pk_fma_f32 v[0:1], v[8:9], v[78:79], v[0:1]
	v_add_f32_e32 v33, 1.0, v40
	v_pk_mul_f32 v[0:1], v[0:1], v[4:5]
	v_pk_fma_f32 v[4:5], v[14:15], v[82:83], v[30:31]
	v_rcp_f32_e32 v40, v33
	v_add_f32_e32 v33, 1.0, v41
	v_pk_fma_f32 v[4:5], v[22:23], v[80:81], v[4:5]
	v_rcp_f32_e32 v41, v33
	v_pk_fma_f32 v[4:5], v[26:27], v[84:85], v[4:5]
	v_pk_fma_f32 v[34:35], v[34:35], v[86:87], v[50:51]
	v_mul_f32_e32 v8, 0xbfb8aa3b, v4
	v_mul_f32_e32 v9, 0xbfb8aa3b, v5
	v_exp_f32_e32 v8, v8
	v_exp_f32_e32 v9, v9
	v_pk_fma_f32 v[34:35], v[38:39], v[96:97], v[34:35]
	v_pk_mul_f32 v[36:37], v[36:37], v[40:41]
	v_pk_fma_f32 v[34:35], v[42:43], v[90:91], v[34:35]
	v_pk_fma_f32 v[2:3], v[2:3], v[70:71], v[18:19]
	v_pk_mul_f32 v[34:35], v[34:35], v[36:37]
	v_pk_fma_f32 v[2:3], v[6:7], v[68:69], v[2:3]
	v_cvt_pk_bf16_f32 v33, v34, v35
	v_cvt_pk_bf16_f32 v34, v0, v1
	v_add_f32_e32 v0, 1.0, v8
	v_add_f32_e32 v1, 1.0, v9
	v_rcp_f32_e32 v0, v0
	v_rcp_f32_e32 v1, v1
	v_pk_fma_f32 v[2:3], v[10:11], v[72:73], v[2:3]
	v_cmp_gt_i32_e32 vcc, s55, v126
	v_pk_mul_f32 v[0:1], v[4:5], v[0:1]
	s_nop 0
	v_pk_mul_f32 v[0:1], v[2:3], v[0:1]
	v_add_u32_e32 v2, s0, v116
	v_cvt_pk_bf16_f32 v35, v0, v1
	v_mov_b64_e32 v[0:1], s[16:17]
	v_mad_i64_i32 v[0:1], s[2:3], v2, s54, v[0:1]
	v_lshl_add_u64 v[0:1], v[64:65], 1, v[0:1]
	global_store_dwordx4 v[0:1], v[32:35], off sc1
	s_and_saveexec_b64 s[4:5], vcc
	s_cbranch_execz .LBB0_728
	v_ashrrev_i32_e32 v4, 5, v126
	v_add_u32_e32 v0, 0xfc, v4
	v_cmp_gt_i32_e32 vcc, 2, v4
	v_and_b32_e32 v6, 63, v145
	s_mul_i32 s0, s27, 44
	v_cndmask_b32_e32 v0, v0, v4, vcc
	v_lshlrev_b32_e32 v1, 9, v0
	v_xor_b32_e32 v0, v0, v6
	v_lshlrev_b32_e32 v0, 4, v0
	v_and_b32_e32 v0, 0x1f0, v0
	v_add3_u32 v0, 0, v1, v0
	s_add_i32 s3, s0, s19
	s_mov_b32 s2, s18
	ds_read_b128 v[0:3], v0
	s_ashr_i64 s[2:3], s[2:3], 21
	v_ashrrev_i32_e32 v5, 31, v4
	s_add_u32 s2, s41, s2
	s_addc_u32 s3, s42, s3
	v_lshlrev_b64 v[4:5], 9, v[4:5]
	v_lshlrev_b32_e32 v6, 4, v6
	v_lshl_add_u64 v[4:5], s[2:3], 0, v[4:5]
	v_and_b32_e32 v132, 0x1f0, v6
	v_lshl_add_u64 v[4:5], v[4:5], 0, v[132:133]
	s_waitcnt lgkmcnt(0)
	global_store_dwordx4 v[4:5], v[0:3], off sc1
	s_branch .LBB0_728

; DI unsigned cvtpk(float lo, float hi) { f32x2 v = {lo, hi}; bf16x2_t b = __builtin_convertvector(v, bf16x2_t); return __builtin_bit_cast(unsigned, b); }
; DI float bflo(unsigned w) { return __uint_as_float(w << 16); }
; DI float bfhi(unsigned w) { return __uint_as_float(w & 0xffff0000u); }
; DI float silu_(float x) { return x * sigm(x); }
; __global__ void __launch_bounds__(512, 2) fwd_megakernel(Params p_unused) {
;     ...
;     u32x4v o;
; #pragma unroll
;     for (int i = 0; i < 4; ++i) {
;       const float a0 = ba[2 * i] + wa[0][2 * i] * bflo(pa[i]) + wa[1][2 * i] * bflo(ca[i]) + wa[2][2 * i] * bflo(na[i]);
;       const float a1 = ba[2 * i + 1] + wa[0][2 * i + 1] * bfhi(pa[i]) + wa[1][2 * i + 1] * bfhi(ca[i]) + wa[2][2 * i + 1] * bfhi(na[i]);
;       const float b0 = bb[2 * i] + wb[0][2 * i] * bflo(pb[i]) + wb[1][2 * i] * bflo(cb[i]) + wb[2][2 * i] * bflo(nb[i]);
;       const float b1 = bb[2 * i + 1] + wb[0][2 * i + 1] * bfhi(pb[i]) + wb[1][2 * i + 1] * bfhi(cb[i]) + wb[2][2 * i + 1] * bfhi(nb[i]);
;       o[i] = cvtpk(silu_(a0) * b0, silu_(a1) * b1); }
;     *(u32x4v*)(U + (size_t)(pm * 256 + (which ? 255 : 0)) * FF + f) = o;
.LBB0_817:
	s_waitcnt vmcnt(3)
	v_lshlrev_b32_e32 v96, 16, v60
	v_and_b32_e32 v97, 0xffff0000, v60
	s_waitcnt vmcnt(0)
	v_pk_fma_f32 v[64:65], v[64:65], v[96:97], v[84:85]
	v_lshlrev_b32_e32 v84, 16, v72
	v_and_b32_e32 v85, 0xffff0000, v72
	v_pk_fma_f32 v[64:65], v[76:77], v[84:85], v[64:65]
	v_lshlrev_b32_e32 v76, 16, v68
	v_and_b32_e32 v77, 0xffff0000, v68
	v_pk_fma_f32 v[64:65], v[80:81], v[76:77], v[64:65]
	v_lshlrev_b32_e32 v76, 16, v36
	v_and_b32_e32 v77, 0xffff0000, v36
	v_mul_f32_e32 v36, 0xbfb8aa3b, v64
	v_pk_fma_f32 v[32:33], v[32:33], v[76:77], v[48:49]
	v_lshlrev_b32_e32 v48, 16, v56
	v_and_b32_e32 v49, 0xffff0000, v56
	v_exp_f32_e32 v36, v36
	v_mul_f32_e32 v56, 0xbfb8aa3b, v65
	v_exp_f32_e32 v56, v56
	v_pk_fma_f32 v[32:33], v[40:41], v[48:49], v[32:33]
	v_add_f32_e32 v36, 1.0, v36
	v_rcp_f32_e32 v40, v36
	v_add_f32_e32 v36, 1.0, v56
	v_rcp_f32_e32 v41, v36
	v_lshlrev_b32_e32 v48, 16, v44
	v_and_b32_e32 v49, 0xffff0000, v44
	v_pk_fma_f32 v[32:33], v[52:53], v[48:49], v[32:33]
	v_pk_mul_f32 v[40:41], v[64:65], v[40:41]
	v_lshlrev_b32_e32 v48, 16, v73
	v_pk_mul_f32 v[32:33], v[40:41], v[32:33]
	v_lshlrev_b32_e32 v40, 16, v61
	v_and_b32_e32 v41, 0xffff0000, v61
	v_pk_fma_f32 v[40:41], v[66:67], v[40:41], v[86:87]
	v_and_b32_e32 v49, 0xffff0000, v73
	v_pk_fma_f32 v[40:41], v[78:79], v[48:49], v[40:41]
	v_lshlrev_b32_e32 v48, 16, v69
	v_and_b32_e32 v49, 0xffff0000, v69
	v_pk_fma_f32 v[40:41], v[82:83], v[48:49], v[40:41]
	v_cvt_pk_bf16_f32 v32, v32, v33
	v_mul_f32_e32 v33, 0xbfb8aa3b, v40
	v_exp_f32_e32 v33, v33
	v_mul_f32_e32 v44, 0xbfb8aa3b, v41
	v_exp_f32_e32 v44, v44
	v_lshlrev_b32_e32 v36, 16, v37
	v_and_b32_e32 v37, 0xffff0000, v37
	v_pk_fma_f32 v[34:35], v[34:35], v[36:37], v[50:51]
	v_lshlrev_b32_e32 v36, 16, v57
	v_and_b32_e32 v37, 0xffff0000, v57
	v_add_f32_e32 v33, 1.0, v33
	v_pk_fma_f32 v[34:35], v[42:43], v[36:37], v[34:35]
	v_rcp_f32_e32 v36, v33
	v_add_f32_e32 v33, 1.0, v44
	v_rcp_f32_e32 v37, v33
	v_lshlrev_b32_e32 v42, 16, v45
	v_and_b32_e32 v43, 0xffff0000, v45
	v_pk_fma_f32 v[34:35], v[54:55], v[42:43], v[34:35]
	v_pk_mul_f32 v[36:37], v[40:41], v[36:37]
	s_lshl_b32 s25, s33, 8
	v_pk_mul_f32 v[34:35], v[36:37], v[34:35]
	s_or_b32 s24, s24, s25
	v_cvt_pk_bf16_f32 v33, v34, v35
	v_lshlrev_b32_e32 v34, 16, v62
	v_and_b32_e32 v35, 0xffff0000, v62
	v_pk_fma_f32 v[16:17], v[16:17], v[34:35], v[28:29]
	v_lshlrev_b32_e32 v28, 16, v74
	v_and_b32_e32 v29, 0xffff0000, v74
	v_pk_fma_f32 v[16:17], v[20:21], v[28:29], v[16:17]
	v_lshlrev_b32_e32 v20, 16, v70
	v_and_b32_e32 v21, 0xffff0000, v70
	v_pk_fma_f32 v[16:17], v[24:25], v[20:21], v[16:17]
	v_lshlrev_b32_e32 v20, 16, v38
	v_and_b32_e32 v21, 0xffff0000, v38
	v_pk_fma_f32 v[0:1], v[0:1], v[20:21], v[4:5]
	v_mul_f32_e32 v20, 0xbfb8aa3b, v16
	v_mul_f32_e32 v21, 0xbfb8aa3b, v17
	v_exp_f32_e32 v20, v20
	v_exp_f32_e32 v21, v21
	v_lshlrev_b32_e32 v4, 16, v58
	v_and_b32_e32 v5, 0xffff0000, v58
	v_pk_fma_f32 v[0:1], v[8:9], v[4:5], v[0:1]
	v_add_f32_e32 v4, 1.0, v20
	v_add_f32_e32 v5, 1.0, v21
	v_rcp_f32_e32 v4, v4
	v_rcp_f32_e32 v5, v5
	v_lshlrev_b32_e32 v8, 16, v46
	v_and_b32_e32 v9, 0xffff0000, v46
	v_pk_fma_f32 v[0:1], v[12:13], v[8:9], v[0:1]
	v_pk_mul_f32 v[4:5], v[16:17], v[4:5]
	s_mul_hi_i32 s25, s24, 0x2c00
	v_pk_mul_f32 v[0:1], v[4:5], v[0:1]
	v_lshlrev_b32_e32 v4, 16, v75
	v_cvt_pk_bf16_f32 v34, v0, v1
	v_lshlrev_b32_e32 v0, 16, v63
	v_and_b32_e32 v1, 0xffff0000, v63
	v_pk_fma_f32 v[0:1], v[18:19], v[0:1], v[30:31]
	v_and_b32_e32 v5, 0xffff0000, v75
	v_pk_fma_f32 v[0:1], v[22:23], v[4:5], v[0:1]
	v_lshlrev_b32_e32 v4, 16, v71
	v_and_b32_e32 v5, 0xffff0000, v71
	v_pk_fma_f32 v[0:1], v[26:27], v[4:5], v[0:1]
	v_lshlrev_b32_e32 v4, 16, v39
	v_and_b32_e32 v5, 0xffff0000, v39
	v_pk_fma_f32 v[2:3], v[2:3], v[4:5], v[6:7]
	v_mul_f32_e32 v6, 0xbfb8aa3b, v0
	v_mul_f32_e32 v7, 0xbfb8aa3b, v1
	v_exp_f32_e32 v6, v6
	v_exp_f32_e32 v7, v7
	v_lshlrev_b32_e32 v4, 16, v59
	v_and_b32_e32 v5, 0xffff0000, v59
	v_pk_fma_f32 v[2:3], v[10:11], v[4:5], v[2:3]
	v_add_f32_e32 v4, 1.0, v6
	v_add_f32_e32 v5, 1.0, v7
	v_rcp_f32_e32 v4, v4
	v_rcp_f32_e32 v5, v5
	v_lshlrev_b32_e32 v6, 16, v47
	v_and_b32_e32 v7, 0xffff0000, v47
	s_mulk_i32 s24, 0x2c00
	v_pk_fma_f32 v[2:3], v[14:15], v[6:7], v[2:3]
	v_pk_mul_f32 v[0:1], v[0:1], v[4:5]
	s_add_u32 s24, s1, s24
	v_pk_mul_f32 v[0:1], v[0:1], v[2:3]
	s_addc_u32 s25, s2, s25
	s_add_i32 s0, s0, s74
	v_cvt_pk_bf16_f32 v35, v0, v1
	v_lshl_add_u64 v[0:1], v[94:95], 1, s[24:25]
	v_add_u32_e32 v89, s3, v89
	s_cmpk_gt_i32 s0, 0x57f
	v_add_u32_e32 v100, s26, v100
	global_store_dwordx4 v[0:1], v[32:35], off sc1
	s_cbranch_scc1 .LBB0_825

;     __device__ __forceinline__ void operator()(const f32x4 (&acc)[2][2][4][2], const Unit& u, int wr, int wc, int fr, int fq) const {
;         const int row0 = u.pm * BM + wr * 64 + fr, col0 = u.pn * BM + wc * 32 + 4 * fq;
;         const float* gb = gate + (size_t)(u.pm >> 3) * NIN;
;         f32x4 gv[2][2];
; #pragma unroll
;         for (int bj = 0; bj < 2; ++bj)
; #pragma unroll
;             for (int n = 0; n < 2; ++n) gv[bj][n] = *(const f32x4*)(gb + col0 + bj * HALF + n * 16);
; #pragma unroll
;         for (int ai = 0; ai < 2; ++ai)
; #pragma unroll
;             for (int m = 0; m < 4; ++m) { const size_t off = (size_t)(row0 + ai * HALF + m * 16) * 2048 + col0;
; #pragma unroll
;                 for (int bj = 0; bj < 2; ++bj)
; #pragma unroll
;                     for (int n = 0; n < 2; ++n) { const f32x4 bs = *(const f32x4*)(base + off + bj * HALF + n * 16);
;                         *(f32x4*)(out + off + bj * HALF + n * 16) = bs + gv[bj][n] * acc[ai][bj][m][n]; } }
;     }
.LBB0_897:
	s_ashr_i32 s26, s52, 3
	v_lshl_add_u32 v160, s52, 8, v169
	v_lshl_or_b32 v64, s53, 8, v171
	s_mul_hi_i32 s27, s26, 0xc000
	s_mul_i32 s26, s26, 0xc000
	s_add_u32 s26, s41, s26
	v_ashrrev_i32_e32 v65, 31, v64
	s_addc_u32 s27, s42, s27
	v_lshlrev_b64 v[158:159], 2, v[64:65]
	v_lshlrev_b32_e32 v192, 13, v160
	v_lshl_add_u64 v[64:65], s[26:27], 0, v[158:159]
	v_add_u32_e32 v192, v192, v158
	global_load_dwordx4 v[128:131], v[64:65], off
	global_load_dwordx4 v[116:119], v[64:65], off offset:64
	global_load_dwordx4 v[108:111], v[64:65], off offset:512
	s_nop 0
	global_load_dwordx4 v[64:67], v[64:65], off offset:576
	s_mov_b64 s[26:27], -1
	v_add_u32_e32 v193, 0x20000, v192
	v_add_u32_e32 v224, 0x40000, v192
	v_add_u32_e32 v225, 0x60000, v192
	v_add_u32_e32 v226, 0x100000, v192
	v_add_u32_e32 v227, 0x120000, v192
	v_add_u32_e32 v228, 0x140000, v192
	v_add_u32_e32 v229, 0x160000, v192
	global_load_dwordx4 v[156:159], v192, s[8:9]
	global_load_dwordx4 v[176:179], v192, s[8:9] offset:64
	global_load_dwordx4 v[180:183], v192, s[8:9] offset:512
	global_load_dwordx4 v[184:187], v192, s[8:9] offset:576
	global_load_dwordx4 v[188:191], v193, s[8:9]
	global_load_dwordx4 v[196:199], v193, s[8:9] offset:64
	global_load_dwordx4 v[200:203], v193, s[8:9] offset:512
	global_load_dwordx4 v[204:207], v193, s[8:9] offset:576
	global_load_dwordx4 v[208:211], v224, s[8:9]
	global_load_dwordx4 v[212:215], v224, s[8:9] offset:64
	global_load_dwordx4 v[216:219], v224, s[8:9] offset:512
	global_load_dwordx4 v[220:223], v224, s[8:9] offset:576
	s_waitcnt vmcnt(11)
	v_pk_fma_f32 v[142:143], v[142:143], v[130:131], v[158:159]
	v_pk_fma_f32 v[140:141], v[140:141], v[128:129], v[156:157]
	global_store_dwordx4 v192, v[140:143], s[8:9] sc1
	s_waitcnt vmcnt(11)
	v_pk_fma_f32 v[138:139], v[138:139], v[118:119], v[178:179]
	v_pk_fma_f32 v[136:137], v[136:137], v[116:117], v[176:177]
	global_store_dwordx4 v192, v[136:139], s[8:9] offset:64 sc1
	s_waitcnt vmcnt(11)
	v_pk_fma_f32 v[134:135], v[134:135], v[110:111], v[182:183]
	v_pk_fma_f32 v[132:133], v[132:133], v[108:109], v[180:181]
	global_store_dwordx4 v192, v[132:135], s[8:9] offset:512 sc1
	s_waitcnt vmcnt(11)
	v_pk_fma_f32 v[126:127], v[126:127], v[66:67], v[186:187]
	v_pk_fma_f32 v[124:125], v[124:125], v[64:65], v[184:185]
	global_store_dwordx4 v192, v[124:127], s[8:9] offset:576 sc1
	global_load_dwordx4 v[156:159], v225, s[8:9]
	global_load_dwordx4 v[176:179], v225, s[8:9] offset:64
	global_load_dwordx4 v[180:183], v225, s[8:9] offset:512
	global_load_dwordx4 v[184:187], v225, s[8:9] offset:576
	global_load_dwordx4 v[140:143], v226, s[8:9]
	global_load_dwordx4 v[136:139], v226, s[8:9] offset:64
	global_load_dwordx4 v[132:135], v226, s[8:9] offset:512
	global_load_dwordx4 v[124:127], v226, s[8:9] offset:576
	s_waitcnt vmcnt(19)
	v_pk_fma_f32 v[122:123], v[122:123], v[130:131], v[190:191]
	v_pk_fma_f32 v[120:121], v[120:121], v[128:129], v[188:189]
	global_store_dwordx4 v193, v[120:123], s[8:9] sc1
	s_waitcnt vmcnt(19)
	v_pk_fma_f32 v[114:115], v[114:115], v[118:119], v[198:199]
	v_pk_fma_f32 v[112:113], v[112:113], v[116:117], v[196:197]
	global_store_dwordx4 v193, v[112:115], s[8:9] offset:64 sc1
	s_waitcnt vmcnt(19)
	v_pk_fma_f32 v[106:107], v[106:107], v[110:111], v[202:203]
	v_pk_fma_f32 v[104:105], v[104:105], v[108:109], v[200:201]
	global_store_dwordx4 v193, v[104:107], s[8:9] offset:512 sc1
	s_waitcnt vmcnt(19)
	v_pk_fma_f32 v[102:103], v[102:103], v[66:67], v[206:207]
	v_pk_fma_f32 v[100:101], v[100:101], v[64:65], v[204:205]
	global_store_dwordx4 v193, v[100:103], s[8:9] offset:576 sc1
	global_load_dwordx4 v[188:191], v227, s[8:9]
	global_load_dwordx4 v[196:199], v227, s[8:9] offset:64
	global_load_dwordx4 v[200:203], v227, s[8:9] offset:512
	global_load_dwordx4 v[204:207], v227, s[8:9] offset:576
	global_load_dwordx4 v[120:123], v228, s[8:9]
	global_load_dwordx4 v[112:115], v228, s[8:9] offset:64
	global_load_dwordx4 v[104:107], v228, s[8:9] offset:512
	global_load_dwordx4 v[100:103], v228, s[8:9] offset:576
	s_waitcnt vmcnt(27)
	v_pk_fma_f32 v[98:99], v[98:99], v[130:131], v[210:211]
	v_pk_fma_f32 v[96:97], v[96:97], v[128:129], v[208:209]
	global_store_dwordx4 v224, v[96:99], s[8:9] sc1
	s_waitcnt vmcnt(27)
	v_pk_fma_f32 v[94:95], v[94:95], v[118:119], v[214:215]
	v_pk_fma_f32 v[92:93], v[92:93], v[116:117], v[212:213]
	global_store_dwordx4 v224, v[92:95], s[8:9] offset:64 sc1
	s_waitcnt vmcnt(27)
; #define PG8_BAR __builtin_amdgcn_s_barrier()
; template <class Epi, class Sched, bool ALIGN_EPI = false, bool SP2 = false>
; __device__ __forceinline__ void gemm_phase(PG8_LAS unsigned char* lds, const Gemm g, const Sched& S, const Epi& E) {
;     ...
;         if constexpr (ALIGN_EPI) { if (wr == 0) PG8_BAR; }
;         if constexpr (!Epi::AFTER_DRAIN) { E(acc, cur, wr, wc, fr, fq); S.done(cur); }
;         if (!has_next) break;
; #pragma unroll
;         for (int a = 0; a < 2; ++a)
; #pragma unroll
;             for (int b = 0; b < 2; ++b)
; #pragma unroll
;                 for (int m = 0; m < 4; ++m)
; #pragma unroll
;                     for (int n = 0; n < 2; ++n) acc[a][b][m][n] = (f32x4){0.f, 0.f, 0.f, 0.f};
;         cur = nxt; cA = nA; cB = nB; ++ui;
;         if constexpr (ALIGN_EPI) { if (wr == 1) PG8_BAR; }
;     }
;     __device__ __forceinline__ void operator()(const f32x4 (&acc)[2][2][4][2], const Unit& u, int wr, int wc, int fr, int fq) const {
;     ...
;             for (int m = 0; m < 4; ++m) { const size_t off = (size_t)(row0 + ai * HALF + m * 16) * 2048 + col0;
; #pragma unroll
;                 for (int bj = 0; bj < 2; ++bj)
; #pragma unroll
;                     for (int n = 0; n < 2; ++n) { const f32x4 bs = *(const f32x4*)(base + off + bj * HALF + n * 16);
;                         *(f32x4*)(out + off + bj * HALF + n * 16) = bs + gv[bj][n] * acc[ai][bj][m][n]; } }
	v_pk_fma_f32 v[90:91], v[90:91], v[110:111], v[218:219]
	v_pk_fma_f32 v[88:89], v[88:89], v[108:109], v[216:217]
	global_store_dwordx4 v224, v[88:91], s[8:9] offset:512 sc1
	s_waitcnt vmcnt(27)
	v_pk_fma_f32 v[86:87], v[86:87], v[66:67], v[222:223]
	v_pk_fma_f32 v[84:85], v[84:85], v[64:65], v[220:221]
	global_store_dwordx4 v224, v[84:87], s[8:9] offset:576 sc1
	global_load_dwordx4 v[208:211], v229, s[8:9]
	global_load_dwordx4 v[212:215], v229, s[8:9] offset:64
	global_load_dwordx4 v[216:219], v229, s[8:9] offset:512
	global_load_dwordx4 v[220:223], v229, s[8:9] offset:576
	s_waitcnt vmcnt(27)
	v_pk_fma_f32 v[82:83], v[82:83], v[130:131], v[158:159]
	v_pk_fma_f32 v[80:81], v[80:81], v[128:129], v[156:157]
	global_store_dwordx4 v225, v[80:83], s[8:9] sc1
	s_waitcnt vmcnt(27)
	v_pk_fma_f32 v[78:79], v[78:79], v[118:119], v[178:179]
	v_pk_fma_f32 v[76:77], v[76:77], v[116:117], v[176:177]
	global_store_dwordx4 v225, v[76:79], s[8:9] offset:64 sc1
	s_waitcnt vmcnt(27)
	v_pk_fma_f32 v[74:75], v[74:75], v[110:111], v[182:183]
	v_pk_fma_f32 v[72:73], v[72:73], v[108:109], v[180:181]
	global_store_dwordx4 v225, v[72:75], s[8:9] offset:512 sc1
	s_waitcnt vmcnt(27)
	v_pk_fma_f32 v[70:71], v[70:71], v[66:67], v[186:187]
	v_pk_fma_f32 v[68:69], v[68:69], v[64:65], v[184:185]
	global_store_dwordx4 v225, v[68:71], s[8:9] offset:576 sc1
	s_waitcnt vmcnt(27)
	v_pk_fma_f32 v[62:63], v[62:63], v[130:131], v[142:143]
	v_pk_fma_f32 v[60:61], v[60:61], v[128:129], v[140:141]
	global_store_dwordx4 v226, v[60:63], s[8:9] sc1
	s_waitcnt vmcnt(27)
	v_pk_fma_f32 v[58:59], v[58:59], v[118:119], v[138:139]
	v_pk_fma_f32 v[56:57], v[56:57], v[116:117], v[136:137]
	global_store_dwordx4 v226, v[56:59], s[8:9] offset:64 sc1
	s_waitcnt vmcnt(27)
	v_pk_fma_f32 v[54:55], v[54:55], v[110:111], v[134:135]
	v_pk_fma_f32 v[52:53], v[52:53], v[108:109], v[132:133]
	global_store_dwordx4 v226, v[52:55], s[8:9] offset:512 sc1
	s_waitcnt vmcnt(27)
	v_pk_fma_f32 v[50:51], v[50:51], v[66:67], v[126:127]
	v_pk_fma_f32 v[48:49], v[48:49], v[64:65], v[124:125]
	global_store_dwordx4 v226, v[48:51], s[8:9] offset:576 sc1
	s_waitcnt vmcnt(23)
	v_pk_fma_f32 v[46:47], v[46:47], v[130:131], v[190:191]
	v_pk_fma_f32 v[44:45], v[44:45], v[128:129], v[188:189]
	global_store_dwordx4 v227, v[44:47], s[8:9] sc1
	s_waitcnt vmcnt(23)
	v_pk_fma_f32 v[42:43], v[42:43], v[118:119], v[198:199]
	v_pk_fma_f32 v[40:41], v[40:41], v[116:117], v[196:197]
	global_store_dwordx4 v227, v[40:43], s[8:9] offset:64 sc1
	s_waitcnt vmcnt(23)
	v_pk_fma_f32 v[38:39], v[38:39], v[110:111], v[202:203]
	v_pk_fma_f32 v[36:37], v[36:37], v[108:109], v[200:201]
	global_store_dwordx4 v227, v[36:39], s[8:9] offset:512 sc1
	s_waitcnt vmcnt(23)
	v_pk_fma_f32 v[34:35], v[34:35], v[66:67], v[206:207]
	v_pk_fma_f32 v[32:33], v[32:33], v[64:65], v[204:205]
	global_store_dwordx4 v227, v[32:35], s[8:9] offset:576 sc1
	s_waitcnt vmcnt(23)
	v_pk_fma_f32 v[30:31], v[30:31], v[130:131], v[122:123]
	v_pk_fma_f32 v[28:29], v[28:29], v[128:129], v[120:121]
	global_store_dwordx4 v228, v[28:31], s[8:9] sc1
	s_waitcnt vmcnt(23)
	v_pk_fma_f32 v[26:27], v[26:27], v[118:119], v[114:115]
	v_pk_fma_f32 v[24:25], v[24:25], v[116:117], v[112:113]
	global_store_dwordx4 v228, v[24:27], s[8:9] offset:64 sc1
	s_waitcnt vmcnt(23)
	v_pk_fma_f32 v[22:23], v[22:23], v[110:111], v[106:107]
	v_pk_fma_f32 v[20:21], v[20:21], v[108:109], v[104:105]
	global_store_dwordx4 v228, v[20:23], s[8:9] offset:512 sc1
	s_waitcnt vmcnt(23)
	v_pk_fma_f32 v[18:19], v[18:19], v[66:67], v[102:103]
	v_pk_fma_f32 v[16:17], v[16:17], v[64:65], v[100:101]
	global_store_dwordx4 v228, v[16:19], s[8:9] offset:576 sc1
	s_waitcnt vmcnt(19)
	v_pk_fma_f32 v[14:15], v[14:15], v[130:131], v[210:211]
	v_pk_fma_f32 v[12:13], v[12:13], v[128:129], v[208:209]
	global_store_dwordx4 v229, v[12:15], s[8:9] sc1
	s_waitcnt vmcnt(19)
	v_pk_fma_f32 v[10:11], v[10:11], v[118:119], v[214:215]
	v_pk_fma_f32 v[8:9], v[8:9], v[116:117], v[212:213]
	global_store_dwordx4 v229, v[8:11], s[8:9] offset:64 sc1
	s_waitcnt vmcnt(19)
	v_pk_fma_f32 v[6:7], v[6:7], v[110:111], v[218:219]
	v_pk_fma_f32 v[4:5], v[4:5], v[108:109], v[216:217]
	global_store_dwordx4 v229, v[4:7], s[8:9] offset:512 sc1
	s_waitcnt vmcnt(19)
	v_pk_fma_f32 v[2:3], v[2:3], v[66:67], v[222:223]
	v_pk_fma_f32 v[0:1], v[0:1], v[64:65], v[220:221]
	global_store_dwordx4 v229, v[0:3], s[8:9] offset:576 sc1
	s_and_b64 vcc, exec, s[4:5]
	s_cbranch_vccnz .LBB0_882
	s_andn2_b64 vcc, exec, s[14:15]
	s_cbranch_vccnz .LBB0_881
	s_barrier
	s_branch .LBB0_881

; __global__ void __launch_bounds__(512, 2) fwd_megakernel(Params p_unused) {
;     ...
;   for (int m = gw; m < MTOK; m += NGW) {
;     f32x4v* xr = (f32x4v*)(p.out + (size_t)m * DM) + lane; f32x4v v[8]; float s = 0.f;
; #pragma unroll
;     for (int j = 0; j < 8; ++j) { v[j] = xr[64 * j]; s += (v[j].x * v[j].x + v[j].y * v[j].y) + (v[j].z * v[j].z + v[j].w * v[j].w); }
;     const float rstd = rsqrtf(wave_sum(s) * (1.f / DM) + EPS);
; #pragma unroll
;     for (int j = 0; j < 8; ++j) { const f32x4v w = *(const f32x4v*)(p.final_norm_w + 4 * (lane + 64 * j)); xr[64 * j] = v[j] * rstd * w; }
;   }
.LBB0_955:
	global_load_dwordx4 v[20:23], v[10:11], off offset:-4096
	global_load_dwordx4 v[24:27], v[10:11], off offset:-3072
	global_load_dwordx4 v[28:31], v[10:11], off offset:-2048
	global_load_dwordx4 v[32:35], v[10:11], off
	global_load_dwordx4 v[36:39], v[10:11], off offset:-1024
	global_load_dwordx4 v[40:43], v[10:11], off offset:1024
	global_load_dwordx4 v[44:47], v[10:11], off offset:3072
	global_load_dwordx4 v[48:51], v[10:11], off offset:2048
	global_load_dwordx4 v[52:55], v[0:1], off
	s_add_i32 s0, s0, s74
	s_cmpk_gt_i32 s0, 0x3fff
	s_waitcnt vmcnt(8)
	v_mov_b32_e32 v58, v21
	s_waitcnt vmcnt(7)
	v_mov_b32_e32 v59, v25
	v_mov_b32_e32 v62, v23
	v_mov_b32_e32 v63, v27
	v_mov_b32_e32 v56, v20
	v_mov_b32_e32 v57, v24
	v_mov_b32_e32 v60, v22
	v_mov_b32_e32 v61, v26
	s_waitcnt vmcnt(6)
	v_pk_mul_f32 v[64:65], v[30:31], v[30:31]
	v_pk_mul_f32 v[66:67], v[28:29], v[28:29]
	v_pk_mul_f32 v[58:59], v[58:59], v[58:59]
	v_pk_mul_f32 v[62:63], v[62:63], v[62:63]
	v_pk_mov_b32 v[80:81], v[66:67], v[64:65] op_sel:[1,0]
	v_mov_b32_e32 v67, v65
	v_pk_fma_f32 v[56:57], v[56:57], v[56:57], v[58:59]
	v_pk_fma_f32 v[58:59], v[60:61], v[60:61], v[62:63]
	s_waitcnt vmcnt(4)
	v_mul_f32_e32 v68, v37, v37
	v_mul_f32_e32 v70, v39, v39
	v_pk_add_f32 v[60:61], v[80:81], v[66:67]
	v_pk_add_f32 v[56:57], v[56:57], v[58:59]
	v_mul_f32_e32 v19, v32, v32
	v_mul_f32_e32 v79, v33, v33
	v_mul_f32_e32 v82, v34, v34
	v_mul_f32_e32 v83, v35, v35
	v_pk_fma_f32 v[64:65], v[36:37], v[36:37], v[68:69] op_sel_hi:[1,1,0]
	v_pk_fma_f32 v[68:69], v[38:39], v[38:39], v[70:71] op_sel_hi:[1,1,0]
	v_pk_add_f32 v[58:59], v[60:61], v[60:61] op_sel:[0,1] op_sel_hi:[1,0]
	v_pk_add_f32 v[56:57], v[56:57], v[56:57] op_sel:[0,1] op_sel_hi:[1,0]
	s_waitcnt vmcnt(3)
	v_pk_mul_f32 v[72:73], v[42:43], v[42:43]
	v_pk_mul_f32 v[74:75], v[40:41], v[40:41]
	v_mov_b32_e32 v65, v82
	v_mov_b32_e32 v69, v83
	v_mov_b32_e32 v59, v79
	v_mov_b32_e32 v57, v19
	v_pk_mov_b32 v[70:71], v[74:75], v[72:73] op_sel:[1,0]
	v_mov_b32_e32 v75, v73
	v_pk_add_f32 v[60:61], v[64:65], v[68:69]
	v_pk_add_f32 v[56:57], v[56:57], v[58:59]
	s_waitcnt vmcnt(1)
	v_mul_f32_e32 v76, v49, v49
	v_mul_f32_e32 v78, v51, v51
	v_pk_add_f32 v[62:63], v[70:71], v[74:75]
	v_pk_add_f32 v[56:57], v[56:57], v[60:61]
	v_mul_f32_e32 v84, v44, v44
	v_mul_f32_e32 v85, v45, v45
	v_mul_f32_e32 v86, v46, v46
	v_mul_f32_e32 v87, v47, v47
	v_pk_fma_f32 v[72:73], v[48:49], v[48:49], v[76:77] op_sel_hi:[1,1,0]
	v_pk_fma_f32 v[76:77], v[50:51], v[50:51], v[78:79] op_sel_hi:[1,1,0]
	v_pk_add_f32 v[62:63], v[62:63], v[62:63] op_sel:[0,1] op_sel_hi:[1,0]
	v_pk_add_f32 v[56:57], v[56:57], v[56:57] op_sel:[0,1] op_sel_hi:[1,0]
	v_mov_b32_e32 v73, v86
	v_mov_b32_e32 v77, v87
	v_mov_b32_e32 v63, v85
	v_mov_b32_e32 v57, v84
	v_pk_add_f32 v[64:65], v[72:73], v[76:77]
	v_pk_add_f32 v[56:57], v[56:57], v[62:63]
	s_nop 0
	v_pk_add_f32 v[56:57], v[56:57], v[64:65]
	s_nop 0
	v_add_f32_e32 v19, v56, v57
	ds_bpermute_b32 v56, v12, v19
	s_waitcnt lgkmcnt(0)
	v_add_f32_e32 v19, v19, v56
	ds_bpermute_b32 v56, v13, v19
	s_waitcnt lgkmcnt(0)
	v_add_f32_e32 v19, v19, v56
	ds_bpermute_b32 v56, v14, v19
	s_waitcnt lgkmcnt(0)
	v_add_f32_e32 v19, v19, v56
	ds_bpermute_b32 v56, v15, v19
	s_waitcnt lgkmcnt(0)
	v_add_f32_e32 v19, v19, v56
	ds_bpermute_b32 v56, v16, v19
	s_waitcnt lgkmcnt(0)
	v_add_f32_e32 v19, v19, v56
	ds_bpermute_b32 v56, v17, v19
	s_waitcnt lgkmcnt(0)
	v_add_f32_e32 v19, v19, v56
	v_fmamk_f32 v19, v19, 0x3a000000, v18
	v_mul_f32_e32 v56, 0x4b800000, v19
	v_cmp_gt_f32_e32 vcc, s1, v19
	s_nop 1
	v_cndmask_b32_e32 v19, v19, v56, vcc
	v_rsq_f32_e32 v19, v19
	s_nop 0
	v_mul_f32_e32 v56, 0x45800000, v19
	v_cndmask_b32_e32 v56, v19, v56, vcc
	v_pk_mul_f32 v[20:21], v[56:57], v[20:21] op_sel_hi:[0,1]
	v_pk_mul_f32 v[22:23], v[56:57], v[22:23] op_sel_hi:[0,1]
	s_waitcnt vmcnt(0)
	v_pk_mul_f32 v[22:23], v[22:23], v[54:55]
	v_pk_mul_f32 v[20:21], v[20:21], v[52:53]
	global_store_dwordx4 v[10:11], v[20:23], off offset:-4096 sc1
	global_load_dwordx4 v[20:23], v[0:1], off offset:1024
	v_pk_mul_f32 v[26:27], v[56:57], v[26:27] op_sel_hi:[0,1]
	v_pk_mul_f32 v[24:25], v[56:57], v[24:25] op_sel_hi:[0,1]
	s_waitcnt vmcnt(0)
	v_pk_mul_f32 v[20:21], v[24:25], v[20:21]
	v_pk_mul_f32 v[22:23], v[26:27], v[22:23]
	global_store_dwordx4 v[10:11], v[20:23], off offset:-3072 sc1
	global_load_dwordx4 v[20:23], v[0:1], off offset:2048
	v_pk_mul_f32 v[24:25], v[56:57], v[30:31] op_sel_hi:[0,1]
	v_pk_mul_f32 v[26:27], v[56:57], v[28:29] op_sel_hi:[0,1]
	s_waitcnt vmcnt(0)
	v_pk_mul_f32 v[20:21], v[26:27], v[20:21]
	v_pk_mul_f32 v[22:23], v[24:25], v[22:23]
	global_store_dwordx4 v[10:11], v[20:23], off offset:-2048 sc1
	global_load_dwordx4 v[20:23], v[0:1], off offset:3072
	v_pk_mul_f32 v[24:25], v[56:57], v[38:39] op_sel_hi:[0,1]
	v_pk_mul_f32 v[26:27], v[56:57], v[36:37] op_sel_hi:[0,1]
	s_waitcnt vmcnt(0)
	v_pk_mul_f32 v[20:21], v[26:27], v[20:21]
	v_pk_mul_f32 v[22:23], v[24:25], v[22:23]
	global_store_dwordx4 v[10:11], v[20:23], off offset:-1024 sc1
	global_load_dwordx4 v[20:23], v[2:3], off
	v_pk_mul_f32 v[24:25], v[56:57], v[34:35] op_sel_hi:[0,1]
	v_pk_mul_f32 v[26:27], v[56:57], v[32:33] op_sel_hi:[0,1]
	s_waitcnt vmcnt(0)
	v_pk_mul_f32 v[20:21], v[26:27], v[20:21]
	v_pk_mul_f32 v[22:23], v[24:25], v[22:23]
	global_store_dwordx4 v[10:11], v[20:23], off sc1
	global_load_dwordx4 v[20:23], v[4:5], off
	v_pk_mul_f32 v[24:25], v[56:57], v[42:43] op_sel_hi:[0,1]
	v_pk_mul_f32 v[26:27], v[56:57], v[40:41] op_sel_hi:[0,1]
	s_waitcnt vmcnt(0)
	v_pk_mul_f32 v[20:21], v[26:27], v[20:21]
	v_pk_mul_f32 v[22:23], v[24:25], v[22:23]
	global_store_dwordx4 v[10:11], v[20:23], off offset:1024 sc1
	global_load_dwordx4 v[20:23], v[6:7], off
	v_pk_mul_f32 v[24:25], v[56:57], v[50:51] op_sel_hi:[0,1]
	v_pk_mul_f32 v[26:27], v[56:57], v[48:49] op_sel_hi:[0,1]
	s_waitcnt vmcnt(0)
	v_pk_mul_f32 v[20:21], v[26:27], v[20:21]
	v_pk_mul_f32 v[22:23], v[24:25], v[22:23]
	global_store_dwordx4 v[10:11], v[20:23], off offset:2048 sc1
	global_load_dwordx4 v[20:23], v[8:9], off
	v_pk_mul_f32 v[24:25], v[56:57], v[46:47] op_sel_hi:[0,1]
	v_pk_mul_f32 v[26:27], v[56:57], v[44:45] op_sel_hi:[0,1]
	s_waitcnt vmcnt(0)
	v_pk_mul_f32 v[20:21], v[26:27], v[20:21]
	v_pk_mul_f32 v[22:23], v[24:25], v[22:23]
	global_store_dwordx4 v[10:11], v[20:23], off offset:3072 sc1
	v_lshl_add_u64 v[10:11], v[10:11], 0, s[2:3]
	s_cbranch_scc0 .LBB0_955
